# speedup vs baseline: 1.0254x; 1.0015x over previous
; __device__ __forceinline__ u16 f2bf(float f) { unsigned u = __float_as_uint(f); u += 0x7fffu + ((u >> 16) & 1u); return (u16)(u >> 16); }
; __device__ __forceinline__ void tr_job(float* lds, int& gt, const float* __restrict__ src, int src_ld, const float* __restrict__ gain,
;                        u16* __restrict__ dst, int dst_ld, int K, int Nvalid, int Ndst) {
;     ...
;     const int gk = k0 + lane;
; #pragma unroll 16
;     for (int n = 0; n < 32; ++n) {
;       const float v = wl[lane * 33 + n];
;       if (gk < K && n0 + n < Ndst) dst[(size_t)(n0 + n) * dst_ld + gk] = f2bf(v);
;     }
.LBB0_225:
	s_and_saveexec_b64 s[4:5], s[0:1]
	s_cbranch_execz .LBB0_230
	v_add_u32_e32 v74, s87, v71
	v_cmp_gt_i32_e32 vcc, s82, v74
	s_and_saveexec_b64 s[6:7], vcc
	s_cbranch_execz .LBB0_228
	ds_read_b32 v75, v73
	v_add_co_u32_e32 v76, vcc, 0xfffd7000, v34
	s_waitcnt lgkmcnt(0)
	v_cvt_pk_bf16_f32 v75, v75, v75
	v_addc_co_u32_e32 v77, vcc, -1, v35, vcc
	global_store_short_d16_hi v[76:77], v75, off offset:-1024

; __device__ __forceinline__ u16 f2bf(float f) { unsigned u = __float_as_uint(f); u += 0x7fffu + ((u >> 16) & 1u); return (u16)(u >> 16); }
; __device__ __forceinline__ void tr_job(float* lds, int& gt, const float* __restrict__ src, int src_ld, const float* __restrict__ gain,
;                        u16* __restrict__ dst, int dst_ld, int K, int Nvalid, int Ndst) {
;     ...
;     const int gk = k0 + lane;
; #pragma unroll 16
;     for (int n = 0; n < 32; ++n) {
;       const float v = wl[lane * 33 + n];
;       if (gk < K && n0 + n < Ndst) dst[(size_t)(n0 + n) * dst_ld + gk] = f2bf(v);
;     }
.LBB0_493:
	s_and_saveexec_b64 s[4:5], s[0:1]
	s_cbranch_execz .LBB0_498
	v_add_u32_e32 v74, s67, v71
	v_cmp_gt_i32_e32 vcc, s62, v74
	s_and_saveexec_b64 s[6:7], vcc
	s_cbranch_execz .LBB0_496
	ds_read_b32 v75, v73
	v_add_co_u32_e32 v76, vcc, 0xfffff000, v34
	s_waitcnt lgkmcnt(0)
	v_cvt_pk_bf16_f32 v75, v75, v75
	v_addc_co_u32_e32 v77, vcc, -1, v35, vcc
	global_store_short_d16_hi v[76:77], v75, off offset:-704

; __device__ __forceinline__ int opaque_tid() { int t; asm volatile("v_mov_b32 %0, %1" : "=v"(t) : "v"((int)threadIdx.x)); return t; }
; #define STAGE(P, BASE, kt) do { const char* _g = (const char*)(BASE) + (size_t)((kt) * (BK * 2)); \
;     __builtin_amdgcn_global_load_lds((const unsigned*)(_g + (size_t)goff0), (unsigned*)((char*)(P) + tid_ * 16), 16, 0, 0); \
;     __builtin_amdgcn_global_load_lds((const unsigned*)(_g + (size_t)goff1), (unsigned*)((char*)(P) + tid_ * 16 + 8192), 16, 0, 0); } while (0)
; #define STAGEA(P, BASE, kt) do { const char* _g = (const char*)(BASE) + (size_t)((kt) * a_kbytes); \
;     __builtin_amdgcn_global_load_lds((const unsigned*)(_g + (size_t)goffA0), (unsigned*)((char*)(P) + tid_ * 16), 16, 0, 0); \
;     __builtin_amdgcn_global_load_lds((const unsigned*)(_g + (size_t)goffA1), (unsigned*)((char*)(P) + tid_ * 16 + 8192), 16, 0, 0); } while (0)
; #define LDA(dst, b, h) for (int m = 0; m < 4; ++m) for (int k = 0; k < 2; ++k) \
;     dst[m][k] = *reinterpret_cast<const bf16x8*>((char*)SA(b, h) + lds_byte(wr * 64 + m * 16 + fr, k * 32 + fq * 8))
; #define LDB(dst, b, h) for (int n = 0; n < 2; ++n) for (int k = 0; k < 2; ++k) \
;     dst[n][k] = *reinterpret_cast<const bf16x8*>((char*)SB(b, h) + lds_byte(wc * 32 + n * 16 + fr, k * 32 + fq * 8))
; #define WAIT_V(n) asm volatile("s_waitcnt vmcnt(" #n ")" ::: "memory")
; #define BAR __builtin_amdgcn_s_barrier()
; #define SCHED __builtin_amdgcn_sched_barrier(0)
; template <int EPI> ...
;     ...
;   const int tid_ = opaque_tid();
;   const int wid = tid_ >> 6, lane = tid_ & 63, wr = wid >> 2, wc = wid & 3, fr = lane & 15, fq = lane >> 4;
;   f32x4 acc[2][2][4][2] = {};
;   bf16x8 At[4][2], B0[2][2], B1[2][2];
;   const int nt = K / BK;
;   STAGE(SB(0, 0), B0p, 0); STAGEA(SA(0, 0), A0, 0);
;   STAGE(SB(0, 1), B1p, 0); STAGEA(SA(0, 1), A1, 0);
;   if (wr == 1) BAR;
;   WAIT_V(4); BAR;
;   STAGE(SB(1, 0), B0p, 1); STAGEA(SA(1, 0), A0, 1); STAGE(SB(1, 1), B1p, 1);
;   WAIT_V(6); BAR;
;   for (int t = 0; t < nt - 2; t += 2) {
;     LDB(B0, 0, 0); SCHED; LDA(At, 0, 0); STAGEA(SA(1, 1), A1, t + 1);
.LBB0_759:
	s_or_b64 exec, exec, s[58:59]
	v_add_u32_e32 v165, s83, v12
	v_add_u32_e32 v166, 0x2000, v165
	v_readfirstlane_b32 s53, v165
	v_lshl_add_u64 v[0:1], v[0:1], 0, s[4:5]
	s_mov_b32 m0, s53
	v_readfirstlane_b32 s53, v166
	v_add_u32_e32 v167, 0x8000, v159
	s_waitcnt vmcnt(4)
	s_barrier
	global_load_lds_dwordx4 v[0:1], off
	v_lshl_add_u64 v[0:1], v[2:3], 0, s[4:5]
	s_mov_b32 m0, s53
	v_readfirstlane_b32 s53, v167
	v_add_u32_e32 v168, 0xa000, v159
	global_load_lds_dwordx4 v[0:1], off
	v_lshl_add_u64 v[0:1], v[4:5], 0, s[4:5]
	s_mov_b32 m0, s53
	v_readfirstlane_b32 s53, v168
	v_add_u32_e32 v170, s84, v12
	global_load_lds_dwordx4 v[0:1], off
	v_lshl_add_u64 v[0:1], v[6:7], 0, s[4:5]
	s_mov_b32 m0, s53
	v_readfirstlane_b32 s53, v170
	v_add_u32_e32 v171, 0x2000, v170
	global_load_lds_dwordx4 v[0:1], off
	v_lshl_add_u64 v[0:1], v[8:9], 0, s[4:5]
	s_mov_b32 m0, s53
	v_readfirstlane_b32 s53, v171
	global_load_lds_dwordx4 v[0:1], off
	v_lshl_add_u64 v[0:1], v[10:11], 0, s[4:5]
	s_mov_b32 m0, s53
	v_and_b32_e32 v149, 15, v136
	global_load_lds_dwordx4 v[0:1], off
	v_bfe_u32 v147, v136, 4, 2
	v_lshlrev_b32_e32 v3, 2, v136
	s_lshl_b32 s53, s62, 11
	s_lshl_b32 s55, s63, 8
	v_lshlrev_b32_e32 v0, 4, v147
	v_lshlrev_b32_e32 v2, 6, v149
	v_and_b32_e32 v3, 32, v3
	v_lshlrev_b32_e32 v9, 6, v136
	s_or_b32 s58, s53, s55
	v_bfe_u32 v148, v136, 6, 2
	s_waitcnt vmcnt(6)
	v_bitop3_b32 v2, v0, v3, v2 bitop3:0x36
	v_lshlrev_b32_e32 v8, 13, v13
	v_and_or_b32 v0, v9, s85, v0
	s_ashr_i32 s59, s58, 31
	v_lshlrev_b32_e32 v1, 12, v148
	v_add_u32_e32 v4, s81, v2
	v_add_u32_e32 v5, s82, v2
	v_add_u32_e32 v6, s83, v2
	v_add_u32_e32 v7, s84, v2
	v_add_u32_e32 v2, 0, v2
	v_xad_u32 v3, v0, v3, 0
	v_or_b32_e32 v9, 0x800, v8
	v_or_b32_e32 v10, 0x1000, v8
	v_or_b32_e32 v11, 0x1800, v8
	s_lshl_b64 s[62:63], s[58:59], 12
	v_mov_b32_e32 v0, 0
	v_lshlrev_b32_e32 v150, 6, v13
	s_mov_b32 s53, -2
	v_add_u32_e32 v172, v4, v1
	v_add_u32_e32 v154, v2, v8
	v_add_u32_e32 v153, v3, v9
	v_add_u32_e32 v152, v3, v10
	v_add_u32_e32 v151, v3, v11
	v_add_u32_e32 v169, v5, v1
	v_add_u32_e32 v157, v6, v1
	v_add_u32_e32 v155, v7, v1
	s_mov_b64 s[58:59], s[74:75]
	v_mov_b32_e32 v1, v0
	v_mov_b32_e32 v2, v0
	v_mov_b32_e32 v3, v0
	v_mov_b32_e32 v4, v0
	v_mov_b32_e32 v5, v0
	v_mov_b32_e32 v6, v0
	v_mov_b32_e32 v7, v0
	v_mov_b32_e32 v8, v0
	v_mov_b32_e32 v9, v0
	v_mov_b32_e32 v10, v0
	v_mov_b32_e32 v11, v0
	v_mov_b32_e32 v12, v0
	v_mov_b32_e32 v13, v0
	v_mov_b32_e32 v14, v0
	v_mov_b32_e32 v15, v0
	v_mov_b32_e32 v16, v0
	v_mov_b32_e32 v17, v0
	v_mov_b32_e32 v18, v0
	v_mov_b32_e32 v19, v0
	v_mov_b32_e32 v20, v0
	v_mov_b32_e32 v21, v0
	v_mov_b32_e32 v22, v0
	v_mov_b32_e32 v23, v0
	v_mov_b32_e32 v24, v0
	v_mov_b32_e32 v25, v0
	v_mov_b32_e32 v26, v0
	v_mov_b32_e32 v27, v0
	v_mov_b32_e32 v28, v0
	v_mov_b32_e32 v29, v0
	v_mov_b32_e32 v30, v0
	v_mov_b32_e32 v31, v0
	v_mov_b32_e32 v32, v0
	v_mov_b32_e32 v33, v0
	v_mov_b32_e32 v34, v0
	v_mov_b32_e32 v35, v0
	v_mov_b32_e32 v36, v0
	v_mov_b32_e32 v37, v0
	v_mov_b32_e32 v38, v0
	v_mov_b32_e32 v39, v0
	v_mov_b32_e32 v40, v0
	v_mov_b32_e32 v41, v0
	v_mov_b32_e32 v42, v0
	v_mov_b32_e32 v43, v0
	v_mov_b32_e32 v44, v0
	v_mov_b32_e32 v45, v0
	v_mov_b32_e32 v46, v0
	v_mov_b32_e32 v47, v0
	v_mov_b32_e32 v48, v0
	v_mov_b32_e32 v49, v0
	v_mov_b32_e32 v50, v0
	v_mov_b32_e32 v51, v0
	v_mov_b32_e32 v52, v0
	v_mov_b32_e32 v53, v0
	v_mov_b32_e32 v54, v0
	v_mov_b32_e32 v55, v0
	v_mov_b32_e32 v56, v0
	v_mov_b32_e32 v57, v0
	v_mov_b32_e32 v58, v0
	v_mov_b32_e32 v59, v0
	v_mov_b32_e32 v60, v0
	v_mov_b32_e32 v61, v0
	v_mov_b32_e32 v62, v0
	v_mov_b32_e32 v63, v0
	v_mov_b32_e32 v64, v0
	v_mov_b32_e32 v65, v0
	v_mov_b32_e32 v66, v0
	v_mov_b32_e32 v67, v0
	v_mov_b32_e32 v68, v0
	v_mov_b32_e32 v69, v0
	v_mov_b32_e32 v70, v0
	v_mov_b32_e32 v71, v0
	v_mov_b32_e32 v72, v0
	v_mov_b32_e32 v73, v0
	v_mov_b32_e32 v74, v0
	v_mov_b32_e32 v75, v0
	v_mov_b32_e32 v76, v0
	v_mov_b32_e32 v77, v0
	v_mov_b32_e32 v78, v0
	v_mov_b32_e32 v79, v0
	v_mov_b32_e32 v80, v0
	v_mov_b32_e32 v81, v0
	v_mov_b32_e32 v82, v0
	v_mov_b32_e32 v83, v0
	v_mov_b32_e32 v84, v0
	v_mov_b32_e32 v85, v0
	v_mov_b32_e32 v86, v0
	v_mov_b32_e32 v87, v0
	v_mov_b32_e32 v88, v0
	v_mov_b32_e32 v89, v0
	v_mov_b32_e32 v90, v0
	v_mov_b32_e32 v91, v0
	v_mov_b32_e32 v92, v0
	v_mov_b32_e32 v93, v0
	v_mov_b32_e32 v94, v0
	v_mov_b32_e32 v95, v0
	v_mov_b32_e32 v96, v0
	v_mov_b32_e32 v97, v0
	v_mov_b32_e32 v98, v0
	v_mov_b32_e32 v99, v0
	v_mov_b32_e32 v100, v0
	v_mov_b32_e32 v101, v0
	v_mov_b32_e32 v102, v0
	v_mov_b32_e32 v103, v0
	v_mov_b32_e32 v104, v0
	v_mov_b32_e32 v105, v0
	v_mov_b32_e32 v106, v0
	v_mov_b32_e32 v107, v0
	v_mov_b32_e32 v108, v0
	v_mov_b32_e32 v109, v0
	v_mov_b32_e32 v110, v0
	v_mov_b32_e32 v111, v0
	v_mov_b32_e32 v112, v0
	v_mov_b32_e32 v113, v0
	v_mov_b32_e32 v114, v0
	v_mov_b32_e32 v115, v0
	v_mov_b32_e32 v116, v0
	v_mov_b32_e32 v117, v0
	v_mov_b32_e32 v118, v0
	v_mov_b32_e32 v119, v0
	v_mov_b32_e32 v120, v0
	v_mov_b32_e32 v121, v0
	v_mov_b32_e32 v122, v0
	v_mov_b32_e32 v123, v0
	v_mov_b32_e32 v124, v0
	v_mov_b32_e32 v125, v0
	v_mov_b32_e32 v126, v0
	v_mov_b32_e32 v127, v0
	v_lshl_add_u64 v[128:129], v[138:139], 0, s[60:61]
	v_lshl_add_u64 v[130:131], v[140:141], 0, s[60:61]
	v_lshl_add_u64 v[142:143], v[138:139], 0, s[62:63]
	v_lshl_add_u64 v[144:145], v[140:141], 0, s[62:63]
	s_barrier
	ds_read_b128 v[176:179], v172
	ds_read_b128 v[180:183], v172 offset:1024
	ds_read_b128 v[184:187], v172 offset:2048
	ds_read_b128 v[188:191], v172 offset:3072
; #define STAGE(P, BASE, kt) do { const char* _g = (const char*)(BASE) + (size_t)((kt) * (BK * 2)); \
;     __builtin_amdgcn_global_load_lds((const unsigned*)(_g + (size_t)goff0), (unsigned*)((char*)(P) + tid_ * 16), 16, 0, 0); \
;     __builtin_amdgcn_global_load_lds((const unsigned*)(_g + (size_t)goff1), (unsigned*)((char*)(P) + tid_ * 16 + 8192), 16, 0, 0); } while (0)
; #define STAGEA(P, BASE, kt) do { const char* _g = (const char*)(BASE) + (size_t)((kt) * a_kbytes); \
;     __builtin_amdgcn_global_load_lds((const unsigned*)(_g + (size_t)goffA0), (unsigned*)((char*)(P) + tid_ * 16), 16, 0, 0); \
;     __builtin_amdgcn_global_load_lds((const unsigned*)(_g + (size_t)goffA1), (unsigned*)((char*)(P) + tid_ * 16 + 8192), 16, 0, 0); } while (0)
; #define LDA(dst, b, h) for (int m = 0; m < 4; ++m) for (int k = 0; k < 2; ++k) \
;     dst[m][k] = *reinterpret_cast<const bf16x8*>((char*)SA(b, h) + lds_byte(wr * 64 + m * 16 + fr, k * 32 + fq * 8))
; #define LDB(dst, b, h) for (int n = 0; n < 2; ++n) for (int k = 0; k < 2; ++k) \
;     dst[n][k] = *reinterpret_cast<const bf16x8*>((char*)SB(b, h) + lds_byte(wc * 32 + n * 16 + fr, k * 32 + fq * 8))
; #define MMA(ai, bj, At, Bt) do { __builtin_amdgcn_s_setprio(1); \
;     for (int m = 0; m < 4; ++m) for (int n = 0; n < 2; ++n) for (int k = 0; k < 2; ++k) \
;       acc[ai][bj][m][n] = __builtin_amdgcn_mfma_f32_16x16x32_bf16(At[m][k], Bt[n][k], acc[ai][bj][m][n], 0, 0, 0); \
;     __builtin_amdgcn_s_setprio(0); } while (0)
; #define WAIT_V(n) asm volatile("s_waitcnt vmcnt(" #n ")" ::: "memory")
; #define WAIT_L(n) asm volatile("s_waitcnt lgkmcnt(" #n ")" ::: "memory")
; #define BAR __builtin_amdgcn_s_barrier()
; #define SCHED __builtin_amdgcn_sched_barrier(0)
; template <int EPI> ...
;     ...
;     LDB(B0, 0, 0); SCHED; LDA(At, 0, 0); STAGEA(SA(1, 1), A1, t + 1);
;     WAIT_L(8); BAR; WAIT_L(0); MMA(0, 0, At, B0); BAR; SCHED;
;     LDB(B1, 0, 1); STAGE(SB(0, 0), B0p, t + 2);
;     BAR; WAIT_L(0); MMA(0, 1, At, B1); BAR;
;     LDA(At, 0, 1); STAGEA(SA(0, 0), A0, t + 2);
;     BAR; WAIT_L(0); MMA(1, 0, At, B0); BAR; SCHED;
;     STAGE(SB(0, 1), B1p, t + 2);
;     WAIT_V(6); BAR; MMA(1, 1, At, B1); BAR;
.LBB0_760:
	v_add_u32_e32 v173, 0xc000, v159
	v_lshl_add_u64 v[240:241], s[58:59], 0, v[142:143]
	v_readfirstlane_b32 s55, v173
	v_lshl_add_u64 v[174:175], v[240:241], 0, s[6:7]
	s_mov_b32 m0, s55
	ds_read_b128 v[192:195], v154
	ds_read_b128 v[196:199], v154 offset:1024
	ds_read_b128 v[200:203], v153
	ds_read_b128 v[204:207], v153 offset:1024
	ds_read_b128 v[208:211], v152
	ds_read_b128 v[212:215], v152 offset:1024
	ds_read_b128 v[216:219], v151
	ds_read_b128 v[220:223], v151 offset:1024
	global_load_lds_dwordx4 v[174:175], off
	v_add_u32_e32 v174, 0xe000, v159
	v_lshl_add_u64 v[242:243], s[58:59], 0, v[144:145]
	v_readfirstlane_b32 s55, v174
	v_lshl_add_u64 v[224:225], v[242:243], 0, s[6:7]
	s_mov_b32 m0, s55
	s_nop 0
	global_load_lds_dwordx4 v[224:225], off
	s_waitcnt lgkmcnt(8)
	s_setprio 1
	s_barrier
	s_waitcnt lgkmcnt(0)
	v_mfma_f32_16x16x32_bf16 v[124:127], v[192:195], v[176:179], v[124:127]
	v_mfma_f32_16x16x32_bf16 v[120:123], v[192:195], v[184:187], v[120:123]
	v_mfma_f32_16x16x32_bf16 v[116:119], v[200:203], v[176:179], v[116:119]
	v_mfma_f32_16x16x32_bf16 v[112:115], v[200:203], v[184:187], v[112:115]
	v_mfma_f32_16x16x32_bf16 v[108:111], v[208:211], v[176:179], v[108:111]
	v_mfma_f32_16x16x32_bf16 v[104:107], v[208:211], v[184:187], v[104:107]
	v_mfma_f32_16x16x32_bf16 v[100:103], v[216:219], v[176:179], v[100:103]
	v_mfma_f32_16x16x32_bf16 v[96:99], v[216:219], v[184:187], v[96:99]
	v_mfma_f32_16x16x32_bf16 v[124:127], v[196:199], v[180:183], v[124:127]
	v_mfma_f32_16x16x32_bf16 v[120:123], v[196:199], v[188:191], v[120:123]
	v_mfma_f32_16x16x32_bf16 v[116:119], v[204:207], v[180:183], v[116:119]
	v_mfma_f32_16x16x32_bf16 v[112:115], v[204:207], v[188:191], v[112:115]
	v_mfma_f32_16x16x32_bf16 v[108:111], v[212:215], v[180:183], v[108:111]
	v_mfma_f32_16x16x32_bf16 v[104:107], v[212:215], v[188:191], v[104:107]
	v_mfma_f32_16x16x32_bf16 v[100:103], v[220:223], v[180:183], v[100:103]
	v_mfma_f32_16x16x32_bf16 v[96:99], v[220:223], v[188:191], v[96:99]
	s_barrier
	s_setprio 0
	v_lshl_add_u64 v[244:245], s[58:59], 0, v[128:129]
	v_readfirstlane_b32 s55, v156
	v_lshl_add_u64 v[246:247], v[244:245], 0, s[8:9]
	s_mov_b32 m0, s55
	ds_read_b128 v[224:227], v169
	ds_read_b128 v[228:231], v169 offset:1024
	ds_read_b128 v[232:235], v169 offset:2048
	ds_read_b128 v[236:239], v169 offset:3072
	global_load_lds_dwordx4 v[246:247], off
	v_lshl_add_u64 v[246:247], s[58:59], 0, v[130:131]
	v_readfirstlane_b32 s55, v158
	v_lshl_add_u64 v[248:249], v[246:247], 0, s[8:9]
	s_mov_b32 m0, s55
	s_nop 0
	global_load_lds_dwordx4 v[248:249], off
	s_setprio 1
	s_barrier
	s_waitcnt lgkmcnt(0)
	v_mfma_f32_16x16x32_bf16 v[92:95], v[192:195], v[224:227], v[92:95]
	v_mfma_f32_16x16x32_bf16 v[88:91], v[192:195], v[232:235], v[88:91]
	v_mfma_f32_16x16x32_bf16 v[84:87], v[200:203], v[224:227], v[84:87]
	v_mfma_f32_16x16x32_bf16 v[80:83], v[200:203], v[232:235], v[80:83]
	v_mfma_f32_16x16x32_bf16 v[76:79], v[208:211], v[224:227], v[76:79]
	v_mfma_f32_16x16x32_bf16 v[72:75], v[208:211], v[232:235], v[72:75]
	v_mfma_f32_16x16x32_bf16 v[68:71], v[216:219], v[224:227], v[68:71]
	v_mfma_f32_16x16x32_bf16 v[64:67], v[216:219], v[232:235], v[64:67]
	v_mfma_f32_16x16x32_bf16 v[92:95], v[196:199], v[228:231], v[92:95]
	v_mfma_f32_16x16x32_bf16 v[88:91], v[196:199], v[236:239], v[88:91]
	v_mfma_f32_16x16x32_bf16 v[84:87], v[204:207], v[228:231], v[84:87]
	v_mfma_f32_16x16x32_bf16 v[80:83], v[204:207], v[236:239], v[80:83]
	v_mfma_f32_16x16x32_bf16 v[76:79], v[212:215], v[228:231], v[76:79]
	v_mfma_f32_16x16x32_bf16 v[72:75], v[212:215], v[236:239], v[72:75]
	v_mfma_f32_16x16x32_bf16 v[68:71], v[220:223], v[228:231], v[68:71]
	v_mfma_f32_16x16x32_bf16 v[64:67], v[220:223], v[236:239], v[64:67]
	s_barrier
	s_setprio 0
	v_readfirstlane_b32 s55, v159
	v_lshl_add_u64 v[248:249], v[240:241], 0, s[10:11]
	s_mov_b32 m0, s55
	v_readfirstlane_b32 s55, v160
	ds_read_b128 v[192:195], v154 offset:16384
	ds_read_b128 v[196:199], v154 offset:17408
	ds_read_b128 v[200:203], v153 offset:16384
	ds_read_b128 v[204:207], v153 offset:17408
	ds_read_b128 v[208:211], v152 offset:16384
	ds_read_b128 v[212:215], v152 offset:17408
	ds_read_b128 v[216:219], v151 offset:16384
	ds_read_b128 v[220:223], v151 offset:17408
	global_load_lds_dwordx4 v[248:249], off
	v_lshl_add_u64 v[248:249], v[242:243], 0, s[10:11]
	s_mov_b32 m0, s55
	s_nop 0
	global_load_lds_dwordx4 v[248:249], off
	s_setprio 1
	s_barrier
	s_waitcnt lgkmcnt(0)
	v_mfma_f32_16x16x32_bf16 v[60:63], v[192:195], v[176:179], v[60:63]
	v_mfma_f32_16x16x32_bf16 v[56:59], v[192:195], v[184:187], v[56:59]
	v_mfma_f32_16x16x32_bf16 v[52:55], v[200:203], v[176:179], v[52:55]
	v_mfma_f32_16x16x32_bf16 v[48:51], v[200:203], v[184:187], v[48:51]
	v_mfma_f32_16x16x32_bf16 v[44:47], v[208:211], v[176:179], v[44:47]
	v_mfma_f32_16x16x32_bf16 v[40:43], v[208:211], v[184:187], v[40:43]
	v_mfma_f32_16x16x32_bf16 v[36:39], v[216:219], v[176:179], v[36:39]
	v_mfma_f32_16x16x32_bf16 v[32:35], v[216:219], v[184:187], v[32:35]
	v_mfma_f32_16x16x32_bf16 v[60:63], v[196:199], v[180:183], v[60:63]
	v_mfma_f32_16x16x32_bf16 v[56:59], v[196:199], v[188:191], v[56:59]
	v_mfma_f32_16x16x32_bf16 v[52:55], v[204:207], v[180:183], v[52:55]
	v_mfma_f32_16x16x32_bf16 v[48:51], v[204:207], v[188:191], v[48:51]
	v_mfma_f32_16x16x32_bf16 v[44:47], v[212:215], v[180:183], v[44:47]
	v_mfma_f32_16x16x32_bf16 v[40:43], v[212:215], v[188:191], v[40:43]
	v_mfma_f32_16x16x32_bf16 v[36:39], v[220:223], v[180:183], v[36:39]
	v_mfma_f32_16x16x32_bf16 v[32:35], v[220:223], v[188:191], v[32:35]
	s_barrier
; #define STAGE(P, BASE, kt) do { const char* _g = (const char*)(BASE) + (size_t)((kt) * (BK * 2)); \
;     __builtin_amdgcn_global_load_lds((const unsigned*)(_g + (size_t)goff0), (unsigned*)((char*)(P) + tid_ * 16), 16, 0, 0); \
;     __builtin_amdgcn_global_load_lds((const unsigned*)(_g + (size_t)goff1), (unsigned*)((char*)(P) + tid_ * 16 + 8192), 16, 0, 0); } while (0)
; #define STAGEA(P, BASE, kt) do { const char* _g = (const char*)(BASE) + (size_t)((kt) * a_kbytes); \
;     __builtin_amdgcn_global_load_lds((const unsigned*)(_g + (size_t)goffA0), (unsigned*)((char*)(P) + tid_ * 16), 16, 0, 0); \
;     __builtin_amdgcn_global_load_lds((const unsigned*)(_g + (size_t)goffA1), (unsigned*)((char*)(P) + tid_ * 16 + 8192), 16, 0, 0); } while (0)
; #define LDA(dst, b, h) for (int m = 0; m < 4; ++m) for (int k = 0; k < 2; ++k) \
;     dst[m][k] = *reinterpret_cast<const bf16x8*>((char*)SA(b, h) + lds_byte(wr * 64 + m * 16 + fr, k * 32 + fq * 8))
; #define LDB(dst, b, h) for (int n = 0; n < 2; ++n) for (int k = 0; k < 2; ++k) \
;     dst[n][k] = *reinterpret_cast<const bf16x8*>((char*)SB(b, h) + lds_byte(wc * 32 + n * 16 + fr, k * 32 + fq * 8))
; #define MMA(ai, bj, At, Bt) do { __builtin_amdgcn_s_setprio(1); \
;     for (int m = 0; m < 4; ++m) for (int n = 0; n < 2; ++n) for (int k = 0; k < 2; ++k) \
;       acc[ai][bj][m][n] = __builtin_amdgcn_mfma_f32_16x16x32_bf16(At[m][k], Bt[n][k], acc[ai][bj][m][n], 0, 0, 0); \
;     __builtin_amdgcn_s_setprio(0); } while (0)
; #define WAIT_V(n) asm volatile("s_waitcnt vmcnt(" #n ")" ::: "memory")
; #define WAIT_L(n) asm volatile("s_waitcnt lgkmcnt(" #n ")" ::: "memory")
; #define BAR __builtin_amdgcn_s_barrier()
; #define SCHED __builtin_amdgcn_sched_barrier(0)
; template <int EPI> ...
;     ...
;     STAGE(SB(0, 1), B1p, t + 2);
;     WAIT_V(6); BAR; MMA(1, 1, At, B1); BAR;
;     LDB(B0, 1, 0); SCHED; LDA(At, 1, 0); STAGEA(SA(0, 1), A1, t + 2);
;     WAIT_L(8); BAR; WAIT_L(0); MMA(0, 0, At, B0); BAR; SCHED;
;     LDB(B1, 1, 1); STAGE(SB(1, 0), B0p, t + 3);
;     BAR; WAIT_L(0); MMA(0, 1, At, B1); BAR;
;     LDA(At, 1, 1); STAGEA(SA(1, 0), A0, t + 3);
	s_setprio 0
	v_readfirstlane_b32 s55, v161
	v_lshl_add_u64 v[176:177], v[244:245], 0, s[12:13]
	s_mov_b32 m0, s55
	v_readfirstlane_b32 s55, v162
	global_load_lds_dwordx4 v[176:177], off
	v_lshl_add_u64 v[176:177], v[246:247], 0, s[12:13]
	s_mov_b32 m0, s55
	s_nop 0
	global_load_lds_dwordx4 v[176:177], off
	s_waitcnt vmcnt(6)
	s_setprio 1
	s_barrier
	v_mfma_f32_16x16x32_bf16 v[28:31], v[192:195], v[224:227], v[28:31]
	v_mfma_f32_16x16x32_bf16 v[24:27], v[192:195], v[232:235], v[24:27]
	v_mfma_f32_16x16x32_bf16 v[20:23], v[200:203], v[224:227], v[20:23]
	v_mfma_f32_16x16x32_bf16 v[16:19], v[200:203], v[232:235], v[16:19]
	ds_read_b128 v[176:179], v157
	v_mfma_f32_16x16x32_bf16 v[12:15], v[208:211], v[224:227], v[12:15]
	v_mfma_f32_16x16x32_bf16 v[8:11], v[208:211], v[232:235], v[8:11]
	ds_read_b128 v[180:183], v157 offset:1024
	v_mfma_f32_16x16x32_bf16 v[4:7], v[216:219], v[224:227], v[4:7]
	v_mfma_f32_16x16x32_bf16 v[0:3], v[216:219], v[232:235], v[0:3]
	ds_read_b128 v[184:187], v157 offset:2048
	v_mfma_f32_16x16x32_bf16 v[28:31], v[196:199], v[228:231], v[28:31]
	v_mfma_f32_16x16x32_bf16 v[24:27], v[196:199], v[236:239], v[24:27]
	ds_read_b128 v[188:191], v157 offset:3072
	v_mfma_f32_16x16x32_bf16 v[20:23], v[204:207], v[228:231], v[20:23]
	v_mfma_f32_16x16x32_bf16 v[16:19], v[204:207], v[236:239], v[16:19]
	v_mfma_f32_16x16x32_bf16 v[12:15], v[212:215], v[228:231], v[12:15]
	v_mfma_f32_16x16x32_bf16 v[8:11], v[212:215], v[236:239], v[8:11]
	v_mfma_f32_16x16x32_bf16 v[4:7], v[220:223], v[228:231], v[4:7]
	v_mfma_f32_16x16x32_bf16 v[0:3], v[220:223], v[236:239], v[0:3]
	s_barrier
	s_setprio 0
	v_readfirstlane_b32 s55, v163
	v_lshl_add_u64 v[224:225], v[240:241], 0, s[14:15]
	s_mov_b32 m0, s55
	v_readfirstlane_b32 s55, v164
	ds_read_b128 v[192:195], v154 offset:32768
	ds_read_b128 v[196:199], v154 offset:33792
	ds_read_b128 v[200:203], v153 offset:32768
	ds_read_b128 v[204:207], v153 offset:33792
	ds_read_b128 v[208:211], v152 offset:32768
	ds_read_b128 v[212:215], v152 offset:33792
	ds_read_b128 v[216:219], v151 offset:32768
	ds_read_b128 v[220:223], v151 offset:33792
	global_load_lds_dwordx4 v[224:225], off
	v_lshl_add_u64 v[224:225], v[242:243], 0, s[14:15]
	s_mov_b32 m0, s55
	s_nop 0
	global_load_lds_dwordx4 v[224:225], off
	s_waitcnt lgkmcnt(8)
	s_setprio 1
	s_barrier
	s_waitcnt lgkmcnt(0)
	v_mfma_f32_16x16x32_bf16 v[124:127], v[192:195], v[176:179], v[124:127]
	v_mfma_f32_16x16x32_bf16 v[120:123], v[192:195], v[184:187], v[120:123]
	v_mfma_f32_16x16x32_bf16 v[116:119], v[200:203], v[176:179], v[116:119]
	v_mfma_f32_16x16x32_bf16 v[112:115], v[200:203], v[184:187], v[112:115]
	v_mfma_f32_16x16x32_bf16 v[108:111], v[208:211], v[176:179], v[108:111]
	v_mfma_f32_16x16x32_bf16 v[104:107], v[208:211], v[184:187], v[104:107]
	v_mfma_f32_16x16x32_bf16 v[100:103], v[216:219], v[176:179], v[100:103]
	v_mfma_f32_16x16x32_bf16 v[96:99], v[216:219], v[184:187], v[96:99]
	v_mfma_f32_16x16x32_bf16 v[124:127], v[196:199], v[180:183], v[124:127]
	v_mfma_f32_16x16x32_bf16 v[120:123], v[196:199], v[188:191], v[120:123]
	v_mfma_f32_16x16x32_bf16 v[116:119], v[204:207], v[180:183], v[116:119]
	v_mfma_f32_16x16x32_bf16 v[112:115], v[204:207], v[188:191], v[112:115]
	v_mfma_f32_16x16x32_bf16 v[108:111], v[212:215], v[180:183], v[108:111]
	v_mfma_f32_16x16x32_bf16 v[104:107], v[212:215], v[188:191], v[104:107]
	v_mfma_f32_16x16x32_bf16 v[100:103], v[220:223], v[180:183], v[100:103]
	v_mfma_f32_16x16x32_bf16 v[96:99], v[220:223], v[188:191], v[96:99]
	s_barrier
	s_setprio 0
	v_readfirstlane_b32 s55, v165
	v_lshl_add_u64 v[248:249], v[244:245], 0, s[24:25]
	s_mov_b32 m0, s55
	v_readfirstlane_b32 s55, v166
	ds_read_b128 v[224:227], v155
	ds_read_b128 v[228:231], v155 offset:1024
	ds_read_b128 v[232:235], v155 offset:2048
	ds_read_b128 v[236:239], v155 offset:3072
	global_load_lds_dwordx4 v[248:249], off
	v_lshl_add_u64 v[248:249], v[246:247], 0, s[24:25]
	s_mov_b32 m0, s55
	s_nop 0
	global_load_lds_dwordx4 v[248:249], off
	s_setprio 1
	s_barrier
	s_waitcnt lgkmcnt(0)
	v_mfma_f32_16x16x32_bf16 v[92:95], v[192:195], v[224:227], v[92:95]
	v_mfma_f32_16x16x32_bf16 v[88:91], v[192:195], v[232:235], v[88:91]
	v_mfma_f32_16x16x32_bf16 v[84:87], v[200:203], v[224:227], v[84:87]
	v_mfma_f32_16x16x32_bf16 v[80:83], v[200:203], v[232:235], v[80:83]
	v_mfma_f32_16x16x32_bf16 v[76:79], v[208:211], v[224:227], v[76:79]
	v_mfma_f32_16x16x32_bf16 v[72:75], v[208:211], v[232:235], v[72:75]
	v_mfma_f32_16x16x32_bf16 v[68:71], v[216:219], v[224:227], v[68:71]
	v_mfma_f32_16x16x32_bf16 v[64:67], v[216:219], v[232:235], v[64:67]
	v_mfma_f32_16x16x32_bf16 v[92:95], v[196:199], v[228:231], v[92:95]
	v_mfma_f32_16x16x32_bf16 v[88:91], v[196:199], v[236:239], v[88:91]
	v_mfma_f32_16x16x32_bf16 v[84:87], v[204:207], v[228:231], v[84:87]
	v_mfma_f32_16x16x32_bf16 v[80:83], v[204:207], v[236:239], v[80:83]
	v_mfma_f32_16x16x32_bf16 v[76:79], v[212:215], v[228:231], v[76:79]
	v_mfma_f32_16x16x32_bf16 v[72:75], v[212:215], v[236:239], v[72:75]
	v_mfma_f32_16x16x32_bf16 v[68:71], v[220:223], v[228:231], v[68:71]
	v_mfma_f32_16x16x32_bf16 v[64:67], v[220:223], v[236:239], v[64:67]
	s_barrier
	s_setprio 0
	v_readfirstlane_b32 s55, v167
	v_lshl_add_u64 v[240:241], v[240:241], 0, s[42:43]
	s_mov_b32 m0, s55
	v_readfirstlane_b32 s55, v168
	ds_read_b128 v[192:195], v154 offset:49152
	ds_read_b128 v[196:199], v154 offset:50176
	ds_read_b128 v[200:203], v153 offset:49152
	ds_read_b128 v[204:207], v153 offset:50176
	ds_read_b128 v[208:211], v152 offset:49152
	ds_read_b128 v[212:215], v152 offset:50176
	ds_read_b128 v[216:219], v151 offset:49152
	ds_read_b128 v[220:223], v151 offset:50176
	global_load_lds_dwordx4 v[240:241], off
	v_lshl_add_u64 v[240:241], v[242:243], 0, s[42:43]
	s_mov_b32 m0, s55
	s_nop 0
	global_load_lds_dwordx4 v[240:241], off
	s_setprio 1
	s_barrier
; #define STAGE(P, BASE, kt) do { const char* _g = (const char*)(BASE) + (size_t)((kt) * (BK * 2)); \
;     __builtin_amdgcn_global_load_lds((const unsigned*)(_g + (size_t)goff0), (unsigned*)((char*)(P) + tid_ * 16), 16, 0, 0); \
;     __builtin_amdgcn_global_load_lds((const unsigned*)(_g + (size_t)goff1), (unsigned*)((char*)(P) + tid_ * 16 + 8192), 16, 0, 0); } while (0)
; #define STAGEA(P, BASE, kt) do { const char* _g = (const char*)(BASE) + (size_t)((kt) * a_kbytes); \
;     __builtin_amdgcn_global_load_lds((const unsigned*)(_g + (size_t)goffA0), (unsigned*)((char*)(P) + tid_ * 16), 16, 0, 0); \
;     __builtin_amdgcn_global_load_lds((const unsigned*)(_g + (size_t)goffA1), (unsigned*)((char*)(P) + tid_ * 16 + 8192), 16, 0, 0); } while (0)
; #define LDA(dst, b, h) for (int m = 0; m < 4; ++m) for (int k = 0; k < 2; ++k) \
;     dst[m][k] = *reinterpret_cast<const bf16x8*>((char*)SA(b, h) + lds_byte(wr * 64 + m * 16 + fr, k * 32 + fq * 8))
; #define LDB(dst, b, h) for (int n = 0; n < 2; ++n) for (int k = 0; k < 2; ++k) \
;     dst[n][k] = *reinterpret_cast<const bf16x8*>((char*)SB(b, h) + lds_byte(wc * 32 + n * 16 + fr, k * 32 + fq * 8))
; #define MMA(ai, bj, At, Bt) do { __builtin_amdgcn_s_setprio(1); \
;     for (int m = 0; m < 4; ++m) for (int n = 0; n < 2; ++n) for (int k = 0; k < 2; ++k) \
;       acc[ai][bj][m][n] = __builtin_amdgcn_mfma_f32_16x16x32_bf16(At[m][k], Bt[n][k], acc[ai][bj][m][n], 0, 0, 0); \
;     __builtin_amdgcn_s_setprio(0); } while (0)
; #define WAIT_V(n) asm volatile("s_waitcnt vmcnt(" #n ")" ::: "memory")
; #define WAIT_L(n) asm volatile("s_waitcnt lgkmcnt(" #n ")" ::: "memory")
; #define BAR __builtin_amdgcn_s_barrier()
; #define SCHED __builtin_amdgcn_sched_barrier(0)
; template <int EPI> ...
;     ...
;     BAR; WAIT_L(0); MMA(1, 0, At, B0); BAR; SCHED;
;     STAGE(SB(1, 1), B1p, t + 3);
;     WAIT_V(6); BAR; MMA(1, 1, At, B1); BAR;
;   }
;   { LDB(B0, 0, 0); LDA(At, 0, 0); STAGEA(SA(1, 1), A1, nt - 1);
;     BAR; WAIT_L(0); MMA(0, 0, At, B0); BAR;
;     LDB(B1, 0, 1); BAR; WAIT_L(0); MMA(0, 1, At, B1); BAR;
	s_waitcnt lgkmcnt(0)
	v_mfma_f32_16x16x32_bf16 v[60:63], v[192:195], v[176:179], v[60:63]
	v_mfma_f32_16x16x32_bf16 v[56:59], v[192:195], v[184:187], v[56:59]
	v_mfma_f32_16x16x32_bf16 v[52:55], v[200:203], v[176:179], v[52:55]
	v_mfma_f32_16x16x32_bf16 v[48:51], v[200:203], v[184:187], v[48:51]
	v_mfma_f32_16x16x32_bf16 v[44:47], v[208:211], v[176:179], v[44:47]
	v_mfma_f32_16x16x32_bf16 v[40:43], v[208:211], v[184:187], v[40:43]
	v_mfma_f32_16x16x32_bf16 v[36:39], v[216:219], v[176:179], v[36:39]
	v_mfma_f32_16x16x32_bf16 v[32:35], v[216:219], v[184:187], v[32:35]
	v_mfma_f32_16x16x32_bf16 v[60:63], v[196:199], v[180:183], v[60:63]
	v_mfma_f32_16x16x32_bf16 v[56:59], v[196:199], v[188:191], v[56:59]
	v_mfma_f32_16x16x32_bf16 v[52:55], v[204:207], v[180:183], v[52:55]
	v_mfma_f32_16x16x32_bf16 v[48:51], v[204:207], v[188:191], v[48:51]
	v_mfma_f32_16x16x32_bf16 v[44:47], v[212:215], v[180:183], v[44:47]
	v_mfma_f32_16x16x32_bf16 v[40:43], v[212:215], v[188:191], v[40:43]
	v_mfma_f32_16x16x32_bf16 v[36:39], v[220:223], v[180:183], v[36:39]
	v_mfma_f32_16x16x32_bf16 v[32:35], v[220:223], v[188:191], v[32:35]
	s_barrier
	s_setprio 0
	v_readfirstlane_b32 s55, v170
	v_lshl_add_u64 v[176:177], v[244:245], 0, s[46:47]
	s_mov_b32 m0, s55
	v_readfirstlane_b32 s55, v171
	global_load_lds_dwordx4 v[176:177], off
	v_lshl_add_u64 v[176:177], v[246:247], 0, s[46:47]
	s_mov_b32 m0, s55
	s_nop 0
	global_load_lds_dwordx4 v[176:177], off
	s_waitcnt vmcnt(6)
	s_setprio 1
	s_barrier
	v_mfma_f32_16x16x32_bf16 v[28:31], v[192:195], v[224:227], v[28:31]
	v_mfma_f32_16x16x32_bf16 v[24:27], v[192:195], v[232:235], v[24:27]
	v_mfma_f32_16x16x32_bf16 v[20:23], v[200:203], v[224:227], v[20:23]
	v_mfma_f32_16x16x32_bf16 v[16:19], v[200:203], v[232:235], v[16:19]
	ds_read_b128 v[176:179], v172
	v_mfma_f32_16x16x32_bf16 v[12:15], v[208:211], v[224:227], v[12:15]
	v_mfma_f32_16x16x32_bf16 v[8:11], v[208:211], v[232:235], v[8:11]
	ds_read_b128 v[180:183], v172 offset:1024
	v_mfma_f32_16x16x32_bf16 v[4:7], v[216:219], v[224:227], v[4:7]
	v_mfma_f32_16x16x32_bf16 v[0:3], v[216:219], v[232:235], v[0:3]
	ds_read_b128 v[184:187], v172 offset:2048
	v_mfma_f32_16x16x32_bf16 v[28:31], v[196:199], v[228:231], v[28:31]
	v_mfma_f32_16x16x32_bf16 v[24:27], v[196:199], v[236:239], v[24:27]
	ds_read_b128 v[188:191], v172 offset:3072
	v_mfma_f32_16x16x32_bf16 v[20:23], v[204:207], v[228:231], v[20:23]
	v_mfma_f32_16x16x32_bf16 v[16:19], v[204:207], v[236:239], v[16:19]
	v_mfma_f32_16x16x32_bf16 v[12:15], v[212:215], v[228:231], v[12:15]
	v_mfma_f32_16x16x32_bf16 v[8:11], v[212:215], v[236:239], v[8:11]
	v_mfma_f32_16x16x32_bf16 v[4:7], v[220:223], v[228:231], v[4:7]
	v_mfma_f32_16x16x32_bf16 v[0:3], v[220:223], v[236:239], v[0:3]
	s_barrier
	s_setprio 0
	s_add_i32 s53, s53, 2
	s_add_u32 s58, s58, 0x100
	s_addc_u32 s59, s59, 0
	s_cmp_lt_u32 s53, 28
	s_cbranch_scc1 .LBB0_760
	s_add_u32 s56, s56, 0x80f80
	s_addc_u32 s57, s57, 0
	v_readfirstlane_b32 s53, v173
	v_lshl_add_u64 v[166:167], s[56:57], 0, v[134:135]
	s_mov_b32 m0, s53
	v_readfirstlane_b32 s53, v174
	ds_read_b128 v[128:131], v172
	ds_read_b128 v[142:145], v172 offset:1024
	ds_read_b128 v[158:161], v172 offset:2048
	ds_read_b128 v[162:165], v172 offset:3072
	ds_read_b128 v[176:179], v154
	ds_read_b128 v[180:183], v154 offset:1024
	ds_read_b128 v[184:187], v153
	ds_read_b128 v[188:191], v153 offset:1024
	ds_read_b128 v[192:195], v152
	ds_read_b128 v[196:199], v152 offset:1024
	ds_read_b128 v[200:203], v151
	ds_read_b128 v[204:207], v151 offset:1024
	global_load_lds_dwordx4 v[166:167], off
	v_lshl_add_u64 v[166:167], s[56:57], 0, v[132:133]
	s_mov_b32 m0, s53
	s_nop 0
	global_load_lds_dwordx4 v[166:167], off
	s_setprio 1
	s_barrier
	s_waitcnt lgkmcnt(0)
	v_mfma_f32_16x16x32_bf16 v[124:127], v[176:179], v[128:131], v[124:127]
	v_mfma_f32_16x16x32_bf16 v[120:123], v[176:179], v[158:161], v[120:123]
	v_mfma_f32_16x16x32_bf16 v[108:111], v[192:195], v[128:131], v[108:111]
	v_mfma_f32_16x16x32_bf16 v[104:107], v[192:195], v[158:161], v[104:107]
	v_mfma_f32_16x16x32_bf16 v[124:127], v[180:183], v[142:145], v[124:127]
	v_mfma_f32_16x16x32_bf16 v[120:123], v[180:183], v[162:165], v[120:123]
	v_mfma_f32_16x16x32_bf16 v[116:119], v[184:187], v[128:131], v[116:119]
	v_mfma_f32_16x16x32_bf16 v[112:115], v[184:187], v[158:161], v[112:115]
	v_mfma_f32_16x16x32_bf16 v[108:111], v[196:199], v[142:145], v[108:111]
	v_mfma_f32_16x16x32_bf16 v[104:107], v[196:199], v[162:165], v[104:107]
	v_mfma_f32_16x16x32_bf16 v[100:103], v[200:203], v[128:131], v[100:103]
	v_mfma_f32_16x16x32_bf16 v[96:99], v[200:203], v[158:161], v[96:99]
	v_mfma_f32_16x16x32_bf16 v[170:173], v[188:191], v[142:145], v[116:119]
	v_mfma_f32_16x16x32_bf16 v[208:211], v[188:191], v[162:165], v[112:115]
	v_mfma_f32_16x16x32_bf16 v[212:215], v[204:207], v[142:145], v[100:103]
	v_mfma_f32_16x16x32_bf16 v[216:219], v[204:207], v[162:165], v[96:99]
	s_barrier
	s_setprio 0
	s_nop 1
	ds_read_b128 v[96:99], v169
	ds_read_b128 v[100:103], v169 offset:1024
	ds_read_b128 v[112:115], v169 offset:2048
	ds_read_b128 v[116:119], v169 offset:3072
	s_setprio 1
	s_barrier
; #define LDA(dst, b, h) for (int m = 0; m < 4; ++m) for (int k = 0; k < 2; ++k) \
;     dst[m][k] = *reinterpret_cast<const bf16x8*>((char*)SA(b, h) + lds_byte(wr * 64 + m * 16 + fr, k * 32 + fq * 8))
; #define LDB(dst, b, h) for (int n = 0; n < 2; ++n) for (int k = 0; k < 2; ++k) \
;     dst[n][k] = *reinterpret_cast<const bf16x8*>((char*)SB(b, h) + lds_byte(wc * 32 + n * 16 + fr, k * 32 + fq * 8))
; #define MMA(ai, bj, At, Bt) do { __builtin_amdgcn_s_setprio(1); \
;     for (int m = 0; m < 4; ++m) for (int n = 0; n < 2; ++n) for (int k = 0; k < 2; ++k) \
;       acc[ai][bj][m][n] = __builtin_amdgcn_mfma_f32_16x16x32_bf16(At[m][k], Bt[n][k], acc[ai][bj][m][n], 0, 0, 0); \
;     __builtin_amdgcn_s_setprio(0); } while (0)
; #define WAIT_V(n) asm volatile("s_waitcnt vmcnt(" #n ")" ::: "memory")
; #define WAIT_L(n) asm volatile("s_waitcnt lgkmcnt(" #n ")" ::: "memory")
; #define BAR __builtin_amdgcn_s_barrier()
; template <int EPI> ...
;     ...
;     LDB(B1, 0, 1); BAR; WAIT_L(0); MMA(0, 1, At, B1); BAR;
;     LDA(At, 0, 1); WAIT_V(4); BAR; WAIT_L(0); MMA(1, 0, At, B0); MMA(1, 1, At, B1); BAR; }
;   { LDB(B0, 1, 0); LDA(At, 1, 0); WAIT_V(2); BAR; WAIT_L(0); MMA(0, 0, At, B0); BAR;
;     LDB(B1, 1, 1); WAIT_V(0); BAR; WAIT_L(0); MMA(0, 1, At, B1); BAR;
	s_waitcnt lgkmcnt(0)
	v_mfma_f32_16x16x32_bf16 v[92:95], v[176:179], v[96:99], v[92:95]
	v_mfma_f32_16x16x32_bf16 v[88:91], v[176:179], v[112:115], v[88:91]
	v_mfma_f32_16x16x32_bf16 v[76:79], v[192:195], v[96:99], v[76:79]
	v_mfma_f32_16x16x32_bf16 v[72:75], v[192:195], v[112:115], v[72:75]
	v_mfma_f32_16x16x32_bf16 v[92:95], v[180:183], v[100:103], v[92:95]
	v_mfma_f32_16x16x32_bf16 v[88:91], v[180:183], v[116:119], v[88:91]
	v_mfma_f32_16x16x32_bf16 v[84:87], v[184:187], v[96:99], v[84:87]
	v_mfma_f32_16x16x32_bf16 v[80:83], v[184:187], v[112:115], v[80:83]
	v_mfma_f32_16x16x32_bf16 v[76:79], v[196:199], v[100:103], v[76:79]
	v_mfma_f32_16x16x32_bf16 v[72:75], v[196:199], v[116:119], v[72:75]
	v_mfma_f32_16x16x32_bf16 v[68:71], v[200:203], v[96:99], v[68:71]
	v_mfma_f32_16x16x32_bf16 v[64:67], v[200:203], v[112:115], v[64:67]
	v_mfma_f32_16x16x32_bf16 v[166:169], v[188:191], v[100:103], v[84:87]
	v_mfma_f32_16x16x32_bf16 v[174:177], v[188:191], v[116:119], v[80:83]
	v_mfma_f32_16x16x32_bf16 v[178:181], v[204:207], v[100:103], v[68:71]
	v_mfma_f32_16x16x32_bf16 v[182:185], v[204:207], v[116:119], v[64:67]
	s_barrier
	s_setprio 0
	s_nop 1
	ds_read_b128 v[64:67], v154 offset:16384
	ds_read_b128 v[68:71], v154 offset:17408
	ds_read_b128 v[80:83], v153 offset:16384
	ds_read_b128 v[84:87], v153 offset:17408
	ds_read_b128 v[186:189], v152 offset:16384
	ds_read_b128 v[190:193], v152 offset:17408
	ds_read_b128 v[194:197], v151 offset:16384
	ds_read_b128 v[198:201], v151 offset:17408
	s_waitcnt vmcnt(4)
	s_setprio 1
	s_barrier
	s_waitcnt lgkmcnt(0)
	v_mfma_f32_16x16x32_bf16 v[60:63], v[64:67], v[128:131], v[60:63]
	v_mfma_f32_16x16x32_bf16 v[52:55], v[80:83], v[128:131], v[52:55]
	v_mfma_f32_16x16x32_bf16 v[44:47], v[186:189], v[128:131], v[44:47]
	v_mfma_f32_16x16x32_bf16 v[36:39], v[194:197], v[128:131], v[36:39]
	v_mfma_f32_16x16x32_bf16 v[60:63], v[68:71], v[142:145], v[60:63]
	v_mfma_f32_16x16x32_bf16 v[56:59], v[64:67], v[158:161], v[56:59]
	v_mfma_f32_16x16x32_bf16 v[52:55], v[84:87], v[142:145], v[52:55]
	v_mfma_f32_16x16x32_bf16 v[48:51], v[80:83], v[158:161], v[48:51]
	v_mfma_f32_16x16x32_bf16 v[44:47], v[190:193], v[142:145], v[44:47]
	v_mfma_f32_16x16x32_bf16 v[40:43], v[186:189], v[158:161], v[40:43]
	v_mfma_f32_16x16x32_bf16 v[36:39], v[198:201], v[142:145], v[36:39]
	v_mfma_f32_16x16x32_bf16 v[32:35], v[194:197], v[158:161], v[32:35]
	v_mfma_f32_16x16x32_bf16 v[202:205], v[68:71], v[162:165], v[56:59]
	v_mfma_f32_16x16x32_bf16 v[220:223], v[84:87], v[162:165], v[48:51]
	v_mfma_f32_16x16x32_bf16 v[224:227], v[190:193], v[162:165], v[40:43]
	v_mfma_f32_16x16x32_bf16 v[128:131], v[198:201], v[162:165], v[32:35]
	s_setprio 0
	s_setprio 1
	v_mfma_f32_16x16x32_bf16 v[28:31], v[64:67], v[96:99], v[28:31]
	v_mfma_f32_16x16x32_bf16 v[20:23], v[80:83], v[96:99], v[20:23]
	v_mfma_f32_16x16x32_bf16 v[12:15], v[186:189], v[96:99], v[12:15]
	v_mfma_f32_16x16x32_bf16 v[4:7], v[194:197], v[96:99], v[4:7]
	v_mfma_f32_16x16x32_bf16 v[28:31], v[68:71], v[100:103], v[28:31]
	v_mfma_f32_16x16x32_bf16 v[24:27], v[64:67], v[112:115], v[24:27]
	v_mfma_f32_16x16x32_bf16 v[20:23], v[84:87], v[100:103], v[20:23]
	v_mfma_f32_16x16x32_bf16 v[16:19], v[80:83], v[112:115], v[16:19]
	v_mfma_f32_16x16x32_bf16 v[12:15], v[190:193], v[100:103], v[12:15]
	v_mfma_f32_16x16x32_bf16 v[8:11], v[186:189], v[112:115], v[8:11]
	v_mfma_f32_16x16x32_bf16 v[4:7], v[198:201], v[100:103], v[4:7]
	v_mfma_f32_16x16x32_bf16 v[0:3], v[194:197], v[112:115], v[0:3]
	v_mfma_f32_16x16x32_bf16 v[142:145], v[68:71], v[116:119], v[24:27]
	v_mfma_f32_16x16x32_bf16 v[158:161], v[84:87], v[116:119], v[16:19]
	v_mfma_f32_16x16x32_bf16 v[162:165], v[190:193], v[116:119], v[8:11]
	v_mfma_f32_16x16x32_bf16 v[186:189], v[198:201], v[116:119], v[0:3]
	s_barrier
	s_setprio 0
	s_nop 1
	ds_read_b128 v[0:3], v157
	ds_read_b128 v[8:11], v157 offset:1024
	ds_read_b128 v[190:193], v157 offset:2048
	ds_read_b128 v[194:197], v157 offset:3072
	ds_read_b128 v[16:19], v154 offset:32768
	ds_read_b128 v[24:27], v154 offset:33792
	ds_read_b128 v[32:35], v153 offset:32768
	ds_read_b128 v[40:43], v153 offset:33792
	ds_read_b128 v[48:51], v152 offset:32768
	ds_read_b128 v[56:59], v152 offset:33792
	ds_read_b128 v[198:201], v151 offset:32768
	ds_read_b128 v[228:231], v151 offset:33792
	s_waitcnt vmcnt(2)
	s_setprio 1
	s_barrier
	s_waitcnt lgkmcnt(0)
	v_mfma_f32_16x16x32_bf16 v[64:67], v[16:19], v[0:3], v[124:127]
	v_mfma_f32_16x16x32_bf16 v[116:119], v[24:27], v[8:11], v[64:67]
	v_mfma_f32_16x16x32_bf16 v[64:67], v[16:19], v[190:193], v[120:123]
	v_mfma_f32_16x16x32_bf16 v[112:115], v[24:27], v[194:197], v[64:67]
	v_mfma_f32_16x16x32_bf16 v[64:67], v[32:35], v[0:3], v[170:173]
	v_mfma_f32_16x16x32_bf16 v[100:103], v[40:43], v[8:11], v[64:67]
	v_mfma_f32_16x16x32_bf16 v[64:67], v[32:35], v[190:193], v[208:211]
	v_mfma_f32_16x16x32_bf16 v[96:99], v[40:43], v[194:197], v[64:67]
	v_mfma_f32_16x16x32_bf16 v[64:67], v[48:51], v[0:3], v[108:111]
	v_mfma_f32_16x16x32_bf16 v[84:87], v[56:59], v[8:11], v[64:67]
	v_mfma_f32_16x16x32_bf16 v[64:67], v[48:51], v[190:193], v[104:107]
	v_mfma_f32_16x16x32_bf16 v[80:83], v[56:59], v[194:197], v[64:67]
	v_mfma_f32_16x16x32_bf16 v[64:67], v[198:201], v[0:3], v[212:215]
	v_mfma_f32_16x16x32_bf16 v[68:71], v[228:231], v[8:11], v[64:67]
	v_mfma_f32_16x16x32_bf16 v[64:67], v[198:201], v[190:193], v[216:219]
	v_mfma_f32_16x16x32_bf16 v[64:67], v[228:231], v[194:197], v[64:67]
	s_barrier
	s_setprio 0
	ds_read_b128 v[170:173], v155
	ds_read_b128 v[206:209], v155 offset:1024
	ds_read_b128 v[210:213], v155 offset:2048
	ds_read_b128 v[214:217], v155 offset:3072
	s_waitcnt vmcnt(0)
	s_setprio 1
	s_barrier
; #define LDA(dst, b, h) for (int m = 0; m < 4; ++m) for (int k = 0; k < 2; ++k) \
;     dst[m][k] = *reinterpret_cast<const bf16x8*>((char*)SA(b, h) + lds_byte(wr * 64 + m * 16 + fr, k * 32 + fq * 8))
; #define LDB(dst, b, h) for (int n = 0; n < 2; ++n) for (int k = 0; k < 2; ++k) \
;     dst[n][k] = *reinterpret_cast<const bf16x8*>((char*)SB(b, h) + lds_byte(wc * 32 + n * 16 + fr, k * 32 + fq * 8))
; #define MMA(ai, bj, At, Bt) do { __builtin_amdgcn_s_setprio(1); \
;     for (int m = 0; m < 4; ++m) for (int n = 0; n < 2; ++n) for (int k = 0; k < 2; ++k) \
;       acc[ai][bj][m][n] = __builtin_amdgcn_mfma_f32_16x16x32_bf16(At[m][k], Bt[n][k], acc[ai][bj][m][n], 0, 0, 0); \
;     __builtin_amdgcn_s_setprio(0); } while (0)
; #define WAIT_V(n) asm volatile("s_waitcnt vmcnt(" #n ")" ::: "memory")
; #define WAIT_L(n) asm volatile("s_waitcnt lgkmcnt(" #n ")" ::: "memory")
; #define BAR __builtin_amdgcn_s_barrier()
; template <int EPI> ...
;     ...
;     LDB(B1, 1, 1); WAIT_V(0); BAR; WAIT_L(0); MMA(0, 1, At, B1); BAR;
;     LDA(At, 1, 1); BAR; WAIT_L(0); MMA(1, 0, At, B0); MMA(1, 1, At, B1); BAR; }
;   if (wr == 0) BAR;
;   {
;     constexpr int NC = (EPI == EPI_GU) ? 128 : 256;
;     constexpr int RB = NC * 2;
;     char* tb = (char*)shm;
; #pragma unroll
;     for (int ai = 0; ai < 2; ++ai)
; #pragma unroll
;       for (int m = 0; m < 4; ++m)
; #pragma unroll
;         for (int j = 0; j < 4; ++j) {
;           const int r = ai * 128 + wr * 64 + m * 16 + fq * 4 + j;
;           float rs = 1.0f;
;           if (EPI != EPI_RES) rs = e.rstd[brow + r];
;           char* rowp = tb + r * RB + fr * 2;
	s_waitcnt lgkmcnt(0)
	v_mfma_f32_16x16x32_bf16 v[92:95], v[16:19], v[170:173], v[92:95]
	v_mfma_f32_16x16x32_bf16 v[16:19], v[16:19], v[210:213], v[88:91]
	v_mfma_f32_16x16x32_bf16 v[120:123], v[24:27], v[214:217], v[16:19]
	v_mfma_f32_16x16x32_bf16 v[16:19], v[32:35], v[170:173], v[166:169]
	v_mfma_f32_16x16x32_bf16 v[108:111], v[40:43], v[206:209], v[16:19]
	v_mfma_f32_16x16x32_bf16 v[16:19], v[32:35], v[210:213], v[174:177]
	v_mfma_f32_16x16x32_bf16 v[104:107], v[40:43], v[214:217], v[16:19]
	v_mfma_f32_16x16x32_bf16 v[16:19], v[48:51], v[170:173], v[76:79]
	v_mfma_f32_16x16x32_bf16 v[124:127], v[24:27], v[206:209], v[92:95]
	v_mfma_f32_16x16x32_bf16 v[92:95], v[56:59], v[206:209], v[16:19]
	v_mfma_f32_16x16x32_bf16 v[16:19], v[48:51], v[210:213], v[72:75]
	v_mfma_f32_16x16x32_bf16 v[88:91], v[56:59], v[214:217], v[16:19]
	v_mfma_f32_16x16x32_bf16 v[16:19], v[198:201], v[170:173], v[178:181]
	v_mfma_f32_16x16x32_bf16 v[76:79], v[228:231], v[206:209], v[16:19]
	v_mfma_f32_16x16x32_bf16 v[16:19], v[198:201], v[210:213], v[182:185]
	v_mfma_f32_16x16x32_bf16 v[72:75], v[228:231], v[214:217], v[16:19]
	s_barrier
	s_setprio 0
	ds_read_b128 v[166:169], v154 offset:49152
	ds_read_b128 v[154:157], v154 offset:50176
	ds_read_b128 v[174:177], v153 offset:49152
	ds_read_b128 v[178:181], v153 offset:50176
	ds_read_b128 v[182:185], v152 offset:49152
	ds_read_b128 v[198:201], v152 offset:50176
	ds_read_b128 v[228:231], v151 offset:49152
	ds_read_b128 v[232:235], v151 offset:50176
	s_setprio 1
	s_barrier
	s_waitcnt lgkmcnt(0)
	v_mfma_f32_16x16x32_bf16 v[16:19], v[166:169], v[0:3], v[60:63]
	v_mfma_f32_16x16x32_bf16 v[56:59], v[154:157], v[8:11], v[16:19]
	v_mfma_f32_16x16x32_bf16 v[16:19], v[166:169], v[190:193], v[202:205]
	v_mfma_f32_16x16x32_bf16 v[48:51], v[154:157], v[194:197], v[16:19]
	v_mfma_f32_16x16x32_bf16 v[16:19], v[174:177], v[0:3], v[52:55]
	v_mfma_f32_16x16x32_bf16 v[40:43], v[178:181], v[8:11], v[16:19]
	v_mfma_f32_16x16x32_bf16 v[16:19], v[174:177], v[190:193], v[220:223]
	v_mfma_f32_16x16x32_bf16 v[32:35], v[178:181], v[194:197], v[16:19]
	v_mfma_f32_16x16x32_bf16 v[16:19], v[182:185], v[0:3], v[44:47]
	v_mfma_f32_16x16x32_bf16 v[0:3], v[228:231], v[0:3], v[36:39]
	v_mfma_f32_16x16x32_bf16 v[24:27], v[198:201], v[8:11], v[16:19]
	v_mfma_f32_16x16x32_bf16 v[16:19], v[182:185], v[190:193], v[224:227]
	v_mfma_f32_16x16x32_bf16 v[8:11], v[232:235], v[8:11], v[0:3]
	v_mfma_f32_16x16x32_bf16 v[0:3], v[228:231], v[190:193], v[128:131]
	v_mfma_f32_16x16x32_bf16 v[16:19], v[198:201], v[194:197], v[16:19]
	v_mfma_f32_16x16x32_bf16 v[0:3], v[232:235], v[194:197], v[0:3]
	s_setprio 0
	s_setprio 1
	v_mfma_f32_16x16x32_bf16 v[28:31], v[166:169], v[170:173], v[28:31]
	v_mfma_f32_16x16x32_bf16 v[60:63], v[154:157], v[206:209], v[28:31]
	v_mfma_f32_16x16x32_bf16 v[28:31], v[166:169], v[210:213], v[142:145]
	v_mfma_f32_16x16x32_bf16 v[20:23], v[174:177], v[170:173], v[20:23]
	v_mfma_f32_16x16x32_bf16 v[12:15], v[182:185], v[170:173], v[12:15]
	v_mfma_f32_16x16x32_bf16 v[52:55], v[154:157], v[214:217], v[28:31]
	v_mfma_f32_16x16x32_bf16 v[44:47], v[178:181], v[206:209], v[20:23]
	v_mfma_f32_16x16x32_bf16 v[20:23], v[174:177], v[210:213], v[158:161]
	v_mfma_f32_16x16x32_bf16 v[28:31], v[198:201], v[206:209], v[12:15]
	v_mfma_f32_16x16x32_bf16 v[12:15], v[182:185], v[210:213], v[162:165]
	v_mfma_f32_16x16x32_bf16 v[4:7], v[228:231], v[170:173], v[4:7]
	v_mfma_f32_16x16x32_bf16 v[36:39], v[178:181], v[214:217], v[20:23]
	v_mfma_f32_16x16x32_bf16 v[20:23], v[198:201], v[214:217], v[12:15]
	v_mfma_f32_16x16x32_bf16 v[12:15], v[232:235], v[206:209], v[4:7]
	v_mfma_f32_16x16x32_bf16 v[4:7], v[228:231], v[210:213], v[186:189]
	v_mfma_f32_16x16x32_bf16 v[4:7], v[232:235], v[214:217], v[4:7]
	s_barrier
	s_setprio 0
	v_cmp_gt_u32_e32 vcc, s86, v136
	s_and_saveexec_b64 s[56:57], vcc
	s_cbranch_execz .LBB0_763
	s_barrier
.LBB0_763:
	s_or_b64 exec, exec, s[56:57]
	v_lshl_or_b32 v145, v147, 2, v150
	v_add_u32_e32 v128, s54, v145
	v_ashrrev_i32_e32 v129, 31, v128
	v_lshl_add_u64 v[128:129], v[128:129], 2, s[0:1]
	global_load_dwordx4 v[150:153], v[128:129], off
	v_lshl_add_u32 v144, v149, 1, 0
	v_lshlrev_b32_e32 v128, 1, v148
	v_lshl_add_u32 v136, v145, 8, v144
	v_xor_b32_e32 v129, v128, v147
	v_bitop3_b32 v128, v128, v147, 1 bitop3:0x36
	v_or_b32_e32 v147, 16, v145
	v_lshlrev_b32_e32 v143, 5, v129
	v_lshlrev_b32_e32 v142, 5, v128
	v_add_u32_e32 v129, 0x100, v136
	v_add_u32_e32 v128, s54, v147
	v_add_u32_e32 v155, v129, v143
	v_add_u32_e32 v156, v129, v142
	v_ashrrev_i32_e32 v129, 31, v128
	v_lshl_add_u64 v[128:129], v[128:129], 2, s[0:1]
	global_load_dwordx4 v[128:131], v[128:129], off
	v_add_u32_e32 v148, 0x200, v136
	v_add_u32_e32 v149, v136, v143
	v_add_u32_e32 v154, v136, v142
	v_add_u32_e32 v157, v148, v143
	s_add_i32 s53, s89, 0xffffff75
	s_ashr_i32 s55, s89, 31
	s_cmpk_lt_i32 s89, 0x8b
	s_cselect_b32 s53, s89, s53
	s_cselect_b32 s55, s55, 0
	s_mul_i32 s55, s55, 0x2c0000
	s_mul_hi_u32 s58, s53, 0x2c0000
	s_cselect_b32 s57, s73, s67
	s_cselect_b32 s56, s72, s66
	s_mul_i32 s53, s53, 0x2c0000
	s_add_i32 s58, s58, s55
	s_add_u32 s56, s56, s53
	s_addc_u32 s57, s57, s58
	s_waitcnt vmcnt(0)
; __device__ __forceinline__ u16 f2bf(float f) { unsigned u = __float_as_uint(f); u += 0x7fffu + ((u >> 16) & 1u); return (u16)(u >> 16); }
; __device__ __forceinline__ float frcp(float x) { return __builtin_amdgcn_rcpf(x); }
; template <int EPI> ...
;     ...
;           const int r = ai * 128 + wr * 64 + m * 16 + fq * 4 + j;
;           float rs = 1.0f;
;           if (EPI != EPI_RES) rs = e.rstd[brow + r];
;           char* rowp = tb + r * RB + fr * 2;
;           if (EPI == EPI_GU) {
; #pragma unroll
;             for (int n = 0; n < 2; ++n) {
;               float g = acc[ai][0][m][n][j] * rs, u = acc[ai][1][m][n][j] * rs;
;               float h = g * frcp(1.0f + __expf(-g)) * u;
;               const int seg = (wc * 2 + n) ^ fq;
;               *(u16*)(rowp + seg * 32) = f2bf(h);
;             }
	v_mul_f32_e32 v116, v116, v150
	v_mul_f32_e32 v112, v112, v150
	v_mul_f32_e32 v124, v124, v150
	v_mul_f32_e32 v120, v120, v150
	v_mul_f32_e32 v117, v117, v151
	v_mul_f32_e32 v125, v125, v151
	v_mul_f32_e32 v113, v113, v151
	v_mul_f32_e32 v121, v121, v151
	v_mul_f32_e32 v118, v118, v152
	v_mul_f32_e32 v150, 0xbfb8aa3b, v116
	v_mul_f32_e32 v151, 0xbfb8aa3b, v112
	v_mul_f32_e32 v126, v126, v152
	v_mul_f32_e32 v114, v114, v152
	v_mul_f32_e32 v122, v122, v152
	v_mul_f32_e32 v152, 0xbfb8aa3b, v117
	v_mul_f32_e32 v158, 0xbfb8aa3b, v113
	v_mul_f32_e32 v159, 0xbfb8aa3b, v118
	v_exp_f32_e32 v150, v150
	v_exp_f32_e32 v151, v151
	v_mul_f32_e32 v160, 0xbfb8aa3b, v114
	v_exp_f32_e32 v152, v152
	v_exp_f32_e32 v158, v158
	v_exp_f32_e32 v159, v159
	v_exp_f32_e32 v160, v160
	v_add_f32_e32 v150, 1.0, v150
	v_add_f32_e32 v151, 1.0, v151
	v_add_f32_e32 v152, 1.0, v152
	v_add_f32_e32 v158, 1.0, v158
	v_add_f32_e32 v159, 1.0, v159
	v_rcp_f32_e32 v150, v150
	v_rcp_f32_e32 v151, v151
	v_add_f32_e32 v160, 1.0, v160
	v_rcp_f32_e32 v152, v152
	v_rcp_f32_e32 v158, v158
	v_rcp_f32_e32 v159, v159
	v_rcp_f32_e32 v160, v160
	v_mul_f32_e32 v116, v116, v150
	v_mul_f32_e32 v112, v112, v151
	v_mul_f32_e32 v117, v117, v152
	v_mul_f32_e32 v113, v113, v158
	v_mul_f32_e32 v118, v118, v159
	v_mul_f32_e32 v116, v124, v116
	v_mul_f32_e32 v112, v120, v112
	v_mul_f32_e32 v114, v114, v160
	v_mul_f32_e32 v117, v125, v117
	v_mul_f32_e32 v113, v121, v113
	v_mul_f32_e32 v118, v126, v118
	v_mul_f32_e32 v114, v122, v114
	v_cvt_pk_bf16_f32 v116, v116, v116
	v_cvt_pk_bf16_f32 v112, v112, v112
	v_cvt_pk_bf16_f32 v117, v117, v117
	v_cvt_pk_bf16_f32 v113, v113, v113
	v_cvt_pk_bf16_f32 v118, v118, v118
	ds_write_b16_d16_hi v149, v116
	ds_write_b16_d16_hi v154, v112
	ds_write_b16_d16_hi v155, v117
	ds_write_b16_d16_hi v156, v113
	ds_write_b16_d16_hi v157, v118
	v_mul_f32_e32 v112, v119, v153
	v_mul_f32_e32 v113, 0xbfb8aa3b, v112
	v_exp_f32_e32 v113, v113
	v_cvt_pk_bf16_f32 v114, v114, v114
	v_add_u32_e32 v116, v148, v142
	v_add_f32_e32 v113, 1.0, v113
	v_rcp_f32_e32 v113, v113
	ds_write_b16_d16_hi v116, v114
	v_mul_f32_e32 v116, v127, v153
	v_add_u32_e32 v114, 0x300, v136
	v_mul_f32_e32 v112, v112, v113
	v_mul_f32_e32 v113, v115, v153
	v_mul_f32_e32 v115, 0xbfb8aa3b, v113
	v_exp_f32_e32 v115, v115
	v_mul_f32_e32 v112, v116, v112
	v_cvt_pk_bf16_f32 v112, v112, v112
	v_add_f32_e32 v115, 1.0, v115
	v_rcp_f32_e32 v115, v115
	v_add_u32_e32 v116, v114, v143
	ds_write_b16_d16_hi v116, v112
	v_mul_f32_e32 v112, v123, v153
	v_mul_f32_e32 v113, v113, v115
	v_mul_f32_e32 v100, v100, v128
	v_mul_f32_e32 v112, v112, v113
	v_mul_f32_e32 v113, 0xbfb8aa3b, v100
	v_exp_f32_e32 v113, v113
	v_bfe_u32 v115, v112, 16, 1
	v_add3_u32 v112, v112, v115, s87
	v_add_u32_e32 v114, v114, v142
	v_add_f32_e32 v113, 1.0, v113
	v_rcp_f32_e32 v113, v113
	v_mul_f32_e32 v96, v96, v128
	ds_write_b16_d16_hi v114, v112
	v_mul_f32_e32 v112, 0xbfb8aa3b, v96
	v_exp_f32_e32 v112, v112
	v_mul_f32_e32 v108, v108, v128
	v_mul_f32_e32 v100, v100, v113
	v_mul_f32_e32 v100, v108, v100
	v_cvt_pk_bf16_f32 v100, v100, v100
	v_add_f32_e32 v108, 1.0, v112
	v_rcp_f32_e32 v108, v108
	v_lshl_add_u32 v116, v147, 8, v144
	v_add_u32_e32 v112, v116, v143
	ds_write_b16_d16_hi v112, v100
	v_mul_f32_e32 v100, v104, v128
	v_mul_f32_e32 v96, v96, v108
	v_or_b32_e32 v108, 32, v145
	v_mul_f32_e32 v96, v100, v96
	v_add_u32_e32 v100, s54, v108
	v_mul_f32_e32 v104, v101, v129
	v_ashrrev_i32_e32 v101, 31, v100
	v_lshl_add_u64 v[100:101], v[100:101], 2, s[0:1]
	global_load_dwordx4 v[112:115], v[100:101], off
	v_mul_f32_e32 v100, 0xbfb8aa3b, v104
	v_exp_f32_e32 v100, v100
	v_mul_f32_e32 v97, v97, v129
	v_cvt_pk_bf16_f32 v96, v96, v96
	v_add_f32_e32 v100, 1.0, v100
	v_rcp_f32_e32 v100, v100
	v_add_u32_e32 v101, v116, v142
	ds_write_b16_d16_hi v101, v96
	v_mul_f32_e32 v101, v109, v129
	v_mul_f32_e32 v100, v104, v100
	v_mul_f32_e32 v104, 0xbfb8aa3b, v97
	v_exp_f32_e32 v104, v104
	v_mul_f32_e32 v100, v101, v100
	v_cvt_pk_bf16_f32 v100, v100, v100
	v_add_f32_e32 v101, 1.0, v104
	v_rcp_f32_e32 v101, v101
	v_add_u32_e32 v96, 0x1100, v136
	v_add_u32_e32 v104, v96, v143
	ds_write_b16_d16_hi v104, v100
	v_mul_f32_e32 v100, v105, v129
	v_mul_f32_e32 v97, v97, v101
	v_mul_f32_e32 v97, v100, v97
	v_mul_f32_e32 v100, v102, v130
	v_mul_f32_e32 v101, 0xbfb8aa3b, v100
	v_exp_f32_e32 v101, v101
	v_mul_f32_e32 v98, v98, v130
	v_cvt_pk_bf16_f32 v97, v97, v97
	v_add_f32_e32 v101, 1.0, v101
	v_rcp_f32_e32 v101, v101
	v_add_u32_e32 v96, v96, v142
	ds_write_b16_d16_hi v96, v97
	v_mul_f32_e32 v97, v110, v130
	v_mul_f32_e32 v100, v100, v101
	v_mul_f32_e32 v101, 0xbfb8aa3b, v98
	v_exp_f32_e32 v101, v101
	v_mul_f32_e32 v97, v97, v100
	v_cvt_pk_bf16_f32 v97, v97, v97
	v_add_f32_e32 v100, 1.0, v101
	v_rcp_f32_e32 v100, v100
	v_add_u32_e32 v96, 0x1200, v136
	v_add_u32_e32 v101, v96, v143
	ds_write_b16_d16_hi v101, v97
	v_mul_f32_e32 v97, v106, v130
	v_mul_f32_e32 v98, v98, v100
	v_mul_f32_e32 v97, v97, v98
	v_mul_f32_e32 v98, v103, v131
	v_mul_f32_e32 v100, 0xbfb8aa3b, v98
	v_exp_f32_e32 v100, v100
	v_cvt_pk_bf16_f32 v97, v97, v97
	v_add_u32_e32 v96, v96, v142
	v_add_f32_e32 v100, 1.0, v100
	v_rcp_f32_e32 v100, v100
	ds_write_b16_d16_hi v96, v97
	v_mul_f32_e32 v96, v111, v131
	v_add_u32_e32 v101, 0x1300, v136
	v_mul_f32_e32 v97, v98, v100
	v_mul_f32_e32 v98, v99, v131
	v_mul_f32_e32 v99, 0xbfb8aa3b, v98
	v_exp_f32_e32 v99, v99
	v_mul_f32_e32 v96, v96, v97
	v_cvt_pk_bf16_f32 v96, v96, v96
	v_add_f32_e32 v97, 1.0, v99
	v_rcp_f32_e32 v97, v97
	v_add_u32_e32 v99, v101, v143
	ds_write_b16_d16_hi v99, v96
	v_mul_f32_e32 v96, v107, v131
	v_mul_f32_e32 v97, v98, v97
	v_or_b32_e32 v102, 48, v145
	v_mul_f32_e32 v100, v96, v97
	v_add_u32_e32 v96, s54, v102
	v_ashrrev_i32_e32 v97, 31, v96
	v_lshl_add_u64 v[96:97], v[96:97], 2, s[0:1]
	global_load_dwordx4 v[96:99], v[96:97], off
	s_waitcnt vmcnt(1)
; __device__ __forceinline__ u16 f2bf(float f) { unsigned u = __float_as_uint(f); u += 0x7fffu + ((u >> 16) & 1u); return (u16)(u >> 16); }
; __device__ __forceinline__ float frcp(float x) { return __builtin_amdgcn_rcpf(x); }
; template <int EPI> ...
;     ...
;           const int r = ai * 128 + wr * 64 + m * 16 + fq * 4 + j;
;           float rs = 1.0f;
;           if (EPI != EPI_RES) rs = e.rstd[brow + r];
;           char* rowp = tb + r * RB + fr * 2;
;           if (EPI == EPI_GU) {
; #pragma unroll
;             for (int n = 0; n < 2; ++n) {
;               float g = acc[ai][0][m][n][j] * rs, u = acc[ai][1][m][n][j] * rs;
;               float h = g * frcp(1.0f + __expf(-g)) * u;
;               const int seg = (wc * 2 + n) ^ fq;
;               *(u16*)(rowp + seg * 32) = f2bf(h);
;             }
	v_mul_f32_e32 v84, v84, v112
	v_mul_f32_e32 v103, 0xbfb8aa3b, v84
	v_exp_f32_e32 v103, v103
	v_cvt_pk_bf16_f32 v100, v100, v100
	v_add_u32_e32 v101, v101, v142
	v_add_f32_e32 v103, 1.0, v103
	v_rcp_f32_e32 v103, v103
	v_mul_f32_e32 v80, v80, v112
	ds_write_b16_d16_hi v101, v100
	v_mul_f32_e32 v101, 0xbfb8aa3b, v80
	v_exp_f32_e32 v101, v101
	v_mul_f32_e32 v92, v92, v112
	v_mul_f32_e32 v84, v84, v103
	v_mul_f32_e32 v84, v92, v84
	v_cvt_pk_bf16_f32 v84, v84, v84
	v_add_f32_e32 v92, 1.0, v101
	v_rcp_f32_e32 v92, v92
	v_lshl_add_u32 v100, v108, 8, v144
	v_add_u32_e32 v101, v100, v143
	ds_write_b16_d16_hi v101, v84
	v_mul_f32_e32 v84, v88, v112
	v_mul_f32_e32 v80, v80, v92
	v_mul_f32_e32 v80, v84, v80
	v_mul_f32_e32 v84, v85, v113
	v_mul_f32_e32 v85, 0xbfb8aa3b, v84
	v_exp_f32_e32 v85, v85
	v_mul_f32_e32 v81, v81, v113
	v_cvt_pk_bf16_f32 v80, v80, v80
	v_add_f32_e32 v85, 1.0, v85
	v_rcp_f32_e32 v85, v85
	v_add_u32_e32 v88, v100, v142
	ds_write_b16_d16_hi v88, v80
	v_mul_f32_e32 v88, v93, v113
	v_mul_f32_e32 v84, v84, v85
	v_mul_f32_e32 v85, 0xbfb8aa3b, v81
	v_exp_f32_e32 v85, v85
	v_mul_f32_e32 v84, v88, v84
	v_add_u32_e32 v80, 0x2100, v136
	v_add_f32_e32 v85, 1.0, v85
	v_rcp_f32_e32 v85, v85
	v_cvt_pk_bf16_f32 v84, v84, v84
	v_add_u32_e32 v88, v80, v143
	ds_write_b16_d16_hi v88, v84
	v_mul_f32_e32 v84, v89, v113
	v_mul_f32_e32 v81, v81, v85
	v_mul_f32_e32 v81, v84, v81
	v_mul_f32_e32 v84, v86, v114
	v_mul_f32_e32 v85, 0xbfb8aa3b, v84
	v_exp_f32_e32 v85, v85
	v_mul_f32_e32 v82, v82, v114
	v_cvt_pk_bf16_f32 v81, v81, v81
	v_add_f32_e32 v85, 1.0, v85
	v_rcp_f32_e32 v85, v85
	v_add_u32_e32 v80, v80, v142
	ds_write_b16_d16_hi v80, v81
	v_mul_f32_e32 v81, v94, v114
	v_mul_f32_e32 v84, v84, v85
	v_mul_f32_e32 v85, 0xbfb8aa3b, v82
	v_exp_f32_e32 v85, v85
	v_mul_f32_e32 v81, v81, v84
	v_cvt_pk_bf16_f32 v81, v81, v81
	v_add_f32_e32 v84, 1.0, v85
	v_rcp_f32_e32 v84, v84
	v_add_u32_e32 v80, 0x2200, v136
	v_add_u32_e32 v85, v80, v143
	ds_write_b16_d16_hi v85, v81
	v_mul_f32_e32 v81, v90, v114
	v_mul_f32_e32 v82, v82, v84
	v_mul_f32_e32 v81, v81, v82
	v_mul_f32_e32 v82, v87, v115
	v_mul_f32_e32 v84, 0xbfb8aa3b, v82
	v_exp_f32_e32 v84, v84
	v_mul_f32_e32 v83, v83, v115
	v_cvt_pk_bf16_f32 v81, v81, v81
	v_add_f32_e32 v84, 1.0, v84
	v_rcp_f32_e32 v84, v84
	v_add_u32_e32 v80, v80, v142
	ds_write_b16_d16_hi v80, v81
	v_mul_f32_e32 v81, v95, v115
	v_mul_f32_e32 v82, v82, v84
	v_mul_f32_e32 v84, 0xbfb8aa3b, v83
	v_exp_f32_e32 v84, v84
	v_mul_f32_e32 v81, v81, v82
	v_cvt_pk_bf16_f32 v81, v81, v81
	v_add_f32_e32 v82, 1.0, v84
	v_rcp_f32_e32 v82, v82
	v_add_u32_e32 v80, 0x2300, v136
	v_add_u32_e32 v84, v80, v143
	ds_write_b16_d16_hi v84, v81
	v_mul_f32_e32 v81, v91, v115
	v_mul_f32_e32 v82, v83, v82
	s_waitcnt vmcnt(0)
	v_mul_f32_e32 v68, v68, v96
	v_mul_f32_e32 v81, v81, v82
	v_mul_f32_e32 v82, 0xbfb8aa3b, v68
	v_exp_f32_e32 v82, v82
	v_bfe_u32 v83, v81, 16, 1
	v_add3_u32 v81, v81, v83, s87
	v_add_u32_e32 v80, v80, v142
	v_add_f32_e32 v82, 1.0, v82
	v_rcp_f32_e32 v82, v82
	v_mul_f32_e32 v64, v64, v96
	ds_write_b16_d16_hi v80, v81
	v_mul_f32_e32 v80, 0xbfb8aa3b, v64
	v_exp_f32_e32 v80, v80
	v_mul_f32_e32 v76, v76, v96
	v_mul_f32_e32 v68, v68, v82
	v_mul_f32_e32 v68, v76, v68
	v_cvt_pk_bf16_f32 v68, v68, v68
	v_add_f32_e32 v76, 1.0, v80
	v_rcp_f32_e32 v76, v76
	v_lshl_add_u32 v84, v102, 8, v144
	v_add_u32_e32 v80, v84, v143
	ds_write_b16_d16_hi v80, v68
	v_mul_f32_e32 v68, v72, v96
	v_mul_f32_e32 v64, v64, v76
	v_add_u32_e32 v76, 0x80, v145
	v_mul_f32_e32 v64, v68, v64
	v_add_u32_e32 v68, s54, v76
	v_mul_f32_e32 v72, v69, v97
	v_ashrrev_i32_e32 v69, 31, v68
	v_lshl_add_u64 v[68:69], v[68:69], 2, s[0:1]
	global_load_dwordx4 v[80:83], v[68:69], off
	v_mul_f32_e32 v68, 0xbfb8aa3b, v72
	v_exp_f32_e32 v68, v68
	v_mul_f32_e32 v65, v65, v97
	v_cvt_pk_bf16_f32 v64, v64, v64
	v_add_f32_e32 v68, 1.0, v68
	v_rcp_f32_e32 v68, v68
	v_add_u32_e32 v69, v84, v142
	ds_write_b16_d16_hi v69, v64
	v_mul_f32_e32 v69, v77, v97
	v_mul_f32_e32 v68, v72, v68
	v_mul_f32_e32 v72, 0xbfb8aa3b, v65
	v_exp_f32_e32 v72, v72
	v_mul_f32_e32 v68, v69, v68
	v_cvt_pk_bf16_f32 v68, v68, v68
	v_add_f32_e32 v69, 1.0, v72
	v_rcp_f32_e32 v69, v69
	v_add_u32_e32 v64, 0x3100, v136
	v_add_u32_e32 v72, v64, v143
	ds_write_b16_d16_hi v72, v68
	v_mul_f32_e32 v68, v73, v97
	v_mul_f32_e32 v65, v65, v69
	v_mul_f32_e32 v65, v68, v65
	v_mul_f32_e32 v68, v70, v98
	v_mul_f32_e32 v69, 0xbfb8aa3b, v68
	v_exp_f32_e32 v69, v69
	v_mul_f32_e32 v66, v66, v98
	v_cvt_pk_bf16_f32 v65, v65, v65
	v_add_f32_e32 v69, 1.0, v69
	v_rcp_f32_e32 v69, v69
	v_add_u32_e32 v64, v64, v142
	ds_write_b16_d16_hi v64, v65
	v_mul_f32_e32 v65, v78, v98
	v_mul_f32_e32 v68, v68, v69
	v_mul_f32_e32 v69, 0xbfb8aa3b, v66
	v_exp_f32_e32 v69, v69
	v_mul_f32_e32 v65, v65, v68
	v_cvt_pk_bf16_f32 v65, v65, v65
	v_add_f32_e32 v68, 1.0, v69
	v_rcp_f32_e32 v68, v68
	v_add_u32_e32 v64, 0x3200, v136
	v_add_u32_e32 v69, v64, v143
	ds_write_b16_d16_hi v69, v65
	v_mul_f32_e32 v65, v74, v98
	v_mul_f32_e32 v66, v66, v68
	v_mul_f32_e32 v65, v65, v66
	v_mul_f32_e32 v66, v71, v99
	v_mul_f32_e32 v68, 0xbfb8aa3b, v66
	v_exp_f32_e32 v68, v68
	v_cvt_pk_bf16_f32 v65, v65, v65
	v_add_u32_e32 v64, v64, v142
	v_add_f32_e32 v68, 1.0, v68
	v_rcp_f32_e32 v68, v68
	ds_write_b16_d16_hi v64, v65
	v_mul_f32_e32 v64, v79, v99
	v_add_u32_e32 v69, 0x3300, v136
	v_mul_f32_e32 v65, v66, v68
	v_mul_f32_e32 v66, v67, v99
	v_mul_f32_e32 v67, 0xbfb8aa3b, v66
	v_exp_f32_e32 v67, v67
	v_mul_f32_e32 v64, v64, v65
	v_cvt_pk_bf16_f32 v64, v64, v64
	v_add_f32_e32 v65, 1.0, v67
	v_rcp_f32_e32 v65, v65
	v_add_u32_e32 v67, v69, v143
	ds_write_b16_d16_hi v67, v64
	v_mul_f32_e32 v64, v75, v99
	v_mul_f32_e32 v65, v66, v65
	v_add_u32_e32 v70, 0x90, v145
	v_mul_f32_e32 v68, v64, v65
	v_add_u32_e32 v64, s54, v70
	v_ashrrev_i32_e32 v65, 31, v64
	v_lshl_add_u64 v[64:65], v[64:65], 2, s[0:1]
	global_load_dwordx4 v[64:67], v[64:65], off
	s_waitcnt vmcnt(1)
; __device__ __forceinline__ u16 f2bf(float f) { unsigned u = __float_as_uint(f); u += 0x7fffu + ((u >> 16) & 1u); return (u16)(u >> 16); }
; __device__ __forceinline__ float frcp(float x) { return __builtin_amdgcn_rcpf(x); }
; template <int EPI> ...
;     ...
;           const int r = ai * 128 + wr * 64 + m * 16 + fq * 4 + j;
;           float rs = 1.0f;
;           if (EPI != EPI_RES) rs = e.rstd[brow + r];
;           char* rowp = tb + r * RB + fr * 2;
;           if (EPI == EPI_GU) {
; #pragma unroll
;             for (int n = 0; n < 2; ++n) {
;               float g = acc[ai][0][m][n][j] * rs, u = acc[ai][1][m][n][j] * rs;
;               float h = g * frcp(1.0f + __expf(-g)) * u;
;               const int seg = (wc * 2 + n) ^ fq;
;               *(u16*)(rowp + seg * 32) = f2bf(h);
;             }
	v_mul_f32_e32 v56, v56, v80
	v_mul_f32_e32 v71, 0xbfb8aa3b, v56
	v_exp_f32_e32 v71, v71
	v_cvt_pk_bf16_f32 v68, v68, v68
	v_add_u32_e32 v69, v69, v142
	v_add_f32_e32 v71, 1.0, v71
	v_rcp_f32_e32 v71, v71
	v_mul_f32_e32 v48, v48, v80
	ds_write_b16_d16_hi v69, v68
	v_mul_f32_e32 v69, 0xbfb8aa3b, v48
	v_exp_f32_e32 v69, v69
	v_mul_f32_e32 v60, v60, v80
	v_mul_f32_e32 v56, v56, v71
	v_mul_f32_e32 v56, v60, v56
	v_cvt_pk_bf16_f32 v56, v56, v56
	v_add_f32_e32 v60, 1.0, v69
	v_rcp_f32_e32 v60, v60
	v_lshl_add_u32 v68, v76, 8, v144
	v_mul_f32_e32 v52, v52, v80
	v_add_u32_e32 v69, v68, v143
	v_mul_f32_e32 v48, v48, v60
	v_mul_f32_e32 v48, v52, v48
	v_mul_f32_e32 v52, v57, v81
	ds_write_b16_d16_hi v69, v56
	v_mul_f32_e32 v56, 0xbfb8aa3b, v52
	v_exp_f32_e32 v56, v56
	v_mul_f32_e32 v49, v49, v81
	v_cvt_pk_bf16_f32 v48, v48, v48
	v_add_f32_e32 v56, 1.0, v56
	v_rcp_f32_e32 v56, v56
	v_add_u32_e32 v57, v68, v142
	ds_write_b16_d16_hi v57, v48
	v_mul_f32_e32 v57, v61, v81
	v_mul_f32_e32 v52, v52, v56
	v_mul_f32_e32 v56, 0xbfb8aa3b, v49
	v_exp_f32_e32 v56, v56
	v_mul_f32_e32 v52, v57, v52
	v_add_u32_e32 v48, 0x8100, v136
	v_add_f32_e32 v56, 1.0, v56
	v_rcp_f32_e32 v56, v56
	v_cvt_pk_bf16_f32 v52, v52, v52
	v_add_u32_e32 v57, v48, v143
	ds_write_b16_d16_hi v57, v52
	v_mul_f32_e32 v52, v53, v81
	v_mul_f32_e32 v49, v49, v56
	v_mul_f32_e32 v49, v52, v49
	v_mul_f32_e32 v52, v58, v82
	v_mul_f32_e32 v53, 0xbfb8aa3b, v52
	v_exp_f32_e32 v53, v53
	v_mul_f32_e32 v50, v50, v82
	v_bfe_u32 v56, v49, 16, 1
	v_add3_u32 v49, v49, v56, s87
	v_add_f32_e32 v53, 1.0, v53
	v_rcp_f32_e32 v53, v53
	v_add_u32_e32 v48, v48, v142
	ds_write_b16_d16_hi v48, v49
	v_mul_f32_e32 v49, v62, v82
	v_mul_f32_e32 v52, v52, v53
	v_mul_f32_e32 v53, 0xbfb8aa3b, v50
	v_exp_f32_e32 v53, v53
	v_mul_f32_e32 v49, v49, v52
	v_cvt_pk_bf16_f32 v49, v49, v49
	v_add_f32_e32 v52, 1.0, v53
	v_rcp_f32_e32 v52, v52
	v_add_u32_e32 v48, 0x8200, v136
	v_add_u32_e32 v53, v48, v143
	ds_write_b16_d16_hi v53, v49
	v_mul_f32_e32 v49, v54, v82
	v_mul_f32_e32 v50, v50, v52
	v_mul_f32_e32 v49, v49, v50
	v_mul_f32_e32 v50, v59, v83
	v_mul_f32_e32 v52, 0xbfb8aa3b, v50
	v_exp_f32_e32 v52, v52
	v_mul_f32_e32 v51, v51, v83
	v_bfe_u32 v53, v49, 16, 1
	v_add3_u32 v49, v49, v53, s87
	v_add_f32_e32 v52, 1.0, v52
	v_rcp_f32_e32 v52, v52
	v_add_u32_e32 v48, v48, v142
	ds_write_b16_d16_hi v48, v49
	v_mul_f32_e32 v49, v63, v83
	v_mul_f32_e32 v50, v50, v52
	v_mul_f32_e32 v52, 0xbfb8aa3b, v51
	v_exp_f32_e32 v52, v52
	v_mul_f32_e32 v49, v49, v50
	v_cvt_pk_bf16_f32 v49, v49, v49
	v_add_f32_e32 v50, 1.0, v52
	v_rcp_f32_e32 v50, v50
	v_add_u32_e32 v48, 0x8300, v136
	v_add_u32_e32 v52, v48, v143
	ds_write_b16_d16_hi v52, v49
	v_mul_f32_e32 v49, v55, v83
	v_mul_f32_e32 v50, v51, v50
	s_waitcnt vmcnt(0)
	v_mul_f32_e32 v40, v40, v64
	v_mul_f32_e32 v49, v49, v50
	v_mul_f32_e32 v50, 0xbfb8aa3b, v40
	v_exp_f32_e32 v50, v50
	v_bfe_u32 v51, v49, 16, 1
	v_add3_u32 v49, v49, v51, s87
	v_add_u32_e32 v48, v48, v142
	v_add_f32_e32 v50, 1.0, v50
	v_rcp_f32_e32 v50, v50
	v_mul_f32_e32 v32, v32, v64
	ds_write_b16_d16_hi v48, v49
	v_mul_f32_e32 v48, 0xbfb8aa3b, v32
	v_exp_f32_e32 v48, v48
	v_mul_f32_e32 v44, v44, v64
	v_mul_f32_e32 v40, v40, v50
	v_mul_f32_e32 v40, v44, v40
	v_cvt_pk_bf16_f32 v40, v40, v40
	v_add_f32_e32 v44, 1.0, v48
	v_rcp_f32_e32 v44, v44
	v_lshl_add_u32 v52, v70, 8, v144
	v_add_u32_e32 v48, v52, v143
	ds_write_b16_d16_hi v48, v40
	v_mul_f32_e32 v32, v32, v44
	v_add_u32_e32 v44, 0xa0, v145
	v_mul_f32_e32 v36, v36, v64
	v_add_u32_e32 v40, s54, v44
	v_mul_f32_e32 v32, v36, v32
	v_mul_f32_e32 v36, v41, v65
	v_ashrrev_i32_e32 v41, 31, v40
	v_lshl_add_u64 v[40:41], v[40:41], 2, s[0:1]
	global_load_dwordx4 v[48:51], v[40:41], off
	v_mul_f32_e32 v40, 0xbfb8aa3b, v36
	v_exp_f32_e32 v40, v40
	v_mul_f32_e32 v33, v33, v65
	v_cvt_pk_bf16_f32 v32, v32, v32
	v_add_f32_e32 v40, 1.0, v40
	v_rcp_f32_e32 v40, v40
	v_add_u32_e32 v41, v52, v142
	ds_write_b16_d16_hi v41, v32
	v_mul_f32_e32 v41, v45, v65
	v_mul_f32_e32 v36, v36, v40
	v_mul_f32_e32 v40, 0xbfb8aa3b, v33
	v_exp_f32_e32 v40, v40
	v_mul_f32_e32 v36, v41, v36
	v_add_u32_e32 v32, 0x9100, v136
	v_add_f32_e32 v40, 1.0, v40
	v_rcp_f32_e32 v40, v40
	v_cvt_pk_bf16_f32 v36, v36, v36
	v_add_u32_e32 v41, v32, v143
	ds_write_b16_d16_hi v41, v36
	v_mul_f32_e32 v36, v37, v65
	v_mul_f32_e32 v33, v33, v40
	v_mul_f32_e32 v33, v36, v33
	v_mul_f32_e32 v36, v42, v66
	v_mul_f32_e32 v37, 0xbfb8aa3b, v36
	v_exp_f32_e32 v37, v37
	v_mul_f32_e32 v34, v34, v66
	v_cvt_pk_bf16_f32 v33, v33, v33
	v_add_f32_e32 v37, 1.0, v37
	v_rcp_f32_e32 v37, v37
	v_add_u32_e32 v32, v32, v142
	ds_write_b16_d16_hi v32, v33
	v_mul_f32_e32 v33, v46, v66
	v_mul_f32_e32 v36, v36, v37
	v_mul_f32_e32 v37, 0xbfb8aa3b, v34
	v_exp_f32_e32 v37, v37
	v_mul_f32_e32 v33, v33, v36
	v_cvt_pk_bf16_f32 v33, v33, v33
	v_add_f32_e32 v36, 1.0, v37
	v_rcp_f32_e32 v36, v36
	v_add_u32_e32 v32, 0x9200, v136
	v_add_u32_e32 v37, v32, v143
	ds_write_b16_d16_hi v37, v33
	v_mul_f32_e32 v33, v38, v66
	v_mul_f32_e32 v34, v34, v36
	v_mul_f32_e32 v33, v33, v34
	v_mul_f32_e32 v34, v43, v67
	v_mul_f32_e32 v36, 0xbfb8aa3b, v34
	v_exp_f32_e32 v36, v36
	v_cvt_pk_bf16_f32 v33, v33, v33
	v_add_u32_e32 v32, v32, v142
	v_add_f32_e32 v36, 1.0, v36
	v_rcp_f32_e32 v36, v36
	ds_write_b16_d16_hi v32, v33
	v_mul_f32_e32 v32, v47, v67
	v_add_u32_e32 v37, 0x9300, v136
	v_mul_f32_e32 v33, v34, v36
	v_mul_f32_e32 v34, v35, v67
	v_mul_f32_e32 v35, 0xbfb8aa3b, v34
	v_exp_f32_e32 v35, v35
	v_mul_f32_e32 v32, v32, v33
	v_cvt_pk_bf16_f32 v32, v32, v32
	v_add_f32_e32 v33, 1.0, v35
	v_rcp_f32_e32 v33, v33
	v_add_u32_e32 v35, v37, v143
	ds_write_b16_d16_hi v35, v32
	v_mul_f32_e32 v32, v39, v67
	v_mul_f32_e32 v33, v34, v33
	v_add_u32_e32 v38, 0xb0, v145
	v_mul_f32_e32 v36, v32, v33
	v_add_u32_e32 v32, s54, v38
	v_ashrrev_i32_e32 v33, 31, v32
	v_lshl_add_u64 v[32:33], v[32:33], 2, s[0:1]
	global_load_dwordx4 v[32:35], v[32:33], off
	s_waitcnt vmcnt(1)
; __device__ __forceinline__ u16 f2bf(float f) { unsigned u = __float_as_uint(f); u += 0x7fffu + ((u >> 16) & 1u); return (u16)(u >> 16); }
; __device__ __forceinline__ int opaque_tid() { int t; asm volatile("v_mov_b32 %0, %1" : "=v"(t) : "v"((int)threadIdx.x)); return t; }
; __device__ __forceinline__ float frcp(float x) { return __builtin_amdgcn_rcpf(x); }
; template <int EPI> ...
;     ...
;           const int r = ai * 128 + wr * 64 + m * 16 + fq * 4 + j;
;           float rs = 1.0f;
;           if (EPI != EPI_RES) rs = e.rstd[brow + r];
;           char* rowp = tb + r * RB + fr * 2;
;           if (EPI == EPI_GU) {
; #pragma unroll
;             for (int n = 0; n < 2; ++n) {
;               float g = acc[ai][0][m][n][j] * rs, u = acc[ai][1][m][n][j] * rs;
;               float h = g * frcp(1.0f + __expf(-g)) * u;
;               const int seg = (wc * 2 + n) ^ fq;
;               *(u16*)(rowp + seg * 32) = f2bf(h);
;             }
;           } else {
; #pragma unroll
;             for (int bj = 0; bj < 2; ++bj)
; #pragma unroll
;               for (int n = 0; n < 2; ++n) {
;                 const int seg = (bj * 8 + wc * 2 + n) ^ fq;
;                 *(u16*)(rowp + seg * 32) = f2bf(acc[ai][bj][m][n][j] * rs);
;               }
;           }
;         }
;     __syncthreads();
;     constexpr int CPR = RB / 16;
;     constexpr int RPI = 512 / CPR;
;     const int tid2 = opaque_tid();
;     const int cc = tid2 % CPR, r0 = tid2 / CPR;
;     u16* gp = (EPI == EPI_GU) ? e.out + ((size_t)((e.bcol >> 6) + (cc >> 3)) * 256 + r0) * 64 + (cc & 7) * 8
;                               : e.out + (size_t)r0 * e.ld + e.bcol + cc * 8;
;     const size_t gstep = (EPI == EPI_GU) ? (size_t)RPI * 64 : (size_t)RPI * e.ld;
	v_mul_f32_e32 v24, v24, v48
	v_mul_f32_e32 v39, 0xbfb8aa3b, v24
	v_exp_f32_e32 v39, v39
	v_bfe_u32 v40, v36, 16, 1
	v_add3_u32 v36, v36, v40, s87
	v_add_u32_e32 v37, v37, v142
	v_add_f32_e32 v39, 1.0, v39
	v_rcp_f32_e32 v39, v39
	v_mul_f32_e32 v16, v16, v48
	ds_write_b16_d16_hi v37, v36
	v_mul_f32_e32 v37, 0xbfb8aa3b, v16
	v_exp_f32_e32 v37, v37
	v_mul_f32_e32 v28, v28, v48
	v_mul_f32_e32 v24, v24, v39
	v_mul_f32_e32 v24, v28, v24
	v_cvt_pk_bf16_f32 v24, v24, v24
	v_add_f32_e32 v28, 1.0, v37
	v_rcp_f32_e32 v28, v28
	v_lshl_add_u32 v36, v44, 8, v144
	v_mul_f32_e32 v20, v20, v48
	v_add_u32_e32 v37, v36, v143
	v_mul_f32_e32 v16, v16, v28
	v_mul_f32_e32 v16, v20, v16
	v_mul_f32_e32 v20, v25, v49
	ds_write_b16_d16_hi v37, v24
	v_mul_f32_e32 v24, 0xbfb8aa3b, v20
	v_exp_f32_e32 v24, v24
	v_mul_f32_e32 v17, v17, v49
	v_cvt_pk_bf16_f32 v16, v16, v16
	v_add_f32_e32 v24, 1.0, v24
	v_rcp_f32_e32 v24, v24
	v_add_u32_e32 v25, v36, v142
	ds_write_b16_d16_hi v25, v16
	v_mul_f32_e32 v25, v29, v49
	v_mul_f32_e32 v20, v20, v24
	v_mul_f32_e32 v24, 0xbfb8aa3b, v17
	v_exp_f32_e32 v24, v24
	v_mul_f32_e32 v20, v25, v20
	v_add_u32_e32 v16, 0xa100, v136
	v_add_f32_e32 v24, 1.0, v24
	v_rcp_f32_e32 v24, v24
	v_cvt_pk_bf16_f32 v20, v20, v20
	v_add_u32_e32 v25, v16, v143
	ds_write_b16_d16_hi v25, v20
	v_mul_f32_e32 v20, v21, v49
	v_mul_f32_e32 v17, v17, v24
	v_mul_f32_e32 v17, v20, v17
	v_mul_f32_e32 v20, v26, v50
	v_mul_f32_e32 v21, 0xbfb8aa3b, v20
	v_exp_f32_e32 v21, v21
	v_mul_f32_e32 v18, v18, v50
	v_bfe_u32 v24, v17, 16, 1
	v_add3_u32 v17, v17, v24, s87
	v_add_f32_e32 v21, 1.0, v21
	v_rcp_f32_e32 v21, v21
	v_add_u32_e32 v16, v16, v142
	ds_write_b16_d16_hi v16, v17
	v_mul_f32_e32 v17, v30, v50
	v_mul_f32_e32 v20, v20, v21
	v_mul_f32_e32 v21, 0xbfb8aa3b, v18
	v_exp_f32_e32 v21, v21
	v_mul_f32_e32 v17, v17, v20
	v_cvt_pk_bf16_f32 v17, v17, v17
	v_add_f32_e32 v20, 1.0, v21
	v_rcp_f32_e32 v20, v20
	v_add_u32_e32 v16, 0xa200, v136
	v_add_u32_e32 v21, v16, v143
	ds_write_b16_d16_hi v21, v17
	v_mul_f32_e32 v17, v22, v50
	v_mul_f32_e32 v18, v18, v20
	v_mul_f32_e32 v17, v17, v18
	v_mul_f32_e32 v18, v27, v51
	v_mul_f32_e32 v20, 0xbfb8aa3b, v18
	v_exp_f32_e32 v20, v20
	v_mul_f32_e32 v19, v19, v51
	v_bfe_u32 v21, v17, 16, 1
	v_add3_u32 v17, v17, v21, s87
	v_add_f32_e32 v20, 1.0, v20
	v_rcp_f32_e32 v20, v20
	v_add_u32_e32 v16, v16, v142
	ds_write_b16_d16_hi v16, v17
	v_mul_f32_e32 v17, v31, v51
	v_mul_f32_e32 v18, v18, v20
	v_mul_f32_e32 v20, 0xbfb8aa3b, v19
	v_exp_f32_e32 v20, v20
	v_mul_f32_e32 v17, v17, v18
	v_cvt_pk_bf16_f32 v17, v17, v17
	v_add_f32_e32 v18, 1.0, v20
	v_rcp_f32_e32 v18, v18
	v_add_u32_e32 v16, 0xa300, v136
	v_add_u32_e32 v20, v16, v143
	ds_write_b16_d16_hi v20, v17
	v_mul_f32_e32 v17, v23, v51
	v_mul_f32_e32 v18, v19, v18
	s_waitcnt vmcnt(0)
	v_mul_f32_e32 v8, v8, v32
	v_mul_f32_e32 v17, v17, v18
	v_mul_f32_e32 v18, 0xbfb8aa3b, v8
	v_exp_f32_e32 v18, v18
	v_bfe_u32 v19, v17, 16, 1
	v_add3_u32 v17, v17, v19, s87
	v_add_u32_e32 v16, v16, v142
	v_add_f32_e32 v18, 1.0, v18
	v_rcp_f32_e32 v18, v18
	v_mul_f32_e32 v0, v0, v32
	ds_write_b16_d16_hi v16, v17
	v_mul_f32_e32 v17, 0xbfb8aa3b, v0
	v_exp_f32_e32 v17, v17
	v_mul_f32_e32 v12, v12, v32
	v_mul_f32_e32 v8, v8, v18
	v_mul_f32_e32 v8, v12, v8
	v_cvt_pk_bf16_f32 v8, v8, v8
	v_add_f32_e32 v12, 1.0, v17
	v_rcp_f32_e32 v12, v12
	v_lshl_add_u32 v16, v38, 8, v144
	v_mul_f32_e32 v4, v4, v32
	v_add_u32_e32 v17, v16, v143
	v_mul_f32_e32 v0, v0, v12
	v_mul_f32_e32 v0, v4, v0
	v_mul_f32_e32 v4, v9, v33
	ds_write_b16_d16_hi v17, v8
	v_mul_f32_e32 v8, 0xbfb8aa3b, v4
	v_exp_f32_e32 v8, v8
	v_mul_f32_e32 v1, v1, v33
	v_cvt_pk_bf16_f32 v0, v0, v0
	v_add_f32_e32 v8, 1.0, v8
	v_rcp_f32_e32 v8, v8
	v_add_u32_e32 v9, v16, v142
	ds_write_b16_d16_hi v9, v0
	v_mul_f32_e32 v9, v13, v33
	v_mul_f32_e32 v4, v4, v8
	v_mul_f32_e32 v8, 0xbfb8aa3b, v1
	v_exp_f32_e32 v8, v8
	v_mul_f32_e32 v4, v9, v4
	v_add_u32_e32 v0, 0xb100, v136
	v_add_f32_e32 v8, 1.0, v8
	v_rcp_f32_e32 v8, v8
	v_cvt_pk_bf16_f32 v4, v4, v4
	v_add_u32_e32 v9, v0, v143
	ds_write_b16_d16_hi v9, v4
	v_mul_f32_e32 v4, v5, v33
	v_mul_f32_e32 v1, v1, v8
	v_mul_f32_e32 v1, v4, v1
	v_mul_f32_e32 v4, v10, v34
	v_mul_f32_e32 v5, 0xbfb8aa3b, v4
	v_exp_f32_e32 v5, v5
	v_mul_f32_e32 v2, v2, v34
	v_bfe_u32 v8, v1, 16, 1
	v_add3_u32 v1, v1, v8, s87
	v_add_f32_e32 v5, 1.0, v5
	v_rcp_f32_e32 v5, v5
	v_add_u32_e32 v0, v0, v142
	ds_write_b16_d16_hi v0, v1
	v_mul_f32_e32 v1, v14, v34
	v_mul_f32_e32 v4, v4, v5
	v_mul_f32_e32 v5, 0xbfb8aa3b, v2
	v_exp_f32_e32 v5, v5
	v_mul_f32_e32 v1, v1, v4
	v_cvt_pk_bf16_f32 v1, v1, v1
	v_add_f32_e32 v4, 1.0, v5
	v_rcp_f32_e32 v4, v4
	v_add_u32_e32 v0, 0xb200, v136
	v_add_u32_e32 v5, v0, v143
	ds_write_b16_d16_hi v5, v1
	v_mul_f32_e32 v1, v6, v34
	v_mul_f32_e32 v2, v2, v4
	v_mul_f32_e32 v1, v1, v2
	v_mul_f32_e32 v2, v11, v35
	v_mul_f32_e32 v4, 0xbfb8aa3b, v2
	v_exp_f32_e32 v4, v4
	v_mul_f32_e32 v3, v3, v35
	v_bfe_u32 v5, v1, 16, 1
	v_add3_u32 v1, v1, v5, s87
	v_add_f32_e32 v4, 1.0, v4
	v_rcp_f32_e32 v4, v4
	v_add_u32_e32 v0, v0, v142
	ds_write_b16_d16_hi v0, v1
	v_mul_f32_e32 v1, v15, v35
	v_mul_f32_e32 v2, v2, v4
	v_mul_f32_e32 v4, 0xbfb8aa3b, v3
	v_exp_f32_e32 v4, v4
	v_mul_f32_e32 v1, v1, v2
	v_cvt_pk_bf16_f32 v1, v1, v1
	v_add_f32_e32 v2, 1.0, v4
	v_rcp_f32_e32 v2, v2
	v_add_u32_e32 v0, 0xb300, v136
	v_add_u32_e32 v4, v0, v143
	ds_write_b16_d16_hi v4, v1
	v_mul_f32_e32 v1, v7, v35
	v_mul_f32_e32 v2, v3, v2
	v_mul_f32_e32 v1, v1, v2
	v_cvt_pk_bf16_f32 v1, v1, v1
	v_add_u32_e32 v0, v0, v142
	ds_write_b16_d16_hi v0, v1
	s_waitcnt lgkmcnt(0)
	s_barrier
	v_mov_b32 v0, v146
	s_nop 0
	v_ashrrev_i32_e32 v1, 31, v0
	v_lshrrev_b32_e32 v1, 28, v1
	v_add_u32_e32 v1, v0, v1
	v_ashrrev_i32_e32 v2, 4, v1
	v_and_b32_e32 v1, -16, v1
	v_sub_u32_e32 v6, v0, v1
	v_ashrrev_i32_e32 v0, 3, v6
	v_lshl_add_u32 v0, s52, 1, v0
	v_ashrrev_i32_e32 v3, 31, v2
	v_ashrrev_i32_e32 v1, 31, v0
	v_lshlrev_b64 v[4:5], 7, v[2:3]
	v_lshlrev_b32_e32 v3, 4, v6
	v_lshlrev_b64 v[0:1], 15, v[0:1]
	v_and_b32_e32 v136, 0x70, v3
	v_lshrrev_b32_e32 v3, 1, v2
	v_lshl_add_u64 v[0:1], s[56:57], 0, v[0:1]
	v_bitop3_b32 v3, v3, v6, 6 bitop3:0x6c
	v_lshl_add_u64 v[0:1], v[0:1], 0, v[4:5]
	v_lshlrev_b32_e32 v2, 8, v2
	v_lshlrev_b32_e32 v3, 4, v3
	v_lshl_add_u64 v[0:1], v[0:1], 0, v[136:137]
	v_add3_u32 v2, 0, v2, v3
	s_mov_b32 s52, 0

; __device__ __forceinline__ int opaque_tid() { int t; asm volatile("v_mov_b32 %0, %1" : "=v"(t) : "v"((int)threadIdx.x)); return t; }
; #define STAGE(P, BASE, kt) do { const char* _g = (const char*)(BASE) + (size_t)((kt) * (BK * 2)); \
;     __builtin_amdgcn_global_load_lds((const unsigned*)(_g + (size_t)goff0), (unsigned*)((char*)(P) + tid_ * 16), 16, 0, 0); \
;     __builtin_amdgcn_global_load_lds((const unsigned*)(_g + (size_t)goff1), (unsigned*)((char*)(P) + tid_ * 16 + 8192), 16, 0, 0); } while (0)
; #define STAGEA(P, BASE, kt) do { const char* _g = (const char*)(BASE) + (size_t)((kt) * a_kbytes); \
;     __builtin_amdgcn_global_load_lds((const unsigned*)(_g + (size_t)goffA0), (unsigned*)((char*)(P) + tid_ * 16), 16, 0, 0); \
;     __builtin_amdgcn_global_load_lds((const unsigned*)(_g + (size_t)goffA1), (unsigned*)((char*)(P) + tid_ * 16 + 8192), 16, 0, 0); } while (0)
; #define LDA(dst, b, h) for (int m = 0; m < 4; ++m) for (int k = 0; k < 2; ++k) \
;     dst[m][k] = *reinterpret_cast<const bf16x8*>((char*)SA(b, h) + lds_byte(wr * 64 + m * 16 + fr, k * 32 + fq * 8))
; #define LDB(dst, b, h) for (int n = 0; n < 2; ++n) for (int k = 0; k < 2; ++k) \
;     dst[n][k] = *reinterpret_cast<const bf16x8*>((char*)SB(b, h) + lds_byte(wc * 32 + n * 16 + fr, k * 32 + fq * 8))
; #define WAIT_V(n) asm volatile("s_waitcnt vmcnt(" #n ")" ::: "memory")
; #define BAR __builtin_amdgcn_s_barrier()
; #define SCHED __builtin_amdgcn_sched_barrier(0)
; template <int EPI> ...
;     ...
;   const int tid_ = opaque_tid();
;   const int wid = tid_ >> 6, lane = tid_ & 63, wr = wid >> 2, wc = wid & 3, fr = lane & 15, fq = lane >> 4;
;   f32x4 acc[2][2][4][2] = {};
;   bf16x8 At[4][2], B0[2][2], B1[2][2];
;   const int nt = K / BK;
;   STAGE(SB(0, 0), B0p, 0); STAGEA(SA(0, 0), A0, 0);
;   STAGE(SB(0, 1), B1p, 0); STAGEA(SA(0, 1), A1, 0);
;   if (wr == 1) BAR;
;   WAIT_V(4); BAR;
;   STAGE(SB(1, 0), B0p, 1); STAGEA(SA(1, 0), A0, 1); STAGE(SB(1, 1), B1p, 1);
;   WAIT_V(6); BAR;
;   for (int t = 0; t < nt - 2; t += 2) {
;     LDB(B0, 0, 0); SCHED; LDA(At, 0, 0); STAGEA(SA(1, 1), A1, t + 1);
.LBB0_781:
	s_or_b64 exec, exec, s[54:55]
	v_add_u32_e32 v164, s64, v4
	v_add_u32_e32 v165, 0x2000, v164
	v_readfirstlane_b32 s54, v164
	v_lshl_add_u64 v[0:1], v[0:1], 0, s[0:1]
	s_mov_b32 m0, s54
	v_readfirstlane_b32 s54, v165
	s_waitcnt vmcnt(4)
	s_barrier
	global_load_lds_dwordx4 v[0:1], off
	s_mov_b32 m0, s54
	s_add_u32 s54, s48, 0x8000
	v_add_u32_e32 v166, 0x8000, v158
	v_lshl_add_u64 v[0:1], v[2:3], 0, s[0:1]
	s_addc_u32 s55, s49, 0
	v_readfirstlane_b32 s87, v166
	global_load_lds_dwordx4 v[0:1], off
	v_lshl_add_u64 v[0:1], s[54:55], 0, v[130:131]
	s_mov_b32 m0, s87
	v_add_u32_e32 v168, 0xa000, v158
	global_load_lds_dwordx4 v[0:1], off
	v_lshl_add_u64 v[0:1], s[54:55], 0, v[128:129]
	v_readfirstlane_b32 s54, v168
	s_add_u32 s52, s52, 0x160080
	v_add_u32_e32 v169, s65, v4
	s_mov_b32 m0, s54
	s_addc_u32 s53, s53, 0
	v_readfirstlane_b32 s54, v169
	global_load_lds_dwordx4 v[0:1], off
	v_lshl_add_u64 v[0:1], s[52:53], 0, v[134:135]
	s_mov_b32 m0, s54
	v_add_u32_e32 v170, 0x2000, v169
	global_load_lds_dwordx4 v[0:1], off
	v_lshl_add_u64 v[0:1], s[52:53], 0, v[132:133]
	v_readfirstlane_b32 s52, v170
	s_mov_b32 m0, s52
	v_and_b32_e32 v149, 15, v144
	global_load_lds_dwordx4 v[0:1], off
	v_bfe_u32 v145, v144, 4, 2
	v_lshlrev_b32_e32 v3, 2, v144
	v_lshlrev_b32_e32 v0, 4, v145
	v_lshlrev_b32_e32 v2, 6, v149
	v_and_b32_e32 v3, 32, v3
	v_lshlrev_b32_e32 v9, 6, v144
	v_bfe_u32 v148, v144, 6, 2
	s_waitcnt vmcnt(6)
	v_bitop3_b32 v2, v0, v3, v2 bitop3:0x36
	v_lshlrev_b32_e32 v8, 13, v147
	v_and_or_b32 v0, v9, s66, v0
	v_lshlrev_b32_e32 v1, 12, v148
	v_add_u32_e32 v4, s62, v2
	v_add_u32_e32 v5, s63, v2
	v_add_u32_e32 v6, s64, v2
	v_add_u32_e32 v7, s65, v2
	v_add_u32_e32 v2, 0, v2
	v_xad_u32 v3, v0, v3, 0
	v_or_b32_e32 v9, 0x800, v8
	v_or_b32_e32 v10, 0x1000, v8
	v_or_b32_e32 v11, 0x1800, v8
	s_add_u32 s52, s74, s86
	v_mov_b32_e32 v0, 0
	s_addc_u32 s53, s75, s85
	s_mov_b32 s85, -2
	v_add_u32_e32 v171, v4, v1
	v_add_u32_e32 v153, v2, v8
	v_add_u32_e32 v152, v3, v9
	v_add_u32_e32 v151, v3, v10
	v_add_u32_e32 v150, v3, v11
	v_add_u32_e32 v167, v5, v1
	v_add_u32_e32 v156, v6, v1
	v_add_u32_e32 v154, v7, v1
	s_mov_b64 s[54:55], s[48:49]
	v_mov_b32_e32 v1, v0
	v_mov_b32_e32 v2, v0
	v_mov_b32_e32 v3, v0
	v_mov_b32_e32 v4, v0
	v_mov_b32_e32 v5, v0
	v_mov_b32_e32 v6, v0
	v_mov_b32_e32 v7, v0
	v_mov_b32_e32 v8, v0
	v_mov_b32_e32 v9, v0
	v_mov_b32_e32 v10, v0
	v_mov_b32_e32 v11, v0
	v_mov_b32_e32 v12, v0
	v_mov_b32_e32 v13, v0
	v_mov_b32_e32 v14, v0
	v_mov_b32_e32 v15, v0
	v_mov_b32_e32 v16, v0
	v_mov_b32_e32 v17, v0
	v_mov_b32_e32 v18, v0
	v_mov_b32_e32 v19, v0
	v_mov_b32_e32 v20, v0
	v_mov_b32_e32 v21, v0
	v_mov_b32_e32 v22, v0
	v_mov_b32_e32 v23, v0
	v_mov_b32_e32 v24, v0
	v_mov_b32_e32 v25, v0
	v_mov_b32_e32 v26, v0
	v_mov_b32_e32 v27, v0
	v_mov_b32_e32 v28, v0
	v_mov_b32_e32 v29, v0
	v_mov_b32_e32 v30, v0
	v_mov_b32_e32 v31, v0
	v_mov_b32_e32 v32, v0
	v_mov_b32_e32 v33, v0
	v_mov_b32_e32 v34, v0
	v_mov_b32_e32 v35, v0
	v_mov_b32_e32 v36, v0
	v_mov_b32_e32 v37, v0
	v_mov_b32_e32 v38, v0
	v_mov_b32_e32 v39, v0
	v_mov_b32_e32 v40, v0
	v_mov_b32_e32 v41, v0
	v_mov_b32_e32 v42, v0
	v_mov_b32_e32 v43, v0
	v_mov_b32_e32 v44, v0
	v_mov_b32_e32 v45, v0
	v_mov_b32_e32 v46, v0
	v_mov_b32_e32 v47, v0
	v_mov_b32_e32 v48, v0
	v_mov_b32_e32 v49, v0
	v_mov_b32_e32 v50, v0
	v_mov_b32_e32 v51, v0
	v_mov_b32_e32 v52, v0
	v_mov_b32_e32 v53, v0
	v_mov_b32_e32 v54, v0
	v_mov_b32_e32 v55, v0
	v_mov_b32_e32 v56, v0
	v_mov_b32_e32 v57, v0
	v_mov_b32_e32 v58, v0
	v_mov_b32_e32 v59, v0
	v_mov_b32_e32 v60, v0
	v_mov_b32_e32 v61, v0
	v_mov_b32_e32 v62, v0
	v_mov_b32_e32 v63, v0
	v_mov_b32_e32 v64, v0
	v_mov_b32_e32 v65, v0
	v_mov_b32_e32 v66, v0
	v_mov_b32_e32 v67, v0
	v_mov_b32_e32 v68, v0
	v_mov_b32_e32 v69, v0
	v_mov_b32_e32 v70, v0
	v_mov_b32_e32 v71, v0
	v_mov_b32_e32 v72, v0
	v_mov_b32_e32 v73, v0
	v_mov_b32_e32 v74, v0
	v_mov_b32_e32 v75, v0
	v_mov_b32_e32 v76, v0
	v_mov_b32_e32 v77, v0
	v_mov_b32_e32 v78, v0
	v_mov_b32_e32 v79, v0
	v_mov_b32_e32 v80, v0
	v_mov_b32_e32 v81, v0
	v_mov_b32_e32 v82, v0
	v_mov_b32_e32 v83, v0
	v_mov_b32_e32 v84, v0
	v_mov_b32_e32 v85, v0
	v_mov_b32_e32 v86, v0
	v_mov_b32_e32 v87, v0
	v_mov_b32_e32 v88, v0
	v_mov_b32_e32 v89, v0
	v_mov_b32_e32 v90, v0
	v_mov_b32_e32 v91, v0
	v_mov_b32_e32 v92, v0
	v_mov_b32_e32 v93, v0
	v_mov_b32_e32 v94, v0
	v_mov_b32_e32 v95, v0
	v_mov_b32_e32 v96, v0
	v_mov_b32_e32 v97, v0
	v_mov_b32_e32 v98, v0
	v_mov_b32_e32 v99, v0
	v_mov_b32_e32 v100, v0
	v_mov_b32_e32 v101, v0
	v_mov_b32_e32 v102, v0
	v_mov_b32_e32 v103, v0
	v_mov_b32_e32 v104, v0
	v_mov_b32_e32 v105, v0
	v_mov_b32_e32 v106, v0
	v_mov_b32_e32 v107, v0
	v_mov_b32_e32 v108, v0
	v_mov_b32_e32 v109, v0
	v_mov_b32_e32 v110, v0
	v_mov_b32_e32 v111, v0
	v_mov_b32_e32 v112, v0
	v_mov_b32_e32 v113, v0
	v_mov_b32_e32 v114, v0
	v_mov_b32_e32 v115, v0
	v_mov_b32_e32 v116, v0
	v_mov_b32_e32 v117, v0
	v_mov_b32_e32 v118, v0
	v_mov_b32_e32 v119, v0
	v_mov_b32_e32 v120, v0
	v_mov_b32_e32 v121, v0
	v_mov_b32_e32 v122, v0
	v_mov_b32_e32 v123, v0
	v_mov_b32_e32 v124, v0
	v_mov_b32_e32 v125, v0
	v_mov_b32_e32 v126, v0
	v_mov_b32_e32 v127, v0
	s_barrier
	ds_read_b128 v[174:177], v171
	ds_read_b128 v[178:181], v171 offset:1024
	ds_read_b128 v[182:185], v171 offset:2048
	ds_read_b128 v[186:189], v171 offset:3072
; #define STAGE(P, BASE, kt) do { const char* _g = (const char*)(BASE) + (size_t)((kt) * (BK * 2)); \
;     __builtin_amdgcn_global_load_lds((const unsigned*)(_g + (size_t)goff0), (unsigned*)((char*)(P) + tid_ * 16), 16, 0, 0); \
;     __builtin_amdgcn_global_load_lds((const unsigned*)(_g + (size_t)goff1), (unsigned*)((char*)(P) + tid_ * 16 + 8192), 16, 0, 0); } while (0)
; #define STAGEA(P, BASE, kt) do { const char* _g = (const char*)(BASE) + (size_t)((kt) * a_kbytes); \
;     __builtin_amdgcn_global_load_lds((const unsigned*)(_g + (size_t)goffA0), (unsigned*)((char*)(P) + tid_ * 16), 16, 0, 0); \
;     __builtin_amdgcn_global_load_lds((const unsigned*)(_g + (size_t)goffA1), (unsigned*)((char*)(P) + tid_ * 16 + 8192), 16, 0, 0); } while (0)
; #define LDA(dst, b, h) for (int m = 0; m < 4; ++m) for (int k = 0; k < 2; ++k) \
;     dst[m][k] = *reinterpret_cast<const bf16x8*>((char*)SA(b, h) + lds_byte(wr * 64 + m * 16 + fr, k * 32 + fq * 8))
; #define LDB(dst, b, h) for (int n = 0; n < 2; ++n) for (int k = 0; k < 2; ++k) \
;     dst[n][k] = *reinterpret_cast<const bf16x8*>((char*)SB(b, h) + lds_byte(wc * 32 + n * 16 + fr, k * 32 + fq * 8))
; #define MMA(ai, bj, At, Bt) do { __builtin_amdgcn_s_setprio(1); \
;     for (int m = 0; m < 4; ++m) for (int n = 0; n < 2; ++n) for (int k = 0; k < 2; ++k) \
;       acc[ai][bj][m][n] = __builtin_amdgcn_mfma_f32_16x16x32_bf16(At[m][k], Bt[n][k], acc[ai][bj][m][n], 0, 0, 0); \
;     __builtin_amdgcn_s_setprio(0); } while (0)
; #define WAIT_V(n) asm volatile("s_waitcnt vmcnt(" #n ")" ::: "memory")
; #define WAIT_L(n) asm volatile("s_waitcnt lgkmcnt(" #n ")" ::: "memory")
; #define BAR __builtin_amdgcn_s_barrier()
; #define SCHED __builtin_amdgcn_sched_barrier(0)
; template <int EPI> ...
;     ...
;     LDB(B0, 0, 0); SCHED; LDA(At, 0, 0); STAGEA(SA(1, 1), A1, t + 1);
;     WAIT_L(8); BAR; WAIT_L(0); MMA(0, 0, At, B0); BAR; SCHED;
;     LDB(B1, 0, 1); STAGE(SB(0, 0), B0p, t + 2);
;     BAR; WAIT_L(0); MMA(0, 1, At, B1); BAR;
;     LDA(At, 0, 1); STAGEA(SA(0, 0), A0, t + 2);
;     BAR; WAIT_L(0); MMA(1, 0, At, B0); BAR; SCHED;
;     STAGE(SB(0, 1), B1p, t + 2);
;     WAIT_V(6); BAR; MMA(1, 1, At, B1); BAR;
.LBB0_782:
	v_add_u32_e32 v172, 0xc000, v158
	v_lshl_add_u64 v[238:239], s[54:55], 0, v[136:137]
	v_readfirstlane_b32 s86, v172
	v_add_u32_e32 v173, 0xe000, v158
	v_lshl_add_u64 v[222:223], v[238:239], 0, s[4:5]
	s_mov_b32 m0, s86
	v_lshl_add_u64 v[240:241], s[54:55], 0, v[138:139]
	v_readfirstlane_b32 s86, v173
	ds_read_b128 v[190:193], v153
	ds_read_b128 v[194:197], v153 offset:1024
	ds_read_b128 v[198:201], v152
	ds_read_b128 v[202:205], v152 offset:1024
	ds_read_b128 v[206:209], v151
	ds_read_b128 v[210:213], v151 offset:1024
	ds_read_b128 v[214:217], v150
	ds_read_b128 v[218:221], v150 offset:1024
	global_load_lds_dwordx4 v[222:223], off
	v_lshl_add_u64 v[222:223], v[240:241], 0, s[4:5]
	s_mov_b32 m0, s86
	s_nop 0
	global_load_lds_dwordx4 v[222:223], off
	s_waitcnt lgkmcnt(8)
	s_setprio 1
	s_barrier
	s_waitcnt lgkmcnt(0)
	v_mfma_f32_16x16x32_bf16 v[124:127], v[190:193], v[174:177], v[124:127]
	v_mfma_f32_16x16x32_bf16 v[120:123], v[190:193], v[182:185], v[120:123]
	v_mfma_f32_16x16x32_bf16 v[116:119], v[198:201], v[174:177], v[116:119]
	v_mfma_f32_16x16x32_bf16 v[112:115], v[198:201], v[182:185], v[112:115]
	v_mfma_f32_16x16x32_bf16 v[108:111], v[206:209], v[174:177], v[108:111]
	v_mfma_f32_16x16x32_bf16 v[104:107], v[206:209], v[182:185], v[104:107]
	v_mfma_f32_16x16x32_bf16 v[100:103], v[214:217], v[174:177], v[100:103]
	v_mfma_f32_16x16x32_bf16 v[96:99], v[214:217], v[182:185], v[96:99]
	v_mfma_f32_16x16x32_bf16 v[124:127], v[194:197], v[178:181], v[124:127]
	v_mfma_f32_16x16x32_bf16 v[120:123], v[194:197], v[186:189], v[120:123]
	v_mfma_f32_16x16x32_bf16 v[116:119], v[202:205], v[178:181], v[116:119]
	v_mfma_f32_16x16x32_bf16 v[112:115], v[202:205], v[186:189], v[112:115]
	v_mfma_f32_16x16x32_bf16 v[108:111], v[210:213], v[178:181], v[108:111]
	v_mfma_f32_16x16x32_bf16 v[104:107], v[210:213], v[186:189], v[104:107]
	v_mfma_f32_16x16x32_bf16 v[100:103], v[218:221], v[178:181], v[100:103]
	v_mfma_f32_16x16x32_bf16 v[96:99], v[218:221], v[186:189], v[96:99]
	s_barrier
	s_setprio 0
	v_lshl_add_u64 v[242:243], s[52:53], 0, v[140:141]
	v_readfirstlane_b32 s86, v155
	v_lshl_add_u64 v[244:245], v[242:243], 0, s[6:7]
	s_mov_b32 m0, s86
	ds_read_b128 v[222:225], v167
	ds_read_b128 v[226:229], v167 offset:1024
	ds_read_b128 v[230:233], v167 offset:2048
	ds_read_b128 v[234:237], v167 offset:3072
	global_load_lds_dwordx4 v[244:245], off
	v_lshl_add_u64 v[244:245], s[52:53], 0, v[142:143]
	v_readfirstlane_b32 s86, v157
	v_lshl_add_u64 v[246:247], v[244:245], 0, s[6:7]
	s_mov_b32 m0, s86
	s_nop 0
	global_load_lds_dwordx4 v[246:247], off
	s_setprio 1
	s_barrier
	s_waitcnt lgkmcnt(0)
	v_mfma_f32_16x16x32_bf16 v[92:95], v[190:193], v[222:225], v[92:95]
	v_mfma_f32_16x16x32_bf16 v[88:91], v[190:193], v[230:233], v[88:91]
	v_mfma_f32_16x16x32_bf16 v[84:87], v[198:201], v[222:225], v[84:87]
	v_mfma_f32_16x16x32_bf16 v[80:83], v[198:201], v[230:233], v[80:83]
	v_mfma_f32_16x16x32_bf16 v[76:79], v[206:209], v[222:225], v[76:79]
	v_mfma_f32_16x16x32_bf16 v[72:75], v[206:209], v[230:233], v[72:75]
	v_mfma_f32_16x16x32_bf16 v[68:71], v[214:217], v[222:225], v[68:71]
	v_mfma_f32_16x16x32_bf16 v[64:67], v[214:217], v[230:233], v[64:67]
	v_mfma_f32_16x16x32_bf16 v[92:95], v[194:197], v[226:229], v[92:95]
	v_mfma_f32_16x16x32_bf16 v[88:91], v[194:197], v[234:237], v[88:91]
	v_mfma_f32_16x16x32_bf16 v[84:87], v[202:205], v[226:229], v[84:87]
	v_mfma_f32_16x16x32_bf16 v[80:83], v[202:205], v[234:237], v[80:83]
	v_mfma_f32_16x16x32_bf16 v[76:79], v[210:213], v[226:229], v[76:79]
	v_mfma_f32_16x16x32_bf16 v[72:75], v[210:213], v[234:237], v[72:75]
	v_mfma_f32_16x16x32_bf16 v[68:71], v[218:221], v[226:229], v[68:71]
	v_mfma_f32_16x16x32_bf16 v[64:67], v[218:221], v[234:237], v[64:67]
	s_barrier
	s_setprio 0
	v_readfirstlane_b32 s86, v158
	v_lshl_add_u64 v[246:247], v[238:239], 0, s[8:9]
	s_mov_b32 m0, s86
	v_readfirstlane_b32 s86, v159
	ds_read_b128 v[190:193], v153 offset:16384
	ds_read_b128 v[194:197], v153 offset:17408
	ds_read_b128 v[198:201], v152 offset:16384
	ds_read_b128 v[202:205], v152 offset:17408
	ds_read_b128 v[206:209], v151 offset:16384
	ds_read_b128 v[210:213], v151 offset:17408
	ds_read_b128 v[214:217], v150 offset:16384
	ds_read_b128 v[218:221], v150 offset:17408
	global_load_lds_dwordx4 v[246:247], off
	v_lshl_add_u64 v[246:247], v[240:241], 0, s[8:9]
	s_mov_b32 m0, s86
	s_nop 0
	global_load_lds_dwordx4 v[246:247], off
	s_setprio 1
	s_barrier
	s_waitcnt lgkmcnt(0)
	v_mfma_f32_16x16x32_bf16 v[60:63], v[190:193], v[174:177], v[60:63]
	v_mfma_f32_16x16x32_bf16 v[56:59], v[190:193], v[182:185], v[56:59]
	v_mfma_f32_16x16x32_bf16 v[52:55], v[198:201], v[174:177], v[52:55]
	v_mfma_f32_16x16x32_bf16 v[48:51], v[198:201], v[182:185], v[48:51]
	v_mfma_f32_16x16x32_bf16 v[44:47], v[206:209], v[174:177], v[44:47]
	v_mfma_f32_16x16x32_bf16 v[40:43], v[206:209], v[182:185], v[40:43]
	v_mfma_f32_16x16x32_bf16 v[36:39], v[214:217], v[174:177], v[36:39]
	v_mfma_f32_16x16x32_bf16 v[32:35], v[214:217], v[182:185], v[32:35]
	v_mfma_f32_16x16x32_bf16 v[60:63], v[194:197], v[178:181], v[60:63]
	v_mfma_f32_16x16x32_bf16 v[56:59], v[194:197], v[186:189], v[56:59]
	v_mfma_f32_16x16x32_bf16 v[52:55], v[202:205], v[178:181], v[52:55]
	v_mfma_f32_16x16x32_bf16 v[48:51], v[202:205], v[186:189], v[48:51]
	v_mfma_f32_16x16x32_bf16 v[44:47], v[210:213], v[178:181], v[44:47]
	v_mfma_f32_16x16x32_bf16 v[40:43], v[210:213], v[186:189], v[40:43]
	v_mfma_f32_16x16x32_bf16 v[36:39], v[218:221], v[178:181], v[36:39]
	v_mfma_f32_16x16x32_bf16 v[32:35], v[218:221], v[186:189], v[32:35]
	s_barrier
; #define STAGE(P, BASE, kt) do { const char* _g = (const char*)(BASE) + (size_t)((kt) * (BK * 2)); \
;     __builtin_amdgcn_global_load_lds((const unsigned*)(_g + (size_t)goff0), (unsigned*)((char*)(P) + tid_ * 16), 16, 0, 0); \
;     __builtin_amdgcn_global_load_lds((const unsigned*)(_g + (size_t)goff1), (unsigned*)((char*)(P) + tid_ * 16 + 8192), 16, 0, 0); } while (0)
; #define STAGEA(P, BASE, kt) do { const char* _g = (const char*)(BASE) + (size_t)((kt) * a_kbytes); \
;     __builtin_amdgcn_global_load_lds((const unsigned*)(_g + (size_t)goffA0), (unsigned*)((char*)(P) + tid_ * 16), 16, 0, 0); \
;     __builtin_amdgcn_global_load_lds((const unsigned*)(_g + (size_t)goffA1), (unsigned*)((char*)(P) + tid_ * 16 + 8192), 16, 0, 0); } while (0)
; #define LDA(dst, b, h) for (int m = 0; m < 4; ++m) for (int k = 0; k < 2; ++k) \
;     dst[m][k] = *reinterpret_cast<const bf16x8*>((char*)SA(b, h) + lds_byte(wr * 64 + m * 16 + fr, k * 32 + fq * 8))
; #define LDB(dst, b, h) for (int n = 0; n < 2; ++n) for (int k = 0; k < 2; ++k) \
;     dst[n][k] = *reinterpret_cast<const bf16x8*>((char*)SB(b, h) + lds_byte(wc * 32 + n * 16 + fr, k * 32 + fq * 8))
; #define MMA(ai, bj, At, Bt) do { __builtin_amdgcn_s_setprio(1); \
;     for (int m = 0; m < 4; ++m) for (int n = 0; n < 2; ++n) for (int k = 0; k < 2; ++k) \
;       acc[ai][bj][m][n] = __builtin_amdgcn_mfma_f32_16x16x32_bf16(At[m][k], Bt[n][k], acc[ai][bj][m][n], 0, 0, 0); \
;     __builtin_amdgcn_s_setprio(0); } while (0)
; #define WAIT_V(n) asm volatile("s_waitcnt vmcnt(" #n ")" ::: "memory")
; #define WAIT_L(n) asm volatile("s_waitcnt lgkmcnt(" #n ")" ::: "memory")
; #define BAR __builtin_amdgcn_s_barrier()
; #define SCHED __builtin_amdgcn_sched_barrier(0)
; template <int EPI> ...
;     ...
;     STAGE(SB(0, 1), B1p, t + 2);
;     WAIT_V(6); BAR; MMA(1, 1, At, B1); BAR;
;     LDB(B0, 1, 0); SCHED; LDA(At, 1, 0); STAGEA(SA(0, 1), A1, t + 2);
;     WAIT_L(8); BAR; WAIT_L(0); MMA(0, 0, At, B0); BAR; SCHED;
;     LDB(B1, 1, 1); STAGE(SB(1, 0), B0p, t + 3);
;     BAR; WAIT_L(0); MMA(0, 1, At, B1); BAR;
;     LDA(At, 1, 1); STAGEA(SA(1, 0), A0, t + 3);
	s_setprio 0
	v_readfirstlane_b32 s86, v160
	v_lshl_add_u64 v[174:175], v[242:243], 0, s[10:11]
	s_mov_b32 m0, s86
	v_readfirstlane_b32 s86, v161
	global_load_lds_dwordx4 v[174:175], off
	v_lshl_add_u64 v[174:175], v[244:245], 0, s[10:11]
	s_mov_b32 m0, s86
	s_nop 0
	global_load_lds_dwordx4 v[174:175], off
	s_waitcnt vmcnt(6)
	s_setprio 1
	s_barrier
	v_mfma_f32_16x16x32_bf16 v[28:31], v[190:193], v[222:225], v[28:31]
	v_mfma_f32_16x16x32_bf16 v[24:27], v[190:193], v[230:233], v[24:27]
	v_mfma_f32_16x16x32_bf16 v[20:23], v[198:201], v[222:225], v[20:23]
	v_mfma_f32_16x16x32_bf16 v[16:19], v[198:201], v[230:233], v[16:19]
	ds_read_b128 v[174:177], v156
	v_mfma_f32_16x16x32_bf16 v[12:15], v[206:209], v[222:225], v[12:15]
	v_mfma_f32_16x16x32_bf16 v[8:11], v[206:209], v[230:233], v[8:11]
	ds_read_b128 v[178:181], v156 offset:1024
	v_mfma_f32_16x16x32_bf16 v[4:7], v[214:217], v[222:225], v[4:7]
	v_mfma_f32_16x16x32_bf16 v[0:3], v[214:217], v[230:233], v[0:3]
	ds_read_b128 v[182:185], v156 offset:2048
	v_mfma_f32_16x16x32_bf16 v[28:31], v[194:197], v[226:229], v[28:31]
	v_mfma_f32_16x16x32_bf16 v[24:27], v[194:197], v[234:237], v[24:27]
	ds_read_b128 v[186:189], v156 offset:3072
	v_mfma_f32_16x16x32_bf16 v[20:23], v[202:205], v[226:229], v[20:23]
	v_mfma_f32_16x16x32_bf16 v[16:19], v[202:205], v[234:237], v[16:19]
	v_mfma_f32_16x16x32_bf16 v[12:15], v[210:213], v[226:229], v[12:15]
	v_mfma_f32_16x16x32_bf16 v[8:11], v[210:213], v[234:237], v[8:11]
	v_mfma_f32_16x16x32_bf16 v[4:7], v[218:221], v[226:229], v[4:7]
	v_mfma_f32_16x16x32_bf16 v[0:3], v[218:221], v[234:237], v[0:3]
	s_barrier
	s_setprio 0
	v_readfirstlane_b32 s86, v162
	v_lshl_add_u64 v[222:223], v[238:239], 0, s[12:13]
	s_mov_b32 m0, s86
	v_readfirstlane_b32 s86, v163
	ds_read_b128 v[190:193], v153 offset:32768
	ds_read_b128 v[194:197], v153 offset:33792
	ds_read_b128 v[198:201], v152 offset:32768
	ds_read_b128 v[202:205], v152 offset:33792
	ds_read_b128 v[206:209], v151 offset:32768
	ds_read_b128 v[210:213], v151 offset:33792
	ds_read_b128 v[214:217], v150 offset:32768
	ds_read_b128 v[218:221], v150 offset:33792
	global_load_lds_dwordx4 v[222:223], off
	v_lshl_add_u64 v[222:223], v[240:241], 0, s[12:13]
	s_mov_b32 m0, s86
	s_nop 0
	global_load_lds_dwordx4 v[222:223], off
	s_waitcnt lgkmcnt(8)
	s_setprio 1
	s_barrier
	s_waitcnt lgkmcnt(0)
	v_mfma_f32_16x16x32_bf16 v[124:127], v[190:193], v[174:177], v[124:127]
	v_mfma_f32_16x16x32_bf16 v[120:123], v[190:193], v[182:185], v[120:123]
	v_mfma_f32_16x16x32_bf16 v[116:119], v[198:201], v[174:177], v[116:119]
	v_mfma_f32_16x16x32_bf16 v[112:115], v[198:201], v[182:185], v[112:115]
	v_mfma_f32_16x16x32_bf16 v[108:111], v[206:209], v[174:177], v[108:111]
	v_mfma_f32_16x16x32_bf16 v[104:107], v[206:209], v[182:185], v[104:107]
	v_mfma_f32_16x16x32_bf16 v[100:103], v[214:217], v[174:177], v[100:103]
	v_mfma_f32_16x16x32_bf16 v[96:99], v[214:217], v[182:185], v[96:99]
	v_mfma_f32_16x16x32_bf16 v[124:127], v[194:197], v[178:181], v[124:127]
	v_mfma_f32_16x16x32_bf16 v[120:123], v[194:197], v[186:189], v[120:123]
	v_mfma_f32_16x16x32_bf16 v[116:119], v[202:205], v[178:181], v[116:119]
	v_mfma_f32_16x16x32_bf16 v[112:115], v[202:205], v[186:189], v[112:115]
	v_mfma_f32_16x16x32_bf16 v[108:111], v[210:213], v[178:181], v[108:111]
	v_mfma_f32_16x16x32_bf16 v[104:107], v[210:213], v[186:189], v[104:107]
	v_mfma_f32_16x16x32_bf16 v[100:103], v[218:221], v[178:181], v[100:103]
	v_mfma_f32_16x16x32_bf16 v[96:99], v[218:221], v[186:189], v[96:99]
	s_barrier
	s_setprio 0
	v_readfirstlane_b32 s86, v164
	v_lshl_add_u64 v[246:247], v[242:243], 0, s[14:15]
	s_mov_b32 m0, s86
	v_readfirstlane_b32 s86, v165
	ds_read_b128 v[222:225], v154
	ds_read_b128 v[226:229], v154 offset:1024
	ds_read_b128 v[230:233], v154 offset:2048
	ds_read_b128 v[234:237], v154 offset:3072
	global_load_lds_dwordx4 v[246:247], off
	v_lshl_add_u64 v[246:247], v[244:245], 0, s[14:15]
	s_mov_b32 m0, s86
	s_nop 0
	global_load_lds_dwordx4 v[246:247], off
	s_setprio 1
	s_barrier
	s_waitcnt lgkmcnt(0)
	v_mfma_f32_16x16x32_bf16 v[92:95], v[190:193], v[222:225], v[92:95]
	v_mfma_f32_16x16x32_bf16 v[88:91], v[190:193], v[230:233], v[88:91]
	v_mfma_f32_16x16x32_bf16 v[84:87], v[198:201], v[222:225], v[84:87]
	v_mfma_f32_16x16x32_bf16 v[80:83], v[198:201], v[230:233], v[80:83]
	v_mfma_f32_16x16x32_bf16 v[76:79], v[206:209], v[222:225], v[76:79]
	v_mfma_f32_16x16x32_bf16 v[72:75], v[206:209], v[230:233], v[72:75]
	v_mfma_f32_16x16x32_bf16 v[68:71], v[214:217], v[222:225], v[68:71]
	v_mfma_f32_16x16x32_bf16 v[64:67], v[214:217], v[230:233], v[64:67]
	v_mfma_f32_16x16x32_bf16 v[92:95], v[194:197], v[226:229], v[92:95]
	v_mfma_f32_16x16x32_bf16 v[88:91], v[194:197], v[234:237], v[88:91]
	v_mfma_f32_16x16x32_bf16 v[84:87], v[202:205], v[226:229], v[84:87]
	v_mfma_f32_16x16x32_bf16 v[80:83], v[202:205], v[234:237], v[80:83]
	v_mfma_f32_16x16x32_bf16 v[76:79], v[210:213], v[226:229], v[76:79]
	v_mfma_f32_16x16x32_bf16 v[72:75], v[210:213], v[234:237], v[72:75]
	v_mfma_f32_16x16x32_bf16 v[68:71], v[218:221], v[226:229], v[68:71]
	v_mfma_f32_16x16x32_bf16 v[64:67], v[218:221], v[234:237], v[64:67]
	s_barrier
	s_setprio 0
	v_readfirstlane_b32 s86, v166
	v_lshl_add_u64 v[238:239], v[238:239], 0, s[24:25]
	s_mov_b32 m0, s86
	v_readfirstlane_b32 s86, v168
	ds_read_b128 v[190:193], v153 offset:49152
	ds_read_b128 v[194:197], v153 offset:50176
	ds_read_b128 v[198:201], v152 offset:49152
	ds_read_b128 v[202:205], v152 offset:50176
	ds_read_b128 v[206:209], v151 offset:49152
	ds_read_b128 v[210:213], v151 offset:50176
	ds_read_b128 v[214:217], v150 offset:49152
	ds_read_b128 v[218:221], v150 offset:50176
	global_load_lds_dwordx4 v[238:239], off
	v_lshl_add_u64 v[238:239], v[240:241], 0, s[24:25]
	s_mov_b32 m0, s86
	s_nop 0
	global_load_lds_dwordx4 v[238:239], off
	s_setprio 1
	s_barrier
; #define STAGE(P, BASE, kt) do { const char* _g = (const char*)(BASE) + (size_t)((kt) * (BK * 2)); \
;     __builtin_amdgcn_global_load_lds((const unsigned*)(_g + (size_t)goff0), (unsigned*)((char*)(P) + tid_ * 16), 16, 0, 0); \
;     __builtin_amdgcn_global_load_lds((const unsigned*)(_g + (size_t)goff1), (unsigned*)((char*)(P) + tid_ * 16 + 8192), 16, 0, 0); } while (0)
; #define STAGEA(P, BASE, kt) do { const char* _g = (const char*)(BASE) + (size_t)((kt) * a_kbytes); \
;     __builtin_amdgcn_global_load_lds((const unsigned*)(_g + (size_t)goffA0), (unsigned*)((char*)(P) + tid_ * 16), 16, 0, 0); \
;     __builtin_amdgcn_global_load_lds((const unsigned*)(_g + (size_t)goffA1), (unsigned*)((char*)(P) + tid_ * 16 + 8192), 16, 0, 0); } while (0)
; #define LDA(dst, b, h) for (int m = 0; m < 4; ++m) for (int k = 0; k < 2; ++k) \
;     dst[m][k] = *reinterpret_cast<const bf16x8*>((char*)SA(b, h) + lds_byte(wr * 64 + m * 16 + fr, k * 32 + fq * 8))
; #define LDB(dst, b, h) for (int n = 0; n < 2; ++n) for (int k = 0; k < 2; ++k) \
;     dst[n][k] = *reinterpret_cast<const bf16x8*>((char*)SB(b, h) + lds_byte(wc * 32 + n * 16 + fr, k * 32 + fq * 8))
; #define MMA(ai, bj, At, Bt) do { __builtin_amdgcn_s_setprio(1); \
;     for (int m = 0; m < 4; ++m) for (int n = 0; n < 2; ++n) for (int k = 0; k < 2; ++k) \
;       acc[ai][bj][m][n] = __builtin_amdgcn_mfma_f32_16x16x32_bf16(At[m][k], Bt[n][k], acc[ai][bj][m][n], 0, 0, 0); \
;     __builtin_amdgcn_s_setprio(0); } while (0)
; #define WAIT_V(n) asm volatile("s_waitcnt vmcnt(" #n ")" ::: "memory")
; #define WAIT_L(n) asm volatile("s_waitcnt lgkmcnt(" #n ")" ::: "memory")
; #define BAR __builtin_amdgcn_s_barrier()
; #define SCHED __builtin_amdgcn_sched_barrier(0)
; template <int EPI> ...
;     ...
;     BAR; WAIT_L(0); MMA(1, 0, At, B0); BAR; SCHED;
;     STAGE(SB(1, 1), B1p, t + 3);
;     WAIT_V(6); BAR; MMA(1, 1, At, B1); BAR;
;   }
;   { LDB(B0, 0, 0); LDA(At, 0, 0); STAGEA(SA(1, 1), A1, nt - 1);
;     BAR; WAIT_L(0); MMA(0, 0, At, B0); BAR;
;     LDB(B1, 0, 1); BAR; WAIT_L(0); MMA(0, 1, At, B1); BAR;
	s_waitcnt lgkmcnt(0)
	v_mfma_f32_16x16x32_bf16 v[60:63], v[190:193], v[174:177], v[60:63]
	v_mfma_f32_16x16x32_bf16 v[56:59], v[190:193], v[182:185], v[56:59]
	v_mfma_f32_16x16x32_bf16 v[52:55], v[198:201], v[174:177], v[52:55]
	v_mfma_f32_16x16x32_bf16 v[48:51], v[198:201], v[182:185], v[48:51]
	v_mfma_f32_16x16x32_bf16 v[44:47], v[206:209], v[174:177], v[44:47]
	v_mfma_f32_16x16x32_bf16 v[40:43], v[206:209], v[182:185], v[40:43]
	v_mfma_f32_16x16x32_bf16 v[36:39], v[214:217], v[174:177], v[36:39]
	v_mfma_f32_16x16x32_bf16 v[32:35], v[214:217], v[182:185], v[32:35]
	v_mfma_f32_16x16x32_bf16 v[60:63], v[194:197], v[178:181], v[60:63]
	v_mfma_f32_16x16x32_bf16 v[56:59], v[194:197], v[186:189], v[56:59]
	v_mfma_f32_16x16x32_bf16 v[52:55], v[202:205], v[178:181], v[52:55]
	v_mfma_f32_16x16x32_bf16 v[48:51], v[202:205], v[186:189], v[48:51]
	v_mfma_f32_16x16x32_bf16 v[44:47], v[210:213], v[178:181], v[44:47]
	v_mfma_f32_16x16x32_bf16 v[40:43], v[210:213], v[186:189], v[40:43]
	v_mfma_f32_16x16x32_bf16 v[36:39], v[218:221], v[178:181], v[36:39]
	v_mfma_f32_16x16x32_bf16 v[32:35], v[218:221], v[186:189], v[32:35]
	s_barrier
	s_setprio 0
	v_readfirstlane_b32 s86, v169
	v_lshl_add_u64 v[174:175], v[242:243], 0, s[42:43]
	s_mov_b32 m0, s86
	v_readfirstlane_b32 s86, v170
	global_load_lds_dwordx4 v[174:175], off
	v_lshl_add_u64 v[174:175], v[244:245], 0, s[42:43]
	s_mov_b32 m0, s86
	s_nop 0
	global_load_lds_dwordx4 v[174:175], off
	s_waitcnt vmcnt(6)
	s_setprio 1
	s_barrier
	v_mfma_f32_16x16x32_bf16 v[28:31], v[190:193], v[222:225], v[28:31]
	v_mfma_f32_16x16x32_bf16 v[24:27], v[190:193], v[230:233], v[24:27]
	v_mfma_f32_16x16x32_bf16 v[20:23], v[198:201], v[222:225], v[20:23]
	v_mfma_f32_16x16x32_bf16 v[16:19], v[198:201], v[230:233], v[16:19]
	ds_read_b128 v[174:177], v171
	v_mfma_f32_16x16x32_bf16 v[12:15], v[206:209], v[222:225], v[12:15]
	v_mfma_f32_16x16x32_bf16 v[8:11], v[206:209], v[230:233], v[8:11]
	ds_read_b128 v[178:181], v171 offset:1024
	v_mfma_f32_16x16x32_bf16 v[4:7], v[214:217], v[222:225], v[4:7]
	v_mfma_f32_16x16x32_bf16 v[0:3], v[214:217], v[230:233], v[0:3]
	ds_read_b128 v[182:185], v171 offset:2048
	v_mfma_f32_16x16x32_bf16 v[28:31], v[194:197], v[226:229], v[28:31]
	v_mfma_f32_16x16x32_bf16 v[24:27], v[194:197], v[234:237], v[24:27]
	ds_read_b128 v[186:189], v171 offset:3072
	v_mfma_f32_16x16x32_bf16 v[20:23], v[202:205], v[226:229], v[20:23]
	v_mfma_f32_16x16x32_bf16 v[16:19], v[202:205], v[234:237], v[16:19]
	v_mfma_f32_16x16x32_bf16 v[12:15], v[210:213], v[226:229], v[12:15]
	v_mfma_f32_16x16x32_bf16 v[8:11], v[210:213], v[234:237], v[8:11]
	v_mfma_f32_16x16x32_bf16 v[4:7], v[218:221], v[226:229], v[4:7]
	v_mfma_f32_16x16x32_bf16 v[0:3], v[218:221], v[234:237], v[0:3]
	s_barrier
	s_setprio 0
	s_add_i32 s85, s85, 2
	s_add_u32 s54, s54, 0x10000
	s_addc_u32 s55, s55, 0
	s_add_u32 s52, s52, 0x100
	s_addc_u32 s53, s53, 0
	s_cmpk_lt_u32 s85, 0x54
	s_cbranch_scc1 .LBB0_782
	s_add_u32 s48, s48, 0x2bc000
	s_addc_u32 s49, s49, 0
	v_readfirstlane_b32 s52, v172
	v_lshl_add_u64 v[210:211], s[48:49], 0, v[130:131]
	s_mov_b32 m0, s52
	ds_read_b128 v[158:161], v171
	ds_read_b128 v[162:165], v171 offset:1024
	ds_read_b128 v[174:177], v171 offset:2048
	ds_read_b128 v[168:171], v171 offset:3072
	ds_read_b128 v[178:181], v153
	ds_read_b128 v[182:185], v153 offset:1024
	ds_read_b128 v[186:189], v152
	ds_read_b128 v[190:193], v152 offset:1024
	ds_read_b128 v[194:197], v151
	ds_read_b128 v[198:201], v151 offset:1024
	ds_read_b128 v[202:205], v150
	ds_read_b128 v[206:209], v150 offset:1024
	global_load_lds_dwordx4 v[210:211], off
	v_lshl_add_u64 v[210:211], s[48:49], 0, v[128:129]
	v_readfirstlane_b32 s48, v173
	s_mov_b32 m0, s48
	s_nop 0
	global_load_lds_dwordx4 v[210:211], off
	s_setprio 1
	s_barrier
	s_waitcnt lgkmcnt(0)
	v_mfma_f32_16x16x32_bf16 v[124:127], v[178:181], v[158:161], v[124:127]
	v_mfma_f32_16x16x32_bf16 v[120:123], v[178:181], v[174:177], v[120:123]
	v_mfma_f32_16x16x32_bf16 v[108:111], v[194:197], v[158:161], v[108:111]
	v_mfma_f32_16x16x32_bf16 v[104:107], v[194:197], v[174:177], v[104:107]
	v_mfma_f32_16x16x32_bf16 v[124:127], v[182:185], v[162:165], v[124:127]
	v_mfma_f32_16x16x32_bf16 v[120:123], v[182:185], v[168:171], v[120:123]
	v_mfma_f32_16x16x32_bf16 v[116:119], v[186:189], v[158:161], v[116:119]
	v_mfma_f32_16x16x32_bf16 v[112:115], v[186:189], v[174:177], v[112:115]
	v_mfma_f32_16x16x32_bf16 v[108:111], v[198:201], v[162:165], v[108:111]
	v_mfma_f32_16x16x32_bf16 v[104:107], v[198:201], v[168:171], v[104:107]
	v_mfma_f32_16x16x32_bf16 v[100:103], v[202:205], v[158:161], v[100:103]
	v_mfma_f32_16x16x32_bf16 v[96:99], v[202:205], v[174:177], v[96:99]
	v_mfma_f32_16x16x32_bf16 v[210:213], v[190:193], v[162:165], v[116:119]
	v_mfma_f32_16x16x32_bf16 v[214:217], v[190:193], v[168:171], v[112:115]
	v_mfma_f32_16x16x32_bf16 v[218:221], v[206:209], v[162:165], v[100:103]
	v_mfma_f32_16x16x32_bf16 v[222:225], v[206:209], v[168:171], v[96:99]
	s_barrier
	s_setprio 0
	s_nop 1
	ds_read_b128 v[96:99], v167
	ds_read_b128 v[100:103], v167 offset:1024
	ds_read_b128 v[112:115], v167 offset:2048
	ds_read_b128 v[116:119], v167 offset:3072
	s_setprio 1
	s_barrier
; #define LDA(dst, b, h) for (int m = 0; m < 4; ++m) for (int k = 0; k < 2; ++k) \
;     dst[m][k] = *reinterpret_cast<const bf16x8*>((char*)SA(b, h) + lds_byte(wr * 64 + m * 16 + fr, k * 32 + fq * 8))
; #define LDB(dst, b, h) for (int n = 0; n < 2; ++n) for (int k = 0; k < 2; ++k) \
;     dst[n][k] = *reinterpret_cast<const bf16x8*>((char*)SB(b, h) + lds_byte(wc * 32 + n * 16 + fr, k * 32 + fq * 8))
; #define MMA(ai, bj, At, Bt) do { __builtin_amdgcn_s_setprio(1); \
;     for (int m = 0; m < 4; ++m) for (int n = 0; n < 2; ++n) for (int k = 0; k < 2; ++k) \
;       acc[ai][bj][m][n] = __builtin_amdgcn_mfma_f32_16x16x32_bf16(At[m][k], Bt[n][k], acc[ai][bj][m][n], 0, 0, 0); \
;     __builtin_amdgcn_s_setprio(0); } while (0)
; #define WAIT_V(n) asm volatile("s_waitcnt vmcnt(" #n ")" ::: "memory")
; #define WAIT_L(n) asm volatile("s_waitcnt lgkmcnt(" #n ")" ::: "memory")
; #define BAR __builtin_amdgcn_s_barrier()
; template <int EPI> ...
;     ...
;     LDB(B1, 0, 1); BAR; WAIT_L(0); MMA(0, 1, At, B1); BAR;
;     LDA(At, 0, 1); WAIT_V(4); BAR; WAIT_L(0); MMA(1, 0, At, B0); MMA(1, 1, At, B1); BAR; }
;   { LDB(B0, 1, 0); LDA(At, 1, 0); WAIT_V(2); BAR; WAIT_L(0); MMA(0, 0, At, B0); BAR;
;     LDB(B1, 1, 1); WAIT_V(0); BAR; WAIT_L(0); MMA(0, 1, At, B1); BAR;
	s_waitcnt lgkmcnt(0)
	v_mfma_f32_16x16x32_bf16 v[92:95], v[178:181], v[96:99], v[92:95]
	v_mfma_f32_16x16x32_bf16 v[88:91], v[178:181], v[112:115], v[88:91]
	v_mfma_f32_16x16x32_bf16 v[76:79], v[194:197], v[96:99], v[76:79]
	v_mfma_f32_16x16x32_bf16 v[72:75], v[194:197], v[112:115], v[72:75]
	v_mfma_f32_16x16x32_bf16 v[92:95], v[182:185], v[100:103], v[92:95]
	v_mfma_f32_16x16x32_bf16 v[88:91], v[182:185], v[116:119], v[88:91]
	v_mfma_f32_16x16x32_bf16 v[84:87], v[186:189], v[96:99], v[84:87]
	v_mfma_f32_16x16x32_bf16 v[80:83], v[186:189], v[112:115], v[80:83]
	v_mfma_f32_16x16x32_bf16 v[76:79], v[198:201], v[100:103], v[76:79]
	v_mfma_f32_16x16x32_bf16 v[72:75], v[198:201], v[116:119], v[72:75]
	v_mfma_f32_16x16x32_bf16 v[68:71], v[202:205], v[96:99], v[68:71]
	v_mfma_f32_16x16x32_bf16 v[64:67], v[202:205], v[112:115], v[64:67]
	v_mfma_f32_16x16x32_bf16 v[178:181], v[190:193], v[100:103], v[84:87]
	v_mfma_f32_16x16x32_bf16 v[182:185], v[190:193], v[116:119], v[80:83]
	v_mfma_f32_16x16x32_bf16 v[186:189], v[206:209], v[100:103], v[68:71]
	v_mfma_f32_16x16x32_bf16 v[190:193], v[206:209], v[116:119], v[64:67]
	s_barrier
	s_setprio 0
	s_nop 1
	ds_read_b128 v[64:67], v153 offset:16384
	ds_read_b128 v[68:71], v153 offset:17408
	ds_read_b128 v[80:83], v152 offset:16384
	ds_read_b128 v[84:87], v152 offset:17408
	ds_read_b128 v[194:197], v151 offset:16384
	ds_read_b128 v[198:201], v151 offset:17408
	ds_read_b128 v[202:205], v150 offset:16384
	ds_read_b128 v[206:209], v150 offset:17408
	s_waitcnt vmcnt(4)
	s_setprio 1
	s_barrier
	s_waitcnt lgkmcnt(0)
	v_mfma_f32_16x16x32_bf16 v[60:63], v[64:67], v[158:161], v[60:63]
	v_mfma_f32_16x16x32_bf16 v[56:59], v[64:67], v[174:177], v[56:59]
	v_mfma_f32_16x16x32_bf16 v[44:47], v[194:197], v[158:161], v[44:47]
	v_mfma_f32_16x16x32_bf16 v[40:43], v[194:197], v[174:177], v[40:43]
	v_mfma_f32_16x16x32_bf16 v[60:63], v[68:71], v[162:165], v[60:63]
	v_mfma_f32_16x16x32_bf16 v[56:59], v[68:71], v[168:171], v[56:59]
	v_mfma_f32_16x16x32_bf16 v[52:55], v[80:83], v[158:161], v[52:55]
	v_mfma_f32_16x16x32_bf16 v[48:51], v[80:83], v[174:177], v[48:51]
	v_mfma_f32_16x16x32_bf16 v[44:47], v[198:201], v[162:165], v[44:47]
	v_mfma_f32_16x16x32_bf16 v[40:43], v[198:201], v[168:171], v[40:43]
	v_mfma_f32_16x16x32_bf16 v[36:39], v[202:205], v[158:161], v[36:39]
	v_mfma_f32_16x16x32_bf16 v[32:35], v[202:205], v[174:177], v[32:35]
	v_mfma_f32_16x16x32_bf16 v[226:229], v[84:87], v[162:165], v[52:55]
	v_mfma_f32_16x16x32_bf16 v[230:233], v[84:87], v[168:171], v[48:51]
	v_mfma_f32_16x16x32_bf16 v[158:161], v[206:209], v[162:165], v[36:39]
	v_mfma_f32_16x16x32_bf16 v[162:165], v[206:209], v[168:171], v[32:35]
	s_setprio 0
	s_setprio 1
	v_mfma_f32_16x16x32_bf16 v[28:31], v[64:67], v[96:99], v[28:31]
	v_mfma_f32_16x16x32_bf16 v[24:27], v[64:67], v[112:115], v[24:27]
	v_mfma_f32_16x16x32_bf16 v[12:15], v[194:197], v[96:99], v[12:15]
	v_mfma_f32_16x16x32_bf16 v[8:11], v[194:197], v[112:115], v[8:11]
	v_mfma_f32_16x16x32_bf16 v[28:31], v[68:71], v[100:103], v[28:31]
	v_mfma_f32_16x16x32_bf16 v[24:27], v[68:71], v[116:119], v[24:27]
	v_mfma_f32_16x16x32_bf16 v[20:23], v[80:83], v[96:99], v[20:23]
	v_mfma_f32_16x16x32_bf16 v[16:19], v[80:83], v[112:115], v[16:19]
	v_mfma_f32_16x16x32_bf16 v[12:15], v[198:201], v[100:103], v[12:15]
	v_mfma_f32_16x16x32_bf16 v[8:11], v[198:201], v[116:119], v[8:11]
	v_mfma_f32_16x16x32_bf16 v[4:7], v[202:205], v[96:99], v[4:7]
	v_mfma_f32_16x16x32_bf16 v[0:3], v[202:205], v[112:115], v[0:3]
	v_mfma_f32_16x16x32_bf16 v[166:169], v[84:87], v[100:103], v[20:23]
	v_mfma_f32_16x16x32_bf16 v[170:173], v[84:87], v[116:119], v[16:19]
	v_mfma_f32_16x16x32_bf16 v[174:177], v[206:209], v[100:103], v[4:7]
	v_mfma_f32_16x16x32_bf16 v[194:197], v[206:209], v[116:119], v[0:3]
	s_barrier
	s_setprio 0
	s_nop 1
	ds_read_b128 v[0:3], v156
	ds_read_b128 v[4:7], v156 offset:1024
	ds_read_b128 v[198:201], v156 offset:2048
	ds_read_b128 v[202:205], v156 offset:3072
	ds_read_b128 v[16:19], v153 offset:32768
	ds_read_b128 v[20:23], v153 offset:33792
	ds_read_b128 v[32:35], v152 offset:32768
	ds_read_b128 v[36:39], v152 offset:33792
	ds_read_b128 v[48:51], v151 offset:32768
	ds_read_b128 v[52:55], v151 offset:33792
	ds_read_b128 v[206:209], v150 offset:32768
	ds_read_b128 v[234:237], v150 offset:33792
	s_waitcnt vmcnt(2)
	s_setprio 1
	s_barrier
	s_waitcnt lgkmcnt(0)
	v_mfma_f32_16x16x32_bf16 v[64:67], v[16:19], v[0:3], v[124:127]
	v_mfma_f32_16x16x32_bf16 v[116:119], v[20:23], v[4:7], v[64:67]
	v_mfma_f32_16x16x32_bf16 v[64:67], v[16:19], v[198:201], v[120:123]
	v_mfma_f32_16x16x32_bf16 v[112:115], v[20:23], v[202:205], v[64:67]
	v_mfma_f32_16x16x32_bf16 v[64:67], v[32:35], v[0:3], v[210:213]
	v_mfma_f32_16x16x32_bf16 v[100:103], v[36:39], v[4:7], v[64:67]
	v_mfma_f32_16x16x32_bf16 v[64:67], v[32:35], v[198:201], v[214:217]
	v_mfma_f32_16x16x32_bf16 v[96:99], v[36:39], v[202:205], v[64:67]
	v_mfma_f32_16x16x32_bf16 v[64:67], v[48:51], v[0:3], v[108:111]
	v_mfma_f32_16x16x32_bf16 v[84:87], v[52:55], v[4:7], v[64:67]
	v_mfma_f32_16x16x32_bf16 v[64:67], v[48:51], v[198:201], v[104:107]
	v_mfma_f32_16x16x32_bf16 v[80:83], v[52:55], v[202:205], v[64:67]
	v_mfma_f32_16x16x32_bf16 v[64:67], v[206:209], v[0:3], v[218:221]
	v_mfma_f32_16x16x32_bf16 v[68:71], v[234:237], v[4:7], v[64:67]
	v_mfma_f32_16x16x32_bf16 v[64:67], v[206:209], v[198:201], v[222:225]
	v_mfma_f32_16x16x32_bf16 v[64:67], v[234:237], v[202:205], v[64:67]
	s_barrier
	s_setprio 0
	ds_read_b128 v[210:213], v154
	ds_read_b128 v[214:217], v154 offset:1024
	ds_read_b128 v[218:221], v154 offset:2048
	ds_read_b128 v[154:157], v154 offset:3072
	s_waitcnt vmcnt(0)
	s_setprio 1
	s_barrier
; __device__ __forceinline__ u16 f2bf(float f) { unsigned u = __float_as_uint(f); u += 0x7fffu + ((u >> 16) & 1u); return (u16)(u >> 16); }
; __device__ __forceinline__ float frcp(float x) { return __builtin_amdgcn_rcpf(x); }
; #define LDA(dst, b, h) for (int m = 0; m < 4; ++m) for (int k = 0; k < 2; ++k) \
;     dst[m][k] = *reinterpret_cast<const bf16x8*>((char*)SA(b, h) + lds_byte(wr * 64 + m * 16 + fr, k * 32 + fq * 8))
; #define LDB(dst, b, h) for (int n = 0; n < 2; ++n) for (int k = 0; k < 2; ++k) \
;     dst[n][k] = *reinterpret_cast<const bf16x8*>((char*)SB(b, h) + lds_byte(wc * 32 + n * 16 + fr, k * 32 + fq * 8))
; #define WAIT_V(n) asm volatile("s_waitcnt vmcnt(" #n ")" ::: "memory")
; #define WAIT_L(n) asm volatile("s_waitcnt lgkmcnt(" #n ")" ::: "memory")
; #define BAR __builtin_amdgcn_s_barrier()
; template <int EPI> ...
;     ...
;   { LDB(B0, 1, 0); LDA(At, 1, 0); WAIT_V(2); BAR; WAIT_L(0); MMA(0, 0, At, B0); BAR;
;     LDB(B1, 1, 1); WAIT_V(0); BAR; WAIT_L(0); MMA(0, 1, At, B1); BAR;
;     LDA(At, 1, 1); BAR; WAIT_L(0); MMA(1, 0, At, B0); MMA(1, 1, At, B1); BAR; }
;   if (wr == 0) BAR;
;   {
;     constexpr int NC = (EPI == EPI_GU) ? 128 : 256;
;     constexpr int RB = NC * 2;
;     char* tb = (char*)shm;
; #pragma unroll
;     for (int ai = 0; ai < 2; ++ai)
; #pragma unroll
;       for (int m = 0; m < 4; ++m)
; #pragma unroll
;         for (int j = 0; j < 4; ++j) {
;           const int r = ai * 128 + wr * 64 + m * 16 + fq * 4 + j;
;           float rs = 1.0f;
;           if (EPI != EPI_RES) rs = e.rstd[brow + r];
;           char* rowp = tb + r * RB + fr * 2;
;           if (EPI == EPI_GU) {
; #pragma unroll
;             for (int n = 0; n < 2; ++n) {
;               float g = acc[ai][0][m][n][j] * rs, u = acc[ai][1][m][n][j] * rs;
;               float h = g * frcp(1.0f + __expf(-g)) * u;
;               const int seg = (wc * 2 + n) ^ fq;
;               *(u16*)(rowp + seg * 32) = f2bf(h);
;             }
;           } else {
; #pragma unroll
;             for (int bj = 0; bj < 2; ++bj)
; #pragma unroll
;               for (int n = 0; n < 2; ++n) {
;                 const int seg = (bj * 8 + wc * 2 + n) ^ fq;
;                 *(u16*)(rowp + seg * 32) = f2bf(acc[ai][bj][m][n][j] * rs);
;               }
;           }
;         }
	s_waitcnt lgkmcnt(0)
	v_mfma_f32_16x16x32_bf16 v[92:95], v[16:19], v[210:213], v[92:95]
	v_mfma_f32_16x16x32_bf16 v[16:19], v[16:19], v[218:221], v[88:91]
	v_mfma_f32_16x16x32_bf16 v[120:123], v[20:23], v[154:157], v[16:19]
	v_mfma_f32_16x16x32_bf16 v[16:19], v[32:35], v[210:213], v[178:181]
	v_mfma_f32_16x16x32_bf16 v[108:111], v[36:39], v[214:217], v[16:19]
	v_mfma_f32_16x16x32_bf16 v[16:19], v[32:35], v[218:221], v[182:185]
	v_mfma_f32_16x16x32_bf16 v[104:107], v[36:39], v[154:157], v[16:19]
	v_mfma_f32_16x16x32_bf16 v[16:19], v[48:51], v[210:213], v[76:79]
	v_mfma_f32_16x16x32_bf16 v[124:127], v[20:23], v[214:217], v[92:95]
	v_mfma_f32_16x16x32_bf16 v[92:95], v[52:55], v[214:217], v[16:19]
	v_mfma_f32_16x16x32_bf16 v[16:19], v[48:51], v[218:221], v[72:75]
	v_mfma_f32_16x16x32_bf16 v[88:91], v[52:55], v[154:157], v[16:19]
	v_mfma_f32_16x16x32_bf16 v[16:19], v[206:209], v[210:213], v[186:189]
	v_mfma_f32_16x16x32_bf16 v[76:79], v[234:237], v[214:217], v[16:19]
	v_mfma_f32_16x16x32_bf16 v[16:19], v[206:209], v[218:221], v[190:193]
	v_mfma_f32_16x16x32_bf16 v[72:75], v[234:237], v[154:157], v[16:19]
	s_barrier
	s_setprio 0
	ds_read_b128 v[178:181], v153 offset:49152
	ds_read_b128 v[182:185], v153 offset:50176
	ds_read_b128 v[186:189], v152 offset:49152
	ds_read_b128 v[190:193], v152 offset:50176
	ds_read_b128 v[206:209], v151 offset:49152
	ds_read_b128 v[222:225], v151 offset:50176
	ds_read_b128 v[234:237], v150 offset:49152
	ds_read_b128 v[150:153], v150 offset:50176
	s_setprio 1
	s_barrier
	s_waitcnt lgkmcnt(0)
	v_mfma_f32_16x16x32_bf16 v[16:19], v[178:181], v[0:3], v[60:63]
	v_mfma_f32_16x16x32_bf16 v[52:55], v[182:185], v[4:7], v[16:19]
	v_mfma_f32_16x16x32_bf16 v[16:19], v[178:181], v[198:201], v[56:59]
	v_mfma_f32_16x16x32_bf16 v[48:51], v[182:185], v[202:205], v[16:19]
	v_mfma_f32_16x16x32_bf16 v[16:19], v[186:189], v[0:3], v[226:229]
	v_mfma_f32_16x16x32_bf16 v[36:39], v[190:193], v[4:7], v[16:19]
	v_mfma_f32_16x16x32_bf16 v[16:19], v[186:189], v[198:201], v[230:233]
	v_mfma_f32_16x16x32_bf16 v[32:35], v[190:193], v[202:205], v[16:19]
	v_mfma_f32_16x16x32_bf16 v[16:19], v[206:209], v[0:3], v[44:47]
	v_mfma_f32_16x16x32_bf16 v[0:3], v[234:237], v[0:3], v[158:161]
	v_mfma_f32_16x16x32_bf16 v[20:23], v[222:225], v[4:7], v[16:19]
	v_mfma_f32_16x16x32_bf16 v[16:19], v[206:209], v[198:201], v[40:43]
	v_mfma_f32_16x16x32_bf16 v[4:7], v[150:153], v[4:7], v[0:3]
	v_mfma_f32_16x16x32_bf16 v[0:3], v[234:237], v[198:201], v[162:165]
	v_mfma_f32_16x16x32_bf16 v[16:19], v[222:225], v[202:205], v[16:19]
	v_mfma_f32_16x16x32_bf16 v[0:3], v[150:153], v[202:205], v[0:3]
	s_setprio 0
	s_setprio 1
	v_mfma_f32_16x16x32_bf16 v[24:27], v[178:181], v[218:221], v[24:27]
	v_mfma_f32_16x16x32_bf16 v[56:59], v[182:185], v[154:157], v[24:27]
	v_mfma_f32_16x16x32_bf16 v[24:27], v[186:189], v[210:213], v[166:169]
	v_mfma_f32_16x16x32_bf16 v[44:47], v[190:193], v[214:217], v[24:27]
	v_mfma_f32_16x16x32_bf16 v[24:27], v[186:189], v[218:221], v[170:173]
	v_mfma_f32_16x16x32_bf16 v[8:11], v[206:209], v[218:221], v[8:11]
	v_mfma_f32_16x16x32_bf16 v[28:31], v[178:181], v[210:213], v[28:31]
	v_mfma_f32_16x16x32_bf16 v[40:43], v[190:193], v[154:157], v[24:27]
	v_mfma_f32_16x16x32_bf16 v[12:15], v[206:209], v[210:213], v[12:15]
	v_mfma_f32_16x16x32_bf16 v[24:27], v[222:225], v[154:157], v[8:11]
	v_mfma_f32_16x16x32_bf16 v[8:11], v[234:237], v[210:213], v[174:177]
	v_mfma_f32_16x16x32_bf16 v[60:63], v[182:185], v[214:217], v[28:31]
	v_mfma_f32_16x16x32_bf16 v[28:31], v[222:225], v[214:217], v[12:15]
	v_mfma_f32_16x16x32_bf16 v[12:15], v[150:153], v[214:217], v[8:11]
	v_mfma_f32_16x16x32_bf16 v[8:11], v[234:237], v[218:221], v[194:197]
	v_mfma_f32_16x16x32_bf16 v[8:11], v[150:153], v[154:157], v[8:11]
	s_barrier
	s_setprio 0
	v_cmp_gt_u32_e32 vcc, s67, v144
	s_and_saveexec_b64 s[48:49], vcc
	s_cbranch_execz .LBB0_785
	s_barrier
.LBB0_785:
	s_or_b64 exec, exec, s[48:49]
	v_lshl_add_u32 v144, v149, 1, 0
	v_lshlrev_b32_e32 v148, 1, v148
	v_lshlrev_b32_e32 v150, 11, v145
	v_lshlrev_b32_e32 v147, 15, v147
	v_add3_u32 v144, v144, v150, v147
	v_xor_b32_e32 v147, v148, v145
	v_lshlrev_b32_e32 v147, 5, v147
	v_cvt_pk_bf16_f32 v116, v116, v116
	v_add_u32_e32 v150, v144, v147
	ds_write_b16_d16_hi v150, v116
	v_bitop3_b32 v116, v148, v145, 1 bitop3:0x36
	v_lshlrev_b32_e32 v116, 5, v116
	v_cvt_pk_bf16_f32 v112, v112, v112
	v_add_u32_e32 v151, v144, v116
	v_bitop3_b32 v149, v148, v145, 8 bitop3:0x36
	ds_write_b16_d16_hi v151, v112
	v_bfe_u32 v112, v124, 16, 1
	v_add3_u32 v112, v124, v112, s77
	v_lshlrev_b32_e32 v124, 5, v149
	v_add_u32_e32 v149, v144, v124
	ds_write_b16_d16_hi v149, v112
	v_bitop3_b32 v112, v148, v145, 9 bitop3:0x36
	v_lshlrev_b32_e32 v112, 5, v112
	v_cvt_pk_bf16_f32 v120, v120, v120
	v_add_u32_e32 v145, v144, v112
	ds_write_b16_d16_hi v145, v120
	v_cvt_pk_bf16_f32 v117, v117, v117
	ds_write_b16_d16_hi v150, v117 offset:512
	v_cvt_pk_bf16_f32 v113, v113, v113
	ds_write_b16_d16_hi v151, v113 offset:512
	v_bfe_u32 v113, v125, 16, 1
	v_add3_u32 v113, v125, v113, s77
	ds_write_b16_d16_hi v149, v113 offset:512
	v_bfe_u32 v113, v121, 16, 1
	v_add3_u32 v113, v121, v113, s77
	ds_write_b16_d16_hi v145, v113 offset:512
	v_bfe_u32 v113, v118, 16, 1
	v_add3_u32 v113, v118, v113, s77
	ds_write_b16_d16_hi v150, v113 offset:1024
	v_bfe_u32 v113, v114, 16, 1
	v_add3_u32 v113, v114, v113, s77
	ds_write_b16_d16_hi v151, v113 offset:1024
	v_bfe_u32 v113, v126, 16, 1
	v_add3_u32 v113, v126, v113, s77
	ds_write_b16_d16_hi v149, v113 offset:1024
	v_bfe_u32 v113, v122, 16, 1
	v_add3_u32 v113, v122, v113, s77
	ds_write_b16_d16_hi v145, v113 offset:1024
	v_bfe_u32 v113, v119, 16, 1
; __device__ __forceinline__ u16 f2bf(float f) { unsigned u = __float_as_uint(f); u += 0x7fffu + ((u >> 16) & 1u); return (u16)(u >> 16); }
; __device__ __forceinline__ float frcp(float x) { return __builtin_amdgcn_rcpf(x); }
; template <int EPI> ...
;     ...
;     for (int ai = 0; ai < 2; ++ai)
; #pragma unroll
;       for (int m = 0; m < 4; ++m)
; #pragma unroll
;         for (int j = 0; j < 4; ++j) {
;           const int r = ai * 128 + wr * 64 + m * 16 + fq * 4 + j;
;           float rs = 1.0f;
;           if (EPI != EPI_RES) rs = e.rstd[brow + r];
;           char* rowp = tb + r * RB + fr * 2;
;           if (EPI == EPI_GU) {
; #pragma unroll
;             for (int n = 0; n < 2; ++n) {
;               float g = acc[ai][0][m][n][j] * rs, u = acc[ai][1][m][n][j] * rs;
;               float h = g * frcp(1.0f + __expf(-g)) * u;
;               const int seg = (wc * 2 + n) ^ fq;
;               *(u16*)(rowp + seg * 32) = f2bf(h);
;             }
;           } else {
; #pragma unroll
;             for (int bj = 0; bj < 2; ++bj)
; #pragma unroll
;               for (int n = 0; n < 2; ++n) {
;                 const int seg = (bj * 8 + wc * 2 + n) ^ fq;
;                 *(u16*)(rowp + seg * 32) = f2bf(acc[ai][bj][m][n][j] * rs);
;               }
;           }
;         }
	v_add3_u32 v113, v119, v113, s77
	ds_write_b16_d16_hi v150, v113 offset:1536
	v_bfe_u32 v113, v115, 16, 1
	v_add3_u32 v113, v115, v113, s77
	ds_write_b16_d16_hi v151, v113 offset:1536
	v_bfe_u32 v113, v127, 16, 1
	v_add3_u32 v113, v127, v113, s77
	ds_write_b16_d16_hi v149, v113 offset:1536
	v_bfe_u32 v113, v123, 16, 1
	v_add3_u32 v113, v123, v113, s77
	ds_write_b16_d16_hi v145, v113 offset:1536
	v_cvt_pk_bf16_f32 v100, v100, v100
	ds_write_b16_d16_hi v150, v100 offset:8192
	v_cvt_pk_bf16_f32 v96, v96, v96
	ds_write_b16_d16_hi v151, v96 offset:8192
	v_bfe_u32 v96, v108, 16, 1
	v_add3_u32 v96, v108, v96, s77
	ds_write_b16_d16_hi v149, v96 offset:8192
	v_bfe_u32 v96, v104, 16, 1
	v_add3_u32 v96, v104, v96, s77
	ds_write_b16_d16_hi v145, v96 offset:8192
	v_bfe_u32 v96, v101, 16, 1
	v_add3_u32 v96, v101, v96, s77
	ds_write_b16_d16_hi v150, v96 offset:8704
	v_bfe_u32 v96, v97, 16, 1
	v_add3_u32 v96, v97, v96, s77
	ds_write_b16_d16_hi v151, v96 offset:8704
	v_bfe_u32 v96, v109, 16, 1
	v_add3_u32 v96, v109, v96, s77
	ds_write_b16_d16_hi v149, v96 offset:8704
	v_bfe_u32 v96, v105, 16, 1
	v_add3_u32 v96, v105, v96, s77
	ds_write_b16_d16_hi v145, v96 offset:8704
	v_bfe_u32 v96, v102, 16, 1
	v_add3_u32 v96, v102, v96, s77
	ds_write_b16_d16_hi v150, v96 offset:9216
	v_bfe_u32 v96, v98, 16, 1
	v_add3_u32 v96, v98, v96, s77
	ds_write_b16_d16_hi v151, v96 offset:9216
	v_bfe_u32 v96, v110, 16, 1
	v_add3_u32 v96, v110, v96, s77
	ds_write_b16_d16_hi v149, v96 offset:9216
	v_bfe_u32 v96, v106, 16, 1
	v_add3_u32 v96, v106, v96, s77
	ds_write_b16_d16_hi v145, v96 offset:9216
	v_bfe_u32 v96, v103, 16, 1
	v_add3_u32 v96, v103, v96, s77
	ds_write_b16_d16_hi v150, v96 offset:9728
	v_bfe_u32 v96, v99, 16, 1
	v_add3_u32 v96, v99, v96, s77
	ds_write_b16_d16_hi v151, v96 offset:9728
	v_bfe_u32 v96, v111, 16, 1
	v_add3_u32 v96, v111, v96, s77
	ds_write_b16_d16_hi v149, v96 offset:9728
	v_bfe_u32 v96, v107, 16, 1
	v_add3_u32 v96, v107, v96, s77
	ds_write_b16_d16_hi v145, v96 offset:9728
	v_bfe_u32 v96, v84, 16, 1
	v_add3_u32 v84, v84, v96, s77
	ds_write_b16_d16_hi v150, v84 offset:16384
	v_bfe_u32 v84, v80, 16, 1
	v_add3_u32 v80, v80, v84, s77
	ds_write_b16_d16_hi v151, v80 offset:16384
	v_bfe_u32 v80, v92, 16, 1
	v_add3_u32 v80, v92, v80, s77
	ds_write_b16_d16_hi v149, v80 offset:16384
	v_bfe_u32 v80, v88, 16, 1
	v_add3_u32 v80, v88, v80, s77
	ds_write_b16_d16_hi v145, v80 offset:16384
	v_bfe_u32 v80, v85, 16, 1
	v_add3_u32 v80, v85, v80, s77
	ds_write_b16_d16_hi v150, v80 offset:16896
	v_bfe_u32 v80, v81, 16, 1
	v_add3_u32 v80, v81, v80, s77
	ds_write_b16_d16_hi v151, v80 offset:16896
	v_bfe_u32 v80, v93, 16, 1
	v_add3_u32 v80, v93, v80, s77
	ds_write_b16_d16_hi v149, v80 offset:16896
	v_bfe_u32 v80, v89, 16, 1
	v_add3_u32 v80, v89, v80, s77
	ds_write_b16_d16_hi v145, v80 offset:16896
	v_bfe_u32 v80, v86, 16, 1
	v_add3_u32 v80, v86, v80, s77
	ds_write_b16_d16_hi v150, v80 offset:17408
	v_bfe_u32 v80, v82, 16, 1
	v_add3_u32 v80, v82, v80, s77
	ds_write_b16_d16_hi v151, v80 offset:17408
	v_bfe_u32 v80, v94, 16, 1
	v_add3_u32 v80, v94, v80, s77
	ds_write_b16_d16_hi v149, v80 offset:17408
	v_bfe_u32 v80, v90, 16, 1
	v_add3_u32 v80, v90, v80, s77
	ds_write_b16_d16_hi v145, v80 offset:17408
	v_bfe_u32 v80, v87, 16, 1
	v_add3_u32 v80, v87, v80, s77
	ds_write_b16_d16_hi v150, v80 offset:17920
	v_bfe_u32 v80, v83, 16, 1
	v_add3_u32 v80, v83, v80, s77
	ds_write_b16_d16_hi v151, v80 offset:17920
	v_bfe_u32 v80, v95, 16, 1
	v_add3_u32 v80, v95, v80, s77
	ds_write_b16_d16_hi v149, v80 offset:17920
	v_bfe_u32 v80, v91, 16, 1
	v_add3_u32 v80, v91, v80, s77
	ds_write_b16_d16_hi v145, v80 offset:17920
	v_bfe_u32 v80, v68, 16, 1
	v_add3_u32 v68, v68, v80, s77
	ds_write_b16_d16_hi v150, v68 offset:24576
	v_bfe_u32 v68, v64, 16, 1
	v_add3_u32 v64, v64, v68, s77
	ds_write_b16_d16_hi v151, v64 offset:24576
	v_bfe_u32 v64, v76, 16, 1
	v_add3_u32 v64, v76, v64, s77
	ds_write_b16_d16_hi v149, v64 offset:24576
	v_bfe_u32 v64, v72, 16, 1
	v_add3_u32 v64, v72, v64, s77
	ds_write_b16_d16_hi v145, v64 offset:24576
	v_bfe_u32 v64, v69, 16, 1
	v_add3_u32 v64, v69, v64, s77
	ds_write_b16_d16_hi v150, v64 offset:25088
	v_bfe_u32 v64, v65, 16, 1
	v_add3_u32 v64, v65, v64, s77
	ds_write_b16_d16_hi v151, v64 offset:25088
	v_bfe_u32 v64, v77, 16, 1
	v_add3_u32 v64, v77, v64, s77
	ds_write_b16_d16_hi v149, v64 offset:25088
	v_bfe_u32 v64, v73, 16, 1
	v_add3_u32 v64, v73, v64, s77
	ds_write_b16_d16_hi v145, v64 offset:25088
	v_bfe_u32 v64, v70, 16, 1
	v_add3_u32 v64, v70, v64, s77
	ds_write_b16_d16_hi v150, v64 offset:25600
	v_bfe_u32 v64, v66, 16, 1
	v_add3_u32 v64, v66, v64, s77
	ds_write_b16_d16_hi v151, v64 offset:25600
	v_bfe_u32 v64, v78, 16, 1
	v_add3_u32 v64, v78, v64, s77
	ds_write_b16_d16_hi v149, v64 offset:25600
	v_bfe_u32 v64, v74, 16, 1
	v_add3_u32 v64, v74, v64, s77
	ds_write_b16_d16_hi v145, v64 offset:25600
	v_bfe_u32 v64, v71, 16, 1
	v_add3_u32 v64, v71, v64, s77
	ds_write_b16_d16_hi v150, v64 offset:26112
	v_bfe_u32 v64, v67, 16, 1
	v_add3_u32 v64, v67, v64, s77
	ds_write_b16_d16_hi v151, v64 offset:26112
	v_bfe_u32 v64, v79, 16, 1
	v_add3_u32 v64, v79, v64, s77
	ds_write_b16_d16_hi v149, v64 offset:26112
	v_bfe_u32 v64, v75, 16, 1
	v_add3_u32 v64, v75, v64, s77
	ds_write_b16_d16_hi v145, v64 offset:26112
	v_add_u32_e32 v64, 0x10000, v144
	v_cvt_pk_bf16_f32 v52, v52, v52
	v_add_u32_e32 v65, v64, v147
	ds_write_b16_d16_hi v65, v52
	v_cvt_pk_bf16_f32 v48, v48, v48
	v_add_u32_e32 v52, v64, v116
	ds_write_b16_d16_hi v52, v48
	v_bfe_u32 v48, v60, 16, 1
	v_add3_u32 v48, v60, v48, s77
	v_add_u32_e32 v52, v64, v124
	ds_write_b16_d16_hi v52, v48
	v_bfe_u32 v48, v56, 16, 1
	v_add3_u32 v48, v56, v48, s77
; __device__ __forceinline__ u16 f2bf(float f) { unsigned u = __float_as_uint(f); u += 0x7fffu + ((u >> 16) & 1u); return (u16)(u >> 16); }
; __device__ __forceinline__ float frcp(float x) { return __builtin_amdgcn_rcpf(x); }
; template <int EPI> ...
;     ...
;     for (int ai = 0; ai < 2; ++ai)
; #pragma unroll
;       for (int m = 0; m < 4; ++m)
; #pragma unroll
;         for (int j = 0; j < 4; ++j) {
;           const int r = ai * 128 + wr * 64 + m * 16 + fq * 4 + j;
;           float rs = 1.0f;
;           if (EPI != EPI_RES) rs = e.rstd[brow + r];
;           char* rowp = tb + r * RB + fr * 2;
;           if (EPI == EPI_GU) {
; #pragma unroll
;             for (int n = 0; n < 2; ++n) {
;               float g = acc[ai][0][m][n][j] * rs, u = acc[ai][1][m][n][j] * rs;
;               float h = g * frcp(1.0f + __expf(-g)) * u;
;               const int seg = (wc * 2 + n) ^ fq;
;               *(u16*)(rowp + seg * 32) = f2bf(h);
;             }
;           } else {
; #pragma unroll
;             for (int bj = 0; bj < 2; ++bj)
; #pragma unroll
;               for (int n = 0; n < 2; ++n) {
;                 const int seg = (bj * 8 + wc * 2 + n) ^ fq;
;                 *(u16*)(rowp + seg * 32) = f2bf(acc[ai][bj][m][n][j] * rs);
;               }
;           }
;         }
	v_add_u32_e32 v52, v64, v112
	ds_write_b16_d16_hi v52, v48
	v_add_u32_e32 v48, 0x10200, v144
	v_bfe_u32 v52, v53, 16, 1
	v_add3_u32 v52, v53, v52, s77
	v_add_u32_e32 v53, v48, v147
	ds_write_b16_d16_hi v53, v52
	v_cvt_pk_bf16_f32 v49, v49, v49
	v_add_u32_e32 v52, v48, v116
	ds_write_b16_d16_hi v52, v49
	v_bfe_u32 v49, v61, 16, 1
	v_add3_u32 v49, v61, v49, s77
	v_add_u32_e32 v52, v48, v124
	ds_write_b16_d16_hi v52, v49
	v_bfe_u32 v49, v57, 16, 1
	v_add3_u32 v49, v57, v49, s77
	v_add_u32_e32 v48, v48, v112
	ds_write_b16_d16_hi v48, v49
	v_add_u32_e32 v48, 0x10400, v144
	v_bfe_u32 v49, v54, 16, 1
	v_add3_u32 v49, v54, v49, s77
	v_add_u32_e32 v52, v48, v147
	ds_write_b16_d16_hi v52, v49
	v_bfe_u32 v49, v50, 16, 1
	v_add3_u32 v49, v50, v49, s77
	v_add_u32_e32 v50, v48, v116
	ds_write_b16_d16_hi v50, v49
	v_bfe_u32 v49, v62, 16, 1
	v_add3_u32 v49, v62, v49, s77
	v_add_u32_e32 v50, v48, v124
	ds_write_b16_d16_hi v50, v49
	v_bfe_u32 v49, v58, 16, 1
	v_add3_u32 v49, v58, v49, s77
	v_add_u32_e32 v48, v48, v112
	ds_write_b16_d16_hi v48, v49
	v_add_u32_e32 v48, 0x10600, v144
	v_bfe_u32 v49, v55, 16, 1
	v_add3_u32 v49, v55, v49, s77
	v_add_u32_e32 v50, v48, v147
	ds_write_b16_d16_hi v50, v49
	v_bfe_u32 v49, v51, 16, 1
	v_add3_u32 v49, v51, v49, s77
	v_add_u32_e32 v50, v48, v116
	ds_write_b16_d16_hi v50, v49
	v_bfe_u32 v49, v63, 16, 1
	v_add3_u32 v49, v63, v49, s77
	v_add_u32_e32 v50, v48, v124
	ds_write_b16_d16_hi v50, v49
	v_bfe_u32 v49, v59, 16, 1
	v_add3_u32 v49, v59, v49, s77
	v_add_u32_e32 v48, v48, v112
	ds_write_b16_d16_hi v48, v49
	v_add_u32_e32 v48, 0x12000, v144
	v_cvt_pk_bf16_f32 v36, v36, v36
	v_add_u32_e32 v49, v48, v147
	ds_write_b16_d16_hi v49, v36
	v_cvt_pk_bf16_f32 v32, v32, v32
	v_add_u32_e32 v36, v48, v116
	ds_write_b16_d16_hi v36, v32
	v_bfe_u32 v32, v44, 16, 1
	v_add3_u32 v32, v44, v32, s77
	v_add_u32_e32 v36, v48, v124
	ds_write_b16_d16_hi v36, v32
	v_bfe_u32 v32, v40, 16, 1
	v_add3_u32 v32, v40, v32, s77
	v_add_u32_e32 v36, v48, v112
	ds_write_b16_d16_hi v36, v32
	v_add_u32_e32 v32, 0x12200, v144
	v_bfe_u32 v36, v37, 16, 1
	v_add3_u32 v36, v37, v36, s77
	v_add_u32_e32 v37, v32, v147
	ds_write_b16_d16_hi v37, v36
	v_cvt_pk_bf16_f32 v33, v33, v33
	v_add_u32_e32 v36, v32, v116
	ds_write_b16_d16_hi v36, v33
	v_bfe_u32 v33, v45, 16, 1
	v_add3_u32 v33, v45, v33, s77
	v_add_u32_e32 v36, v32, v124
	ds_write_b16_d16_hi v36, v33
	v_bfe_u32 v33, v41, 16, 1
	v_add3_u32 v33, v41, v33, s77
	v_add_u32_e32 v32, v32, v112
	ds_write_b16_d16_hi v32, v33
	v_add_u32_e32 v32, 0x12400, v144
	v_bfe_u32 v33, v38, 16, 1
	v_add3_u32 v33, v38, v33, s77
	v_add_u32_e32 v36, v32, v147
	ds_write_b16_d16_hi v36, v33
	v_bfe_u32 v33, v34, 16, 1
	v_add3_u32 v33, v34, v33, s77
	v_add_u32_e32 v34, v32, v116
	ds_write_b16_d16_hi v34, v33
	v_bfe_u32 v33, v46, 16, 1
	v_add3_u32 v33, v46, v33, s77
	v_add_u32_e32 v34, v32, v124
	ds_write_b16_d16_hi v34, v33
	v_bfe_u32 v33, v42, 16, 1
	v_add3_u32 v33, v42, v33, s77
	v_add_u32_e32 v32, v32, v112
	ds_write_b16_d16_hi v32, v33
	v_add_u32_e32 v32, 0x12600, v144
	v_bfe_u32 v33, v39, 16, 1
	v_add3_u32 v33, v39, v33, s77
	v_add_u32_e32 v34, v32, v147
	ds_write_b16_d16_hi v34, v33
	v_bfe_u32 v33, v35, 16, 1
	v_add3_u32 v33, v35, v33, s77
	v_add_u32_e32 v34, v32, v116
	ds_write_b16_d16_hi v34, v33
	v_bfe_u32 v33, v47, 16, 1
	v_add3_u32 v33, v47, v33, s77
	v_add_u32_e32 v34, v32, v124
	ds_write_b16_d16_hi v34, v33
	v_bfe_u32 v33, v43, 16, 1
	v_add3_u32 v33, v43, v33, s77
	v_add_u32_e32 v32, v32, v112
	ds_write_b16_d16_hi v32, v33
	v_add_u32_e32 v32, 0x14000, v144
	v_cvt_pk_bf16_f32 v20, v20, v20
	v_add_u32_e32 v33, v32, v147
	ds_write_b16_d16_hi v33, v20
	v_cvt_pk_bf16_f32 v16, v16, v16
	v_add_u32_e32 v20, v32, v116
	ds_write_b16_d16_hi v20, v16
	v_bfe_u32 v16, v28, 16, 1
	v_add3_u32 v16, v28, v16, s77
	v_add_u32_e32 v20, v32, v124
	ds_write_b16_d16_hi v20, v16
	v_bfe_u32 v16, v24, 16, 1
	v_add3_u32 v16, v24, v16, s77
	v_add_u32_e32 v20, v32, v112
	ds_write_b16_d16_hi v20, v16
	v_add_u32_e32 v16, 0x14200, v144
	v_bfe_u32 v20, v21, 16, 1
	v_add3_u32 v20, v21, v20, s77
; __device__ __forceinline__ u16 f2bf(float f) { unsigned u = __float_as_uint(f); u += 0x7fffu + ((u >> 16) & 1u); return (u16)(u >> 16); }
; __device__ __forceinline__ int opaque_tid() { int t; asm volatile("v_mov_b32 %0, %1" : "=v"(t) : "v"((int)threadIdx.x)); return t; }
; template <int EPI> ...
;     ...
; #pragma unroll
;             for (int bj = 0; bj < 2; ++bj)
; #pragma unroll
;               for (int n = 0; n < 2; ++n) {
;                 const int seg = (bj * 8 + wc * 2 + n) ^ fq;
;                 *(u16*)(rowp + seg * 32) = f2bf(acc[ai][bj][m][n][j] * rs);
;               }
;           }
;         }
;     __syncthreads();
;     constexpr int CPR = RB / 16;
;     constexpr int RPI = 512 / CPR;
;     const int tid2 = opaque_tid();
;     const int cc = tid2 % CPR, r0 = tid2 / CPR;
;     u16* gp = (EPI == EPI_GU) ? e.out + ((size_t)((e.bcol >> 6) + (cc >> 3)) * 256 + r0) * 64 + (cc & 7) * 8
;                               : e.out + (size_t)r0 * e.ld + e.bcol + cc * 8;
;     const size_t gstep = (EPI == EPI_GU) ? (size_t)RPI * 64 : (size_t)RPI * e.ld;
	v_add_u32_e32 v21, v16, v147
	ds_write_b16_d16_hi v21, v20
	v_cvt_pk_bf16_f32 v17, v17, v17
	v_add_u32_e32 v20, v16, v116
	ds_write_b16_d16_hi v20, v17
	v_bfe_u32 v17, v29, 16, 1
	v_add3_u32 v17, v29, v17, s77
	v_add_u32_e32 v20, v16, v124
	ds_write_b16_d16_hi v20, v17
	v_bfe_u32 v17, v25, 16, 1
	v_add3_u32 v17, v25, v17, s77
	v_add_u32_e32 v16, v16, v112
	ds_write_b16_d16_hi v16, v17
	v_add_u32_e32 v16, 0x14400, v144
	v_bfe_u32 v17, v22, 16, 1
	v_add3_u32 v17, v22, v17, s77
	v_add_u32_e32 v20, v16, v147
	ds_write_b16_d16_hi v20, v17
	v_bfe_u32 v17, v18, 16, 1
	v_add3_u32 v17, v18, v17, s77
	v_add_u32_e32 v18, v16, v116
	ds_write_b16_d16_hi v18, v17
	v_bfe_u32 v17, v30, 16, 1
	v_add3_u32 v17, v30, v17, s77
	v_add_u32_e32 v18, v16, v124
	ds_write_b16_d16_hi v18, v17
	v_bfe_u32 v17, v26, 16, 1
	v_add3_u32 v17, v26, v17, s77
	v_add_u32_e32 v16, v16, v112
	ds_write_b16_d16_hi v16, v17
	v_add_u32_e32 v16, 0x14600, v144
	v_bfe_u32 v17, v23, 16, 1
	v_add3_u32 v17, v23, v17, s77
	v_add_u32_e32 v18, v16, v147
	ds_write_b16_d16_hi v18, v17
	v_bfe_u32 v17, v19, 16, 1
	v_add3_u32 v17, v19, v17, s77
	v_add_u32_e32 v18, v16, v116
	ds_write_b16_d16_hi v18, v17
	v_bfe_u32 v17, v31, 16, 1
	v_add3_u32 v17, v31, v17, s77
	v_add_u32_e32 v18, v16, v124
	ds_write_b16_d16_hi v18, v17
	v_bfe_u32 v17, v27, 16, 1
	v_add3_u32 v17, v27, v17, s77
	v_add_u32_e32 v16, v16, v112
	ds_write_b16_d16_hi v16, v17
	v_add_u32_e32 v16, 0x16000, v144
	v_cvt_pk_bf16_f32 v4, v4, v4
	v_add_u32_e32 v17, v16, v147
	ds_write_b16_d16_hi v17, v4
	v_cvt_pk_bf16_f32 v0, v0, v0
	v_add_u32_e32 v4, v16, v116
	ds_write_b16_d16_hi v4, v0
	v_bfe_u32 v0, v12, 16, 1
	v_add3_u32 v0, v12, v0, s77
	v_add_u32_e32 v4, v16, v124
	ds_write_b16_d16_hi v4, v0
	v_bfe_u32 v0, v8, 16, 1
	v_add3_u32 v0, v8, v0, s77
	v_add_u32_e32 v4, v16, v112
	ds_write_b16_d16_hi v4, v0
	v_add_u32_e32 v0, 0x16200, v144
	v_bfe_u32 v4, v5, 16, 1
	v_add3_u32 v4, v5, v4, s77
	v_add_u32_e32 v5, v0, v147
	ds_write_b16_d16_hi v5, v4
	v_cvt_pk_bf16_f32 v1, v1, v1
	v_add_u32_e32 v4, v0, v116
	ds_write_b16_d16_hi v4, v1
	v_bfe_u32 v1, v13, 16, 1
	v_add3_u32 v1, v13, v1, s77
	v_add_u32_e32 v4, v0, v124
	ds_write_b16_d16_hi v4, v1
	v_bfe_u32 v1, v9, 16, 1
	v_add3_u32 v1, v9, v1, s77
	v_add_u32_e32 v0, v0, v112
	ds_write_b16_d16_hi v0, v1
	v_add_u32_e32 v0, 0x16400, v144
	v_bfe_u32 v1, v6, 16, 1
	v_add3_u32 v1, v6, v1, s77
	v_add_u32_e32 v4, v0, v147
	ds_write_b16_d16_hi v4, v1
	v_bfe_u32 v1, v2, 16, 1
	v_add3_u32 v1, v2, v1, s77
	v_add_u32_e32 v2, v0, v116
	ds_write_b16_d16_hi v2, v1
	v_bfe_u32 v1, v14, 16, 1
	v_add3_u32 v1, v14, v1, s77
	v_add_u32_e32 v2, v0, v124
	ds_write_b16_d16_hi v2, v1
	v_bfe_u32 v1, v10, 16, 1
	v_add3_u32 v1, v10, v1, s77
	v_add_u32_e32 v0, v0, v112
	ds_write_b16_d16_hi v0, v1
	v_add_u32_e32 v0, 0x16600, v144
	v_bfe_u32 v1, v7, 16, 1
	v_add3_u32 v1, v7, v1, s77
	v_add_u32_e32 v2, v0, v147
	ds_write_b16_d16_hi v2, v1
	v_bfe_u32 v1, v3, 16, 1
	v_add3_u32 v1, v3, v1, s77
	v_add_u32_e32 v2, v0, v116
	ds_write_b16_d16_hi v2, v1
	v_bfe_u32 v1, v15, 16, 1
	v_add3_u32 v1, v15, v1, s77
	v_add_u32_e32 v2, v0, v124
	ds_write_b16_d16_hi v2, v1
	v_bfe_u32 v1, v11, 16, 1
	v_add3_u32 v1, v11, v1, s77
	v_add_u32_e32 v0, v0, v112
	ds_write_b16_d16_hi v0, v1
	s_waitcnt vmcnt(0) lgkmcnt(0)
	s_barrier
	v_mov_b32 v0, v146
	s_lshl_b32 s48, s84, 8
	v_ashrrev_i32_e32 v1, 31, v0
	v_lshrrev_b32_e32 v1, 27, v1
	s_ashr_i32 s49, s48, 31
	v_add_u32_e32 v1, v0, v1
	s_lshl_b64 s[48:49], s[48:49], 12
	v_ashrrev_i32_e32 v2, 5, v1
	s_add_u32 s48, s74, s48
	v_and_b32_e32 v1, 0xffffffe0, v1
	v_ashrrev_i32_e32 v3, 31, v2
	s_addc_u32 s49, s75, s49
	s_lshl_b32 s52, s83, 8
	v_sub_u32_e32 v6, v0, v1
	v_lshlrev_b64 v[0:1], 12, v[2:3]
	v_lshrrev_b32_e32 v3, 1, v2
	v_lshl_add_u64 v[0:1], s[48:49], 0, v[0:1]
	s_ashr_i32 s53, s52, 31
	v_lshlrev_b32_e32 v4, 3, v6
	v_bitop3_b32 v3, v3, v6, 6 bitop3:0x6c
	v_lshl_add_u64 v[0:1], s[52:53], 1, v[0:1]
	v_ashrrev_i32_e32 v5, 31, v4
	v_lshlrev_b32_e32 v2, 9, v2
	v_lshlrev_b32_e32 v3, 4, v3
	v_lshl_add_u64 v[0:1], v[4:5], 1, v[0:1]
	v_add3_u32 v2, 0, v2, v3
	s_mov_b32 s48, 0

; __device__ __forceinline__ int opaque_tid() { int t; asm volatile("v_mov_b32 %0, %1" : "=v"(t) : "v"((int)threadIdx.x)); return t; }
; #define STAGE(P, BASE, kt) do { const char* _g = (const char*)(BASE) + (size_t)((kt) * (BK * 2)); \
;     __builtin_amdgcn_global_load_lds((const unsigned*)(_g + (size_t)goff0), (unsigned*)((char*)(P) + tid_ * 16), 16, 0, 0); \
;     __builtin_amdgcn_global_load_lds((const unsigned*)(_g + (size_t)goff1), (unsigned*)((char*)(P) + tid_ * 16 + 8192), 16, 0, 0); } while (0)
; #define STAGEA(P, BASE, kt) do { const char* _g = (const char*)(BASE) + (size_t)((kt) * a_kbytes); \
;     __builtin_amdgcn_global_load_lds((const unsigned*)(_g + (size_t)goffA0), (unsigned*)((char*)(P) + tid_ * 16), 16, 0, 0); \
;     __builtin_amdgcn_global_load_lds((const unsigned*)(_g + (size_t)goffA1), (unsigned*)((char*)(P) + tid_ * 16 + 8192), 16, 0, 0); } while (0)
; #define WAIT_V(n) asm volatile("s_waitcnt vmcnt(" #n ")" ::: "memory")
; #define BAR __builtin_amdgcn_s_barrier()
; template <int EPI> ...
;     ...
;   const int tid_ = opaque_tid();
;   const int wid = tid_ >> 6, lane = tid_ & 63, wr = wid >> 2, wc = wid & 3, fr = lane & 15, fq = lane >> 4;
;   f32x4 acc[2][2][4][2] = {};
;   bf16x8 At[4][2], B0[2][2], B1[2][2];
;   const int nt = K / BK;
;   STAGE(SB(0, 0), B0p, 0); STAGEA(SA(0, 0), A0, 0);
;   STAGE(SB(0, 1), B1p, 0); STAGEA(SA(0, 1), A1, 0);
;   if (wr == 1) BAR;
;   WAIT_V(4); BAR;
;   STAGE(SB(1, 0), B0p, 1); STAGEA(SA(1, 0), A0, 1); STAGE(SB(1, 1), B1p, 1);
;   WAIT_V(6); BAR;
;   for (int t = 0; t < nt - 2; t += 2) {
.LBB0_817:
	s_or_b64 exec, exec, s[62:63]
	v_add_u32_e32 v164, s80, v8
	v_add_u32_e32 v165, 0x2000, v164
	v_readfirstlane_b32 s53, v164
	v_lshl_add_u64 v[0:1], v[0:1], 0, s[4:5]
	s_mov_b32 m0, s53
	v_readfirstlane_b32 s53, v165
	v_add_u32_e32 v166, 0x8000, v158
	s_waitcnt vmcnt(4)
	s_barrier
	global_load_lds_dwordx4 v[0:1], off
	v_lshl_add_u64 v[0:1], v[2:3], 0, s[4:5]
	s_mov_b32 m0, s53
	v_readfirstlane_b32 s53, v166
	v_add_u32_e32 v167, 0xa000, v158
	global_load_lds_dwordx4 v[0:1], off
	v_lshl_add_u64 v[0:1], v[4:5], 0, s[4:5]
	s_mov_b32 m0, s53
	v_readfirstlane_b32 s53, v167
	s_add_u32 s60, s60, 0x80080
	v_add_u32_e32 v169, s81, v8
	global_load_lds_dwordx4 v[0:1], off
	v_lshl_add_u64 v[0:1], v[6:7], 0, s[4:5]
	s_mov_b32 m0, s53
	s_addc_u32 s61, s61, 0
	v_readfirstlane_b32 s53, v169
	v_add_u32_e32 v170, 0x2000, v169
	global_load_lds_dwordx4 v[0:1], off
	v_lshl_add_u64 v[0:1], s[60:61], 0, v[130:131]
	s_mov_b32 m0, s53
	v_readfirstlane_b32 s53, v170
	global_load_lds_dwordx4 v[0:1], off
	v_lshl_add_u64 v[0:1], s[60:61], 0, v[128:129]
	s_mov_b32 m0, s53
	v_and_b32_e32 v148, 15, v144
	global_load_lds_dwordx4 v[0:1], off
	v_bfe_u32 v145, v144, 4, 2
	v_lshlrev_b32_e32 v3, 2, v144
	v_lshlrev_b32_e32 v0, 4, v145
	v_lshlrev_b32_e32 v2, 6, v148
	v_and_b32_e32 v3, 32, v3
	v_lshlrev_b32_e32 v149, 6, v9
	v_lshlrev_b32_e32 v8, 13, v9
	v_lshlrev_b32_e32 v9, 6, v144
	v_lshl_add_u64 v[136:137], v[132:133], 0, s[58:59]
	v_lshl_add_u64 v[138:139], v[134:135], 0, s[58:59]
	s_add_i32 s58, s87, s88
	v_bfe_u32 v147, v144, 6, 2
	s_waitcnt vmcnt(6)
	v_bitop3_b32 v2, v0, v3, v2 bitop3:0x36
	v_and_or_b32 v0, v9, s82, v0
	s_ashr_i32 s59, s58, 31
	v_lshlrev_b32_e32 v1, 12, v147
	v_add_u32_e32 v4, s67, v2
	v_add_u32_e32 v5, s77, v2
	v_add_u32_e32 v6, s80, v2
	v_add_u32_e32 v7, s81, v2
	v_add_u32_e32 v2, 0, v2
	v_xad_u32 v3, v0, v3, 0
	v_or_b32_e32 v9, 0x800, v8
	v_or_b32_e32 v10, 0x1000, v8
	v_or_b32_e32 v11, 0x1800, v8
	s_lshl_b64 s[58:59], s[58:59], 12
	v_mov_b32_e32 v0, 0
	v_lshl_add_u64 v[140:141], v[132:133], 0, s[58:59]
	v_lshl_add_u64 v[142:143], v[134:135], 0, s[58:59]
	s_mov_b32 s53, -2
	v_add_u32_e32 v171, v4, v1
	v_add_u32_e32 v153, v2, v8
	v_add_u32_e32 v152, v3, v9
	v_add_u32_e32 v151, v3, v10
	v_add_u32_e32 v150, v3, v11
	v_add_u32_e32 v168, v5, v1
	v_add_u32_e32 v157, v6, v1
	v_add_u32_e32 v154, v7, v1
	s_mov_b64 s[58:59], s[74:75]
	v_mov_b32_e32 v1, v0
	v_mov_b32_e32 v2, v0
	v_mov_b32_e32 v3, v0
	v_mov_b32_e32 v4, v0
	v_mov_b32_e32 v5, v0
	v_mov_b32_e32 v6, v0
	v_mov_b32_e32 v7, v0
	v_mov_b32_e32 v8, v0
	v_mov_b32_e32 v9, v0
	v_mov_b32_e32 v10, v0
	v_mov_b32_e32 v11, v0
	v_mov_b32_e32 v12, v0
	v_mov_b32_e32 v13, v0
	v_mov_b32_e32 v14, v0
	v_mov_b32_e32 v15, v0
	v_mov_b32_e32 v16, v0
	v_mov_b32_e32 v17, v0
	v_mov_b32_e32 v18, v0
	v_mov_b32_e32 v19, v0
	v_mov_b32_e32 v20, v0
	v_mov_b32_e32 v21, v0
	v_mov_b32_e32 v22, v0
	v_mov_b32_e32 v23, v0
	v_mov_b32_e32 v24, v0
	v_mov_b32_e32 v25, v0
	v_mov_b32_e32 v26, v0
	v_mov_b32_e32 v27, v0
	v_mov_b32_e32 v28, v0
	v_mov_b32_e32 v29, v0
	v_mov_b32_e32 v30, v0
	v_mov_b32_e32 v31, v0
	v_mov_b32_e32 v32, v0
	v_mov_b32_e32 v33, v0
	v_mov_b32_e32 v34, v0
	v_mov_b32_e32 v35, v0
	v_mov_b32_e32 v36, v0
	v_mov_b32_e32 v37, v0
	v_mov_b32_e32 v38, v0
	v_mov_b32_e32 v39, v0
	v_mov_b32_e32 v40, v0
	v_mov_b32_e32 v41, v0
	v_mov_b32_e32 v42, v0
	v_mov_b32_e32 v43, v0
	v_mov_b32_e32 v44, v0
	v_mov_b32_e32 v45, v0
	v_mov_b32_e32 v46, v0
	v_mov_b32_e32 v47, v0
	v_mov_b32_e32 v48, v0
	v_mov_b32_e32 v49, v0
	v_mov_b32_e32 v50, v0
	v_mov_b32_e32 v51, v0
	v_mov_b32_e32 v52, v0
	v_mov_b32_e32 v53, v0
	v_mov_b32_e32 v54, v0
	v_mov_b32_e32 v55, v0
	v_mov_b32_e32 v56, v0
	v_mov_b32_e32 v57, v0
	v_mov_b32_e32 v58, v0
	v_mov_b32_e32 v59, v0
	v_mov_b32_e32 v60, v0
	v_mov_b32_e32 v61, v0
	v_mov_b32_e32 v62, v0
	v_mov_b32_e32 v63, v0
	v_mov_b32_e32 v64, v0
	v_mov_b32_e32 v65, v0
	v_mov_b32_e32 v66, v0
	v_mov_b32_e32 v67, v0
	v_mov_b32_e32 v68, v0
	v_mov_b32_e32 v69, v0
	v_mov_b32_e32 v70, v0
	v_mov_b32_e32 v71, v0
	v_mov_b32_e32 v72, v0
	v_mov_b32_e32 v73, v0
	v_mov_b32_e32 v74, v0
	v_mov_b32_e32 v75, v0
	v_mov_b32_e32 v76, v0
	v_mov_b32_e32 v77, v0
	v_mov_b32_e32 v78, v0
	v_mov_b32_e32 v79, v0
	v_mov_b32_e32 v80, v0
	v_mov_b32_e32 v81, v0
	v_mov_b32_e32 v82, v0
	v_mov_b32_e32 v83, v0
	v_mov_b32_e32 v84, v0
	v_mov_b32_e32 v85, v0
	v_mov_b32_e32 v86, v0
	v_mov_b32_e32 v87, v0
	v_mov_b32_e32 v88, v0
	v_mov_b32_e32 v89, v0
	v_mov_b32_e32 v90, v0
	v_mov_b32_e32 v91, v0
	v_mov_b32_e32 v92, v0
	v_mov_b32_e32 v93, v0
	v_mov_b32_e32 v94, v0
	v_mov_b32_e32 v95, v0
	v_mov_b32_e32 v96, v0
	v_mov_b32_e32 v97, v0
	v_mov_b32_e32 v98, v0
	v_mov_b32_e32 v99, v0
	v_mov_b32_e32 v100, v0
	v_mov_b32_e32 v101, v0
	v_mov_b32_e32 v102, v0
	v_mov_b32_e32 v103, v0
	v_mov_b32_e32 v104, v0
	v_mov_b32_e32 v105, v0
	v_mov_b32_e32 v106, v0
	v_mov_b32_e32 v107, v0
	v_mov_b32_e32 v108, v0
	v_mov_b32_e32 v109, v0
	v_mov_b32_e32 v110, v0
	v_mov_b32_e32 v111, v0
	v_mov_b32_e32 v112, v0
	v_mov_b32_e32 v113, v0
	v_mov_b32_e32 v114, v0
	v_mov_b32_e32 v115, v0
	v_mov_b32_e32 v116, v0
	v_mov_b32_e32 v117, v0
	v_mov_b32_e32 v118, v0
	v_mov_b32_e32 v119, v0
	v_mov_b32_e32 v120, v0
	v_mov_b32_e32 v121, v0
	v_mov_b32_e32 v122, v0
	v_mov_b32_e32 v123, v0
	v_mov_b32_e32 v124, v0
	v_mov_b32_e32 v125, v0
	v_mov_b32_e32 v126, v0
	v_mov_b32_e32 v127, v0
	s_barrier
	ds_read_b128 v[174:177], v171
	ds_read_b128 v[178:181], v171 offset:1024
	ds_read_b128 v[182:185], v171 offset:2048
	ds_read_b128 v[186:189], v171 offset:3072
; #define STAGE(P, BASE, kt) do { const char* _g = (const char*)(BASE) + (size_t)((kt) * (BK * 2)); \
;     __builtin_amdgcn_global_load_lds((const unsigned*)(_g + (size_t)goff0), (unsigned*)((char*)(P) + tid_ * 16), 16, 0, 0); \
;     __builtin_amdgcn_global_load_lds((const unsigned*)(_g + (size_t)goff1), (unsigned*)((char*)(P) + tid_ * 16 + 8192), 16, 0, 0); } while (0)
; #define STAGEA(P, BASE, kt) do { const char* _g = (const char*)(BASE) + (size_t)((kt) * a_kbytes); \
;     __builtin_amdgcn_global_load_lds((const unsigned*)(_g + (size_t)goffA0), (unsigned*)((char*)(P) + tid_ * 16), 16, 0, 0); \
;     __builtin_amdgcn_global_load_lds((const unsigned*)(_g + (size_t)goffA1), (unsigned*)((char*)(P) + tid_ * 16 + 8192), 16, 0, 0); } while (0)
; #define LDA(dst, b, h) for (int m = 0; m < 4; ++m) for (int k = 0; k < 2; ++k) \
;     dst[m][k] = *reinterpret_cast<const bf16x8*>((char*)SA(b, h) + lds_byte(wr * 64 + m * 16 + fr, k * 32 + fq * 8))
; #define LDB(dst, b, h) for (int n = 0; n < 2; ++n) for (int k = 0; k < 2; ++k) \
;     dst[n][k] = *reinterpret_cast<const bf16x8*>((char*)SB(b, h) + lds_byte(wc * 32 + n * 16 + fr, k * 32 + fq * 8))
; #define MMA(ai, bj, At, Bt) do { __builtin_amdgcn_s_setprio(1); \
;     for (int m = 0; m < 4; ++m) for (int n = 0; n < 2; ++n) for (int k = 0; k < 2; ++k) \
;       acc[ai][bj][m][n] = __builtin_amdgcn_mfma_f32_16x16x32_bf16(At[m][k], Bt[n][k], acc[ai][bj][m][n], 0, 0, 0); \
;     __builtin_amdgcn_s_setprio(0); } while (0)
; #define WAIT_V(n) asm volatile("s_waitcnt vmcnt(" #n ")" ::: "memory")
; #define WAIT_L(n) asm volatile("s_waitcnt lgkmcnt(" #n ")" ::: "memory")
; #define BAR __builtin_amdgcn_s_barrier()
; #define SCHED __builtin_amdgcn_sched_barrier(0)
; template <int EPI> ...
;     ...
;     LDB(B0, 0, 0); SCHED; LDA(At, 0, 0); STAGEA(SA(1, 1), A1, t + 1);
;     WAIT_L(8); BAR; WAIT_L(0); MMA(0, 0, At, B0); BAR; SCHED;
;     LDB(B1, 0, 1); STAGE(SB(0, 0), B0p, t + 2);
;     BAR; WAIT_L(0); MMA(0, 1, At, B1); BAR;
;     LDA(At, 0, 1); STAGEA(SA(0, 0), A0, t + 2);
;     BAR; WAIT_L(0); MMA(1, 0, At, B0); BAR; SCHED;
;     STAGE(SB(0, 1), B1p, t + 2);
;     WAIT_V(6); BAR; MMA(1, 1, At, B1); BAR;
.LBB0_818:
	v_add_u32_e32 v172, 0xc000, v158
	v_lshl_add_u64 v[238:239], s[58:59], 0, v[140:141]
	v_readfirstlane_b32 s55, v172
	v_add_u32_e32 v173, 0xe000, v158
	v_lshl_add_u64 v[222:223], v[238:239], 0, s[6:7]
	s_mov_b32 m0, s55
	v_lshl_add_u64 v[240:241], s[58:59], 0, v[142:143]
	v_readfirstlane_b32 s55, v173
	ds_read_b128 v[190:193], v153
	ds_read_b128 v[194:197], v153 offset:1024
	ds_read_b128 v[198:201], v152
	ds_read_b128 v[202:205], v152 offset:1024
	ds_read_b128 v[206:209], v151
	ds_read_b128 v[210:213], v151 offset:1024
	ds_read_b128 v[214:217], v150
	ds_read_b128 v[218:221], v150 offset:1024
	global_load_lds_dwordx4 v[222:223], off
	v_lshl_add_u64 v[222:223], v[240:241], 0, s[6:7]
	s_mov_b32 m0, s55
	s_nop 0
	global_load_lds_dwordx4 v[222:223], off
	s_waitcnt lgkmcnt(8)
	s_setprio 1
	s_barrier
	s_waitcnt lgkmcnt(0)
	v_mfma_f32_16x16x32_bf16 v[124:127], v[190:193], v[174:177], v[124:127]
	v_mfma_f32_16x16x32_bf16 v[120:123], v[190:193], v[182:185], v[120:123]
	v_mfma_f32_16x16x32_bf16 v[116:119], v[198:201], v[174:177], v[116:119]
	v_mfma_f32_16x16x32_bf16 v[112:115], v[198:201], v[182:185], v[112:115]
	v_mfma_f32_16x16x32_bf16 v[108:111], v[206:209], v[174:177], v[108:111]
	v_mfma_f32_16x16x32_bf16 v[104:107], v[206:209], v[182:185], v[104:107]
	v_mfma_f32_16x16x32_bf16 v[100:103], v[214:217], v[174:177], v[100:103]
	v_mfma_f32_16x16x32_bf16 v[96:99], v[214:217], v[182:185], v[96:99]
	v_mfma_f32_16x16x32_bf16 v[124:127], v[194:197], v[178:181], v[124:127]
	v_mfma_f32_16x16x32_bf16 v[120:123], v[194:197], v[186:189], v[120:123]
	v_mfma_f32_16x16x32_bf16 v[116:119], v[202:205], v[178:181], v[116:119]
	v_mfma_f32_16x16x32_bf16 v[112:115], v[202:205], v[186:189], v[112:115]
	v_mfma_f32_16x16x32_bf16 v[108:111], v[210:213], v[178:181], v[108:111]
	v_mfma_f32_16x16x32_bf16 v[104:107], v[210:213], v[186:189], v[104:107]
	v_mfma_f32_16x16x32_bf16 v[100:103], v[218:221], v[178:181], v[100:103]
	v_mfma_f32_16x16x32_bf16 v[96:99], v[218:221], v[186:189], v[96:99]
	s_barrier
	s_setprio 0
	v_lshl_add_u64 v[242:243], s[58:59], 0, v[136:137]
	v_readfirstlane_b32 s55, v155
	v_lshl_add_u64 v[244:245], v[242:243], 0, s[8:9]
	s_mov_b32 m0, s55
	ds_read_b128 v[222:225], v168
	ds_read_b128 v[226:229], v168 offset:1024
	ds_read_b128 v[230:233], v168 offset:2048
	ds_read_b128 v[234:237], v168 offset:3072
	global_load_lds_dwordx4 v[244:245], off
	v_lshl_add_u64 v[244:245], s[58:59], 0, v[138:139]
	v_readfirstlane_b32 s55, v156
	v_lshl_add_u64 v[246:247], v[244:245], 0, s[8:9]
	s_mov_b32 m0, s55
	s_nop 0
	global_load_lds_dwordx4 v[246:247], off
	s_setprio 1
	s_barrier
	s_waitcnt lgkmcnt(0)
	v_mfma_f32_16x16x32_bf16 v[92:95], v[190:193], v[222:225], v[92:95]
	v_mfma_f32_16x16x32_bf16 v[88:91], v[190:193], v[230:233], v[88:91]
	v_mfma_f32_16x16x32_bf16 v[84:87], v[198:201], v[222:225], v[84:87]
	v_mfma_f32_16x16x32_bf16 v[80:83], v[198:201], v[230:233], v[80:83]
	v_mfma_f32_16x16x32_bf16 v[76:79], v[206:209], v[222:225], v[76:79]
	v_mfma_f32_16x16x32_bf16 v[72:75], v[206:209], v[230:233], v[72:75]
	v_mfma_f32_16x16x32_bf16 v[68:71], v[214:217], v[222:225], v[68:71]
	v_mfma_f32_16x16x32_bf16 v[64:67], v[214:217], v[230:233], v[64:67]
	v_mfma_f32_16x16x32_bf16 v[92:95], v[194:197], v[226:229], v[92:95]
	v_mfma_f32_16x16x32_bf16 v[88:91], v[194:197], v[234:237], v[88:91]
	v_mfma_f32_16x16x32_bf16 v[84:87], v[202:205], v[226:229], v[84:87]
	v_mfma_f32_16x16x32_bf16 v[80:83], v[202:205], v[234:237], v[80:83]
	v_mfma_f32_16x16x32_bf16 v[76:79], v[210:213], v[226:229], v[76:79]
	v_mfma_f32_16x16x32_bf16 v[72:75], v[210:213], v[234:237], v[72:75]
	v_mfma_f32_16x16x32_bf16 v[68:71], v[218:221], v[226:229], v[68:71]
	v_mfma_f32_16x16x32_bf16 v[64:67], v[218:221], v[234:237], v[64:67]
	s_barrier
	s_setprio 0
	v_readfirstlane_b32 s55, v158
	v_lshl_add_u64 v[246:247], v[238:239], 0, s[10:11]
	s_mov_b32 m0, s55
	v_readfirstlane_b32 s55, v159
	ds_read_b128 v[190:193], v153 offset:16384
	ds_read_b128 v[194:197], v153 offset:17408
	ds_read_b128 v[198:201], v152 offset:16384
	ds_read_b128 v[202:205], v152 offset:17408
	ds_read_b128 v[206:209], v151 offset:16384
	ds_read_b128 v[210:213], v151 offset:17408
	ds_read_b128 v[214:217], v150 offset:16384
	ds_read_b128 v[218:221], v150 offset:17408
	global_load_lds_dwordx4 v[246:247], off
	v_lshl_add_u64 v[246:247], v[240:241], 0, s[10:11]
	s_mov_b32 m0, s55
	s_nop 0
	global_load_lds_dwordx4 v[246:247], off
	s_setprio 1
	s_barrier
	s_waitcnt lgkmcnt(0)
	v_mfma_f32_16x16x32_bf16 v[60:63], v[190:193], v[174:177], v[60:63]
	v_mfma_f32_16x16x32_bf16 v[56:59], v[190:193], v[182:185], v[56:59]
	v_mfma_f32_16x16x32_bf16 v[52:55], v[198:201], v[174:177], v[52:55]
	v_mfma_f32_16x16x32_bf16 v[48:51], v[198:201], v[182:185], v[48:51]
	v_mfma_f32_16x16x32_bf16 v[44:47], v[206:209], v[174:177], v[44:47]
	v_mfma_f32_16x16x32_bf16 v[40:43], v[206:209], v[182:185], v[40:43]
	v_mfma_f32_16x16x32_bf16 v[36:39], v[214:217], v[174:177], v[36:39]
	v_mfma_f32_16x16x32_bf16 v[32:35], v[214:217], v[182:185], v[32:35]
	v_mfma_f32_16x16x32_bf16 v[60:63], v[194:197], v[178:181], v[60:63]
	v_mfma_f32_16x16x32_bf16 v[56:59], v[194:197], v[186:189], v[56:59]
	v_mfma_f32_16x16x32_bf16 v[52:55], v[202:205], v[178:181], v[52:55]
	v_mfma_f32_16x16x32_bf16 v[48:51], v[202:205], v[186:189], v[48:51]
	v_mfma_f32_16x16x32_bf16 v[44:47], v[210:213], v[178:181], v[44:47]
	v_mfma_f32_16x16x32_bf16 v[40:43], v[210:213], v[186:189], v[40:43]
	v_mfma_f32_16x16x32_bf16 v[36:39], v[218:221], v[178:181], v[36:39]
	v_mfma_f32_16x16x32_bf16 v[32:35], v[218:221], v[186:189], v[32:35]
	s_barrier
; #define STAGE(P, BASE, kt) do { const char* _g = (const char*)(BASE) + (size_t)((kt) * (BK * 2)); \
;     __builtin_amdgcn_global_load_lds((const unsigned*)(_g + (size_t)goff0), (unsigned*)((char*)(P) + tid_ * 16), 16, 0, 0); \
;     __builtin_amdgcn_global_load_lds((const unsigned*)(_g + (size_t)goff1), (unsigned*)((char*)(P) + tid_ * 16 + 8192), 16, 0, 0); } while (0)
; #define STAGEA(P, BASE, kt) do { const char* _g = (const char*)(BASE) + (size_t)((kt) * a_kbytes); \
;     __builtin_amdgcn_global_load_lds((const unsigned*)(_g + (size_t)goffA0), (unsigned*)((char*)(P) + tid_ * 16), 16, 0, 0); \
;     __builtin_amdgcn_global_load_lds((const unsigned*)(_g + (size_t)goffA1), (unsigned*)((char*)(P) + tid_ * 16 + 8192), 16, 0, 0); } while (0)
; #define LDA(dst, b, h) for (int m = 0; m < 4; ++m) for (int k = 0; k < 2; ++k) \
;     dst[m][k] = *reinterpret_cast<const bf16x8*>((char*)SA(b, h) + lds_byte(wr * 64 + m * 16 + fr, k * 32 + fq * 8))
; #define LDB(dst, b, h) for (int n = 0; n < 2; ++n) for (int k = 0; k < 2; ++k) \
;     dst[n][k] = *reinterpret_cast<const bf16x8*>((char*)SB(b, h) + lds_byte(wc * 32 + n * 16 + fr, k * 32 + fq * 8))
; #define MMA(ai, bj, At, Bt) do { __builtin_amdgcn_s_setprio(1); \
;     for (int m = 0; m < 4; ++m) for (int n = 0; n < 2; ++n) for (int k = 0; k < 2; ++k) \
;       acc[ai][bj][m][n] = __builtin_amdgcn_mfma_f32_16x16x32_bf16(At[m][k], Bt[n][k], acc[ai][bj][m][n], 0, 0, 0); \
;     __builtin_amdgcn_s_setprio(0); } while (0)
; #define WAIT_V(n) asm volatile("s_waitcnt vmcnt(" #n ")" ::: "memory")
; #define WAIT_L(n) asm volatile("s_waitcnt lgkmcnt(" #n ")" ::: "memory")
; #define BAR __builtin_amdgcn_s_barrier()
; #define SCHED __builtin_amdgcn_sched_barrier(0)
; template <int EPI> ...
;     ...
;     STAGE(SB(0, 1), B1p, t + 2);
;     WAIT_V(6); BAR; MMA(1, 1, At, B1); BAR;
;     LDB(B0, 1, 0); SCHED; LDA(At, 1, 0); STAGEA(SA(0, 1), A1, t + 2);
;     WAIT_L(8); BAR; WAIT_L(0); MMA(0, 0, At, B0); BAR; SCHED;
;     LDB(B1, 1, 1); STAGE(SB(1, 0), B0p, t + 3);
;     BAR; WAIT_L(0); MMA(0, 1, At, B1); BAR;
;     LDA(At, 1, 1); STAGEA(SA(1, 0), A0, t + 3);
;     BAR; WAIT_L(0); MMA(1, 0, At, B0); BAR; SCHED;
	s_setprio 0
	v_readfirstlane_b32 s55, v160
	v_lshl_add_u64 v[174:175], v[242:243], 0, s[12:13]
	s_mov_b32 m0, s55
	v_readfirstlane_b32 s55, v161
	global_load_lds_dwordx4 v[174:175], off
	v_lshl_add_u64 v[174:175], v[244:245], 0, s[12:13]
	s_mov_b32 m0, s55
	s_nop 0
	global_load_lds_dwordx4 v[174:175], off
	s_waitcnt vmcnt(6)
	s_setprio 1
	s_barrier
	v_mfma_f32_16x16x32_bf16 v[28:31], v[190:193], v[222:225], v[28:31]
	v_mfma_f32_16x16x32_bf16 v[24:27], v[190:193], v[230:233], v[24:27]
	v_mfma_f32_16x16x32_bf16 v[20:23], v[198:201], v[222:225], v[20:23]
	v_mfma_f32_16x16x32_bf16 v[16:19], v[198:201], v[230:233], v[16:19]
	ds_read_b128 v[174:177], v157
	v_mfma_f32_16x16x32_bf16 v[12:15], v[206:209], v[222:225], v[12:15]
	v_mfma_f32_16x16x32_bf16 v[8:11], v[206:209], v[230:233], v[8:11]
	ds_read_b128 v[178:181], v157 offset:1024
	v_mfma_f32_16x16x32_bf16 v[4:7], v[214:217], v[222:225], v[4:7]
	v_mfma_f32_16x16x32_bf16 v[0:3], v[214:217], v[230:233], v[0:3]
	ds_read_b128 v[182:185], v157 offset:2048
	v_mfma_f32_16x16x32_bf16 v[28:31], v[194:197], v[226:229], v[28:31]
	v_mfma_f32_16x16x32_bf16 v[24:27], v[194:197], v[234:237], v[24:27]
	ds_read_b128 v[186:189], v157 offset:3072
	v_mfma_f32_16x16x32_bf16 v[20:23], v[202:205], v[226:229], v[20:23]
	v_mfma_f32_16x16x32_bf16 v[16:19], v[202:205], v[234:237], v[16:19]
	v_mfma_f32_16x16x32_bf16 v[12:15], v[210:213], v[226:229], v[12:15]
	v_mfma_f32_16x16x32_bf16 v[8:11], v[210:213], v[234:237], v[8:11]
	v_mfma_f32_16x16x32_bf16 v[4:7], v[218:221], v[226:229], v[4:7]
	v_mfma_f32_16x16x32_bf16 v[0:3], v[218:221], v[234:237], v[0:3]
	s_barrier
	s_setprio 0
	v_readfirstlane_b32 s55, v162
	v_lshl_add_u64 v[222:223], v[238:239], 0, s[14:15]
	s_mov_b32 m0, s55
	v_readfirstlane_b32 s55, v163
	ds_read_b128 v[190:193], v153 offset:32768
	ds_read_b128 v[194:197], v153 offset:33792
	ds_read_b128 v[198:201], v152 offset:32768
	ds_read_b128 v[202:205], v152 offset:33792
	ds_read_b128 v[206:209], v151 offset:32768
	ds_read_b128 v[210:213], v151 offset:33792
	ds_read_b128 v[214:217], v150 offset:32768
	ds_read_b128 v[218:221], v150 offset:33792
	global_load_lds_dwordx4 v[222:223], off
	v_lshl_add_u64 v[222:223], v[240:241], 0, s[14:15]
	s_mov_b32 m0, s55
	s_nop 0
	global_load_lds_dwordx4 v[222:223], off
	s_waitcnt lgkmcnt(8)
	s_setprio 1
	s_barrier
	s_waitcnt lgkmcnt(0)
	v_mfma_f32_16x16x32_bf16 v[124:127], v[190:193], v[174:177], v[124:127]
	v_mfma_f32_16x16x32_bf16 v[120:123], v[190:193], v[182:185], v[120:123]
	v_mfma_f32_16x16x32_bf16 v[116:119], v[198:201], v[174:177], v[116:119]
	v_mfma_f32_16x16x32_bf16 v[112:115], v[198:201], v[182:185], v[112:115]
	v_mfma_f32_16x16x32_bf16 v[108:111], v[206:209], v[174:177], v[108:111]
	v_mfma_f32_16x16x32_bf16 v[104:107], v[206:209], v[182:185], v[104:107]
	v_mfma_f32_16x16x32_bf16 v[100:103], v[214:217], v[174:177], v[100:103]
	v_mfma_f32_16x16x32_bf16 v[96:99], v[214:217], v[182:185], v[96:99]
	v_mfma_f32_16x16x32_bf16 v[124:127], v[194:197], v[178:181], v[124:127]
	v_mfma_f32_16x16x32_bf16 v[120:123], v[194:197], v[186:189], v[120:123]
	v_mfma_f32_16x16x32_bf16 v[116:119], v[202:205], v[178:181], v[116:119]
	v_mfma_f32_16x16x32_bf16 v[112:115], v[202:205], v[186:189], v[112:115]
	v_mfma_f32_16x16x32_bf16 v[108:111], v[210:213], v[178:181], v[108:111]
	v_mfma_f32_16x16x32_bf16 v[104:107], v[210:213], v[186:189], v[104:107]
	v_mfma_f32_16x16x32_bf16 v[100:103], v[218:221], v[178:181], v[100:103]
	v_mfma_f32_16x16x32_bf16 v[96:99], v[218:221], v[186:189], v[96:99]
	s_barrier
	s_setprio 0
	v_readfirstlane_b32 s55, v164
	v_lshl_add_u64 v[246:247], v[242:243], 0, s[24:25]
	s_mov_b32 m0, s55
	v_readfirstlane_b32 s55, v165
	ds_read_b128 v[222:225], v154
	ds_read_b128 v[226:229], v154 offset:1024
	ds_read_b128 v[230:233], v154 offset:2048
	ds_read_b128 v[234:237], v154 offset:3072
	global_load_lds_dwordx4 v[246:247], off
	v_lshl_add_u64 v[246:247], v[244:245], 0, s[24:25]
	s_mov_b32 m0, s55
	s_nop 0
	global_load_lds_dwordx4 v[246:247], off
	s_setprio 1
	s_barrier
	s_waitcnt lgkmcnt(0)
	v_mfma_f32_16x16x32_bf16 v[92:95], v[190:193], v[222:225], v[92:95]
	v_mfma_f32_16x16x32_bf16 v[88:91], v[190:193], v[230:233], v[88:91]
	v_mfma_f32_16x16x32_bf16 v[84:87], v[198:201], v[222:225], v[84:87]
	v_mfma_f32_16x16x32_bf16 v[80:83], v[198:201], v[230:233], v[80:83]
	v_mfma_f32_16x16x32_bf16 v[76:79], v[206:209], v[222:225], v[76:79]
	v_mfma_f32_16x16x32_bf16 v[72:75], v[206:209], v[230:233], v[72:75]
	v_mfma_f32_16x16x32_bf16 v[68:71], v[214:217], v[222:225], v[68:71]
	v_mfma_f32_16x16x32_bf16 v[64:67], v[214:217], v[230:233], v[64:67]
	v_mfma_f32_16x16x32_bf16 v[92:95], v[194:197], v[226:229], v[92:95]
	v_mfma_f32_16x16x32_bf16 v[88:91], v[194:197], v[234:237], v[88:91]
	v_mfma_f32_16x16x32_bf16 v[84:87], v[202:205], v[226:229], v[84:87]
	v_mfma_f32_16x16x32_bf16 v[80:83], v[202:205], v[234:237], v[80:83]
	v_mfma_f32_16x16x32_bf16 v[76:79], v[210:213], v[226:229], v[76:79]
	v_mfma_f32_16x16x32_bf16 v[72:75], v[210:213], v[234:237], v[72:75]
	v_mfma_f32_16x16x32_bf16 v[68:71], v[218:221], v[226:229], v[68:71]
	v_mfma_f32_16x16x32_bf16 v[64:67], v[218:221], v[234:237], v[64:67]
	s_barrier
	s_setprio 0
	v_readfirstlane_b32 s55, v166
	v_lshl_add_u64 v[238:239], v[238:239], 0, s[42:43]
	s_mov_b32 m0, s55
	v_readfirstlane_b32 s55, v167
	ds_read_b128 v[190:193], v153 offset:49152
	ds_read_b128 v[194:197], v153 offset:50176
	ds_read_b128 v[198:201], v152 offset:49152
	ds_read_b128 v[202:205], v152 offset:50176
	ds_read_b128 v[206:209], v151 offset:49152
	ds_read_b128 v[210:213], v151 offset:50176
	ds_read_b128 v[214:217], v150 offset:49152
	ds_read_b128 v[218:221], v150 offset:50176
	global_load_lds_dwordx4 v[238:239], off
	v_lshl_add_u64 v[238:239], v[240:241], 0, s[42:43]
	s_mov_b32 m0, s55
	s_nop 0
	global_load_lds_dwordx4 v[238:239], off
	s_setprio 1
	s_barrier
; #define STAGE(P, BASE, kt) do { const char* _g = (const char*)(BASE) + (size_t)((kt) * (BK * 2)); \
;     __builtin_amdgcn_global_load_lds((const unsigned*)(_g + (size_t)goff0), (unsigned*)((char*)(P) + tid_ * 16), 16, 0, 0); \
;     __builtin_amdgcn_global_load_lds((const unsigned*)(_g + (size_t)goff1), (unsigned*)((char*)(P) + tid_ * 16 + 8192), 16, 0, 0); } while (0)
; #define STAGEA(P, BASE, kt) do { const char* _g = (const char*)(BASE) + (size_t)((kt) * a_kbytes); \
;     __builtin_amdgcn_global_load_lds((const unsigned*)(_g + (size_t)goffA0), (unsigned*)((char*)(P) + tid_ * 16), 16, 0, 0); \
;     __builtin_amdgcn_global_load_lds((const unsigned*)(_g + (size_t)goffA1), (unsigned*)((char*)(P) + tid_ * 16 + 8192), 16, 0, 0); } while (0)
; #define LDA(dst, b, h) for (int m = 0; m < 4; ++m) for (int k = 0; k < 2; ++k) \
;     dst[m][k] = *reinterpret_cast<const bf16x8*>((char*)SA(b, h) + lds_byte(wr * 64 + m * 16 + fr, k * 32 + fq * 8))
; #define LDB(dst, b, h) for (int n = 0; n < 2; ++n) for (int k = 0; k < 2; ++k) \
;     dst[n][k] = *reinterpret_cast<const bf16x8*>((char*)SB(b, h) + lds_byte(wc * 32 + n * 16 + fr, k * 32 + fq * 8))
; #define MMA(ai, bj, At, Bt) do { __builtin_amdgcn_s_setprio(1); \
;     for (int m = 0; m < 4; ++m) for (int n = 0; n < 2; ++n) for (int k = 0; k < 2; ++k) \
;       acc[ai][bj][m][n] = __builtin_amdgcn_mfma_f32_16x16x32_bf16(At[m][k], Bt[n][k], acc[ai][bj][m][n], 0, 0, 0); \
;     __builtin_amdgcn_s_setprio(0); } while (0)
; #define WAIT_V(n) asm volatile("s_waitcnt vmcnt(" #n ")" ::: "memory")
; #define WAIT_L(n) asm volatile("s_waitcnt lgkmcnt(" #n ")" ::: "memory")
; #define BAR __builtin_amdgcn_s_barrier()
; template <int EPI> ...
;     ...
;     STAGE(SB(1, 1), B1p, t + 3);
;     WAIT_V(6); BAR; MMA(1, 1, At, B1); BAR;
;   }
;   { LDB(B0, 0, 0); LDA(At, 0, 0); STAGEA(SA(1, 1), A1, nt - 1);
;     BAR; WAIT_L(0); MMA(0, 0, At, B0); BAR;
;     LDB(B1, 0, 1); BAR; WAIT_L(0); MMA(0, 1, At, B1); BAR;
	s_waitcnt lgkmcnt(0)
	v_mfma_f32_16x16x32_bf16 v[60:63], v[190:193], v[174:177], v[60:63]
	v_mfma_f32_16x16x32_bf16 v[56:59], v[190:193], v[182:185], v[56:59]
	v_mfma_f32_16x16x32_bf16 v[52:55], v[198:201], v[174:177], v[52:55]
	v_mfma_f32_16x16x32_bf16 v[48:51], v[198:201], v[182:185], v[48:51]
	v_mfma_f32_16x16x32_bf16 v[44:47], v[206:209], v[174:177], v[44:47]
	v_mfma_f32_16x16x32_bf16 v[40:43], v[206:209], v[182:185], v[40:43]
	v_mfma_f32_16x16x32_bf16 v[36:39], v[214:217], v[174:177], v[36:39]
	v_mfma_f32_16x16x32_bf16 v[32:35], v[214:217], v[182:185], v[32:35]
	v_mfma_f32_16x16x32_bf16 v[60:63], v[194:197], v[178:181], v[60:63]
	v_mfma_f32_16x16x32_bf16 v[56:59], v[194:197], v[186:189], v[56:59]
	v_mfma_f32_16x16x32_bf16 v[52:55], v[202:205], v[178:181], v[52:55]
	v_mfma_f32_16x16x32_bf16 v[48:51], v[202:205], v[186:189], v[48:51]
	v_mfma_f32_16x16x32_bf16 v[44:47], v[210:213], v[178:181], v[44:47]
	v_mfma_f32_16x16x32_bf16 v[40:43], v[210:213], v[186:189], v[40:43]
	v_mfma_f32_16x16x32_bf16 v[36:39], v[218:221], v[178:181], v[36:39]
	v_mfma_f32_16x16x32_bf16 v[32:35], v[218:221], v[186:189], v[32:35]
	s_barrier
	s_setprio 0
	v_readfirstlane_b32 s55, v169
	v_lshl_add_u64 v[174:175], v[242:243], 0, s[46:47]
	s_mov_b32 m0, s55
	v_readfirstlane_b32 s55, v170
	global_load_lds_dwordx4 v[174:175], off
	v_lshl_add_u64 v[174:175], v[244:245], 0, s[46:47]
	s_mov_b32 m0, s55
	s_nop 0
	global_load_lds_dwordx4 v[174:175], off
	s_waitcnt vmcnt(6)
	s_setprio 1
	s_barrier
	v_mfma_f32_16x16x32_bf16 v[28:31], v[190:193], v[222:225], v[28:31]
	v_mfma_f32_16x16x32_bf16 v[24:27], v[190:193], v[230:233], v[24:27]
	v_mfma_f32_16x16x32_bf16 v[20:23], v[198:201], v[222:225], v[20:23]
	v_mfma_f32_16x16x32_bf16 v[16:19], v[198:201], v[230:233], v[16:19]
	ds_read_b128 v[174:177], v171
	v_mfma_f32_16x16x32_bf16 v[12:15], v[206:209], v[222:225], v[12:15]
	v_mfma_f32_16x16x32_bf16 v[8:11], v[206:209], v[230:233], v[8:11]
	ds_read_b128 v[178:181], v171 offset:1024
	v_mfma_f32_16x16x32_bf16 v[4:7], v[214:217], v[222:225], v[4:7]
	v_mfma_f32_16x16x32_bf16 v[0:3], v[214:217], v[230:233], v[0:3]
	ds_read_b128 v[182:185], v171 offset:2048
	v_mfma_f32_16x16x32_bf16 v[28:31], v[194:197], v[226:229], v[28:31]
	v_mfma_f32_16x16x32_bf16 v[24:27], v[194:197], v[234:237], v[24:27]
	ds_read_b128 v[186:189], v171 offset:3072
	v_mfma_f32_16x16x32_bf16 v[20:23], v[202:205], v[226:229], v[20:23]
	v_mfma_f32_16x16x32_bf16 v[16:19], v[202:205], v[234:237], v[16:19]
	v_mfma_f32_16x16x32_bf16 v[12:15], v[210:213], v[226:229], v[12:15]
	v_mfma_f32_16x16x32_bf16 v[8:11], v[210:213], v[234:237], v[8:11]
	v_mfma_f32_16x16x32_bf16 v[4:7], v[218:221], v[226:229], v[4:7]
	v_mfma_f32_16x16x32_bf16 v[0:3], v[218:221], v[234:237], v[0:3]
	s_barrier
	s_setprio 0
	s_add_i32 s53, s53, 2
	s_add_u32 s58, s58, 0x100
	s_addc_u32 s59, s59, 0
	s_cmp_lt_u32 s53, 28
	s_cbranch_scc1 .LBB0_818
	s_add_u32 s56, s56, 0x80f80
	s_addc_u32 s57, s57, 0
	v_readfirstlane_b32 s53, v172
	v_lshl_add_u64 v[166:167], s[56:57], 0, v[130:131]
	s_mov_b32 m0, s53
	v_readfirstlane_b32 s53, v173
	ds_read_b128 v[136:139], v171
	ds_read_b128 v[140:143], v171 offset:1024
	ds_read_b128 v[158:161], v171 offset:2048
	ds_read_b128 v[162:165], v171 offset:3072
	ds_read_b128 v[174:177], v153
	ds_read_b128 v[178:181], v153 offset:1024
	ds_read_b128 v[182:185], v152
	ds_read_b128 v[186:189], v152 offset:1024
	ds_read_b128 v[190:193], v151
	ds_read_b128 v[194:197], v151 offset:1024
	ds_read_b128 v[198:201], v150
	ds_read_b128 v[202:205], v150 offset:1024
	global_load_lds_dwordx4 v[166:167], off
	v_lshl_add_u64 v[166:167], s[56:57], 0, v[128:129]
	s_mov_b32 m0, s53
	s_nop 0
	global_load_lds_dwordx4 v[166:167], off
	s_setprio 1
	s_barrier
	s_waitcnt lgkmcnt(0)
	v_mfma_f32_16x16x32_bf16 v[124:127], v[174:177], v[136:139], v[124:127]
	v_mfma_f32_16x16x32_bf16 v[120:123], v[174:177], v[158:161], v[120:123]
	v_mfma_f32_16x16x32_bf16 v[108:111], v[190:193], v[136:139], v[108:111]
	v_mfma_f32_16x16x32_bf16 v[104:107], v[190:193], v[158:161], v[104:107]
	v_mfma_f32_16x16x32_bf16 v[124:127], v[178:181], v[140:143], v[124:127]
	v_mfma_f32_16x16x32_bf16 v[120:123], v[178:181], v[162:165], v[120:123]
	v_mfma_f32_16x16x32_bf16 v[116:119], v[182:185], v[136:139], v[116:119]
	v_mfma_f32_16x16x32_bf16 v[112:115], v[182:185], v[158:161], v[112:115]
	v_mfma_f32_16x16x32_bf16 v[108:111], v[194:197], v[140:143], v[108:111]
	v_mfma_f32_16x16x32_bf16 v[104:107], v[194:197], v[162:165], v[104:107]
	v_mfma_f32_16x16x32_bf16 v[100:103], v[198:201], v[136:139], v[100:103]
	v_mfma_f32_16x16x32_bf16 v[96:99], v[198:201], v[158:161], v[96:99]
	v_mfma_f32_16x16x32_bf16 v[170:173], v[186:189], v[140:143], v[116:119]
	v_mfma_f32_16x16x32_bf16 v[206:209], v[186:189], v[162:165], v[112:115]
	v_mfma_f32_16x16x32_bf16 v[210:213], v[202:205], v[140:143], v[100:103]
	v_mfma_f32_16x16x32_bf16 v[214:217], v[202:205], v[162:165], v[96:99]
	s_barrier
	s_setprio 0
	s_nop 1
	ds_read_b128 v[96:99], v168
	ds_read_b128 v[100:103], v168 offset:1024
	ds_read_b128 v[112:115], v168 offset:2048
	ds_read_b128 v[116:119], v168 offset:3072
	s_setprio 1
	s_barrier
; #define STAGEA(P, BASE, kt) do { const char* _g = (const char*)(BASE) + (size_t)((kt) * a_kbytes); \
;     __builtin_amdgcn_global_load_lds((const unsigned*)(_g + (size_t)goffA0), (unsigned*)((char*)(P) + tid_ * 16), 16, 0, 0); \
;     __builtin_amdgcn_global_load_lds((const unsigned*)(_g + (size_t)goffA1), (unsigned*)((char*)(P) + tid_ * 16 + 8192), 16, 0, 0); } while (0)
; #define LDA(dst, b, h) for (int m = 0; m < 4; ++m) for (int k = 0; k < 2; ++k) \
;     dst[m][k] = *reinterpret_cast<const bf16x8*>((char*)SA(b, h) + lds_byte(wr * 64 + m * 16 + fr, k * 32 + fq * 8))
; #define LDB(dst, b, h) for (int n = 0; n < 2; ++n) for (int k = 0; k < 2; ++k) \
;     dst[n][k] = *reinterpret_cast<const bf16x8*>((char*)SB(b, h) + lds_byte(wc * 32 + n * 16 + fr, k * 32 + fq * 8))
; #define MMA(ai, bj, At, Bt) do { __builtin_amdgcn_s_setprio(1); \
;     for (int m = 0; m < 4; ++m) for (int n = 0; n < 2; ++n) for (int k = 0; k < 2; ++k) \
;       acc[ai][bj][m][n] = __builtin_amdgcn_mfma_f32_16x16x32_bf16(At[m][k], Bt[n][k], acc[ai][bj][m][n], 0, 0, 0); \
;     __builtin_amdgcn_s_setprio(0); } while (0)
; #define WAIT_V(n) asm volatile("s_waitcnt vmcnt(" #n ")" ::: "memory")
; #define WAIT_L(n) asm volatile("s_waitcnt lgkmcnt(" #n ")" ::: "memory")
; #define BAR __builtin_amdgcn_s_barrier()
; template <int EPI> ...
;     ...
;   { LDB(B0, 0, 0); LDA(At, 0, 0); STAGEA(SA(1, 1), A1, nt - 1);
;     BAR; WAIT_L(0); MMA(0, 0, At, B0); BAR;
;     LDB(B1, 0, 1); BAR; WAIT_L(0); MMA(0, 1, At, B1); BAR;
;     LDA(At, 0, 1); WAIT_V(4); BAR; WAIT_L(0); MMA(1, 0, At, B0); MMA(1, 1, At, B1); BAR; }
;   { LDB(B0, 1, 0); LDA(At, 1, 0); WAIT_V(2); BAR; WAIT_L(0); MMA(0, 0, At, B0); BAR;
;     LDB(B1, 1, 1); WAIT_V(0); BAR; WAIT_L(0); MMA(0, 1, At, B1); BAR;
;     LDA(At, 1, 1); BAR; WAIT_L(0); MMA(1, 0, At, B0); MMA(1, 1, At, B1); BAR; }
	s_waitcnt lgkmcnt(0)
	v_mfma_f32_16x16x32_bf16 v[92:95], v[174:177], v[96:99], v[92:95]
	v_mfma_f32_16x16x32_bf16 v[88:91], v[174:177], v[112:115], v[88:91]
	v_mfma_f32_16x16x32_bf16 v[76:79], v[190:193], v[96:99], v[76:79]
	v_mfma_f32_16x16x32_bf16 v[72:75], v[190:193], v[112:115], v[72:75]
	v_mfma_f32_16x16x32_bf16 v[92:95], v[178:181], v[100:103], v[92:95]
	v_mfma_f32_16x16x32_bf16 v[88:91], v[178:181], v[116:119], v[88:91]
	v_mfma_f32_16x16x32_bf16 v[84:87], v[182:185], v[96:99], v[84:87]
	v_mfma_f32_16x16x32_bf16 v[80:83], v[182:185], v[112:115], v[80:83]
	v_mfma_f32_16x16x32_bf16 v[76:79], v[194:197], v[100:103], v[76:79]
	v_mfma_f32_16x16x32_bf16 v[72:75], v[194:197], v[116:119], v[72:75]
	v_mfma_f32_16x16x32_bf16 v[68:71], v[198:201], v[96:99], v[68:71]
	v_mfma_f32_16x16x32_bf16 v[64:67], v[198:201], v[112:115], v[64:67]
	v_mfma_f32_16x16x32_bf16 v[166:169], v[186:189], v[100:103], v[84:87]
	v_mfma_f32_16x16x32_bf16 v[174:177], v[186:189], v[116:119], v[80:83]
	v_mfma_f32_16x16x32_bf16 v[178:181], v[202:205], v[100:103], v[68:71]
	v_mfma_f32_16x16x32_bf16 v[182:185], v[202:205], v[116:119], v[64:67]
	s_barrier
	s_setprio 0
	s_nop 1
	ds_read_b128 v[64:67], v153 offset:16384
	ds_read_b128 v[68:71], v153 offset:17408
	ds_read_b128 v[80:83], v152 offset:16384
	ds_read_b128 v[84:87], v152 offset:17408
	ds_read_b128 v[186:189], v151 offset:16384
	ds_read_b128 v[190:193], v151 offset:17408
	ds_read_b128 v[194:197], v150 offset:16384
	ds_read_b128 v[198:201], v150 offset:17408
	s_waitcnt vmcnt(4)
	s_setprio 1
	s_barrier
	s_waitcnt lgkmcnt(0)
	v_mfma_f32_16x16x32_bf16 v[60:63], v[64:67], v[136:139], v[60:63]
	v_mfma_f32_16x16x32_bf16 v[56:59], v[64:67], v[158:161], v[56:59]
	v_mfma_f32_16x16x32_bf16 v[44:47], v[186:189], v[136:139], v[44:47]
	v_mfma_f32_16x16x32_bf16 v[40:43], v[186:189], v[158:161], v[40:43]
	v_mfma_f32_16x16x32_bf16 v[60:63], v[68:71], v[140:143], v[60:63]
	v_mfma_f32_16x16x32_bf16 v[56:59], v[68:71], v[162:165], v[56:59]
	v_mfma_f32_16x16x32_bf16 v[52:55], v[80:83], v[136:139], v[52:55]
	v_mfma_f32_16x16x32_bf16 v[48:51], v[80:83], v[158:161], v[48:51]
	v_mfma_f32_16x16x32_bf16 v[44:47], v[190:193], v[140:143], v[44:47]
	v_mfma_f32_16x16x32_bf16 v[40:43], v[190:193], v[162:165], v[40:43]
	v_mfma_f32_16x16x32_bf16 v[36:39], v[194:197], v[136:139], v[36:39]
	v_mfma_f32_16x16x32_bf16 v[32:35], v[194:197], v[158:161], v[32:35]
	v_mfma_f32_16x16x32_bf16 v[202:205], v[84:87], v[140:143], v[52:55]
	v_mfma_f32_16x16x32_bf16 v[218:221], v[84:87], v[162:165], v[48:51]
	v_mfma_f32_16x16x32_bf16 v[136:139], v[198:201], v[140:143], v[36:39]
	v_mfma_f32_16x16x32_bf16 v[140:143], v[198:201], v[162:165], v[32:35]
	s_setprio 0
	s_setprio 1
	v_mfma_f32_16x16x32_bf16 v[28:31], v[64:67], v[96:99], v[28:31]
	v_mfma_f32_16x16x32_bf16 v[24:27], v[64:67], v[112:115], v[24:27]
	v_mfma_f32_16x16x32_bf16 v[12:15], v[186:189], v[96:99], v[12:15]
	v_mfma_f32_16x16x32_bf16 v[8:11], v[186:189], v[112:115], v[8:11]
	v_mfma_f32_16x16x32_bf16 v[28:31], v[68:71], v[100:103], v[28:31]
	v_mfma_f32_16x16x32_bf16 v[24:27], v[68:71], v[116:119], v[24:27]
	v_mfma_f32_16x16x32_bf16 v[20:23], v[80:83], v[96:99], v[20:23]
	v_mfma_f32_16x16x32_bf16 v[16:19], v[80:83], v[112:115], v[16:19]
	v_mfma_f32_16x16x32_bf16 v[12:15], v[190:193], v[100:103], v[12:15]
	v_mfma_f32_16x16x32_bf16 v[8:11], v[190:193], v[116:119], v[8:11]
	v_mfma_f32_16x16x32_bf16 v[4:7], v[194:197], v[96:99], v[4:7]
	v_mfma_f32_16x16x32_bf16 v[0:3], v[194:197], v[112:115], v[0:3]
	v_mfma_f32_16x16x32_bf16 v[158:161], v[84:87], v[100:103], v[20:23]
	v_mfma_f32_16x16x32_bf16 v[162:165], v[84:87], v[116:119], v[16:19]
	v_mfma_f32_16x16x32_bf16 v[186:189], v[198:201], v[100:103], v[4:7]
	v_mfma_f32_16x16x32_bf16 v[190:193], v[198:201], v[116:119], v[0:3]
	s_barrier
	s_setprio 0
	s_nop 1
	ds_read_b128 v[0:3], v157
	ds_read_b128 v[4:7], v157 offset:1024
	ds_read_b128 v[194:197], v157 offset:2048
	ds_read_b128 v[198:201], v157 offset:3072
	ds_read_b128 v[16:19], v153 offset:32768
	ds_read_b128 v[20:23], v153 offset:33792
	ds_read_b128 v[32:35], v152 offset:32768
	ds_read_b128 v[36:39], v152 offset:33792
	ds_read_b128 v[48:51], v151 offset:32768
	ds_read_b128 v[52:55], v151 offset:33792
	ds_read_b128 v[222:225], v150 offset:32768
	ds_read_b128 v[226:229], v150 offset:33792
	s_waitcnt vmcnt(2)
	s_setprio 1
	s_barrier
	s_waitcnt lgkmcnt(0)
	v_mfma_f32_16x16x32_bf16 v[64:67], v[16:19], v[0:3], v[124:127]
	v_mfma_f32_16x16x32_bf16 v[116:119], v[20:23], v[4:7], v[64:67]
	v_mfma_f32_16x16x32_bf16 v[64:67], v[16:19], v[194:197], v[120:123]
	v_mfma_f32_16x16x32_bf16 v[112:115], v[20:23], v[198:201], v[64:67]
	v_mfma_f32_16x16x32_bf16 v[64:67], v[32:35], v[0:3], v[170:173]
	v_mfma_f32_16x16x32_bf16 v[100:103], v[36:39], v[4:7], v[64:67]
	v_mfma_f32_16x16x32_bf16 v[64:67], v[32:35], v[194:197], v[206:209]
	v_mfma_f32_16x16x32_bf16 v[96:99], v[36:39], v[198:201], v[64:67]
	v_mfma_f32_16x16x32_bf16 v[64:67], v[48:51], v[0:3], v[108:111]
	v_mfma_f32_16x16x32_bf16 v[84:87], v[52:55], v[4:7], v[64:67]
	v_mfma_f32_16x16x32_bf16 v[64:67], v[48:51], v[194:197], v[104:107]
	v_mfma_f32_16x16x32_bf16 v[80:83], v[52:55], v[198:201], v[64:67]
	v_mfma_f32_16x16x32_bf16 v[64:67], v[222:225], v[0:3], v[210:213]
	v_mfma_f32_16x16x32_bf16 v[68:71], v[226:229], v[4:7], v[64:67]
	v_mfma_f32_16x16x32_bf16 v[64:67], v[222:225], v[194:197], v[214:217]
	v_mfma_f32_16x16x32_bf16 v[64:67], v[226:229], v[198:201], v[64:67]
	s_barrier
	s_setprio 0
	ds_read_b128 v[170:173], v154
	ds_read_b128 v[206:209], v154 offset:1024
	ds_read_b128 v[210:213], v154 offset:2048
	ds_read_b128 v[154:157], v154 offset:3072
	s_waitcnt vmcnt(0)
	s_setprio 1
	s_barrier
; #define LDA(dst, b, h) for (int m = 0; m < 4; ++m) for (int k = 0; k < 2; ++k) \
;     dst[m][k] = *reinterpret_cast<const bf16x8*>((char*)SA(b, h) + lds_byte(wr * 64 + m * 16 + fr, k * 32 + fq * 8))
; #define LDB(dst, b, h) for (int n = 0; n < 2; ++n) for (int k = 0; k < 2; ++k) \
;     dst[n][k] = *reinterpret_cast<const bf16x8*>((char*)SB(b, h) + lds_byte(wc * 32 + n * 16 + fr, k * 32 + fq * 8))
; #define MMA(ai, bj, At, Bt) do { __builtin_amdgcn_s_setprio(1); \
;     for (int m = 0; m < 4; ++m) for (int n = 0; n < 2; ++n) for (int k = 0; k < 2; ++k) \
;       acc[ai][bj][m][n] = __builtin_amdgcn_mfma_f32_16x16x32_bf16(At[m][k], Bt[n][k], acc[ai][bj][m][n], 0, 0, 0); \
;     __builtin_amdgcn_s_setprio(0); } while (0)
; #define WAIT_V(n) asm volatile("s_waitcnt vmcnt(" #n ")" ::: "memory")
; #define WAIT_L(n) asm volatile("s_waitcnt lgkmcnt(" #n ")" ::: "memory")
; #define BAR __builtin_amdgcn_s_barrier()
; template <int EPI> ...
;     ...
;   { LDB(B0, 1, 0); LDA(At, 1, 0); WAIT_V(2); BAR; WAIT_L(0); MMA(0, 0, At, B0); BAR;
;     LDB(B1, 1, 1); WAIT_V(0); BAR; WAIT_L(0); MMA(0, 1, At, B1); BAR;
;     LDA(At, 1, 1); BAR; WAIT_L(0); MMA(1, 0, At, B0); MMA(1, 1, At, B1); BAR; }
;   if (wr == 0) BAR;
;   {
;     constexpr int NC = (EPI == EPI_GU) ? 128 : 256;
;     constexpr int RB = NC * 2;
;     char* tb = (char*)shm;
; #pragma unroll
;     for (int ai = 0; ai < 2; ++ai)
; #pragma unroll
;       for (int m = 0; m < 4; ++m)
; #pragma unroll
;         for (int j = 0; j < 4; ++j) {
;           const int r = ai * 128 + wr * 64 + m * 16 + fq * 4 + j;
;           float rs = 1.0f;
;           if (EPI != EPI_RES) rs = e.rstd[brow + r];
	s_waitcnt lgkmcnt(0)
	v_mfma_f32_16x16x32_bf16 v[92:95], v[16:19], v[170:173], v[92:95]
	v_mfma_f32_16x16x32_bf16 v[16:19], v[16:19], v[210:213], v[88:91]
	v_mfma_f32_16x16x32_bf16 v[120:123], v[20:23], v[154:157], v[16:19]
	v_mfma_f32_16x16x32_bf16 v[16:19], v[32:35], v[170:173], v[166:169]
	v_mfma_f32_16x16x32_bf16 v[108:111], v[36:39], v[206:209], v[16:19]
	v_mfma_f32_16x16x32_bf16 v[16:19], v[32:35], v[210:213], v[174:177]
	v_mfma_f32_16x16x32_bf16 v[104:107], v[36:39], v[154:157], v[16:19]
	v_mfma_f32_16x16x32_bf16 v[16:19], v[48:51], v[170:173], v[76:79]
	v_mfma_f32_16x16x32_bf16 v[124:127], v[20:23], v[206:209], v[92:95]
	v_mfma_f32_16x16x32_bf16 v[92:95], v[52:55], v[206:209], v[16:19]
	v_mfma_f32_16x16x32_bf16 v[16:19], v[48:51], v[210:213], v[72:75]
	v_mfma_f32_16x16x32_bf16 v[88:91], v[52:55], v[154:157], v[16:19]
	v_mfma_f32_16x16x32_bf16 v[16:19], v[222:225], v[170:173], v[178:181]
	v_mfma_f32_16x16x32_bf16 v[76:79], v[226:229], v[206:209], v[16:19]
	v_mfma_f32_16x16x32_bf16 v[16:19], v[222:225], v[210:213], v[182:185]
	v_mfma_f32_16x16x32_bf16 v[72:75], v[226:229], v[154:157], v[16:19]
	s_barrier
	s_setprio 0
	ds_read_b128 v[166:169], v153 offset:49152
	ds_read_b128 v[174:177], v153 offset:50176
	ds_read_b128 v[178:181], v152 offset:49152
	ds_read_b128 v[182:185], v152 offset:50176
	ds_read_b128 v[214:217], v151 offset:49152
	ds_read_b128 v[222:225], v151 offset:50176
	ds_read_b128 v[226:229], v150 offset:49152
	ds_read_b128 v[150:153], v150 offset:50176
	s_setprio 1
	s_barrier
	s_waitcnt lgkmcnt(0)
	v_mfma_f32_16x16x32_bf16 v[16:19], v[166:169], v[0:3], v[60:63]
	v_mfma_f32_16x16x32_bf16 v[52:55], v[174:177], v[4:7], v[16:19]
	v_mfma_f32_16x16x32_bf16 v[16:19], v[166:169], v[194:197], v[56:59]
	v_mfma_f32_16x16x32_bf16 v[48:51], v[174:177], v[198:201], v[16:19]
	v_mfma_f32_16x16x32_bf16 v[16:19], v[178:181], v[0:3], v[202:205]
	v_mfma_f32_16x16x32_bf16 v[36:39], v[182:185], v[4:7], v[16:19]
	v_mfma_f32_16x16x32_bf16 v[16:19], v[178:181], v[194:197], v[218:221]
	v_mfma_f32_16x16x32_bf16 v[32:35], v[182:185], v[198:201], v[16:19]
	v_mfma_f32_16x16x32_bf16 v[16:19], v[214:217], v[0:3], v[44:47]
	v_mfma_f32_16x16x32_bf16 v[0:3], v[226:229], v[0:3], v[136:139]
	v_mfma_f32_16x16x32_bf16 v[20:23], v[222:225], v[4:7], v[16:19]
	v_mfma_f32_16x16x32_bf16 v[16:19], v[214:217], v[194:197], v[40:43]
	v_mfma_f32_16x16x32_bf16 v[4:7], v[150:153], v[4:7], v[0:3]
	v_mfma_f32_16x16x32_bf16 v[0:3], v[226:229], v[194:197], v[140:143]
	v_mfma_f32_16x16x32_bf16 v[16:19], v[222:225], v[198:201], v[16:19]
	v_mfma_f32_16x16x32_bf16 v[0:3], v[150:153], v[198:201], v[0:3]
	s_setprio 0
	s_setprio 1
	v_mfma_f32_16x16x32_bf16 v[24:27], v[166:169], v[210:213], v[24:27]
	v_mfma_f32_16x16x32_bf16 v[56:59], v[174:177], v[154:157], v[24:27]
	v_mfma_f32_16x16x32_bf16 v[24:27], v[178:181], v[170:173], v[158:161]
	v_mfma_f32_16x16x32_bf16 v[44:47], v[182:185], v[206:209], v[24:27]
	v_mfma_f32_16x16x32_bf16 v[24:27], v[178:181], v[210:213], v[162:165]
	v_mfma_f32_16x16x32_bf16 v[8:11], v[214:217], v[210:213], v[8:11]
	v_mfma_f32_16x16x32_bf16 v[28:31], v[166:169], v[170:173], v[28:31]
	v_mfma_f32_16x16x32_bf16 v[40:43], v[182:185], v[154:157], v[24:27]
	v_mfma_f32_16x16x32_bf16 v[12:15], v[214:217], v[170:173], v[12:15]
	v_mfma_f32_16x16x32_bf16 v[24:27], v[222:225], v[154:157], v[8:11]
	v_mfma_f32_16x16x32_bf16 v[8:11], v[226:229], v[170:173], v[186:189]
	v_mfma_f32_16x16x32_bf16 v[60:63], v[174:177], v[206:209], v[28:31]
	v_mfma_f32_16x16x32_bf16 v[28:31], v[222:225], v[206:209], v[12:15]
	v_mfma_f32_16x16x32_bf16 v[12:15], v[150:153], v[206:209], v[8:11]
	v_mfma_f32_16x16x32_bf16 v[8:11], v[226:229], v[210:213], v[190:193]
	v_mfma_f32_16x16x32_bf16 v[8:11], v[150:153], v[154:157], v[8:11]
	s_barrier
	s_setprio 0
	v_cmp_gt_u32_e32 vcc, s84, v144
	s_and_saveexec_b64 s[56:57], vcc
	s_cbranch_execz .LBB0_821
	s_barrier
.LBB0_821:
	s_or_b64 exec, exec, s[56:57]
	v_lshl_or_b32 v142, v145, 2, v149
	v_add_u32_e32 v136, s52, v142
	v_ashrrev_i32_e32 v137, 31, v136
	v_lshl_add_u64 v[136:137], v[136:137], 2, s[0:1]
	global_load_dwordx4 v[150:153], v[136:137], off
	v_lshlrev_b32_e32 v138, 1, v147
	v_or_b32_e32 v147, 16, v142
	v_add_u32_e32 v144, s52, v147
	v_bitop3_b32 v139, v138, v145, 8 bitop3:0x36
	v_xor_b32_e32 v140, v138, v145
	v_bitop3_b32 v143, v138, v145, 1 bitop3:0x36
	v_bitop3_b32 v138, v138, v145, 9 bitop3:0x36
	v_ashrrev_i32_e32 v145, 31, v144
	v_lshl_add_u64 v[144:145], v[144:145], 2, s[0:1]
	global_load_dwordx4 v[154:157], v[144:145], off
	v_lshl_add_u32 v137, v148, 1, 0
	v_lshl_add_u32 v136, v142, 9, v137
	v_lshlrev_b32_e32 v141, 5, v140
	v_lshlrev_b32_e32 v140, 5, v143
	v_lshlrev_b32_e32 v139, 5, v139
	v_lshlrev_b32_e32 v138, 5, v138
	v_add_u32_e32 v143, 0x200, v136
	v_add_u32_e32 v148, 0x400, v136
	v_add_u32_e32 v149, v136, v141
	v_add_u32_e32 v158, v136, v140
	v_add_u32_e32 v159, v136, v139
	v_add_u32_e32 v144, v136, v138
	v_add_u32_e32 v145, v143, v141
	v_add_u32_e32 v160, v143, v140
	v_add_u32_e32 v161, v143, v139
	v_add_u32_e32 v143, v143, v138
	v_add_u32_e32 v162, v148, v141
	v_add_u32_e32 v163, v148, v140
	v_add_u32_e32 v164, v148, v139
	v_add_u32_e32 v148, v148, v138
	s_mul_i32 s55, s52, 0x1800
	s_mul_hi_i32 s53, s52, 0x1800
	s_add_u32 s56, s72, s55
	s_addc_u32 s57, s73, s53
	s_lshl_b32 s54, s54, 8
	s_ashr_i32 s55, s54, 31
	s_waitcnt vmcnt(0)
; __device__ __forceinline__ u16 f2bf(float f) { unsigned u = __float_as_uint(f); u += 0x7fffu + ((u >> 16) & 1u); return (u16)(u >> 16); }
; __device__ __forceinline__ float frcp(float x) { return __builtin_amdgcn_rcpf(x); }
; template <int EPI> ...
;     ...
;           const int r = ai * 128 + wr * 64 + m * 16 + fq * 4 + j;
;           float rs = 1.0f;
;           if (EPI != EPI_RES) rs = e.rstd[brow + r];
;           char* rowp = tb + r * RB + fr * 2;
;           if (EPI == EPI_GU) {
; #pragma unroll
;             for (int n = 0; n < 2; ++n) {
;               float g = acc[ai][0][m][n][j] * rs, u = acc[ai][1][m][n][j] * rs;
;               float h = g * frcp(1.0f + __expf(-g)) * u;
;               const int seg = (wc * 2 + n) ^ fq;
;               *(u16*)(rowp + seg * 32) = f2bf(h);
;             }
;           } else {
; #pragma unroll
;             for (int bj = 0; bj < 2; ++bj)
; #pragma unroll
;               for (int n = 0; n < 2; ++n) {
;                 const int seg = (bj * 8 + wc * 2 + n) ^ fq;
;                 *(u16*)(rowp + seg * 32) = f2bf(acc[ai][bj][m][n][j] * rs);
;               }
	v_mul_f32_e32 v116, v116, v150
	v_mul_f32_e32 v113, v113, v151
	v_mul_f32_e32 v112, v112, v150
	v_mul_f32_e32 v124, v124, v150
	v_mul_f32_e32 v120, v120, v150
	v_mul_f32_e32 v117, v117, v151
	v_mul_f32_e32 v125, v125, v151
	v_mul_f32_e32 v121, v121, v151
	v_mul_f32_e32 v118, v118, v152
	v_mul_f32_e32 v114, v114, v152
	v_mul_f32_e32 v126, v126, v152
	v_mul_f32_e32 v122, v122, v152
	v_cvt_pk_bf16_f32 v116, v116, v116
	v_cvt_pk_bf16_f32 v113, v113, v113
	v_cvt_pk_bf16_f32 v112, v112, v112
	v_cvt_pk_bf16_f32 v124, v124, v124
	v_cvt_pk_bf16_f32 v120, v120, v120
	v_cvt_pk_bf16_f32 v117, v117, v117
	v_cvt_pk_bf16_f32 v125, v125, v125
	v_cvt_pk_bf16_f32 v121, v121, v121
	v_cvt_pk_bf16_f32 v118, v118, v118
	v_cvt_pk_bf16_f32 v114, v114, v114
	v_cvt_pk_bf16_f32 v126, v126, v126
	v_cvt_pk_bf16_f32 v122, v122, v122
	ds_write_b16_d16_hi v149, v116
	ds_write_b16_d16_hi v158, v112
	ds_write_b16_d16_hi v159, v124
	ds_write_b16_d16_hi v144, v120
	ds_write_b16_d16_hi v145, v117
	ds_write_b16_d16_hi v160, v113
	ds_write_b16_d16_hi v161, v125
	ds_write_b16_d16_hi v143, v121
	ds_write_b16_d16_hi v162, v118
	ds_write_b16_d16_hi v163, v114
	ds_write_b16_d16_hi v164, v126
	ds_write_b16_d16_hi v148, v122
	v_mul_f32_e32 v113, v119, v153
	v_add_u32_e32 v112, 0x600, v136
	v_cvt_pk_bf16_f32 v113, v113, v113
	v_add_u32_e32 v114, v112, v141
	ds_write_b16_d16_hi v114, v113
	v_mul_f32_e32 v113, v115, v153
	v_cvt_pk_bf16_f32 v113, v113, v113
	v_add_u32_e32 v114, v112, v140
	ds_write_b16_d16_hi v114, v113
	v_mul_f32_e32 v113, v127, v153
	v_cvt_pk_bf16_f32 v113, v113, v113
	v_add_u32_e32 v114, v112, v139
	ds_write_b16_d16_hi v114, v113
	v_mul_f32_e32 v113, v123, v153
	v_bfe_u32 v114, v113, 16, 1
	v_add3_u32 v113, v113, v114, s85
	v_add_u32_e32 v112, v112, v138
	v_mul_f32_e32 v100, v100, v154
	ds_write_b16_d16_hi v112, v113
	v_lshl_add_u32 v116, v147, 9, v137
	v_cvt_pk_bf16_f32 v100, v100, v100
	v_add_u32_e32 v112, v116, v141
	v_mul_f32_e32 v96, v96, v154
	ds_write_b16_d16_hi v112, v100
	v_cvt_pk_bf16_f32 v96, v96, v96
	v_add_u32_e32 v100, v116, v140
	ds_write_b16_d16_hi v100, v96
	v_or_b32_e32 v96, 32, v142
	v_add_u32_e32 v112, s52, v96
	v_ashrrev_i32_e32 v113, 31, v112
	v_lshl_add_u64 v[112:113], v[112:113], 2, s[0:1]
	global_load_dwordx4 v[112:115], v[112:113], off
	v_mul_f32_e32 v100, v108, v154
	v_cvt_pk_bf16_f32 v100, v100, v100
	v_add_u32_e32 v108, v116, v139
	ds_write_b16_d16_hi v108, v100
	v_mul_f32_e32 v100, v104, v154
	v_cvt_pk_bf16_f32 v100, v100, v100
	v_add_u32_e32 v104, v116, v138
	v_mul_f32_e32 v101, v101, v155
	ds_write_b16_d16_hi v104, v100
	v_add_u32_e32 v100, 0x2200, v136
	v_cvt_pk_bf16_f32 v101, v101, v101
	v_add_u32_e32 v104, v100, v141
	v_mul_f32_e32 v97, v97, v155
	ds_write_b16_d16_hi v104, v101
	v_cvt_pk_bf16_f32 v97, v97, v97
	v_add_u32_e32 v101, v100, v140
	ds_write_b16_d16_hi v101, v97
	v_mul_f32_e32 v97, v109, v155
	v_cvt_pk_bf16_f32 v97, v97, v97
	v_add_u32_e32 v101, v100, v139
	ds_write_b16_d16_hi v101, v97
	v_mul_f32_e32 v97, v105, v155
	v_cvt_pk_bf16_f32 v97, v97, v97
	v_add_u32_e32 v100, v100, v138
	ds_write_b16_d16_hi v100, v97
	v_mul_f32_e32 v100, v102, v156
	v_add_u32_e32 v97, 0x2400, v136
	v_cvt_pk_bf16_f32 v100, v100, v100
	v_add_u32_e32 v101, v97, v141
	v_mul_f32_e32 v98, v98, v156
	ds_write_b16_d16_hi v101, v100
	v_cvt_pk_bf16_f32 v98, v98, v98
	v_add_u32_e32 v100, v97, v140
	ds_write_b16_d16_hi v100, v98
	v_mul_f32_e32 v98, v110, v156
	v_cvt_pk_bf16_f32 v98, v98, v98
	v_add_u32_e32 v100, v97, v139
	ds_write_b16_d16_hi v100, v98
	v_mul_f32_e32 v98, v106, v156
	v_cvt_pk_bf16_f32 v98, v98, v98
	v_add_u32_e32 v97, v97, v138
	ds_write_b16_d16_hi v97, v98
	v_mul_f32_e32 v98, v103, v157
	v_add_u32_e32 v97, 0x2600, v136
	v_cvt_pk_bf16_f32 v98, v98, v98
	v_add_u32_e32 v100, v97, v141
	ds_write_b16_d16_hi v100, v98
	v_mul_f32_e32 v98, v99, v157
	v_cvt_pk_bf16_f32 v98, v98, v98
	v_add_u32_e32 v99, v97, v140
	ds_write_b16_d16_hi v99, v98
	v_mul_f32_e32 v98, v111, v157
	v_cvt_pk_bf16_f32 v98, v98, v98
	v_add_u32_e32 v99, v97, v139
	ds_write_b16_d16_hi v99, v98
	v_mul_f32_e32 v98, v107, v157
	v_bfe_u32 v99, v98, 16, 1
	v_or_b32_e32 v101, 48, v142
	v_add3_u32 v98, v98, v99, s85
	v_add_u32_e32 v97, v97, v138
	v_lshl_add_u32 v100, v96, 9, v137
	v_add_u32_e32 v96, s52, v101
	ds_write_b16_d16_hi v97, v98
	v_ashrrev_i32_e32 v97, 31, v96
	v_lshl_add_u64 v[96:97], v[96:97], 2, s[0:1]
	global_load_dwordx4 v[96:99], v[96:97], off
	s_waitcnt vmcnt(1)
	v_mul_f32_e32 v84, v84, v112
	v_cvt_pk_bf16_f32 v84, v84, v84
	v_add_u32_e32 v102, v100, v141
	v_mul_f32_e32 v80, v80, v112
	ds_write_b16_d16_hi v102, v84
	v_cvt_pk_bf16_f32 v80, v80, v80
	v_add_u32_e32 v84, v100, v140
	ds_write_b16_d16_hi v84, v80
	v_mul_f32_e32 v80, v92, v112
	v_cvt_pk_bf16_f32 v80, v80, v80
	v_add_u32_e32 v84, v100, v139
	ds_write_b16_d16_hi v84, v80
	v_mul_f32_e32 v80, v88, v112
	v_cvt_pk_bf16_f32 v80, v80, v80
	v_add_u32_e32 v84, v100, v138
	ds_write_b16_d16_hi v84, v80
	v_mul_f32_e32 v84, v85, v113
	v_add_u32_e32 v80, 0x4200, v136
	v_cvt_pk_bf16_f32 v84, v84, v84
	v_add_u32_e32 v85, v80, v141
	v_mul_f32_e32 v81, v81, v113
	ds_write_b16_d16_hi v85, v84
	v_cvt_pk_bf16_f32 v81, v81, v81
	v_add_u32_e32 v84, v80, v140
	ds_write_b16_d16_hi v84, v81
	v_mul_f32_e32 v81, v93, v113
	v_cvt_pk_bf16_f32 v81, v81, v81
	v_add_u32_e32 v84, v80, v139
	ds_write_b16_d16_hi v84, v81
	v_mul_f32_e32 v81, v89, v113
	v_cvt_pk_bf16_f32 v81, v81, v81
	v_add_u32_e32 v80, v80, v138
	ds_write_b16_d16_hi v80, v81
	v_mul_f32_e32 v81, v86, v114
	v_add_u32_e32 v80, 0x4400, v136
	v_cvt_pk_bf16_f32 v81, v81, v81
	v_add_u32_e32 v84, v80, v141
	ds_write_b16_d16_hi v84, v81
	v_mul_f32_e32 v81, v82, v114
	v_cvt_pk_bf16_f32 v81, v81, v81
	v_add_u32_e32 v82, v80, v140
	ds_write_b16_d16_hi v82, v81
	v_mul_f32_e32 v81, v94, v114
	v_cvt_pk_bf16_f32 v81, v81, v81
	v_add_u32_e32 v82, v80, v139
	ds_write_b16_d16_hi v82, v81
	v_mul_f32_e32 v81, v90, v114
	v_cvt_pk_bf16_f32 v81, v81, v81
	v_add_u32_e32 v80, v80, v138
	ds_write_b16_d16_hi v80, v81
	v_mul_f32_e32 v81, v87, v115
	v_add_u32_e32 v80, 0x4600, v136
	v_cvt_pk_bf16_f32 v81, v81, v81
	v_add_u32_e32 v82, v80, v141
	ds_write_b16_d16_hi v82, v81
	v_mul_f32_e32 v81, v83, v115
	v_cvt_pk_bf16_f32 v81, v81, v81
	v_add_u32_e32 v82, v80, v140
	ds_write_b16_d16_hi v82, v81
	v_mul_f32_e32 v81, v95, v115
	v_cvt_pk_bf16_f32 v81, v81, v81
	v_add_u32_e32 v82, v80, v139
	ds_write_b16_d16_hi v82, v81
	v_mul_f32_e32 v81, v91, v115
	v_bfe_u32 v82, v81, 16, 1
	v_add3_u32 v81, v81, v82, s85
	v_add_u32_e32 v80, v80, v138
	s_waitcnt vmcnt(0)
; __device__ __forceinline__ u16 f2bf(float f) { unsigned u = __float_as_uint(f); u += 0x7fffu + ((u >> 16) & 1u); return (u16)(u >> 16); }
; __device__ __forceinline__ float frcp(float x) { return __builtin_amdgcn_rcpf(x); }
; template <int EPI> ...
;     ...
;           const int r = ai * 128 + wr * 64 + m * 16 + fq * 4 + j;
;           float rs = 1.0f;
;           if (EPI != EPI_RES) rs = e.rstd[brow + r];
;           char* rowp = tb + r * RB + fr * 2;
;           if (EPI == EPI_GU) {
; #pragma unroll
;             for (int n = 0; n < 2; ++n) {
;               float g = acc[ai][0][m][n][j] * rs, u = acc[ai][1][m][n][j] * rs;
;               float h = g * frcp(1.0f + __expf(-g)) * u;
;               const int seg = (wc * 2 + n) ^ fq;
;               *(u16*)(rowp + seg * 32) = f2bf(h);
;             }
;           } else {
; #pragma unroll
;             for (int bj = 0; bj < 2; ++bj)
; #pragma unroll
;               for (int n = 0; n < 2; ++n) {
;                 const int seg = (bj * 8 + wc * 2 + n) ^ fq;
;                 *(u16*)(rowp + seg * 32) = f2bf(acc[ai][bj][m][n][j] * rs);
;               }
	v_mul_f32_e32 v68, v68, v96
	ds_write_b16_d16_hi v80, v81
	v_lshl_add_u32 v84, v101, 9, v137
	v_cvt_pk_bf16_f32 v68, v68, v68
	v_add_u32_e32 v80, v84, v141
	v_mul_f32_e32 v64, v64, v96
	ds_write_b16_d16_hi v80, v68
	v_cvt_pk_bf16_f32 v64, v64, v64
	v_add_u32_e32 v68, v84, v140
	ds_write_b16_d16_hi v68, v64
	v_add_u32_e32 v64, 0x80, v142
	v_add_u32_e32 v80, s52, v64
	v_ashrrev_i32_e32 v81, 31, v80
	v_lshl_add_u64 v[80:81], v[80:81], 2, s[0:1]
	global_load_dwordx4 v[80:83], v[80:81], off
	v_mul_f32_e32 v68, v76, v96
	v_cvt_pk_bf16_f32 v68, v68, v68
	v_add_u32_e32 v76, v84, v139
	ds_write_b16_d16_hi v76, v68
	v_mul_f32_e32 v68, v72, v96
	v_cvt_pk_bf16_f32 v68, v68, v68
	v_add_u32_e32 v72, v84, v138
	v_mul_f32_e32 v69, v69, v97
	ds_write_b16_d16_hi v72, v68
	v_add_u32_e32 v68, 0x6200, v136
	v_cvt_pk_bf16_f32 v69, v69, v69
	v_add_u32_e32 v72, v68, v141
	v_mul_f32_e32 v65, v65, v97
	ds_write_b16_d16_hi v72, v69
	v_cvt_pk_bf16_f32 v65, v65, v65
	v_add_u32_e32 v69, v68, v140
	ds_write_b16_d16_hi v69, v65
	v_mul_f32_e32 v65, v77, v97
	v_cvt_pk_bf16_f32 v65, v65, v65
	v_add_u32_e32 v69, v68, v139
	ds_write_b16_d16_hi v69, v65
	v_mul_f32_e32 v65, v73, v97
	v_cvt_pk_bf16_f32 v65, v65, v65
	v_add_u32_e32 v68, v68, v138
	ds_write_b16_d16_hi v68, v65
	v_mul_f32_e32 v68, v70, v98
	v_add_u32_e32 v65, 0x6400, v136
	v_cvt_pk_bf16_f32 v68, v68, v68
	v_add_u32_e32 v69, v65, v141
	v_mul_f32_e32 v66, v66, v98
	ds_write_b16_d16_hi v69, v68
	v_cvt_pk_bf16_f32 v66, v66, v66
	v_add_u32_e32 v68, v65, v140
	ds_write_b16_d16_hi v68, v66
	v_mul_f32_e32 v66, v78, v98
	v_cvt_pk_bf16_f32 v66, v66, v66
	v_add_u32_e32 v68, v65, v139
	ds_write_b16_d16_hi v68, v66
	v_mul_f32_e32 v66, v74, v98
	v_cvt_pk_bf16_f32 v66, v66, v66
	v_add_u32_e32 v65, v65, v138
	ds_write_b16_d16_hi v65, v66
	v_mul_f32_e32 v66, v71, v99
	v_add_u32_e32 v65, 0x6600, v136
	v_cvt_pk_bf16_f32 v66, v66, v66
	v_add_u32_e32 v68, v65, v141
	ds_write_b16_d16_hi v68, v66
	v_mul_f32_e32 v66, v67, v99
	v_cvt_pk_bf16_f32 v66, v66, v66
	v_add_u32_e32 v67, v65, v140
	ds_write_b16_d16_hi v67, v66
	v_mul_f32_e32 v66, v79, v99
	v_cvt_pk_bf16_f32 v66, v66, v66
	v_add_u32_e32 v67, v65, v139
	ds_write_b16_d16_hi v67, v66
	v_mul_f32_e32 v66, v75, v99
	v_bfe_u32 v67, v66, 16, 1
	v_add_u32_e32 v69, 0x90, v142
	v_add3_u32 v66, v66, v67, s85
	v_add_u32_e32 v65, v65, v138
	v_lshl_add_u32 v68, v64, 9, v137
	v_add_u32_e32 v64, s52, v69
	ds_write_b16_d16_hi v65, v66
	v_ashrrev_i32_e32 v65, 31, v64
	v_lshl_add_u64 v[64:65], v[64:65], 2, s[0:1]
	global_load_dwordx4 v[64:67], v[64:65], off
	s_waitcnt vmcnt(1)
	v_mul_f32_e32 v52, v52, v80
	v_cvt_pk_bf16_f32 v52, v52, v52
	v_add_u32_e32 v70, v68, v141
	v_mul_f32_e32 v48, v48, v80
	ds_write_b16_d16_hi v70, v52
	v_cvt_pk_bf16_f32 v48, v48, v48
	v_add_u32_e32 v52, v68, v140
	ds_write_b16_d16_hi v52, v48
	v_mul_f32_e32 v48, v60, v80
	v_cvt_pk_bf16_f32 v48, v48, v48
	v_add_u32_e32 v52, v68, v139
	ds_write_b16_d16_hi v52, v48
	v_mul_f32_e32 v48, v56, v80
	v_cvt_pk_bf16_f32 v48, v48, v48
	v_add_u32_e32 v52, v68, v138
	ds_write_b16_d16_hi v52, v48
	v_mul_f32_e32 v52, v53, v81
	v_add_u32_e32 v48, 0x10200, v136
	v_cvt_pk_bf16_f32 v52, v52, v52
	v_add_u32_e32 v53, v48, v141
	v_mul_f32_e32 v49, v49, v81
	ds_write_b16_d16_hi v53, v52
	v_cvt_pk_bf16_f32 v49, v49, v49
	v_add_u32_e32 v52, v48, v140
	ds_write_b16_d16_hi v52, v49
	v_mul_f32_e32 v49, v61, v81
	v_cvt_pk_bf16_f32 v49, v49, v49
	v_add_u32_e32 v52, v48, v139
	ds_write_b16_d16_hi v52, v49
	v_mul_f32_e32 v49, v57, v81
	v_cvt_pk_bf16_f32 v49, v49, v49
	v_add_u32_e32 v48, v48, v138
	ds_write_b16_d16_hi v48, v49
	v_mul_f32_e32 v49, v54, v82
	v_add_u32_e32 v48, 0x10400, v136
	v_cvt_pk_bf16_f32 v49, v49, v49
	v_add_u32_e32 v52, v48, v141
	ds_write_b16_d16_hi v52, v49
	v_mul_f32_e32 v49, v50, v82
	v_cvt_pk_bf16_f32 v49, v49, v49
	v_add_u32_e32 v50, v48, v140
	ds_write_b16_d16_hi v50, v49
	v_mul_f32_e32 v49, v62, v82
	v_cvt_pk_bf16_f32 v49, v49, v49
	v_add_u32_e32 v50, v48, v139
	ds_write_b16_d16_hi v50, v49
	v_mul_f32_e32 v49, v58, v82
	v_cvt_pk_bf16_f32 v49, v49, v49
	v_add_u32_e32 v48, v48, v138
	ds_write_b16_d16_hi v48, v49
	v_mul_f32_e32 v49, v55, v83
	v_add_u32_e32 v48, 0x10600, v136
	v_cvt_pk_bf16_f32 v49, v49, v49
	v_add_u32_e32 v50, v48, v141
	ds_write_b16_d16_hi v50, v49
	v_mul_f32_e32 v49, v51, v83
	v_cvt_pk_bf16_f32 v49, v49, v49
	v_add_u32_e32 v50, v48, v140
	ds_write_b16_d16_hi v50, v49
	v_mul_f32_e32 v49, v63, v83
	v_cvt_pk_bf16_f32 v49, v49, v49
	v_add_u32_e32 v50, v48, v139
	ds_write_b16_d16_hi v50, v49
	v_mul_f32_e32 v49, v59, v83
	v_bfe_u32 v50, v49, 16, 1
	v_add3_u32 v49, v49, v50, s85
	v_add_u32_e32 v48, v48, v138
	s_waitcnt vmcnt(0)
; __device__ __forceinline__ u16 f2bf(float f) { unsigned u = __float_as_uint(f); u += 0x7fffu + ((u >> 16) & 1u); return (u16)(u >> 16); }
; __device__ __forceinline__ float frcp(float x) { return __builtin_amdgcn_rcpf(x); }
; template <int EPI> ...
;     ...
;           const int r = ai * 128 + wr * 64 + m * 16 + fq * 4 + j;
;           float rs = 1.0f;
;           if (EPI != EPI_RES) rs = e.rstd[brow + r];
;           char* rowp = tb + r * RB + fr * 2;
;           if (EPI == EPI_GU) {
; #pragma unroll
;             for (int n = 0; n < 2; ++n) {
;               float g = acc[ai][0][m][n][j] * rs, u = acc[ai][1][m][n][j] * rs;
;               float h = g * frcp(1.0f + __expf(-g)) * u;
;               const int seg = (wc * 2 + n) ^ fq;
;               *(u16*)(rowp + seg * 32) = f2bf(h);
;             }
;           } else {
; #pragma unroll
;             for (int bj = 0; bj < 2; ++bj)
; #pragma unroll
;               for (int n = 0; n < 2; ++n) {
;                 const int seg = (bj * 8 + wc * 2 + n) ^ fq;
;                 *(u16*)(rowp + seg * 32) = f2bf(acc[ai][bj][m][n][j] * rs);
;               }
;           }
;         }
;     __syncthreads();
	v_mul_f32_e32 v36, v36, v64
	ds_write_b16_d16_hi v48, v49
	v_lshl_add_u32 v52, v69, 9, v137
	v_cvt_pk_bf16_f32 v36, v36, v36
	v_add_u32_e32 v48, v52, v141
	v_mul_f32_e32 v32, v32, v64
	ds_write_b16_d16_hi v48, v36
	v_cvt_pk_bf16_f32 v32, v32, v32
	v_add_u32_e32 v36, v52, v140
	ds_write_b16_d16_hi v36, v32
	v_add_u32_e32 v32, 0xa0, v142
	v_add_u32_e32 v48, s52, v32
	v_ashrrev_i32_e32 v49, 31, v48
	v_lshl_add_u64 v[48:49], v[48:49], 2, s[0:1]
	global_load_dwordx4 v[48:51], v[48:49], off
	v_mul_f32_e32 v36, v44, v64
	v_cvt_pk_bf16_f32 v36, v36, v36
	v_add_u32_e32 v44, v52, v139
	ds_write_b16_d16_hi v44, v36
	v_mul_f32_e32 v36, v40, v64
	v_cvt_pk_bf16_f32 v36, v36, v36
	v_add_u32_e32 v40, v52, v138
	v_mul_f32_e32 v37, v37, v65
	ds_write_b16_d16_hi v40, v36
	v_add_u32_e32 v36, 0x12200, v136
	v_cvt_pk_bf16_f32 v37, v37, v37
	v_add_u32_e32 v40, v36, v141
	v_mul_f32_e32 v33, v33, v65
	ds_write_b16_d16_hi v40, v37
	v_cvt_pk_bf16_f32 v33, v33, v33
	v_add_u32_e32 v37, v36, v140
	ds_write_b16_d16_hi v37, v33
	v_mul_f32_e32 v33, v45, v65
	v_cvt_pk_bf16_f32 v33, v33, v33
	v_add_u32_e32 v37, v36, v139
	ds_write_b16_d16_hi v37, v33
	v_mul_f32_e32 v33, v41, v65
	v_cvt_pk_bf16_f32 v33, v33, v33
	v_add_u32_e32 v36, v36, v138
	ds_write_b16_d16_hi v36, v33
	v_mul_f32_e32 v36, v38, v66
	v_add_u32_e32 v33, 0x12400, v136
	v_cvt_pk_bf16_f32 v36, v36, v36
	v_add_u32_e32 v37, v33, v141
	v_mul_f32_e32 v34, v34, v66
	ds_write_b16_d16_hi v37, v36
	v_cvt_pk_bf16_f32 v34, v34, v34
	v_add_u32_e32 v36, v33, v140
	ds_write_b16_d16_hi v36, v34
	v_mul_f32_e32 v34, v46, v66
	v_cvt_pk_bf16_f32 v34, v34, v34
	v_add_u32_e32 v36, v33, v139
	ds_write_b16_d16_hi v36, v34
	v_mul_f32_e32 v34, v42, v66
	v_cvt_pk_bf16_f32 v34, v34, v34
	v_add_u32_e32 v33, v33, v138
	ds_write_b16_d16_hi v33, v34
	v_mul_f32_e32 v34, v39, v67
	v_add_u32_e32 v33, 0x12600, v136
	v_cvt_pk_bf16_f32 v34, v34, v34
	v_add_u32_e32 v36, v33, v141
	ds_write_b16_d16_hi v36, v34
	v_mul_f32_e32 v34, v35, v67
	v_cvt_pk_bf16_f32 v34, v34, v34
	v_add_u32_e32 v35, v33, v140
	ds_write_b16_d16_hi v35, v34
	v_mul_f32_e32 v34, v47, v67
	v_cvt_pk_bf16_f32 v34, v34, v34
	v_add_u32_e32 v35, v33, v139
	ds_write_b16_d16_hi v35, v34
	v_mul_f32_e32 v34, v43, v67
	v_bfe_u32 v35, v34, 16, 1
	v_add_u32_e32 v37, 0xb0, v142
	v_add3_u32 v34, v34, v35, s85
	v_add_u32_e32 v33, v33, v138
	v_lshl_add_u32 v36, v32, 9, v137
	v_add_u32_e32 v32, s52, v37
	ds_write_b16_d16_hi v33, v34
	v_ashrrev_i32_e32 v33, 31, v32
	v_lshl_add_u64 v[32:33], v[32:33], 2, s[0:1]
	global_load_dwordx4 v[32:35], v[32:33], off
	s_waitcnt vmcnt(1)
	v_mul_f32_e32 v20, v20, v48
	v_cvt_pk_bf16_f32 v20, v20, v20
	v_add_u32_e32 v38, v36, v141
	v_mul_f32_e32 v16, v16, v48
	ds_write_b16_d16_hi v38, v20
	v_cvt_pk_bf16_f32 v16, v16, v16
	v_add_u32_e32 v20, v36, v140
	ds_write_b16_d16_hi v20, v16
	v_mul_f32_e32 v16, v28, v48
	v_cvt_pk_bf16_f32 v16, v16, v16
	v_add_u32_e32 v20, v36, v139
	ds_write_b16_d16_hi v20, v16
	v_mul_f32_e32 v16, v24, v48
	v_cvt_pk_bf16_f32 v16, v16, v16
	v_add_u32_e32 v20, v36, v138
	ds_write_b16_d16_hi v20, v16
	v_mul_f32_e32 v20, v21, v49
	v_add_u32_e32 v16, 0x14200, v136
	v_cvt_pk_bf16_f32 v20, v20, v20
	v_add_u32_e32 v21, v16, v141
	v_mul_f32_e32 v17, v17, v49
	ds_write_b16_d16_hi v21, v20
	v_cvt_pk_bf16_f32 v17, v17, v17
	v_add_u32_e32 v20, v16, v140
	ds_write_b16_d16_hi v20, v17
	v_mul_f32_e32 v17, v29, v49
	v_cvt_pk_bf16_f32 v17, v17, v17
	v_add_u32_e32 v20, v16, v139
	ds_write_b16_d16_hi v20, v17
	v_mul_f32_e32 v17, v25, v49
	v_cvt_pk_bf16_f32 v17, v17, v17
	v_add_u32_e32 v16, v16, v138
	ds_write_b16_d16_hi v16, v17
	v_mul_f32_e32 v17, v22, v50
	v_add_u32_e32 v16, 0x14400, v136
	v_cvt_pk_bf16_f32 v17, v17, v17
	v_add_u32_e32 v20, v16, v141
	ds_write_b16_d16_hi v20, v17
	v_mul_f32_e32 v17, v18, v50
	v_cvt_pk_bf16_f32 v17, v17, v17
	v_add_u32_e32 v18, v16, v140
	ds_write_b16_d16_hi v18, v17
	v_mul_f32_e32 v17, v30, v50
	v_cvt_pk_bf16_f32 v17, v17, v17
	v_add_u32_e32 v18, v16, v139
	ds_write_b16_d16_hi v18, v17
	v_mul_f32_e32 v17, v26, v50
	v_cvt_pk_bf16_f32 v17, v17, v17
	v_add_u32_e32 v16, v16, v138
	ds_write_b16_d16_hi v16, v17
	v_mul_f32_e32 v17, v23, v51
	v_add_u32_e32 v16, 0x14600, v136
	v_cvt_pk_bf16_f32 v17, v17, v17
	v_add_u32_e32 v18, v16, v141
	ds_write_b16_d16_hi v18, v17
	v_mul_f32_e32 v17, v19, v51
	v_cvt_pk_bf16_f32 v17, v17, v17
	v_add_u32_e32 v18, v16, v140
	ds_write_b16_d16_hi v18, v17
	v_mul_f32_e32 v17, v31, v51
	v_cvt_pk_bf16_f32 v17, v17, v17
	v_add_u32_e32 v18, v16, v139
	ds_write_b16_d16_hi v18, v17
	v_mul_f32_e32 v17, v27, v51
	v_bfe_u32 v18, v17, 16, 1
	v_add3_u32 v17, v17, v18, s85
	v_add_u32_e32 v16, v16, v138
	s_waitcnt vmcnt(0)
	v_mul_f32_e32 v4, v4, v32
	ds_write_b16_d16_hi v16, v17
	v_lshl_add_u32 v16, v37, 9, v137
	v_cvt_pk_bf16_f32 v4, v4, v4
	v_add_u32_e32 v17, v16, v141
	v_mul_f32_e32 v0, v0, v32
	ds_write_b16_d16_hi v17, v4
	v_cvt_pk_bf16_f32 v0, v0, v0
	v_add_u32_e32 v4, v16, v140
	ds_write_b16_d16_hi v4, v0
	v_mul_f32_e32 v0, v12, v32
	v_cvt_pk_bf16_f32 v0, v0, v0
	v_add_u32_e32 v4, v16, v139
	ds_write_b16_d16_hi v4, v0
	v_mul_f32_e32 v0, v8, v32
	v_cvt_pk_bf16_f32 v0, v0, v0
	v_add_u32_e32 v4, v16, v138
	ds_write_b16_d16_hi v4, v0
	v_mul_f32_e32 v4, v5, v33
	v_add_u32_e32 v0, 0x16200, v136
	v_cvt_pk_bf16_f32 v4, v4, v4
	v_add_u32_e32 v5, v0, v141
	v_mul_f32_e32 v1, v1, v33
	ds_write_b16_d16_hi v5, v4
	v_cvt_pk_bf16_f32 v1, v1, v1
	v_add_u32_e32 v4, v0, v140
	ds_write_b16_d16_hi v4, v1
	v_mul_f32_e32 v1, v13, v33
	v_cvt_pk_bf16_f32 v1, v1, v1
	v_add_u32_e32 v4, v0, v139
	ds_write_b16_d16_hi v4, v1
	v_mul_f32_e32 v1, v9, v33
	v_cvt_pk_bf16_f32 v1, v1, v1
	v_add_u32_e32 v0, v0, v138
	ds_write_b16_d16_hi v0, v1
	v_mul_f32_e32 v1, v6, v34
	v_add_u32_e32 v0, 0x16400, v136
	v_cvt_pk_bf16_f32 v1, v1, v1
	v_add_u32_e32 v4, v0, v141
	ds_write_b16_d16_hi v4, v1
	v_mul_f32_e32 v1, v2, v34
	v_cvt_pk_bf16_f32 v1, v1, v1
	v_add_u32_e32 v2, v0, v140
	ds_write_b16_d16_hi v2, v1
	v_mul_f32_e32 v1, v14, v34
	v_cvt_pk_bf16_f32 v1, v1, v1
	v_add_u32_e32 v2, v0, v139
	ds_write_b16_d16_hi v2, v1
	v_mul_f32_e32 v1, v10, v34
	v_cvt_pk_bf16_f32 v1, v1, v1
	v_add_u32_e32 v0, v0, v138
	ds_write_b16_d16_hi v0, v1
	v_mul_f32_e32 v1, v7, v35
	v_add_u32_e32 v0, 0x16600, v136
	v_cvt_pk_bf16_f32 v1, v1, v1
	v_add_u32_e32 v2, v0, v141
	ds_write_b16_d16_hi v2, v1
	v_mul_f32_e32 v1, v3, v35
	v_cvt_pk_bf16_f32 v1, v1, v1
	v_add_u32_e32 v2, v0, v140
	ds_write_b16_d16_hi v2, v1
	v_mul_f32_e32 v1, v15, v35
	v_cvt_pk_bf16_f32 v1, v1, v1
	v_add_u32_e32 v2, v0, v139
	ds_write_b16_d16_hi v2, v1
	v_mul_f32_e32 v1, v11, v35
	v_cvt_pk_bf16_f32 v1, v1, v1
	v_add_u32_e32 v0, v0, v138
	ds_write_b16_d16_hi v0, v1
	s_waitcnt lgkmcnt(0)
	s_barrier
; __device__ __forceinline__ int opaque_tid() { int t; asm volatile("v_mov_b32 %0, %1" : "=v"(t) : "v"((int)threadIdx.x)); return t; }
; template <int EPI> ...
;     ...
;     constexpr int CPR = RB / 16;
;     constexpr int RPI = 512 / CPR;
;     const int tid2 = opaque_tid();
;     const int cc = tid2 % CPR, r0 = tid2 / CPR;
;     u16* gp = (EPI == EPI_GU) ? e.out + ((size_t)((e.bcol >> 6) + (cc >> 3)) * 256 + r0) * 64 + (cc & 7) * 8
;                               : e.out + (size_t)r0 * e.ld + e.bcol + cc * 8;
;     const size_t gstep = (EPI == EPI_GU) ? (size_t)RPI * 64 : (size_t)RPI * e.ld;
; #pragma unroll 4
;     for (int it = 0; it < 256 / RPI; ++it) {
;       const int r = r0 + it * RPI;
;       const int pc = cc ^ (((r >> 2) & 3) << 1);
	v_mov_b32 v0, v146
	s_nop 0
	v_ashrrev_i32_e32 v1, 31, v0
	v_lshrrev_b32_e32 v1, 27, v1
	v_add_u32_e32 v1, v0, v1
	v_ashrrev_i32_e32 v4, 5, v1
	v_and_b32_e32 v1, 0xffffffe0, v1
	v_sub_u32_e32 v5, v0, v1
	v_mov_b64_e32 v[0:1], s[56:57]
	v_mad_i64_i32 v[0:1], s[52:53], v4, s83, v[0:1]
	v_lshlrev_b32_e32 v2, 3, v5
	v_lshl_add_u64 v[0:1], s[54:55], 1, v[0:1]
	v_ashrrev_i32_e32 v3, 31, v2
	v_lshl_add_u64 v[0:1], v[2:3], 1, v[0:1]
	v_lshrrev_b32_e32 v2, 1, v4
	v_bitop3_b32 v2, v2, v5, 6 bitop3:0x6c
	v_lshlrev_b32_e32 v3, 9, v4
	v_lshlrev_b32_e32 v2, 4, v2
	v_add3_u32 v2, 0, v3, v2
	s_mov_b32 s52, 0

; __device__ __forceinline__ int opaque_tid() { int t; asm volatile("v_mov_b32 %0, %1" : "=v"(t) : "v"((int)threadIdx.x)); return t; }
; #define STAGE(P, BASE, kt) do { const char* _g = (const char*)(BASE) + (size_t)((kt) * (BK * 2)); \
;     __builtin_amdgcn_global_load_lds((const unsigned*)(_g + (size_t)goff0), (unsigned*)((char*)(P) + tid_ * 16), 16, 0, 0); \
;     __builtin_amdgcn_global_load_lds((const unsigned*)(_g + (size_t)goff1), (unsigned*)((char*)(P) + tid_ * 16 + 8192), 16, 0, 0); } while (0)
; #define STAGEA(P, BASE, kt) do { const char* _g = (const char*)(BASE) + (size_t)((kt) * a_kbytes); \
;     __builtin_amdgcn_global_load_lds((const unsigned*)(_g + (size_t)goffA0), (unsigned*)((char*)(P) + tid_ * 16), 16, 0, 0); \
;     __builtin_amdgcn_global_load_lds((const unsigned*)(_g + (size_t)goffA1), (unsigned*)((char*)(P) + tid_ * 16 + 8192), 16, 0, 0); } while (0)
; #define WAIT_V(n) asm volatile("s_waitcnt vmcnt(" #n ")" ::: "memory")
; #define BAR __builtin_amdgcn_s_barrier()
; template <int EPI> ...
;     ...
;   const int tid_ = opaque_tid();
;   const int wid = tid_ >> 6, lane = tid_ & 63, wr = wid >> 2, wc = wid & 3, fr = lane & 15, fq = lane >> 4;
;   f32x4 acc[2][2][4][2] = {};
;   bf16x8 At[4][2], B0[2][2], B1[2][2];
;   const int nt = K / BK;
;   STAGE(SB(0, 0), B0p, 0); STAGEA(SA(0, 0), A0, 0);
;   STAGE(SB(0, 1), B1p, 0); STAGEA(SA(0, 1), A1, 0);
;   if (wr == 1) BAR;
;   WAIT_V(4); BAR;
;   STAGE(SB(1, 0), B0p, 1); STAGEA(SA(1, 0), A0, 1); STAGE(SB(1, 1), B1p, 1);
;   WAIT_V(6); BAR;
;   for (int t = 0; t < nt - 2; t += 2) {
.LBB0_855:
	s_or_b64 exec, exec, s[60:61]
	v_add_u32_e32 v164, s67, v8
	v_add_u32_e32 v165, 0x2000, v164
	v_readfirstlane_b32 s49, v164
	v_lshl_add_u64 v[0:1], v[0:1], 0, s[4:5]
	s_mov_b32 m0, s49
	v_readfirstlane_b32 s49, v165
	v_add_u32_e32 v166, 0x8000, v158
	s_waitcnt vmcnt(4)
	s_barrier
	global_load_lds_dwordx4 v[0:1], off
	v_lshl_add_u64 v[0:1], v[2:3], 0, s[4:5]
	s_mov_b32 m0, s49
	v_readfirstlane_b32 s49, v166
	v_add_u32_e32 v167, 0xa000, v158
	global_load_lds_dwordx4 v[0:1], off
	v_lshl_add_u64 v[0:1], v[4:5], 0, s[4:5]
	s_mov_b32 m0, s49
	v_readfirstlane_b32 s49, v167
	s_add_u32 s58, s58, 0x80080
	v_add_u32_e32 v169, s77, v8
	global_load_lds_dwordx4 v[0:1], off
	v_lshl_add_u64 v[0:1], v[6:7], 0, s[4:5]
	s_mov_b32 m0, s49
	s_addc_u32 s59, s59, 0
	v_readfirstlane_b32 s49, v169
	v_add_u32_e32 v170, 0x2000, v169
	global_load_lds_dwordx4 v[0:1], off
	v_lshl_add_u64 v[0:1], s[58:59], 0, v[130:131]
	s_mov_b32 m0, s49
	v_readfirstlane_b32 s49, v170
	global_load_lds_dwordx4 v[0:1], off
	v_lshl_add_u64 v[0:1], s[58:59], 0, v[128:129]
	s_mov_b32 m0, s49
	v_and_b32_e32 v148, 15, v144
	global_load_lds_dwordx4 v[0:1], off
	v_bfe_u32 v145, v144, 4, 2
	v_lshlrev_b32_e32 v3, 2, v144
	v_lshlrev_b32_e32 v0, 4, v145
	v_lshlrev_b32_e32 v2, 6, v148
	v_and_b32_e32 v3, 32, v3
	v_lshlrev_b32_e32 v149, 6, v9
	v_lshlrev_b32_e32 v8, 13, v9
	v_lshlrev_b32_e32 v9, 6, v144
	v_lshl_add_u64 v[136:137], v[132:133], 0, s[56:57]
	v_lshl_add_u64 v[138:139], v[134:135], 0, s[56:57]
	s_add_i32 s56, s85, s86
	v_bfe_u32 v147, v144, 6, 2
	s_waitcnt vmcnt(6)
	v_bitop3_b32 v2, v0, v3, v2 bitop3:0x36
	v_and_or_b32 v0, v9, s80, v0
	s_ashr_i32 s57, s56, 31
	v_lshlrev_b32_e32 v1, 12, v147
	v_add_u32_e32 v4, s65, v2
	v_add_u32_e32 v5, s66, v2
	v_add_u32_e32 v6, s67, v2
	v_add_u32_e32 v7, s77, v2
	v_add_u32_e32 v2, 0, v2
	v_xad_u32 v3, v0, v3, 0
	v_or_b32_e32 v9, 0x800, v8
	v_or_b32_e32 v10, 0x1000, v8
	v_or_b32_e32 v11, 0x1800, v8
	s_lshl_b64 s[56:57], s[56:57], 12
	v_mov_b32_e32 v0, 0
	v_lshl_add_u64 v[140:141], v[132:133], 0, s[56:57]
	v_lshl_add_u64 v[142:143], v[134:135], 0, s[56:57]
	s_mov_b32 s49, -2
	v_add_u32_e32 v171, v4, v1
	v_add_u32_e32 v153, v2, v8
	v_add_u32_e32 v152, v3, v9
	v_add_u32_e32 v151, v3, v10
	v_add_u32_e32 v150, v3, v11
	v_add_u32_e32 v168, v5, v1
	v_add_u32_e32 v157, v6, v1
	v_add_u32_e32 v154, v7, v1
	s_mov_b64 s[56:57], s[74:75]
	v_mov_b32_e32 v1, v0
	v_mov_b32_e32 v2, v0
	v_mov_b32_e32 v3, v0
	v_mov_b32_e32 v4, v0
	v_mov_b32_e32 v5, v0
	v_mov_b32_e32 v6, v0
	v_mov_b32_e32 v7, v0
	v_mov_b32_e32 v8, v0
	v_mov_b32_e32 v9, v0
	v_mov_b32_e32 v10, v0
	v_mov_b32_e32 v11, v0
	v_mov_b32_e32 v12, v0
	v_mov_b32_e32 v13, v0
	v_mov_b32_e32 v14, v0
	v_mov_b32_e32 v15, v0
	v_mov_b32_e32 v16, v0
	v_mov_b32_e32 v17, v0
	v_mov_b32_e32 v18, v0
	v_mov_b32_e32 v19, v0
	v_mov_b32_e32 v20, v0
	v_mov_b32_e32 v21, v0
	v_mov_b32_e32 v22, v0
	v_mov_b32_e32 v23, v0
	v_mov_b32_e32 v24, v0
	v_mov_b32_e32 v25, v0
	v_mov_b32_e32 v26, v0
	v_mov_b32_e32 v27, v0
	v_mov_b32_e32 v28, v0
	v_mov_b32_e32 v29, v0
	v_mov_b32_e32 v30, v0
	v_mov_b32_e32 v31, v0
	v_mov_b32_e32 v32, v0
	v_mov_b32_e32 v33, v0
	v_mov_b32_e32 v34, v0
	v_mov_b32_e32 v35, v0
	v_mov_b32_e32 v36, v0
	v_mov_b32_e32 v37, v0
	v_mov_b32_e32 v38, v0
	v_mov_b32_e32 v39, v0
	v_mov_b32_e32 v40, v0
	v_mov_b32_e32 v41, v0
	v_mov_b32_e32 v42, v0
	v_mov_b32_e32 v43, v0
	v_mov_b32_e32 v44, v0
	v_mov_b32_e32 v45, v0
	v_mov_b32_e32 v46, v0
	v_mov_b32_e32 v47, v0
	v_mov_b32_e32 v48, v0
	v_mov_b32_e32 v49, v0
	v_mov_b32_e32 v50, v0
	v_mov_b32_e32 v51, v0
	v_mov_b32_e32 v52, v0
	v_mov_b32_e32 v53, v0
	v_mov_b32_e32 v54, v0
	v_mov_b32_e32 v55, v0
	v_mov_b32_e32 v56, v0
	v_mov_b32_e32 v57, v0
	v_mov_b32_e32 v58, v0
	v_mov_b32_e32 v59, v0
	v_mov_b32_e32 v60, v0
	v_mov_b32_e32 v61, v0
	v_mov_b32_e32 v62, v0
	v_mov_b32_e32 v63, v0
	v_mov_b32_e32 v64, v0
	v_mov_b32_e32 v65, v0
	v_mov_b32_e32 v66, v0
	v_mov_b32_e32 v67, v0
	v_mov_b32_e32 v68, v0
	v_mov_b32_e32 v69, v0
	v_mov_b32_e32 v70, v0
	v_mov_b32_e32 v71, v0
	v_mov_b32_e32 v72, v0
	v_mov_b32_e32 v73, v0
	v_mov_b32_e32 v74, v0
	v_mov_b32_e32 v75, v0
	v_mov_b32_e32 v76, v0
	v_mov_b32_e32 v77, v0
	v_mov_b32_e32 v78, v0
	v_mov_b32_e32 v79, v0
	v_mov_b32_e32 v80, v0
	v_mov_b32_e32 v81, v0
	v_mov_b32_e32 v82, v0
	v_mov_b32_e32 v83, v0
	v_mov_b32_e32 v84, v0
	v_mov_b32_e32 v85, v0
	v_mov_b32_e32 v86, v0
	v_mov_b32_e32 v87, v0
	v_mov_b32_e32 v88, v0
	v_mov_b32_e32 v89, v0
	v_mov_b32_e32 v90, v0
	v_mov_b32_e32 v91, v0
	v_mov_b32_e32 v92, v0
	v_mov_b32_e32 v93, v0
	v_mov_b32_e32 v94, v0
	v_mov_b32_e32 v95, v0
	v_mov_b32_e32 v96, v0
	v_mov_b32_e32 v97, v0
	v_mov_b32_e32 v98, v0
	v_mov_b32_e32 v99, v0
	v_mov_b32_e32 v100, v0
	v_mov_b32_e32 v101, v0
	v_mov_b32_e32 v102, v0
	v_mov_b32_e32 v103, v0
	v_mov_b32_e32 v104, v0
	v_mov_b32_e32 v105, v0
	v_mov_b32_e32 v106, v0
	v_mov_b32_e32 v107, v0
	v_mov_b32_e32 v108, v0
	v_mov_b32_e32 v109, v0
	v_mov_b32_e32 v110, v0
	v_mov_b32_e32 v111, v0
	v_mov_b32_e32 v112, v0
	v_mov_b32_e32 v113, v0
	v_mov_b32_e32 v114, v0
	v_mov_b32_e32 v115, v0
	v_mov_b32_e32 v116, v0
	v_mov_b32_e32 v117, v0
	v_mov_b32_e32 v118, v0
	v_mov_b32_e32 v119, v0
	v_mov_b32_e32 v120, v0
	v_mov_b32_e32 v121, v0
	v_mov_b32_e32 v122, v0
	v_mov_b32_e32 v123, v0
	v_mov_b32_e32 v124, v0
	v_mov_b32_e32 v125, v0
	v_mov_b32_e32 v126, v0
	v_mov_b32_e32 v127, v0
	s_barrier
	ds_read_b128 v[174:177], v171
	ds_read_b128 v[178:181], v171 offset:1024
	ds_read_b128 v[182:185], v171 offset:2048
	ds_read_b128 v[186:189], v171 offset:3072
; #define STAGE(P, BASE, kt) do { const char* _g = (const char*)(BASE) + (size_t)((kt) * (BK * 2)); \
;     __builtin_amdgcn_global_load_lds((const unsigned*)(_g + (size_t)goff0), (unsigned*)((char*)(P) + tid_ * 16), 16, 0, 0); \
;     __builtin_amdgcn_global_load_lds((const unsigned*)(_g + (size_t)goff1), (unsigned*)((char*)(P) + tid_ * 16 + 8192), 16, 0, 0); } while (0)
; #define STAGEA(P, BASE, kt) do { const char* _g = (const char*)(BASE) + (size_t)((kt) * a_kbytes); \
;     __builtin_amdgcn_global_load_lds((const unsigned*)(_g + (size_t)goffA0), (unsigned*)((char*)(P) + tid_ * 16), 16, 0, 0); \
;     __builtin_amdgcn_global_load_lds((const unsigned*)(_g + (size_t)goffA1), (unsigned*)((char*)(P) + tid_ * 16 + 8192), 16, 0, 0); } while (0)
; #define LDA(dst, b, h) for (int m = 0; m < 4; ++m) for (int k = 0; k < 2; ++k) \
;     dst[m][k] = *reinterpret_cast<const bf16x8*>((char*)SA(b, h) + lds_byte(wr * 64 + m * 16 + fr, k * 32 + fq * 8))
; #define LDB(dst, b, h) for (int n = 0; n < 2; ++n) for (int k = 0; k < 2; ++k) \
;     dst[n][k] = *reinterpret_cast<const bf16x8*>((char*)SB(b, h) + lds_byte(wc * 32 + n * 16 + fr, k * 32 + fq * 8))
; #define MMA(ai, bj, At, Bt) do { __builtin_amdgcn_s_setprio(1); \
;     for (int m = 0; m < 4; ++m) for (int n = 0; n < 2; ++n) for (int k = 0; k < 2; ++k) \
;       acc[ai][bj][m][n] = __builtin_amdgcn_mfma_f32_16x16x32_bf16(At[m][k], Bt[n][k], acc[ai][bj][m][n], 0, 0, 0); \
;     __builtin_amdgcn_s_setprio(0); } while (0)
; #define WAIT_V(n) asm volatile("s_waitcnt vmcnt(" #n ")" ::: "memory")
; #define WAIT_L(n) asm volatile("s_waitcnt lgkmcnt(" #n ")" ::: "memory")
; #define BAR __builtin_amdgcn_s_barrier()
; #define SCHED __builtin_amdgcn_sched_barrier(0)
; template <int EPI> ...
;     ...
;     LDB(B0, 0, 0); SCHED; LDA(At, 0, 0); STAGEA(SA(1, 1), A1, t + 1);
;     WAIT_L(8); BAR; WAIT_L(0); MMA(0, 0, At, B0); BAR; SCHED;
;     LDB(B1, 0, 1); STAGE(SB(0, 0), B0p, t + 2);
;     BAR; WAIT_L(0); MMA(0, 1, At, B1); BAR;
;     LDA(At, 0, 1); STAGEA(SA(0, 0), A0, t + 2);
;     BAR; WAIT_L(0); MMA(1, 0, At, B0); BAR; SCHED;
;     STAGE(SB(0, 1), B1p, t + 2);
;     WAIT_V(6); BAR; MMA(1, 1, At, B1); BAR;
.LBB0_856:
	v_add_u32_e32 v172, 0xc000, v158
	v_lshl_add_u64 v[238:239], s[56:57], 0, v[140:141]
	v_readfirstlane_b32 s53, v172
	v_add_u32_e32 v173, 0xe000, v158
	v_lshl_add_u64 v[222:223], v[238:239], 0, s[6:7]
	s_mov_b32 m0, s53
	v_lshl_add_u64 v[240:241], s[56:57], 0, v[142:143]
	v_readfirstlane_b32 s53, v173
	ds_read_b128 v[190:193], v153
	ds_read_b128 v[194:197], v153 offset:1024
	ds_read_b128 v[198:201], v152
	ds_read_b128 v[202:205], v152 offset:1024
	ds_read_b128 v[206:209], v151
	ds_read_b128 v[210:213], v151 offset:1024
	ds_read_b128 v[214:217], v150
	ds_read_b128 v[218:221], v150 offset:1024
	global_load_lds_dwordx4 v[222:223], off
	v_lshl_add_u64 v[222:223], v[240:241], 0, s[6:7]
	s_mov_b32 m0, s53
	s_nop 0
	global_load_lds_dwordx4 v[222:223], off
	s_waitcnt lgkmcnt(8)
	s_setprio 1
	s_barrier
	s_waitcnt lgkmcnt(0)
	v_mfma_f32_16x16x32_bf16 v[124:127], v[190:193], v[174:177], v[124:127]
	v_mfma_f32_16x16x32_bf16 v[120:123], v[190:193], v[182:185], v[120:123]
	v_mfma_f32_16x16x32_bf16 v[116:119], v[198:201], v[174:177], v[116:119]
	v_mfma_f32_16x16x32_bf16 v[112:115], v[198:201], v[182:185], v[112:115]
	v_mfma_f32_16x16x32_bf16 v[108:111], v[206:209], v[174:177], v[108:111]
	v_mfma_f32_16x16x32_bf16 v[104:107], v[206:209], v[182:185], v[104:107]
	v_mfma_f32_16x16x32_bf16 v[100:103], v[214:217], v[174:177], v[100:103]
	v_mfma_f32_16x16x32_bf16 v[96:99], v[214:217], v[182:185], v[96:99]
	v_mfma_f32_16x16x32_bf16 v[124:127], v[194:197], v[178:181], v[124:127]
	v_mfma_f32_16x16x32_bf16 v[120:123], v[194:197], v[186:189], v[120:123]
	v_mfma_f32_16x16x32_bf16 v[116:119], v[202:205], v[178:181], v[116:119]
	v_mfma_f32_16x16x32_bf16 v[112:115], v[202:205], v[186:189], v[112:115]
	v_mfma_f32_16x16x32_bf16 v[108:111], v[210:213], v[178:181], v[108:111]
	v_mfma_f32_16x16x32_bf16 v[104:107], v[210:213], v[186:189], v[104:107]
	v_mfma_f32_16x16x32_bf16 v[100:103], v[218:221], v[178:181], v[100:103]
	v_mfma_f32_16x16x32_bf16 v[96:99], v[218:221], v[186:189], v[96:99]
	s_barrier
	s_setprio 0
	v_lshl_add_u64 v[242:243], s[56:57], 0, v[136:137]
	v_readfirstlane_b32 s53, v155
	v_lshl_add_u64 v[244:245], v[242:243], 0, s[8:9]
	s_mov_b32 m0, s53
	ds_read_b128 v[222:225], v168
	ds_read_b128 v[226:229], v168 offset:1024
	ds_read_b128 v[230:233], v168 offset:2048
	ds_read_b128 v[234:237], v168 offset:3072
	global_load_lds_dwordx4 v[244:245], off
	v_lshl_add_u64 v[244:245], s[56:57], 0, v[138:139]
	v_readfirstlane_b32 s53, v156
	v_lshl_add_u64 v[246:247], v[244:245], 0, s[8:9]
	s_mov_b32 m0, s53
	s_nop 0
	global_load_lds_dwordx4 v[246:247], off
	s_setprio 1
	s_barrier
	s_waitcnt lgkmcnt(0)
	v_mfma_f32_16x16x32_bf16 v[92:95], v[190:193], v[222:225], v[92:95]
	v_mfma_f32_16x16x32_bf16 v[88:91], v[190:193], v[230:233], v[88:91]
	v_mfma_f32_16x16x32_bf16 v[84:87], v[198:201], v[222:225], v[84:87]
	v_mfma_f32_16x16x32_bf16 v[80:83], v[198:201], v[230:233], v[80:83]
	v_mfma_f32_16x16x32_bf16 v[76:79], v[206:209], v[222:225], v[76:79]
	v_mfma_f32_16x16x32_bf16 v[72:75], v[206:209], v[230:233], v[72:75]
	v_mfma_f32_16x16x32_bf16 v[68:71], v[214:217], v[222:225], v[68:71]
	v_mfma_f32_16x16x32_bf16 v[64:67], v[214:217], v[230:233], v[64:67]
	v_mfma_f32_16x16x32_bf16 v[92:95], v[194:197], v[226:229], v[92:95]
	v_mfma_f32_16x16x32_bf16 v[88:91], v[194:197], v[234:237], v[88:91]
	v_mfma_f32_16x16x32_bf16 v[84:87], v[202:205], v[226:229], v[84:87]
	v_mfma_f32_16x16x32_bf16 v[80:83], v[202:205], v[234:237], v[80:83]
	v_mfma_f32_16x16x32_bf16 v[76:79], v[210:213], v[226:229], v[76:79]
	v_mfma_f32_16x16x32_bf16 v[72:75], v[210:213], v[234:237], v[72:75]
	v_mfma_f32_16x16x32_bf16 v[68:71], v[218:221], v[226:229], v[68:71]
	v_mfma_f32_16x16x32_bf16 v[64:67], v[218:221], v[234:237], v[64:67]
	s_barrier
	s_setprio 0
	v_readfirstlane_b32 s53, v158
	v_lshl_add_u64 v[246:247], v[238:239], 0, s[10:11]
	s_mov_b32 m0, s53
	v_readfirstlane_b32 s53, v159
	ds_read_b128 v[190:193], v153 offset:16384
	ds_read_b128 v[194:197], v153 offset:17408
	ds_read_b128 v[198:201], v152 offset:16384
	ds_read_b128 v[202:205], v152 offset:17408
	ds_read_b128 v[206:209], v151 offset:16384
	ds_read_b128 v[210:213], v151 offset:17408
	ds_read_b128 v[214:217], v150 offset:16384
	ds_read_b128 v[218:221], v150 offset:17408
	global_load_lds_dwordx4 v[246:247], off
	v_lshl_add_u64 v[246:247], v[240:241], 0, s[10:11]
	s_mov_b32 m0, s53
	s_nop 0
	global_load_lds_dwordx4 v[246:247], off
	s_setprio 1
	s_barrier
	s_waitcnt lgkmcnt(0)
	v_mfma_f32_16x16x32_bf16 v[60:63], v[190:193], v[174:177], v[60:63]
	v_mfma_f32_16x16x32_bf16 v[56:59], v[190:193], v[182:185], v[56:59]
	v_mfma_f32_16x16x32_bf16 v[52:55], v[198:201], v[174:177], v[52:55]
	v_mfma_f32_16x16x32_bf16 v[48:51], v[198:201], v[182:185], v[48:51]
	v_mfma_f32_16x16x32_bf16 v[44:47], v[206:209], v[174:177], v[44:47]
	v_mfma_f32_16x16x32_bf16 v[40:43], v[206:209], v[182:185], v[40:43]
	v_mfma_f32_16x16x32_bf16 v[36:39], v[214:217], v[174:177], v[36:39]
	v_mfma_f32_16x16x32_bf16 v[32:35], v[214:217], v[182:185], v[32:35]
	v_mfma_f32_16x16x32_bf16 v[60:63], v[194:197], v[178:181], v[60:63]
	v_mfma_f32_16x16x32_bf16 v[56:59], v[194:197], v[186:189], v[56:59]
	v_mfma_f32_16x16x32_bf16 v[52:55], v[202:205], v[178:181], v[52:55]
	v_mfma_f32_16x16x32_bf16 v[48:51], v[202:205], v[186:189], v[48:51]
	v_mfma_f32_16x16x32_bf16 v[44:47], v[210:213], v[178:181], v[44:47]
	v_mfma_f32_16x16x32_bf16 v[40:43], v[210:213], v[186:189], v[40:43]
	v_mfma_f32_16x16x32_bf16 v[36:39], v[218:221], v[178:181], v[36:39]
	v_mfma_f32_16x16x32_bf16 v[32:35], v[218:221], v[186:189], v[32:35]
	s_barrier
; #define STAGE(P, BASE, kt) do { const char* _g = (const char*)(BASE) + (size_t)((kt) * (BK * 2)); \
;     __builtin_amdgcn_global_load_lds((const unsigned*)(_g + (size_t)goff0), (unsigned*)((char*)(P) + tid_ * 16), 16, 0, 0); \
;     __builtin_amdgcn_global_load_lds((const unsigned*)(_g + (size_t)goff1), (unsigned*)((char*)(P) + tid_ * 16 + 8192), 16, 0, 0); } while (0)
; #define STAGEA(P, BASE, kt) do { const char* _g = (const char*)(BASE) + (size_t)((kt) * a_kbytes); \
;     __builtin_amdgcn_global_load_lds((const unsigned*)(_g + (size_t)goffA0), (unsigned*)((char*)(P) + tid_ * 16), 16, 0, 0); \
;     __builtin_amdgcn_global_load_lds((const unsigned*)(_g + (size_t)goffA1), (unsigned*)((char*)(P) + tid_ * 16 + 8192), 16, 0, 0); } while (0)
; #define LDA(dst, b, h) for (int m = 0; m < 4; ++m) for (int k = 0; k < 2; ++k) \
;     dst[m][k] = *reinterpret_cast<const bf16x8*>((char*)SA(b, h) + lds_byte(wr * 64 + m * 16 + fr, k * 32 + fq * 8))
; #define LDB(dst, b, h) for (int n = 0; n < 2; ++n) for (int k = 0; k < 2; ++k) \
;     dst[n][k] = *reinterpret_cast<const bf16x8*>((char*)SB(b, h) + lds_byte(wc * 32 + n * 16 + fr, k * 32 + fq * 8))
; #define MMA(ai, bj, At, Bt) do { __builtin_amdgcn_s_setprio(1); \
;     for (int m = 0; m < 4; ++m) for (int n = 0; n < 2; ++n) for (int k = 0; k < 2; ++k) \
;       acc[ai][bj][m][n] = __builtin_amdgcn_mfma_f32_16x16x32_bf16(At[m][k], Bt[n][k], acc[ai][bj][m][n], 0, 0, 0); \
;     __builtin_amdgcn_s_setprio(0); } while (0)
; #define WAIT_V(n) asm volatile("s_waitcnt vmcnt(" #n ")" ::: "memory")
; #define WAIT_L(n) asm volatile("s_waitcnt lgkmcnt(" #n ")" ::: "memory")
; #define BAR __builtin_amdgcn_s_barrier()
; #define SCHED __builtin_amdgcn_sched_barrier(0)
; template <int EPI> ...
;     ...
;     STAGE(SB(0, 1), B1p, t + 2);
;     WAIT_V(6); BAR; MMA(1, 1, At, B1); BAR;
;     LDB(B0, 1, 0); SCHED; LDA(At, 1, 0); STAGEA(SA(0, 1), A1, t + 2);
;     WAIT_L(8); BAR; WAIT_L(0); MMA(0, 0, At, B0); BAR; SCHED;
;     LDB(B1, 1, 1); STAGE(SB(1, 0), B0p, t + 3);
;     BAR; WAIT_L(0); MMA(0, 1, At, B1); BAR;
;     LDA(At, 1, 1); STAGEA(SA(1, 0), A0, t + 3);
;     BAR; WAIT_L(0); MMA(1, 0, At, B0); BAR; SCHED;
	s_setprio 0
	v_readfirstlane_b32 s53, v160
	v_lshl_add_u64 v[174:175], v[242:243], 0, s[12:13]
	s_mov_b32 m0, s53
	v_readfirstlane_b32 s53, v161
	global_load_lds_dwordx4 v[174:175], off
	v_lshl_add_u64 v[174:175], v[244:245], 0, s[12:13]
	s_mov_b32 m0, s53
	s_nop 0
	global_load_lds_dwordx4 v[174:175], off
	s_waitcnt vmcnt(6)
	s_setprio 1
	s_barrier
	v_mfma_f32_16x16x32_bf16 v[28:31], v[190:193], v[222:225], v[28:31]
	v_mfma_f32_16x16x32_bf16 v[24:27], v[190:193], v[230:233], v[24:27]
	v_mfma_f32_16x16x32_bf16 v[20:23], v[198:201], v[222:225], v[20:23]
	v_mfma_f32_16x16x32_bf16 v[16:19], v[198:201], v[230:233], v[16:19]
	ds_read_b128 v[174:177], v157
	v_mfma_f32_16x16x32_bf16 v[12:15], v[206:209], v[222:225], v[12:15]
	v_mfma_f32_16x16x32_bf16 v[8:11], v[206:209], v[230:233], v[8:11]
	ds_read_b128 v[178:181], v157 offset:1024
	v_mfma_f32_16x16x32_bf16 v[4:7], v[214:217], v[222:225], v[4:7]
	v_mfma_f32_16x16x32_bf16 v[0:3], v[214:217], v[230:233], v[0:3]
	ds_read_b128 v[182:185], v157 offset:2048
	v_mfma_f32_16x16x32_bf16 v[28:31], v[194:197], v[226:229], v[28:31]
	v_mfma_f32_16x16x32_bf16 v[24:27], v[194:197], v[234:237], v[24:27]
	ds_read_b128 v[186:189], v157 offset:3072
	v_mfma_f32_16x16x32_bf16 v[20:23], v[202:205], v[226:229], v[20:23]
	v_mfma_f32_16x16x32_bf16 v[16:19], v[202:205], v[234:237], v[16:19]
	v_mfma_f32_16x16x32_bf16 v[12:15], v[210:213], v[226:229], v[12:15]
	v_mfma_f32_16x16x32_bf16 v[8:11], v[210:213], v[234:237], v[8:11]
	v_mfma_f32_16x16x32_bf16 v[4:7], v[218:221], v[226:229], v[4:7]
	v_mfma_f32_16x16x32_bf16 v[0:3], v[218:221], v[234:237], v[0:3]
	s_barrier
	s_setprio 0
	v_readfirstlane_b32 s53, v162
	v_lshl_add_u64 v[222:223], v[238:239], 0, s[14:15]
	s_mov_b32 m0, s53
	v_readfirstlane_b32 s53, v163
	ds_read_b128 v[190:193], v153 offset:32768
	ds_read_b128 v[194:197], v153 offset:33792
	ds_read_b128 v[198:201], v152 offset:32768
	ds_read_b128 v[202:205], v152 offset:33792
	ds_read_b128 v[206:209], v151 offset:32768
	ds_read_b128 v[210:213], v151 offset:33792
	ds_read_b128 v[214:217], v150 offset:32768
	ds_read_b128 v[218:221], v150 offset:33792
	global_load_lds_dwordx4 v[222:223], off
	v_lshl_add_u64 v[222:223], v[240:241], 0, s[14:15]
	s_mov_b32 m0, s53
	s_nop 0
	global_load_lds_dwordx4 v[222:223], off
	s_waitcnt lgkmcnt(8)
	s_setprio 1
	s_barrier
	s_waitcnt lgkmcnt(0)
	v_mfma_f32_16x16x32_bf16 v[124:127], v[190:193], v[174:177], v[124:127]
	v_mfma_f32_16x16x32_bf16 v[120:123], v[190:193], v[182:185], v[120:123]
	v_mfma_f32_16x16x32_bf16 v[116:119], v[198:201], v[174:177], v[116:119]
	v_mfma_f32_16x16x32_bf16 v[112:115], v[198:201], v[182:185], v[112:115]
	v_mfma_f32_16x16x32_bf16 v[108:111], v[206:209], v[174:177], v[108:111]
	v_mfma_f32_16x16x32_bf16 v[104:107], v[206:209], v[182:185], v[104:107]
	v_mfma_f32_16x16x32_bf16 v[100:103], v[214:217], v[174:177], v[100:103]
	v_mfma_f32_16x16x32_bf16 v[96:99], v[214:217], v[182:185], v[96:99]
	v_mfma_f32_16x16x32_bf16 v[124:127], v[194:197], v[178:181], v[124:127]
	v_mfma_f32_16x16x32_bf16 v[120:123], v[194:197], v[186:189], v[120:123]
	v_mfma_f32_16x16x32_bf16 v[116:119], v[202:205], v[178:181], v[116:119]
	v_mfma_f32_16x16x32_bf16 v[112:115], v[202:205], v[186:189], v[112:115]
	v_mfma_f32_16x16x32_bf16 v[108:111], v[210:213], v[178:181], v[108:111]
	v_mfma_f32_16x16x32_bf16 v[104:107], v[210:213], v[186:189], v[104:107]
	v_mfma_f32_16x16x32_bf16 v[100:103], v[218:221], v[178:181], v[100:103]
	v_mfma_f32_16x16x32_bf16 v[96:99], v[218:221], v[186:189], v[96:99]
	s_barrier
	s_setprio 0
	v_readfirstlane_b32 s53, v164
	v_lshl_add_u64 v[246:247], v[242:243], 0, s[24:25]
	s_mov_b32 m0, s53
	v_readfirstlane_b32 s53, v165
	ds_read_b128 v[222:225], v154
	ds_read_b128 v[226:229], v154 offset:1024
	ds_read_b128 v[230:233], v154 offset:2048
	ds_read_b128 v[234:237], v154 offset:3072
	global_load_lds_dwordx4 v[246:247], off
	v_lshl_add_u64 v[246:247], v[244:245], 0, s[24:25]
	s_mov_b32 m0, s53
	s_nop 0
	global_load_lds_dwordx4 v[246:247], off
	s_setprio 1
	s_barrier
	s_waitcnt lgkmcnt(0)
	v_mfma_f32_16x16x32_bf16 v[92:95], v[190:193], v[222:225], v[92:95]
	v_mfma_f32_16x16x32_bf16 v[88:91], v[190:193], v[230:233], v[88:91]
	v_mfma_f32_16x16x32_bf16 v[84:87], v[198:201], v[222:225], v[84:87]
	v_mfma_f32_16x16x32_bf16 v[80:83], v[198:201], v[230:233], v[80:83]
	v_mfma_f32_16x16x32_bf16 v[76:79], v[206:209], v[222:225], v[76:79]
	v_mfma_f32_16x16x32_bf16 v[72:75], v[206:209], v[230:233], v[72:75]
	v_mfma_f32_16x16x32_bf16 v[68:71], v[214:217], v[222:225], v[68:71]
	v_mfma_f32_16x16x32_bf16 v[64:67], v[214:217], v[230:233], v[64:67]
	v_mfma_f32_16x16x32_bf16 v[92:95], v[194:197], v[226:229], v[92:95]
	v_mfma_f32_16x16x32_bf16 v[88:91], v[194:197], v[234:237], v[88:91]
	v_mfma_f32_16x16x32_bf16 v[84:87], v[202:205], v[226:229], v[84:87]
	v_mfma_f32_16x16x32_bf16 v[80:83], v[202:205], v[234:237], v[80:83]
	v_mfma_f32_16x16x32_bf16 v[76:79], v[210:213], v[226:229], v[76:79]
	v_mfma_f32_16x16x32_bf16 v[72:75], v[210:213], v[234:237], v[72:75]
	v_mfma_f32_16x16x32_bf16 v[68:71], v[218:221], v[226:229], v[68:71]
	v_mfma_f32_16x16x32_bf16 v[64:67], v[218:221], v[234:237], v[64:67]
	s_barrier
	s_setprio 0
	v_readfirstlane_b32 s53, v166
	v_lshl_add_u64 v[238:239], v[238:239], 0, s[36:37]
	s_mov_b32 m0, s53
	v_readfirstlane_b32 s53, v167
	ds_read_b128 v[190:193], v153 offset:49152
	ds_read_b128 v[194:197], v153 offset:50176
	ds_read_b128 v[198:201], v152 offset:49152
	ds_read_b128 v[202:205], v152 offset:50176
	ds_read_b128 v[206:209], v151 offset:49152
	ds_read_b128 v[210:213], v151 offset:50176
	ds_read_b128 v[214:217], v150 offset:49152
	ds_read_b128 v[218:221], v150 offset:50176
	global_load_lds_dwordx4 v[238:239], off
	v_lshl_add_u64 v[238:239], v[240:241], 0, s[36:37]
	s_mov_b32 m0, s53
	s_nop 0
	global_load_lds_dwordx4 v[238:239], off
	s_setprio 1
	s_barrier
; #define STAGE(P, BASE, kt) do { const char* _g = (const char*)(BASE) + (size_t)((kt) * (BK * 2)); \
;     __builtin_amdgcn_global_load_lds((const unsigned*)(_g + (size_t)goff0), (unsigned*)((char*)(P) + tid_ * 16), 16, 0, 0); \
;     __builtin_amdgcn_global_load_lds((const unsigned*)(_g + (size_t)goff1), (unsigned*)((char*)(P) + tid_ * 16 + 8192), 16, 0, 0); } while (0)
; #define STAGEA(P, BASE, kt) do { const char* _g = (const char*)(BASE) + (size_t)((kt) * a_kbytes); \
;     __builtin_amdgcn_global_load_lds((const unsigned*)(_g + (size_t)goffA0), (unsigned*)((char*)(P) + tid_ * 16), 16, 0, 0); \
;     __builtin_amdgcn_global_load_lds((const unsigned*)(_g + (size_t)goffA1), (unsigned*)((char*)(P) + tid_ * 16 + 8192), 16, 0, 0); } while (0)
; #define LDA(dst, b, h) for (int m = 0; m < 4; ++m) for (int k = 0; k < 2; ++k) \
;     dst[m][k] = *reinterpret_cast<const bf16x8*>((char*)SA(b, h) + lds_byte(wr * 64 + m * 16 + fr, k * 32 + fq * 8))
; #define LDB(dst, b, h) for (int n = 0; n < 2; ++n) for (int k = 0; k < 2; ++k) \
;     dst[n][k] = *reinterpret_cast<const bf16x8*>((char*)SB(b, h) + lds_byte(wc * 32 + n * 16 + fr, k * 32 + fq * 8))
; #define MMA(ai, bj, At, Bt) do { __builtin_amdgcn_s_setprio(1); \
;     for (int m = 0; m < 4; ++m) for (int n = 0; n < 2; ++n) for (int k = 0; k < 2; ++k) \
;       acc[ai][bj][m][n] = __builtin_amdgcn_mfma_f32_16x16x32_bf16(At[m][k], Bt[n][k], acc[ai][bj][m][n], 0, 0, 0); \
;     __builtin_amdgcn_s_setprio(0); } while (0)
; #define WAIT_V(n) asm volatile("s_waitcnt vmcnt(" #n ")" ::: "memory")
; #define WAIT_L(n) asm volatile("s_waitcnt lgkmcnt(" #n ")" ::: "memory")
; #define BAR __builtin_amdgcn_s_barrier()
; template <int EPI> ...
;     ...
;     STAGE(SB(1, 1), B1p, t + 3);
;     WAIT_V(6); BAR; MMA(1, 1, At, B1); BAR;
;   }
;   { LDB(B0, 0, 0); LDA(At, 0, 0); STAGEA(SA(1, 1), A1, nt - 1);
;     BAR; WAIT_L(0); MMA(0, 0, At, B0); BAR;
;     LDB(B1, 0, 1); BAR; WAIT_L(0); MMA(0, 1, At, B1); BAR;
	s_waitcnt lgkmcnt(0)
	v_mfma_f32_16x16x32_bf16 v[60:63], v[190:193], v[174:177], v[60:63]
	v_mfma_f32_16x16x32_bf16 v[56:59], v[190:193], v[182:185], v[56:59]
	v_mfma_f32_16x16x32_bf16 v[52:55], v[198:201], v[174:177], v[52:55]
	v_mfma_f32_16x16x32_bf16 v[48:51], v[198:201], v[182:185], v[48:51]
	v_mfma_f32_16x16x32_bf16 v[44:47], v[206:209], v[174:177], v[44:47]
	v_mfma_f32_16x16x32_bf16 v[40:43], v[206:209], v[182:185], v[40:43]
	v_mfma_f32_16x16x32_bf16 v[36:39], v[214:217], v[174:177], v[36:39]
	v_mfma_f32_16x16x32_bf16 v[32:35], v[214:217], v[182:185], v[32:35]
	v_mfma_f32_16x16x32_bf16 v[60:63], v[194:197], v[178:181], v[60:63]
	v_mfma_f32_16x16x32_bf16 v[56:59], v[194:197], v[186:189], v[56:59]
	v_mfma_f32_16x16x32_bf16 v[52:55], v[202:205], v[178:181], v[52:55]
	v_mfma_f32_16x16x32_bf16 v[48:51], v[202:205], v[186:189], v[48:51]
	v_mfma_f32_16x16x32_bf16 v[44:47], v[210:213], v[178:181], v[44:47]
	v_mfma_f32_16x16x32_bf16 v[40:43], v[210:213], v[186:189], v[40:43]
	v_mfma_f32_16x16x32_bf16 v[36:39], v[218:221], v[178:181], v[36:39]
	v_mfma_f32_16x16x32_bf16 v[32:35], v[218:221], v[186:189], v[32:35]
	s_barrier
	s_setprio 0
	v_readfirstlane_b32 s53, v169
	v_lshl_add_u64 v[174:175], v[242:243], 0, s[42:43]
	s_mov_b32 m0, s53
	v_readfirstlane_b32 s53, v170
	global_load_lds_dwordx4 v[174:175], off
	v_lshl_add_u64 v[174:175], v[244:245], 0, s[42:43]
	s_mov_b32 m0, s53
	s_nop 0
	global_load_lds_dwordx4 v[174:175], off
	s_waitcnt vmcnt(6)
	s_setprio 1
	s_barrier
	v_mfma_f32_16x16x32_bf16 v[28:31], v[190:193], v[222:225], v[28:31]
	v_mfma_f32_16x16x32_bf16 v[24:27], v[190:193], v[230:233], v[24:27]
	v_mfma_f32_16x16x32_bf16 v[20:23], v[198:201], v[222:225], v[20:23]
	v_mfma_f32_16x16x32_bf16 v[16:19], v[198:201], v[230:233], v[16:19]
	ds_read_b128 v[174:177], v171
	v_mfma_f32_16x16x32_bf16 v[12:15], v[206:209], v[222:225], v[12:15]
	v_mfma_f32_16x16x32_bf16 v[8:11], v[206:209], v[230:233], v[8:11]
	ds_read_b128 v[178:181], v171 offset:1024
	v_mfma_f32_16x16x32_bf16 v[4:7], v[214:217], v[222:225], v[4:7]
	v_mfma_f32_16x16x32_bf16 v[0:3], v[214:217], v[230:233], v[0:3]
	ds_read_b128 v[182:185], v171 offset:2048
	v_mfma_f32_16x16x32_bf16 v[28:31], v[194:197], v[226:229], v[28:31]
	v_mfma_f32_16x16x32_bf16 v[24:27], v[194:197], v[234:237], v[24:27]
	ds_read_b128 v[186:189], v171 offset:3072
	v_mfma_f32_16x16x32_bf16 v[20:23], v[202:205], v[226:229], v[20:23]
	v_mfma_f32_16x16x32_bf16 v[16:19], v[202:205], v[234:237], v[16:19]
	v_mfma_f32_16x16x32_bf16 v[12:15], v[210:213], v[226:229], v[12:15]
	v_mfma_f32_16x16x32_bf16 v[8:11], v[210:213], v[234:237], v[8:11]
	v_mfma_f32_16x16x32_bf16 v[4:7], v[218:221], v[226:229], v[4:7]
	v_mfma_f32_16x16x32_bf16 v[0:3], v[218:221], v[234:237], v[0:3]
	s_barrier
	s_setprio 0
	s_add_i32 s49, s49, 2
	s_add_u32 s56, s56, 0x100
	s_addc_u32 s57, s57, 0
	s_cmp_lt_u32 s49, 28
	s_cbranch_scc1 .LBB0_856
	s_add_u32 s54, s54, 0x80f80
	s_addc_u32 s55, s55, 0
	v_readfirstlane_b32 s49, v172
	v_lshl_add_u64 v[166:167], s[54:55], 0, v[130:131]
	s_mov_b32 m0, s49
	v_readfirstlane_b32 s49, v173
	ds_read_b128 v[136:139], v171
	ds_read_b128 v[140:143], v171 offset:1024
	ds_read_b128 v[158:161], v171 offset:2048
	ds_read_b128 v[162:165], v171 offset:3072
	ds_read_b128 v[174:177], v153
	ds_read_b128 v[178:181], v153 offset:1024
	ds_read_b128 v[182:185], v152
	ds_read_b128 v[186:189], v152 offset:1024
	ds_read_b128 v[190:193], v151
	ds_read_b128 v[194:197], v151 offset:1024
	ds_read_b128 v[198:201], v150
	ds_read_b128 v[202:205], v150 offset:1024
	global_load_lds_dwordx4 v[166:167], off
	v_lshl_add_u64 v[166:167], s[54:55], 0, v[128:129]
	s_mov_b32 m0, s49
	s_nop 0
	global_load_lds_dwordx4 v[166:167], off
	s_setprio 1
	s_barrier
	s_waitcnt lgkmcnt(0)
	v_mfma_f32_16x16x32_bf16 v[124:127], v[174:177], v[136:139], v[124:127]
	v_mfma_f32_16x16x32_bf16 v[120:123], v[174:177], v[158:161], v[120:123]
	v_mfma_f32_16x16x32_bf16 v[108:111], v[190:193], v[136:139], v[108:111]
	v_mfma_f32_16x16x32_bf16 v[104:107], v[190:193], v[158:161], v[104:107]
	v_mfma_f32_16x16x32_bf16 v[124:127], v[178:181], v[140:143], v[124:127]
	v_mfma_f32_16x16x32_bf16 v[120:123], v[178:181], v[162:165], v[120:123]
	v_mfma_f32_16x16x32_bf16 v[116:119], v[182:185], v[136:139], v[116:119]
	v_mfma_f32_16x16x32_bf16 v[112:115], v[182:185], v[158:161], v[112:115]
	v_mfma_f32_16x16x32_bf16 v[108:111], v[194:197], v[140:143], v[108:111]
	v_mfma_f32_16x16x32_bf16 v[104:107], v[194:197], v[162:165], v[104:107]
	v_mfma_f32_16x16x32_bf16 v[100:103], v[198:201], v[136:139], v[100:103]
	v_mfma_f32_16x16x32_bf16 v[96:99], v[198:201], v[158:161], v[96:99]
	v_mfma_f32_16x16x32_bf16 v[170:173], v[186:189], v[140:143], v[116:119]
	v_mfma_f32_16x16x32_bf16 v[206:209], v[186:189], v[162:165], v[112:115]
	v_mfma_f32_16x16x32_bf16 v[210:213], v[202:205], v[140:143], v[100:103]
	v_mfma_f32_16x16x32_bf16 v[214:217], v[202:205], v[162:165], v[96:99]
	s_barrier
	s_setprio 0
	s_nop 1
	ds_read_b128 v[96:99], v168
	ds_read_b128 v[100:103], v168 offset:1024
	ds_read_b128 v[112:115], v168 offset:2048
	ds_read_b128 v[116:119], v168 offset:3072
	s_setprio 1
	s_barrier
; #define STAGEA(P, BASE, kt) do { const char* _g = (const char*)(BASE) + (size_t)((kt) * a_kbytes); \
;     __builtin_amdgcn_global_load_lds((const unsigned*)(_g + (size_t)goffA0), (unsigned*)((char*)(P) + tid_ * 16), 16, 0, 0); \
;     __builtin_amdgcn_global_load_lds((const unsigned*)(_g + (size_t)goffA1), (unsigned*)((char*)(P) + tid_ * 16 + 8192), 16, 0, 0); } while (0)
; #define LDA(dst, b, h) for (int m = 0; m < 4; ++m) for (int k = 0; k < 2; ++k) \
;     dst[m][k] = *reinterpret_cast<const bf16x8*>((char*)SA(b, h) + lds_byte(wr * 64 + m * 16 + fr, k * 32 + fq * 8))
; #define LDB(dst, b, h) for (int n = 0; n < 2; ++n) for (int k = 0; k < 2; ++k) \
;     dst[n][k] = *reinterpret_cast<const bf16x8*>((char*)SB(b, h) + lds_byte(wc * 32 + n * 16 + fr, k * 32 + fq * 8))
; #define MMA(ai, bj, At, Bt) do { __builtin_amdgcn_s_setprio(1); \
;     for (int m = 0; m < 4; ++m) for (int n = 0; n < 2; ++n) for (int k = 0; k < 2; ++k) \
;       acc[ai][bj][m][n] = __builtin_amdgcn_mfma_f32_16x16x32_bf16(At[m][k], Bt[n][k], acc[ai][bj][m][n], 0, 0, 0); \
;     __builtin_amdgcn_s_setprio(0); } while (0)
; #define WAIT_V(n) asm volatile("s_waitcnt vmcnt(" #n ")" ::: "memory")
; #define WAIT_L(n) asm volatile("s_waitcnt lgkmcnt(" #n ")" ::: "memory")
; #define BAR __builtin_amdgcn_s_barrier()
; template <int EPI> ...
;     ...
;   { LDB(B0, 0, 0); LDA(At, 0, 0); STAGEA(SA(1, 1), A1, nt - 1);
;     BAR; WAIT_L(0); MMA(0, 0, At, B0); BAR;
;     LDB(B1, 0, 1); BAR; WAIT_L(0); MMA(0, 1, At, B1); BAR;
;     LDA(At, 0, 1); WAIT_V(4); BAR; WAIT_L(0); MMA(1, 0, At, B0); MMA(1, 1, At, B1); BAR; }
;   { LDB(B0, 1, 0); LDA(At, 1, 0); WAIT_V(2); BAR; WAIT_L(0); MMA(0, 0, At, B0); BAR;
;     LDB(B1, 1, 1); WAIT_V(0); BAR; WAIT_L(0); MMA(0, 1, At, B1); BAR;
;     LDA(At, 1, 1); BAR; WAIT_L(0); MMA(1, 0, At, B0); MMA(1, 1, At, B1); BAR; }
	s_waitcnt lgkmcnt(0)
	v_mfma_f32_16x16x32_bf16 v[92:95], v[174:177], v[96:99], v[92:95]
	v_mfma_f32_16x16x32_bf16 v[88:91], v[174:177], v[112:115], v[88:91]
	v_mfma_f32_16x16x32_bf16 v[76:79], v[190:193], v[96:99], v[76:79]
	v_mfma_f32_16x16x32_bf16 v[72:75], v[190:193], v[112:115], v[72:75]
	v_mfma_f32_16x16x32_bf16 v[92:95], v[178:181], v[100:103], v[92:95]
	v_mfma_f32_16x16x32_bf16 v[88:91], v[178:181], v[116:119], v[88:91]
	v_mfma_f32_16x16x32_bf16 v[84:87], v[182:185], v[96:99], v[84:87]
	v_mfma_f32_16x16x32_bf16 v[80:83], v[182:185], v[112:115], v[80:83]
	v_mfma_f32_16x16x32_bf16 v[76:79], v[194:197], v[100:103], v[76:79]
	v_mfma_f32_16x16x32_bf16 v[72:75], v[194:197], v[116:119], v[72:75]
	v_mfma_f32_16x16x32_bf16 v[68:71], v[198:201], v[96:99], v[68:71]
	v_mfma_f32_16x16x32_bf16 v[64:67], v[198:201], v[112:115], v[64:67]
	v_mfma_f32_16x16x32_bf16 v[166:169], v[186:189], v[100:103], v[84:87]
	v_mfma_f32_16x16x32_bf16 v[174:177], v[186:189], v[116:119], v[80:83]
	v_mfma_f32_16x16x32_bf16 v[178:181], v[202:205], v[100:103], v[68:71]
	v_mfma_f32_16x16x32_bf16 v[182:185], v[202:205], v[116:119], v[64:67]
	s_barrier
	s_setprio 0
	s_nop 1
	ds_read_b128 v[64:67], v153 offset:16384
	ds_read_b128 v[68:71], v153 offset:17408
	ds_read_b128 v[80:83], v152 offset:16384
	ds_read_b128 v[84:87], v152 offset:17408
	ds_read_b128 v[186:189], v151 offset:16384
	ds_read_b128 v[190:193], v151 offset:17408
	ds_read_b128 v[194:197], v150 offset:16384
	ds_read_b128 v[198:201], v150 offset:17408
	s_waitcnt vmcnt(4)
	s_setprio 1
	s_barrier
	s_waitcnt lgkmcnt(0)
	v_mfma_f32_16x16x32_bf16 v[60:63], v[64:67], v[136:139], v[60:63]
	v_mfma_f32_16x16x32_bf16 v[56:59], v[64:67], v[158:161], v[56:59]
	v_mfma_f32_16x16x32_bf16 v[44:47], v[186:189], v[136:139], v[44:47]
	v_mfma_f32_16x16x32_bf16 v[40:43], v[186:189], v[158:161], v[40:43]
	v_mfma_f32_16x16x32_bf16 v[60:63], v[68:71], v[140:143], v[60:63]
	v_mfma_f32_16x16x32_bf16 v[56:59], v[68:71], v[162:165], v[56:59]
	v_mfma_f32_16x16x32_bf16 v[52:55], v[80:83], v[136:139], v[52:55]
	v_mfma_f32_16x16x32_bf16 v[48:51], v[80:83], v[158:161], v[48:51]
	v_mfma_f32_16x16x32_bf16 v[44:47], v[190:193], v[140:143], v[44:47]
	v_mfma_f32_16x16x32_bf16 v[40:43], v[190:193], v[162:165], v[40:43]
	v_mfma_f32_16x16x32_bf16 v[36:39], v[194:197], v[136:139], v[36:39]
	v_mfma_f32_16x16x32_bf16 v[32:35], v[194:197], v[158:161], v[32:35]
	v_mfma_f32_16x16x32_bf16 v[202:205], v[84:87], v[140:143], v[52:55]
	v_mfma_f32_16x16x32_bf16 v[218:221], v[84:87], v[162:165], v[48:51]
	v_mfma_f32_16x16x32_bf16 v[136:139], v[198:201], v[140:143], v[36:39]
	v_mfma_f32_16x16x32_bf16 v[140:143], v[198:201], v[162:165], v[32:35]
	s_setprio 0
	s_setprio 1
	v_mfma_f32_16x16x32_bf16 v[28:31], v[64:67], v[96:99], v[28:31]
	v_mfma_f32_16x16x32_bf16 v[24:27], v[64:67], v[112:115], v[24:27]
	v_mfma_f32_16x16x32_bf16 v[12:15], v[186:189], v[96:99], v[12:15]
	v_mfma_f32_16x16x32_bf16 v[8:11], v[186:189], v[112:115], v[8:11]
	v_mfma_f32_16x16x32_bf16 v[28:31], v[68:71], v[100:103], v[28:31]
	v_mfma_f32_16x16x32_bf16 v[24:27], v[68:71], v[116:119], v[24:27]
	v_mfma_f32_16x16x32_bf16 v[20:23], v[80:83], v[96:99], v[20:23]
	v_mfma_f32_16x16x32_bf16 v[16:19], v[80:83], v[112:115], v[16:19]
	v_mfma_f32_16x16x32_bf16 v[12:15], v[190:193], v[100:103], v[12:15]
	v_mfma_f32_16x16x32_bf16 v[8:11], v[190:193], v[116:119], v[8:11]
	v_mfma_f32_16x16x32_bf16 v[4:7], v[194:197], v[96:99], v[4:7]
	v_mfma_f32_16x16x32_bf16 v[0:3], v[194:197], v[112:115], v[0:3]
	v_mfma_f32_16x16x32_bf16 v[158:161], v[84:87], v[100:103], v[20:23]
	v_mfma_f32_16x16x32_bf16 v[162:165], v[84:87], v[116:119], v[16:19]
	v_mfma_f32_16x16x32_bf16 v[186:189], v[198:201], v[100:103], v[4:7]
	v_mfma_f32_16x16x32_bf16 v[190:193], v[198:201], v[116:119], v[0:3]
	s_barrier
	s_setprio 0
	s_nop 1
	ds_read_b128 v[0:3], v157
	ds_read_b128 v[4:7], v157 offset:1024
	ds_read_b128 v[194:197], v157 offset:2048
	ds_read_b128 v[198:201], v157 offset:3072
	ds_read_b128 v[16:19], v153 offset:32768
	ds_read_b128 v[20:23], v153 offset:33792
	ds_read_b128 v[32:35], v152 offset:32768
	ds_read_b128 v[36:39], v152 offset:33792
	ds_read_b128 v[48:51], v151 offset:32768
	ds_read_b128 v[52:55], v151 offset:33792
	ds_read_b128 v[222:225], v150 offset:32768
	ds_read_b128 v[226:229], v150 offset:33792
	s_waitcnt vmcnt(2)
	s_setprio 1
	s_barrier
	s_waitcnt lgkmcnt(0)
	v_mfma_f32_16x16x32_bf16 v[64:67], v[16:19], v[0:3], v[124:127]
	v_mfma_f32_16x16x32_bf16 v[116:119], v[20:23], v[4:7], v[64:67]
	v_mfma_f32_16x16x32_bf16 v[64:67], v[16:19], v[194:197], v[120:123]
	v_mfma_f32_16x16x32_bf16 v[112:115], v[20:23], v[198:201], v[64:67]
	v_mfma_f32_16x16x32_bf16 v[64:67], v[32:35], v[0:3], v[170:173]
	v_mfma_f32_16x16x32_bf16 v[100:103], v[36:39], v[4:7], v[64:67]
	v_mfma_f32_16x16x32_bf16 v[64:67], v[32:35], v[194:197], v[206:209]
	v_mfma_f32_16x16x32_bf16 v[96:99], v[36:39], v[198:201], v[64:67]
	v_mfma_f32_16x16x32_bf16 v[64:67], v[48:51], v[0:3], v[108:111]
	v_mfma_f32_16x16x32_bf16 v[84:87], v[52:55], v[4:7], v[64:67]
	v_mfma_f32_16x16x32_bf16 v[64:67], v[48:51], v[194:197], v[104:107]
	v_mfma_f32_16x16x32_bf16 v[80:83], v[52:55], v[198:201], v[64:67]
	v_mfma_f32_16x16x32_bf16 v[64:67], v[222:225], v[0:3], v[210:213]
	v_mfma_f32_16x16x32_bf16 v[68:71], v[226:229], v[4:7], v[64:67]
	v_mfma_f32_16x16x32_bf16 v[64:67], v[222:225], v[194:197], v[214:217]
	v_mfma_f32_16x16x32_bf16 v[64:67], v[226:229], v[198:201], v[64:67]
	s_barrier
	s_setprio 0
	ds_read_b128 v[170:173], v154
	ds_read_b128 v[206:209], v154 offset:1024
	ds_read_b128 v[210:213], v154 offset:2048
	ds_read_b128 v[154:157], v154 offset:3072
	s_waitcnt vmcnt(0)
	s_setprio 1
	s_barrier
; #define LDA(dst, b, h) for (int m = 0; m < 4; ++m) for (int k = 0; k < 2; ++k) \
;     dst[m][k] = *reinterpret_cast<const bf16x8*>((char*)SA(b, h) + lds_byte(wr * 64 + m * 16 + fr, k * 32 + fq * 8))
; #define LDB(dst, b, h) for (int n = 0; n < 2; ++n) for (int k = 0; k < 2; ++k) \
;     dst[n][k] = *reinterpret_cast<const bf16x8*>((char*)SB(b, h) + lds_byte(wc * 32 + n * 16 + fr, k * 32 + fq * 8))
; #define MMA(ai, bj, At, Bt) do { __builtin_amdgcn_s_setprio(1); \
;     for (int m = 0; m < 4; ++m) for (int n = 0; n < 2; ++n) for (int k = 0; k < 2; ++k) \
;       acc[ai][bj][m][n] = __builtin_amdgcn_mfma_f32_16x16x32_bf16(At[m][k], Bt[n][k], acc[ai][bj][m][n], 0, 0, 0); \
;     __builtin_amdgcn_s_setprio(0); } while (0)
; #define WAIT_V(n) asm volatile("s_waitcnt vmcnt(" #n ")" ::: "memory")
; #define WAIT_L(n) asm volatile("s_waitcnt lgkmcnt(" #n ")" ::: "memory")
; #define BAR __builtin_amdgcn_s_barrier()
; template <int EPI> ...
;     ...
;   { LDB(B0, 1, 0); LDA(At, 1, 0); WAIT_V(2); BAR; WAIT_L(0); MMA(0, 0, At, B0); BAR;
;     LDB(B1, 1, 1); WAIT_V(0); BAR; WAIT_L(0); MMA(0, 1, At, B1); BAR;
;     LDA(At, 1, 1); BAR; WAIT_L(0); MMA(1, 0, At, B0); MMA(1, 1, At, B1); BAR; }
;   if (wr == 0) BAR;
;   {
;     constexpr int NC = (EPI == EPI_GU) ? 128 : 256;
;     constexpr int RB = NC * 2;
;     char* tb = (char*)shm;
; #pragma unroll
;     for (int ai = 0; ai < 2; ++ai)
; #pragma unroll
;       for (int m = 0; m < 4; ++m)
; #pragma unroll
;         for (int j = 0; j < 4; ++j) {
;           const int r = ai * 128 + wr * 64 + m * 16 + fq * 4 + j;
;           float rs = 1.0f;
;           if (EPI != EPI_RES) rs = e.rstd[brow + r];
	s_waitcnt lgkmcnt(0)
	v_mfma_f32_16x16x32_bf16 v[92:95], v[16:19], v[170:173], v[92:95]
	v_mfma_f32_16x16x32_bf16 v[16:19], v[16:19], v[210:213], v[88:91]
	v_mfma_f32_16x16x32_bf16 v[120:123], v[20:23], v[154:157], v[16:19]
	v_mfma_f32_16x16x32_bf16 v[16:19], v[32:35], v[170:173], v[166:169]
	v_mfma_f32_16x16x32_bf16 v[108:111], v[36:39], v[206:209], v[16:19]
	v_mfma_f32_16x16x32_bf16 v[16:19], v[32:35], v[210:213], v[174:177]
	v_mfma_f32_16x16x32_bf16 v[104:107], v[36:39], v[154:157], v[16:19]
	v_mfma_f32_16x16x32_bf16 v[16:19], v[48:51], v[170:173], v[76:79]
	v_mfma_f32_16x16x32_bf16 v[124:127], v[20:23], v[206:209], v[92:95]
	v_mfma_f32_16x16x32_bf16 v[92:95], v[52:55], v[206:209], v[16:19]
	v_mfma_f32_16x16x32_bf16 v[16:19], v[48:51], v[210:213], v[72:75]
	v_mfma_f32_16x16x32_bf16 v[88:91], v[52:55], v[154:157], v[16:19]
	v_mfma_f32_16x16x32_bf16 v[16:19], v[222:225], v[170:173], v[178:181]
	v_mfma_f32_16x16x32_bf16 v[76:79], v[226:229], v[206:209], v[16:19]
	v_mfma_f32_16x16x32_bf16 v[16:19], v[222:225], v[210:213], v[182:185]
	v_mfma_f32_16x16x32_bf16 v[72:75], v[226:229], v[154:157], v[16:19]
	s_barrier
	s_setprio 0
	ds_read_b128 v[166:169], v153 offset:49152
	ds_read_b128 v[174:177], v153 offset:50176
	ds_read_b128 v[178:181], v152 offset:49152
	ds_read_b128 v[182:185], v152 offset:50176
	ds_read_b128 v[214:217], v151 offset:49152
	ds_read_b128 v[222:225], v151 offset:50176
	ds_read_b128 v[226:229], v150 offset:49152
	ds_read_b128 v[150:153], v150 offset:50176
	s_setprio 1
	s_barrier
	s_waitcnt lgkmcnt(0)
	v_mfma_f32_16x16x32_bf16 v[16:19], v[166:169], v[0:3], v[60:63]
	v_mfma_f32_16x16x32_bf16 v[52:55], v[174:177], v[4:7], v[16:19]
	v_mfma_f32_16x16x32_bf16 v[16:19], v[166:169], v[194:197], v[56:59]
	v_mfma_f32_16x16x32_bf16 v[48:51], v[174:177], v[198:201], v[16:19]
	v_mfma_f32_16x16x32_bf16 v[16:19], v[178:181], v[0:3], v[202:205]
	v_mfma_f32_16x16x32_bf16 v[36:39], v[182:185], v[4:7], v[16:19]
	v_mfma_f32_16x16x32_bf16 v[16:19], v[178:181], v[194:197], v[218:221]
	v_mfma_f32_16x16x32_bf16 v[32:35], v[182:185], v[198:201], v[16:19]
	v_mfma_f32_16x16x32_bf16 v[16:19], v[214:217], v[0:3], v[44:47]
	v_mfma_f32_16x16x32_bf16 v[0:3], v[226:229], v[0:3], v[136:139]
	v_mfma_f32_16x16x32_bf16 v[20:23], v[222:225], v[4:7], v[16:19]
	v_mfma_f32_16x16x32_bf16 v[16:19], v[214:217], v[194:197], v[40:43]
	v_mfma_f32_16x16x32_bf16 v[4:7], v[150:153], v[4:7], v[0:3]
	v_mfma_f32_16x16x32_bf16 v[0:3], v[226:229], v[194:197], v[140:143]
	v_mfma_f32_16x16x32_bf16 v[16:19], v[222:225], v[198:201], v[16:19]
	v_mfma_f32_16x16x32_bf16 v[0:3], v[150:153], v[198:201], v[0:3]
	s_setprio 0
	s_setprio 1
	v_mfma_f32_16x16x32_bf16 v[24:27], v[166:169], v[210:213], v[24:27]
	v_mfma_f32_16x16x32_bf16 v[56:59], v[174:177], v[154:157], v[24:27]
	v_mfma_f32_16x16x32_bf16 v[24:27], v[178:181], v[170:173], v[158:161]
	v_mfma_f32_16x16x32_bf16 v[44:47], v[182:185], v[206:209], v[24:27]
	v_mfma_f32_16x16x32_bf16 v[24:27], v[178:181], v[210:213], v[162:165]
	v_mfma_f32_16x16x32_bf16 v[8:11], v[214:217], v[210:213], v[8:11]
	v_mfma_f32_16x16x32_bf16 v[28:31], v[166:169], v[170:173], v[28:31]
	v_mfma_f32_16x16x32_bf16 v[40:43], v[182:185], v[154:157], v[24:27]
	v_mfma_f32_16x16x32_bf16 v[12:15], v[214:217], v[170:173], v[12:15]
	v_mfma_f32_16x16x32_bf16 v[24:27], v[222:225], v[154:157], v[8:11]
	v_mfma_f32_16x16x32_bf16 v[8:11], v[226:229], v[170:173], v[186:189]
	v_mfma_f32_16x16x32_bf16 v[60:63], v[174:177], v[206:209], v[28:31]
	v_mfma_f32_16x16x32_bf16 v[28:31], v[222:225], v[206:209], v[12:15]
	v_mfma_f32_16x16x32_bf16 v[12:15], v[150:153], v[206:209], v[8:11]
	v_mfma_f32_16x16x32_bf16 v[8:11], v[226:229], v[210:213], v[190:193]
	v_mfma_f32_16x16x32_bf16 v[8:11], v[150:153], v[154:157], v[8:11]
	s_barrier
	s_setprio 0
	v_cmp_gt_u32_e32 vcc, s81, v144
	s_and_saveexec_b64 s[54:55], vcc
	s_cbranch_execz .LBB0_859
	s_barrier
.LBB0_859:
	s_or_b64 exec, exec, s[54:55]
	v_lshl_or_b32 v142, v145, 2, v149
	v_add_u32_e32 v136, s48, v142
	v_ashrrev_i32_e32 v137, 31, v136
	v_lshl_add_u64 v[136:137], v[136:137], 2, s[0:1]
	global_load_dwordx4 v[150:153], v[136:137], off
	v_lshlrev_b32_e32 v138, 1, v147
	v_or_b32_e32 v147, 16, v142
	v_add_u32_e32 v144, s48, v147
	v_bitop3_b32 v139, v138, v145, 8 bitop3:0x36
	v_xor_b32_e32 v140, v138, v145
	v_bitop3_b32 v143, v138, v145, 1 bitop3:0x36
	v_bitop3_b32 v138, v138, v145, 9 bitop3:0x36
	v_ashrrev_i32_e32 v145, 31, v144
	v_lshl_add_u64 v[144:145], v[144:145], 2, s[0:1]
	global_load_dwordx4 v[154:157], v[144:145], off
	v_lshl_add_u32 v137, v148, 1, 0
	v_lshl_add_u32 v136, v142, 9, v137
	v_lshlrev_b32_e32 v141, 5, v140
	v_lshlrev_b32_e32 v140, 5, v143
	v_lshlrev_b32_e32 v139, 5, v139
	v_lshlrev_b32_e32 v138, 5, v138
	v_add_u32_e32 v143, 0x200, v136
	v_add_u32_e32 v148, 0x400, v136
	v_add_u32_e32 v149, v136, v141
	v_add_u32_e32 v158, v136, v140
	v_add_u32_e32 v159, v136, v139
	v_add_u32_e32 v144, v136, v138
	v_add_u32_e32 v145, v143, v141
	v_add_u32_e32 v160, v143, v140
	v_add_u32_e32 v161, v143, v139
	v_add_u32_e32 v143, v143, v138
	v_add_u32_e32 v162, v148, v141
	v_add_u32_e32 v163, v148, v140
	v_add_u32_e32 v164, v148, v139
	v_add_u32_e32 v148, v148, v138
	s_mul_i32 s53, s48, 0x1c00
	s_mul_hi_i32 s49, s48, 0x1c00
	s_add_u32 s54, s72, s53
	s_addc_u32 s55, s73, s49
	s_lshl_b32 s52, s52, 8
	s_ashr_i32 s53, s52, 31
	s_waitcnt vmcnt(0)
; __device__ __forceinline__ u16 f2bf(float f) { unsigned u = __float_as_uint(f); u += 0x7fffu + ((u >> 16) & 1u); return (u16)(u >> 16); }
; __device__ __forceinline__ float frcp(float x) { return __builtin_amdgcn_rcpf(x); }
; template <int EPI> ...
;     ...
;           const int r = ai * 128 + wr * 64 + m * 16 + fq * 4 + j;
;           float rs = 1.0f;
;           if (EPI != EPI_RES) rs = e.rstd[brow + r];
;           char* rowp = tb + r * RB + fr * 2;
;           if (EPI == EPI_GU) {
; #pragma unroll
;             for (int n = 0; n < 2; ++n) {
;               float g = acc[ai][0][m][n][j] * rs, u = acc[ai][1][m][n][j] * rs;
;               float h = g * frcp(1.0f + __expf(-g)) * u;
;               const int seg = (wc * 2 + n) ^ fq;
;               *(u16*)(rowp + seg * 32) = f2bf(h);
;             }
;           } else {
; #pragma unroll
;             for (int bj = 0; bj < 2; ++bj)
; #pragma unroll
;               for (int n = 0; n < 2; ++n) {
;                 const int seg = (bj * 8 + wc * 2 + n) ^ fq;
;                 *(u16*)(rowp + seg * 32) = f2bf(acc[ai][bj][m][n][j] * rs);
;               }
	v_mul_f32_e32 v116, v116, v150
	v_mul_f32_e32 v113, v113, v151
	v_mul_f32_e32 v112, v112, v150
	v_mul_f32_e32 v124, v124, v150
	v_mul_f32_e32 v120, v120, v150
	v_mul_f32_e32 v117, v117, v151
	v_mul_f32_e32 v125, v125, v151
	v_mul_f32_e32 v121, v121, v151
	v_mul_f32_e32 v118, v118, v152
	v_mul_f32_e32 v114, v114, v152
	v_mul_f32_e32 v126, v126, v152
	v_mul_f32_e32 v122, v122, v152
	v_cvt_pk_bf16_f32 v116, v116, v116
	v_cvt_pk_bf16_f32 v113, v113, v113
	v_cvt_pk_bf16_f32 v112, v112, v112
	v_cvt_pk_bf16_f32 v124, v124, v124
	v_cvt_pk_bf16_f32 v120, v120, v120
	v_cvt_pk_bf16_f32 v117, v117, v117
	v_cvt_pk_bf16_f32 v125, v125, v125
	v_cvt_pk_bf16_f32 v121, v121, v121
	v_cvt_pk_bf16_f32 v118, v118, v118
	v_cvt_pk_bf16_f32 v114, v114, v114
	v_cvt_pk_bf16_f32 v126, v126, v126
	v_cvt_pk_bf16_f32 v122, v122, v122
	ds_write_b16_d16_hi v149, v116
	ds_write_b16_d16_hi v158, v112
	ds_write_b16_d16_hi v159, v124
	ds_write_b16_d16_hi v144, v120
	ds_write_b16_d16_hi v145, v117
	ds_write_b16_d16_hi v160, v113
	ds_write_b16_d16_hi v161, v125
	ds_write_b16_d16_hi v143, v121
	ds_write_b16_d16_hi v162, v118
	ds_write_b16_d16_hi v163, v114
	ds_write_b16_d16_hi v164, v126
	ds_write_b16_d16_hi v148, v122
	v_mul_f32_e32 v113, v119, v153
	v_add_u32_e32 v112, 0x600, v136
	v_cvt_pk_bf16_f32 v113, v113, v113
	v_add_u32_e32 v114, v112, v141
	ds_write_b16_d16_hi v114, v113
	v_mul_f32_e32 v113, v115, v153
	v_cvt_pk_bf16_f32 v113, v113, v113
	v_add_u32_e32 v114, v112, v140
	ds_write_b16_d16_hi v114, v113
	v_mul_f32_e32 v113, v127, v153
	v_cvt_pk_bf16_f32 v113, v113, v113
	v_add_u32_e32 v114, v112, v139
	ds_write_b16_d16_hi v114, v113
	v_mul_f32_e32 v113, v123, v153
	v_bfe_u32 v114, v113, 16, 1
	v_add3_u32 v113, v113, v114, s83
	v_add_u32_e32 v112, v112, v138
	v_mul_f32_e32 v100, v100, v154
	ds_write_b16_d16_hi v112, v113
	v_lshl_add_u32 v116, v147, 9, v137
	v_cvt_pk_bf16_f32 v100, v100, v100
	v_add_u32_e32 v112, v116, v141
	v_mul_f32_e32 v96, v96, v154
	ds_write_b16_d16_hi v112, v100
	v_cvt_pk_bf16_f32 v96, v96, v96
	v_add_u32_e32 v100, v116, v140
	ds_write_b16_d16_hi v100, v96
	v_or_b32_e32 v96, 32, v142
	v_add_u32_e32 v112, s48, v96
	v_ashrrev_i32_e32 v113, 31, v112
	v_lshl_add_u64 v[112:113], v[112:113], 2, s[0:1]
	global_load_dwordx4 v[112:115], v[112:113], off
	v_mul_f32_e32 v100, v108, v154
	v_cvt_pk_bf16_f32 v100, v100, v100
	v_add_u32_e32 v108, v116, v139
	ds_write_b16_d16_hi v108, v100
	v_mul_f32_e32 v100, v104, v154
	v_cvt_pk_bf16_f32 v100, v100, v100
	v_add_u32_e32 v104, v116, v138
	v_mul_f32_e32 v101, v101, v155
	ds_write_b16_d16_hi v104, v100
	v_add_u32_e32 v100, 0x2200, v136
	v_cvt_pk_bf16_f32 v101, v101, v101
	v_add_u32_e32 v104, v100, v141
	v_mul_f32_e32 v97, v97, v155
	ds_write_b16_d16_hi v104, v101
	v_cvt_pk_bf16_f32 v97, v97, v97
	v_add_u32_e32 v101, v100, v140
	ds_write_b16_d16_hi v101, v97
	v_mul_f32_e32 v97, v109, v155
	v_cvt_pk_bf16_f32 v97, v97, v97
	v_add_u32_e32 v101, v100, v139
	ds_write_b16_d16_hi v101, v97
	v_mul_f32_e32 v97, v105, v155
	v_cvt_pk_bf16_f32 v97, v97, v97
	v_add_u32_e32 v100, v100, v138
	ds_write_b16_d16_hi v100, v97
	v_mul_f32_e32 v100, v102, v156
	v_add_u32_e32 v97, 0x2400, v136
	v_cvt_pk_bf16_f32 v100, v100, v100
	v_add_u32_e32 v101, v97, v141
	v_mul_f32_e32 v98, v98, v156
	ds_write_b16_d16_hi v101, v100
	v_cvt_pk_bf16_f32 v98, v98, v98
	v_add_u32_e32 v100, v97, v140
	ds_write_b16_d16_hi v100, v98
	v_mul_f32_e32 v98, v110, v156
	v_cvt_pk_bf16_f32 v98, v98, v98
	v_add_u32_e32 v100, v97, v139
	ds_write_b16_d16_hi v100, v98
	v_mul_f32_e32 v98, v106, v156
	v_cvt_pk_bf16_f32 v98, v98, v98
	v_add_u32_e32 v97, v97, v138
	ds_write_b16_d16_hi v97, v98
	v_mul_f32_e32 v98, v103, v157
	v_add_u32_e32 v97, 0x2600, v136
	v_cvt_pk_bf16_f32 v98, v98, v98
	v_add_u32_e32 v100, v97, v141
	ds_write_b16_d16_hi v100, v98
	v_mul_f32_e32 v98, v99, v157
	v_cvt_pk_bf16_f32 v98, v98, v98
	v_add_u32_e32 v99, v97, v140
	ds_write_b16_d16_hi v99, v98
	v_mul_f32_e32 v98, v111, v157
	v_cvt_pk_bf16_f32 v98, v98, v98
	v_add_u32_e32 v99, v97, v139
	ds_write_b16_d16_hi v99, v98
	v_mul_f32_e32 v98, v107, v157
	v_bfe_u32 v99, v98, 16, 1
	v_or_b32_e32 v101, 48, v142
	v_add3_u32 v98, v98, v99, s83
	v_add_u32_e32 v97, v97, v138
	v_lshl_add_u32 v100, v96, 9, v137
	v_add_u32_e32 v96, s48, v101
	ds_write_b16_d16_hi v97, v98
	v_ashrrev_i32_e32 v97, 31, v96
	v_lshl_add_u64 v[96:97], v[96:97], 2, s[0:1]
	global_load_dwordx4 v[96:99], v[96:97], off
	s_waitcnt vmcnt(1)
	v_mul_f32_e32 v84, v84, v112
	v_cvt_pk_bf16_f32 v84, v84, v84
	v_add_u32_e32 v102, v100, v141
	v_mul_f32_e32 v80, v80, v112
	ds_write_b16_d16_hi v102, v84
	v_cvt_pk_bf16_f32 v80, v80, v80
	v_add_u32_e32 v84, v100, v140
	ds_write_b16_d16_hi v84, v80
	v_mul_f32_e32 v80, v92, v112
	v_cvt_pk_bf16_f32 v80, v80, v80
	v_add_u32_e32 v84, v100, v139
	ds_write_b16_d16_hi v84, v80
	v_mul_f32_e32 v80, v88, v112
	v_cvt_pk_bf16_f32 v80, v80, v80
	v_add_u32_e32 v84, v100, v138
	ds_write_b16_d16_hi v84, v80
	v_mul_f32_e32 v84, v85, v113
	v_add_u32_e32 v80, 0x4200, v136
	v_cvt_pk_bf16_f32 v84, v84, v84
	v_add_u32_e32 v85, v80, v141
	v_mul_f32_e32 v81, v81, v113
	ds_write_b16_d16_hi v85, v84
	v_cvt_pk_bf16_f32 v81, v81, v81
	v_add_u32_e32 v84, v80, v140
	ds_write_b16_d16_hi v84, v81
	v_mul_f32_e32 v81, v93, v113
	v_cvt_pk_bf16_f32 v81, v81, v81
	v_add_u32_e32 v84, v80, v139
	ds_write_b16_d16_hi v84, v81
	v_mul_f32_e32 v81, v89, v113
	v_cvt_pk_bf16_f32 v81, v81, v81
	v_add_u32_e32 v80, v80, v138
	ds_write_b16_d16_hi v80, v81
	v_mul_f32_e32 v81, v86, v114
	v_add_u32_e32 v80, 0x4400, v136
	v_cvt_pk_bf16_f32 v81, v81, v81
	v_add_u32_e32 v84, v80, v141
	ds_write_b16_d16_hi v84, v81
	v_mul_f32_e32 v81, v82, v114
	v_cvt_pk_bf16_f32 v81, v81, v81
	v_add_u32_e32 v82, v80, v140
	ds_write_b16_d16_hi v82, v81
	v_mul_f32_e32 v81, v94, v114
	v_cvt_pk_bf16_f32 v81, v81, v81
	v_add_u32_e32 v82, v80, v139
	ds_write_b16_d16_hi v82, v81
	v_mul_f32_e32 v81, v90, v114
	v_cvt_pk_bf16_f32 v81, v81, v81
	v_add_u32_e32 v80, v80, v138
	ds_write_b16_d16_hi v80, v81
	v_mul_f32_e32 v81, v87, v115
	v_add_u32_e32 v80, 0x4600, v136
	v_cvt_pk_bf16_f32 v81, v81, v81
	v_add_u32_e32 v82, v80, v141
	ds_write_b16_d16_hi v82, v81
	v_mul_f32_e32 v81, v83, v115
	v_cvt_pk_bf16_f32 v81, v81, v81
	v_add_u32_e32 v82, v80, v140
	ds_write_b16_d16_hi v82, v81
	v_mul_f32_e32 v81, v95, v115
	v_cvt_pk_bf16_f32 v81, v81, v81
	v_add_u32_e32 v82, v80, v139
	ds_write_b16_d16_hi v82, v81
	v_mul_f32_e32 v81, v91, v115
	v_bfe_u32 v82, v81, 16, 1
	v_add3_u32 v81, v81, v82, s83
	v_add_u32_e32 v80, v80, v138
	s_waitcnt vmcnt(0)
; __device__ __forceinline__ u16 f2bf(float f) { unsigned u = __float_as_uint(f); u += 0x7fffu + ((u >> 16) & 1u); return (u16)(u >> 16); }
; __device__ __forceinline__ float frcp(float x) { return __builtin_amdgcn_rcpf(x); }
; template <int EPI> ...
;     ...
;           const int r = ai * 128 + wr * 64 + m * 16 + fq * 4 + j;
;           float rs = 1.0f;
;           if (EPI != EPI_RES) rs = e.rstd[brow + r];
;           char* rowp = tb + r * RB + fr * 2;
;           if (EPI == EPI_GU) {
; #pragma unroll
;             for (int n = 0; n < 2; ++n) {
;               float g = acc[ai][0][m][n][j] * rs, u = acc[ai][1][m][n][j] * rs;
;               float h = g * frcp(1.0f + __expf(-g)) * u;
;               const int seg = (wc * 2 + n) ^ fq;
;               *(u16*)(rowp + seg * 32) = f2bf(h);
;             }
;           } else {
; #pragma unroll
;             for (int bj = 0; bj < 2; ++bj)
; #pragma unroll
;               for (int n = 0; n < 2; ++n) {
;                 const int seg = (bj * 8 + wc * 2 + n) ^ fq;
;                 *(u16*)(rowp + seg * 32) = f2bf(acc[ai][bj][m][n][j] * rs);
;               }
	v_mul_f32_e32 v68, v68, v96
	ds_write_b16_d16_hi v80, v81
	v_lshl_add_u32 v84, v101, 9, v137
	v_cvt_pk_bf16_f32 v68, v68, v68
	v_add_u32_e32 v80, v84, v141
	v_mul_f32_e32 v64, v64, v96
	ds_write_b16_d16_hi v80, v68
	v_cvt_pk_bf16_f32 v64, v64, v64
	v_add_u32_e32 v68, v84, v140
	ds_write_b16_d16_hi v68, v64
	v_add_u32_e32 v64, 0x80, v142
	v_add_u32_e32 v80, s48, v64
	v_ashrrev_i32_e32 v81, 31, v80
	v_lshl_add_u64 v[80:81], v[80:81], 2, s[0:1]
	global_load_dwordx4 v[80:83], v[80:81], off
	v_mul_f32_e32 v68, v76, v96
	v_cvt_pk_bf16_f32 v68, v68, v68
	v_add_u32_e32 v76, v84, v139
	ds_write_b16_d16_hi v76, v68
	v_mul_f32_e32 v68, v72, v96
	v_cvt_pk_bf16_f32 v68, v68, v68
	v_add_u32_e32 v72, v84, v138
	v_mul_f32_e32 v69, v69, v97
	ds_write_b16_d16_hi v72, v68
	v_add_u32_e32 v68, 0x6200, v136
	v_cvt_pk_bf16_f32 v69, v69, v69
	v_add_u32_e32 v72, v68, v141
	v_mul_f32_e32 v65, v65, v97
	ds_write_b16_d16_hi v72, v69
	v_cvt_pk_bf16_f32 v65, v65, v65
	v_add_u32_e32 v69, v68, v140
	ds_write_b16_d16_hi v69, v65
	v_mul_f32_e32 v65, v77, v97
	v_cvt_pk_bf16_f32 v65, v65, v65
	v_add_u32_e32 v69, v68, v139
	ds_write_b16_d16_hi v69, v65
	v_mul_f32_e32 v65, v73, v97
	v_cvt_pk_bf16_f32 v65, v65, v65
	v_add_u32_e32 v68, v68, v138
	ds_write_b16_d16_hi v68, v65
	v_mul_f32_e32 v68, v70, v98
	v_add_u32_e32 v65, 0x6400, v136
	v_cvt_pk_bf16_f32 v68, v68, v68
	v_add_u32_e32 v69, v65, v141
	v_mul_f32_e32 v66, v66, v98
	ds_write_b16_d16_hi v69, v68
	v_cvt_pk_bf16_f32 v66, v66, v66
	v_add_u32_e32 v68, v65, v140
	ds_write_b16_d16_hi v68, v66
	v_mul_f32_e32 v66, v78, v98
	v_cvt_pk_bf16_f32 v66, v66, v66
	v_add_u32_e32 v68, v65, v139
	ds_write_b16_d16_hi v68, v66
	v_mul_f32_e32 v66, v74, v98
	v_cvt_pk_bf16_f32 v66, v66, v66
	v_add_u32_e32 v65, v65, v138
	ds_write_b16_d16_hi v65, v66
	v_mul_f32_e32 v66, v71, v99
	v_add_u32_e32 v65, 0x6600, v136
	v_cvt_pk_bf16_f32 v66, v66, v66
	v_add_u32_e32 v68, v65, v141
	ds_write_b16_d16_hi v68, v66
	v_mul_f32_e32 v66, v67, v99
	v_cvt_pk_bf16_f32 v66, v66, v66
	v_add_u32_e32 v67, v65, v140
	ds_write_b16_d16_hi v67, v66
	v_mul_f32_e32 v66, v79, v99
	v_cvt_pk_bf16_f32 v66, v66, v66
	v_add_u32_e32 v67, v65, v139
	ds_write_b16_d16_hi v67, v66
	v_mul_f32_e32 v66, v75, v99
	v_bfe_u32 v67, v66, 16, 1
	v_add_u32_e32 v69, 0x90, v142
	v_add3_u32 v66, v66, v67, s83
	v_add_u32_e32 v65, v65, v138
	v_lshl_add_u32 v68, v64, 9, v137
	v_add_u32_e32 v64, s48, v69
	ds_write_b16_d16_hi v65, v66
	v_ashrrev_i32_e32 v65, 31, v64
	v_lshl_add_u64 v[64:65], v[64:65], 2, s[0:1]
	global_load_dwordx4 v[64:67], v[64:65], off
	s_waitcnt vmcnt(1)
	v_mul_f32_e32 v52, v52, v80
	v_cvt_pk_bf16_f32 v52, v52, v52
	v_add_u32_e32 v70, v68, v141
	v_mul_f32_e32 v48, v48, v80
	ds_write_b16_d16_hi v70, v52
	v_cvt_pk_bf16_f32 v48, v48, v48
	v_add_u32_e32 v52, v68, v140
	ds_write_b16_d16_hi v52, v48
	v_mul_f32_e32 v48, v60, v80
	v_cvt_pk_bf16_f32 v48, v48, v48
	v_add_u32_e32 v52, v68, v139
	ds_write_b16_d16_hi v52, v48
	v_mul_f32_e32 v48, v56, v80
	v_cvt_pk_bf16_f32 v48, v48, v48
	v_add_u32_e32 v52, v68, v138
	ds_write_b16_d16_hi v52, v48
	v_mul_f32_e32 v52, v53, v81
	v_add_u32_e32 v48, 0x10200, v136
	v_cvt_pk_bf16_f32 v52, v52, v52
	v_add_u32_e32 v53, v48, v141
	v_mul_f32_e32 v49, v49, v81
	ds_write_b16_d16_hi v53, v52
	v_cvt_pk_bf16_f32 v49, v49, v49
	v_add_u32_e32 v52, v48, v140
	ds_write_b16_d16_hi v52, v49
	v_mul_f32_e32 v49, v61, v81
	v_cvt_pk_bf16_f32 v49, v49, v49
	v_add_u32_e32 v52, v48, v139
	ds_write_b16_d16_hi v52, v49
	v_mul_f32_e32 v49, v57, v81
	v_cvt_pk_bf16_f32 v49, v49, v49
	v_add_u32_e32 v48, v48, v138
	ds_write_b16_d16_hi v48, v49
	v_mul_f32_e32 v49, v54, v82
	v_add_u32_e32 v48, 0x10400, v136
	v_cvt_pk_bf16_f32 v49, v49, v49
	v_add_u32_e32 v52, v48, v141
	ds_write_b16_d16_hi v52, v49
	v_mul_f32_e32 v49, v50, v82
	v_cvt_pk_bf16_f32 v49, v49, v49
	v_add_u32_e32 v50, v48, v140
	ds_write_b16_d16_hi v50, v49
	v_mul_f32_e32 v49, v62, v82
	v_cvt_pk_bf16_f32 v49, v49, v49
	v_add_u32_e32 v50, v48, v139
	ds_write_b16_d16_hi v50, v49
	v_mul_f32_e32 v49, v58, v82
	v_cvt_pk_bf16_f32 v49, v49, v49
	v_add_u32_e32 v48, v48, v138
	ds_write_b16_d16_hi v48, v49
	v_mul_f32_e32 v49, v55, v83
	v_add_u32_e32 v48, 0x10600, v136
	v_cvt_pk_bf16_f32 v49, v49, v49
	v_add_u32_e32 v50, v48, v141
	ds_write_b16_d16_hi v50, v49
	v_mul_f32_e32 v49, v51, v83
	v_cvt_pk_bf16_f32 v49, v49, v49
	v_add_u32_e32 v50, v48, v140
	ds_write_b16_d16_hi v50, v49
	v_mul_f32_e32 v49, v63, v83
	v_cvt_pk_bf16_f32 v49, v49, v49
	v_add_u32_e32 v50, v48, v139
	ds_write_b16_d16_hi v50, v49
	v_mul_f32_e32 v49, v59, v83
	v_bfe_u32 v50, v49, 16, 1
	v_add3_u32 v49, v49, v50, s83
	v_add_u32_e32 v48, v48, v138
	s_waitcnt vmcnt(0)
; __device__ __forceinline__ u16 f2bf(float f) { unsigned u = __float_as_uint(f); u += 0x7fffu + ((u >> 16) & 1u); return (u16)(u >> 16); }
; __device__ __forceinline__ float frcp(float x) { return __builtin_amdgcn_rcpf(x); }
; template <int EPI> ...
;     ...
;           const int r = ai * 128 + wr * 64 + m * 16 + fq * 4 + j;
;           float rs = 1.0f;
;           if (EPI != EPI_RES) rs = e.rstd[brow + r];
;           char* rowp = tb + r * RB + fr * 2;
;           if (EPI == EPI_GU) {
; #pragma unroll
;             for (int n = 0; n < 2; ++n) {
;               float g = acc[ai][0][m][n][j] * rs, u = acc[ai][1][m][n][j] * rs;
;               float h = g * frcp(1.0f + __expf(-g)) * u;
;               const int seg = (wc * 2 + n) ^ fq;
;               *(u16*)(rowp + seg * 32) = f2bf(h);
;             }
;           } else {
; #pragma unroll
;             for (int bj = 0; bj < 2; ++bj)
; #pragma unroll
;               for (int n = 0; n < 2; ++n) {
;                 const int seg = (bj * 8 + wc * 2 + n) ^ fq;
;                 *(u16*)(rowp + seg * 32) = f2bf(acc[ai][bj][m][n][j] * rs);
;               }
	v_mul_f32_e32 v36, v36, v64
	ds_write_b16_d16_hi v48, v49
	v_lshl_add_u32 v52, v69, 9, v137
	v_cvt_pk_bf16_f32 v36, v36, v36
	v_add_u32_e32 v48, v52, v141
	v_mul_f32_e32 v32, v32, v64
	ds_write_b16_d16_hi v48, v36
	v_cvt_pk_bf16_f32 v32, v32, v32
	v_add_u32_e32 v36, v52, v140
	ds_write_b16_d16_hi v36, v32
	v_add_u32_e32 v32, 0xa0, v142
	v_add_u32_e32 v48, s48, v32
	v_ashrrev_i32_e32 v49, 31, v48
	v_lshl_add_u64 v[48:49], v[48:49], 2, s[0:1]
	global_load_dwordx4 v[48:51], v[48:49], off
	v_mul_f32_e32 v36, v44, v64
	v_cvt_pk_bf16_f32 v36, v36, v36
	v_add_u32_e32 v44, v52, v139
	ds_write_b16_d16_hi v44, v36
	v_mul_f32_e32 v36, v40, v64
	v_cvt_pk_bf16_f32 v36, v36, v36
	v_add_u32_e32 v40, v52, v138
	v_mul_f32_e32 v37, v37, v65
	ds_write_b16_d16_hi v40, v36
	v_add_u32_e32 v36, 0x12200, v136
	v_cvt_pk_bf16_f32 v37, v37, v37
	v_add_u32_e32 v40, v36, v141
	v_mul_f32_e32 v33, v33, v65
	ds_write_b16_d16_hi v40, v37
	v_cvt_pk_bf16_f32 v33, v33, v33
	v_add_u32_e32 v37, v36, v140
	ds_write_b16_d16_hi v37, v33
	v_mul_f32_e32 v33, v45, v65
	v_cvt_pk_bf16_f32 v33, v33, v33
	v_add_u32_e32 v37, v36, v139
	ds_write_b16_d16_hi v37, v33
	v_mul_f32_e32 v33, v41, v65
	v_cvt_pk_bf16_f32 v33, v33, v33
	v_add_u32_e32 v36, v36, v138
	ds_write_b16_d16_hi v36, v33
	v_mul_f32_e32 v36, v38, v66
	v_add_u32_e32 v33, 0x12400, v136
	v_cvt_pk_bf16_f32 v36, v36, v36
	v_add_u32_e32 v37, v33, v141
	v_mul_f32_e32 v34, v34, v66
	ds_write_b16_d16_hi v37, v36
	v_cvt_pk_bf16_f32 v34, v34, v34
	v_add_u32_e32 v36, v33, v140
	ds_write_b16_d16_hi v36, v34
	v_mul_f32_e32 v34, v46, v66
	v_cvt_pk_bf16_f32 v34, v34, v34
	v_add_u32_e32 v36, v33, v139
	ds_write_b16_d16_hi v36, v34
	v_mul_f32_e32 v34, v42, v66
	v_cvt_pk_bf16_f32 v34, v34, v34
	v_add_u32_e32 v33, v33, v138
	ds_write_b16_d16_hi v33, v34
	v_mul_f32_e32 v34, v39, v67
	v_add_u32_e32 v33, 0x12600, v136
	v_cvt_pk_bf16_f32 v34, v34, v34
	v_add_u32_e32 v36, v33, v141
	ds_write_b16_d16_hi v36, v34
	v_mul_f32_e32 v34, v35, v67
	v_cvt_pk_bf16_f32 v34, v34, v34
	v_add_u32_e32 v35, v33, v140
	ds_write_b16_d16_hi v35, v34
	v_mul_f32_e32 v34, v47, v67
	v_cvt_pk_bf16_f32 v34, v34, v34
	v_add_u32_e32 v35, v33, v139
	ds_write_b16_d16_hi v35, v34
	v_mul_f32_e32 v34, v43, v67
	v_bfe_u32 v35, v34, 16, 1
	v_add_u32_e32 v37, 0xb0, v142
	v_add3_u32 v34, v34, v35, s83
	v_add_u32_e32 v33, v33, v138
	v_lshl_add_u32 v36, v32, 9, v137
	v_add_u32_e32 v32, s48, v37
	ds_write_b16_d16_hi v33, v34
	v_ashrrev_i32_e32 v33, 31, v32
	v_lshl_add_u64 v[32:33], v[32:33], 2, s[0:1]
	global_load_dwordx4 v[32:35], v[32:33], off
	s_waitcnt vmcnt(1)
	v_mul_f32_e32 v20, v20, v48
	v_cvt_pk_bf16_f32 v20, v20, v20
	v_add_u32_e32 v38, v36, v141
	v_mul_f32_e32 v16, v16, v48
	ds_write_b16_d16_hi v38, v20
	v_cvt_pk_bf16_f32 v16, v16, v16
	v_add_u32_e32 v20, v36, v140
	ds_write_b16_d16_hi v20, v16
	v_mul_f32_e32 v16, v28, v48
	v_cvt_pk_bf16_f32 v16, v16, v16
	v_add_u32_e32 v20, v36, v139
	ds_write_b16_d16_hi v20, v16
	v_mul_f32_e32 v16, v24, v48
	v_cvt_pk_bf16_f32 v16, v16, v16
	v_add_u32_e32 v20, v36, v138
	ds_write_b16_d16_hi v20, v16
	v_mul_f32_e32 v20, v21, v49
	v_add_u32_e32 v16, 0x14200, v136
	v_cvt_pk_bf16_f32 v20, v20, v20
	v_add_u32_e32 v21, v16, v141
	v_mul_f32_e32 v17, v17, v49
	ds_write_b16_d16_hi v21, v20
	v_cvt_pk_bf16_f32 v17, v17, v17
	v_add_u32_e32 v20, v16, v140
	ds_write_b16_d16_hi v20, v17
	v_mul_f32_e32 v17, v29, v49
	v_cvt_pk_bf16_f32 v17, v17, v17
	v_add_u32_e32 v20, v16, v139
	ds_write_b16_d16_hi v20, v17
	v_mul_f32_e32 v17, v25, v49
	v_cvt_pk_bf16_f32 v17, v17, v17
	v_add_u32_e32 v16, v16, v138
	ds_write_b16_d16_hi v16, v17
	v_mul_f32_e32 v17, v22, v50
	v_add_u32_e32 v16, 0x14400, v136
	v_cvt_pk_bf16_f32 v17, v17, v17
	v_add_u32_e32 v20, v16, v141
	ds_write_b16_d16_hi v20, v17
	v_mul_f32_e32 v17, v18, v50
	v_cvt_pk_bf16_f32 v17, v17, v17
	v_add_u32_e32 v18, v16, v140
	ds_write_b16_d16_hi v18, v17
	v_mul_f32_e32 v17, v30, v50
	v_cvt_pk_bf16_f32 v17, v17, v17
	v_add_u32_e32 v18, v16, v139
	ds_write_b16_d16_hi v18, v17
	v_mul_f32_e32 v17, v26, v50
	v_cvt_pk_bf16_f32 v17, v17, v17
	v_add_u32_e32 v16, v16, v138
	ds_write_b16_d16_hi v16, v17
	v_mul_f32_e32 v17, v23, v51
	v_add_u32_e32 v16, 0x14600, v136
	v_cvt_pk_bf16_f32 v17, v17, v17
	v_add_u32_e32 v18, v16, v141
	ds_write_b16_d16_hi v18, v17
	v_mul_f32_e32 v17, v19, v51
	v_cvt_pk_bf16_f32 v17, v17, v17
	v_add_u32_e32 v18, v16, v140
	ds_write_b16_d16_hi v18, v17
	v_mul_f32_e32 v17, v31, v51
	v_cvt_pk_bf16_f32 v17, v17, v17
	v_add_u32_e32 v18, v16, v139
	ds_write_b16_d16_hi v18, v17
	v_mul_f32_e32 v17, v27, v51
	v_bfe_u32 v18, v17, 16, 1
	v_add3_u32 v17, v17, v18, s83
	v_add_u32_e32 v16, v16, v138
	s_waitcnt vmcnt(0)
	v_mul_f32_e32 v4, v4, v32
	ds_write_b16_d16_hi v16, v17
	v_lshl_add_u32 v16, v37, 9, v137
	v_cvt_pk_bf16_f32 v4, v4, v4
	v_add_u32_e32 v17, v16, v141
	v_mul_f32_e32 v0, v0, v32
	ds_write_b16_d16_hi v17, v4
	v_cvt_pk_bf16_f32 v0, v0, v0
	v_add_u32_e32 v4, v16, v140
	ds_write_b16_d16_hi v4, v0
	v_mul_f32_e32 v0, v12, v32
	v_cvt_pk_bf16_f32 v0, v0, v0
	v_add_u32_e32 v4, v16, v139
	ds_write_b16_d16_hi v4, v0
	v_mul_f32_e32 v0, v8, v32
	v_cvt_pk_bf16_f32 v0, v0, v0
	v_add_u32_e32 v4, v16, v138
	ds_write_b16_d16_hi v4, v0
	v_mul_f32_e32 v4, v5, v33
	v_add_u32_e32 v0, 0x16200, v136
	v_cvt_pk_bf16_f32 v4, v4, v4
	v_add_u32_e32 v5, v0, v141
	v_mul_f32_e32 v1, v1, v33
	ds_write_b16_d16_hi v5, v4
	v_cvt_pk_bf16_f32 v1, v1, v1
	v_add_u32_e32 v4, v0, v140
	ds_write_b16_d16_hi v4, v1
	v_mul_f32_e32 v1, v13, v33
	v_cvt_pk_bf16_f32 v1, v1, v1
	v_add_u32_e32 v4, v0, v139
	ds_write_b16_d16_hi v4, v1
	v_mul_f32_e32 v1, v9, v33
	v_cvt_pk_bf16_f32 v1, v1, v1
	v_add_u32_e32 v0, v0, v138
	ds_write_b16_d16_hi v0, v1
	v_mul_f32_e32 v1, v6, v34
	v_add_u32_e32 v0, 0x16400, v136
	v_cvt_pk_bf16_f32 v1, v1, v1
	v_add_u32_e32 v4, v0, v141
	ds_write_b16_d16_hi v4, v1
	v_mul_f32_e32 v1, v2, v34
	v_cvt_pk_bf16_f32 v1, v1, v1
	v_add_u32_e32 v2, v0, v140
	ds_write_b16_d16_hi v2, v1
	v_mul_f32_e32 v1, v14, v34
	v_cvt_pk_bf16_f32 v1, v1, v1
	v_add_u32_e32 v2, v0, v139
	ds_write_b16_d16_hi v2, v1
	v_mul_f32_e32 v1, v10, v34
	v_cvt_pk_bf16_f32 v1, v1, v1
	v_add_u32_e32 v0, v0, v138
	ds_write_b16_d16_hi v0, v1
	v_mul_f32_e32 v1, v7, v35
	v_add_u32_e32 v0, 0x16600, v136
	v_cvt_pk_bf16_f32 v1, v1, v1
	v_add_u32_e32 v2, v0, v141
	ds_write_b16_d16_hi v2, v1
	v_mul_f32_e32 v1, v3, v35
	v_cvt_pk_bf16_f32 v1, v1, v1
	v_add_u32_e32 v2, v0, v140
	ds_write_b16_d16_hi v2, v1
	v_mul_f32_e32 v1, v15, v35
	v_cvt_pk_bf16_f32 v1, v1, v1
	v_add_u32_e32 v2, v0, v139
	ds_write_b16_d16_hi v2, v1
	v_mul_f32_e32 v1, v11, v35
	v_cvt_pk_bf16_f32 v1, v1, v1
	v_add_u32_e32 v0, v0, v138
	ds_write_b16_d16_hi v0, v1
	s_waitcnt lgkmcnt(0)
	s_barrier
; __device__ __forceinline__ int opaque_tid() { int t; asm volatile("v_mov_b32 %0, %1" : "=v"(t) : "v"((int)threadIdx.x)); return t; }
; template <int EPI> ...
;     ...
;     __syncthreads();
;     constexpr int CPR = RB / 16;
;     constexpr int RPI = 512 / CPR;
;     const int tid2 = opaque_tid();
;     const int cc = tid2 % CPR, r0 = tid2 / CPR;
;     u16* gp = (EPI == EPI_GU) ? e.out + ((size_t)((e.bcol >> 6) + (cc >> 3)) * 256 + r0) * 64 + (cc & 7) * 8
;                               : e.out + (size_t)r0 * e.ld + e.bcol + cc * 8;
;     const size_t gstep = (EPI == EPI_GU) ? (size_t)RPI * 64 : (size_t)RPI * e.ld;
; #pragma unroll 4
;     for (int it = 0; it < 256 / RPI; ++it) {
;       const int r = r0 + it * RPI;
;       const int pc = cc ^ (((r >> 2) & 3) << 1);
	v_mov_b32 v0, v146
	s_nop 0
	v_ashrrev_i32_e32 v1, 31, v0
	v_lshrrev_b32_e32 v1, 27, v1
	v_add_u32_e32 v1, v0, v1
	v_ashrrev_i32_e32 v4, 5, v1
	v_and_b32_e32 v1, 0xffffffe0, v1
	v_sub_u32_e32 v5, v0, v1
	v_mov_b64_e32 v[0:1], s[54:55]
	v_mad_i64_i32 v[0:1], s[48:49], v4, s82, v[0:1]
	v_lshlrev_b32_e32 v2, 3, v5
	v_lshl_add_u64 v[0:1], s[52:53], 1, v[0:1]
	v_ashrrev_i32_e32 v3, 31, v2
	v_lshl_add_u64 v[0:1], v[2:3], 1, v[0:1]
	v_lshrrev_b32_e32 v2, 1, v4
	v_bitop3_b32 v2, v2, v5, 6 bitop3:0x6c
	v_lshlrev_b32_e32 v3, 9, v4
	v_lshlrev_b32_e32 v2, 4, v2
	v_add3_u32 v2, 0, v3, v2
	s_mov_b32 s48, 0

; __device__ __forceinline__ float sigmoidf_(float x) { return frcp(1.0f + __expf(-x)); }
; __device__ __forceinline__ void load_shift8(const u16* __restrict__ z, long row, bool hp, bool hn, int col,
;                                             const float* __restrict__ mu, float* out) {
;   const u16* q = z + row * NRWP + col;
;   const uint4 c = *(const uint4*)q;
;   const uint4 pv = *(const uint4*)(q - (hp ? NRWP : 0));
;   const uint4 nx = *(const uint4*)(q + (hn ? NRWP : 0));
;   const float mp = hp ? 0.5f : 0.f, mn = hn ? 0.5f : 0.f;
;   const float4 m0 = *(const float4*)(mu + col), m1 = *(const float4*)(mu + col + 4);
; __device__ __forceinline__ void phase_post(const Params& p) {
;     ...
;     {
;       const long row_a = (long)tt * 16 + fr;
;       bool hp, hn; seq_bounds(row_a, hp, hn);
; #pragma unroll
;       for (int ks = 0; ks < 5; ++ks) {
;         float x[8];
;         load_shift8(zr, row_a, hp, hn, 3328 + ks * 32 + fq * 8, p.mu_shift, x);
; #pragma unroll
;         for (int j = 0; j < 8; ++j) x[j] = sigmoidf_(x[j]);
;         af[ks] = pack8(x);
;       }
;     }
.LBB0_1365:
	v_ashrrev_i32_e32 v40, 4, v81
	v_and_b32_e32 v42, -16, v81
	v_and_b32_e32 v127, 15, v81
	v_ashrrev_i32_e32 v41, 31, v40
	v_or_b32_e32 v110, v42, v120
	v_lshl_or_b32 v132, v127, 6, v80
	v_bitop3_b32 v42, v42, s46, v120 bitop3:0xc8
	v_cmp_lt_u32_e32 vcc, s42, v81
	v_lshlrev_b64 v[40:41], 4, v[40:41]
	v_cmp_gt_i32_e64 s[0:1], s42, v110
	v_or_b32_e32 v126, 0x800, v132
	v_cndmask_b32_e32 v42, v110, v42, vcc
	v_mul_lo_u32 v43, v110, s47
	v_or_b32_e32 v40, v40, v80
	s_or_b64 s[0:1], vcc, s[0:1]
	v_add_lshl_u32 v134, v126, v43, 1
	v_cmp_lt_i32_e64 s[4:5], 0, v42
	v_cndmask_b32_e64 v45, 0, v124, s[0:1]
	v_and_b32_e32 v46, 0x7ff, v40
	v_mad_i64_i32 v[42:43], s[6:7], v40, s43, v[96:97]
	v_cndmask_b32_e64 v129, 0, 0.5, s[0:1]
	v_cmp_gt_i64_e64 s[0:1], s[18:19], v[40:41]
	global_load_dwordx4 v[0:3], v[86:87], off offset:16
	global_load_dwordx4 v[4:7], v[86:87], off
	global_load_dwordx4 v[8:11], v[88:89], off offset:16
	global_load_dwordx4 v[12:15], v[88:89], off
	global_load_dwordx4 v[16:19], v[90:91], off offset:16
	global_load_dwordx4 v[20:23], v[90:91], off
	global_load_dwordx4 v[24:27], v[92:93], off offset:16
	global_load_dwordx4 v[28:31], v[92:93], off
	global_load_dwordx4 v[32:35], v[94:95], off offset:16
	global_load_dwordx4 v[36:39], v[94:95], off
	v_cndmask_b32_e64 v50, v46, v40, s[0:1]
	v_lshl_add_u64 v[40:41], v[42:43], 0, v[98:99]
	v_cndmask_b32_e64 v52, v121, v122, s[0:1]
	v_lshl_add_u64 v[46:47], v[42:43], 0, v[102:103]
	global_load_dwordx4 v[64:67], v[40:41], off
	global_load_dwordx4 v[68:71], v[46:47], off
	v_cndmask_b32_e64 v44, 0, v123, s[4:5]
	v_cndmask_b32_e64 v128, 0, 0.5, s[4:5]
	v_cmp_lt_i32_e64 s[4:5], v50, v52
	v_add_u32_e32 v135, v44, v134
	v_add_u32_e32 v136, v134, v45
	v_cndmask_b32_e64 v82, 0, v124, s[4:5]
	v_lshl_add_u64 v[44:45], v[42:43], 0, v[100:101]
	v_lshl_add_u64 v[48:49], v[42:43], 0, v[104:105]
	v_lshl_add_u64 v[42:43], v[42:43], 0, v[106:107]
	v_lshl_add_u64 v[52:53], v[40:41], 0, v[82:83]
	global_load_dwordx4 v[72:75], v[42:43], off
	v_lshl_add_u64 v[56:57], v[46:47], 0, v[82:83]
	global_load_dwordx4 v[76:79], v[52:53], off
	global_load_dwordx4 v[138:141], v[44:45], off
	global_load_dwordx4 v[142:145], v[56:57], off
	global_load_dwordx4 v[148:151], v[48:49], off
	v_cmp_lt_i32_e64 s[0:1], 0, v50
	v_lshl_add_u64 v[60:61], v[42:43], 0, v[82:83]
	v_lshl_add_u64 v[54:55], v[44:45], 0, v[82:83]
	v_cndmask_b32_e64 v51, 0, -1, s[0:1]
	v_cndmask_b32_e64 v50, 0, v123, s[0:1]
	v_lshl_add_u64 v[40:41], v[40:41], 0, v[50:51]
	v_lshl_add_u64 v[58:59], v[48:49], 0, v[82:83]
	v_lshl_add_u64 v[44:45], v[44:45], 0, v[50:51]
	v_lshl_add_u64 v[46:47], v[46:47], 0, v[50:51]
	v_lshl_add_u64 v[48:49], v[48:49], 0, v[50:51]
	v_lshl_add_u64 v[42:43], v[42:43], 0, v[50:51]
	global_load_dwordx4 v[152:155], v[60:61], off
	global_load_dwordx4 v[156:159], v[40:41], off
	global_load_dwordx4 v[160:163], v[44:45], off
	global_load_dwordx4 v[164:167], v[54:55], off
	global_load_dwordx4 v[168:171], v[46:47], off
	global_load_dwordx4 v[172:175], v[48:49], off
	global_load_dwordx4 v[176:179], v[58:59], off
	global_load_dwordx4 v[180:183], v[42:43], off
	v_mul_u32_u24_e32 v62, 0xa0, v132
	v_lshlrev_b32_e32 v82, 1, v62
	v_lshl_add_u64 v[116:117], v[84:85], 0, v[82:83]
	v_cndmask_b32_e64 v119, 0, 0.5, s[0:1]
	v_add_co_u32_e64 v60, s[0:1], s44, v116
	v_lshl_add_u64 v[184:185], v[116:117], 0, s[24:25]
	s_nop 0
	v_addc_co_u32_e64 v61, s[0:1], 0, v117, s[0:1]
	global_load_dwordx4 v[56:59], v[116:117], off
	global_load_dwordx4 v[52:55], v[116:117], off offset:64
	global_load_dwordx4 v[48:51], v[116:117], off offset:128
	global_load_dwordx4 v[44:47], v[116:117], off offset:192
	global_load_dwordx4 v[40:43], v[116:117], off offset:256
	s_nop 0
	global_load_dwordx4 v[60:63], v[60:61], off offset:1024
	v_lshl_add_u64 v[114:115], v[116:117], 0, s[36:37]
	v_add_co_u32_e64 v118, s[0:1], s45, v116
	v_cndmask_b32_e64 v137, 0, 0.5, s[4:5]
	v_add_u32_e32 v82, 0x3c00, v82
	v_lshlrev_b32_e32 v125, 1, v132
	v_mov_b32_e32 v111, v83
	v_or_b32_e32 v130, 0x800, v125
	v_lshlrev_b64 v[112:113], 7, v[110:111]
	v_lshl_or_b32 v133, v110, 11, v125
	v_lshl_or_b32 v111, v110, 12, v130
	v_bitop3_b32 v131, v110, s41, 3 bitop3:0xc8
	v_cmp_gt_u32_e64 s[6:7], s50, v81
	v_add_u32_e32 v81, s3, v81
	s_waitcnt vmcnt(20)
	v_lshlrev_b32_e32 v116, 16, v64
	v_and_b32_e32 v147, 0xffff0000, v64
	v_lshlrev_b32_e32 v186, 16, v65
	v_and_b32_e32 v187, 0xffff0000, v65
	v_lshlrev_b32_e32 v188, 16, v66
	v_and_b32_e32 v189, 0xffff0000, v66
	v_lshlrev_b32_e32 v190, 16, v67
	v_and_b32_e32 v191, 0xffff0000, v67
	global_load_dwordx4 v[64:67], v[184:185], off offset:64
	s_waitcnt vmcnt(20)
	v_lshlrev_b32_e32 v192, 16, v68
	v_and_b32_e32 v193, 0xffff0000, v68
	s_waitcnt vmcnt(18)
	v_lshlrev_b32_e32 v68, 16, v76
	v_lshlrev_b32_e32 v194, 16, v69
	v_and_b32_e32 v195, 0xffff0000, v69
	v_lshlrev_b32_e32 v196, 16, v70
	v_and_b32_e32 v197, 0xffff0000, v70
	v_lshlrev_b32_e32 v198, 16, v71
	v_and_b32_e32 v199, 0xffff0000, v71
	v_and_b32_e32 v69, 0xffff0000, v76
	v_lshlrev_b32_e32 v70, 16, v77
	v_mul_f32_e32 v248, v137, v68
	s_waitcnt vmcnt(13)
; __device__ __forceinline__ float bflo(unsigned w) { return __uint_as_float(w << 16); }
; __device__ __forceinline__ float bfhi(unsigned w) { return __uint_as_float(w & 0xffff0000u); }
; __device__ __forceinline__ void load_shift8(const u16* __restrict__ z, long row, bool hp, bool hn, int col,
;                                             const float* __restrict__ mu, float* out) {
;   const u16* q = z + row * NRWP + col;
;   const uint4 c = *(const uint4*)q;
;   const uint4 pv = *(const uint4*)(q - (hp ? NRWP : 0));
;   const uint4 nx = *(const uint4*)(q + (hn ? NRWP : 0));
;   const float mp = hp ? 0.5f : 0.f, mn = hn ? 0.5f : 0.f;
;   const float4 m0 = *(const float4*)(mu + col), m1 = *(const float4*)(mu + col + 4);
;   float zc, nb;
;   zc = bflo(c.x); nb = bflo(pv.x) * mp + bflo(nx.x) * mn; out[0] = zc + m0.x * (nb - zc);
;   zc = bfhi(c.x); nb = bfhi(pv.x) * mp + bfhi(nx.x) * mn; out[1] = zc + m0.y * (nb - zc);
;   zc = bflo(c.y); nb = bflo(pv.y) * mp + bflo(nx.y) * mn; out[2] = zc + m0.z * (nb - zc);
;   zc = bfhi(c.y); nb = bfhi(pv.y) * mp + bfhi(nx.y) * mn; out[3] = zc + m0.w * (nb - zc);
;   zc = bflo(c.z); nb = bflo(pv.z) * mp + bflo(nx.z) * mn; out[4] = zc + m1.x * (nb - zc);
;   zc = bfhi(c.z); nb = bfhi(pv.z) * mp + bfhi(nx.z) * mn; out[5] = zc + m1.y * (nb - zc);
;   zc = bflo(c.w); nb = bflo(pv.w) * mp + bflo(nx.w) * mn; out[6] = zc + m1.z * (nb - zc);
;   zc = bfhi(c.w); nb = bfhi(pv.w) * mp + bfhi(nx.w) * mn; out[7] = zc + m1.w * (nb - zc);
; }
	v_lshlrev_b32_e32 v71, 16, v156
	v_mul_f32_e32 v249, v137, v69
	v_mul_f32_e32 v250, v137, v70
	v_fmac_f32_e32 v248, v119, v71
	global_load_dwordx4 v[68:71], v[184:185], off offset:128
	v_lshlrev_b32_e32 v200, 16, v72
	v_and_b32_e32 v201, 0xffff0000, v72
	v_lshlrev_b32_e32 v202, 16, v73
	v_and_b32_e32 v203, 0xffff0000, v73
	v_lshlrev_b32_e32 v204, 16, v74
	v_and_b32_e32 v205, 0xffff0000, v74
	v_lshlrev_b32_e32 v206, 16, v75
	v_and_b32_e32 v207, 0xffff0000, v75
	v_and_b32_e32 v72, 0xffff0000, v77
	v_lshlrev_b32_e32 v73, 16, v78
	v_and_b32_e32 v74, 0xffff0000, v78
	v_lshlrev_b32_e32 v75, 16, v79
	v_mul_f32_e32 v251, v137, v72
	v_mul_f32_e32 v252, v137, v73
	v_mul_f32_e32 v253, v137, v74
	v_mul_f32_e32 v254, v137, v75
	global_load_dwordx4 v[72:75], v[184:185], off offset:192
	v_and_b32_e32 v76, 0xffff0000, v79
	v_lshlrev_b32_e32 v77, 16, v142
	v_and_b32_e32 v78, 0xffff0000, v156
	v_lshlrev_b32_e32 v79, 16, v157
	v_and_b32_e32 v156, 0xffff0000, v157
	v_lshlrev_b32_e32 v157, 16, v158
	v_fmac_f32_e32 v249, v119, v78
	v_fmac_f32_e32 v250, v119, v79
	v_fmac_f32_e32 v251, v119, v156
	v_fmac_f32_e32 v252, v119, v157
	v_mul_f32_e32 v156, v137, v76
	v_mul_f32_e32 v157, v137, v77
	global_load_dwordx4 v[76:79], v[184:185], off offset:256
	v_and_b32_e32 v142, 0xffff0000, v142
	v_lshlrev_b32_e32 v212, 16, v143
	v_and_b32_e32 v143, 0xffff0000, v143
	v_lshlrev_b32_e32 v213, 16, v144
	v_and_b32_e32 v144, 0xffff0000, v144
	v_lshlrev_b32_e32 v214, 16, v145
	v_and_b32_e32 v145, 0xffff0000, v145
	v_lshlrev_b32_e32 v219, 16, v152
	v_and_b32_e32 v152, 0xffff0000, v152
	v_lshlrev_b32_e32 v220, 16, v153
	v_and_b32_e32 v153, 0xffff0000, v153
	v_lshlrev_b32_e32 v221, 16, v154
	v_and_b32_e32 v154, 0xffff0000, v154
	v_lshlrev_b32_e32 v222, 16, v155
	v_and_b32_e32 v155, 0xffff0000, v155
	v_and_b32_e32 v158, 0xffff0000, v158
	v_lshlrev_b32_e32 v223, 16, v159
	v_and_b32_e32 v159, 0xffff0000, v159
	s_waitcnt vmcnt(14)
	v_lshlrev_b32_e32 v225, 16, v164
	v_and_b32_e32 v164, 0xffff0000, v164
	v_lshlrev_b32_e32 v227, 16, v165
	v_and_b32_e32 v165, 0xffff0000, v165
	v_lshlrev_b32_e32 v229, 16, v166
	v_and_b32_e32 v166, 0xffff0000, v166
	v_lshlrev_b32_e32 v231, 16, v167
	v_and_b32_e32 v167, 0xffff0000, v167
	s_waitcnt vmcnt(13)
	v_lshlrev_b32_e32 v232, 16, v168
	v_and_b32_e32 v168, 0xffff0000, v168
	v_lshlrev_b32_e32 v233, 16, v169
	v_and_b32_e32 v169, 0xffff0000, v169
	v_lshlrev_b32_e32 v234, 16, v170
	v_and_b32_e32 v170, 0xffff0000, v170
	v_lshlrev_b32_e32 v235, 16, v171
	v_and_b32_e32 v171, 0xffff0000, v171
	s_waitcnt vmcnt(11)
	v_lshlrev_b32_e32 v237, 16, v176
	v_and_b32_e32 v176, 0xffff0000, v176
	v_lshlrev_b32_e32 v239, 16, v177
	v_and_b32_e32 v177, 0xffff0000, v177
	v_lshlrev_b32_e32 v241, 16, v178
	v_and_b32_e32 v178, 0xffff0000, v178
	v_lshlrev_b32_e32 v243, 16, v179
	v_and_b32_e32 v179, 0xffff0000, v179
	s_waitcnt vmcnt(10)
	v_lshlrev_b32_e32 v244, 16, v180
	v_and_b32_e32 v180, 0xffff0000, v180
	v_lshlrev_b32_e32 v245, 16, v181
	v_and_b32_e32 v181, 0xffff0000, v181
	v_lshlrev_b32_e32 v246, 16, v182
	v_and_b32_e32 v182, 0xffff0000, v182
	v_lshlrev_b32_e32 v247, 16, v183
	v_and_b32_e32 v183, 0xffff0000, v183
	v_fmac_f32_e32 v253, v119, v158
	v_fmac_f32_e32 v254, v119, v223
	v_fmac_f32_e32 v156, v119, v159
	v_mul_f32_e32 v142, v137, v142
	v_mul_f32_e32 v158, v137, v212
	v_mul_f32_e32 v143, v137, v143
	v_mul_f32_e32 v159, v137, v213
	v_mul_f32_e32 v144, v137, v144
	v_mul_f32_e32 v184, v137, v214
	v_mul_f32_e32 v145, v137, v145
	v_mul_f32_e32 v185, v137, v219
	v_mul_f32_e32 v152, v137, v152
	v_mul_f32_e32 v212, v137, v220
	v_mul_f32_e32 v153, v137, v153
	v_mul_f32_e32 v213, v137, v221
	v_mul_f32_e32 v154, v137, v154
	v_mul_f32_e32 v214, v137, v222
	v_mul_f32_e32 v155, v137, v155
	v_lshlrev_b32_e32 v224, 16, v160
	v_and_b32_e32 v160, 0xffff0000, v160
	v_lshlrev_b32_e32 v226, 16, v161
	v_and_b32_e32 v161, 0xffff0000, v161
	v_lshlrev_b32_e32 v228, 16, v162
	v_and_b32_e32 v162, 0xffff0000, v162
	v_lshlrev_b32_e32 v230, 16, v163
	v_and_b32_e32 v163, 0xffff0000, v163
	v_lshlrev_b32_e32 v236, 16, v172
	v_and_b32_e32 v172, 0xffff0000, v172
	v_lshlrev_b32_e32 v238, 16, v173
	v_and_b32_e32 v173, 0xffff0000, v173
	v_lshlrev_b32_e32 v240, 16, v174
	v_and_b32_e32 v174, 0xffff0000, v174
	v_lshlrev_b32_e32 v242, 16, v175
	v_and_b32_e32 v175, 0xffff0000, v175
	v_fmac_f32_e32 v157, v119, v232
	v_mul_f32_e32 v219, v137, v225
	v_mul_f32_e32 v164, v137, v164
	v_mul_f32_e32 v220, v137, v227
	v_mul_f32_e32 v165, v137, v165
	v_mul_f32_e32 v221, v137, v229
	v_mul_f32_e32 v166, v137, v166
	v_mul_f32_e32 v222, v137, v231
	v_mul_f32_e32 v167, v137, v167
	v_fmac_f32_e32 v142, v119, v168
	v_fmac_f32_e32 v158, v119, v233
	v_fmac_f32_e32 v143, v119, v169
	v_fmac_f32_e32 v159, v119, v234
	v_fmac_f32_e32 v144, v119, v170
	v_fmac_f32_e32 v184, v119, v235
	v_fmac_f32_e32 v145, v119, v171
	v_mul_f32_e32 v168, v137, v237
	v_mul_f32_e32 v169, v137, v176
	v_mul_f32_e32 v170, v137, v239
	v_mul_f32_e32 v171, v137, v177
	v_mul_f32_e32 v176, v137, v241
	v_mul_f32_e32 v177, v137, v178
	v_mul_f32_e32 v178, v137, v243
	v_mul_f32_e32 v137, v137, v179
	v_fmac_f32_e32 v185, v119, v244
	v_fmac_f32_e32 v152, v119, v180
	v_fmac_f32_e32 v212, v119, v245
	v_fmac_f32_e32 v153, v119, v181
	v_fmac_f32_e32 v213, v119, v246
	v_fmac_f32_e32 v154, v119, v182
	v_fmac_f32_e32 v214, v119, v247
	v_fmac_f32_e32 v155, v119, v183
	v_sub_f32_e32 v179, v248, v116
	v_sub_f32_e32 v180, v249, v147
	v_sub_f32_e32 v181, v250, v186
	v_sub_f32_e32 v182, v251, v187
	v_sub_f32_e32 v183, v252, v188
	v_sub_f32_e32 v223, v253, v189
	v_sub_f32_e32 v225, v254, v190
	v_sub_f32_e32 v156, v156, v191
	v_lshlrev_b32_e32 v215, 16, v148
	v_and_b32_e32 v148, 0xffff0000, v148
; __device__ __forceinline__ float bflo(unsigned w) { return __uint_as_float(w << 16); }
; __device__ __forceinline__ float bfhi(unsigned w) { return __uint_as_float(w & 0xffff0000u); }
; __device__ __forceinline__ float sigmoidf_(float x) { return frcp(1.0f + __expf(-x)); }
; __device__ __forceinline__ void load_shift8(const u16* __restrict__ z, long row, bool hp, bool hn, int col,
;                                             const float* __restrict__ mu, float* out) {
;     ...
;   zc = bflo(c.x); nb = bflo(pv.x) * mp + bflo(nx.x) * mn; out[0] = zc + m0.x * (nb - zc);
;   zc = bfhi(c.x); nb = bfhi(pv.x) * mp + bfhi(nx.x) * mn; out[1] = zc + m0.y * (nb - zc);
;   zc = bflo(c.y); nb = bflo(pv.y) * mp + bflo(nx.y) * mn; out[2] = zc + m0.z * (nb - zc);
;   zc = bfhi(c.y); nb = bfhi(pv.y) * mp + bfhi(nx.y) * mn; out[3] = zc + m0.w * (nb - zc);
;   zc = bflo(c.z); nb = bflo(pv.z) * mp + bflo(nx.z) * mn; out[4] = zc + m1.x * (nb - zc);
;   zc = bfhi(c.z); nb = bfhi(pv.z) * mp + bfhi(nx.z) * mn; out[5] = zc + m1.y * (nb - zc);
;   zc = bflo(c.w); nb = bflo(pv.w) * mp + bflo(nx.w) * mn; out[6] = zc + m1.z * (nb - zc);
;   zc = bfhi(c.w); nb = bfhi(pv.w) * mp + bfhi(nx.w) * mn; out[7] = zc + m1.w * (nb - zc);
; __device__ __forceinline__ void phase_post(const Params& p) {
;     ...
;       for (int ks = 0; ks < 5; ++ks) {
;         float x[8];
;         load_shift8(zr, row_a, hp, hn, 3328 + ks * 32 + fq * 8, p.mu_shift, x);
; #pragma unroll
;         for (int j = 0; j < 8; ++j) x[j] = sigmoidf_(x[j]);
;         af[ks] = pack8(x);
	v_lshlrev_b32_e32 v216, 16, v149
	v_and_b32_e32 v149, 0xffff0000, v149
	v_lshlrev_b32_e32 v217, 16, v150
	v_and_b32_e32 v150, 0xffff0000, v150
	v_lshlrev_b32_e32 v218, 16, v151
	v_and_b32_e32 v151, 0xffff0000, v151
	v_fmac_f32_e32 v219, v119, v224
	v_fmac_f32_e32 v164, v119, v160
	v_fmac_f32_e32 v220, v119, v226
	v_fmac_f32_e32 v165, v119, v161
	v_fmac_f32_e32 v221, v119, v228
	v_fmac_f32_e32 v166, v119, v162
	v_fmac_f32_e32 v222, v119, v230
	v_fmac_f32_e32 v167, v119, v163
	v_sub_f32_e32 v157, v157, v192
	v_sub_f32_e32 v142, v142, v193
	v_sub_f32_e32 v158, v158, v194
	v_sub_f32_e32 v143, v143, v195
	v_sub_f32_e32 v159, v159, v196
	v_sub_f32_e32 v144, v144, v197
	v_sub_f32_e32 v160, v184, v198
	v_sub_f32_e32 v145, v145, v199
	v_fmac_f32_e32 v168, v119, v236
	v_fmac_f32_e32 v169, v119, v172
	v_fmac_f32_e32 v170, v119, v238
	v_fmac_f32_e32 v171, v119, v173
	v_fmac_f32_e32 v176, v119, v240
	v_fmac_f32_e32 v177, v119, v174
	v_fmac_f32_e32 v178, v119, v242
	v_fmac_f32_e32 v137, v119, v175
	v_sub_f32_e32 v119, v185, v200
	v_sub_f32_e32 v152, v152, v201
	v_sub_f32_e32 v161, v212, v202
	v_sub_f32_e32 v153, v153, v203
	v_sub_f32_e32 v162, v213, v204
	v_sub_f32_e32 v154, v154, v205
	v_sub_f32_e32 v163, v214, v206
	v_sub_f32_e32 v155, v155, v207
	v_fmac_f32_e32 v116, v4, v179
	v_fmac_f32_e32 v147, v5, v180
	v_fmac_f32_e32 v186, v6, v181
	v_fmac_f32_e32 v187, v182, v7
	v_fmac_f32_e32 v188, v183, v0
	v_fmac_f32_e32 v189, v223, v1
	v_fmac_f32_e32 v190, v225, v2
	v_fmac_f32_e32 v191, v156, v3
	v_fmac_f32_e32 v192, v20, v157
	v_fmac_f32_e32 v193, v21, v142
	v_fmac_f32_e32 v194, v22, v158
	v_fmac_f32_e32 v195, v143, v23
	v_fmac_f32_e32 v196, v159, v16
	v_fmac_f32_e32 v197, v144, v17
	v_fmac_f32_e32 v198, v160, v18
	v_fmac_f32_e32 v199, v145, v19
	v_sub_f32_e32 v16, v168, v215
	v_sub_f32_e32 v17, v169, v148
	v_sub_f32_e32 v18, v170, v216
	v_sub_f32_e32 v19, v171, v149
	v_sub_f32_e32 v20, v176, v217
	v_sub_f32_e32 v21, v177, v150
	v_sub_f32_e32 v22, v178, v218
	v_sub_f32_e32 v23, v137, v151
	v_fmac_f32_e32 v200, v36, v119
	v_fmac_f32_e32 v201, v37, v152
	v_fmac_f32_e32 v202, v38, v161
	v_fmac_f32_e32 v203, v153, v39
	v_fmac_f32_e32 v204, v162, v32
	v_fmac_f32_e32 v205, v154, v33
	v_fmac_f32_e32 v206, v163, v34
	v_fmac_f32_e32 v207, v155, v35
	v_mul_f32_e32 v32, 0xbfb8aa3b, v116
	v_mul_f32_e32 v33, 0xbfb8aa3b, v147
	v_mul_f32_e32 v34, 0xbfb8aa3b, v186
	v_mul_f32_e32 v35, 0xbfb8aa3b, v187
	v_mul_f32_e32 v36, 0xbfb8aa3b, v188
	v_mul_f32_e32 v37, 0xbfb8aa3b, v189
	v_mul_f32_e32 v38, 0xbfb8aa3b, v190
	v_mul_f32_e32 v39, 0xbfb8aa3b, v191
	v_lshlrev_b32_e32 v208, 16, v138
	v_and_b32_e32 v138, 0xffff0000, v138
	v_lshlrev_b32_e32 v209, 16, v139
	v_and_b32_e32 v139, 0xffff0000, v139
	v_lshlrev_b32_e32 v210, 16, v140
	v_and_b32_e32 v140, 0xffff0000, v140
	v_lshlrev_b32_e32 v211, 16, v141
	v_and_b32_e32 v141, 0xffff0000, v141
	v_fmac_f32_e32 v215, v28, v16
	v_fmac_f32_e32 v148, v29, v17
	v_fmac_f32_e32 v216, v30, v18
	v_fmac_f32_e32 v149, v19, v31
	v_fmac_f32_e32 v217, v20, v24
	v_fmac_f32_e32 v150, v21, v25
	v_fmac_f32_e32 v218, v22, v26
	v_fmac_f32_e32 v151, v23, v27
	v_exp_f32_e32 v16, v32
	v_exp_f32_e32 v17, v33
	v_exp_f32_e32 v18, v34
	v_exp_f32_e32 v19, v35
	v_exp_f32_e32 v20, v36
	v_exp_f32_e32 v21, v37
	v_exp_f32_e32 v22, v38
	v_exp_f32_e32 v23, v39
	v_sub_f32_e32 v0, v219, v208
	v_sub_f32_e32 v1, v164, v138
	v_sub_f32_e32 v2, v220, v209
	v_sub_f32_e32 v3, v165, v139
	v_sub_f32_e32 v4, v221, v210
	v_sub_f32_e32 v5, v166, v140
	v_sub_f32_e32 v6, v222, v211
	v_sub_f32_e32 v7, v167, v141
	v_fmac_f32_e32 v208, v12, v0
	v_fmac_f32_e32 v138, v13, v1
	v_fmac_f32_e32 v209, v14, v2
	v_fmac_f32_e32 v139, v3, v15
	v_fmac_f32_e32 v210, v4, v8
	v_fmac_f32_e32 v140, v5, v9
	v_fmac_f32_e32 v211, v6, v10
	v_fmac_f32_e32 v141, v7, v11
	v_mul_f32_e32 v0, 0xbfb8aa3b, v192
	v_mul_f32_e32 v1, 0xbfb8aa3b, v193
	v_mul_f32_e32 v2, 0xbfb8aa3b, v194
	v_mul_f32_e32 v3, 0xbfb8aa3b, v195
	v_mul_f32_e32 v4, 0xbfb8aa3b, v196
	v_mul_f32_e32 v5, 0xbfb8aa3b, v197
	v_mul_f32_e32 v6, 0xbfb8aa3b, v198
	v_mul_f32_e32 v7, 0xbfb8aa3b, v199
	v_mul_f32_e32 v8, 0xbfb8aa3b, v200
	v_mul_f32_e32 v9, 0xbfb8aa3b, v201
	v_mul_f32_e32 v10, 0xbfb8aa3b, v202
	v_mul_f32_e32 v11, 0xbfb8aa3b, v203
	v_mul_f32_e32 v12, 0xbfb8aa3b, v204
	v_mul_f32_e32 v13, 0xbfb8aa3b, v205
	v_mul_f32_e32 v14, 0xbfb8aa3b, v206
	v_mul_f32_e32 v15, 0xbfb8aa3b, v207
	v_mul_f32_e32 v24, 0xbfb8aa3b, v208
	v_mul_f32_e32 v25, 0xbfb8aa3b, v138
	v_mul_f32_e32 v26, 0xbfb8aa3b, v209
	v_mul_f32_e32 v27, 0xbfb8aa3b, v139
	v_mul_f32_e32 v28, 0xbfb8aa3b, v210
	v_mul_f32_e32 v29, 0xbfb8aa3b, v140
	v_mul_f32_e32 v30, 0xbfb8aa3b, v211
	v_mul_f32_e32 v31, 0xbfb8aa3b, v141
	v_exp_f32_e32 v0, v0
	v_exp_f32_e32 v1, v1
	v_exp_f32_e32 v2, v2
	v_exp_f32_e32 v3, v3
	v_exp_f32_e32 v4, v4
	v_exp_f32_e32 v5, v5
	v_exp_f32_e32 v6, v6
	v_exp_f32_e32 v7, v7
	v_mul_f32_e32 v32, 0xbfb8aa3b, v215
	v_mul_f32_e32 v33, 0xbfb8aa3b, v148
	v_mul_f32_e32 v34, 0xbfb8aa3b, v216
	v_mul_f32_e32 v35, 0xbfb8aa3b, v149
	v_mul_f32_e32 v36, 0xbfb8aa3b, v217
	v_mul_f32_e32 v37, 0xbfb8aa3b, v150
	v_mul_f32_e32 v38, 0xbfb8aa3b, v218
	v_mul_f32_e32 v39, 0xbfb8aa3b, v151
	v_exp_f32_e32 v8, v8
	v_exp_f32_e32 v9, v9
	v_exp_f32_e32 v10, v10
	v_exp_f32_e32 v11, v11
	v_exp_f32_e32 v12, v12
	v_exp_f32_e32 v13, v13
	v_exp_f32_e32 v14, v14
	v_exp_f32_e32 v15, v15
	v_exp_f32_e32 v24, v24
	v_exp_f32_e32 v25, v25
	v_exp_f32_e32 v26, v26
	v_exp_f32_e32 v27, v27
	v_exp_f32_e32 v28, v28
	v_exp_f32_e32 v29, v29
	v_exp_f32_e32 v30, v30
	v_exp_f32_e32 v31, v31
	v_add_f32_e32 v16, 1.0, v16
	v_add_f32_e32 v17, 1.0, v17
	v_add_f32_e32 v18, 1.0, v18
	v_add_f32_e32 v19, 1.0, v19
	v_add_f32_e32 v20, 1.0, v20
; __device__ __forceinline__ float sigmoidf_(float x) { return frcp(1.0f + __expf(-x)); }
; __device__ __forceinline__ void phase_post(const Params& p) {
;     ...
;       for (int ks = 0; ks < 5; ++ks) {
;         float x[8];
;         load_shift8(zr, row_a, hp, hn, 3328 + ks * 32 + fq * 8, p.mu_shift, x);
; #pragma unroll
;         for (int j = 0; j < 8; ++j) x[j] = sigmoidf_(x[j]);
;         af[ks] = pack8(x);
;       }
;     }
;     asm volatile("" ::: "memory");
;     f32x4 acc[4];
; #pragma unroll
;     for (int nt = 0; nt < 4; ++nt) {
;       acc[nt] = (f32x4){0.f, 0.f, 0.f, 0.f};
;       const u16* gp = g2t + (size_t)(64 * head + nt * 16 + fr) * 160 + fq * 8;
; #pragma unroll
;       for (int ks = 0; ks < 5; ++ks) {
;         bf16x8 bfr = *(const bf16x8*)(gp + ks * 32);
;         acc[nt] = __builtin_amdgcn_mfma_f32_16x16x32_bf16(af[ks], bfr, acc[nt], 0, 0, 0);
;       }
;       if (nt & 1) asm volatile("" : "+v"(acc[nt]) :: "memory");
	v_add_f32_e32 v21, 1.0, v21
	v_add_f32_e32 v22, 1.0, v22
	v_add_f32_e32 v23, 1.0, v23
	v_exp_f32_e32 v32, v32
	v_exp_f32_e32 v33, v33
	v_exp_f32_e32 v34, v34
	v_exp_f32_e32 v35, v35
	v_exp_f32_e32 v36, v36
	v_exp_f32_e32 v37, v37
	v_exp_f32_e32 v38, v38
	v_exp_f32_e32 v39, v39
	v_rcp_f32_e32 v16, v16
	v_rcp_f32_e32 v17, v17
	v_rcp_f32_e32 v18, v18
	v_rcp_f32_e32 v19, v19
	v_rcp_f32_e32 v20, v20
	v_rcp_f32_e32 v21, v21
	v_rcp_f32_e32 v22, v22
	v_rcp_f32_e32 v23, v23
	v_add_f32_e32 v0, 1.0, v0
	v_add_f32_e32 v1, 1.0, v1
	v_add_f32_e32 v2, 1.0, v2
	v_add_f32_e32 v3, 1.0, v3
	v_add_f32_e32 v4, 1.0, v4
	v_add_f32_e32 v5, 1.0, v5
	v_add_f32_e32 v6, 1.0, v6
	v_add_f32_e32 v7, 1.0, v7
	v_add_f32_e32 v8, 1.0, v8
	v_add_f32_e32 v9, 1.0, v9
	v_add_f32_e32 v10, 1.0, v10
	v_add_f32_e32 v11, 1.0, v11
	v_add_f32_e32 v12, 1.0, v12
	v_add_f32_e32 v13, 1.0, v13
	v_add_f32_e32 v14, 1.0, v14
	v_add_f32_e32 v15, 1.0, v15
	v_add_f32_e32 v24, 1.0, v24
	v_add_f32_e32 v25, 1.0, v25
	v_add_f32_e32 v26, 1.0, v26
	v_add_f32_e32 v27, 1.0, v27
	v_add_f32_e32 v28, 1.0, v28
	v_add_f32_e32 v29, 1.0, v29
	v_add_f32_e32 v30, 1.0, v30
	v_add_f32_e32 v31, 1.0, v31
	v_rcp_f32_e32 v116, v0
	v_rcp_f32_e32 v119, v1
	v_rcp_f32_e32 v137, v2
	v_rcp_f32_e32 v138, v3
	v_rcp_f32_e32 v139, v4
	v_rcp_f32_e32 v140, v5
	v_rcp_f32_e32 v141, v6
	v_rcp_f32_e32 v142, v7
	v_add_f32_e32 v0, 1.0, v32
	v_add_f32_e32 v1, 1.0, v33
	v_add_f32_e32 v2, 1.0, v34
	v_add_f32_e32 v3, 1.0, v35
	v_add_f32_e32 v4, 1.0, v36
	v_add_f32_e32 v5, 1.0, v37
	v_add_f32_e32 v6, 1.0, v38
	v_add_f32_e32 v7, 1.0, v39
	v_rcp_f32_e32 v32, v8
	v_rcp_f32_e32 v33, v9
	v_rcp_f32_e32 v34, v10
	v_rcp_f32_e32 v35, v11
	v_rcp_f32_e32 v36, v12
	v_rcp_f32_e32 v37, v13
	v_rcp_f32_e32 v38, v14
	v_rcp_f32_e32 v39, v15
	v_rcp_f32_e32 v12, v24
	v_rcp_f32_e32 v13, v25
	v_rcp_f32_e32 v14, v26
	v_rcp_f32_e32 v15, v27
	v_rcp_f32_e32 v24, v28
	v_rcp_f32_e32 v25, v29
	v_rcp_f32_e32 v26, v30
	v_rcp_f32_e32 v27, v31
	v_cvt_pk_bf16_f32 v8, v16, v17
	v_cvt_pk_bf16_f32 v9, v18, v19
	v_cvt_pk_bf16_f32 v10, v20, v21
	v_cvt_pk_bf16_f32 v11, v22, v23
	v_cvt_pk_bf16_f32 v12, v12, v13
	v_cvt_pk_bf16_f32 v13, v14, v15
	v_cvt_pk_bf16_f32 v14, v24, v25
	v_cvt_pk_bf16_f32 v15, v26, v27
	v_rcp_f32_e32 v143, v4
	v_rcp_f32_e32 v144, v5
	v_rcp_f32_e32 v145, v6
	v_rcp_f32_e32 v147, v7
	s_waitcnt vmcnt(4)
	v_mfma_f32_16x16x32_bf16 v[4:7], v[8:11], v[60:63], 0
	v_rcp_f32_e32 v28, v0
	v_rcp_f32_e32 v29, v1
	v_rcp_f32_e32 v30, v2
	v_rcp_f32_e32 v31, v3
	v_cvt_pk_bf16_f32 v16, v116, v119
	v_cvt_pk_bf16_f32 v17, v137, v138
	v_cvt_pk_bf16_f32 v18, v139, v140
	v_cvt_pk_bf16_f32 v19, v141, v142
	s_waitcnt vmcnt(3)
	v_mfma_f32_16x16x32_bf16 v[4:7], v[12:15], v[64:67], v[4:7]
	v_cvt_pk_bf16_f32 v20, v28, v29
	v_cvt_pk_bf16_f32 v21, v30, v31
	v_cvt_pk_bf16_f32 v22, v143, v144
	v_mfma_f32_16x16x32_bf16 v[0:3], v[8:11], v[56:59], 0
	v_cvt_pk_bf16_f32 v23, v145, v147
	v_cvt_pk_bf16_f32 v24, v32, v33
	v_cvt_pk_bf16_f32 v25, v34, v35
	s_waitcnt vmcnt(2)
	v_mfma_f32_16x16x32_bf16 v[4:7], v[16:19], v[68:71], v[4:7]
	v_cvt_pk_bf16_f32 v26, v36, v37
	v_cvt_pk_bf16_f32 v27, v38, v39
	v_addc_co_u32_e64 v119, s[0:1], 0, v117, s[0:1]
	v_mfma_f32_16x16x32_bf16 v[0:3], v[12:15], v[52:55], v[0:3]
	s_waitcnt vmcnt(1)
	v_mfma_f32_16x16x32_bf16 v[4:7], v[20:23], v[72:75], v[4:7]
	v_mfma_f32_16x16x32_bf16 v[0:3], v[16:19], v[48:51], v[0:3]
	s_waitcnt vmcnt(0)
	v_mfma_f32_16x16x32_bf16 v[4:7], v[24:27], v[76:79], v[4:7]
	v_cndmask_b32_e64 v78, v121, v122, s[6:7]
	v_mfma_f32_16x16x32_bf16 v[0:3], v[20:23], v[44:47], v[0:3]
	v_lshl_add_u64 v[44:45], v[84:85], 0, v[82:83]
	global_load_dwordx4 v[28:31], v[118:119], off offset:2048
	global_load_dwordx4 v[32:35], v[44:45], off
	global_load_dwordx4 v[36:39], v[114:115], off offset:64
	v_lshlrev_b32_e32 v82, 2, v132
	v_mfma_f32_16x16x32_bf16 v[0:3], v[24:27], v[40:43], v[0:3]
	global_load_dwordx4 v[40:43], v[44:45], off offset:64
	s_waitcnt vmcnt(3)
	v_mfma_f32_16x16x32_bf16 v[28:31], v[8:11], v[28:31], 0
	s_waitcnt vmcnt(2)
	v_mfma_f32_16x16x32_bf16 v[8:11], v[8:11], v[32:35], 0
	global_load_dwordx4 v[32:35], v[114:115], off offset:128
	s_waitcnt vmcnt(2)
	v_mfma_f32_16x16x32_bf16 v[28:31], v[12:15], v[36:39], v[28:31]
	global_load_dwordx4 v[36:39], v[44:45], off offset:128
	s_waitcnt vmcnt(2)
	v_mfma_f32_16x16x32_bf16 v[8:11], v[12:15], v[40:43], v[8:11]
	global_load_dwordx4 v[12:15], v[114:115], off offset:192
	s_waitcnt vmcnt(2)
	v_mfma_f32_16x16x32_bf16 v[28:31], v[16:19], v[32:35], v[28:31]
	global_load_dwordx4 v[32:35], v[44:45], off offset:192
	s_waitcnt vmcnt(2)
	v_mfma_f32_16x16x32_bf16 v[8:11], v[16:19], v[36:39], v[8:11]
	global_load_dwordx4 v[16:19], v[114:115], off offset:256
	v_add_u32_e32 v39, 0x1c00, v134
	s_waitcnt vmcnt(2)
	v_mfma_f32_16x16x32_bf16 v[12:15], v[20:23], v[12:15], v[28:31]
	s_nop 2
	global_load_dwordx4 v[28:31], v[44:45], off offset:256
	s_waitcnt vmcnt(2)
	v_mfma_f32_16x16x32_bf16 v[20:23], v[20:23], v[32:35], v[8:11]
	v_lshl_add_u64 v[32:33], s[38:39], 0, v[82:83]
	s_waitcnt vmcnt(1)
	v_mfma_f32_16x16x32_bf16 v[8:11], v[24:27], v[16:19], v[12:15]
	v_add_co_u32_e64 v16, s[0:1], s45, v32
	s_waitcnt vmcnt(0)
; __device__ __forceinline__ float bf2f(u16 h) { return __uint_as_float(((unsigned)h) << 16); }
; __device__ __forceinline__ void phase_post(const Params& p) {
;     ...
;     float lw[4], lb[4], muv[4];
; #pragma unroll
;     for (int nt = 0; nt < 4; ++nt) {
;       const int ch = 64 * head + nt * 16 + fr;
;       lw[nt] = p.ln_w[ch]; lb[nt] = p.ln_b[ch]; muv[nt] = p.mu_shift[2048 + ch];
;     }
; #pragma unroll
;     for (int jh = 0; jh < 4; jh += 2) {
;     float oy[4][4], ovc[4][4], ovp[4][4], ovn[4][4], rkv[4];
;     unsigned yo[4];
; #pragma unroll
;     for (int j = jh; j < jh + 2; ++j) {
;       const unsigned row = (unsigned)tt * 16u + (unsigned)(fq * 4 + j);
;       bool hp, hn; seq_bounds((long)row, hp, hn);
;       yo[j] = (row * (unsigned)DM + 1024u + (unsigned)(64 * head + fr)) * 2u;
;       const unsigned obo = (row * 1024u + (unsigned)(64 * head + fr)) * 2u;
;       const unsigned zo = (row * (unsigned)NRWP + 2048u + (unsigned)(64 * head + fr)) * 2u;
;       const unsigned zpo = zo - (hp ? (unsigned)NRWP * 2u : 0u), zno = zo + (hn ? (unsigned)NRWP * 2u : 0u);
;       const float mp = hp ? 0.5f : 0.f, mn = hn ? 0.5f : 0.f;
; #pragma unroll
;       for (int nt = 0; nt < 4; ++nt) {
;         oy[j][nt] = bf2f(*(const u16*)((const char*)y + (size_t)yo[j] + nt * 32)) + bf2f(*(const u16*)((const char*)ob + (size_t)obo + nt * 32));
;         ovc[j][nt] = bf2f(*(const u16*)((const char*)zr + (size_t)zo + nt * 32));
;         ovp[j][nt] = bf2f(*(const u16*)((const char*)zr + (size_t)zpo + nt * 32)) * mp;
;         ovn[j][nt] = bf2f(*(const u16*)((const char*)zr + (size_t)zno + nt * 32)) * mn;
;       }
;       rkv[j] = rkbuf[(size_t)row * 32 + head * 2] + rkbuf[(size_t)row * 32 + head * 2 + 1];
;     }
	v_mfma_f32_16x16x32_bf16 v[12:15], v[24:27], v[28:31], v[20:23]
	v_addc_co_u32_e64 v17, s[0:1], 0, v33, s[0:1]
	global_load_dword v28, v82, s[20:21]
	global_load_dword v24, v82, s[22:23]
	global_load_dword v29, v82, s[20:21] offset:64
	global_load_dword v25, v82, s[22:23] offset:64
	global_load_dword v30, v82, s[20:21] offset:128
	global_load_dword v26, v82, s[22:23] offset:128
	global_load_dword v31, v82, s[20:21] offset:192
	global_load_dword v27, v82, s[22:23] offset:192
	global_load_dword v33, v[16:17], off
	global_load_dword v34, v[16:17], off offset:64
	global_load_dword v35, v[16:17], off offset:128
	global_load_dword v36, v[16:17], off offset:192
	v_lshlrev_b32_e32 v82, 3, v127
	global_load_ushort v42, v135, s[72:73]
	global_load_ushort v43, v136, s[72:73]
	global_load_ushort v44, v136, s[72:73] offset:32
	global_load_ushort v45, v136, s[72:73] offset:64
	global_load_ushort v46, v136, s[72:73] offset:96
	global_load_ushort v47, v39, s[72:73]
	global_load_ushort v48, v39, s[72:73] offset:32
	global_load_ushort v49, v39, s[72:73] offset:64
	global_load_ushort v50, v135, s[72:73] offset:32
	global_load_ushort v51, v135, s[72:73] offset:64
	global_load_ushort v52, v135, s[72:73] offset:96
	global_load_ushort v53, v134, s[72:73]
	global_load_ushort v54, v134, s[72:73] offset:32
	global_load_ushort v55, v134, s[72:73] offset:64
	global_load_ushort v56, v134, s[72:73] offset:96
	global_load_ushort v57, v111, s[12:13] offset:96
	global_load_ushort v58, v133, s[14:15] offset:96
	global_load_ushort v59, v133, s[14:15] offset:64
	global_load_ushort v60, v133, s[14:15]
	global_load_ushort v61, v133, s[14:15] offset:32
	global_load_ushort v62, v111, s[12:13] offset:64
	global_load_ushort v63, v111, s[12:13]
	global_load_ushort v64, v111, s[12:13] offset:32
	v_lshl_add_u64 v[18:19], s[10:11], 0, v[82:83]
	v_or_b32_e32 v82, 1, v110
	v_lshl_add_u64 v[16:17], v[18:19], 0, v[112:113]
	v_lshl_or_b32 v22, v82, 11, v125
	v_lshlrev_b64 v[20:21], 7, v[82:83]
	v_lshl_or_b32 v38, v82, 12, v130
	v_lshl_add_u64 v[20:21], v[18:19], 0, v[20:21]
	global_load_ushort v65, v22, s[14:15] offset:96
	s_nop 0
	global_load_dwordx2 v[16:17], v[16:17], off
	s_nop 0
	global_load_ushort v66, v38, s[12:13] offset:96
	global_load_ushort v67, v22, s[14:15] offset:64
	global_load_ushort v68, v22, s[14:15]
	global_load_ushort v69, v22, s[14:15] offset:32
	global_load_ushort v70, v38, s[12:13] offset:64
	global_load_ushort v71, v38, s[12:13]
	global_load_ushort v72, v38, s[12:13] offset:32
	v_cmp_gt_i32_e64 s[0:1], s42, v82
	global_load_dwordx2 v[20:21], v[20:21], off
	s_or_b64 s[0:1], vcc, s[0:1]
	v_or_b32_e32 v82, 2, v110
	v_cndmask_b32_e64 v40, 0, v124, s[0:1]
	v_cmp_gt_i32_e64 s[4:5], s42, v82
	v_lshl_or_b32 v32, v82, 12, v130
	v_lshl_or_b32 v37, v82, 11, v125
	v_mul_lo_u32 v41, v82, s47
	v_lshlrev_b64 v[22:23], 7, v[82:83]
	v_or_b32_e32 v82, 3, v110
	v_add_u32_e32 v73, v39, v40
	v_add_lshl_u32 v75, v126, v41, 1
	v_cndmask_b32_e64 v77, v131, v82, s[6:7]
	v_lshl_or_b32 v79, v82, 12, v130
	v_lshl_or_b32 v110, v82, 11, v125
	v_lshlrev_b64 v[40:41], 7, v[82:83]
	global_load_ushort v82, v73, s[72:73]
	global_load_ushort v112, v73, s[72:73] offset:32
	global_load_ushort v113, v73, s[72:73] offset:64
	s_nop 0
	global_load_ushort v73, v73, s[72:73] offset:96
	s_nop 0
	global_load_ushort v39, v39, s[72:73] offset:96
	v_lshl_add_u64 v[22:23], v[18:19], 0, v[22:23]
	v_lshl_add_u64 v[18:19], v[18:19], 0, v[40:41]
	v_cndmask_b32_e64 v74, 0, 0.5, s[0:1]
	s_or_b64 vcc, vcc, s[4:5]
	v_cndmask_b32_e32 v76, 0, v124, vcc
	v_cndmask_b32_e64 v115, 0, 0.5, vcc
	v_cmp_lt_i32_e32 vcc, 0, v77
	v_cmp_lt_i32_e64 s[0:1], v77, v78
	v_add_u32_e32 v116, 0x1c00, v75
	v_cndmask_b32_e32 v117, 0, v123, vcc
	v_cndmask_b32_e64 v77, 0, v124, s[0:1]
	v_cndmask_b32_e64 v118, 0, 0.5, s[0:1]
	v_add_u32_e32 v78, v117, v116
	v_cndmask_b32_e64 v117, 0, 0.5, vcc
	v_add_u32_e32 v76, v75, v76
	v_add_u32_e32 v114, 0xffffe400, v75
	v_add_u32_e32 v77, v77, v116
	s_waitcnt vmcnt(37)
	v_lshlrev_b32_e32 v119, 16, v42
	s_waitcnt vmcnt(36)
	v_lshlrev_b32_e32 v125, 16, v43
	s_waitcnt vmcnt(35)
	v_lshlrev_b32_e32 v126, 16, v44
	s_waitcnt vmcnt(34)
	v_lshlrev_b32_e32 v127, 16, v45
	s_waitcnt vmcnt(33)
	v_lshlrev_b32_e32 v130, 16, v46
	s_waitcnt vmcnt(32)
	v_lshlrev_b32_e32 v131, 16, v47
	s_waitcnt vmcnt(31)
	v_lshlrev_b32_e32 v132, 16, v48
	s_waitcnt vmcnt(30)
	v_lshlrev_b32_e32 v133, 16, v49
	s_waitcnt vmcnt(29)
	v_lshlrev_b32_e32 v50, 16, v50
	v_mul_f32_e32 v48, v129, v125
	v_mul_f32_e32 v49, v129, v126
	s_waitcnt vmcnt(28)
	v_lshlrev_b32_e32 v51, 16, v51
	s_waitcnt vmcnt(27)
	v_lshlrev_b32_e32 v52, 16, v52
	s_waitcnt vmcnt(26)
	v_lshlrev_b32_e32 v53, 16, v53
	s_waitcnt vmcnt(25)
	v_lshlrev_b32_e32 v54, 16, v54
	s_waitcnt vmcnt(22)
	v_lshlrev_b32_e32 v40, 16, v57
	s_waitcnt vmcnt(21)
	v_lshlrev_b32_e32 v42, 16, v58
	s_waitcnt vmcnt(20)
	v_lshlrev_b32_e32 v43, 16, v59
	s_waitcnt vmcnt(19)
	v_lshlrev_b32_e32 v46, 16, v60
	s_waitcnt vmcnt(18)
	v_lshlrev_b32_e32 v47, 16, v61
	s_waitcnt vmcnt(17)
	v_lshlrev_b32_e32 v41, 16, v62
	s_waitcnt vmcnt(16)
	v_lshlrev_b32_e32 v44, 16, v63
	s_waitcnt vmcnt(15)
	v_lshlrev_b32_e32 v45, 16, v64
	v_pk_add_f32 v[40:41], v[40:41], v[42:43]
	v_pk_add_f32 v[42:43], v[44:45], v[46:47]
	v_mul_f32_e32 v57, v129, v127
	v_mul_f32_e32 v58, v129, v130
	v_mov_b32_e32 v44, v42
	v_mov_b32_e32 v45, v41
	v_pk_mov_b32 v[46:47], v[42:43], v[40:41] op_sel:[1,0]
	v_fmac_f32_e32 v48, v128, v119
	v_fmac_f32_e32 v49, v128, v50
	v_fmac_f32_e32 v57, v128, v51
	v_fmac_f32_e32 v58, v128, v52
	s_waitcnt vmcnt(13)
	v_add_f32_e32 v59, v16, v17
	v_pk_add_f32 v[16:17], v[44:45], v[46:47]
	v_sub_f32_e32 v52, v48, v53
	v_sub_f32_e32 v60, v49, v54
	s_waitcnt vmcnt(8)
; __device__ __forceinline__ u16 f2bf(float f) { unsigned u = __float_as_uint(f); u += 0x7fffu + ((u >> 16) & 1u); return (u16)(u >> 16); }
; __device__ __forceinline__ float row16_sum(float x) { x = red8_sum(x); x += dpp_f<0x140>(x); return x; }
; __device__ __forceinline__ void phase_post(const Params& p) {
;     ...
; #pragma unroll
;     for (int j = jh; j < jh + 2; ++j) {
;       float sum = (oy[j][0] + oy[j][1]) + (oy[j][2] + oy[j][3]);
;       sum = row16_sum(sum);
;       const float mean = sum * (1.0f / 64.0f);
;       float sq = 0.f;
; #pragma unroll
;       for (int nt = 0; nt < 4; ++nt) { const float d = oy[j][nt] - mean; sq += d * d; }
;       sq = row16_sum(sq);
;       const float rs = rsqrtf(sq * (1.0f / 64.0f) + 64e-5f);
; #pragma unroll
;       for (int nt = 0; nt < 4; ++nt) {
;         const float v = ovc[j][nt] + muv[nt] * ((ovp[j][nt] + ovn[j][nt]) - ovc[j][nt]);
;         const float o = ((oy[j][nt] - mean) * rs * lw[nt] + lb[nt] + rkv[j] * v) * acc[nt][j];
;         *(u16*)((char*)y + (size_t)yo[j] + nt * 32) = f2bf(o);
;       }
;     }
	v_lshlrev_b32_e32 v45, 16, v70
	v_lshlrev_b32_e32 v44, 16, v66
	v_lshlrev_b32_e32 v47, 16, v67
	v_lshlrev_b32_e32 v46, 16, v65
	s_waitcnt vmcnt(6)
	v_lshlrev_b32_e32 v49, 16, v72
	v_lshlrev_b32_e32 v48, 16, v71
	v_lshlrev_b32_e32 v51, 16, v69
	v_lshlrev_b32_e32 v50, 16, v68
	s_waitcnt vmcnt(5)
	v_add_f32_e32 v61, v20, v21
	v_add_f32_e32 v62, v16, v17
	v_pk_add_f32 v[16:17], v[44:45], v[46:47]
	v_pk_add_f32 v[20:21], v[48:49], v[50:51]
	v_fma_f32 v63, v33, v52, v53
	v_add_f32_dpp v52, v62, v62 quad_perm:[1,0,3,2] row_mask:0xf bank_mask:0xf bound_ctrl:1
	v_mov_b32_e32 v44, v20
	v_mov_b32_e32 v45, v17
	v_pk_mov_b32 v[46:47], v[20:21], v[16:17] op_sel:[1,0]
	s_waitcnt vmcnt(4)
	v_lshlrev_b32_e32 v48, 16, v82
	s_waitcnt vmcnt(3)
	v_lshlrev_b32_e32 v49, 16, v112
	v_add_f32_dpp v52, v52, v52 quad_perm:[2,3,0,1] row_mask:0xf bank_mask:0xf bound_ctrl:1
	v_pk_add_f32 v[44:45], v[44:45], v[46:47]
	v_mul_f32_e32 v48, v74, v48
	v_mul_f32_e32 v49, v74, v49
	v_add_f32_dpp v46, v52, v52 row_half_mirror row_mask:0xf bank_mask:0xf bound_ctrl:1
	v_add_f32_e32 v44, v44, v45
	s_waitcnt vmcnt(2)
	v_lshlrev_b32_e32 v50, 16, v113
	v_fmac_f32_e32 v48, 0.5, v53
	v_fmac_f32_e32 v49, 0.5, v54
	v_add_f32_dpp v45, v46, v46 row_mirror row_mask:0xf bank_mask:0xf bound_ctrl:1
	v_add_f32_dpp v46, v44, v44 quad_perm:[1,0,3,2] row_mask:0xf bank_mask:0xf bound_ctrl:1
	v_lshlrev_b32_e32 v55, 16, v55
	v_mul_f32_e32 v50, v74, v50
	v_sub_f32_e32 v47, v48, v131
	v_sub_f32_e32 v48, v49, v132
	v_mul_f32_e32 v44, 0x3c800000, v45
	v_add_f32_dpp v45, v46, v46 quad_perm:[2,3,0,1] row_mask:0xf bank_mask:0xf bound_ctrl:1
	v_fmac_f32_e32 v50, 0.5, v55
	v_fmac_f32_e32 v132, v34, v48
	v_pk_add_f32 v[42:43], v[42:43], v[44:45] op_sel_hi:[1,0] neg_lo:[0,1] neg_hi:[0,1]
	v_add_f32_dpp v48, v45, v45 row_half_mirror row_mask:0xf bank_mask:0xf bound_ctrl:1
	v_sub_f32_e32 v49, v50, v133
	v_pk_add_f32 v[40:41], v[40:41], v[44:45] op_sel_hi:[1,0] neg_lo:[0,1] neg_hi:[0,1]
	v_pk_mul_f32 v[44:45], v[42:43], v[42:43]
	v_add_f32_dpp v48, v48, v48 row_mirror row_mask:0xf bank_mask:0xf bound_ctrl:1
	s_waitcnt vmcnt(1)
	v_lshlrev_b32_e32 v51, 16, v73
	v_fmac_f32_e32 v133, v35, v49
	v_mul_f32_e32 v48, 0x3c800000, v48
	v_mov_b32_e32 v49, v44
	v_lshlrev_b32_e32 v56, 16, v56
	v_mul_f32_e32 v51, v74, v51
	v_pk_add_f32 v[20:21], v[20:21], v[48:49] op_sel_hi:[1,0] neg_lo:[0,1] neg_hi:[0,1]
	v_sub_f32_e32 v57, v57, v55
	s_waitcnt vmcnt(0)
	v_lshlrev_b32_e32 v39, 16, v39
	v_fmac_f32_e32 v51, 0.5, v56
	v_pk_add_f32 v[16:17], v[16:17], v[48:49] op_sel_hi:[1,0] neg_lo:[0,1] neg_hi:[0,1]
	v_pk_mul_f32 v[52:53], v[20:21], v[20:21]
	v_fma_f32 v60, v34, v60, v54
	v_fma_f32 v57, v35, v57, v55
	v_sub_f32_e32 v50, v51, v39
	v_fmac_f32_e32 v131, v33, v47
	v_pk_mul_f32 v[46:47], v[40:41], v[40:41]
	v_pk_mul_f32 v[54:55], v[16:17], v[16:17]
	v_mov_b32_e32 v48, v52
	v_mov_b32_e32 v44, v53
	v_fmac_f32_e32 v39, v36, v50
	v_mov_b32_e32 v51, v47
	v_mov_b32_e32 v50, v55
	v_pk_add_f32 v[44:45], v[48:49], v[44:45]
	v_mov_b32_e32 v55, v46
	v_pk_add_f32 v[44:45], v[50:51], v[44:45]
	v_sub_f32_e32 v58, v58, v56
	v_pk_add_f32 v[44:45], v[54:55], v[44:45]
	v_fma_f32 v58, v36, v58, v56
	s_nop 0
	v_mov_b32_dpp v47, v45 quad_perm:[1,0,3,2] row_mask:0xf bank_mask:0xf bound_ctrl:1
	v_mov_b32_dpp v46, v44 quad_perm:[1,0,3,2] row_mask:0xf bank_mask:0xf bound_ctrl:1
	v_pk_add_f32 v[44:45], v[44:45], v[46:47]
	s_nop 1
	v_mov_b32_dpp v47, v45 quad_perm:[2,3,0,1] row_mask:0xf bank_mask:0xf bound_ctrl:1
	v_mov_b32_dpp v46, v44 quad_perm:[2,3,0,1] row_mask:0xf bank_mask:0xf bound_ctrl:1
	v_pk_add_f32 v[44:45], v[44:45], v[46:47]
	s_nop 1
	v_mov_b32_dpp v47, v45 row_half_mirror row_mask:0xf bank_mask:0xf bound_ctrl:1
	v_mov_b32_dpp v46, v44 row_half_mirror row_mask:0xf bank_mask:0xf bound_ctrl:1
	v_pk_add_f32 v[44:45], v[44:45], v[46:47]
	s_nop 1
	v_mov_b32_dpp v47, v45 row_mirror row_mask:0xf bank_mask:0xf bound_ctrl:1
	v_mov_b32_dpp v46, v44 row_mirror row_mask:0xf bank_mask:0xf bound_ctrl:1
	v_pk_add_f32 v[44:45], v[44:45], v[46:47]
	s_nop 0
	v_pk_fma_f32 v[44:45], v[44:45], s[40:41], v[108:109] op_sel_hi:[1,0,0]
	s_nop 0
	v_mul_f32_e32 v46, 0x4b800000, v45
	v_cmp_gt_f32_e64 s[0:1], s48, v45
	v_mul_f32_e32 v47, 0x4b800000, v44
	v_cmp_gt_f32_e32 vcc, s48, v44
	v_cndmask_b32_e64 v45, v45, v46, s[0:1]
	v_rsq_f32_e32 v45, v45
	v_cndmask_b32_e32 v44, v44, v47, vcc
	v_rsq_f32_e32 v44, v44
	v_mul_f32_e32 v46, 0x45800000, v45
	v_cndmask_b32_e64 v45, v45, v46, s[0:1]
	v_mul_f32_e32 v47, 0x45800000, v44
	v_cndmask_b32_e32 v44, v44, v47, vcc
	v_mul_f32_e32 v42, v42, v45
	v_mul_f32_e32 v43, v43, v45
	v_mul_f32_e32 v41, v41, v45
	v_mul_f32_e32 v40, v40, v45
	v_mul_f32_e32 v20, v20, v44
	v_mul_f32_e32 v21, v21, v44
	v_mul_f32_e32 v17, v17, v44
	v_mul_f32_e32 v16, v16, v44
	v_fma_f32 v42, v28, v42, v24
	v_fma_f32 v43, v29, v43, v25
	v_fma_f32 v41, v30, v41, v26
	v_fma_f32 v40, v31, v40, v27
	v_fma_f32 v20, v28, v20, v24
	v_fma_f32 v21, v29, v21, v25
	v_fma_f32 v17, v30, v17, v26
	v_fma_f32 v16, v31, v16, v27
	v_fmac_f32_e32 v42, v63, v59
	v_fmac_f32_e32 v43, v60, v59
	v_fmac_f32_e32 v41, v59, v57
	v_fmac_f32_e32 v40, v59, v58
	v_fmac_f32_e32 v20, v131, v61
	v_fmac_f32_e32 v21, v132, v61
	v_fmac_f32_e32 v17, v61, v133
	v_fmac_f32_e32 v16, v61, v39
	v_mul_f32_e32 v0, v0, v42
	v_mul_f32_e32 v4, v4, v43
	v_mul_f32_e32 v8, v8, v41
	v_mul_f32_e32 v12, v12, v40
	v_mul_f32_e32 v1, v1, v20
	v_mul_f32_e32 v5, v5, v21
	v_mul_f32_e32 v9, v9, v17
	v_mul_f32_e32 v13, v13, v16
	v_cvt_pk_bf16_f32 v0, v0, v0
	v_cvt_pk_bf16_f32 v4, v4, v4
	v_cvt_pk_bf16_f32 v8, v8, v8
	v_cvt_pk_bf16_f32 v12, v12, v12
	v_cvt_pk_bf16_f32 v1, v1, v1
	v_cvt_pk_bf16_f32 v5, v5, v5
	v_cvt_pk_bf16_f32 v9, v9, v9
; __device__ __forceinline__ u16 f2bf(float f) { unsigned u = __float_as_uint(f); u += 0x7fffu + ((u >> 16) & 1u); return (u16)(u >> 16); }
; __device__ __forceinline__ float bf2f(u16 h) { return __uint_as_float(((unsigned)h) << 16); }
; __device__ __forceinline__ void phase_post(const Params& p) {
;     ...
;     for (int j = jh; j < jh + 2; ++j) {
;       const unsigned row = (unsigned)tt * 16u + (unsigned)(fq * 4 + j);
;       bool hp, hn; seq_bounds((long)row, hp, hn);
;       yo[j] = (row * (unsigned)DM + 1024u + (unsigned)(64 * head + fr)) * 2u;
;       const unsigned obo = (row * 1024u + (unsigned)(64 * head + fr)) * 2u;
;       const unsigned zo = (row * (unsigned)NRWP + 2048u + (unsigned)(64 * head + fr)) * 2u;
;       const unsigned zpo = zo - (hp ? (unsigned)NRWP * 2u : 0u), zno = zo + (hn ? (unsigned)NRWP * 2u : 0u);
;       const float mp = hp ? 0.5f : 0.f, mn = hn ? 0.5f : 0.f;
; #pragma unroll
;       for (int nt = 0; nt < 4; ++nt) {
;         oy[j][nt] = bf2f(*(const u16*)((const char*)y + (size_t)yo[j] + nt * 32)) + bf2f(*(const u16*)((const char*)ob + (size_t)obo + nt * 32));
;         ovc[j][nt] = bf2f(*(const u16*)((const char*)zr + (size_t)zo + nt * 32));
;         ovp[j][nt] = bf2f(*(const u16*)((const char*)zr + (size_t)zpo + nt * 32)) * mp;
;         ovn[j][nt] = bf2f(*(const u16*)((const char*)zr + (size_t)zno + nt * 32)) * mn;
;       }
;       rkv[j] = rkbuf[(size_t)row * 32 + head * 2] + rkbuf[(size_t)row * 32 + head * 2 + 1];
;     }
;     ...
;         *(u16*)((char*)y + (size_t)yo[j] + nt * 32) = f2bf(o);
	v_cvt_pk_bf16_f32 v13, v13, v13
	global_store_short_d16_hi v111, v0, s[12:13]
	global_store_short_d16_hi v111, v4, s[12:13] offset:32
	global_store_short_d16_hi v111, v8, s[12:13] offset:64
	global_store_short_d16_hi v111, v12, s[12:13] offset:96
	global_store_short_d16_hi v38, v1, s[12:13]
	global_store_short_d16_hi v38, v5, s[12:13] offset:32
	global_store_short_d16_hi v38, v9, s[12:13] offset:64
	global_store_short_d16_hi v38, v13, s[12:13] offset:96
	global_load_ushort v8, v76, s[72:73]
	global_load_ushort v9, v76, s[72:73] offset:32
	global_load_ushort v12, v75, s[72:73]
	global_load_ushort v13, v114, s[72:73]
	global_load_ushort v16, v75, s[72:73] offset:32
	global_load_ushort v17, v114, s[72:73] offset:32
	global_load_ushort v20, v75, s[72:73] offset:64
	global_load_ushort v21, v114, s[72:73] offset:64
	global_load_ushort v38, v114, s[72:73] offset:96
	global_load_ushort v39, v75, s[72:73] offset:96
	global_load_ushort v40, v76, s[72:73] offset:64
	global_load_ushort v41, v76, s[72:73] offset:96
	global_load_dwordx2 v[0:1], v[22:23], off
	s_nop 0
	global_load_ushort v22, v77, s[72:73]
	global_load_ushort v23, v77, s[72:73] offset:32
	global_load_ushort v42, v116, s[72:73]
	global_load_ushort v43, v78, s[72:73]
	global_load_ushort v44, v116, s[72:73] offset:32
	global_load_ushort v45, v78, s[72:73] offset:32
	global_load_ushort v46, v116, s[72:73] offset:64
	global_load_ushort v47, v78, s[72:73] offset:64
	global_load_ushort v48, v78, s[72:73] offset:96
	global_load_ushort v49, v116, s[72:73] offset:96
	global_load_ushort v50, v77, s[72:73] offset:64
	global_load_ushort v51, v77, s[72:73] offset:96
	global_load_dwordx2 v[4:5], v[18:19], off
	s_nop 0
	global_load_ushort v18, v37, s[14:15] offset:32
	global_load_ushort v19, v32, s[12:13] offset:64
	global_load_ushort v52, v37, s[14:15] offset:64
	global_load_ushort v53, v37, s[14:15] offset:96
	global_load_ushort v54, v32, s[12:13] offset:96
	s_nop 0
	global_load_ushort v37, v37, s[14:15]
	s_nop 0
	global_load_ushort v55, v32, s[12:13] offset:32
	global_load_ushort v56, v32, s[12:13]
	global_load_ushort v57, v110, s[14:15] offset:32
	global_load_ushort v58, v79, s[12:13] offset:64
	global_load_ushort v59, v110, s[14:15] offset:64
	global_load_ushort v60, v79, s[12:13] offset:96
	global_load_ushort v61, v110, s[14:15] offset:96
	global_load_ushort v62, v79, s[12:13] offset:32
	global_load_ushort v63, v79, s[12:13]
	global_load_ushort v64, v110, s[14:15]
	s_waitcnt vmcnt(41)
	v_lshlrev_b32_e32 v67, 16, v8
	s_waitcnt vmcnt(40)
	v_lshlrev_b32_e32 v70, 16, v9
	s_waitcnt vmcnt(39)
	v_lshlrev_b32_e32 v65, 16, v12
	s_waitcnt vmcnt(38)
	v_lshlrev_b32_e32 v66, 16, v13
	s_waitcnt vmcnt(37)
	v_lshlrev_b32_e32 v68, 16, v16
	s_waitcnt vmcnt(36)
	v_lshlrev_b32_e32 v69, 16, v17
	s_waitcnt vmcnt(35)
	v_lshlrev_b32_e32 v71, 16, v20
	s_waitcnt vmcnt(34)
	v_lshlrev_b32_e32 v72, 16, v21
	s_waitcnt vmcnt(33)
	v_lshlrev_b32_e32 v38, 16, v38
	s_waitcnt vmcnt(32)
	v_lshlrev_b32_e32 v39, 16, v39
	s_waitcnt vmcnt(31)
	v_lshlrev_b32_e32 v40, 16, v40
	s_waitcnt vmcnt(30)
	v_lshlrev_b32_e32 v41, 16, v41
	s_waitcnt vmcnt(29)
	v_add_f32_e32 v73, v0, v1
	s_waitcnt vmcnt(28)
	v_lshlrev_b32_e32 v74, 16, v22
	s_waitcnt vmcnt(27)
	v_lshlrev_b32_e32 v75, 16, v23
	s_waitcnt vmcnt(26)
	v_lshlrev_b32_e32 v42, 16, v42
	s_waitcnt vmcnt(25)
	v_lshlrev_b32_e32 v43, 16, v43
	s_waitcnt vmcnt(24)
	v_lshlrev_b32_e32 v44, 16, v44
	s_waitcnt vmcnt(23)
	v_lshlrev_b32_e32 v45, 16, v45
	v_mul_f32_e32 v40, v115, v40
	s_waitcnt vmcnt(21)
	v_lshlrev_b32_e32 v47, 16, v47
	s_waitcnt vmcnt(20)
	v_lshlrev_b32_e32 v48, 16, v48
	v_lshlrev_b32_e32 v46, 16, v46
	s_waitcnt vmcnt(18)
	v_lshlrev_b32_e32 v50, 16, v50
	s_waitcnt vmcnt(17)
	v_lshlrev_b32_e32 v51, 16, v51
	s_waitcnt vmcnt(16)
	v_add_f32_e32 v76, v4, v5
	s_waitcnt vmcnt(15)
	v_lshlrev_b32_e32 v13, 16, v18
	s_waitcnt vmcnt(14)
	v_lshlrev_b32_e32 v1, 16, v19
	s_waitcnt vmcnt(13)
	v_lshlrev_b32_e32 v5, 16, v52
	s_waitcnt vmcnt(12)
	v_lshlrev_b32_e32 v4, 16, v53
	s_waitcnt vmcnt(11)
	v_lshlrev_b32_e32 v0, 16, v54
	s_waitcnt vmcnt(10)
	v_lshlrev_b32_e32 v12, 16, v37
	s_waitcnt vmcnt(9)
	v_lshlrev_b32_e32 v9, 16, v55
	s_waitcnt vmcnt(8)
	v_lshlrev_b32_e32 v8, 16, v56
	s_waitcnt vmcnt(7)
	v_lshlrev_b32_e32 v23, 16, v57
	s_waitcnt vmcnt(6)
	v_lshlrev_b32_e32 v17, 16, v58
	s_waitcnt vmcnt(5)
	v_lshlrev_b32_e32 v19, 16, v59
	s_waitcnt vmcnt(4)
	v_lshlrev_b32_e32 v16, 16, v60
	s_waitcnt vmcnt(3)
	v_lshlrev_b32_e32 v18, 16, v61
	s_waitcnt vmcnt(2)
	v_lshlrev_b32_e32 v21, 16, v62
	s_waitcnt vmcnt(1)
	v_lshlrev_b32_e32 v20, 16, v63
	s_waitcnt vmcnt(0)
; __device__ __forceinline__ u16 f2bf(float f) { unsigned u = __float_as_uint(f); u += 0x7fffu + ((u >> 16) & 1u); return (u16)(u >> 16); }
; __device__ __forceinline__ float row16_sum(float x) { x = red8_sum(x); x += dpp_f<0x140>(x); return x; }
; __device__ __forceinline__ void phase_post(const Params& p) {
;     ...
; #pragma unroll
;     for (int j = jh; j < jh + 2; ++j) {
;       float sum = (oy[j][0] + oy[j][1]) + (oy[j][2] + oy[j][3]);
;       sum = row16_sum(sum);
;       const float mean = sum * (1.0f / 64.0f);
;       float sq = 0.f;
; #pragma unroll
;       for (int nt = 0; nt < 4; ++nt) { const float d = oy[j][nt] - mean; sq += d * d; }
;       sq = row16_sum(sq);
;       const float rs = rsqrtf(sq * (1.0f / 64.0f) + 64e-5f);
; #pragma unroll
;       for (int nt = 0; nt < 4; ++nt) {
;         const float v = ovc[j][nt] + muv[nt] * ((ovp[j][nt] + ovn[j][nt]) - ovc[j][nt]);
;         const float o = ((oy[j][nt] - mean) * rs * lw[nt] + lb[nt] + rkv[j] * v) * acc[nt][j];
;         *(u16*)((char*)y + (size_t)yo[j] + nt * 32) = f2bf(o);
;       }
;     }
	v_lshlrev_b32_e32 v22, 16, v64
	v_pk_add_f32 v[0:1], v[0:1], v[4:5]
	v_pk_add_f32 v[4:5], v[8:9], v[12:13]
	v_pk_add_f32 v[8:9], v[16:17], v[18:19]
	v_pk_add_f32 v[12:13], v[20:21], v[22:23]
	v_mov_b32_e32 v16, v4
	v_mov_b32_e32 v17, v1
	v_pk_mov_b32 v[18:19], v[4:5], v[0:1] op_sel:[1,0]
	v_mov_b32_e32 v20, v12
	v_mov_b32_e32 v21, v9
	v_pk_mov_b32 v[22:23], v[12:13], v[8:9] op_sel:[1,0]
	v_pk_add_f32 v[16:17], v[16:17], v[18:19]
	v_pk_add_f32 v[18:19], v[20:21], v[22:23]
	v_add_f32_e32 v16, v16, v17
	v_add_f32_e32 v17, v18, v19
	v_mul_f32_e32 v53, v118, v74
	v_add_f32_dpp v16, v16, v16 quad_perm:[1,0,3,2] row_mask:0xf bank_mask:0xf bound_ctrl:1
	v_add_f32_dpp v17, v17, v17 quad_perm:[1,0,3,2] row_mask:0xf bank_mask:0xf bound_ctrl:1
	v_mul_f32_e32 v54, v118, v75
	v_add_f32_dpp v16, v16, v16 quad_perm:[2,3,0,1] row_mask:0xf bank_mask:0xf bound_ctrl:1
	v_add_f32_dpp v17, v17, v17 quad_perm:[2,3,0,1] row_mask:0xf bank_mask:0xf bound_ctrl:1
	v_mul_f32_e32 v52, v115, v70
	v_add_f32_dpp v16, v16, v16 row_half_mirror row_mask:0xf bank_mask:0xf bound_ctrl:1
	v_add_f32_dpp v17, v17, v17 row_half_mirror row_mask:0xf bank_mask:0xf bound_ctrl:1
	v_mul_f32_e32 v50, v118, v50
	v_add_f32_dpp v16, v16, v16 row_mirror row_mask:0xf bank_mask:0xf bound_ctrl:1
	v_add_f32_dpp v17, v17, v17 row_mirror row_mask:0xf bank_mask:0xf bound_ctrl:1
	v_mul_f32_e32 v51, v118, v51
	v_fmac_f32_e32 v53, v117, v43
	v_fmac_f32_e32 v54, v117, v45
	v_mul_f32_e32 v16, 0x3c800000, v16
	v_mul_f32_e32 v18, 0x3c800000, v17
	v_lshlrev_b32_e32 v49, 16, v49
	v_mul_f32_e32 v41, v115, v41
	v_fmac_f32_e32 v52, 0.5, v69
	v_fmac_f32_e32 v40, 0.5, v72
	v_fmac_f32_e32 v50, v117, v47
	v_fmac_f32_e32 v51, v117, v48
	v_sub_f32_e32 v20, v53, v42
	v_sub_f32_e32 v21, v54, v44
	v_pk_add_f32 v[4:5], v[4:5], v[16:17] op_sel_hi:[1,0] neg_lo:[0,1] neg_hi:[0,1]
	v_pk_add_f32 v[12:13], v[12:13], v[18:19] op_sel_hi:[1,0] neg_lo:[0,1] neg_hi:[0,1]
	v_fmac_f32_e32 v41, 0.5, v38
	v_sub_f32_e32 v38, v52, v68
	v_sub_f32_e32 v40, v40, v71
	v_sub_f32_e32 v22, v50, v46
	v_sub_f32_e32 v23, v51, v49
	v_fmac_f32_e32 v42, v33, v20
	v_fmac_f32_e32 v44, v34, v21
	v_pk_add_f32 v[0:1], v[0:1], v[16:17] op_sel_hi:[1,0] neg_lo:[0,1] neg_hi:[0,1]
	v_pk_add_f32 v[8:9], v[8:9], v[18:19] op_sel_hi:[1,0] neg_lo:[0,1] neg_hi:[0,1]
	v_pk_mul_f32 v[16:17], v[4:5], v[4:5]
	v_pk_mul_f32 v[20:21], v[12:13], v[12:13]
	v_fmac_f32_e32 v68, v34, v38
	v_fmac_f32_e32 v71, v35, v40
	v_fmac_f32_e32 v46, v35, v22
	v_fmac_f32_e32 v49, v36, v23
	v_pk_mul_f32 v[18:19], v[0:1], v[0:1]
	v_pk_mul_f32 v[22:23], v[8:9], v[8:9]
	v_mov_b32_e32 v34, v20
	v_mov_b32_e32 v35, v16
	v_mov_b32_e32 v16, v21
	v_mov_b32_e32 v20, v23
	v_mov_b32_e32 v21, v19
	v_pk_add_f32 v[16:17], v[34:35], v[16:17]
	v_mov_b32_e32 v23, v18
	v_pk_add_f32 v[16:17], v[20:21], v[16:17]
	v_mul_f32_e32 v37, v115, v67
	v_pk_add_f32 v[16:17], v[22:23], v[16:17]
	v_fmac_f32_e32 v37, 0.5, v66
	v_sub_f32_e32 v37, v37, v65
	v_mov_b32_dpp v19, v17 quad_perm:[1,0,3,2] row_mask:0xf bank_mask:0xf bound_ctrl:1
	v_mov_b32_dpp v18, v16 quad_perm:[1,0,3,2] row_mask:0xf bank_mask:0xf bound_ctrl:1
	v_pk_add_f32 v[16:17], v[16:17], v[18:19]
	v_sub_f32_e32 v41, v41, v39
	v_fmac_f32_e32 v65, v33, v37
	v_mov_b32_dpp v19, v17 quad_perm:[2,3,0,1] row_mask:0xf bank_mask:0xf bound_ctrl:1
	v_mov_b32_dpp v18, v16 quad_perm:[2,3,0,1] row_mask:0xf bank_mask:0xf bound_ctrl:1
	v_pk_add_f32 v[16:17], v[16:17], v[18:19]
	v_fmac_f32_e32 v39, v36, v41
	s_nop 0
	v_mov_b32_dpp v19, v17 row_half_mirror row_mask:0xf bank_mask:0xf bound_ctrl:1
	v_mov_b32_dpp v18, v16 row_half_mirror row_mask:0xf bank_mask:0xf bound_ctrl:1
	v_pk_add_f32 v[16:17], v[16:17], v[18:19]
	s_nop 1
	v_mov_b32_dpp v19, v17 row_mirror row_mask:0xf bank_mask:0xf bound_ctrl:1
	v_mov_b32_dpp v18, v16 row_mirror row_mask:0xf bank_mask:0xf bound_ctrl:1
	v_pk_add_f32 v[16:17], v[16:17], v[18:19]
	s_nop 0
	v_pk_fma_f32 v[16:17], v[16:17], s[40:41], v[108:109] op_sel_hi:[1,0,0]
	s_nop 0
	v_mul_f32_e32 v18, 0x4b800000, v17
	v_cmp_gt_f32_e64 s[0:1], s48, v17
	v_mul_f32_e32 v19, 0x4b800000, v16
	v_cmp_gt_f32_e32 vcc, s48, v16
	v_cndmask_b32_e64 v17, v17, v18, s[0:1]
	v_rsq_f32_e32 v17, v17
	v_cndmask_b32_e32 v16, v16, v19, vcc
	v_rsq_f32_e32 v16, v16
	v_mul_f32_e32 v18, 0x45800000, v17
	v_cndmask_b32_e64 v17, v17, v18, s[0:1]
	v_mul_f32_e32 v19, 0x45800000, v16
	v_cndmask_b32_e32 v16, v16, v19, vcc
	v_mul_f32_e32 v4, v4, v17
	v_mul_f32_e32 v5, v5, v17
	v_mul_f32_e32 v1, v1, v17
	v_mul_f32_e32 v0, v0, v17
	v_mul_f32_e32 v12, v12, v16
	v_mul_f32_e32 v13, v13, v16
	v_mul_f32_e32 v9, v9, v16
	v_mul_f32_e32 v8, v8, v16
	v_fma_f32 v4, v28, v4, v24
	v_fma_f32 v5, v29, v5, v25
	v_fma_f32 v1, v30, v1, v26
	v_fma_f32 v0, v31, v0, v27
	v_fmac_f32_e32 v24, v28, v12
	v_fmac_f32_e32 v25, v29, v13
	v_fmac_f32_e32 v26, v30, v9
	v_fmac_f32_e32 v27, v31, v8
	v_fmac_f32_e32 v4, v65, v73
	v_fmac_f32_e32 v5, v68, v73
	v_fmac_f32_e32 v1, v73, v71
	v_fmac_f32_e32 v0, v73, v39
	v_fmac_f32_e32 v24, v42, v76
	v_fmac_f32_e32 v25, v44, v76
	v_fmac_f32_e32 v26, v76, v46
	v_fmac_f32_e32 v27, v76, v49
	v_mul_f32_e32 v2, v2, v4
	v_mul_f32_e32 v4, v6, v5
	v_mul_f32_e32 v1, v10, v1
	v_mul_f32_e32 v0, v14, v0
	v_mul_f32_e32 v3, v3, v24
	v_mul_f32_e32 v5, v7, v25
	v_mul_f32_e32 v6, v11, v26
	v_mul_f32_e32 v7, v15, v27
	v_bfe_u32 v8, v2, 16, 1
	v_bfe_u32 v9, v4, 16, 1
	v_bfe_u32 v10, v1, 16, 1
	v_bfe_u32 v11, v0, 16, 1
	v_bfe_u32 v12, v3, 16, 1
	v_bfe_u32 v13, v5, 16, 1
	v_bfe_u32 v14, v6, 16, 1
	v_bfe_u32 v15, v7, 16, 1
	v_add3_u32 v2, v2, v8, s49
	v_add3_u32 v4, v4, v9, s49
	v_add3_u32 v1, v1, v10, s49
	v_add3_u32 v0, v0, v11, s49
	v_add3_u32 v3, v3, v12, s49
	v_add3_u32 v5, v5, v13, s49
	v_add3_u32 v6, v6, v14, s49
	v_add3_u32 v7, v7, v15, s49
	global_store_short_d16_hi v32, v2, s[12:13]
	global_store_short_d16_hi v32, v4, s[12:13] offset:32
	global_store_short_d16_hi v32, v1, s[12:13] offset:64
	global_store_short_d16_hi v32, v0, s[12:13] offset:96
	global_store_short_d16_hi v79, v3, s[12:13]
	global_store_short_d16_hi v79, v5, s[12:13] offset:32
	global_store_short_d16_hi v79, v6, s[12:13] offset:64
	global_store_short_d16_hi v79, v7, s[12:13] offset:96
	v_cmp_lt_i32_e32 vcc, s51, v81
	s_or_b64 s[16:17], vcc, s[16:17]
	s_andn2_b64 exec, exec, s[16:17]
	s_cbranch_execnz .LBB0_1365

; __device__ __forceinline__ int opaque_tid() { int t; asm volatile("v_mov_b32 %0, %1" : "=v"(t) : "v"((int)threadIdx.x)); return t; }
; #define STAGE(P, BASE, kt) do { const char* _g = (const char*)(BASE) + (size_t)((kt) * (BK * 2)); \
;     __builtin_amdgcn_global_load_lds((const unsigned*)(_g + (size_t)goff0), (unsigned*)((char*)(P) + tid_ * 16), 16, 0, 0); \
;     __builtin_amdgcn_global_load_lds((const unsigned*)(_g + (size_t)goff1), (unsigned*)((char*)(P) + tid_ * 16 + 8192), 16, 0, 0); } while (0)
; #define STAGEA(P, BASE, kt) do { const char* _g = (const char*)(BASE) + (size_t)((kt) * a_kbytes); \
;     __builtin_amdgcn_global_load_lds((const unsigned*)(_g + (size_t)goffA0), (unsigned*)((char*)(P) + tid_ * 16), 16, 0, 0); \
;     __builtin_amdgcn_global_load_lds((const unsigned*)(_g + (size_t)goffA1), (unsigned*)((char*)(P) + tid_ * 16 + 8192), 16, 0, 0); } while (0)
; #define WAIT_V(n) asm volatile("s_waitcnt vmcnt(" #n ")" ::: "memory")
; #define BAR __builtin_amdgcn_s_barrier()
; template <int EPI> ...
;     ...
;   const int tid_ = opaque_tid();
;   const int wid = tid_ >> 6, lane = tid_ & 63, wr = wid >> 2, wc = wid & 3, fr = lane & 15, fq = lane >> 4;
;   f32x4 acc[2][2][4][2] = {};
;   bf16x8 At[4][2], B0[2][2], B1[2][2];
;   const int nt = K / BK;
;   STAGE(SB(0, 0), B0p, 0); STAGEA(SA(0, 0), A0, 0);
;   STAGE(SB(0, 1), B1p, 0); STAGEA(SA(0, 1), A1, 0);
;   if (wr == 1) BAR;
;   WAIT_V(4); BAR;
;   STAGE(SB(1, 0), B0p, 1); STAGEA(SA(1, 0), A0, 1); STAGE(SB(1, 1), B1p, 1);
;   WAIT_V(6); BAR;
;   for (int t = 0; t < nt - 2; t += 2) {
.LBB0_1381:
	s_or_b64 exec, exec, s[42:43]
	v_add_u32_e32 v164, s52, v8
	v_add_u32_e32 v165, 0x2000, v164
	v_readfirstlane_b32 s23, v164
	v_lshl_add_u64 v[0:1], v[0:1], 0, s[0:1]
	s_mov_b32 m0, s23
	v_readfirstlane_b32 s23, v165
	v_add_u32_e32 v166, 0x8000, v158
	s_lshl_b64 s[24:25], s[24:25], 11
	s_waitcnt vmcnt(4)
	s_barrier
	global_load_lds_dwordx4 v[0:1], off
	v_lshl_add_u64 v[0:1], v[2:3], 0, s[0:1]
	s_mov_b32 m0, s23
	v_readfirstlane_b32 s23, v166
	v_add_u32_e32 v167, 0xa000, v158
	global_load_lds_dwordx4 v[0:1], off
	v_lshl_add_u64 v[0:1], v[4:5], 0, s[0:1]
	s_mov_b32 m0, s23
	v_readfirstlane_b32 s23, v167
	s_add_u32 s40, s40, 0x80080
	v_add_u32_e32 v169, s53, v8
	global_load_lds_dwordx4 v[0:1], off
	v_lshl_add_u64 v[0:1], v[6:7], 0, s[0:1]
	s_mov_b32 m0, s23
	s_addc_u32 s41, s41, 0
	v_readfirstlane_b32 s23, v169
	v_add_u32_e32 v170, 0x2000, v169
	global_load_lds_dwordx4 v[0:1], off
	v_lshl_add_u64 v[0:1], s[40:41], 0, v[130:131]
	s_mov_b32 m0, s23
	v_readfirstlane_b32 s23, v170
	global_load_lds_dwordx4 v[0:1], off
	v_lshl_add_u64 v[0:1], s[40:41], 0, v[128:129]
	s_mov_b32 m0, s23
	v_and_b32_e32 v149, 15, v144
	global_load_lds_dwordx4 v[0:1], off
	v_bfe_u32 v145, v144, 4, 2
	v_lshlrev_b32_e32 v3, 2, v144
	v_lshlrev_b32_e32 v0, 4, v145
	v_lshlrev_b32_e32 v2, 6, v149
	v_and_b32_e32 v3, 32, v3
	v_lshlrev_b32_e32 v9, 6, v144
	v_lshl_add_u64 v[136:137], v[132:133], 0, s[38:39]
	v_lshl_add_u64 v[138:139], v[134:135], 0, s[38:39]
	s_add_i32 s38, s60, s61
	v_bfe_u32 v148, v144, 6, 2
	s_waitcnt vmcnt(6)
	v_bitop3_b32 v2, v0, v3, v2 bitop3:0x36
	v_lshlrev_b32_e32 v8, 13, v147
	v_and_or_b32 v0, v9, s54, v0
	s_ashr_i32 s39, s38, 31
	v_lshlrev_b32_e32 v1, 12, v148
	v_add_u32_e32 v4, s50, v2
	v_add_u32_e32 v5, s51, v2
	v_add_u32_e32 v6, s52, v2
	v_add_u32_e32 v7, s53, v2
	v_add_u32_e32 v2, 0, v2
	v_xad_u32 v3, v0, v3, 0
	v_or_b32_e32 v9, 0x800, v8
	v_or_b32_e32 v10, 0x1000, v8
	v_or_b32_e32 v11, 0x1800, v8
	s_lshl_b64 s[38:39], s[38:39], 12
	v_mov_b32_e32 v0, 0
	v_lshl_add_u64 v[140:141], v[132:133], 0, s[38:39]
	v_lshl_add_u64 v[142:143], v[134:135], 0, s[38:39]
	s_mov_b32 s23, -2
	v_add_u32_e32 v171, v4, v1
	v_add_u32_e32 v153, v2, v8
	v_add_u32_e32 v152, v3, v9
	v_add_u32_e32 v151, v3, v10
	v_add_u32_e32 v150, v3, v11
	v_add_u32_e32 v168, v5, v1
	v_add_u32_e32 v157, v6, v1
	v_add_u32_e32 v154, v7, v1
	s_mov_b64 s[38:39], s[74:75]
	v_mov_b32_e32 v1, v0
	v_mov_b32_e32 v2, v0
	v_mov_b32_e32 v3, v0
	v_mov_b32_e32 v4, v0
	v_mov_b32_e32 v5, v0
	v_mov_b32_e32 v6, v0
	v_mov_b32_e32 v7, v0
	v_mov_b32_e32 v8, v0
	v_mov_b32_e32 v9, v0
	v_mov_b32_e32 v10, v0
	v_mov_b32_e32 v11, v0
	v_mov_b32_e32 v12, v0
	v_mov_b32_e32 v13, v0
	v_mov_b32_e32 v14, v0
	v_mov_b32_e32 v15, v0
	v_mov_b32_e32 v16, v0
	v_mov_b32_e32 v17, v0
	v_mov_b32_e32 v18, v0
	v_mov_b32_e32 v19, v0
	v_mov_b32_e32 v20, v0
	v_mov_b32_e32 v21, v0
	v_mov_b32_e32 v22, v0
	v_mov_b32_e32 v23, v0
	v_mov_b32_e32 v24, v0
	v_mov_b32_e32 v25, v0
	v_mov_b32_e32 v26, v0
	v_mov_b32_e32 v27, v0
	v_mov_b32_e32 v28, v0
	v_mov_b32_e32 v29, v0
	v_mov_b32_e32 v30, v0
	v_mov_b32_e32 v31, v0
	v_mov_b32_e32 v32, v0
	v_mov_b32_e32 v33, v0
	v_mov_b32_e32 v34, v0
	v_mov_b32_e32 v35, v0
	v_mov_b32_e32 v36, v0
	v_mov_b32_e32 v37, v0
	v_mov_b32_e32 v38, v0
	v_mov_b32_e32 v39, v0
	v_mov_b32_e32 v40, v0
	v_mov_b32_e32 v41, v0
	v_mov_b32_e32 v42, v0
	v_mov_b32_e32 v43, v0
	v_mov_b32_e32 v44, v0
	v_mov_b32_e32 v45, v0
	v_mov_b32_e32 v46, v0
	v_mov_b32_e32 v47, v0
	v_mov_b32_e32 v48, v0
	v_mov_b32_e32 v49, v0
	v_mov_b32_e32 v50, v0
	v_mov_b32_e32 v51, v0
	v_mov_b32_e32 v52, v0
	v_mov_b32_e32 v53, v0
	v_mov_b32_e32 v54, v0
	v_mov_b32_e32 v55, v0
	v_mov_b32_e32 v56, v0
	v_mov_b32_e32 v57, v0
	v_mov_b32_e32 v58, v0
	v_mov_b32_e32 v59, v0
	v_mov_b32_e32 v60, v0
	v_mov_b32_e32 v61, v0
	v_mov_b32_e32 v62, v0
	v_mov_b32_e32 v63, v0
	v_mov_b32_e32 v64, v0
	v_mov_b32_e32 v65, v0
	v_mov_b32_e32 v66, v0
	v_mov_b32_e32 v67, v0
	v_mov_b32_e32 v68, v0
	v_mov_b32_e32 v69, v0
	v_mov_b32_e32 v70, v0
	v_mov_b32_e32 v71, v0
	v_mov_b32_e32 v72, v0
	v_mov_b32_e32 v73, v0
	v_mov_b32_e32 v74, v0
	v_mov_b32_e32 v75, v0
	v_mov_b32_e32 v76, v0
	v_mov_b32_e32 v77, v0
	v_mov_b32_e32 v78, v0
	v_mov_b32_e32 v79, v0
	v_mov_b32_e32 v80, v0
	v_mov_b32_e32 v81, v0
	v_mov_b32_e32 v82, v0
	v_mov_b32_e32 v83, v0
	v_mov_b32_e32 v84, v0
	v_mov_b32_e32 v85, v0
	v_mov_b32_e32 v86, v0
	v_mov_b32_e32 v87, v0
	v_mov_b32_e32 v88, v0
	v_mov_b32_e32 v89, v0
	v_mov_b32_e32 v90, v0
	v_mov_b32_e32 v91, v0
	v_mov_b32_e32 v92, v0
	v_mov_b32_e32 v93, v0
	v_mov_b32_e32 v94, v0
	v_mov_b32_e32 v95, v0
	v_mov_b32_e32 v96, v0
	v_mov_b32_e32 v97, v0
	v_mov_b32_e32 v98, v0
	v_mov_b32_e32 v99, v0
	v_mov_b32_e32 v100, v0
	v_mov_b32_e32 v101, v0
	v_mov_b32_e32 v102, v0
	v_mov_b32_e32 v103, v0
	v_mov_b32_e32 v104, v0
	v_mov_b32_e32 v105, v0
	v_mov_b32_e32 v106, v0
	v_mov_b32_e32 v107, v0
	v_mov_b32_e32 v108, v0
	v_mov_b32_e32 v109, v0
	v_mov_b32_e32 v110, v0
	v_mov_b32_e32 v111, v0
	v_mov_b32_e32 v112, v0
	v_mov_b32_e32 v113, v0
	v_mov_b32_e32 v114, v0
	v_mov_b32_e32 v115, v0
	v_mov_b32_e32 v116, v0
	v_mov_b32_e32 v117, v0
	v_mov_b32_e32 v118, v0
	v_mov_b32_e32 v119, v0
	v_mov_b32_e32 v120, v0
	v_mov_b32_e32 v121, v0
	v_mov_b32_e32 v122, v0
	v_mov_b32_e32 v123, v0
	v_mov_b32_e32 v124, v0
	v_mov_b32_e32 v125, v0
	v_mov_b32_e32 v126, v0
	v_mov_b32_e32 v127, v0
	s_barrier
	ds_read_b128 v[174:177], v171
	ds_read_b128 v[178:181], v171 offset:1024
	ds_read_b128 v[182:185], v171 offset:2048
	ds_read_b128 v[186:189], v171 offset:3072
; #define STAGE(P, BASE, kt) do { const char* _g = (const char*)(BASE) + (size_t)((kt) * (BK * 2)); \
;     __builtin_amdgcn_global_load_lds((const unsigned*)(_g + (size_t)goff0), (unsigned*)((char*)(P) + tid_ * 16), 16, 0, 0); \
;     __builtin_amdgcn_global_load_lds((const unsigned*)(_g + (size_t)goff1), (unsigned*)((char*)(P) + tid_ * 16 + 8192), 16, 0, 0); } while (0)
; #define STAGEA(P, BASE, kt) do { const char* _g = (const char*)(BASE) + (size_t)((kt) * a_kbytes); \
;     __builtin_amdgcn_global_load_lds((const unsigned*)(_g + (size_t)goffA0), (unsigned*)((char*)(P) + tid_ * 16), 16, 0, 0); \
;     __builtin_amdgcn_global_load_lds((const unsigned*)(_g + (size_t)goffA1), (unsigned*)((char*)(P) + tid_ * 16 + 8192), 16, 0, 0); } while (0)
; #define LDA(dst, b, h) for (int m = 0; m < 4; ++m) for (int k = 0; k < 2; ++k) \
;     dst[m][k] = *reinterpret_cast<const bf16x8*>((char*)SA(b, h) + lds_byte(wr * 64 + m * 16 + fr, k * 32 + fq * 8))
; #define LDB(dst, b, h) for (int n = 0; n < 2; ++n) for (int k = 0; k < 2; ++k) \
;     dst[n][k] = *reinterpret_cast<const bf16x8*>((char*)SB(b, h) + lds_byte(wc * 32 + n * 16 + fr, k * 32 + fq * 8))
; #define MMA(ai, bj, At, Bt) do { __builtin_amdgcn_s_setprio(1); \
;     for (int m = 0; m < 4; ++m) for (int n = 0; n < 2; ++n) for (int k = 0; k < 2; ++k) \
;       acc[ai][bj][m][n] = __builtin_amdgcn_mfma_f32_16x16x32_bf16(At[m][k], Bt[n][k], acc[ai][bj][m][n], 0, 0, 0); \
;     __builtin_amdgcn_s_setprio(0); } while (0)
; #define WAIT_L(n) asm volatile("s_waitcnt lgkmcnt(" #n ")" ::: "memory")
; #define BAR __builtin_amdgcn_s_barrier()
; #define SCHED __builtin_amdgcn_sched_barrier(0)
; template <int EPI> ...
;     ...
;   for (int t = 0; t < nt - 2; t += 2) {
;     LDB(B0, 0, 0); SCHED; LDA(At, 0, 0); STAGEA(SA(1, 1), A1, t + 1);
;     WAIT_L(8); BAR; WAIT_L(0); MMA(0, 0, At, B0); BAR; SCHED;
;     LDB(B1, 0, 1); STAGE(SB(0, 0), B0p, t + 2);
;     BAR; WAIT_L(0); MMA(0, 1, At, B1); BAR;
;     LDA(At, 0, 1); STAGEA(SA(0, 0), A0, t + 2);
;     BAR; WAIT_L(0); MMA(1, 0, At, B0); BAR; SCHED;
.LBB0_1382:
	v_add_u32_e32 v172, 0xc000, v158
	v_lshl_add_u64 v[238:239], s[38:39], 0, v[140:141]
	v_readfirstlane_b32 s40, v172
	v_add_u32_e32 v173, 0xe000, v158
	v_lshl_add_u64 v[222:223], v[238:239], 0, s[4:5]
	s_mov_b32 m0, s40
	v_lshl_add_u64 v[240:241], s[38:39], 0, v[142:143]
	v_readfirstlane_b32 s40, v173
	ds_read_b128 v[190:193], v153
	ds_read_b128 v[194:197], v153 offset:1024
	ds_read_b128 v[198:201], v152
	ds_read_b128 v[202:205], v152 offset:1024
	ds_read_b128 v[206:209], v151
	ds_read_b128 v[210:213], v151 offset:1024
	ds_read_b128 v[214:217], v150
	ds_read_b128 v[218:221], v150 offset:1024
	global_load_lds_dwordx4 v[222:223], off
	v_lshl_add_u64 v[222:223], v[240:241], 0, s[4:5]
	s_mov_b32 m0, s40
	s_nop 0
	global_load_lds_dwordx4 v[222:223], off
	s_waitcnt lgkmcnt(8)
	s_setprio 1
	s_barrier
	s_waitcnt lgkmcnt(0)
	v_mfma_f32_16x16x32_bf16 v[124:127], v[190:193], v[174:177], v[124:127]
	v_mfma_f32_16x16x32_bf16 v[120:123], v[190:193], v[182:185], v[120:123]
	v_mfma_f32_16x16x32_bf16 v[116:119], v[198:201], v[174:177], v[116:119]
	v_mfma_f32_16x16x32_bf16 v[112:115], v[198:201], v[182:185], v[112:115]
	v_mfma_f32_16x16x32_bf16 v[108:111], v[206:209], v[174:177], v[108:111]
	v_mfma_f32_16x16x32_bf16 v[104:107], v[206:209], v[182:185], v[104:107]
	v_mfma_f32_16x16x32_bf16 v[100:103], v[214:217], v[174:177], v[100:103]
	v_mfma_f32_16x16x32_bf16 v[96:99], v[214:217], v[182:185], v[96:99]
	v_mfma_f32_16x16x32_bf16 v[124:127], v[194:197], v[178:181], v[124:127]
	v_mfma_f32_16x16x32_bf16 v[120:123], v[194:197], v[186:189], v[120:123]
	v_mfma_f32_16x16x32_bf16 v[116:119], v[202:205], v[178:181], v[116:119]
	v_mfma_f32_16x16x32_bf16 v[112:115], v[202:205], v[186:189], v[112:115]
	v_mfma_f32_16x16x32_bf16 v[108:111], v[210:213], v[178:181], v[108:111]
	v_mfma_f32_16x16x32_bf16 v[104:107], v[210:213], v[186:189], v[104:107]
	v_mfma_f32_16x16x32_bf16 v[100:103], v[218:221], v[178:181], v[100:103]
	v_mfma_f32_16x16x32_bf16 v[96:99], v[218:221], v[186:189], v[96:99]
	s_barrier
	s_setprio 0
	v_lshl_add_u64 v[242:243], s[38:39], 0, v[136:137]
	v_readfirstlane_b32 s40, v155
	v_lshl_add_u64 v[244:245], v[242:243], 0, s[6:7]
	s_mov_b32 m0, s40
	ds_read_b128 v[222:225], v168
	ds_read_b128 v[226:229], v168 offset:1024
	ds_read_b128 v[230:233], v168 offset:2048
	ds_read_b128 v[234:237], v168 offset:3072
	global_load_lds_dwordx4 v[244:245], off
	v_lshl_add_u64 v[244:245], s[38:39], 0, v[138:139]
	v_readfirstlane_b32 s40, v156
	v_lshl_add_u64 v[246:247], v[244:245], 0, s[6:7]
	s_mov_b32 m0, s40
	s_nop 0
	global_load_lds_dwordx4 v[246:247], off
	s_setprio 1
	s_barrier
	s_waitcnt lgkmcnt(0)
	v_mfma_f32_16x16x32_bf16 v[92:95], v[190:193], v[222:225], v[92:95]
	v_mfma_f32_16x16x32_bf16 v[88:91], v[190:193], v[230:233], v[88:91]
	v_mfma_f32_16x16x32_bf16 v[84:87], v[198:201], v[222:225], v[84:87]
	v_mfma_f32_16x16x32_bf16 v[80:83], v[198:201], v[230:233], v[80:83]
	v_mfma_f32_16x16x32_bf16 v[76:79], v[206:209], v[222:225], v[76:79]
	v_mfma_f32_16x16x32_bf16 v[72:75], v[206:209], v[230:233], v[72:75]
	v_mfma_f32_16x16x32_bf16 v[68:71], v[214:217], v[222:225], v[68:71]
	v_mfma_f32_16x16x32_bf16 v[64:67], v[214:217], v[230:233], v[64:67]
	v_mfma_f32_16x16x32_bf16 v[92:95], v[194:197], v[226:229], v[92:95]
	v_mfma_f32_16x16x32_bf16 v[88:91], v[194:197], v[234:237], v[88:91]
	v_mfma_f32_16x16x32_bf16 v[84:87], v[202:205], v[226:229], v[84:87]
	v_mfma_f32_16x16x32_bf16 v[80:83], v[202:205], v[234:237], v[80:83]
	v_mfma_f32_16x16x32_bf16 v[76:79], v[210:213], v[226:229], v[76:79]
	v_mfma_f32_16x16x32_bf16 v[72:75], v[210:213], v[234:237], v[72:75]
	v_mfma_f32_16x16x32_bf16 v[68:71], v[218:221], v[226:229], v[68:71]
	v_mfma_f32_16x16x32_bf16 v[64:67], v[218:221], v[234:237], v[64:67]
	s_barrier
	s_setprio 0
	v_readfirstlane_b32 s40, v158
	v_lshl_add_u64 v[246:247], v[238:239], 0, s[8:9]
	s_mov_b32 m0, s40
	v_readfirstlane_b32 s40, v159
	ds_read_b128 v[190:193], v153 offset:16384
	ds_read_b128 v[194:197], v153 offset:17408
	ds_read_b128 v[198:201], v152 offset:16384
	ds_read_b128 v[202:205], v152 offset:17408
	ds_read_b128 v[206:209], v151 offset:16384
	ds_read_b128 v[210:213], v151 offset:17408
	ds_read_b128 v[214:217], v150 offset:16384
	ds_read_b128 v[218:221], v150 offset:17408
	global_load_lds_dwordx4 v[246:247], off
	v_lshl_add_u64 v[246:247], v[240:241], 0, s[8:9]
	s_mov_b32 m0, s40
	s_nop 0
	global_load_lds_dwordx4 v[246:247], off
	s_setprio 1
	s_barrier
	s_waitcnt lgkmcnt(0)
	v_mfma_f32_16x16x32_bf16 v[60:63], v[190:193], v[174:177], v[60:63]
	v_mfma_f32_16x16x32_bf16 v[56:59], v[190:193], v[182:185], v[56:59]
	v_mfma_f32_16x16x32_bf16 v[52:55], v[198:201], v[174:177], v[52:55]
	v_mfma_f32_16x16x32_bf16 v[48:51], v[198:201], v[182:185], v[48:51]
	v_mfma_f32_16x16x32_bf16 v[44:47], v[206:209], v[174:177], v[44:47]
	v_mfma_f32_16x16x32_bf16 v[40:43], v[206:209], v[182:185], v[40:43]
	v_mfma_f32_16x16x32_bf16 v[36:39], v[214:217], v[174:177], v[36:39]
	v_mfma_f32_16x16x32_bf16 v[32:35], v[214:217], v[182:185], v[32:35]
	v_mfma_f32_16x16x32_bf16 v[60:63], v[194:197], v[178:181], v[60:63]
	v_mfma_f32_16x16x32_bf16 v[56:59], v[194:197], v[186:189], v[56:59]
	v_mfma_f32_16x16x32_bf16 v[52:55], v[202:205], v[178:181], v[52:55]
	v_mfma_f32_16x16x32_bf16 v[48:51], v[202:205], v[186:189], v[48:51]
	v_mfma_f32_16x16x32_bf16 v[44:47], v[210:213], v[178:181], v[44:47]
	v_mfma_f32_16x16x32_bf16 v[40:43], v[210:213], v[186:189], v[40:43]
	v_mfma_f32_16x16x32_bf16 v[36:39], v[218:221], v[178:181], v[36:39]
	v_mfma_f32_16x16x32_bf16 v[32:35], v[218:221], v[186:189], v[32:35]
	s_barrier
; #define STAGE(P, BASE, kt) do { const char* _g = (const char*)(BASE) + (size_t)((kt) * (BK * 2)); \
;     __builtin_amdgcn_global_load_lds((const unsigned*)(_g + (size_t)goff0), (unsigned*)((char*)(P) + tid_ * 16), 16, 0, 0); \
;     __builtin_amdgcn_global_load_lds((const unsigned*)(_g + (size_t)goff1), (unsigned*)((char*)(P) + tid_ * 16 + 8192), 16, 0, 0); } while (0)
; #define STAGEA(P, BASE, kt) do { const char* _g = (const char*)(BASE) + (size_t)((kt) * a_kbytes); \
;     __builtin_amdgcn_global_load_lds((const unsigned*)(_g + (size_t)goffA0), (unsigned*)((char*)(P) + tid_ * 16), 16, 0, 0); \
;     __builtin_amdgcn_global_load_lds((const unsigned*)(_g + (size_t)goffA1), (unsigned*)((char*)(P) + tid_ * 16 + 8192), 16, 0, 0); } while (0)
; #define LDA(dst, b, h) for (int m = 0; m < 4; ++m) for (int k = 0; k < 2; ++k) \
;     dst[m][k] = *reinterpret_cast<const bf16x8*>((char*)SA(b, h) + lds_byte(wr * 64 + m * 16 + fr, k * 32 + fq * 8))
; #define LDB(dst, b, h) for (int n = 0; n < 2; ++n) for (int k = 0; k < 2; ++k) \
;     dst[n][k] = *reinterpret_cast<const bf16x8*>((char*)SB(b, h) + lds_byte(wc * 32 + n * 16 + fr, k * 32 + fq * 8))
; #define MMA(ai, bj, At, Bt) do { __builtin_amdgcn_s_setprio(1); \
;     for (int m = 0; m < 4; ++m) for (int n = 0; n < 2; ++n) for (int k = 0; k < 2; ++k) \
;       acc[ai][bj][m][n] = __builtin_amdgcn_mfma_f32_16x16x32_bf16(At[m][k], Bt[n][k], acc[ai][bj][m][n], 0, 0, 0); \
;     __builtin_amdgcn_s_setprio(0); } while (0)
; #define WAIT_V(n) asm volatile("s_waitcnt vmcnt(" #n ")" ::: "memory")
; #define WAIT_L(n) asm volatile("s_waitcnt lgkmcnt(" #n ")" ::: "memory")
; #define BAR __builtin_amdgcn_s_barrier()
; #define SCHED __builtin_amdgcn_sched_barrier(0)
; template <int EPI> ...
;     ...
;     STAGE(SB(0, 1), B1p, t + 2);
;     WAIT_V(6); BAR; MMA(1, 1, At, B1); BAR;
;     LDB(B0, 1, 0); SCHED; LDA(At, 1, 0); STAGEA(SA(0, 1), A1, t + 2);
;     WAIT_L(8); BAR; WAIT_L(0); MMA(0, 0, At, B0); BAR; SCHED;
;     LDB(B1, 1, 1); STAGE(SB(1, 0), B0p, t + 3);
;     BAR; WAIT_L(0); MMA(0, 1, At, B1); BAR;
;     LDA(At, 1, 1); STAGEA(SA(1, 0), A0, t + 3);
	s_setprio 0
	v_readfirstlane_b32 s40, v160
	v_lshl_add_u64 v[174:175], v[242:243], 0, s[10:11]
	s_mov_b32 m0, s40
	v_readfirstlane_b32 s40, v161
	global_load_lds_dwordx4 v[174:175], off
	v_lshl_add_u64 v[174:175], v[244:245], 0, s[10:11]
	s_mov_b32 m0, s40
	s_nop 0
	global_load_lds_dwordx4 v[174:175], off
	s_waitcnt vmcnt(6)
	s_setprio 1
	s_barrier
	v_mfma_f32_16x16x32_bf16 v[28:31], v[190:193], v[222:225], v[28:31]
	v_mfma_f32_16x16x32_bf16 v[24:27], v[190:193], v[230:233], v[24:27]
	v_mfma_f32_16x16x32_bf16 v[20:23], v[198:201], v[222:225], v[20:23]
	v_mfma_f32_16x16x32_bf16 v[16:19], v[198:201], v[230:233], v[16:19]
	ds_read_b128 v[174:177], v157
	v_mfma_f32_16x16x32_bf16 v[12:15], v[206:209], v[222:225], v[12:15]
	v_mfma_f32_16x16x32_bf16 v[8:11], v[206:209], v[230:233], v[8:11]
	ds_read_b128 v[178:181], v157 offset:1024
	v_mfma_f32_16x16x32_bf16 v[4:7], v[214:217], v[222:225], v[4:7]
	v_mfma_f32_16x16x32_bf16 v[0:3], v[214:217], v[230:233], v[0:3]
	ds_read_b128 v[182:185], v157 offset:2048
	v_mfma_f32_16x16x32_bf16 v[28:31], v[194:197], v[226:229], v[28:31]
	v_mfma_f32_16x16x32_bf16 v[24:27], v[194:197], v[234:237], v[24:27]
	ds_read_b128 v[186:189], v157 offset:3072
	v_mfma_f32_16x16x32_bf16 v[20:23], v[202:205], v[226:229], v[20:23]
	v_mfma_f32_16x16x32_bf16 v[16:19], v[202:205], v[234:237], v[16:19]
	v_mfma_f32_16x16x32_bf16 v[12:15], v[210:213], v[226:229], v[12:15]
	v_mfma_f32_16x16x32_bf16 v[8:11], v[210:213], v[234:237], v[8:11]
	v_mfma_f32_16x16x32_bf16 v[4:7], v[218:221], v[226:229], v[4:7]
	v_mfma_f32_16x16x32_bf16 v[0:3], v[218:221], v[234:237], v[0:3]
	s_barrier
	s_setprio 0
	v_readfirstlane_b32 s40, v162
	v_lshl_add_u64 v[222:223], v[238:239], 0, s[12:13]
	s_mov_b32 m0, s40
	v_readfirstlane_b32 s40, v163
	ds_read_b128 v[190:193], v153 offset:32768
	ds_read_b128 v[194:197], v153 offset:33792
	ds_read_b128 v[198:201], v152 offset:32768
	ds_read_b128 v[202:205], v152 offset:33792
	ds_read_b128 v[206:209], v151 offset:32768
	ds_read_b128 v[210:213], v151 offset:33792
	ds_read_b128 v[214:217], v150 offset:32768
	ds_read_b128 v[218:221], v150 offset:33792
	global_load_lds_dwordx4 v[222:223], off
	v_lshl_add_u64 v[222:223], v[240:241], 0, s[12:13]
	s_mov_b32 m0, s40
	s_nop 0
	global_load_lds_dwordx4 v[222:223], off
	s_waitcnt lgkmcnt(8)
	s_setprio 1
	s_barrier
	s_waitcnt lgkmcnt(0)
	v_mfma_f32_16x16x32_bf16 v[124:127], v[190:193], v[174:177], v[124:127]
	v_mfma_f32_16x16x32_bf16 v[120:123], v[190:193], v[182:185], v[120:123]
	v_mfma_f32_16x16x32_bf16 v[116:119], v[198:201], v[174:177], v[116:119]
	v_mfma_f32_16x16x32_bf16 v[112:115], v[198:201], v[182:185], v[112:115]
	v_mfma_f32_16x16x32_bf16 v[108:111], v[206:209], v[174:177], v[108:111]
	v_mfma_f32_16x16x32_bf16 v[104:107], v[206:209], v[182:185], v[104:107]
	v_mfma_f32_16x16x32_bf16 v[100:103], v[214:217], v[174:177], v[100:103]
	v_mfma_f32_16x16x32_bf16 v[96:99], v[214:217], v[182:185], v[96:99]
	v_mfma_f32_16x16x32_bf16 v[124:127], v[194:197], v[178:181], v[124:127]
	v_mfma_f32_16x16x32_bf16 v[120:123], v[194:197], v[186:189], v[120:123]
	v_mfma_f32_16x16x32_bf16 v[116:119], v[202:205], v[178:181], v[116:119]
	v_mfma_f32_16x16x32_bf16 v[112:115], v[202:205], v[186:189], v[112:115]
	v_mfma_f32_16x16x32_bf16 v[108:111], v[210:213], v[178:181], v[108:111]
	v_mfma_f32_16x16x32_bf16 v[104:107], v[210:213], v[186:189], v[104:107]
	v_mfma_f32_16x16x32_bf16 v[100:103], v[218:221], v[178:181], v[100:103]
	v_mfma_f32_16x16x32_bf16 v[96:99], v[218:221], v[186:189], v[96:99]
	s_barrier
	s_setprio 0
	v_readfirstlane_b32 s40, v164
	v_lshl_add_u64 v[246:247], v[242:243], 0, s[14:15]
	s_mov_b32 m0, s40
	v_readfirstlane_b32 s40, v165
	ds_read_b128 v[222:225], v154
	ds_read_b128 v[226:229], v154 offset:1024
	ds_read_b128 v[230:233], v154 offset:2048
	ds_read_b128 v[234:237], v154 offset:3072
	global_load_lds_dwordx4 v[246:247], off
	v_lshl_add_u64 v[246:247], v[244:245], 0, s[14:15]
	s_mov_b32 m0, s40
	s_nop 0
	global_load_lds_dwordx4 v[246:247], off
	s_setprio 1
	s_barrier
	s_waitcnt lgkmcnt(0)
	v_mfma_f32_16x16x32_bf16 v[92:95], v[190:193], v[222:225], v[92:95]
	v_mfma_f32_16x16x32_bf16 v[88:91], v[190:193], v[230:233], v[88:91]
	v_mfma_f32_16x16x32_bf16 v[84:87], v[198:201], v[222:225], v[84:87]
	v_mfma_f32_16x16x32_bf16 v[80:83], v[198:201], v[230:233], v[80:83]
	v_mfma_f32_16x16x32_bf16 v[76:79], v[206:209], v[222:225], v[76:79]
	v_mfma_f32_16x16x32_bf16 v[72:75], v[206:209], v[230:233], v[72:75]
	v_mfma_f32_16x16x32_bf16 v[68:71], v[214:217], v[222:225], v[68:71]
	v_mfma_f32_16x16x32_bf16 v[64:67], v[214:217], v[230:233], v[64:67]
	v_mfma_f32_16x16x32_bf16 v[92:95], v[194:197], v[226:229], v[92:95]
	v_mfma_f32_16x16x32_bf16 v[88:91], v[194:197], v[234:237], v[88:91]
	v_mfma_f32_16x16x32_bf16 v[84:87], v[202:205], v[226:229], v[84:87]
	v_mfma_f32_16x16x32_bf16 v[80:83], v[202:205], v[234:237], v[80:83]
	v_mfma_f32_16x16x32_bf16 v[76:79], v[210:213], v[226:229], v[76:79]
	v_mfma_f32_16x16x32_bf16 v[72:75], v[210:213], v[234:237], v[72:75]
	v_mfma_f32_16x16x32_bf16 v[68:71], v[218:221], v[226:229], v[68:71]
	v_mfma_f32_16x16x32_bf16 v[64:67], v[218:221], v[234:237], v[64:67]
	s_barrier
	s_setprio 0
	v_readfirstlane_b32 s40, v166
	v_lshl_add_u64 v[238:239], v[238:239], 0, s[16:17]
	s_mov_b32 m0, s40
	v_readfirstlane_b32 s40, v167
	ds_read_b128 v[190:193], v153 offset:49152
	ds_read_b128 v[194:197], v153 offset:50176
	ds_read_b128 v[198:201], v152 offset:49152
	ds_read_b128 v[202:205], v152 offset:50176
	ds_read_b128 v[206:209], v151 offset:49152
	ds_read_b128 v[210:213], v151 offset:50176
	ds_read_b128 v[214:217], v150 offset:49152
	ds_read_b128 v[218:221], v150 offset:50176
	global_load_lds_dwordx4 v[238:239], off
	v_lshl_add_u64 v[238:239], v[240:241], 0, s[16:17]
	s_mov_b32 m0, s40
	s_nop 0
	global_load_lds_dwordx4 v[238:239], off
	s_setprio 1
	s_barrier
; #define STAGE(P, BASE, kt) do { const char* _g = (const char*)(BASE) + (size_t)((kt) * (BK * 2)); \
;     __builtin_amdgcn_global_load_lds((const unsigned*)(_g + (size_t)goff0), (unsigned*)((char*)(P) + tid_ * 16), 16, 0, 0); \
;     __builtin_amdgcn_global_load_lds((const unsigned*)(_g + (size_t)goff1), (unsigned*)((char*)(P) + tid_ * 16 + 8192), 16, 0, 0); } while (0)
; #define STAGEA(P, BASE, kt) do { const char* _g = (const char*)(BASE) + (size_t)((kt) * a_kbytes); \
;     __builtin_amdgcn_global_load_lds((const unsigned*)(_g + (size_t)goffA0), (unsigned*)((char*)(P) + tid_ * 16), 16, 0, 0); \
;     __builtin_amdgcn_global_load_lds((const unsigned*)(_g + (size_t)goffA1), (unsigned*)((char*)(P) + tid_ * 16 + 8192), 16, 0, 0); } while (0)
; #define LDA(dst, b, h) for (int m = 0; m < 4; ++m) for (int k = 0; k < 2; ++k) \
;     dst[m][k] = *reinterpret_cast<const bf16x8*>((char*)SA(b, h) + lds_byte(wr * 64 + m * 16 + fr, k * 32 + fq * 8))
; #define LDB(dst, b, h) for (int n = 0; n < 2; ++n) for (int k = 0; k < 2; ++k) \
;     dst[n][k] = *reinterpret_cast<const bf16x8*>((char*)SB(b, h) + lds_byte(wc * 32 + n * 16 + fr, k * 32 + fq * 8))
; #define MMA(ai, bj, At, Bt) do { __builtin_amdgcn_s_setprio(1); \
;     for (int m = 0; m < 4; ++m) for (int n = 0; n < 2; ++n) for (int k = 0; k < 2; ++k) \
;       acc[ai][bj][m][n] = __builtin_amdgcn_mfma_f32_16x16x32_bf16(At[m][k], Bt[n][k], acc[ai][bj][m][n], 0, 0, 0); \
;     __builtin_amdgcn_s_setprio(0); } while (0)
; #define WAIT_V(n) asm volatile("s_waitcnt vmcnt(" #n ")" ::: "memory")
; #define WAIT_L(n) asm volatile("s_waitcnt lgkmcnt(" #n ")" ::: "memory")
; #define BAR __builtin_amdgcn_s_barrier()
; #define SCHED __builtin_amdgcn_sched_barrier(0)
; template <int EPI> ...
;     ...
;     BAR; WAIT_L(0); MMA(1, 0, At, B0); BAR; SCHED;
;     STAGE(SB(1, 1), B1p, t + 3);
;     WAIT_V(6); BAR; MMA(1, 1, At, B1); BAR;
;   }
;   { LDB(B0, 0, 0); LDA(At, 0, 0); STAGEA(SA(1, 1), A1, nt - 1);
;     BAR; WAIT_L(0); MMA(0, 0, At, B0); BAR;
;     LDB(B1, 0, 1); BAR; WAIT_L(0); MMA(0, 1, At, B1); BAR;
;     LDA(At, 0, 1); WAIT_V(4); BAR; WAIT_L(0); MMA(1, 0, At, B0); MMA(1, 1, At, B1); BAR; }
	s_waitcnt lgkmcnt(0)
	v_mfma_f32_16x16x32_bf16 v[60:63], v[190:193], v[174:177], v[60:63]
	v_mfma_f32_16x16x32_bf16 v[56:59], v[190:193], v[182:185], v[56:59]
	v_mfma_f32_16x16x32_bf16 v[52:55], v[198:201], v[174:177], v[52:55]
	v_mfma_f32_16x16x32_bf16 v[48:51], v[198:201], v[182:185], v[48:51]
	v_mfma_f32_16x16x32_bf16 v[44:47], v[206:209], v[174:177], v[44:47]
	v_mfma_f32_16x16x32_bf16 v[40:43], v[206:209], v[182:185], v[40:43]
	v_mfma_f32_16x16x32_bf16 v[36:39], v[214:217], v[174:177], v[36:39]
	v_mfma_f32_16x16x32_bf16 v[32:35], v[214:217], v[182:185], v[32:35]
	v_mfma_f32_16x16x32_bf16 v[60:63], v[194:197], v[178:181], v[60:63]
	v_mfma_f32_16x16x32_bf16 v[56:59], v[194:197], v[186:189], v[56:59]
	v_mfma_f32_16x16x32_bf16 v[52:55], v[202:205], v[178:181], v[52:55]
	v_mfma_f32_16x16x32_bf16 v[48:51], v[202:205], v[186:189], v[48:51]
	v_mfma_f32_16x16x32_bf16 v[44:47], v[210:213], v[178:181], v[44:47]
	v_mfma_f32_16x16x32_bf16 v[40:43], v[210:213], v[186:189], v[40:43]
	v_mfma_f32_16x16x32_bf16 v[36:39], v[218:221], v[178:181], v[36:39]
	v_mfma_f32_16x16x32_bf16 v[32:35], v[218:221], v[186:189], v[32:35]
	s_barrier
	s_setprio 0
	v_readfirstlane_b32 s40, v169
	v_lshl_add_u64 v[174:175], v[242:243], 0, s[18:19]
	s_mov_b32 m0, s40
	v_readfirstlane_b32 s40, v170
	global_load_lds_dwordx4 v[174:175], off
	v_lshl_add_u64 v[174:175], v[244:245], 0, s[18:19]
	s_mov_b32 m0, s40
	s_nop 0
	global_load_lds_dwordx4 v[174:175], off
	s_waitcnt vmcnt(6)
	s_setprio 1
	s_barrier
	v_mfma_f32_16x16x32_bf16 v[28:31], v[190:193], v[222:225], v[28:31]
	v_mfma_f32_16x16x32_bf16 v[24:27], v[190:193], v[230:233], v[24:27]
	v_mfma_f32_16x16x32_bf16 v[20:23], v[198:201], v[222:225], v[20:23]
	v_mfma_f32_16x16x32_bf16 v[16:19], v[198:201], v[230:233], v[16:19]
	ds_read_b128 v[174:177], v171
	v_mfma_f32_16x16x32_bf16 v[12:15], v[206:209], v[222:225], v[12:15]
	v_mfma_f32_16x16x32_bf16 v[8:11], v[206:209], v[230:233], v[8:11]
	ds_read_b128 v[178:181], v171 offset:1024
	v_mfma_f32_16x16x32_bf16 v[4:7], v[214:217], v[222:225], v[4:7]
	v_mfma_f32_16x16x32_bf16 v[0:3], v[214:217], v[230:233], v[0:3]
	ds_read_b128 v[182:185], v171 offset:2048
	v_mfma_f32_16x16x32_bf16 v[28:31], v[194:197], v[226:229], v[28:31]
	v_mfma_f32_16x16x32_bf16 v[24:27], v[194:197], v[234:237], v[24:27]
	ds_read_b128 v[186:189], v171 offset:3072
	v_mfma_f32_16x16x32_bf16 v[20:23], v[202:205], v[226:229], v[20:23]
	v_mfma_f32_16x16x32_bf16 v[16:19], v[202:205], v[234:237], v[16:19]
	v_mfma_f32_16x16x32_bf16 v[12:15], v[210:213], v[226:229], v[12:15]
	v_mfma_f32_16x16x32_bf16 v[8:11], v[210:213], v[234:237], v[8:11]
	v_mfma_f32_16x16x32_bf16 v[4:7], v[218:221], v[226:229], v[4:7]
	v_mfma_f32_16x16x32_bf16 v[0:3], v[218:221], v[234:237], v[0:3]
	s_barrier
	s_setprio 0
	s_add_i32 s23, s23, 2
	s_add_u32 s38, s38, 0x100
	s_addc_u32 s39, s39, 0
	s_cmp_lt_u32 s23, 28
	s_cbranch_scc1 .LBB0_1382
	s_add_u32 s36, s36, 0x80f80
	s_addc_u32 s37, s37, 0
	v_readfirstlane_b32 s23, v172
	v_lshl_add_u64 v[166:167], s[36:37], 0, v[130:131]
	s_mov_b32 m0, s23
	v_readfirstlane_b32 s23, v173
	ds_read_b128 v[136:139], v171
	ds_read_b128 v[140:143], v171 offset:1024
	ds_read_b128 v[158:161], v171 offset:2048
	ds_read_b128 v[162:165], v171 offset:3072
	ds_read_b128 v[174:177], v153
	ds_read_b128 v[178:181], v153 offset:1024
	ds_read_b128 v[182:185], v152
	ds_read_b128 v[186:189], v152 offset:1024
	ds_read_b128 v[190:193], v151
	ds_read_b128 v[194:197], v151 offset:1024
	ds_read_b128 v[198:201], v150
	ds_read_b128 v[202:205], v150 offset:1024
	global_load_lds_dwordx4 v[166:167], off
	v_lshl_add_u64 v[166:167], s[36:37], 0, v[128:129]
	s_mov_b32 m0, s23
	s_nop 0
	global_load_lds_dwordx4 v[166:167], off
	s_setprio 1
	s_barrier
	s_waitcnt lgkmcnt(0)
	v_mfma_f32_16x16x32_bf16 v[124:127], v[174:177], v[136:139], v[124:127]
	v_mfma_f32_16x16x32_bf16 v[120:123], v[174:177], v[158:161], v[120:123]
	v_mfma_f32_16x16x32_bf16 v[108:111], v[190:193], v[136:139], v[108:111]
	v_mfma_f32_16x16x32_bf16 v[104:107], v[190:193], v[158:161], v[104:107]
	v_mfma_f32_16x16x32_bf16 v[124:127], v[178:181], v[140:143], v[124:127]
	v_mfma_f32_16x16x32_bf16 v[120:123], v[178:181], v[162:165], v[120:123]
	v_mfma_f32_16x16x32_bf16 v[116:119], v[182:185], v[136:139], v[116:119]
	v_mfma_f32_16x16x32_bf16 v[112:115], v[182:185], v[158:161], v[112:115]
	v_mfma_f32_16x16x32_bf16 v[108:111], v[194:197], v[140:143], v[108:111]
	v_mfma_f32_16x16x32_bf16 v[104:107], v[194:197], v[162:165], v[104:107]
	v_mfma_f32_16x16x32_bf16 v[100:103], v[198:201], v[136:139], v[100:103]
	v_mfma_f32_16x16x32_bf16 v[96:99], v[198:201], v[158:161], v[96:99]
	v_mfma_f32_16x16x32_bf16 v[170:173], v[186:189], v[140:143], v[116:119]
	v_mfma_f32_16x16x32_bf16 v[206:209], v[186:189], v[162:165], v[112:115]
	v_mfma_f32_16x16x32_bf16 v[210:213], v[202:205], v[140:143], v[100:103]
	v_mfma_f32_16x16x32_bf16 v[214:217], v[202:205], v[162:165], v[96:99]
	s_barrier
	s_setprio 0
	s_nop 1
	ds_read_b128 v[96:99], v168
	ds_read_b128 v[100:103], v168 offset:1024
	ds_read_b128 v[112:115], v168 offset:2048
	ds_read_b128 v[116:119], v168 offset:3072
	s_setprio 1
	s_barrier
; #define STAGEA(P, BASE, kt) do { const char* _g = (const char*)(BASE) + (size_t)((kt) * a_kbytes); \
;     __builtin_amdgcn_global_load_lds((const unsigned*)(_g + (size_t)goffA0), (unsigned*)((char*)(P) + tid_ * 16), 16, 0, 0); \
;     __builtin_amdgcn_global_load_lds((const unsigned*)(_g + (size_t)goffA1), (unsigned*)((char*)(P) + tid_ * 16 + 8192), 16, 0, 0); } while (0)
; #define LDA(dst, b, h) for (int m = 0; m < 4; ++m) for (int k = 0; k < 2; ++k) \
;     dst[m][k] = *reinterpret_cast<const bf16x8*>((char*)SA(b, h) + lds_byte(wr * 64 + m * 16 + fr, k * 32 + fq * 8))
; #define LDB(dst, b, h) for (int n = 0; n < 2; ++n) for (int k = 0; k < 2; ++k) \
;     dst[n][k] = *reinterpret_cast<const bf16x8*>((char*)SB(b, h) + lds_byte(wc * 32 + n * 16 + fr, k * 32 + fq * 8))
; #define MMA(ai, bj, At, Bt) do { __builtin_amdgcn_s_setprio(1); \
;     for (int m = 0; m < 4; ++m) for (int n = 0; n < 2; ++n) for (int k = 0; k < 2; ++k) \
;       acc[ai][bj][m][n] = __builtin_amdgcn_mfma_f32_16x16x32_bf16(At[m][k], Bt[n][k], acc[ai][bj][m][n], 0, 0, 0); \
;     __builtin_amdgcn_s_setprio(0); } while (0)
; #define WAIT_V(n) asm volatile("s_waitcnt vmcnt(" #n ")" ::: "memory")
; #define WAIT_L(n) asm volatile("s_waitcnt lgkmcnt(" #n ")" ::: "memory")
; #define BAR __builtin_amdgcn_s_barrier()
; template <int EPI> ...
;     ...
;   { LDB(B0, 0, 0); LDA(At, 0, 0); STAGEA(SA(1, 1), A1, nt - 1);
;     BAR; WAIT_L(0); MMA(0, 0, At, B0); BAR;
;     LDB(B1, 0, 1); BAR; WAIT_L(0); MMA(0, 1, At, B1); BAR;
;     LDA(At, 0, 1); WAIT_V(4); BAR; WAIT_L(0); MMA(1, 0, At, B0); MMA(1, 1, At, B1); BAR; }
;   { LDB(B0, 1, 0); LDA(At, 1, 0); WAIT_V(2); BAR; WAIT_L(0); MMA(0, 0, At, B0); BAR;
;     LDB(B1, 1, 1); WAIT_V(0); BAR; WAIT_L(0); MMA(0, 1, At, B1); BAR;
;     LDA(At, 1, 1); BAR; WAIT_L(0); MMA(1, 0, At, B0); MMA(1, 1, At, B1); BAR; }
	s_waitcnt lgkmcnt(0)
	v_mfma_f32_16x16x32_bf16 v[92:95], v[174:177], v[96:99], v[92:95]
	v_mfma_f32_16x16x32_bf16 v[88:91], v[174:177], v[112:115], v[88:91]
	v_mfma_f32_16x16x32_bf16 v[76:79], v[190:193], v[96:99], v[76:79]
	v_mfma_f32_16x16x32_bf16 v[72:75], v[190:193], v[112:115], v[72:75]
	v_mfma_f32_16x16x32_bf16 v[92:95], v[178:181], v[100:103], v[92:95]
	v_mfma_f32_16x16x32_bf16 v[88:91], v[178:181], v[116:119], v[88:91]
	v_mfma_f32_16x16x32_bf16 v[84:87], v[182:185], v[96:99], v[84:87]
	v_mfma_f32_16x16x32_bf16 v[80:83], v[182:185], v[112:115], v[80:83]
	v_mfma_f32_16x16x32_bf16 v[76:79], v[194:197], v[100:103], v[76:79]
	v_mfma_f32_16x16x32_bf16 v[72:75], v[194:197], v[116:119], v[72:75]
	v_mfma_f32_16x16x32_bf16 v[68:71], v[198:201], v[96:99], v[68:71]
	v_mfma_f32_16x16x32_bf16 v[64:67], v[198:201], v[112:115], v[64:67]
	v_mfma_f32_16x16x32_bf16 v[166:169], v[186:189], v[100:103], v[84:87]
	v_mfma_f32_16x16x32_bf16 v[174:177], v[186:189], v[116:119], v[80:83]
	v_mfma_f32_16x16x32_bf16 v[178:181], v[202:205], v[100:103], v[68:71]
	v_mfma_f32_16x16x32_bf16 v[182:185], v[202:205], v[116:119], v[64:67]
	s_barrier
	s_setprio 0
	s_nop 1
	ds_read_b128 v[64:67], v153 offset:16384
	ds_read_b128 v[68:71], v153 offset:17408
	ds_read_b128 v[80:83], v152 offset:16384
	ds_read_b128 v[84:87], v152 offset:17408
	ds_read_b128 v[186:189], v151 offset:16384
	ds_read_b128 v[190:193], v151 offset:17408
	ds_read_b128 v[194:197], v150 offset:16384
	ds_read_b128 v[198:201], v150 offset:17408
	s_waitcnt vmcnt(4)
	s_setprio 1
	s_barrier
	s_waitcnt lgkmcnt(0)
	v_mfma_f32_16x16x32_bf16 v[60:63], v[64:67], v[136:139], v[60:63]
	v_mfma_f32_16x16x32_bf16 v[56:59], v[64:67], v[158:161], v[56:59]
	v_mfma_f32_16x16x32_bf16 v[44:47], v[186:189], v[136:139], v[44:47]
	v_mfma_f32_16x16x32_bf16 v[40:43], v[186:189], v[158:161], v[40:43]
	v_mfma_f32_16x16x32_bf16 v[60:63], v[68:71], v[140:143], v[60:63]
	v_mfma_f32_16x16x32_bf16 v[56:59], v[68:71], v[162:165], v[56:59]
	v_mfma_f32_16x16x32_bf16 v[52:55], v[80:83], v[136:139], v[52:55]
	v_mfma_f32_16x16x32_bf16 v[48:51], v[80:83], v[158:161], v[48:51]
	v_mfma_f32_16x16x32_bf16 v[44:47], v[190:193], v[140:143], v[44:47]
	v_mfma_f32_16x16x32_bf16 v[40:43], v[190:193], v[162:165], v[40:43]
	v_mfma_f32_16x16x32_bf16 v[36:39], v[194:197], v[136:139], v[36:39]
	v_mfma_f32_16x16x32_bf16 v[32:35], v[194:197], v[158:161], v[32:35]
	v_mfma_f32_16x16x32_bf16 v[202:205], v[84:87], v[140:143], v[52:55]
	v_mfma_f32_16x16x32_bf16 v[218:221], v[84:87], v[162:165], v[48:51]
	v_mfma_f32_16x16x32_bf16 v[136:139], v[198:201], v[140:143], v[36:39]
	v_mfma_f32_16x16x32_bf16 v[140:143], v[198:201], v[162:165], v[32:35]
	s_setprio 0
	s_setprio 1
	v_mfma_f32_16x16x32_bf16 v[28:31], v[64:67], v[96:99], v[28:31]
	v_mfma_f32_16x16x32_bf16 v[24:27], v[64:67], v[112:115], v[24:27]
	v_mfma_f32_16x16x32_bf16 v[12:15], v[186:189], v[96:99], v[12:15]
	v_mfma_f32_16x16x32_bf16 v[8:11], v[186:189], v[112:115], v[8:11]
	v_mfma_f32_16x16x32_bf16 v[28:31], v[68:71], v[100:103], v[28:31]
	v_mfma_f32_16x16x32_bf16 v[24:27], v[68:71], v[116:119], v[24:27]
	v_mfma_f32_16x16x32_bf16 v[20:23], v[80:83], v[96:99], v[20:23]
	v_mfma_f32_16x16x32_bf16 v[16:19], v[80:83], v[112:115], v[16:19]
	v_mfma_f32_16x16x32_bf16 v[12:15], v[190:193], v[100:103], v[12:15]
	v_mfma_f32_16x16x32_bf16 v[8:11], v[190:193], v[116:119], v[8:11]
	v_mfma_f32_16x16x32_bf16 v[4:7], v[194:197], v[96:99], v[4:7]
	v_mfma_f32_16x16x32_bf16 v[0:3], v[194:197], v[112:115], v[0:3]
	v_mfma_f32_16x16x32_bf16 v[158:161], v[84:87], v[100:103], v[20:23]
	v_mfma_f32_16x16x32_bf16 v[162:165], v[84:87], v[116:119], v[16:19]
	v_mfma_f32_16x16x32_bf16 v[186:189], v[198:201], v[100:103], v[4:7]
	v_mfma_f32_16x16x32_bf16 v[190:193], v[198:201], v[116:119], v[0:3]
	s_barrier
	s_setprio 0
	s_nop 1
	ds_read_b128 v[0:3], v157
	ds_read_b128 v[4:7], v157 offset:1024
	ds_read_b128 v[194:197], v157 offset:2048
	ds_read_b128 v[198:201], v157 offset:3072
	ds_read_b128 v[16:19], v153 offset:32768
	ds_read_b128 v[20:23], v153 offset:33792
	ds_read_b128 v[32:35], v152 offset:32768
	ds_read_b128 v[36:39], v152 offset:33792
	ds_read_b128 v[48:51], v151 offset:32768
	ds_read_b128 v[52:55], v151 offset:33792
	ds_read_b128 v[222:225], v150 offset:32768
	ds_read_b128 v[226:229], v150 offset:33792
	s_waitcnt vmcnt(2)
	s_setprio 1
	s_barrier
	s_waitcnt lgkmcnt(0)
	v_mfma_f32_16x16x32_bf16 v[64:67], v[16:19], v[0:3], v[124:127]
	v_mfma_f32_16x16x32_bf16 v[116:119], v[20:23], v[4:7], v[64:67]
	v_mfma_f32_16x16x32_bf16 v[64:67], v[16:19], v[194:197], v[120:123]
	v_mfma_f32_16x16x32_bf16 v[112:115], v[20:23], v[198:201], v[64:67]
	v_mfma_f32_16x16x32_bf16 v[64:67], v[32:35], v[0:3], v[170:173]
	v_mfma_f32_16x16x32_bf16 v[100:103], v[36:39], v[4:7], v[64:67]
	v_mfma_f32_16x16x32_bf16 v[64:67], v[32:35], v[194:197], v[206:209]
	v_mfma_f32_16x16x32_bf16 v[96:99], v[36:39], v[198:201], v[64:67]
	v_mfma_f32_16x16x32_bf16 v[64:67], v[48:51], v[0:3], v[108:111]
	v_mfma_f32_16x16x32_bf16 v[84:87], v[52:55], v[4:7], v[64:67]
	v_mfma_f32_16x16x32_bf16 v[64:67], v[48:51], v[194:197], v[104:107]
	v_mfma_f32_16x16x32_bf16 v[80:83], v[52:55], v[198:201], v[64:67]
	v_mfma_f32_16x16x32_bf16 v[64:67], v[222:225], v[0:3], v[210:213]
	v_mfma_f32_16x16x32_bf16 v[68:71], v[226:229], v[4:7], v[64:67]
	v_mfma_f32_16x16x32_bf16 v[64:67], v[222:225], v[194:197], v[214:217]
	v_mfma_f32_16x16x32_bf16 v[64:67], v[226:229], v[198:201], v[64:67]
	s_barrier
	s_setprio 0
	ds_read_b128 v[170:173], v154
	ds_read_b128 v[206:209], v154 offset:1024
	ds_read_b128 v[210:213], v154 offset:2048
	ds_read_b128 v[154:157], v154 offset:3072
	s_waitcnt vmcnt(0)
	s_setprio 1
	s_barrier
; __device__ __forceinline__ u16 f2bf(float f) { unsigned u = __float_as_uint(f); u += 0x7fffu + ((u >> 16) & 1u); return (u16)(u >> 16); }
; __device__ __forceinline__ float frcp(float x) { return __builtin_amdgcn_rcpf(x); }
; #define LDA(dst, b, h) for (int m = 0; m < 4; ++m) for (int k = 0; k < 2; ++k) \
;     dst[m][k] = *reinterpret_cast<const bf16x8*>((char*)SA(b, h) + lds_byte(wr * 64 + m * 16 + fr, k * 32 + fq * 8))
; #define LDB(dst, b, h) for (int n = 0; n < 2; ++n) for (int k = 0; k < 2; ++k) \
;     dst[n][k] = *reinterpret_cast<const bf16x8*>((char*)SB(b, h) + lds_byte(wc * 32 + n * 16 + fr, k * 32 + fq * 8))
; #define MMA(ai, bj, At, Bt) do { __builtin_amdgcn_s_setprio(1); \
;     for (int m = 0; m < 4; ++m) for (int n = 0; n < 2; ++n) for (int k = 0; k < 2; ++k) \
;       acc[ai][bj][m][n] = __builtin_amdgcn_mfma_f32_16x16x32_bf16(At[m][k], Bt[n][k], acc[ai][bj][m][n], 0, 0, 0); \
;     __builtin_amdgcn_s_setprio(0); } while (0)
; template <int EPI> ...
;     ...
;   { LDB(B0, 1, 0); LDA(At, 1, 0); WAIT_V(2); BAR; WAIT_L(0); MMA(0, 0, At, B0); BAR;
;     LDB(B1, 1, 1); WAIT_V(0); BAR; WAIT_L(0); MMA(0, 1, At, B1); BAR;
;     LDA(At, 1, 1); BAR; WAIT_L(0); MMA(1, 0, At, B0); MMA(1, 1, At, B1); BAR; }
;   if (wr == 0) BAR;
;   {
;     constexpr int NC = (EPI == EPI_GU) ? 128 : 256;
;     constexpr int RB = NC * 2;
;     char* tb = (char*)shm;
; #pragma unroll
;     for (int ai = 0; ai < 2; ++ai)
; #pragma unroll
;       for (int m = 0; m < 4; ++m)
; #pragma unroll
;         for (int j = 0; j < 4; ++j) {
;           const int r = ai * 128 + wr * 64 + m * 16 + fq * 4 + j;
;           float rs = 1.0f;
;           if (EPI != EPI_RES) rs = e.rstd[brow + r];
;           char* rowp = tb + r * RB + fr * 2;
;           if (EPI == EPI_GU) {
; #pragma unroll
;             for (int n = 0; n < 2; ++n) {
;               float g = acc[ai][0][m][n][j] * rs, u = acc[ai][1][m][n][j] * rs;
;               float h = g * frcp(1.0f + __expf(-g)) * u;
;               const int seg = (wc * 2 + n) ^ fq;
;               *(u16*)(rowp + seg * 32) = f2bf(h);
;             }
;           } else {
; #pragma unroll
;             for (int bj = 0; bj < 2; ++bj)
; #pragma unroll
;               for (int n = 0; n < 2; ++n) {
;                 const int seg = (bj * 8 + wc * 2 + n) ^ fq;
;                 *(u16*)(rowp + seg * 32) = f2bf(acc[ai][bj][m][n][j] * rs);
;               }
	s_waitcnt lgkmcnt(0)
	v_mfma_f32_16x16x32_bf16 v[92:95], v[16:19], v[170:173], v[92:95]
	v_mfma_f32_16x16x32_bf16 v[16:19], v[16:19], v[210:213], v[88:91]
	v_mfma_f32_16x16x32_bf16 v[120:123], v[20:23], v[154:157], v[16:19]
	v_mfma_f32_16x16x32_bf16 v[16:19], v[32:35], v[170:173], v[166:169]
	v_mfma_f32_16x16x32_bf16 v[108:111], v[36:39], v[206:209], v[16:19]
	v_mfma_f32_16x16x32_bf16 v[16:19], v[32:35], v[210:213], v[174:177]
	v_mfma_f32_16x16x32_bf16 v[104:107], v[36:39], v[154:157], v[16:19]
	v_mfma_f32_16x16x32_bf16 v[16:19], v[48:51], v[170:173], v[76:79]
	v_mfma_f32_16x16x32_bf16 v[124:127], v[20:23], v[206:209], v[92:95]
	v_mfma_f32_16x16x32_bf16 v[92:95], v[52:55], v[206:209], v[16:19]
	v_mfma_f32_16x16x32_bf16 v[16:19], v[48:51], v[210:213], v[72:75]
	v_mfma_f32_16x16x32_bf16 v[88:91], v[52:55], v[154:157], v[16:19]
	v_mfma_f32_16x16x32_bf16 v[16:19], v[222:225], v[170:173], v[178:181]
	v_mfma_f32_16x16x32_bf16 v[76:79], v[226:229], v[206:209], v[16:19]
	v_mfma_f32_16x16x32_bf16 v[16:19], v[222:225], v[210:213], v[182:185]
	v_mfma_f32_16x16x32_bf16 v[72:75], v[226:229], v[154:157], v[16:19]
	s_barrier
	s_setprio 0
	ds_read_b128 v[166:169], v153 offset:49152
	ds_read_b128 v[174:177], v153 offset:50176
	ds_read_b128 v[178:181], v152 offset:49152
	ds_read_b128 v[182:185], v152 offset:50176
	ds_read_b128 v[214:217], v151 offset:49152
	ds_read_b128 v[222:225], v151 offset:50176
	ds_read_b128 v[226:229], v150 offset:49152
	ds_read_b128 v[150:153], v150 offset:50176
	s_setprio 1
	s_barrier
	s_waitcnt lgkmcnt(0)
	v_mfma_f32_16x16x32_bf16 v[16:19], v[166:169], v[0:3], v[60:63]
	v_mfma_f32_16x16x32_bf16 v[52:55], v[174:177], v[4:7], v[16:19]
	v_mfma_f32_16x16x32_bf16 v[16:19], v[166:169], v[194:197], v[56:59]
	v_mfma_f32_16x16x32_bf16 v[48:51], v[174:177], v[198:201], v[16:19]
	v_mfma_f32_16x16x32_bf16 v[16:19], v[178:181], v[0:3], v[202:205]
	v_mfma_f32_16x16x32_bf16 v[36:39], v[182:185], v[4:7], v[16:19]
	v_mfma_f32_16x16x32_bf16 v[16:19], v[178:181], v[194:197], v[218:221]
	v_mfma_f32_16x16x32_bf16 v[32:35], v[182:185], v[198:201], v[16:19]
	v_mfma_f32_16x16x32_bf16 v[16:19], v[214:217], v[0:3], v[44:47]
	v_mfma_f32_16x16x32_bf16 v[0:3], v[226:229], v[0:3], v[136:139]
	v_mfma_f32_16x16x32_bf16 v[20:23], v[222:225], v[4:7], v[16:19]
	v_mfma_f32_16x16x32_bf16 v[16:19], v[214:217], v[194:197], v[40:43]
	v_mfma_f32_16x16x32_bf16 v[4:7], v[150:153], v[4:7], v[0:3]
	v_mfma_f32_16x16x32_bf16 v[0:3], v[226:229], v[194:197], v[140:143]
	v_mfma_f32_16x16x32_bf16 v[16:19], v[222:225], v[198:201], v[16:19]
	v_mfma_f32_16x16x32_bf16 v[0:3], v[150:153], v[198:201], v[0:3]
	s_setprio 0
	s_setprio 1
	v_mfma_f32_16x16x32_bf16 v[24:27], v[166:169], v[210:213], v[24:27]
	v_mfma_f32_16x16x32_bf16 v[56:59], v[174:177], v[154:157], v[24:27]
	v_mfma_f32_16x16x32_bf16 v[24:27], v[178:181], v[170:173], v[158:161]
	v_mfma_f32_16x16x32_bf16 v[44:47], v[182:185], v[206:209], v[24:27]
	v_mfma_f32_16x16x32_bf16 v[24:27], v[178:181], v[210:213], v[162:165]
	v_mfma_f32_16x16x32_bf16 v[8:11], v[214:217], v[210:213], v[8:11]
	v_mfma_f32_16x16x32_bf16 v[28:31], v[166:169], v[170:173], v[28:31]
	v_mfma_f32_16x16x32_bf16 v[40:43], v[182:185], v[154:157], v[24:27]
	v_mfma_f32_16x16x32_bf16 v[12:15], v[214:217], v[170:173], v[12:15]
	v_mfma_f32_16x16x32_bf16 v[24:27], v[222:225], v[154:157], v[8:11]
	v_mfma_f32_16x16x32_bf16 v[8:11], v[226:229], v[170:173], v[186:189]
	v_mfma_f32_16x16x32_bf16 v[60:63], v[174:177], v[206:209], v[28:31]
	v_mfma_f32_16x16x32_bf16 v[28:31], v[222:225], v[206:209], v[12:15]
	v_mfma_f32_16x16x32_bf16 v[12:15], v[150:153], v[206:209], v[8:11]
	v_mfma_f32_16x16x32_bf16 v[8:11], v[226:229], v[210:213], v[190:193]
	v_mfma_f32_16x16x32_bf16 v[8:11], v[150:153], v[154:157], v[8:11]
	s_barrier
	s_setprio 0
	v_cmp_gt_u32_e32 vcc, s55, v144
	s_and_saveexec_b64 s[36:37], vcc
	s_cbranch_execz .LBB0_1385
	s_barrier
.LBB0_1385:
	s_or_b64 exec, exec, s[36:37]
	v_lshl_add_u32 v136, v149, 1, 0
	v_lshlrev_b32_e32 v137, 1, v148
	v_lshlrev_b32_e32 v139, 11, v145
	v_lshlrev_b32_e32 v140, 15, v147
	v_add3_u32 v136, v136, v139, v140
	v_xor_b32_e32 v139, v137, v145
	v_lshlrev_b32_e32 v139, 5, v139
	v_cvt_pk_bf16_f32 v116, v116, v116
	v_add_u32_e32 v140, v136, v139
	ds_write_b16_d16_hi v140, v116
	v_bitop3_b32 v116, v137, v145, 1 bitop3:0x36
	v_lshlrev_b32_e32 v116, 5, v116
	v_cvt_pk_bf16_f32 v112, v112, v112
	v_add_u32_e32 v141, v136, v116
	v_bitop3_b32 v138, v137, v145, 8 bitop3:0x36
	ds_write_b16_d16_hi v141, v112
	v_bfe_u32 v112, v124, 16, 1
	v_add3_u32 v112, v124, v112, s56
	v_lshlrev_b32_e32 v124, 5, v138
	v_add_u32_e32 v138, v136, v124
	ds_write_b16_d16_hi v138, v112
	v_bitop3_b32 v112, v137, v145, 9 bitop3:0x36
	v_lshlrev_b32_e32 v112, 5, v112
	v_cvt_pk_bf16_f32 v120, v120, v120
	v_add_u32_e32 v137, v136, v112
	ds_write_b16_d16_hi v137, v120
	v_cvt_pk_bf16_f32 v117, v117, v117
	ds_write_b16_d16_hi v140, v117 offset:512
	v_cvt_pk_bf16_f32 v113, v113, v113
	ds_write_b16_d16_hi v141, v113 offset:512
	v_bfe_u32 v113, v125, 16, 1
	v_add3_u32 v113, v125, v113, s56
	ds_write_b16_d16_hi v138, v113 offset:512
	v_bfe_u32 v113, v121, 16, 1
	v_add3_u32 v113, v121, v113, s56
	ds_write_b16_d16_hi v137, v113 offset:512
	v_bfe_u32 v113, v118, 16, 1
	v_add3_u32 v113, v118, v113, s56
	ds_write_b16_d16_hi v140, v113 offset:1024
	v_bfe_u32 v113, v114, 16, 1
	v_add3_u32 v113, v114, v113, s56
	ds_write_b16_d16_hi v141, v113 offset:1024
	v_bfe_u32 v113, v126, 16, 1
	v_add3_u32 v113, v126, v113, s56
	ds_write_b16_d16_hi v138, v113 offset:1024
	v_bfe_u32 v113, v122, 16, 1
	v_add3_u32 v113, v122, v113, s56
	ds_write_b16_d16_hi v137, v113 offset:1024
	v_bfe_u32 v113, v119, 16, 1
; __device__ __forceinline__ u16 f2bf(float f) { unsigned u = __float_as_uint(f); u += 0x7fffu + ((u >> 16) & 1u); return (u16)(u >> 16); }
; __device__ __forceinline__ float frcp(float x) { return __builtin_amdgcn_rcpf(x); }
; template <int EPI> ...
;     ...
;           const int r = ai * 128 + wr * 64 + m * 16 + fq * 4 + j;
;           float rs = 1.0f;
;           if (EPI != EPI_RES) rs = e.rstd[brow + r];
;           char* rowp = tb + r * RB + fr * 2;
;           if (EPI == EPI_GU) {
; #pragma unroll
;             for (int n = 0; n < 2; ++n) {
;               float g = acc[ai][0][m][n][j] * rs, u = acc[ai][1][m][n][j] * rs;
;               float h = g * frcp(1.0f + __expf(-g)) * u;
;               const int seg = (wc * 2 + n) ^ fq;
;               *(u16*)(rowp + seg * 32) = f2bf(h);
;             }
;           } else {
; #pragma unroll
;             for (int bj = 0; bj < 2; ++bj)
; #pragma unroll
;               for (int n = 0; n < 2; ++n) {
;                 const int seg = (bj * 8 + wc * 2 + n) ^ fq;
;                 *(u16*)(rowp + seg * 32) = f2bf(acc[ai][bj][m][n][j] * rs);
;               }
	v_add3_u32 v113, v119, v113, s56
	ds_write_b16_d16_hi v140, v113 offset:1536
	v_bfe_u32 v113, v115, 16, 1
	v_add3_u32 v113, v115, v113, s56
	ds_write_b16_d16_hi v141, v113 offset:1536
	v_bfe_u32 v113, v127, 16, 1
	v_add3_u32 v113, v127, v113, s56
	ds_write_b16_d16_hi v138, v113 offset:1536
	v_bfe_u32 v113, v123, 16, 1
	v_add3_u32 v113, v123, v113, s56
	ds_write_b16_d16_hi v137, v113 offset:1536
	v_cvt_pk_bf16_f32 v100, v100, v100
	ds_write_b16_d16_hi v140, v100 offset:8192
	v_cvt_pk_bf16_f32 v96, v96, v96
	ds_write_b16_d16_hi v141, v96 offset:8192
	v_bfe_u32 v96, v108, 16, 1
	v_add3_u32 v96, v108, v96, s56
	ds_write_b16_d16_hi v138, v96 offset:8192
	v_bfe_u32 v96, v104, 16, 1
	v_add3_u32 v96, v104, v96, s56
	ds_write_b16_d16_hi v137, v96 offset:8192
	v_bfe_u32 v96, v101, 16, 1
	v_add3_u32 v96, v101, v96, s56
	ds_write_b16_d16_hi v140, v96 offset:8704
	v_bfe_u32 v96, v97, 16, 1
	v_add3_u32 v96, v97, v96, s56
	ds_write_b16_d16_hi v141, v96 offset:8704
	v_bfe_u32 v96, v109, 16, 1
	v_add3_u32 v96, v109, v96, s56
	ds_write_b16_d16_hi v138, v96 offset:8704
	v_bfe_u32 v96, v105, 16, 1
	v_add3_u32 v96, v105, v96, s56
	ds_write_b16_d16_hi v137, v96 offset:8704
	v_bfe_u32 v96, v102, 16, 1
	v_add3_u32 v96, v102, v96, s56
	ds_write_b16_d16_hi v140, v96 offset:9216
	v_bfe_u32 v96, v98, 16, 1
	v_add3_u32 v96, v98, v96, s56
	ds_write_b16_d16_hi v141, v96 offset:9216
	v_bfe_u32 v96, v110, 16, 1
	v_add3_u32 v96, v110, v96, s56
	ds_write_b16_d16_hi v138, v96 offset:9216
	v_bfe_u32 v96, v106, 16, 1
	v_add3_u32 v96, v106, v96, s56
	ds_write_b16_d16_hi v137, v96 offset:9216
	v_bfe_u32 v96, v103, 16, 1
	v_add3_u32 v96, v103, v96, s56
	ds_write_b16_d16_hi v140, v96 offset:9728
	v_bfe_u32 v96, v99, 16, 1
	v_add3_u32 v96, v99, v96, s56
	ds_write_b16_d16_hi v141, v96 offset:9728
	v_bfe_u32 v96, v111, 16, 1
	v_add3_u32 v96, v111, v96, s56
	ds_write_b16_d16_hi v138, v96 offset:9728
	v_bfe_u32 v96, v107, 16, 1
	v_add3_u32 v96, v107, v96, s56
	ds_write_b16_d16_hi v137, v96 offset:9728
	v_bfe_u32 v96, v84, 16, 1
	v_add3_u32 v84, v84, v96, s56
	ds_write_b16_d16_hi v140, v84 offset:16384
	v_bfe_u32 v84, v80, 16, 1
	v_add3_u32 v80, v80, v84, s56
	ds_write_b16_d16_hi v141, v80 offset:16384
	v_bfe_u32 v80, v92, 16, 1
	v_add3_u32 v80, v92, v80, s56
	ds_write_b16_d16_hi v138, v80 offset:16384
	v_bfe_u32 v80, v88, 16, 1
	v_add3_u32 v80, v88, v80, s56
	ds_write_b16_d16_hi v137, v80 offset:16384
	v_bfe_u32 v80, v85, 16, 1
	v_add3_u32 v80, v85, v80, s56
	ds_write_b16_d16_hi v140, v80 offset:16896
	v_bfe_u32 v80, v81, 16, 1
	v_add3_u32 v80, v81, v80, s56
	ds_write_b16_d16_hi v141, v80 offset:16896
	v_bfe_u32 v80, v93, 16, 1
	v_add3_u32 v80, v93, v80, s56
	ds_write_b16_d16_hi v138, v80 offset:16896
	v_bfe_u32 v80, v89, 16, 1
	v_add3_u32 v80, v89, v80, s56
	ds_write_b16_d16_hi v137, v80 offset:16896
	v_bfe_u32 v80, v86, 16, 1
	v_add3_u32 v80, v86, v80, s56
	ds_write_b16_d16_hi v140, v80 offset:17408
	v_bfe_u32 v80, v82, 16, 1
	v_add3_u32 v80, v82, v80, s56
	ds_write_b16_d16_hi v141, v80 offset:17408
	v_bfe_u32 v80, v94, 16, 1
	v_add3_u32 v80, v94, v80, s56
	ds_write_b16_d16_hi v138, v80 offset:17408
	v_bfe_u32 v80, v90, 16, 1
	v_add3_u32 v80, v90, v80, s56
	ds_write_b16_d16_hi v137, v80 offset:17408
	v_bfe_u32 v80, v87, 16, 1
	v_add3_u32 v80, v87, v80, s56
	ds_write_b16_d16_hi v140, v80 offset:17920
	v_bfe_u32 v80, v83, 16, 1
	v_add3_u32 v80, v83, v80, s56
	ds_write_b16_d16_hi v141, v80 offset:17920
	v_bfe_u32 v80, v95, 16, 1
	v_add3_u32 v80, v95, v80, s56
	ds_write_b16_d16_hi v138, v80 offset:17920
	v_bfe_u32 v80, v91, 16, 1
	v_add3_u32 v80, v91, v80, s56
	ds_write_b16_d16_hi v137, v80 offset:17920
	v_bfe_u32 v80, v68, 16, 1
	v_add3_u32 v68, v68, v80, s56
	ds_write_b16_d16_hi v140, v68 offset:24576
	v_bfe_u32 v68, v64, 16, 1
	v_add3_u32 v64, v64, v68, s56
	ds_write_b16_d16_hi v141, v64 offset:24576
	v_bfe_u32 v64, v76, 16, 1
	v_add3_u32 v64, v76, v64, s56
	ds_write_b16_d16_hi v138, v64 offset:24576
	v_bfe_u32 v64, v72, 16, 1
	v_add3_u32 v64, v72, v64, s56
	ds_write_b16_d16_hi v137, v64 offset:24576
	v_bfe_u32 v64, v69, 16, 1
	v_add3_u32 v64, v69, v64, s56
	ds_write_b16_d16_hi v140, v64 offset:25088
	v_bfe_u32 v64, v65, 16, 1
	v_add3_u32 v64, v65, v64, s56
	ds_write_b16_d16_hi v141, v64 offset:25088
	v_bfe_u32 v64, v77, 16, 1
	v_add3_u32 v64, v77, v64, s56
	ds_write_b16_d16_hi v138, v64 offset:25088
	v_bfe_u32 v64, v73, 16, 1
	v_add3_u32 v64, v73, v64, s56
	ds_write_b16_d16_hi v137, v64 offset:25088
	v_bfe_u32 v64, v70, 16, 1
	v_add3_u32 v64, v70, v64, s56
	ds_write_b16_d16_hi v140, v64 offset:25600
	v_bfe_u32 v64, v66, 16, 1
	v_add3_u32 v64, v66, v64, s56
	ds_write_b16_d16_hi v141, v64 offset:25600
	v_bfe_u32 v64, v78, 16, 1
	v_add3_u32 v64, v78, v64, s56
	ds_write_b16_d16_hi v138, v64 offset:25600
	v_bfe_u32 v64, v74, 16, 1
	v_add3_u32 v64, v74, v64, s56
	ds_write_b16_d16_hi v137, v64 offset:25600
	v_bfe_u32 v64, v71, 16, 1
	v_add3_u32 v64, v71, v64, s56
	ds_write_b16_d16_hi v140, v64 offset:26112
	v_bfe_u32 v64, v67, 16, 1
	v_add3_u32 v64, v67, v64, s56
	ds_write_b16_d16_hi v141, v64 offset:26112
	v_bfe_u32 v64, v79, 16, 1
	v_add3_u32 v64, v79, v64, s56
	ds_write_b16_d16_hi v138, v64 offset:26112
	v_bfe_u32 v64, v75, 16, 1
	v_add3_u32 v64, v75, v64, s56
	ds_write_b16_d16_hi v137, v64 offset:26112
	v_add_u32_e32 v64, 0x10000, v136
	v_cvt_pk_bf16_f32 v52, v52, v52
	v_add_u32_e32 v65, v64, v139
	ds_write_b16_d16_hi v65, v52
	v_cvt_pk_bf16_f32 v48, v48, v48
	v_add_u32_e32 v52, v64, v116
	ds_write_b16_d16_hi v52, v48
	v_bfe_u32 v48, v60, 16, 1
	v_add3_u32 v48, v60, v48, s56
	v_add_u32_e32 v52, v64, v124
	ds_write_b16_d16_hi v52, v48
	v_bfe_u32 v48, v56, 16, 1
	v_add3_u32 v48, v56, v48, s56
; __device__ __forceinline__ u16 f2bf(float f) { unsigned u = __float_as_uint(f); u += 0x7fffu + ((u >> 16) & 1u); return (u16)(u >> 16); }
; __device__ __forceinline__ float frcp(float x) { return __builtin_amdgcn_rcpf(x); }
; template <int EPI> ...
;     ...
;           const int r = ai * 128 + wr * 64 + m * 16 + fq * 4 + j;
;           float rs = 1.0f;
;           if (EPI != EPI_RES) rs = e.rstd[brow + r];
;           char* rowp = tb + r * RB + fr * 2;
;           if (EPI == EPI_GU) {
; #pragma unroll
;             for (int n = 0; n < 2; ++n) {
;               float g = acc[ai][0][m][n][j] * rs, u = acc[ai][1][m][n][j] * rs;
;               float h = g * frcp(1.0f + __expf(-g)) * u;
;               const int seg = (wc * 2 + n) ^ fq;
;               *(u16*)(rowp + seg * 32) = f2bf(h);
;             }
;           } else {
; #pragma unroll
;             for (int bj = 0; bj < 2; ++bj)
; #pragma unroll
;               for (int n = 0; n < 2; ++n) {
;                 const int seg = (bj * 8 + wc * 2 + n) ^ fq;
;                 *(u16*)(rowp + seg * 32) = f2bf(acc[ai][bj][m][n][j] * rs);
;               }
	v_add_u32_e32 v52, v64, v112
	ds_write_b16_d16_hi v52, v48
	v_add_u32_e32 v48, 0x10200, v136
	v_bfe_u32 v52, v53, 16, 1
	v_add3_u32 v52, v53, v52, s56
	v_add_u32_e32 v53, v48, v139
	ds_write_b16_d16_hi v53, v52
	v_cvt_pk_bf16_f32 v49, v49, v49
	v_add_u32_e32 v52, v48, v116
	ds_write_b16_d16_hi v52, v49
	v_bfe_u32 v49, v61, 16, 1
	v_add3_u32 v49, v61, v49, s56
	v_add_u32_e32 v52, v48, v124
	ds_write_b16_d16_hi v52, v49
	v_bfe_u32 v49, v57, 16, 1
	v_add3_u32 v49, v57, v49, s56
	v_add_u32_e32 v48, v48, v112
	ds_write_b16_d16_hi v48, v49
	v_add_u32_e32 v48, 0x10400, v136
	v_bfe_u32 v49, v54, 16, 1
	v_add3_u32 v49, v54, v49, s56
	v_add_u32_e32 v52, v48, v139
	ds_write_b16_d16_hi v52, v49
	v_bfe_u32 v49, v50, 16, 1
	v_add3_u32 v49, v50, v49, s56
	v_add_u32_e32 v50, v48, v116
	ds_write_b16_d16_hi v50, v49
	v_bfe_u32 v49, v62, 16, 1
	v_add3_u32 v49, v62, v49, s56
	v_add_u32_e32 v50, v48, v124
	ds_write_b16_d16_hi v50, v49
	v_bfe_u32 v49, v58, 16, 1
	v_add3_u32 v49, v58, v49, s56
	v_add_u32_e32 v48, v48, v112
	ds_write_b16_d16_hi v48, v49
	v_add_u32_e32 v48, 0x10600, v136
	v_bfe_u32 v49, v55, 16, 1
	v_add3_u32 v49, v55, v49, s56
	v_add_u32_e32 v50, v48, v139
	ds_write_b16_d16_hi v50, v49
	v_bfe_u32 v49, v51, 16, 1
	v_add3_u32 v49, v51, v49, s56
	v_add_u32_e32 v50, v48, v116
	ds_write_b16_d16_hi v50, v49
	v_bfe_u32 v49, v63, 16, 1
	v_add3_u32 v49, v63, v49, s56
	v_add_u32_e32 v50, v48, v124
	ds_write_b16_d16_hi v50, v49
	v_bfe_u32 v49, v59, 16, 1
	v_add3_u32 v49, v59, v49, s56
	v_add_u32_e32 v48, v48, v112
	ds_write_b16_d16_hi v48, v49
	v_add_u32_e32 v48, 0x12000, v136
	v_cvt_pk_bf16_f32 v36, v36, v36
	v_add_u32_e32 v49, v48, v139
	ds_write_b16_d16_hi v49, v36
	v_cvt_pk_bf16_f32 v32, v32, v32
	v_add_u32_e32 v36, v48, v116
	ds_write_b16_d16_hi v36, v32
	v_bfe_u32 v32, v44, 16, 1
	v_add3_u32 v32, v44, v32, s56
	v_add_u32_e32 v36, v48, v124
	ds_write_b16_d16_hi v36, v32
	v_bfe_u32 v32, v40, 16, 1
	v_add3_u32 v32, v40, v32, s56
	v_add_u32_e32 v36, v48, v112
	ds_write_b16_d16_hi v36, v32
	v_add_u32_e32 v32, 0x12200, v136
	v_bfe_u32 v36, v37, 16, 1
	v_add3_u32 v36, v37, v36, s56
	v_add_u32_e32 v37, v32, v139
	ds_write_b16_d16_hi v37, v36
	v_cvt_pk_bf16_f32 v33, v33, v33
	v_add_u32_e32 v36, v32, v116
	ds_write_b16_d16_hi v36, v33
	v_bfe_u32 v33, v45, 16, 1
	v_add3_u32 v33, v45, v33, s56
	v_add_u32_e32 v36, v32, v124
	ds_write_b16_d16_hi v36, v33
	v_bfe_u32 v33, v41, 16, 1
	v_add3_u32 v33, v41, v33, s56
	v_add_u32_e32 v32, v32, v112
	ds_write_b16_d16_hi v32, v33
	v_add_u32_e32 v32, 0x12400, v136
	v_bfe_u32 v33, v38, 16, 1
	v_add3_u32 v33, v38, v33, s56
	v_add_u32_e32 v36, v32, v139
	ds_write_b16_d16_hi v36, v33
	v_bfe_u32 v33, v34, 16, 1
	v_add3_u32 v33, v34, v33, s56
	v_add_u32_e32 v34, v32, v116
	ds_write_b16_d16_hi v34, v33
	v_bfe_u32 v33, v46, 16, 1
	v_add3_u32 v33, v46, v33, s56
	v_add_u32_e32 v34, v32, v124
	ds_write_b16_d16_hi v34, v33
	v_bfe_u32 v33, v42, 16, 1
	v_add3_u32 v33, v42, v33, s56
	v_add_u32_e32 v32, v32, v112
	ds_write_b16_d16_hi v32, v33
	v_add_u32_e32 v32, 0x12600, v136
	v_bfe_u32 v33, v39, 16, 1
	v_add3_u32 v33, v39, v33, s56
	v_add_u32_e32 v34, v32, v139
	ds_write_b16_d16_hi v34, v33
	v_bfe_u32 v33, v35, 16, 1
	v_add3_u32 v33, v35, v33, s56
	v_add_u32_e32 v34, v32, v116
	ds_write_b16_d16_hi v34, v33
	v_bfe_u32 v33, v47, 16, 1
	v_add3_u32 v33, v47, v33, s56
	v_add_u32_e32 v34, v32, v124
	ds_write_b16_d16_hi v34, v33
	v_bfe_u32 v33, v43, 16, 1
	v_add3_u32 v33, v43, v33, s56
	v_add_u32_e32 v32, v32, v112
	ds_write_b16_d16_hi v32, v33
	v_add_u32_e32 v32, 0x14000, v136
	v_cvt_pk_bf16_f32 v20, v20, v20
	v_add_u32_e32 v33, v32, v139
	ds_write_b16_d16_hi v33, v20
	v_cvt_pk_bf16_f32 v16, v16, v16
	v_add_u32_e32 v20, v32, v116
	ds_write_b16_d16_hi v20, v16
	v_bfe_u32 v16, v28, 16, 1
	v_add3_u32 v16, v28, v16, s56
	v_add_u32_e32 v20, v32, v124
	ds_write_b16_d16_hi v20, v16
	v_bfe_u32 v16, v24, 16, 1
	v_add3_u32 v16, v24, v16, s56
	v_add_u32_e32 v20, v32, v112
	ds_write_b16_d16_hi v20, v16
	v_add_u32_e32 v16, 0x14200, v136
	v_bfe_u32 v20, v21, 16, 1
	v_add3_u32 v20, v21, v20, s56
; __device__ __forceinline__ u16 f2bf(float f) { unsigned u = __float_as_uint(f); u += 0x7fffu + ((u >> 16) & 1u); return (u16)(u >> 16); }
; __device__ __forceinline__ int opaque_tid() { int t; asm volatile("v_mov_b32 %0, %1" : "=v"(t) : "v"((int)threadIdx.x)); return t; }
; __device__ __forceinline__ float frcp(float x) { return __builtin_amdgcn_rcpf(x); }
; template <int EPI> ...
;     ...
;           const int r = ai * 128 + wr * 64 + m * 16 + fq * 4 + j;
;           float rs = 1.0f;
;           if (EPI != EPI_RES) rs = e.rstd[brow + r];
;           char* rowp = tb + r * RB + fr * 2;
;           if (EPI == EPI_GU) {
; #pragma unroll
;             for (int n = 0; n < 2; ++n) {
;               float g = acc[ai][0][m][n][j] * rs, u = acc[ai][1][m][n][j] * rs;
;               float h = g * frcp(1.0f + __expf(-g)) * u;
;               const int seg = (wc * 2 + n) ^ fq;
;               *(u16*)(rowp + seg * 32) = f2bf(h);
;             }
;           } else {
; #pragma unroll
;             for (int bj = 0; bj < 2; ++bj)
; #pragma unroll
;               for (int n = 0; n < 2; ++n) {
;                 const int seg = (bj * 8 + wc * 2 + n) ^ fq;
;                 *(u16*)(rowp + seg * 32) = f2bf(acc[ai][bj][m][n][j] * rs);
;               }
;           }
;         }
;     __syncthreads();
;     constexpr int CPR = RB / 16;
;     constexpr int RPI = 512 / CPR;
;     const int tid2 = opaque_tid();
;     const int cc = tid2 % CPR, r0 = tid2 / CPR;
;     u16* gp = (EPI == EPI_GU) ? e.out + ((size_t)((e.bcol >> 6) + (cc >> 3)) * 256 + r0) * 64 + (cc & 7) * 8
;                               : e.out + (size_t)r0 * e.ld + e.bcol + cc * 8;
;     const size_t gstep = (EPI == EPI_GU) ? (size_t)RPI * 64 : (size_t)RPI * e.ld;
	v_add_u32_e32 v21, v16, v139
	ds_write_b16_d16_hi v21, v20
	v_cvt_pk_bf16_f32 v17, v17, v17
	v_add_u32_e32 v20, v16, v116
	ds_write_b16_d16_hi v20, v17
	v_bfe_u32 v17, v29, 16, 1
	v_add3_u32 v17, v29, v17, s56
	v_add_u32_e32 v20, v16, v124
	ds_write_b16_d16_hi v20, v17
	v_bfe_u32 v17, v25, 16, 1
	v_add3_u32 v17, v25, v17, s56
	v_add_u32_e32 v16, v16, v112
	ds_write_b16_d16_hi v16, v17
	v_add_u32_e32 v16, 0x14400, v136
	v_bfe_u32 v17, v22, 16, 1
	v_add3_u32 v17, v22, v17, s56
	v_add_u32_e32 v20, v16, v139
	ds_write_b16_d16_hi v20, v17
	v_bfe_u32 v17, v18, 16, 1
	v_add3_u32 v17, v18, v17, s56
	v_add_u32_e32 v18, v16, v116
	ds_write_b16_d16_hi v18, v17
	v_bfe_u32 v17, v30, 16, 1
	v_add3_u32 v17, v30, v17, s56
	v_add_u32_e32 v18, v16, v124
	ds_write_b16_d16_hi v18, v17
	v_bfe_u32 v17, v26, 16, 1
	v_add3_u32 v17, v26, v17, s56
	v_add_u32_e32 v16, v16, v112
	ds_write_b16_d16_hi v16, v17
	v_add_u32_e32 v16, 0x14600, v136
	v_bfe_u32 v17, v23, 16, 1
	v_add3_u32 v17, v23, v17, s56
	v_add_u32_e32 v18, v16, v139
	ds_write_b16_d16_hi v18, v17
	v_bfe_u32 v17, v19, 16, 1
	v_add3_u32 v17, v19, v17, s56
	v_add_u32_e32 v18, v16, v116
	ds_write_b16_d16_hi v18, v17
	v_bfe_u32 v17, v31, 16, 1
	v_add3_u32 v17, v31, v17, s56
	v_add_u32_e32 v18, v16, v124
	ds_write_b16_d16_hi v18, v17
	v_bfe_u32 v17, v27, 16, 1
	v_add3_u32 v17, v27, v17, s56
	v_add_u32_e32 v16, v16, v112
	ds_write_b16_d16_hi v16, v17
	v_add_u32_e32 v16, 0x16000, v136
	v_cvt_pk_bf16_f32 v4, v4, v4
	v_add_u32_e32 v17, v16, v139
	ds_write_b16_d16_hi v17, v4
	v_cvt_pk_bf16_f32 v0, v0, v0
	v_add_u32_e32 v4, v16, v116
	ds_write_b16_d16_hi v4, v0
	v_bfe_u32 v0, v12, 16, 1
	v_add3_u32 v0, v12, v0, s56
	v_add_u32_e32 v4, v16, v124
	ds_write_b16_d16_hi v4, v0
	v_bfe_u32 v0, v8, 16, 1
	v_add3_u32 v0, v8, v0, s56
	v_add_u32_e32 v4, v16, v112
	ds_write_b16_d16_hi v4, v0
	v_add_u32_e32 v0, 0x16200, v136
	v_bfe_u32 v4, v5, 16, 1
	v_add3_u32 v4, v5, v4, s56
	v_add_u32_e32 v5, v0, v139
	ds_write_b16_d16_hi v5, v4
	v_cvt_pk_bf16_f32 v1, v1, v1
	v_add_u32_e32 v4, v0, v116
	ds_write_b16_d16_hi v4, v1
	v_bfe_u32 v1, v13, 16, 1
	v_add3_u32 v1, v13, v1, s56
	v_add_u32_e32 v4, v0, v124
	ds_write_b16_d16_hi v4, v1
	v_bfe_u32 v1, v9, 16, 1
	v_add3_u32 v1, v9, v1, s56
	v_add_u32_e32 v0, v0, v112
	ds_write_b16_d16_hi v0, v1
	v_add_u32_e32 v0, 0x16400, v136
	v_bfe_u32 v1, v6, 16, 1
	v_add3_u32 v1, v6, v1, s56
	v_add_u32_e32 v4, v0, v139
	ds_write_b16_d16_hi v4, v1
	v_bfe_u32 v1, v2, 16, 1
	v_add3_u32 v1, v2, v1, s56
	v_add_u32_e32 v2, v0, v116
	ds_write_b16_d16_hi v2, v1
	v_bfe_u32 v1, v14, 16, 1
	v_add3_u32 v1, v14, v1, s56
	v_add_u32_e32 v2, v0, v124
	ds_write_b16_d16_hi v2, v1
	v_bfe_u32 v1, v10, 16, 1
	v_add3_u32 v1, v10, v1, s56
	v_add_u32_e32 v0, v0, v112
	ds_write_b16_d16_hi v0, v1
	v_add_u32_e32 v0, 0x16600, v136
	v_bfe_u32 v1, v7, 16, 1
	v_add3_u32 v1, v7, v1, s56
	v_add_u32_e32 v2, v0, v139
	ds_write_b16_d16_hi v2, v1
	v_bfe_u32 v1, v3, 16, 1
	v_add3_u32 v1, v3, v1, s56
	v_add_u32_e32 v2, v0, v116
	ds_write_b16_d16_hi v2, v1
	v_bfe_u32 v1, v15, 16, 1
	v_add3_u32 v1, v15, v1, s56
	v_add_u32_e32 v2, v0, v124
	ds_write_b16_d16_hi v2, v1
	v_bfe_u32 v1, v11, 16, 1
	v_add3_u32 v1, v11, v1, s56
	v_add_u32_e32 v0, v0, v112
	ds_write_b16_d16_hi v0, v1
	s_waitcnt vmcnt(0) lgkmcnt(0)
	s_barrier
	v_mov_b32 v0, v146
	s_lshl_b64 s[24:25], s[24:25], 1
	v_ashrrev_i32_e32 v1, 31, v0
	v_lshrrev_b32_e32 v1, 27, v1
	v_add_u32_e32 v1, v0, v1
	v_ashrrev_i32_e32 v2, 5, v1
	s_add_u32 s24, s74, s24
	v_and_b32_e32 v1, 0xffffffe0, v1
	v_ashrrev_i32_e32 v3, 31, v2
	s_addc_u32 s25, s75, s25
	s_lshl_b32 s22, s22, 8
	v_sub_u32_e32 v6, v0, v1
	v_lshlrev_b64 v[0:1], 12, v[2:3]
	v_lshrrev_b32_e32 v3, 1, v2
	v_lshl_add_u64 v[0:1], s[24:25], 0, v[0:1]
	s_ashr_i32 s23, s22, 31
	v_lshlrev_b32_e32 v4, 3, v6
	v_bitop3_b32 v3, v3, v6, 6 bitop3:0x6c
	v_lshl_add_u64 v[0:1], s[22:23], 1, v[0:1]
	v_ashrrev_i32_e32 v5, 31, v4
	v_lshlrev_b32_e32 v2, 9, v2
	v_lshlrev_b32_e32 v3, 4, v3
	v_lshl_add_u64 v[0:1], v[4:5], 1, v[0:1]
	v_add3_u32 v2, 0, v2, v3
	s_mov_b32 s22, 0

; __device__ __forceinline__ u16 f2bf(float f) { unsigned u = __float_as_uint(f); u += 0x7fffu + ((u >> 16) & 1u); return (u16)(u >> 16); }
; __device__ __forceinline__ void tr_job(float* lds, int& gt, const float* __restrict__ src, int src_ld, const float* __restrict__ gain,
;                        u16* __restrict__ dst, int dst_ld, int K, int Nvalid, int Ndst) {
;     ...
; #pragma unroll 16
;     for (int n = 0; n < 32; ++n) {
;       const float v = wl[lane * 33 + n];
;       if (gk < K && n0 + n < Ndst) dst[(size_t)(n0 + n) * dst_ld + gk] = f2bf(v);
;     }
.LBB0_1603:
	s_and_saveexec_b64 s[4:5], s[0:1]
	s_cbranch_execz .LBB0_1608
	v_add_u32_e32 v72, s31, v70
	v_cmp_gt_i32_e32 vcc, s26, v72
	s_and_saveexec_b64 s[6:7], vcc
	s_cbranch_execz .LBB0_1606
	ds_read_b32 v73, v71
	v_add_co_u32_e32 v74, vcc, 0xfffd7000, v32
	s_waitcnt lgkmcnt(0)
	v_cvt_pk_bf16_f32 v73, v73, v73
	v_addc_co_u32_e32 v75, vcc, -1, v33, vcc
	global_store_short_d16_hi v[74:75], v73, off offset:-1024

; __device__ __forceinline__ int opaque_tid() { int t; asm volatile("v_mov_b32 %0, %1" : "=v"(t) : "v"((int)threadIdx.x)); return t; }
; #define STAGE(P, BASE, kt) do { const char* _g = (const char*)(BASE) + (size_t)((kt) * (BK * 2)); \
;     __builtin_amdgcn_global_load_lds((const unsigned*)(_g + (size_t)goff0), (unsigned*)((char*)(P) + tid_ * 16), 16, 0, 0); \
;     __builtin_amdgcn_global_load_lds((const unsigned*)(_g + (size_t)goff1), (unsigned*)((char*)(P) + tid_ * 16 + 8192), 16, 0, 0); } while (0)
; #define STAGEA(P, BASE, kt) do { const char* _g = (const char*)(BASE) + (size_t)((kt) * a_kbytes); \
;     __builtin_amdgcn_global_load_lds((const unsigned*)(_g + (size_t)goffA0), (unsigned*)((char*)(P) + tid_ * 16), 16, 0, 0); \
;     __builtin_amdgcn_global_load_lds((const unsigned*)(_g + (size_t)goffA1), (unsigned*)((char*)(P) + tid_ * 16 + 8192), 16, 0, 0); } while (0)
; #define WAIT_V(n) asm volatile("s_waitcnt vmcnt(" #n ")" ::: "memory")
; #define BAR __builtin_amdgcn_s_barrier()
; template <int EPI> ...
;     ...
;   const int tid_ = opaque_tid();
;   const int wid = tid_ >> 6, lane = tid_ & 63, wr = wid >> 2, wc = wid & 3, fr = lane & 15, fq = lane >> 4;
;   f32x4 acc[2][2][4][2] = {};
;   bf16x8 At[4][2], B0[2][2], B1[2][2];
;   const int nt = K / BK;
;   STAGE(SB(0, 0), B0p, 0); STAGEA(SA(0, 0), A0, 0);
;   STAGE(SB(0, 1), B1p, 0); STAGEA(SA(0, 1), A1, 0);
;   if (wr == 1) BAR;
;   WAIT_V(4); BAR;
;   STAGE(SB(1, 0), B0p, 1); STAGEA(SA(1, 0), A0, 1); STAGE(SB(1, 1), B1p, 1);
;   WAIT_V(6); BAR;
;   for (int t = 0; t < nt - 2; t += 2) {
.LBB0_1715:
	s_or_b64 exec, exec, s[36:37]
	v_add_u32_e32 v165, s47, v12
	v_add_u32_e32 v166, 0x2000, v165
	v_readfirstlane_b32 s25, v165
	v_lshl_add_u64 v[0:1], v[0:1], 0, s[4:5]
	s_mov_b32 m0, s25
	v_readfirstlane_b32 s25, v166
	v_add_u32_e32 v167, 0x8000, v159
	s_waitcnt vmcnt(4)
	s_barrier
	global_load_lds_dwordx4 v[0:1], off
	v_lshl_add_u64 v[0:1], v[2:3], 0, s[4:5]
	s_mov_b32 m0, s25
	v_readfirstlane_b32 s25, v167
	v_add_u32_e32 v168, 0xa000, v159
	global_load_lds_dwordx4 v[0:1], off
	v_lshl_add_u64 v[0:1], v[4:5], 0, s[4:5]
	s_mov_b32 m0, s25
	v_readfirstlane_b32 s25, v168
	v_add_u32_e32 v170, s48, v12
	global_load_lds_dwordx4 v[0:1], off
	v_lshl_add_u64 v[0:1], v[6:7], 0, s[4:5]
	s_mov_b32 m0, s25
	v_readfirstlane_b32 s25, v170
	v_add_u32_e32 v171, 0x2000, v170
	global_load_lds_dwordx4 v[0:1], off
	v_lshl_add_u64 v[0:1], v[8:9], 0, s[4:5]
	s_mov_b32 m0, s25
	v_readfirstlane_b32 s25, v171
	global_load_lds_dwordx4 v[0:1], off
	v_lshl_add_u64 v[0:1], v[10:11], 0, s[4:5]
	s_mov_b32 m0, s25
	v_and_b32_e32 v149, 15, v136
	global_load_lds_dwordx4 v[0:1], off
	v_bfe_u32 v147, v136, 4, 2
	v_lshlrev_b32_e32 v3, 2, v136
	s_lshl_b32 s25, s54, 11
	s_lshl_b32 s27, s55, 8
	v_lshlrev_b32_e32 v0, 4, v147
	v_lshlrev_b32_e32 v2, 6, v149
	v_and_b32_e32 v3, 32, v3
	v_lshlrev_b32_e32 v9, 6, v136
	v_lshl_add_u64 v[128:129], v[138:139], 0, s[30:31]
	v_lshl_add_u64 v[130:131], v[140:141], 0, s[30:31]
	s_or_b32 s30, s25, s27
	v_bfe_u32 v148, v136, 6, 2
	s_waitcnt vmcnt(6)
	v_bitop3_b32 v2, v0, v3, v2 bitop3:0x36
	v_lshlrev_b32_e32 v8, 13, v13
	v_and_or_b32 v0, v9, s49, v0
	s_ashr_i32 s31, s30, 31
	v_lshlrev_b32_e32 v1, 12, v148
	v_add_u32_e32 v4, s45, v2
	v_add_u32_e32 v5, s46, v2
	v_add_u32_e32 v6, s47, v2
	v_add_u32_e32 v7, s48, v2
	v_add_u32_e32 v2, 0, v2
	v_xad_u32 v3, v0, v3, 0
	v_or_b32_e32 v9, 0x800, v8
	v_or_b32_e32 v10, 0x1000, v8
	v_or_b32_e32 v11, 0x1800, v8
	s_lshl_b64 s[30:31], s[30:31], 12
	v_mov_b32_e32 v0, 0
	v_lshlrev_b32_e32 v150, 6, v13
	v_lshl_add_u64 v[142:143], v[138:139], 0, s[30:31]
	v_lshl_add_u64 v[144:145], v[140:141], 0, s[30:31]
	s_mov_b32 s25, -2
	v_add_u32_e32 v172, v4, v1
	v_add_u32_e32 v154, v2, v8
	v_add_u32_e32 v153, v3, v9
	v_add_u32_e32 v152, v3, v10
	v_add_u32_e32 v151, v3, v11
	v_add_u32_e32 v169, v5, v1
	v_add_u32_e32 v157, v6, v1
	v_add_u32_e32 v155, v7, v1
	s_mov_b64 s[30:31], s[74:75]
	v_mov_b32_e32 v1, v0
	v_mov_b32_e32 v2, v0
	v_mov_b32_e32 v3, v0
	v_mov_b32_e32 v4, v0
	v_mov_b32_e32 v5, v0
	v_mov_b32_e32 v6, v0
	v_mov_b32_e32 v7, v0
	v_mov_b32_e32 v8, v0
	v_mov_b32_e32 v9, v0
	v_mov_b32_e32 v10, v0
	v_mov_b32_e32 v11, v0
	v_mov_b32_e32 v12, v0
	v_mov_b32_e32 v13, v0
	v_mov_b32_e32 v14, v0
	v_mov_b32_e32 v15, v0
	v_mov_b32_e32 v16, v0
	v_mov_b32_e32 v17, v0
	v_mov_b32_e32 v18, v0
	v_mov_b32_e32 v19, v0
	v_mov_b32_e32 v20, v0
	v_mov_b32_e32 v21, v0
	v_mov_b32_e32 v22, v0
	v_mov_b32_e32 v23, v0
	v_mov_b32_e32 v24, v0
	v_mov_b32_e32 v25, v0
	v_mov_b32_e32 v26, v0
	v_mov_b32_e32 v27, v0
	v_mov_b32_e32 v28, v0
	v_mov_b32_e32 v29, v0
	v_mov_b32_e32 v30, v0
	v_mov_b32_e32 v31, v0
	v_mov_b32_e32 v32, v0
	v_mov_b32_e32 v33, v0
	v_mov_b32_e32 v34, v0
	v_mov_b32_e32 v35, v0
	v_mov_b32_e32 v36, v0
	v_mov_b32_e32 v37, v0
	v_mov_b32_e32 v38, v0
	v_mov_b32_e32 v39, v0
	v_mov_b32_e32 v40, v0
	v_mov_b32_e32 v41, v0
	v_mov_b32_e32 v42, v0
	v_mov_b32_e32 v43, v0
	v_mov_b32_e32 v44, v0
	v_mov_b32_e32 v45, v0
	v_mov_b32_e32 v46, v0
	v_mov_b32_e32 v47, v0
	v_mov_b32_e32 v48, v0
	v_mov_b32_e32 v49, v0
	v_mov_b32_e32 v50, v0
	v_mov_b32_e32 v51, v0
	v_mov_b32_e32 v52, v0
	v_mov_b32_e32 v53, v0
	v_mov_b32_e32 v54, v0
	v_mov_b32_e32 v55, v0
	v_mov_b32_e32 v56, v0
	v_mov_b32_e32 v57, v0
	v_mov_b32_e32 v58, v0
	v_mov_b32_e32 v59, v0
	v_mov_b32_e32 v60, v0
	v_mov_b32_e32 v61, v0
	v_mov_b32_e32 v62, v0
	v_mov_b32_e32 v63, v0
	v_mov_b32_e32 v64, v0
	v_mov_b32_e32 v65, v0
	v_mov_b32_e32 v66, v0
	v_mov_b32_e32 v67, v0
	v_mov_b32_e32 v68, v0
	v_mov_b32_e32 v69, v0
	v_mov_b32_e32 v70, v0
	v_mov_b32_e32 v71, v0
	v_mov_b32_e32 v72, v0
	v_mov_b32_e32 v73, v0
	v_mov_b32_e32 v74, v0
	v_mov_b32_e32 v75, v0
	v_mov_b32_e32 v76, v0
	v_mov_b32_e32 v77, v0
	v_mov_b32_e32 v78, v0
	v_mov_b32_e32 v79, v0
	v_mov_b32_e32 v80, v0
	v_mov_b32_e32 v81, v0
	v_mov_b32_e32 v82, v0
	v_mov_b32_e32 v83, v0
	v_mov_b32_e32 v84, v0
	v_mov_b32_e32 v85, v0
	v_mov_b32_e32 v86, v0
	v_mov_b32_e32 v87, v0
	v_mov_b32_e32 v88, v0
	v_mov_b32_e32 v89, v0
	v_mov_b32_e32 v90, v0
	v_mov_b32_e32 v91, v0
	v_mov_b32_e32 v92, v0
	v_mov_b32_e32 v93, v0
	v_mov_b32_e32 v94, v0
	v_mov_b32_e32 v95, v0
	v_mov_b32_e32 v96, v0
	v_mov_b32_e32 v97, v0
	v_mov_b32_e32 v98, v0
	v_mov_b32_e32 v99, v0
	v_mov_b32_e32 v100, v0
	v_mov_b32_e32 v101, v0
	v_mov_b32_e32 v102, v0
	v_mov_b32_e32 v103, v0
	v_mov_b32_e32 v104, v0
	v_mov_b32_e32 v105, v0
	v_mov_b32_e32 v106, v0
	v_mov_b32_e32 v107, v0
	v_mov_b32_e32 v108, v0
	v_mov_b32_e32 v109, v0
	v_mov_b32_e32 v110, v0
	v_mov_b32_e32 v111, v0
	v_mov_b32_e32 v112, v0
	v_mov_b32_e32 v113, v0
	v_mov_b32_e32 v114, v0
	v_mov_b32_e32 v115, v0
	v_mov_b32_e32 v116, v0
	v_mov_b32_e32 v117, v0
	v_mov_b32_e32 v118, v0
	v_mov_b32_e32 v119, v0
	v_mov_b32_e32 v120, v0
	v_mov_b32_e32 v121, v0
	v_mov_b32_e32 v122, v0
	v_mov_b32_e32 v123, v0
	v_mov_b32_e32 v124, v0
	v_mov_b32_e32 v125, v0
	v_mov_b32_e32 v126, v0
	v_mov_b32_e32 v127, v0
	s_barrier
	ds_read_b128 v[176:179], v172
	ds_read_b128 v[180:183], v172 offset:1024
	ds_read_b128 v[184:187], v172 offset:2048
	ds_read_b128 v[188:191], v172 offset:3072
; #define STAGE(P, BASE, kt) do { const char* _g = (const char*)(BASE) + (size_t)((kt) * (BK * 2)); \
;     __builtin_amdgcn_global_load_lds((const unsigned*)(_g + (size_t)goff0), (unsigned*)((char*)(P) + tid_ * 16), 16, 0, 0); \
;     __builtin_amdgcn_global_load_lds((const unsigned*)(_g + (size_t)goff1), (unsigned*)((char*)(P) + tid_ * 16 + 8192), 16, 0, 0); } while (0)
; #define STAGEA(P, BASE, kt) do { const char* _g = (const char*)(BASE) + (size_t)((kt) * a_kbytes); \
;     __builtin_amdgcn_global_load_lds((const unsigned*)(_g + (size_t)goffA0), (unsigned*)((char*)(P) + tid_ * 16), 16, 0, 0); \
;     __builtin_amdgcn_global_load_lds((const unsigned*)(_g + (size_t)goffA1), (unsigned*)((char*)(P) + tid_ * 16 + 8192), 16, 0, 0); } while (0)
; #define LDA(dst, b, h) for (int m = 0; m < 4; ++m) for (int k = 0; k < 2; ++k) \
;     dst[m][k] = *reinterpret_cast<const bf16x8*>((char*)SA(b, h) + lds_byte(wr * 64 + m * 16 + fr, k * 32 + fq * 8))
; #define LDB(dst, b, h) for (int n = 0; n < 2; ++n) for (int k = 0; k < 2; ++k) \
;     dst[n][k] = *reinterpret_cast<const bf16x8*>((char*)SB(b, h) + lds_byte(wc * 32 + n * 16 + fr, k * 32 + fq * 8))
; #define MMA(ai, bj, At, Bt) do { __builtin_amdgcn_s_setprio(1); \
;     for (int m = 0; m < 4; ++m) for (int n = 0; n < 2; ++n) for (int k = 0; k < 2; ++k) \
;       acc[ai][bj][m][n] = __builtin_amdgcn_mfma_f32_16x16x32_bf16(At[m][k], Bt[n][k], acc[ai][bj][m][n], 0, 0, 0); \
;     __builtin_amdgcn_s_setprio(0); } while (0)
; #define WAIT_L(n) asm volatile("s_waitcnt lgkmcnt(" #n ")" ::: "memory")
; #define BAR __builtin_amdgcn_s_barrier()
; #define SCHED __builtin_amdgcn_sched_barrier(0)
; template <int EPI> ...
;     ...
;   for (int t = 0; t < nt - 2; t += 2) {
;     LDB(B0, 0, 0); SCHED; LDA(At, 0, 0); STAGEA(SA(1, 1), A1, t + 1);
;     WAIT_L(8); BAR; WAIT_L(0); MMA(0, 0, At, B0); BAR; SCHED;
;     LDB(B1, 0, 1); STAGE(SB(0, 0), B0p, t + 2);
;     BAR; WAIT_L(0); MMA(0, 1, At, B1); BAR;
;     LDA(At, 0, 1); STAGEA(SA(0, 0), A0, t + 2);
;     BAR; WAIT_L(0); MMA(1, 0, At, B0); BAR; SCHED;
.LBB0_1716:
	v_add_u32_e32 v173, 0xc000, v159
	v_lshl_add_u64 v[240:241], s[30:31], 0, v[142:143]
	v_readfirstlane_b32 s27, v173
	v_lshl_add_u64 v[174:175], v[240:241], 0, s[6:7]
	s_mov_b32 m0, s27
	ds_read_b128 v[192:195], v154
	ds_read_b128 v[196:199], v154 offset:1024
	ds_read_b128 v[200:203], v153
	ds_read_b128 v[204:207], v153 offset:1024
	ds_read_b128 v[208:211], v152
	ds_read_b128 v[212:215], v152 offset:1024
	ds_read_b128 v[216:219], v151
	ds_read_b128 v[220:223], v151 offset:1024
	global_load_lds_dwordx4 v[174:175], off
	v_add_u32_e32 v174, 0xe000, v159
	v_lshl_add_u64 v[242:243], s[30:31], 0, v[144:145]
	v_readfirstlane_b32 s27, v174
	v_lshl_add_u64 v[224:225], v[242:243], 0, s[6:7]
	s_mov_b32 m0, s27
	s_nop 0
	global_load_lds_dwordx4 v[224:225], off
	s_waitcnt lgkmcnt(8)
	s_setprio 1
	s_barrier
	s_waitcnt lgkmcnt(0)
	v_mfma_f32_16x16x32_bf16 v[124:127], v[192:195], v[176:179], v[124:127]
	v_mfma_f32_16x16x32_bf16 v[120:123], v[192:195], v[184:187], v[120:123]
	v_mfma_f32_16x16x32_bf16 v[116:119], v[200:203], v[176:179], v[116:119]
	v_mfma_f32_16x16x32_bf16 v[112:115], v[200:203], v[184:187], v[112:115]
	v_mfma_f32_16x16x32_bf16 v[108:111], v[208:211], v[176:179], v[108:111]
	v_mfma_f32_16x16x32_bf16 v[104:107], v[208:211], v[184:187], v[104:107]
	v_mfma_f32_16x16x32_bf16 v[100:103], v[216:219], v[176:179], v[100:103]
	v_mfma_f32_16x16x32_bf16 v[96:99], v[216:219], v[184:187], v[96:99]
	v_mfma_f32_16x16x32_bf16 v[124:127], v[196:199], v[180:183], v[124:127]
	v_mfma_f32_16x16x32_bf16 v[120:123], v[196:199], v[188:191], v[120:123]
	v_mfma_f32_16x16x32_bf16 v[116:119], v[204:207], v[180:183], v[116:119]
	v_mfma_f32_16x16x32_bf16 v[112:115], v[204:207], v[188:191], v[112:115]
	v_mfma_f32_16x16x32_bf16 v[108:111], v[212:215], v[180:183], v[108:111]
	v_mfma_f32_16x16x32_bf16 v[104:107], v[212:215], v[188:191], v[104:107]
	v_mfma_f32_16x16x32_bf16 v[100:103], v[220:223], v[180:183], v[100:103]
	v_mfma_f32_16x16x32_bf16 v[96:99], v[220:223], v[188:191], v[96:99]
	s_barrier
	s_setprio 0
	v_lshl_add_u64 v[244:245], s[30:31], 0, v[128:129]
	v_readfirstlane_b32 s27, v156
	v_lshl_add_u64 v[246:247], v[244:245], 0, s[8:9]
	s_mov_b32 m0, s27
	ds_read_b128 v[224:227], v169
	ds_read_b128 v[228:231], v169 offset:1024
	ds_read_b128 v[232:235], v169 offset:2048
	ds_read_b128 v[236:239], v169 offset:3072
	global_load_lds_dwordx4 v[246:247], off
	v_lshl_add_u64 v[246:247], s[30:31], 0, v[130:131]
	v_readfirstlane_b32 s27, v158
	v_lshl_add_u64 v[248:249], v[246:247], 0, s[8:9]
	s_mov_b32 m0, s27
	s_nop 0
	global_load_lds_dwordx4 v[248:249], off
	s_setprio 1
	s_barrier
	s_waitcnt lgkmcnt(0)
	v_mfma_f32_16x16x32_bf16 v[92:95], v[192:195], v[224:227], v[92:95]
	v_mfma_f32_16x16x32_bf16 v[88:91], v[192:195], v[232:235], v[88:91]
	v_mfma_f32_16x16x32_bf16 v[84:87], v[200:203], v[224:227], v[84:87]
	v_mfma_f32_16x16x32_bf16 v[80:83], v[200:203], v[232:235], v[80:83]
	v_mfma_f32_16x16x32_bf16 v[76:79], v[208:211], v[224:227], v[76:79]
	v_mfma_f32_16x16x32_bf16 v[72:75], v[208:211], v[232:235], v[72:75]
	v_mfma_f32_16x16x32_bf16 v[68:71], v[216:219], v[224:227], v[68:71]
	v_mfma_f32_16x16x32_bf16 v[64:67], v[216:219], v[232:235], v[64:67]
	v_mfma_f32_16x16x32_bf16 v[92:95], v[196:199], v[228:231], v[92:95]
	v_mfma_f32_16x16x32_bf16 v[88:91], v[196:199], v[236:239], v[88:91]
	v_mfma_f32_16x16x32_bf16 v[84:87], v[204:207], v[228:231], v[84:87]
	v_mfma_f32_16x16x32_bf16 v[80:83], v[204:207], v[236:239], v[80:83]
	v_mfma_f32_16x16x32_bf16 v[76:79], v[212:215], v[228:231], v[76:79]
	v_mfma_f32_16x16x32_bf16 v[72:75], v[212:215], v[236:239], v[72:75]
	v_mfma_f32_16x16x32_bf16 v[68:71], v[220:223], v[228:231], v[68:71]
	v_mfma_f32_16x16x32_bf16 v[64:67], v[220:223], v[236:239], v[64:67]
	s_barrier
	s_setprio 0
	v_readfirstlane_b32 s27, v159
	v_lshl_add_u64 v[248:249], v[240:241], 0, s[10:11]
	s_mov_b32 m0, s27
	v_readfirstlane_b32 s27, v160
	ds_read_b128 v[192:195], v154 offset:16384
	ds_read_b128 v[196:199], v154 offset:17408
	ds_read_b128 v[200:203], v153 offset:16384
	ds_read_b128 v[204:207], v153 offset:17408
	ds_read_b128 v[208:211], v152 offset:16384
	ds_read_b128 v[212:215], v152 offset:17408
	ds_read_b128 v[216:219], v151 offset:16384
	ds_read_b128 v[220:223], v151 offset:17408
	global_load_lds_dwordx4 v[248:249], off
	v_lshl_add_u64 v[248:249], v[242:243], 0, s[10:11]
	s_mov_b32 m0, s27
	s_nop 0
	global_load_lds_dwordx4 v[248:249], off
	s_setprio 1
	s_barrier
	s_waitcnt lgkmcnt(0)
	v_mfma_f32_16x16x32_bf16 v[60:63], v[192:195], v[176:179], v[60:63]
	v_mfma_f32_16x16x32_bf16 v[56:59], v[192:195], v[184:187], v[56:59]
	v_mfma_f32_16x16x32_bf16 v[52:55], v[200:203], v[176:179], v[52:55]
	v_mfma_f32_16x16x32_bf16 v[48:51], v[200:203], v[184:187], v[48:51]
	v_mfma_f32_16x16x32_bf16 v[44:47], v[208:211], v[176:179], v[44:47]
	v_mfma_f32_16x16x32_bf16 v[40:43], v[208:211], v[184:187], v[40:43]
	v_mfma_f32_16x16x32_bf16 v[36:39], v[216:219], v[176:179], v[36:39]
	v_mfma_f32_16x16x32_bf16 v[32:35], v[216:219], v[184:187], v[32:35]
	v_mfma_f32_16x16x32_bf16 v[60:63], v[196:199], v[180:183], v[60:63]
	v_mfma_f32_16x16x32_bf16 v[56:59], v[196:199], v[188:191], v[56:59]
	v_mfma_f32_16x16x32_bf16 v[52:55], v[204:207], v[180:183], v[52:55]
	v_mfma_f32_16x16x32_bf16 v[48:51], v[204:207], v[188:191], v[48:51]
	v_mfma_f32_16x16x32_bf16 v[44:47], v[212:215], v[180:183], v[44:47]
	v_mfma_f32_16x16x32_bf16 v[40:43], v[212:215], v[188:191], v[40:43]
	v_mfma_f32_16x16x32_bf16 v[36:39], v[220:223], v[180:183], v[36:39]
	v_mfma_f32_16x16x32_bf16 v[32:35], v[220:223], v[188:191], v[32:35]
	s_barrier
; #define STAGE(P, BASE, kt) do { const char* _g = (const char*)(BASE) + (size_t)((kt) * (BK * 2)); \
;     __builtin_amdgcn_global_load_lds((const unsigned*)(_g + (size_t)goff0), (unsigned*)((char*)(P) + tid_ * 16), 16, 0, 0); \
;     __builtin_amdgcn_global_load_lds((const unsigned*)(_g + (size_t)goff1), (unsigned*)((char*)(P) + tid_ * 16 + 8192), 16, 0, 0); } while (0)
; #define STAGEA(P, BASE, kt) do { const char* _g = (const char*)(BASE) + (size_t)((kt) * a_kbytes); \
;     __builtin_amdgcn_global_load_lds((const unsigned*)(_g + (size_t)goffA0), (unsigned*)((char*)(P) + tid_ * 16), 16, 0, 0); \
;     __builtin_amdgcn_global_load_lds((const unsigned*)(_g + (size_t)goffA1), (unsigned*)((char*)(P) + tid_ * 16 + 8192), 16, 0, 0); } while (0)
; #define LDA(dst, b, h) for (int m = 0; m < 4; ++m) for (int k = 0; k < 2; ++k) \
;     dst[m][k] = *reinterpret_cast<const bf16x8*>((char*)SA(b, h) + lds_byte(wr * 64 + m * 16 + fr, k * 32 + fq * 8))
; #define LDB(dst, b, h) for (int n = 0; n < 2; ++n) for (int k = 0; k < 2; ++k) \
;     dst[n][k] = *reinterpret_cast<const bf16x8*>((char*)SB(b, h) + lds_byte(wc * 32 + n * 16 + fr, k * 32 + fq * 8))
; #define MMA(ai, bj, At, Bt) do { __builtin_amdgcn_s_setprio(1); \
;     for (int m = 0; m < 4; ++m) for (int n = 0; n < 2; ++n) for (int k = 0; k < 2; ++k) \
;       acc[ai][bj][m][n] = __builtin_amdgcn_mfma_f32_16x16x32_bf16(At[m][k], Bt[n][k], acc[ai][bj][m][n], 0, 0, 0); \
;     __builtin_amdgcn_s_setprio(0); } while (0)
; #define WAIT_V(n) asm volatile("s_waitcnt vmcnt(" #n ")" ::: "memory")
; #define WAIT_L(n) asm volatile("s_waitcnt lgkmcnt(" #n ")" ::: "memory")
; #define BAR __builtin_amdgcn_s_barrier()
; #define SCHED __builtin_amdgcn_sched_barrier(0)
; template <int EPI> ...
;     ...
;     STAGE(SB(0, 1), B1p, t + 2);
;     WAIT_V(6); BAR; MMA(1, 1, At, B1); BAR;
;     LDB(B0, 1, 0); SCHED; LDA(At, 1, 0); STAGEA(SA(0, 1), A1, t + 2);
;     WAIT_L(8); BAR; WAIT_L(0); MMA(0, 0, At, B0); BAR; SCHED;
;     LDB(B1, 1, 1); STAGE(SB(1, 0), B0p, t + 3);
;     BAR; WAIT_L(0); MMA(0, 1, At, B1); BAR;
;     LDA(At, 1, 1); STAGEA(SA(1, 0), A0, t + 3);
;     BAR; WAIT_L(0); MMA(1, 0, At, B0); BAR; SCHED;
;     STAGE(SB(1, 1), B1p, t + 3);
;     WAIT_V(6); BAR; MMA(1, 1, At, B1); BAR;
	s_setprio 0
	v_readfirstlane_b32 s27, v161
	v_lshl_add_u64 v[176:177], v[244:245], 0, s[12:13]
	s_mov_b32 m0, s27
	v_readfirstlane_b32 s27, v162
	global_load_lds_dwordx4 v[176:177], off
	v_lshl_add_u64 v[176:177], v[246:247], 0, s[12:13]
	s_mov_b32 m0, s27
	s_nop 0
	global_load_lds_dwordx4 v[176:177], off
	s_waitcnt vmcnt(6)
	s_setprio 1
	s_barrier
	v_mfma_f32_16x16x32_bf16 v[28:31], v[192:195], v[224:227], v[28:31]
	v_mfma_f32_16x16x32_bf16 v[24:27], v[192:195], v[232:235], v[24:27]
	v_mfma_f32_16x16x32_bf16 v[20:23], v[200:203], v[224:227], v[20:23]
	v_mfma_f32_16x16x32_bf16 v[16:19], v[200:203], v[232:235], v[16:19]
	ds_read_b128 v[176:179], v157
	v_mfma_f32_16x16x32_bf16 v[12:15], v[208:211], v[224:227], v[12:15]
	v_mfma_f32_16x16x32_bf16 v[8:11], v[208:211], v[232:235], v[8:11]
	ds_read_b128 v[180:183], v157 offset:1024
	v_mfma_f32_16x16x32_bf16 v[4:7], v[216:219], v[224:227], v[4:7]
	v_mfma_f32_16x16x32_bf16 v[0:3], v[216:219], v[232:235], v[0:3]
	ds_read_b128 v[184:187], v157 offset:2048
	v_mfma_f32_16x16x32_bf16 v[28:31], v[196:199], v[228:231], v[28:31]
	v_mfma_f32_16x16x32_bf16 v[24:27], v[196:199], v[236:239], v[24:27]
	ds_read_b128 v[188:191], v157 offset:3072
	v_mfma_f32_16x16x32_bf16 v[20:23], v[204:207], v[228:231], v[20:23]
	v_mfma_f32_16x16x32_bf16 v[16:19], v[204:207], v[236:239], v[16:19]
	v_mfma_f32_16x16x32_bf16 v[12:15], v[212:215], v[228:231], v[12:15]
	v_mfma_f32_16x16x32_bf16 v[8:11], v[212:215], v[236:239], v[8:11]
	v_mfma_f32_16x16x32_bf16 v[4:7], v[220:223], v[228:231], v[4:7]
	v_mfma_f32_16x16x32_bf16 v[0:3], v[220:223], v[236:239], v[0:3]
	s_barrier
	s_setprio 0
	v_readfirstlane_b32 s27, v163
	v_lshl_add_u64 v[224:225], v[240:241], 0, s[14:15]
	s_mov_b32 m0, s27
	v_readfirstlane_b32 s27, v164
	ds_read_b128 v[192:195], v154 offset:32768
	ds_read_b128 v[196:199], v154 offset:33792
	ds_read_b128 v[200:203], v153 offset:32768
	ds_read_b128 v[204:207], v153 offset:33792
	ds_read_b128 v[208:211], v152 offset:32768
	ds_read_b128 v[212:215], v152 offset:33792
	ds_read_b128 v[216:219], v151 offset:32768
	ds_read_b128 v[220:223], v151 offset:33792
	global_load_lds_dwordx4 v[224:225], off
	v_lshl_add_u64 v[224:225], v[242:243], 0, s[14:15]
	s_mov_b32 m0, s27
	s_nop 0
	global_load_lds_dwordx4 v[224:225], off
	s_waitcnt lgkmcnt(8)
	s_setprio 1
	s_barrier
	s_waitcnt lgkmcnt(0)
	v_mfma_f32_16x16x32_bf16 v[124:127], v[192:195], v[176:179], v[124:127]
	v_mfma_f32_16x16x32_bf16 v[120:123], v[192:195], v[184:187], v[120:123]
	v_mfma_f32_16x16x32_bf16 v[116:119], v[200:203], v[176:179], v[116:119]
	v_mfma_f32_16x16x32_bf16 v[112:115], v[200:203], v[184:187], v[112:115]
	v_mfma_f32_16x16x32_bf16 v[108:111], v[208:211], v[176:179], v[108:111]
	v_mfma_f32_16x16x32_bf16 v[104:107], v[208:211], v[184:187], v[104:107]
	v_mfma_f32_16x16x32_bf16 v[100:103], v[216:219], v[176:179], v[100:103]
	v_mfma_f32_16x16x32_bf16 v[96:99], v[216:219], v[184:187], v[96:99]
	v_mfma_f32_16x16x32_bf16 v[124:127], v[196:199], v[180:183], v[124:127]
	v_mfma_f32_16x16x32_bf16 v[120:123], v[196:199], v[188:191], v[120:123]
	v_mfma_f32_16x16x32_bf16 v[116:119], v[204:207], v[180:183], v[116:119]
	v_mfma_f32_16x16x32_bf16 v[112:115], v[204:207], v[188:191], v[112:115]
	v_mfma_f32_16x16x32_bf16 v[108:111], v[212:215], v[180:183], v[108:111]
	v_mfma_f32_16x16x32_bf16 v[104:107], v[212:215], v[188:191], v[104:107]
	v_mfma_f32_16x16x32_bf16 v[100:103], v[220:223], v[180:183], v[100:103]
	v_mfma_f32_16x16x32_bf16 v[96:99], v[220:223], v[188:191], v[96:99]
	s_barrier
	s_setprio 0
	v_readfirstlane_b32 s27, v165
	v_lshl_add_u64 v[248:249], v[244:245], 0, s[16:17]
	s_mov_b32 m0, s27
	v_readfirstlane_b32 s27, v166
	ds_read_b128 v[224:227], v155
	ds_read_b128 v[228:231], v155 offset:1024
	ds_read_b128 v[232:235], v155 offset:2048
	ds_read_b128 v[236:239], v155 offset:3072
	global_load_lds_dwordx4 v[248:249], off
	v_lshl_add_u64 v[248:249], v[246:247], 0, s[16:17]
	s_mov_b32 m0, s27
	s_nop 0
	global_load_lds_dwordx4 v[248:249], off
	s_setprio 1
	s_barrier
	s_waitcnt lgkmcnt(0)
	v_mfma_f32_16x16x32_bf16 v[92:95], v[192:195], v[224:227], v[92:95]
	v_mfma_f32_16x16x32_bf16 v[88:91], v[192:195], v[232:235], v[88:91]
	v_mfma_f32_16x16x32_bf16 v[84:87], v[200:203], v[224:227], v[84:87]
	v_mfma_f32_16x16x32_bf16 v[80:83], v[200:203], v[232:235], v[80:83]
	v_mfma_f32_16x16x32_bf16 v[76:79], v[208:211], v[224:227], v[76:79]
	v_mfma_f32_16x16x32_bf16 v[72:75], v[208:211], v[232:235], v[72:75]
	v_mfma_f32_16x16x32_bf16 v[68:71], v[216:219], v[224:227], v[68:71]
	v_mfma_f32_16x16x32_bf16 v[64:67], v[216:219], v[232:235], v[64:67]
	v_mfma_f32_16x16x32_bf16 v[92:95], v[196:199], v[228:231], v[92:95]
	v_mfma_f32_16x16x32_bf16 v[88:91], v[196:199], v[236:239], v[88:91]
	v_mfma_f32_16x16x32_bf16 v[84:87], v[204:207], v[228:231], v[84:87]
	v_mfma_f32_16x16x32_bf16 v[80:83], v[204:207], v[236:239], v[80:83]
	v_mfma_f32_16x16x32_bf16 v[76:79], v[212:215], v[228:231], v[76:79]
	v_mfma_f32_16x16x32_bf16 v[72:75], v[212:215], v[236:239], v[72:75]
	v_mfma_f32_16x16x32_bf16 v[68:71], v[220:223], v[228:231], v[68:71]
	v_mfma_f32_16x16x32_bf16 v[64:67], v[220:223], v[236:239], v[64:67]
	s_barrier
	s_setprio 0
	v_readfirstlane_b32 s27, v167
	v_lshl_add_u64 v[240:241], v[240:241], 0, s[18:19]
	s_mov_b32 m0, s27
	v_readfirstlane_b32 s27, v168
	ds_read_b128 v[192:195], v154 offset:49152
	ds_read_b128 v[196:199], v154 offset:50176
	ds_read_b128 v[200:203], v153 offset:49152
	ds_read_b128 v[204:207], v153 offset:50176
	ds_read_b128 v[208:211], v152 offset:49152
	ds_read_b128 v[212:215], v152 offset:50176
	ds_read_b128 v[216:219], v151 offset:49152
	ds_read_b128 v[220:223], v151 offset:50176
	global_load_lds_dwordx4 v[240:241], off
	v_lshl_add_u64 v[240:241], v[242:243], 0, s[18:19]
	s_mov_b32 m0, s27
	s_nop 0
	global_load_lds_dwordx4 v[240:241], off
	s_setprio 1
	s_barrier
; #define STAGE(P, BASE, kt) do { const char* _g = (const char*)(BASE) + (size_t)((kt) * (BK * 2)); \
;     __builtin_amdgcn_global_load_lds((const unsigned*)(_g + (size_t)goff0), (unsigned*)((char*)(P) + tid_ * 16), 16, 0, 0); \
;     __builtin_amdgcn_global_load_lds((const unsigned*)(_g + (size_t)goff1), (unsigned*)((char*)(P) + tid_ * 16 + 8192), 16, 0, 0); } while (0)
; #define STAGEA(P, BASE, kt) do { const char* _g = (const char*)(BASE) + (size_t)((kt) * a_kbytes); \
;     __builtin_amdgcn_global_load_lds((const unsigned*)(_g + (size_t)goffA0), (unsigned*)((char*)(P) + tid_ * 16), 16, 0, 0); \
;     __builtin_amdgcn_global_load_lds((const unsigned*)(_g + (size_t)goffA1), (unsigned*)((char*)(P) + tid_ * 16 + 8192), 16, 0, 0); } while (0)
; #define LDA(dst, b, h) for (int m = 0; m < 4; ++m) for (int k = 0; k < 2; ++k) \
;     dst[m][k] = *reinterpret_cast<const bf16x8*>((char*)SA(b, h) + lds_byte(wr * 64 + m * 16 + fr, k * 32 + fq * 8))
; #define LDB(dst, b, h) for (int n = 0; n < 2; ++n) for (int k = 0; k < 2; ++k) \
;     dst[n][k] = *reinterpret_cast<const bf16x8*>((char*)SB(b, h) + lds_byte(wc * 32 + n * 16 + fr, k * 32 + fq * 8))
; #define MMA(ai, bj, At, Bt) do { __builtin_amdgcn_s_setprio(1); \
;     for (int m = 0; m < 4; ++m) for (int n = 0; n < 2; ++n) for (int k = 0; k < 2; ++k) \
;       acc[ai][bj][m][n] = __builtin_amdgcn_mfma_f32_16x16x32_bf16(At[m][k], Bt[n][k], acc[ai][bj][m][n], 0, 0, 0); \
;     __builtin_amdgcn_s_setprio(0); } while (0)
; #define WAIT_V(n) asm volatile("s_waitcnt vmcnt(" #n ")" ::: "memory")
; #define WAIT_L(n) asm volatile("s_waitcnt lgkmcnt(" #n ")" ::: "memory")
; #define BAR __builtin_amdgcn_s_barrier()
; template <int EPI> ...
;     ...
;     STAGE(SB(1, 1), B1p, t + 3);
;     WAIT_V(6); BAR; MMA(1, 1, At, B1); BAR;
;   }
;   { LDB(B0, 0, 0); LDA(At, 0, 0); STAGEA(SA(1, 1), A1, nt - 1);
;     BAR; WAIT_L(0); MMA(0, 0, At, B0); BAR;
;     LDB(B1, 0, 1); BAR; WAIT_L(0); MMA(0, 1, At, B1); BAR;
	s_waitcnt lgkmcnt(0)
	v_mfma_f32_16x16x32_bf16 v[60:63], v[192:195], v[176:179], v[60:63]
	v_mfma_f32_16x16x32_bf16 v[56:59], v[192:195], v[184:187], v[56:59]
	v_mfma_f32_16x16x32_bf16 v[52:55], v[200:203], v[176:179], v[52:55]
	v_mfma_f32_16x16x32_bf16 v[48:51], v[200:203], v[184:187], v[48:51]
	v_mfma_f32_16x16x32_bf16 v[44:47], v[208:211], v[176:179], v[44:47]
	v_mfma_f32_16x16x32_bf16 v[40:43], v[208:211], v[184:187], v[40:43]
	v_mfma_f32_16x16x32_bf16 v[36:39], v[216:219], v[176:179], v[36:39]
	v_mfma_f32_16x16x32_bf16 v[32:35], v[216:219], v[184:187], v[32:35]
	v_mfma_f32_16x16x32_bf16 v[60:63], v[196:199], v[180:183], v[60:63]
	v_mfma_f32_16x16x32_bf16 v[56:59], v[196:199], v[188:191], v[56:59]
	v_mfma_f32_16x16x32_bf16 v[52:55], v[204:207], v[180:183], v[52:55]
	v_mfma_f32_16x16x32_bf16 v[48:51], v[204:207], v[188:191], v[48:51]
	v_mfma_f32_16x16x32_bf16 v[44:47], v[212:215], v[180:183], v[44:47]
	v_mfma_f32_16x16x32_bf16 v[40:43], v[212:215], v[188:191], v[40:43]
	v_mfma_f32_16x16x32_bf16 v[36:39], v[220:223], v[180:183], v[36:39]
	v_mfma_f32_16x16x32_bf16 v[32:35], v[220:223], v[188:191], v[32:35]
	s_barrier
	s_setprio 0
	v_readfirstlane_b32 s27, v170
	v_lshl_add_u64 v[176:177], v[244:245], 0, s[20:21]
	s_mov_b32 m0, s27
	v_readfirstlane_b32 s27, v171
	global_load_lds_dwordx4 v[176:177], off
	v_lshl_add_u64 v[176:177], v[246:247], 0, s[20:21]
	s_mov_b32 m0, s27
	s_nop 0
	global_load_lds_dwordx4 v[176:177], off
	s_waitcnt vmcnt(6)
	s_setprio 1
	s_barrier
	v_mfma_f32_16x16x32_bf16 v[28:31], v[192:195], v[224:227], v[28:31]
	v_mfma_f32_16x16x32_bf16 v[24:27], v[192:195], v[232:235], v[24:27]
	v_mfma_f32_16x16x32_bf16 v[20:23], v[200:203], v[224:227], v[20:23]
	v_mfma_f32_16x16x32_bf16 v[16:19], v[200:203], v[232:235], v[16:19]
	ds_read_b128 v[176:179], v172
	v_mfma_f32_16x16x32_bf16 v[12:15], v[208:211], v[224:227], v[12:15]
	v_mfma_f32_16x16x32_bf16 v[8:11], v[208:211], v[232:235], v[8:11]
	ds_read_b128 v[180:183], v172 offset:1024
	v_mfma_f32_16x16x32_bf16 v[4:7], v[216:219], v[224:227], v[4:7]
	v_mfma_f32_16x16x32_bf16 v[0:3], v[216:219], v[232:235], v[0:3]
	ds_read_b128 v[184:187], v172 offset:2048
	v_mfma_f32_16x16x32_bf16 v[28:31], v[196:199], v[228:231], v[28:31]
	v_mfma_f32_16x16x32_bf16 v[24:27], v[196:199], v[236:239], v[24:27]
	ds_read_b128 v[188:191], v172 offset:3072
	v_mfma_f32_16x16x32_bf16 v[20:23], v[204:207], v[228:231], v[20:23]
	v_mfma_f32_16x16x32_bf16 v[16:19], v[204:207], v[236:239], v[16:19]
	v_mfma_f32_16x16x32_bf16 v[12:15], v[212:215], v[228:231], v[12:15]
	v_mfma_f32_16x16x32_bf16 v[8:11], v[212:215], v[236:239], v[8:11]
	v_mfma_f32_16x16x32_bf16 v[4:7], v[220:223], v[228:231], v[4:7]
	v_mfma_f32_16x16x32_bf16 v[0:3], v[220:223], v[236:239], v[0:3]
	s_barrier
	s_setprio 0
	s_add_i32 s25, s25, 2
	s_add_u32 s30, s30, 0x100
	s_addc_u32 s31, s31, 0
	s_cmp_lt_u32 s25, 28
	s_cbranch_scc1 .LBB0_1716
	s_add_u32 s28, s28, 0x80f80
	s_addc_u32 s29, s29, 0
	v_readfirstlane_b32 s25, v173
	v_lshl_add_u64 v[166:167], s[28:29], 0, v[134:135]
	s_mov_b32 m0, s25
	v_readfirstlane_b32 s25, v174
	ds_read_b128 v[128:131], v172
	ds_read_b128 v[142:145], v172 offset:1024
	ds_read_b128 v[158:161], v172 offset:2048
	ds_read_b128 v[162:165], v172 offset:3072
	ds_read_b128 v[176:179], v154
	ds_read_b128 v[180:183], v154 offset:1024
	ds_read_b128 v[184:187], v153
	ds_read_b128 v[188:191], v153 offset:1024
	ds_read_b128 v[192:195], v152
	ds_read_b128 v[196:199], v152 offset:1024
	ds_read_b128 v[200:203], v151
	ds_read_b128 v[204:207], v151 offset:1024
	global_load_lds_dwordx4 v[166:167], off
	v_lshl_add_u64 v[166:167], s[28:29], 0, v[132:133]
	s_mov_b32 m0, s25
	s_nop 0
	global_load_lds_dwordx4 v[166:167], off
	s_setprio 1
	s_barrier
	s_waitcnt lgkmcnt(0)
	v_mfma_f32_16x16x32_bf16 v[124:127], v[176:179], v[128:131], v[124:127]
	v_mfma_f32_16x16x32_bf16 v[120:123], v[176:179], v[158:161], v[120:123]
	v_mfma_f32_16x16x32_bf16 v[108:111], v[192:195], v[128:131], v[108:111]
	v_mfma_f32_16x16x32_bf16 v[104:107], v[192:195], v[158:161], v[104:107]
	v_mfma_f32_16x16x32_bf16 v[124:127], v[180:183], v[142:145], v[124:127]
	v_mfma_f32_16x16x32_bf16 v[120:123], v[180:183], v[162:165], v[120:123]
	v_mfma_f32_16x16x32_bf16 v[116:119], v[184:187], v[128:131], v[116:119]
	v_mfma_f32_16x16x32_bf16 v[112:115], v[184:187], v[158:161], v[112:115]
	v_mfma_f32_16x16x32_bf16 v[108:111], v[196:199], v[142:145], v[108:111]
	v_mfma_f32_16x16x32_bf16 v[104:107], v[196:199], v[162:165], v[104:107]
	v_mfma_f32_16x16x32_bf16 v[100:103], v[200:203], v[128:131], v[100:103]
	v_mfma_f32_16x16x32_bf16 v[96:99], v[200:203], v[158:161], v[96:99]
	v_mfma_f32_16x16x32_bf16 v[170:173], v[188:191], v[142:145], v[116:119]
	v_mfma_f32_16x16x32_bf16 v[208:211], v[188:191], v[162:165], v[112:115]
	v_mfma_f32_16x16x32_bf16 v[212:215], v[204:207], v[142:145], v[100:103]
	v_mfma_f32_16x16x32_bf16 v[216:219], v[204:207], v[162:165], v[96:99]
	s_barrier
	s_setprio 0
	s_nop 1
	ds_read_b128 v[96:99], v169
	ds_read_b128 v[100:103], v169 offset:1024
	ds_read_b128 v[112:115], v169 offset:2048
	ds_read_b128 v[116:119], v169 offset:3072
	s_setprio 1
	s_barrier
; #define LDA(dst, b, h) for (int m = 0; m < 4; ++m) for (int k = 0; k < 2; ++k) \
;     dst[m][k] = *reinterpret_cast<const bf16x8*>((char*)SA(b, h) + lds_byte(wr * 64 + m * 16 + fr, k * 32 + fq * 8))
; #define LDB(dst, b, h) for (int n = 0; n < 2; ++n) for (int k = 0; k < 2; ++k) \
;     dst[n][k] = *reinterpret_cast<const bf16x8*>((char*)SB(b, h) + lds_byte(wc * 32 + n * 16 + fr, k * 32 + fq * 8))
; #define MMA(ai, bj, At, Bt) do { __builtin_amdgcn_s_setprio(1); \
;     for (int m = 0; m < 4; ++m) for (int n = 0; n < 2; ++n) for (int k = 0; k < 2; ++k) \
;       acc[ai][bj][m][n] = __builtin_amdgcn_mfma_f32_16x16x32_bf16(At[m][k], Bt[n][k], acc[ai][bj][m][n], 0, 0, 0); \
;     __builtin_amdgcn_s_setprio(0); } while (0)
; #define WAIT_V(n) asm volatile("s_waitcnt vmcnt(" #n ")" ::: "memory")
; #define WAIT_L(n) asm volatile("s_waitcnt lgkmcnt(" #n ")" ::: "memory")
; #define BAR __builtin_amdgcn_s_barrier()
; template <int EPI> ...
;     ...
;     BAR; WAIT_L(0); MMA(0, 0, At, B0); BAR;
;     LDB(B1, 0, 1); BAR; WAIT_L(0); MMA(0, 1, At, B1); BAR;
;     LDA(At, 0, 1); WAIT_V(4); BAR; WAIT_L(0); MMA(1, 0, At, B0); MMA(1, 1, At, B1); BAR; }
;   { LDB(B0, 1, 0); LDA(At, 1, 0); WAIT_V(2); BAR; WAIT_L(0); MMA(0, 0, At, B0); BAR;
;     LDB(B1, 1, 1); WAIT_V(0); BAR; WAIT_L(0); MMA(0, 1, At, B1); BAR;
;     LDA(At, 1, 1); BAR; WAIT_L(0); MMA(1, 0, At, B0); MMA(1, 1, At, B1); BAR; }
	s_waitcnt lgkmcnt(0)
	v_mfma_f32_16x16x32_bf16 v[92:95], v[176:179], v[96:99], v[92:95]
	v_mfma_f32_16x16x32_bf16 v[88:91], v[176:179], v[112:115], v[88:91]
	v_mfma_f32_16x16x32_bf16 v[76:79], v[192:195], v[96:99], v[76:79]
	v_mfma_f32_16x16x32_bf16 v[72:75], v[192:195], v[112:115], v[72:75]
	v_mfma_f32_16x16x32_bf16 v[92:95], v[180:183], v[100:103], v[92:95]
	v_mfma_f32_16x16x32_bf16 v[88:91], v[180:183], v[116:119], v[88:91]
	v_mfma_f32_16x16x32_bf16 v[84:87], v[184:187], v[96:99], v[84:87]
	v_mfma_f32_16x16x32_bf16 v[80:83], v[184:187], v[112:115], v[80:83]
	v_mfma_f32_16x16x32_bf16 v[76:79], v[196:199], v[100:103], v[76:79]
	v_mfma_f32_16x16x32_bf16 v[72:75], v[196:199], v[116:119], v[72:75]
	v_mfma_f32_16x16x32_bf16 v[68:71], v[200:203], v[96:99], v[68:71]
	v_mfma_f32_16x16x32_bf16 v[64:67], v[200:203], v[112:115], v[64:67]
	v_mfma_f32_16x16x32_bf16 v[166:169], v[188:191], v[100:103], v[84:87]
	v_mfma_f32_16x16x32_bf16 v[174:177], v[188:191], v[116:119], v[80:83]
	v_mfma_f32_16x16x32_bf16 v[178:181], v[204:207], v[100:103], v[68:71]
	v_mfma_f32_16x16x32_bf16 v[182:185], v[204:207], v[116:119], v[64:67]
	s_barrier
	s_setprio 0
	s_nop 1
	ds_read_b128 v[64:67], v154 offset:16384
	ds_read_b128 v[68:71], v154 offset:17408
	ds_read_b128 v[80:83], v153 offset:16384
	ds_read_b128 v[84:87], v153 offset:17408
	ds_read_b128 v[186:189], v152 offset:16384
	ds_read_b128 v[190:193], v152 offset:17408
	ds_read_b128 v[194:197], v151 offset:16384
	ds_read_b128 v[198:201], v151 offset:17408
	s_waitcnt vmcnt(4)
	s_setprio 1
	s_barrier
	s_waitcnt lgkmcnt(0)
	v_mfma_f32_16x16x32_bf16 v[60:63], v[64:67], v[128:131], v[60:63]
	v_mfma_f32_16x16x32_bf16 v[52:55], v[80:83], v[128:131], v[52:55]
	v_mfma_f32_16x16x32_bf16 v[44:47], v[186:189], v[128:131], v[44:47]
	v_mfma_f32_16x16x32_bf16 v[36:39], v[194:197], v[128:131], v[36:39]
	v_mfma_f32_16x16x32_bf16 v[60:63], v[68:71], v[142:145], v[60:63]
	v_mfma_f32_16x16x32_bf16 v[56:59], v[64:67], v[158:161], v[56:59]
	v_mfma_f32_16x16x32_bf16 v[52:55], v[84:87], v[142:145], v[52:55]
	v_mfma_f32_16x16x32_bf16 v[48:51], v[80:83], v[158:161], v[48:51]
	v_mfma_f32_16x16x32_bf16 v[44:47], v[190:193], v[142:145], v[44:47]
	v_mfma_f32_16x16x32_bf16 v[40:43], v[186:189], v[158:161], v[40:43]
	v_mfma_f32_16x16x32_bf16 v[36:39], v[198:201], v[142:145], v[36:39]
	v_mfma_f32_16x16x32_bf16 v[32:35], v[194:197], v[158:161], v[32:35]
	v_mfma_f32_16x16x32_bf16 v[202:205], v[68:71], v[162:165], v[56:59]
	v_mfma_f32_16x16x32_bf16 v[220:223], v[84:87], v[162:165], v[48:51]
	v_mfma_f32_16x16x32_bf16 v[224:227], v[190:193], v[162:165], v[40:43]
	v_mfma_f32_16x16x32_bf16 v[128:131], v[198:201], v[162:165], v[32:35]
	s_setprio 0
	s_setprio 1
	v_mfma_f32_16x16x32_bf16 v[28:31], v[64:67], v[96:99], v[28:31]
	v_mfma_f32_16x16x32_bf16 v[20:23], v[80:83], v[96:99], v[20:23]
	v_mfma_f32_16x16x32_bf16 v[12:15], v[186:189], v[96:99], v[12:15]
	v_mfma_f32_16x16x32_bf16 v[4:7], v[194:197], v[96:99], v[4:7]
	v_mfma_f32_16x16x32_bf16 v[28:31], v[68:71], v[100:103], v[28:31]
	v_mfma_f32_16x16x32_bf16 v[24:27], v[64:67], v[112:115], v[24:27]
	v_mfma_f32_16x16x32_bf16 v[20:23], v[84:87], v[100:103], v[20:23]
	v_mfma_f32_16x16x32_bf16 v[16:19], v[80:83], v[112:115], v[16:19]
	v_mfma_f32_16x16x32_bf16 v[12:15], v[190:193], v[100:103], v[12:15]
	v_mfma_f32_16x16x32_bf16 v[8:11], v[186:189], v[112:115], v[8:11]
	v_mfma_f32_16x16x32_bf16 v[4:7], v[198:201], v[100:103], v[4:7]
	v_mfma_f32_16x16x32_bf16 v[0:3], v[194:197], v[112:115], v[0:3]
	v_mfma_f32_16x16x32_bf16 v[142:145], v[68:71], v[116:119], v[24:27]
	v_mfma_f32_16x16x32_bf16 v[158:161], v[84:87], v[116:119], v[16:19]
	v_mfma_f32_16x16x32_bf16 v[162:165], v[190:193], v[116:119], v[8:11]
	v_mfma_f32_16x16x32_bf16 v[186:189], v[198:201], v[116:119], v[0:3]
	s_barrier
	s_setprio 0
	s_nop 1
	ds_read_b128 v[0:3], v157
	ds_read_b128 v[8:11], v157 offset:1024
	ds_read_b128 v[190:193], v157 offset:2048
	ds_read_b128 v[194:197], v157 offset:3072
	ds_read_b128 v[16:19], v154 offset:32768
	ds_read_b128 v[24:27], v154 offset:33792
	ds_read_b128 v[32:35], v153 offset:32768
	ds_read_b128 v[40:43], v153 offset:33792
	ds_read_b128 v[48:51], v152 offset:32768
	ds_read_b128 v[56:59], v152 offset:33792
	ds_read_b128 v[198:201], v151 offset:32768
	ds_read_b128 v[228:231], v151 offset:33792
	s_waitcnt vmcnt(2)
	s_setprio 1
	s_barrier
	s_waitcnt lgkmcnt(0)
	v_mfma_f32_16x16x32_bf16 v[64:67], v[16:19], v[0:3], v[124:127]
	v_mfma_f32_16x16x32_bf16 v[116:119], v[24:27], v[8:11], v[64:67]
	v_mfma_f32_16x16x32_bf16 v[64:67], v[16:19], v[190:193], v[120:123]
	v_mfma_f32_16x16x32_bf16 v[112:115], v[24:27], v[194:197], v[64:67]
	v_mfma_f32_16x16x32_bf16 v[64:67], v[32:35], v[0:3], v[170:173]
	v_mfma_f32_16x16x32_bf16 v[100:103], v[40:43], v[8:11], v[64:67]
	v_mfma_f32_16x16x32_bf16 v[64:67], v[32:35], v[190:193], v[208:211]
	v_mfma_f32_16x16x32_bf16 v[96:99], v[40:43], v[194:197], v[64:67]
	v_mfma_f32_16x16x32_bf16 v[64:67], v[48:51], v[0:3], v[108:111]
	v_mfma_f32_16x16x32_bf16 v[84:87], v[56:59], v[8:11], v[64:67]
	v_mfma_f32_16x16x32_bf16 v[64:67], v[48:51], v[190:193], v[104:107]
	v_mfma_f32_16x16x32_bf16 v[80:83], v[56:59], v[194:197], v[64:67]
	v_mfma_f32_16x16x32_bf16 v[64:67], v[198:201], v[0:3], v[212:215]
	v_mfma_f32_16x16x32_bf16 v[68:71], v[228:231], v[8:11], v[64:67]
	v_mfma_f32_16x16x32_bf16 v[64:67], v[198:201], v[190:193], v[216:219]
	v_mfma_f32_16x16x32_bf16 v[64:67], v[228:231], v[194:197], v[64:67]
	s_barrier
	s_setprio 0
	ds_read_b128 v[170:173], v155
	ds_read_b128 v[206:209], v155 offset:1024
	ds_read_b128 v[210:213], v155 offset:2048
	ds_read_b128 v[214:217], v155 offset:3072
	s_waitcnt vmcnt(0)
	s_setprio 1
	s_barrier
; #define LDA(dst, b, h) for (int m = 0; m < 4; ++m) for (int k = 0; k < 2; ++k) \
;     dst[m][k] = *reinterpret_cast<const bf16x8*>((char*)SA(b, h) + lds_byte(wr * 64 + m * 16 + fr, k * 32 + fq * 8))
; #define LDB(dst, b, h) for (int n = 0; n < 2; ++n) for (int k = 0; k < 2; ++k) \
;     dst[n][k] = *reinterpret_cast<const bf16x8*>((char*)SB(b, h) + lds_byte(wc * 32 + n * 16 + fr, k * 32 + fq * 8))
; #define MMA(ai, bj, At, Bt) do { __builtin_amdgcn_s_setprio(1); \
;     for (int m = 0; m < 4; ++m) for (int n = 0; n < 2; ++n) for (int k = 0; k < 2; ++k) \
;       acc[ai][bj][m][n] = __builtin_amdgcn_mfma_f32_16x16x32_bf16(At[m][k], Bt[n][k], acc[ai][bj][m][n], 0, 0, 0); \
;     __builtin_amdgcn_s_setprio(0); } while (0)
; #define WAIT_V(n) asm volatile("s_waitcnt vmcnt(" #n ")" ::: "memory")
; #define WAIT_L(n) asm volatile("s_waitcnt lgkmcnt(" #n ")" ::: "memory")
; #define BAR __builtin_amdgcn_s_barrier()
; template <int EPI> ...
;     ...
;   { LDB(B0, 1, 0); LDA(At, 1, 0); WAIT_V(2); BAR; WAIT_L(0); MMA(0, 0, At, B0); BAR;
;     LDB(B1, 1, 1); WAIT_V(0); BAR; WAIT_L(0); MMA(0, 1, At, B1); BAR;
;     LDA(At, 1, 1); BAR; WAIT_L(0); MMA(1, 0, At, B0); MMA(1, 1, At, B1); BAR; }
;   if (wr == 0) BAR;
;   {
;     constexpr int NC = (EPI == EPI_GU) ? 128 : 256;
;     constexpr int RB = NC * 2;
;     char* tb = (char*)shm;
; #pragma unroll
;     for (int ai = 0; ai < 2; ++ai)
; #pragma unroll
;       for (int m = 0; m < 4; ++m)
; #pragma unroll
;         for (int j = 0; j < 4; ++j) {
;           const int r = ai * 128 + wr * 64 + m * 16 + fq * 4 + j;
;           float rs = 1.0f;
;           if (EPI != EPI_RES) rs = e.rstd[brow + r];
;           char* rowp = tb + r * RB + fr * 2;
	s_waitcnt lgkmcnt(0)
	v_mfma_f32_16x16x32_bf16 v[92:95], v[16:19], v[170:173], v[92:95]
	v_mfma_f32_16x16x32_bf16 v[16:19], v[16:19], v[210:213], v[88:91]
	v_mfma_f32_16x16x32_bf16 v[120:123], v[24:27], v[214:217], v[16:19]
	v_mfma_f32_16x16x32_bf16 v[16:19], v[32:35], v[170:173], v[166:169]
	v_mfma_f32_16x16x32_bf16 v[108:111], v[40:43], v[206:209], v[16:19]
	v_mfma_f32_16x16x32_bf16 v[16:19], v[32:35], v[210:213], v[174:177]
	v_mfma_f32_16x16x32_bf16 v[104:107], v[40:43], v[214:217], v[16:19]
	v_mfma_f32_16x16x32_bf16 v[16:19], v[48:51], v[170:173], v[76:79]
	v_mfma_f32_16x16x32_bf16 v[124:127], v[24:27], v[206:209], v[92:95]
	v_mfma_f32_16x16x32_bf16 v[92:95], v[56:59], v[206:209], v[16:19]
	v_mfma_f32_16x16x32_bf16 v[16:19], v[48:51], v[210:213], v[72:75]
	v_mfma_f32_16x16x32_bf16 v[88:91], v[56:59], v[214:217], v[16:19]
	v_mfma_f32_16x16x32_bf16 v[16:19], v[198:201], v[170:173], v[178:181]
	v_mfma_f32_16x16x32_bf16 v[76:79], v[228:231], v[206:209], v[16:19]
	v_mfma_f32_16x16x32_bf16 v[16:19], v[198:201], v[210:213], v[182:185]
	v_mfma_f32_16x16x32_bf16 v[72:75], v[228:231], v[214:217], v[16:19]
	s_barrier
	s_setprio 0
	ds_read_b128 v[166:169], v154 offset:49152
	ds_read_b128 v[154:157], v154 offset:50176
	ds_read_b128 v[174:177], v153 offset:49152
	ds_read_b128 v[178:181], v153 offset:50176
	ds_read_b128 v[182:185], v152 offset:49152
	ds_read_b128 v[198:201], v152 offset:50176
	ds_read_b128 v[228:231], v151 offset:49152
	ds_read_b128 v[232:235], v151 offset:50176
	s_setprio 1
	s_barrier
	s_waitcnt lgkmcnt(0)
	v_mfma_f32_16x16x32_bf16 v[16:19], v[166:169], v[0:3], v[60:63]
	v_mfma_f32_16x16x32_bf16 v[56:59], v[154:157], v[8:11], v[16:19]
	v_mfma_f32_16x16x32_bf16 v[16:19], v[166:169], v[190:193], v[202:205]
	v_mfma_f32_16x16x32_bf16 v[48:51], v[154:157], v[194:197], v[16:19]
	v_mfma_f32_16x16x32_bf16 v[16:19], v[174:177], v[0:3], v[52:55]
	v_mfma_f32_16x16x32_bf16 v[40:43], v[178:181], v[8:11], v[16:19]
	v_mfma_f32_16x16x32_bf16 v[16:19], v[174:177], v[190:193], v[220:223]
	v_mfma_f32_16x16x32_bf16 v[32:35], v[178:181], v[194:197], v[16:19]
	v_mfma_f32_16x16x32_bf16 v[16:19], v[182:185], v[0:3], v[44:47]
	v_mfma_f32_16x16x32_bf16 v[0:3], v[228:231], v[0:3], v[36:39]
	v_mfma_f32_16x16x32_bf16 v[24:27], v[198:201], v[8:11], v[16:19]
	v_mfma_f32_16x16x32_bf16 v[16:19], v[182:185], v[190:193], v[224:227]
	v_mfma_f32_16x16x32_bf16 v[8:11], v[232:235], v[8:11], v[0:3]
	v_mfma_f32_16x16x32_bf16 v[0:3], v[228:231], v[190:193], v[128:131]
	v_mfma_f32_16x16x32_bf16 v[16:19], v[198:201], v[194:197], v[16:19]
	v_mfma_f32_16x16x32_bf16 v[0:3], v[232:235], v[194:197], v[0:3]
	s_setprio 0
	s_setprio 1
	v_mfma_f32_16x16x32_bf16 v[28:31], v[166:169], v[170:173], v[28:31]
	v_mfma_f32_16x16x32_bf16 v[60:63], v[154:157], v[206:209], v[28:31]
	v_mfma_f32_16x16x32_bf16 v[28:31], v[166:169], v[210:213], v[142:145]
	v_mfma_f32_16x16x32_bf16 v[20:23], v[174:177], v[170:173], v[20:23]
	v_mfma_f32_16x16x32_bf16 v[12:15], v[182:185], v[170:173], v[12:15]
	v_mfma_f32_16x16x32_bf16 v[52:55], v[154:157], v[214:217], v[28:31]
	v_mfma_f32_16x16x32_bf16 v[44:47], v[178:181], v[206:209], v[20:23]
	v_mfma_f32_16x16x32_bf16 v[20:23], v[174:177], v[210:213], v[158:161]
	v_mfma_f32_16x16x32_bf16 v[28:31], v[198:201], v[206:209], v[12:15]
	v_mfma_f32_16x16x32_bf16 v[12:15], v[182:185], v[210:213], v[162:165]
	v_mfma_f32_16x16x32_bf16 v[4:7], v[228:231], v[170:173], v[4:7]
	v_mfma_f32_16x16x32_bf16 v[36:39], v[178:181], v[214:217], v[20:23]
	v_mfma_f32_16x16x32_bf16 v[20:23], v[198:201], v[214:217], v[12:15]
	v_mfma_f32_16x16x32_bf16 v[12:15], v[232:235], v[206:209], v[4:7]
	v_mfma_f32_16x16x32_bf16 v[4:7], v[228:231], v[210:213], v[186:189]
	v_mfma_f32_16x16x32_bf16 v[4:7], v[232:235], v[214:217], v[4:7]
	s_barrier
	s_setprio 0
	v_cmp_gt_u32_e32 vcc, s50, v136
	s_and_saveexec_b64 s[28:29], vcc
	s_cbranch_execz .LBB0_1719
	s_barrier
.LBB0_1719:
	s_or_b64 exec, exec, s[28:29]
	v_lshl_or_b32 v145, v147, 2, v150
	v_add_u32_e32 v128, s26, v145
	v_ashrrev_i32_e32 v129, 31, v128
	v_lshl_add_u64 v[128:129], v[128:129], 2, s[0:1]
	global_load_dwordx4 v[150:153], v[128:129], off
	v_lshl_add_u32 v144, v149, 1, 0
	v_lshlrev_b32_e32 v128, 1, v148
	v_lshl_add_u32 v136, v145, 8, v144
	v_xor_b32_e32 v129, v128, v147
	v_bitop3_b32 v128, v128, v147, 1 bitop3:0x36
	v_or_b32_e32 v147, 16, v145
	v_lshlrev_b32_e32 v143, 5, v129
	v_lshlrev_b32_e32 v142, 5, v128
	v_add_u32_e32 v129, 0x100, v136
	v_add_u32_e32 v128, s26, v147
	v_add_u32_e32 v155, v129, v143
	v_add_u32_e32 v156, v129, v142
	v_ashrrev_i32_e32 v129, 31, v128
	v_lshl_add_u64 v[128:129], v[128:129], 2, s[0:1]
	global_load_dwordx4 v[128:131], v[128:129], off
	v_add_u32_e32 v148, 0x200, v136
	v_add_u32_e32 v149, v136, v143
	v_add_u32_e32 v154, v136, v142
	v_add_u32_e32 v157, v148, v143
	s_add_i32 s25, s53, 0xffffff75
	s_ashr_i32 s27, s53, 31
	s_cmpk_lt_i32 s53, 0x8b
	s_cselect_b32 s25, s53, s25
	s_cselect_b32 s27, s27, 0
	s_mul_i32 s27, s27, 0x2c0000
	s_mul_hi_u32 s30, s25, 0x2c0000
	s_cselect_b32 s29, s73, s42
	s_cselect_b32 s28, s72, s41
	s_mul_i32 s25, s25, 0x2c0000
	s_add_i32 s30, s30, s27
	s_add_u32 s28, s28, s25
	s_addc_u32 s29, s29, s30
	s_waitcnt vmcnt(0)
; __device__ __forceinline__ u16 f2bf(float f) { unsigned u = __float_as_uint(f); u += 0x7fffu + ((u >> 16) & 1u); return (u16)(u >> 16); }
; __device__ __forceinline__ float frcp(float x) { return __builtin_amdgcn_rcpf(x); }
; template <int EPI> ...
;     ...
;     for (int ai = 0; ai < 2; ++ai)
; #pragma unroll
;       for (int m = 0; m < 4; ++m)
; #pragma unroll
;         for (int j = 0; j < 4; ++j) {
;           const int r = ai * 128 + wr * 64 + m * 16 + fq * 4 + j;
;           float rs = 1.0f;
;           if (EPI != EPI_RES) rs = e.rstd[brow + r];
;           char* rowp = tb + r * RB + fr * 2;
;           if (EPI == EPI_GU) {
; #pragma unroll
;             for (int n = 0; n < 2; ++n) {
;               float g = acc[ai][0][m][n][j] * rs, u = acc[ai][1][m][n][j] * rs;
;               float h = g * frcp(1.0f + __expf(-g)) * u;
;               const int seg = (wc * 2 + n) ^ fq;
;               *(u16*)(rowp + seg * 32) = f2bf(h);
;             }
	v_mul_f32_e32 v116, v116, v150
	v_mul_f32_e32 v112, v112, v150
	v_mul_f32_e32 v124, v124, v150
	v_mul_f32_e32 v120, v120, v150
	v_mul_f32_e32 v117, v117, v151
	v_mul_f32_e32 v125, v125, v151
	v_mul_f32_e32 v113, v113, v151
	v_mul_f32_e32 v121, v121, v151
	v_mul_f32_e32 v118, v118, v152
	v_mul_f32_e32 v150, 0xbfb8aa3b, v116
	v_mul_f32_e32 v151, 0xbfb8aa3b, v112
	v_mul_f32_e32 v126, v126, v152
	v_mul_f32_e32 v114, v114, v152
	v_mul_f32_e32 v122, v122, v152
	v_mul_f32_e32 v152, 0xbfb8aa3b, v117
	v_mul_f32_e32 v158, 0xbfb8aa3b, v113
	v_mul_f32_e32 v159, 0xbfb8aa3b, v118
	v_exp_f32_e32 v150, v150
	v_exp_f32_e32 v151, v151
	v_mul_f32_e32 v160, 0xbfb8aa3b, v114
	v_exp_f32_e32 v152, v152
	v_exp_f32_e32 v158, v158
	v_exp_f32_e32 v159, v159
	v_exp_f32_e32 v160, v160
	v_add_f32_e32 v150, 1.0, v150
	v_add_f32_e32 v151, 1.0, v151
	v_add_f32_e32 v152, 1.0, v152
	v_add_f32_e32 v158, 1.0, v158
	v_add_f32_e32 v159, 1.0, v159
	v_rcp_f32_e32 v150, v150
	v_rcp_f32_e32 v151, v151
	v_add_f32_e32 v160, 1.0, v160
	v_rcp_f32_e32 v152, v152
	v_rcp_f32_e32 v158, v158
	v_rcp_f32_e32 v159, v159
	v_rcp_f32_e32 v160, v160
	v_mul_f32_e32 v116, v116, v150
	v_mul_f32_e32 v112, v112, v151
	v_mul_f32_e32 v117, v117, v152
	v_mul_f32_e32 v113, v113, v158
	v_mul_f32_e32 v118, v118, v159
	v_mul_f32_e32 v116, v124, v116
	v_mul_f32_e32 v112, v120, v112
	v_mul_f32_e32 v114, v114, v160
	v_mul_f32_e32 v117, v125, v117
	v_mul_f32_e32 v113, v121, v113
	v_mul_f32_e32 v118, v126, v118
	v_mul_f32_e32 v114, v122, v114
	v_cvt_pk_bf16_f32 v116, v116, v116
	v_cvt_pk_bf16_f32 v112, v112, v112
	v_cvt_pk_bf16_f32 v117, v117, v117
	v_cvt_pk_bf16_f32 v113, v113, v113
	v_cvt_pk_bf16_f32 v118, v118, v118
	ds_write_b16_d16_hi v149, v116
	ds_write_b16_d16_hi v154, v112
	ds_write_b16_d16_hi v155, v117
	ds_write_b16_d16_hi v156, v113
	ds_write_b16_d16_hi v157, v118
	v_mul_f32_e32 v112, v119, v153
	v_mul_f32_e32 v113, 0xbfb8aa3b, v112
	v_exp_f32_e32 v113, v113
	v_cvt_pk_bf16_f32 v114, v114, v114
	v_add_u32_e32 v116, v148, v142
	v_add_f32_e32 v113, 1.0, v113
	v_rcp_f32_e32 v113, v113
	ds_write_b16_d16_hi v116, v114
	v_mul_f32_e32 v116, v127, v153
	v_add_u32_e32 v114, 0x300, v136
	v_mul_f32_e32 v112, v112, v113
	v_mul_f32_e32 v113, v115, v153
	v_mul_f32_e32 v115, 0xbfb8aa3b, v113
	v_exp_f32_e32 v115, v115
	v_mul_f32_e32 v112, v116, v112
	v_cvt_pk_bf16_f32 v112, v112, v112
	v_add_f32_e32 v115, 1.0, v115
	v_rcp_f32_e32 v115, v115
	v_add_u32_e32 v116, v114, v143
	ds_write_b16_d16_hi v116, v112
	v_mul_f32_e32 v112, v123, v153
	v_mul_f32_e32 v113, v113, v115
	v_mul_f32_e32 v100, v100, v128
	v_mul_f32_e32 v112, v112, v113
	v_mul_f32_e32 v113, 0xbfb8aa3b, v100
	v_exp_f32_e32 v113, v113
	v_bfe_u32 v115, v112, 16, 1
	v_add3_u32 v112, v112, v115, s51
	v_add_u32_e32 v114, v114, v142
	v_add_f32_e32 v113, 1.0, v113
	v_rcp_f32_e32 v113, v113
	v_mul_f32_e32 v96, v96, v128
	ds_write_b16_d16_hi v114, v112
	v_mul_f32_e32 v112, 0xbfb8aa3b, v96
	v_exp_f32_e32 v112, v112
	v_mul_f32_e32 v108, v108, v128
	v_mul_f32_e32 v100, v100, v113
	v_mul_f32_e32 v100, v108, v100
	v_cvt_pk_bf16_f32 v100, v100, v100
	v_add_f32_e32 v108, 1.0, v112
	v_rcp_f32_e32 v108, v108
	v_lshl_add_u32 v116, v147, 8, v144
	v_add_u32_e32 v112, v116, v143
	ds_write_b16_d16_hi v112, v100
	v_mul_f32_e32 v100, v104, v128
	v_mul_f32_e32 v96, v96, v108
	v_or_b32_e32 v108, 32, v145
	v_mul_f32_e32 v96, v100, v96
	v_add_u32_e32 v100, s26, v108
	v_mul_f32_e32 v104, v101, v129
	v_ashrrev_i32_e32 v101, 31, v100
	v_lshl_add_u64 v[100:101], v[100:101], 2, s[0:1]
	global_load_dwordx4 v[112:115], v[100:101], off
	v_mul_f32_e32 v100, 0xbfb8aa3b, v104
	v_exp_f32_e32 v100, v100
	v_mul_f32_e32 v97, v97, v129
	v_cvt_pk_bf16_f32 v96, v96, v96
	v_add_f32_e32 v100, 1.0, v100
	v_rcp_f32_e32 v100, v100
	v_add_u32_e32 v101, v116, v142
	ds_write_b16_d16_hi v101, v96
	v_mul_f32_e32 v101, v109, v129
	v_mul_f32_e32 v100, v104, v100
	v_mul_f32_e32 v104, 0xbfb8aa3b, v97
	v_exp_f32_e32 v104, v104
	v_mul_f32_e32 v100, v101, v100
	v_cvt_pk_bf16_f32 v100, v100, v100
	v_add_f32_e32 v101, 1.0, v104
	v_rcp_f32_e32 v101, v101
	v_add_u32_e32 v96, 0x1100, v136
	v_add_u32_e32 v104, v96, v143
	ds_write_b16_d16_hi v104, v100
	v_mul_f32_e32 v100, v105, v129
	v_mul_f32_e32 v97, v97, v101
	v_mul_f32_e32 v97, v100, v97
	v_mul_f32_e32 v100, v102, v130
	v_mul_f32_e32 v101, 0xbfb8aa3b, v100
	v_exp_f32_e32 v101, v101
	v_mul_f32_e32 v98, v98, v130
	v_cvt_pk_bf16_f32 v97, v97, v97
	v_add_f32_e32 v101, 1.0, v101
	v_rcp_f32_e32 v101, v101
	v_add_u32_e32 v96, v96, v142
	ds_write_b16_d16_hi v96, v97
	v_mul_f32_e32 v97, v110, v130
	v_mul_f32_e32 v100, v100, v101
	v_mul_f32_e32 v101, 0xbfb8aa3b, v98
	v_exp_f32_e32 v101, v101
	v_mul_f32_e32 v97, v97, v100
	v_cvt_pk_bf16_f32 v97, v97, v97
	v_add_f32_e32 v100, 1.0, v101
	v_rcp_f32_e32 v100, v100
	v_add_u32_e32 v96, 0x1200, v136
	v_add_u32_e32 v101, v96, v143
	ds_write_b16_d16_hi v101, v97
	v_mul_f32_e32 v97, v106, v130
	v_mul_f32_e32 v98, v98, v100
	v_mul_f32_e32 v97, v97, v98
	v_mul_f32_e32 v98, v103, v131
	v_mul_f32_e32 v100, 0xbfb8aa3b, v98
	v_exp_f32_e32 v100, v100
	v_cvt_pk_bf16_f32 v97, v97, v97
	v_add_u32_e32 v96, v96, v142
	v_add_f32_e32 v100, 1.0, v100
	v_rcp_f32_e32 v100, v100
	ds_write_b16_d16_hi v96, v97
	v_mul_f32_e32 v96, v111, v131
	v_add_u32_e32 v101, 0x1300, v136
	v_mul_f32_e32 v97, v98, v100
	v_mul_f32_e32 v98, v99, v131
	v_mul_f32_e32 v99, 0xbfb8aa3b, v98
	v_exp_f32_e32 v99, v99
	v_mul_f32_e32 v96, v96, v97
	v_cvt_pk_bf16_f32 v96, v96, v96
	v_add_f32_e32 v97, 1.0, v99
	v_rcp_f32_e32 v97, v97
	v_add_u32_e32 v99, v101, v143
	ds_write_b16_d16_hi v99, v96
	v_mul_f32_e32 v96, v107, v131
	v_mul_f32_e32 v97, v98, v97
	v_or_b32_e32 v102, 48, v145
	v_mul_f32_e32 v100, v96, v97
	v_add_u32_e32 v96, s26, v102
	v_ashrrev_i32_e32 v97, 31, v96
	v_lshl_add_u64 v[96:97], v[96:97], 2, s[0:1]
	global_load_dwordx4 v[96:99], v[96:97], off
	s_waitcnt vmcnt(1)
; __device__ __forceinline__ u16 f2bf(float f) { unsigned u = __float_as_uint(f); u += 0x7fffu + ((u >> 16) & 1u); return (u16)(u >> 16); }
; __device__ __forceinline__ float frcp(float x) { return __builtin_amdgcn_rcpf(x); }
; template <int EPI> ...
;     ...
;     for (int ai = 0; ai < 2; ++ai)
; #pragma unroll
;       for (int m = 0; m < 4; ++m)
; #pragma unroll
;         for (int j = 0; j < 4; ++j) {
;           const int r = ai * 128 + wr * 64 + m * 16 + fq * 4 + j;
;           float rs = 1.0f;
;           if (EPI != EPI_RES) rs = e.rstd[brow + r];
;           char* rowp = tb + r * RB + fr * 2;
;           if (EPI == EPI_GU) {
; #pragma unroll
;             for (int n = 0; n < 2; ++n) {
;               float g = acc[ai][0][m][n][j] * rs, u = acc[ai][1][m][n][j] * rs;
;               float h = g * frcp(1.0f + __expf(-g)) * u;
;               const int seg = (wc * 2 + n) ^ fq;
;               *(u16*)(rowp + seg * 32) = f2bf(h);
;             }
	v_mul_f32_e32 v84, v84, v112
	v_mul_f32_e32 v103, 0xbfb8aa3b, v84
	v_exp_f32_e32 v103, v103
	v_cvt_pk_bf16_f32 v100, v100, v100
	v_add_u32_e32 v101, v101, v142
	v_add_f32_e32 v103, 1.0, v103
	v_rcp_f32_e32 v103, v103
	v_mul_f32_e32 v80, v80, v112
	ds_write_b16_d16_hi v101, v100
	v_mul_f32_e32 v101, 0xbfb8aa3b, v80
	v_exp_f32_e32 v101, v101
	v_mul_f32_e32 v92, v92, v112
	v_mul_f32_e32 v84, v84, v103
	v_mul_f32_e32 v84, v92, v84
	v_cvt_pk_bf16_f32 v84, v84, v84
	v_add_f32_e32 v92, 1.0, v101
	v_rcp_f32_e32 v92, v92
	v_lshl_add_u32 v100, v108, 8, v144
	v_add_u32_e32 v101, v100, v143
	ds_write_b16_d16_hi v101, v84
	v_mul_f32_e32 v84, v88, v112
	v_mul_f32_e32 v80, v80, v92
	v_mul_f32_e32 v80, v84, v80
	v_mul_f32_e32 v84, v85, v113
	v_mul_f32_e32 v85, 0xbfb8aa3b, v84
	v_exp_f32_e32 v85, v85
	v_mul_f32_e32 v81, v81, v113
	v_cvt_pk_bf16_f32 v80, v80, v80
	v_add_f32_e32 v85, 1.0, v85
	v_rcp_f32_e32 v85, v85
	v_add_u32_e32 v88, v100, v142
	ds_write_b16_d16_hi v88, v80
	v_mul_f32_e32 v88, v93, v113
	v_mul_f32_e32 v84, v84, v85
	v_mul_f32_e32 v85, 0xbfb8aa3b, v81
	v_exp_f32_e32 v85, v85
	v_mul_f32_e32 v84, v88, v84
	v_add_u32_e32 v80, 0x2100, v136
	v_add_f32_e32 v85, 1.0, v85
	v_rcp_f32_e32 v85, v85
	v_cvt_pk_bf16_f32 v84, v84, v84
	v_add_u32_e32 v88, v80, v143
	ds_write_b16_d16_hi v88, v84
	v_mul_f32_e32 v84, v89, v113
	v_mul_f32_e32 v81, v81, v85
	v_mul_f32_e32 v81, v84, v81
	v_mul_f32_e32 v84, v86, v114
	v_mul_f32_e32 v85, 0xbfb8aa3b, v84
	v_exp_f32_e32 v85, v85
	v_mul_f32_e32 v82, v82, v114
	v_cvt_pk_bf16_f32 v81, v81, v81
	v_add_f32_e32 v85, 1.0, v85
	v_rcp_f32_e32 v85, v85
	v_add_u32_e32 v80, v80, v142
	ds_write_b16_d16_hi v80, v81
	v_mul_f32_e32 v81, v94, v114
	v_mul_f32_e32 v84, v84, v85
	v_mul_f32_e32 v85, 0xbfb8aa3b, v82
	v_exp_f32_e32 v85, v85
	v_mul_f32_e32 v81, v81, v84
	v_cvt_pk_bf16_f32 v81, v81, v81
	v_add_f32_e32 v84, 1.0, v85
	v_rcp_f32_e32 v84, v84
	v_add_u32_e32 v80, 0x2200, v136
	v_add_u32_e32 v85, v80, v143
	ds_write_b16_d16_hi v85, v81
	v_mul_f32_e32 v81, v90, v114
	v_mul_f32_e32 v82, v82, v84
	v_mul_f32_e32 v81, v81, v82
	v_mul_f32_e32 v82, v87, v115
	v_mul_f32_e32 v84, 0xbfb8aa3b, v82
	v_exp_f32_e32 v84, v84
	v_mul_f32_e32 v83, v83, v115
	v_cvt_pk_bf16_f32 v81, v81, v81
	v_add_f32_e32 v84, 1.0, v84
	v_rcp_f32_e32 v84, v84
	v_add_u32_e32 v80, v80, v142
	ds_write_b16_d16_hi v80, v81
	v_mul_f32_e32 v81, v95, v115
	v_mul_f32_e32 v82, v82, v84
	v_mul_f32_e32 v84, 0xbfb8aa3b, v83
	v_exp_f32_e32 v84, v84
	v_mul_f32_e32 v81, v81, v82
	v_cvt_pk_bf16_f32 v81, v81, v81
	v_add_f32_e32 v82, 1.0, v84
	v_rcp_f32_e32 v82, v82
	v_add_u32_e32 v80, 0x2300, v136
	v_add_u32_e32 v84, v80, v143
	ds_write_b16_d16_hi v84, v81
	v_mul_f32_e32 v81, v91, v115
	v_mul_f32_e32 v82, v83, v82
	s_waitcnt vmcnt(0)
	v_mul_f32_e32 v68, v68, v96
	v_mul_f32_e32 v81, v81, v82
	v_mul_f32_e32 v82, 0xbfb8aa3b, v68
	v_exp_f32_e32 v82, v82
	v_bfe_u32 v83, v81, 16, 1
	v_add3_u32 v81, v81, v83, s51
	v_add_u32_e32 v80, v80, v142
	v_add_f32_e32 v82, 1.0, v82
	v_rcp_f32_e32 v82, v82
	v_mul_f32_e32 v64, v64, v96
	ds_write_b16_d16_hi v80, v81
	v_mul_f32_e32 v80, 0xbfb8aa3b, v64
	v_exp_f32_e32 v80, v80
	v_mul_f32_e32 v76, v76, v96
	v_mul_f32_e32 v68, v68, v82
	v_mul_f32_e32 v68, v76, v68
	v_cvt_pk_bf16_f32 v68, v68, v68
	v_add_f32_e32 v76, 1.0, v80
	v_rcp_f32_e32 v76, v76
	v_lshl_add_u32 v84, v102, 8, v144
	v_add_u32_e32 v80, v84, v143
	ds_write_b16_d16_hi v80, v68
	v_mul_f32_e32 v68, v72, v96
	v_mul_f32_e32 v64, v64, v76
	v_add_u32_e32 v76, 0x80, v145
	v_mul_f32_e32 v64, v68, v64
	v_add_u32_e32 v68, s26, v76
	v_mul_f32_e32 v72, v69, v97
	v_ashrrev_i32_e32 v69, 31, v68
	v_lshl_add_u64 v[68:69], v[68:69], 2, s[0:1]
	global_load_dwordx4 v[80:83], v[68:69], off
	v_mul_f32_e32 v68, 0xbfb8aa3b, v72
	v_exp_f32_e32 v68, v68
	v_mul_f32_e32 v65, v65, v97
	v_cvt_pk_bf16_f32 v64, v64, v64
	v_add_f32_e32 v68, 1.0, v68
	v_rcp_f32_e32 v68, v68
	v_add_u32_e32 v69, v84, v142
	ds_write_b16_d16_hi v69, v64
	v_mul_f32_e32 v69, v77, v97
	v_mul_f32_e32 v68, v72, v68
	v_mul_f32_e32 v72, 0xbfb8aa3b, v65
	v_exp_f32_e32 v72, v72
	v_mul_f32_e32 v68, v69, v68
	v_cvt_pk_bf16_f32 v68, v68, v68
	v_add_f32_e32 v69, 1.0, v72
	v_rcp_f32_e32 v69, v69
	v_add_u32_e32 v64, 0x3100, v136
	v_add_u32_e32 v72, v64, v143
	ds_write_b16_d16_hi v72, v68
	v_mul_f32_e32 v68, v73, v97
	v_mul_f32_e32 v65, v65, v69
	v_mul_f32_e32 v65, v68, v65
	v_mul_f32_e32 v68, v70, v98
	v_mul_f32_e32 v69, 0xbfb8aa3b, v68
	v_exp_f32_e32 v69, v69
	v_mul_f32_e32 v66, v66, v98
	v_cvt_pk_bf16_f32 v65, v65, v65
	v_add_f32_e32 v69, 1.0, v69
	v_rcp_f32_e32 v69, v69
	v_add_u32_e32 v64, v64, v142
	ds_write_b16_d16_hi v64, v65
	v_mul_f32_e32 v65, v78, v98
	v_mul_f32_e32 v68, v68, v69
	v_mul_f32_e32 v69, 0xbfb8aa3b, v66
	v_exp_f32_e32 v69, v69
	v_mul_f32_e32 v65, v65, v68
	v_cvt_pk_bf16_f32 v65, v65, v65
	v_add_f32_e32 v68, 1.0, v69
	v_rcp_f32_e32 v68, v68
	v_add_u32_e32 v64, 0x3200, v136
	v_add_u32_e32 v69, v64, v143
	ds_write_b16_d16_hi v69, v65
	v_mul_f32_e32 v65, v74, v98
	v_mul_f32_e32 v66, v66, v68
	v_mul_f32_e32 v65, v65, v66
	v_mul_f32_e32 v66, v71, v99
	v_mul_f32_e32 v68, 0xbfb8aa3b, v66
	v_exp_f32_e32 v68, v68
	v_cvt_pk_bf16_f32 v65, v65, v65
	v_add_u32_e32 v64, v64, v142
	v_add_f32_e32 v68, 1.0, v68
	v_rcp_f32_e32 v68, v68
	ds_write_b16_d16_hi v64, v65
	v_mul_f32_e32 v64, v79, v99
	v_add_u32_e32 v69, 0x3300, v136
	v_mul_f32_e32 v65, v66, v68
	v_mul_f32_e32 v66, v67, v99
	v_mul_f32_e32 v67, 0xbfb8aa3b, v66
	v_exp_f32_e32 v67, v67
	v_mul_f32_e32 v64, v64, v65
	v_cvt_pk_bf16_f32 v64, v64, v64
	v_add_f32_e32 v65, 1.0, v67
	v_rcp_f32_e32 v65, v65
	v_add_u32_e32 v67, v69, v143
	ds_write_b16_d16_hi v67, v64
	v_mul_f32_e32 v64, v75, v99
	v_mul_f32_e32 v65, v66, v65
	v_add_u32_e32 v70, 0x90, v145
	v_mul_f32_e32 v68, v64, v65
	v_add_u32_e32 v64, s26, v70
	v_ashrrev_i32_e32 v65, 31, v64
	v_lshl_add_u64 v[64:65], v[64:65], 2, s[0:1]
	global_load_dwordx4 v[64:67], v[64:65], off
	s_waitcnt vmcnt(1)
; __device__ __forceinline__ u16 f2bf(float f) { unsigned u = __float_as_uint(f); u += 0x7fffu + ((u >> 16) & 1u); return (u16)(u >> 16); }
; __device__ __forceinline__ float frcp(float x) { return __builtin_amdgcn_rcpf(x); }
; template <int EPI> ...
;     ...
;     for (int ai = 0; ai < 2; ++ai)
; #pragma unroll
;       for (int m = 0; m < 4; ++m)
; #pragma unroll
;         for (int j = 0; j < 4; ++j) {
;           const int r = ai * 128 + wr * 64 + m * 16 + fq * 4 + j;
;           float rs = 1.0f;
;           if (EPI != EPI_RES) rs = e.rstd[brow + r];
;           char* rowp = tb + r * RB + fr * 2;
;           if (EPI == EPI_GU) {
; #pragma unroll
;             for (int n = 0; n < 2; ++n) {
;               float g = acc[ai][0][m][n][j] * rs, u = acc[ai][1][m][n][j] * rs;
;               float h = g * frcp(1.0f + __expf(-g)) * u;
;               const int seg = (wc * 2 + n) ^ fq;
;               *(u16*)(rowp + seg * 32) = f2bf(h);
;             }
	v_mul_f32_e32 v56, v56, v80
	v_mul_f32_e32 v71, 0xbfb8aa3b, v56
	v_exp_f32_e32 v71, v71
	v_cvt_pk_bf16_f32 v68, v68, v68
	v_add_u32_e32 v69, v69, v142
	v_add_f32_e32 v71, 1.0, v71
	v_rcp_f32_e32 v71, v71
	v_mul_f32_e32 v48, v48, v80
	ds_write_b16_d16_hi v69, v68
	v_mul_f32_e32 v69, 0xbfb8aa3b, v48
	v_exp_f32_e32 v69, v69
	v_mul_f32_e32 v60, v60, v80
	v_mul_f32_e32 v56, v56, v71
	v_mul_f32_e32 v56, v60, v56
	v_cvt_pk_bf16_f32 v56, v56, v56
	v_add_f32_e32 v60, 1.0, v69
	v_rcp_f32_e32 v60, v60
	v_lshl_add_u32 v68, v76, 8, v144
	v_mul_f32_e32 v52, v52, v80
	v_add_u32_e32 v69, v68, v143
	v_mul_f32_e32 v48, v48, v60
	v_mul_f32_e32 v48, v52, v48
	v_mul_f32_e32 v52, v57, v81
	ds_write_b16_d16_hi v69, v56
	v_mul_f32_e32 v56, 0xbfb8aa3b, v52
	v_exp_f32_e32 v56, v56
	v_mul_f32_e32 v49, v49, v81
	v_cvt_pk_bf16_f32 v48, v48, v48
	v_add_f32_e32 v56, 1.0, v56
	v_rcp_f32_e32 v56, v56
	v_add_u32_e32 v57, v68, v142
	ds_write_b16_d16_hi v57, v48
	v_mul_f32_e32 v57, v61, v81
	v_mul_f32_e32 v52, v52, v56
	v_mul_f32_e32 v56, 0xbfb8aa3b, v49
	v_exp_f32_e32 v56, v56
	v_mul_f32_e32 v52, v57, v52
	v_add_u32_e32 v48, 0x8100, v136
	v_add_f32_e32 v56, 1.0, v56
	v_rcp_f32_e32 v56, v56
	v_cvt_pk_bf16_f32 v52, v52, v52
	v_add_u32_e32 v57, v48, v143
	ds_write_b16_d16_hi v57, v52
	v_mul_f32_e32 v52, v53, v81
	v_mul_f32_e32 v49, v49, v56
	v_mul_f32_e32 v49, v52, v49
	v_mul_f32_e32 v52, v58, v82
	v_mul_f32_e32 v53, 0xbfb8aa3b, v52
	v_exp_f32_e32 v53, v53
	v_mul_f32_e32 v50, v50, v82
	v_bfe_u32 v56, v49, 16, 1
	v_add3_u32 v49, v49, v56, s51
	v_add_f32_e32 v53, 1.0, v53
	v_rcp_f32_e32 v53, v53
	v_add_u32_e32 v48, v48, v142
	ds_write_b16_d16_hi v48, v49
	v_mul_f32_e32 v49, v62, v82
	v_mul_f32_e32 v52, v52, v53
	v_mul_f32_e32 v53, 0xbfb8aa3b, v50
	v_exp_f32_e32 v53, v53
	v_mul_f32_e32 v49, v49, v52
	v_cvt_pk_bf16_f32 v49, v49, v49
	v_add_f32_e32 v52, 1.0, v53
	v_rcp_f32_e32 v52, v52
	v_add_u32_e32 v48, 0x8200, v136
	v_add_u32_e32 v53, v48, v143
	ds_write_b16_d16_hi v53, v49
	v_mul_f32_e32 v49, v54, v82
	v_mul_f32_e32 v50, v50, v52
	v_mul_f32_e32 v49, v49, v50
	v_mul_f32_e32 v50, v59, v83
	v_mul_f32_e32 v52, 0xbfb8aa3b, v50
	v_exp_f32_e32 v52, v52
	v_mul_f32_e32 v51, v51, v83
	v_bfe_u32 v53, v49, 16, 1
	v_add3_u32 v49, v49, v53, s51
	v_add_f32_e32 v52, 1.0, v52
	v_rcp_f32_e32 v52, v52
	v_add_u32_e32 v48, v48, v142
	ds_write_b16_d16_hi v48, v49
	v_mul_f32_e32 v49, v63, v83
	v_mul_f32_e32 v50, v50, v52
	v_mul_f32_e32 v52, 0xbfb8aa3b, v51
	v_exp_f32_e32 v52, v52
	v_mul_f32_e32 v49, v49, v50
	v_cvt_pk_bf16_f32 v49, v49, v49
	v_add_f32_e32 v50, 1.0, v52
	v_rcp_f32_e32 v50, v50
	v_add_u32_e32 v48, 0x8300, v136
	v_add_u32_e32 v52, v48, v143
	ds_write_b16_d16_hi v52, v49
	v_mul_f32_e32 v49, v55, v83
	v_mul_f32_e32 v50, v51, v50
	s_waitcnt vmcnt(0)
	v_mul_f32_e32 v40, v40, v64
	v_mul_f32_e32 v49, v49, v50
	v_mul_f32_e32 v50, 0xbfb8aa3b, v40
	v_exp_f32_e32 v50, v50
	v_bfe_u32 v51, v49, 16, 1
	v_add3_u32 v49, v49, v51, s51
	v_add_u32_e32 v48, v48, v142
	v_add_f32_e32 v50, 1.0, v50
	v_rcp_f32_e32 v50, v50
	v_mul_f32_e32 v32, v32, v64
	ds_write_b16_d16_hi v48, v49
	v_mul_f32_e32 v48, 0xbfb8aa3b, v32
	v_exp_f32_e32 v48, v48
	v_mul_f32_e32 v44, v44, v64
	v_mul_f32_e32 v40, v40, v50
	v_mul_f32_e32 v40, v44, v40
	v_cvt_pk_bf16_f32 v40, v40, v40
	v_add_f32_e32 v44, 1.0, v48
	v_rcp_f32_e32 v44, v44
	v_lshl_add_u32 v52, v70, 8, v144
	v_add_u32_e32 v48, v52, v143
	ds_write_b16_d16_hi v48, v40
	v_mul_f32_e32 v32, v32, v44
	v_add_u32_e32 v44, 0xa0, v145
	v_mul_f32_e32 v36, v36, v64
	v_add_u32_e32 v40, s26, v44
	v_mul_f32_e32 v32, v36, v32
	v_mul_f32_e32 v36, v41, v65
	v_ashrrev_i32_e32 v41, 31, v40
	v_lshl_add_u64 v[40:41], v[40:41], 2, s[0:1]
	global_load_dwordx4 v[48:51], v[40:41], off
	v_mul_f32_e32 v40, 0xbfb8aa3b, v36
	v_exp_f32_e32 v40, v40
	v_mul_f32_e32 v33, v33, v65
	v_cvt_pk_bf16_f32 v32, v32, v32
	v_add_f32_e32 v40, 1.0, v40
	v_rcp_f32_e32 v40, v40
	v_add_u32_e32 v41, v52, v142
	ds_write_b16_d16_hi v41, v32
	v_mul_f32_e32 v41, v45, v65
	v_mul_f32_e32 v36, v36, v40
	v_mul_f32_e32 v40, 0xbfb8aa3b, v33
	v_exp_f32_e32 v40, v40
	v_mul_f32_e32 v36, v41, v36
	v_add_u32_e32 v32, 0x9100, v136
	v_add_f32_e32 v40, 1.0, v40
	v_rcp_f32_e32 v40, v40
	v_cvt_pk_bf16_f32 v36, v36, v36
	v_add_u32_e32 v41, v32, v143
	ds_write_b16_d16_hi v41, v36
	v_mul_f32_e32 v36, v37, v65
	v_mul_f32_e32 v33, v33, v40
	v_mul_f32_e32 v33, v36, v33
	v_mul_f32_e32 v36, v42, v66
	v_mul_f32_e32 v37, 0xbfb8aa3b, v36
	v_exp_f32_e32 v37, v37
	v_mul_f32_e32 v34, v34, v66
	v_cvt_pk_bf16_f32 v33, v33, v33
	v_add_f32_e32 v37, 1.0, v37
	v_rcp_f32_e32 v37, v37
	v_add_u32_e32 v32, v32, v142
	ds_write_b16_d16_hi v32, v33
	v_mul_f32_e32 v33, v46, v66
	v_mul_f32_e32 v36, v36, v37
	v_mul_f32_e32 v37, 0xbfb8aa3b, v34
	v_exp_f32_e32 v37, v37
	v_mul_f32_e32 v33, v33, v36
	v_cvt_pk_bf16_f32 v33, v33, v33
	v_add_f32_e32 v36, 1.0, v37
	v_rcp_f32_e32 v36, v36
	v_add_u32_e32 v32, 0x9200, v136
	v_add_u32_e32 v37, v32, v143
	ds_write_b16_d16_hi v37, v33
	v_mul_f32_e32 v33, v38, v66
	v_mul_f32_e32 v34, v34, v36
	v_mul_f32_e32 v33, v33, v34
	v_mul_f32_e32 v34, v43, v67
	v_mul_f32_e32 v36, 0xbfb8aa3b, v34
	v_exp_f32_e32 v36, v36
	v_cvt_pk_bf16_f32 v33, v33, v33
	v_add_u32_e32 v32, v32, v142
	v_add_f32_e32 v36, 1.0, v36
	v_rcp_f32_e32 v36, v36
	ds_write_b16_d16_hi v32, v33
	v_mul_f32_e32 v32, v47, v67
	v_add_u32_e32 v37, 0x9300, v136
	v_mul_f32_e32 v33, v34, v36
	v_mul_f32_e32 v34, v35, v67
	v_mul_f32_e32 v35, 0xbfb8aa3b, v34
	v_exp_f32_e32 v35, v35
	v_mul_f32_e32 v32, v32, v33
	v_cvt_pk_bf16_f32 v32, v32, v32
	v_add_f32_e32 v33, 1.0, v35
	v_rcp_f32_e32 v33, v33
	v_add_u32_e32 v35, v37, v143
	ds_write_b16_d16_hi v35, v32
	v_mul_f32_e32 v32, v39, v67
	v_mul_f32_e32 v33, v34, v33
	v_add_u32_e32 v38, 0xb0, v145
	v_mul_f32_e32 v36, v32, v33
	v_add_u32_e32 v32, s26, v38
	v_ashrrev_i32_e32 v33, 31, v32
	v_lshl_add_u64 v[32:33], v[32:33], 2, s[0:1]
	global_load_dwordx4 v[32:35], v[32:33], off
	s_waitcnt vmcnt(1)
; __device__ __forceinline__ u16 f2bf(float f) { unsigned u = __float_as_uint(f); u += 0x7fffu + ((u >> 16) & 1u); return (u16)(u >> 16); }
; __device__ __forceinline__ int opaque_tid() { int t; asm volatile("v_mov_b32 %0, %1" : "=v"(t) : "v"((int)threadIdx.x)); return t; }
; __device__ __forceinline__ float frcp(float x) { return __builtin_amdgcn_rcpf(x); }
; template <int EPI> ...
;     ...
;     for (int ai = 0; ai < 2; ++ai)
; #pragma unroll
;       for (int m = 0; m < 4; ++m)
; #pragma unroll
;         for (int j = 0; j < 4; ++j) {
;           const int r = ai * 128 + wr * 64 + m * 16 + fq * 4 + j;
;           float rs = 1.0f;
;           if (EPI != EPI_RES) rs = e.rstd[brow + r];
;           char* rowp = tb + r * RB + fr * 2;
;           if (EPI == EPI_GU) {
; #pragma unroll
;             for (int n = 0; n < 2; ++n) {
;               float g = acc[ai][0][m][n][j] * rs, u = acc[ai][1][m][n][j] * rs;
;               float h = g * frcp(1.0f + __expf(-g)) * u;
;               const int seg = (wc * 2 + n) ^ fq;
;               *(u16*)(rowp + seg * 32) = f2bf(h);
;             }
;           } else {
; #pragma unroll
;             for (int bj = 0; bj < 2; ++bj)
; #pragma unroll
;               for (int n = 0; n < 2; ++n) {
;                 const int seg = (bj * 8 + wc * 2 + n) ^ fq;
;                 *(u16*)(rowp + seg * 32) = f2bf(acc[ai][bj][m][n][j] * rs);
;               }
;           }
;         }
;     __syncthreads();
;     constexpr int CPR = RB / 16;
;     constexpr int RPI = 512 / CPR;
;     const int tid2 = opaque_tid();
;     const int cc = tid2 % CPR, r0 = tid2 / CPR;
;     u16* gp = (EPI == EPI_GU) ? e.out + ((size_t)((e.bcol >> 6) + (cc >> 3)) * 256 + r0) * 64 + (cc & 7) * 8
;                               : e.out + (size_t)r0 * e.ld + e.bcol + cc * 8;
;     const size_t gstep = (EPI == EPI_GU) ? (size_t)RPI * 64 : (size_t)RPI * e.ld;
	v_mul_f32_e32 v24, v24, v48
	v_mul_f32_e32 v39, 0xbfb8aa3b, v24
	v_exp_f32_e32 v39, v39
	v_bfe_u32 v40, v36, 16, 1
	v_add3_u32 v36, v36, v40, s51
	v_add_u32_e32 v37, v37, v142
	v_add_f32_e32 v39, 1.0, v39
	v_rcp_f32_e32 v39, v39
	v_mul_f32_e32 v16, v16, v48
	ds_write_b16_d16_hi v37, v36
	v_mul_f32_e32 v37, 0xbfb8aa3b, v16
	v_exp_f32_e32 v37, v37
	v_mul_f32_e32 v28, v28, v48
	v_mul_f32_e32 v24, v24, v39
	v_mul_f32_e32 v24, v28, v24
	v_cvt_pk_bf16_f32 v24, v24, v24
	v_add_f32_e32 v28, 1.0, v37
	v_rcp_f32_e32 v28, v28
	v_lshl_add_u32 v36, v44, 8, v144
	v_mul_f32_e32 v20, v20, v48
	v_add_u32_e32 v37, v36, v143
	v_mul_f32_e32 v16, v16, v28
	v_mul_f32_e32 v16, v20, v16
	v_mul_f32_e32 v20, v25, v49
	ds_write_b16_d16_hi v37, v24
	v_mul_f32_e32 v24, 0xbfb8aa3b, v20
	v_exp_f32_e32 v24, v24
	v_mul_f32_e32 v17, v17, v49
	v_cvt_pk_bf16_f32 v16, v16, v16
	v_add_f32_e32 v24, 1.0, v24
	v_rcp_f32_e32 v24, v24
	v_add_u32_e32 v25, v36, v142
	ds_write_b16_d16_hi v25, v16
	v_mul_f32_e32 v25, v29, v49
	v_mul_f32_e32 v20, v20, v24
	v_mul_f32_e32 v24, 0xbfb8aa3b, v17
	v_exp_f32_e32 v24, v24
	v_mul_f32_e32 v20, v25, v20
	v_add_u32_e32 v16, 0xa100, v136
	v_add_f32_e32 v24, 1.0, v24
	v_rcp_f32_e32 v24, v24
	v_cvt_pk_bf16_f32 v20, v20, v20
	v_add_u32_e32 v25, v16, v143
	ds_write_b16_d16_hi v25, v20
	v_mul_f32_e32 v20, v21, v49
	v_mul_f32_e32 v17, v17, v24
	v_mul_f32_e32 v17, v20, v17
	v_mul_f32_e32 v20, v26, v50
	v_mul_f32_e32 v21, 0xbfb8aa3b, v20
	v_exp_f32_e32 v21, v21
	v_mul_f32_e32 v18, v18, v50
	v_bfe_u32 v24, v17, 16, 1
	v_add3_u32 v17, v17, v24, s51
	v_add_f32_e32 v21, 1.0, v21
	v_rcp_f32_e32 v21, v21
	v_add_u32_e32 v16, v16, v142
	ds_write_b16_d16_hi v16, v17
	v_mul_f32_e32 v17, v30, v50
	v_mul_f32_e32 v20, v20, v21
	v_mul_f32_e32 v21, 0xbfb8aa3b, v18
	v_exp_f32_e32 v21, v21
	v_mul_f32_e32 v17, v17, v20
	v_cvt_pk_bf16_f32 v17, v17, v17
	v_add_f32_e32 v20, 1.0, v21
	v_rcp_f32_e32 v20, v20
	v_add_u32_e32 v16, 0xa200, v136
	v_add_u32_e32 v21, v16, v143
	ds_write_b16_d16_hi v21, v17
	v_mul_f32_e32 v17, v22, v50
	v_mul_f32_e32 v18, v18, v20
	v_mul_f32_e32 v17, v17, v18
	v_mul_f32_e32 v18, v27, v51
	v_mul_f32_e32 v20, 0xbfb8aa3b, v18
	v_exp_f32_e32 v20, v20
	v_mul_f32_e32 v19, v19, v51
	v_bfe_u32 v21, v17, 16, 1
	v_add3_u32 v17, v17, v21, s51
	v_add_f32_e32 v20, 1.0, v20
	v_rcp_f32_e32 v20, v20
	v_add_u32_e32 v16, v16, v142
	ds_write_b16_d16_hi v16, v17
	v_mul_f32_e32 v17, v31, v51
	v_mul_f32_e32 v18, v18, v20
	v_mul_f32_e32 v20, 0xbfb8aa3b, v19
	v_exp_f32_e32 v20, v20
	v_mul_f32_e32 v17, v17, v18
	v_cvt_pk_bf16_f32 v17, v17, v17
	v_add_f32_e32 v18, 1.0, v20
	v_rcp_f32_e32 v18, v18
	v_add_u32_e32 v16, 0xa300, v136
	v_add_u32_e32 v20, v16, v143
	ds_write_b16_d16_hi v20, v17
	v_mul_f32_e32 v17, v23, v51
	v_mul_f32_e32 v18, v19, v18
	s_waitcnt vmcnt(0)
	v_mul_f32_e32 v8, v8, v32
	v_mul_f32_e32 v17, v17, v18
	v_mul_f32_e32 v18, 0xbfb8aa3b, v8
	v_exp_f32_e32 v18, v18
	v_bfe_u32 v19, v17, 16, 1
	v_add3_u32 v17, v17, v19, s51
	v_add_u32_e32 v16, v16, v142
	v_add_f32_e32 v18, 1.0, v18
	v_rcp_f32_e32 v18, v18
	v_mul_f32_e32 v0, v0, v32
	ds_write_b16_d16_hi v16, v17
	v_mul_f32_e32 v17, 0xbfb8aa3b, v0
	v_exp_f32_e32 v17, v17
	v_mul_f32_e32 v12, v12, v32
	v_mul_f32_e32 v8, v8, v18
	v_mul_f32_e32 v8, v12, v8
	v_cvt_pk_bf16_f32 v8, v8, v8
	v_add_f32_e32 v12, 1.0, v17
	v_rcp_f32_e32 v12, v12
	v_lshl_add_u32 v16, v38, 8, v144
	v_mul_f32_e32 v4, v4, v32
	v_add_u32_e32 v17, v16, v143
	v_mul_f32_e32 v0, v0, v12
	v_mul_f32_e32 v0, v4, v0
	v_mul_f32_e32 v4, v9, v33
	ds_write_b16_d16_hi v17, v8
	v_mul_f32_e32 v8, 0xbfb8aa3b, v4
	v_exp_f32_e32 v8, v8
	v_mul_f32_e32 v1, v1, v33
	v_cvt_pk_bf16_f32 v0, v0, v0
	v_add_f32_e32 v8, 1.0, v8
	v_rcp_f32_e32 v8, v8
	v_add_u32_e32 v9, v16, v142
	ds_write_b16_d16_hi v9, v0
	v_mul_f32_e32 v9, v13, v33
	v_mul_f32_e32 v4, v4, v8
	v_mul_f32_e32 v8, 0xbfb8aa3b, v1
	v_exp_f32_e32 v8, v8
	v_mul_f32_e32 v4, v9, v4
	v_add_u32_e32 v0, 0xb100, v136
	v_add_f32_e32 v8, 1.0, v8
	v_rcp_f32_e32 v8, v8
	v_cvt_pk_bf16_f32 v4, v4, v4
	v_add_u32_e32 v9, v0, v143
	ds_write_b16_d16_hi v9, v4
	v_mul_f32_e32 v4, v5, v33
	v_mul_f32_e32 v1, v1, v8
	v_mul_f32_e32 v1, v4, v1
	v_mul_f32_e32 v4, v10, v34
	v_mul_f32_e32 v5, 0xbfb8aa3b, v4
	v_exp_f32_e32 v5, v5
	v_mul_f32_e32 v2, v2, v34
	v_bfe_u32 v8, v1, 16, 1
	v_add3_u32 v1, v1, v8, s51
	v_add_f32_e32 v5, 1.0, v5
	v_rcp_f32_e32 v5, v5
	v_add_u32_e32 v0, v0, v142
	ds_write_b16_d16_hi v0, v1
	v_mul_f32_e32 v1, v14, v34
	v_mul_f32_e32 v4, v4, v5
	v_mul_f32_e32 v5, 0xbfb8aa3b, v2
	v_exp_f32_e32 v5, v5
	v_mul_f32_e32 v1, v1, v4
	v_cvt_pk_bf16_f32 v1, v1, v1
	v_add_f32_e32 v4, 1.0, v5
	v_rcp_f32_e32 v4, v4
	v_add_u32_e32 v0, 0xb200, v136
	v_add_u32_e32 v5, v0, v143
	ds_write_b16_d16_hi v5, v1
	v_mul_f32_e32 v1, v6, v34
	v_mul_f32_e32 v2, v2, v4
	v_mul_f32_e32 v1, v1, v2
	v_mul_f32_e32 v2, v11, v35
	v_mul_f32_e32 v4, 0xbfb8aa3b, v2
	v_exp_f32_e32 v4, v4
	v_mul_f32_e32 v3, v3, v35
	v_bfe_u32 v5, v1, 16, 1
	v_add3_u32 v1, v1, v5, s51
	v_add_f32_e32 v4, 1.0, v4
	v_rcp_f32_e32 v4, v4
	v_add_u32_e32 v0, v0, v142
	ds_write_b16_d16_hi v0, v1
	v_mul_f32_e32 v1, v15, v35
	v_mul_f32_e32 v2, v2, v4
	v_mul_f32_e32 v4, 0xbfb8aa3b, v3
	v_exp_f32_e32 v4, v4
	v_mul_f32_e32 v1, v1, v2
	v_cvt_pk_bf16_f32 v1, v1, v1
	v_add_f32_e32 v2, 1.0, v4
	v_rcp_f32_e32 v2, v2
	v_add_u32_e32 v0, 0xb300, v136
	v_add_u32_e32 v4, v0, v143
	ds_write_b16_d16_hi v4, v1
	v_mul_f32_e32 v1, v7, v35
	v_mul_f32_e32 v2, v3, v2
	v_mul_f32_e32 v1, v1, v2
	v_cvt_pk_bf16_f32 v1, v1, v1
	v_add_u32_e32 v0, v0, v142
	ds_write_b16_d16_hi v0, v1
	s_waitcnt lgkmcnt(0)
	s_barrier
	v_mov_b32 v0, v146
	s_nop 0
	v_ashrrev_i32_e32 v1, 31, v0
	v_lshrrev_b32_e32 v1, 28, v1
	v_add_u32_e32 v1, v0, v1
	v_ashrrev_i32_e32 v2, 4, v1
	v_and_b32_e32 v1, -16, v1
	v_sub_u32_e32 v6, v0, v1
	v_ashrrev_i32_e32 v0, 3, v6
	v_lshl_add_u32 v0, s24, 1, v0
	v_ashrrev_i32_e32 v3, 31, v2
	v_ashrrev_i32_e32 v1, 31, v0
	v_lshlrev_b64 v[4:5], 7, v[2:3]
	v_lshlrev_b32_e32 v3, 4, v6
	v_lshlrev_b64 v[0:1], 15, v[0:1]
	v_and_b32_e32 v136, 0x70, v3
	v_lshrrev_b32_e32 v3, 1, v2
	v_lshl_add_u64 v[0:1], s[28:29], 0, v[0:1]
	v_bitop3_b32 v3, v3, v6, 6 bitop3:0x6c
	v_lshl_add_u64 v[0:1], v[0:1], 0, v[4:5]
	v_lshlrev_b32_e32 v2, 8, v2
	v_lshlrev_b32_e32 v3, 4, v3
	v_lshl_add_u64 v[0:1], v[0:1], 0, v[136:137]
	v_add3_u32 v2, 0, v2, v3
	s_mov_b32 s24, 0

; __device__ __forceinline__ int opaque_tid() { int t; asm volatile("v_mov_b32 %0, %1" : "=v"(t) : "v"((int)threadIdx.x)); return t; }
; #define STAGE(P, BASE, kt) do { const char* _g = (const char*)(BASE) + (size_t)((kt) * (BK * 2)); \
;     __builtin_amdgcn_global_load_lds((const unsigned*)(_g + (size_t)goff0), (unsigned*)((char*)(P) + tid_ * 16), 16, 0, 0); \
;     __builtin_amdgcn_global_load_lds((const unsigned*)(_g + (size_t)goff1), (unsigned*)((char*)(P) + tid_ * 16 + 8192), 16, 0, 0); } while (0)
; #define STAGEA(P, BASE, kt) do { const char* _g = (const char*)(BASE) + (size_t)((kt) * a_kbytes); \
;     __builtin_amdgcn_global_load_lds((const unsigned*)(_g + (size_t)goffA0), (unsigned*)((char*)(P) + tid_ * 16), 16, 0, 0); \
;     __builtin_amdgcn_global_load_lds((const unsigned*)(_g + (size_t)goffA1), (unsigned*)((char*)(P) + tid_ * 16 + 8192), 16, 0, 0); } while (0)
; #define LDA(dst, b, h) for (int m = 0; m < 4; ++m) for (int k = 0; k < 2; ++k) \
;     dst[m][k] = *reinterpret_cast<const bf16x8*>((char*)SA(b, h) + lds_byte(wr * 64 + m * 16 + fr, k * 32 + fq * 8))
; #define LDB(dst, b, h) for (int n = 0; n < 2; ++n) for (int k = 0; k < 2; ++k) \
;     dst[n][k] = *reinterpret_cast<const bf16x8*>((char*)SB(b, h) + lds_byte(wc * 32 + n * 16 + fr, k * 32 + fq * 8))
; #define MMA(ai, bj, At, Bt) do { __builtin_amdgcn_s_setprio(1); \
;     for (int m = 0; m < 4; ++m) for (int n = 0; n < 2; ++n) for (int k = 0; k < 2; ++k) \
;       acc[ai][bj][m][n] = __builtin_amdgcn_mfma_f32_16x16x32_bf16(At[m][k], Bt[n][k], acc[ai][bj][m][n], 0, 0, 0); \
;     __builtin_amdgcn_s_setprio(0); } while (0)
; #define WAIT_V(n) asm volatile("s_waitcnt vmcnt(" #n ")" ::: "memory")
; template <int EPI> ...
;     ...
;   const int tid_ = opaque_tid();
;   const int wid = tid_ >> 6, lane = tid_ & 63, wr = wid >> 2, wc = wid & 3, fr = lane & 15, fq = lane >> 4;
;   f32x4 acc[2][2][4][2] = {};
;   bf16x8 At[4][2], B0[2][2], B1[2][2];
;   const int nt = K / BK;
;   STAGE(SB(0, 0), B0p, 0); STAGEA(SA(0, 0), A0, 0);
;   STAGE(SB(0, 1), B1p, 0); STAGEA(SA(0, 1), A1, 0);
;   if (wr == 1) BAR;
;   WAIT_V(4); BAR;
;   STAGE(SB(1, 0), B0p, 1); STAGEA(SA(1, 0), A0, 1); STAGE(SB(1, 1), B1p, 1);
;   WAIT_V(6); BAR;
;   for (int t = 0; t < nt - 2; t += 2) {
;     LDB(B0, 0, 0); SCHED; LDA(At, 0, 0); STAGEA(SA(1, 1), A1, t + 1);
;     WAIT_L(8); BAR; WAIT_L(0); MMA(0, 0, At, B0); BAR; SCHED;
.LBB0_1737:
	s_or_b64 exec, exec, s[26:27]
	v_add_u32_e32 v164, s40, v4
	v_add_u32_e32 v165, 0x2000, v164
	v_readfirstlane_b32 s26, v164
	v_lshl_add_u64 v[0:1], v[0:1], 0, s[0:1]
	s_mov_b32 m0, s26
	v_readfirstlane_b32 s26, v165
	s_waitcnt vmcnt(4)
	s_barrier
	global_load_lds_dwordx4 v[0:1], off
	s_mov_b32 m0, s26
	s_add_u32 s26, s22, 0x8000
	v_add_u32_e32 v166, 0x8000, v158
	v_lshl_add_u64 v[0:1], v[2:3], 0, s[0:1]
	s_addc_u32 s27, s23, 0
	v_readfirstlane_b32 s52, v166
	global_load_lds_dwordx4 v[0:1], off
	v_lshl_add_u64 v[0:1], s[26:27], 0, v[130:131]
	s_mov_b32 m0, s52
	v_add_u32_e32 v168, 0xa000, v158
	global_load_lds_dwordx4 v[0:1], off
	v_lshl_add_u64 v[0:1], s[26:27], 0, v[128:129]
	v_readfirstlane_b32 s26, v168
	s_add_u32 s24, s24, 0x160080
	v_add_u32_e32 v169, s41, v4
	s_mov_b32 m0, s26
	s_addc_u32 s25, s25, 0
	v_readfirstlane_b32 s26, v169
	global_load_lds_dwordx4 v[0:1], off
	v_lshl_add_u64 v[0:1], s[24:25], 0, v[134:135]
	s_mov_b32 m0, s26
	v_add_u32_e32 v170, 0x2000, v169
	global_load_lds_dwordx4 v[0:1], off
	v_lshl_add_u64 v[0:1], s[24:25], 0, v[132:133]
	v_readfirstlane_b32 s24, v170
	s_mov_b32 m0, s24
	v_and_b32_e32 v149, 15, v144
	global_load_lds_dwordx4 v[0:1], off
	v_bfe_u32 v145, v144, 4, 2
	v_lshlrev_b32_e32 v3, 2, v144
	v_lshlrev_b32_e32 v0, 4, v145
	v_lshlrev_b32_e32 v2, 6, v149
	v_and_b32_e32 v3, 32, v3
	v_lshlrev_b32_e32 v9, 6, v144
	v_bfe_u32 v148, v144, 6, 2
	s_waitcnt vmcnt(6)
	v_bitop3_b32 v2, v0, v3, v2 bitop3:0x36
	v_lshlrev_b32_e32 v8, 13, v147
	v_and_or_b32 v0, v9, s42, v0
	v_lshlrev_b32_e32 v1, 12, v148
	v_add_u32_e32 v4, s38, v2
	v_add_u32_e32 v5, s39, v2
	v_add_u32_e32 v6, s40, v2
	v_add_u32_e32 v7, s41, v2
	v_add_u32_e32 v2, 0, v2
	v_xad_u32 v3, v0, v3, 0
	v_or_b32_e32 v9, 0x800, v8
	v_or_b32_e32 v10, 0x1000, v8
	v_or_b32_e32 v11, 0x1800, v8
	s_add_u32 s24, s74, s51
	v_mov_b32_e32 v0, 0
	s_addc_u32 s25, s75, s50
	s_mov_b32 s50, -2
	v_add_u32_e32 v171, v4, v1
	v_add_u32_e32 v153, v2, v8
	v_add_u32_e32 v152, v3, v9
	v_add_u32_e32 v151, v3, v10
	v_add_u32_e32 v150, v3, v11
	v_add_u32_e32 v167, v5, v1
	v_add_u32_e32 v156, v6, v1
	v_add_u32_e32 v154, v7, v1
	s_mov_b64 s[26:27], s[22:23]
	v_mov_b32_e32 v1, v0
	v_mov_b32_e32 v2, v0
	v_mov_b32_e32 v3, v0
	v_mov_b32_e32 v4, v0
	v_mov_b32_e32 v5, v0
	v_mov_b32_e32 v6, v0
	v_mov_b32_e32 v7, v0
	v_mov_b32_e32 v8, v0
	v_mov_b32_e32 v9, v0
	v_mov_b32_e32 v10, v0
	v_mov_b32_e32 v11, v0
	v_mov_b32_e32 v12, v0
	v_mov_b32_e32 v13, v0
	v_mov_b32_e32 v14, v0
	v_mov_b32_e32 v15, v0
	v_mov_b32_e32 v16, v0
	v_mov_b32_e32 v17, v0
	v_mov_b32_e32 v18, v0
	v_mov_b32_e32 v19, v0
	v_mov_b32_e32 v20, v0
	v_mov_b32_e32 v21, v0
	v_mov_b32_e32 v22, v0
	v_mov_b32_e32 v23, v0
	v_mov_b32_e32 v24, v0
	v_mov_b32_e32 v25, v0
	v_mov_b32_e32 v26, v0
	v_mov_b32_e32 v27, v0
	v_mov_b32_e32 v28, v0
	v_mov_b32_e32 v29, v0
	v_mov_b32_e32 v30, v0
	v_mov_b32_e32 v31, v0
	v_mov_b32_e32 v32, v0
	v_mov_b32_e32 v33, v0
	v_mov_b32_e32 v34, v0
	v_mov_b32_e32 v35, v0
	v_mov_b32_e32 v36, v0
	v_mov_b32_e32 v37, v0
	v_mov_b32_e32 v38, v0
	v_mov_b32_e32 v39, v0
	v_mov_b32_e32 v40, v0
	v_mov_b32_e32 v41, v0
	v_mov_b32_e32 v42, v0
	v_mov_b32_e32 v43, v0
	v_mov_b32_e32 v44, v0
	v_mov_b32_e32 v45, v0
	v_mov_b32_e32 v46, v0
	v_mov_b32_e32 v47, v0
	v_mov_b32_e32 v48, v0
	v_mov_b32_e32 v49, v0
	v_mov_b32_e32 v50, v0
	v_mov_b32_e32 v51, v0
	v_mov_b32_e32 v52, v0
	v_mov_b32_e32 v53, v0
	v_mov_b32_e32 v54, v0
	v_mov_b32_e32 v55, v0
	v_mov_b32_e32 v56, v0
	v_mov_b32_e32 v57, v0
	v_mov_b32_e32 v58, v0
	v_mov_b32_e32 v59, v0
	v_mov_b32_e32 v60, v0
	v_mov_b32_e32 v61, v0
	v_mov_b32_e32 v62, v0
	v_mov_b32_e32 v63, v0
	v_mov_b32_e32 v64, v0
	v_mov_b32_e32 v65, v0
	v_mov_b32_e32 v66, v0
	v_mov_b32_e32 v67, v0
	v_mov_b32_e32 v68, v0
	v_mov_b32_e32 v69, v0
	v_mov_b32_e32 v70, v0
	v_mov_b32_e32 v71, v0
	v_mov_b32_e32 v72, v0
	v_mov_b32_e32 v73, v0
	v_mov_b32_e32 v74, v0
	v_mov_b32_e32 v75, v0
	v_mov_b32_e32 v76, v0
	v_mov_b32_e32 v77, v0
	v_mov_b32_e32 v78, v0
	v_mov_b32_e32 v79, v0
	v_mov_b32_e32 v80, v0
	v_mov_b32_e32 v81, v0
	v_mov_b32_e32 v82, v0
	v_mov_b32_e32 v83, v0
	v_mov_b32_e32 v84, v0
	v_mov_b32_e32 v85, v0
	v_mov_b32_e32 v86, v0
	v_mov_b32_e32 v87, v0
	v_mov_b32_e32 v88, v0
	v_mov_b32_e32 v89, v0
	v_mov_b32_e32 v90, v0
	v_mov_b32_e32 v91, v0
	v_mov_b32_e32 v92, v0
	v_mov_b32_e32 v93, v0
	v_mov_b32_e32 v94, v0
	v_mov_b32_e32 v95, v0
	v_mov_b32_e32 v96, v0
	v_mov_b32_e32 v97, v0
	v_mov_b32_e32 v98, v0
	v_mov_b32_e32 v99, v0
	v_mov_b32_e32 v100, v0
	v_mov_b32_e32 v101, v0
	v_mov_b32_e32 v102, v0
	v_mov_b32_e32 v103, v0
	v_mov_b32_e32 v104, v0
	v_mov_b32_e32 v105, v0
	v_mov_b32_e32 v106, v0
	v_mov_b32_e32 v107, v0
	v_mov_b32_e32 v108, v0
	v_mov_b32_e32 v109, v0
	v_mov_b32_e32 v110, v0
	v_mov_b32_e32 v111, v0
	v_mov_b32_e32 v112, v0
	v_mov_b32_e32 v113, v0
	v_mov_b32_e32 v114, v0
	v_mov_b32_e32 v115, v0
	v_mov_b32_e32 v116, v0
	v_mov_b32_e32 v117, v0
	v_mov_b32_e32 v118, v0
	v_mov_b32_e32 v119, v0
	v_mov_b32_e32 v120, v0
	v_mov_b32_e32 v121, v0
	v_mov_b32_e32 v122, v0
	v_mov_b32_e32 v123, v0
	v_mov_b32_e32 v124, v0
	v_mov_b32_e32 v125, v0
	v_mov_b32_e32 v126, v0
	v_mov_b32_e32 v127, v0
	s_barrier
	ds_read_b128 v[174:177], v171
	ds_read_b128 v[178:181], v171 offset:1024
	ds_read_b128 v[182:185], v171 offset:2048
	ds_read_b128 v[186:189], v171 offset:3072
; #define STAGE(P, BASE, kt) do { const char* _g = (const char*)(BASE) + (size_t)((kt) * (BK * 2)); \
;     __builtin_amdgcn_global_load_lds((const unsigned*)(_g + (size_t)goff0), (unsigned*)((char*)(P) + tid_ * 16), 16, 0, 0); \
;     __builtin_amdgcn_global_load_lds((const unsigned*)(_g + (size_t)goff1), (unsigned*)((char*)(P) + tid_ * 16 + 8192), 16, 0, 0); } while (0)
; #define STAGEA(P, BASE, kt) do { const char* _g = (const char*)(BASE) + (size_t)((kt) * a_kbytes); \
;     __builtin_amdgcn_global_load_lds((const unsigned*)(_g + (size_t)goffA0), (unsigned*)((char*)(P) + tid_ * 16), 16, 0, 0); \
;     __builtin_amdgcn_global_load_lds((const unsigned*)(_g + (size_t)goffA1), (unsigned*)((char*)(P) + tid_ * 16 + 8192), 16, 0, 0); } while (0)
; #define LDA(dst, b, h) for (int m = 0; m < 4; ++m) for (int k = 0; k < 2; ++k) \
;     dst[m][k] = *reinterpret_cast<const bf16x8*>((char*)SA(b, h) + lds_byte(wr * 64 + m * 16 + fr, k * 32 + fq * 8))
; #define LDB(dst, b, h) for (int n = 0; n < 2; ++n) for (int k = 0; k < 2; ++k) \
;     dst[n][k] = *reinterpret_cast<const bf16x8*>((char*)SB(b, h) + lds_byte(wc * 32 + n * 16 + fr, k * 32 + fq * 8))
; #define MMA(ai, bj, At, Bt) do { __builtin_amdgcn_s_setprio(1); \
;     for (int m = 0; m < 4; ++m) for (int n = 0; n < 2; ++n) for (int k = 0; k < 2; ++k) \
;       acc[ai][bj][m][n] = __builtin_amdgcn_mfma_f32_16x16x32_bf16(At[m][k], Bt[n][k], acc[ai][bj][m][n], 0, 0, 0); \
;     __builtin_amdgcn_s_setprio(0); } while (0)
; #define WAIT_V(n) asm volatile("s_waitcnt vmcnt(" #n ")" ::: "memory")
; #define WAIT_L(n) asm volatile("s_waitcnt lgkmcnt(" #n ")" ::: "memory")
; #define BAR __builtin_amdgcn_s_barrier()
; #define SCHED __builtin_amdgcn_sched_barrier(0)
; template <int EPI> ...
;     ...
;     LDB(B0, 0, 0); SCHED; LDA(At, 0, 0); STAGEA(SA(1, 1), A1, t + 1);
;     WAIT_L(8); BAR; WAIT_L(0); MMA(0, 0, At, B0); BAR; SCHED;
;     LDB(B1, 0, 1); STAGE(SB(0, 0), B0p, t + 2);
;     BAR; WAIT_L(0); MMA(0, 1, At, B1); BAR;
;     LDA(At, 0, 1); STAGEA(SA(0, 0), A0, t + 2);
;     BAR; WAIT_L(0); MMA(1, 0, At, B0); BAR; SCHED;
;     STAGE(SB(0, 1), B1p, t + 2);
;     WAIT_V(6); BAR; MMA(1, 1, At, B1); BAR;
;     LDB(B0, 1, 0); SCHED; LDA(At, 1, 0); STAGEA(SA(0, 1), A1, t + 2);
;     WAIT_L(8); BAR; WAIT_L(0); MMA(0, 0, At, B0); BAR; SCHED;
.LBB0_1738:
	v_add_u32_e32 v172, 0xc000, v158
	v_lshl_add_u64 v[238:239], s[26:27], 0, v[136:137]
	v_readfirstlane_b32 s51, v172
	v_add_u32_e32 v173, 0xe000, v158
	v_lshl_add_u64 v[222:223], v[238:239], 0, s[4:5]
	s_mov_b32 m0, s51
	v_lshl_add_u64 v[240:241], s[26:27], 0, v[138:139]
	v_readfirstlane_b32 s51, v173
	ds_read_b128 v[190:193], v153
	ds_read_b128 v[194:197], v153 offset:1024
	ds_read_b128 v[198:201], v152
	ds_read_b128 v[202:205], v152 offset:1024
	ds_read_b128 v[206:209], v151
	ds_read_b128 v[210:213], v151 offset:1024
	ds_read_b128 v[214:217], v150
	ds_read_b128 v[218:221], v150 offset:1024
	global_load_lds_dwordx4 v[222:223], off
	v_lshl_add_u64 v[222:223], v[240:241], 0, s[4:5]
	s_mov_b32 m0, s51
	s_nop 0
	global_load_lds_dwordx4 v[222:223], off
	s_waitcnt lgkmcnt(8)
	s_setprio 1
	s_barrier
	s_waitcnt lgkmcnt(0)
	v_mfma_f32_16x16x32_bf16 v[124:127], v[190:193], v[174:177], v[124:127]
	v_mfma_f32_16x16x32_bf16 v[120:123], v[190:193], v[182:185], v[120:123]
	v_mfma_f32_16x16x32_bf16 v[116:119], v[198:201], v[174:177], v[116:119]
	v_mfma_f32_16x16x32_bf16 v[112:115], v[198:201], v[182:185], v[112:115]
	v_mfma_f32_16x16x32_bf16 v[108:111], v[206:209], v[174:177], v[108:111]
	v_mfma_f32_16x16x32_bf16 v[104:107], v[206:209], v[182:185], v[104:107]
	v_mfma_f32_16x16x32_bf16 v[100:103], v[214:217], v[174:177], v[100:103]
	v_mfma_f32_16x16x32_bf16 v[96:99], v[214:217], v[182:185], v[96:99]
	v_mfma_f32_16x16x32_bf16 v[124:127], v[194:197], v[178:181], v[124:127]
	v_mfma_f32_16x16x32_bf16 v[120:123], v[194:197], v[186:189], v[120:123]
	v_mfma_f32_16x16x32_bf16 v[116:119], v[202:205], v[178:181], v[116:119]
	v_mfma_f32_16x16x32_bf16 v[112:115], v[202:205], v[186:189], v[112:115]
	v_mfma_f32_16x16x32_bf16 v[108:111], v[210:213], v[178:181], v[108:111]
	v_mfma_f32_16x16x32_bf16 v[104:107], v[210:213], v[186:189], v[104:107]
	v_mfma_f32_16x16x32_bf16 v[100:103], v[218:221], v[178:181], v[100:103]
	v_mfma_f32_16x16x32_bf16 v[96:99], v[218:221], v[186:189], v[96:99]
	s_barrier
	s_setprio 0
	v_lshl_add_u64 v[242:243], s[24:25], 0, v[140:141]
	v_readfirstlane_b32 s51, v155
	v_lshl_add_u64 v[244:245], v[242:243], 0, s[6:7]
	s_mov_b32 m0, s51
	ds_read_b128 v[222:225], v167
	ds_read_b128 v[226:229], v167 offset:1024
	ds_read_b128 v[230:233], v167 offset:2048
	ds_read_b128 v[234:237], v167 offset:3072
	global_load_lds_dwordx4 v[244:245], off
	v_lshl_add_u64 v[244:245], s[24:25], 0, v[142:143]
	v_readfirstlane_b32 s51, v157
	v_lshl_add_u64 v[246:247], v[244:245], 0, s[6:7]
	s_mov_b32 m0, s51
	s_nop 0
	global_load_lds_dwordx4 v[246:247], off
	s_setprio 1
	s_barrier
	s_waitcnt lgkmcnt(0)
	v_mfma_f32_16x16x32_bf16 v[92:95], v[190:193], v[222:225], v[92:95]
	v_mfma_f32_16x16x32_bf16 v[88:91], v[190:193], v[230:233], v[88:91]
	v_mfma_f32_16x16x32_bf16 v[84:87], v[198:201], v[222:225], v[84:87]
	v_mfma_f32_16x16x32_bf16 v[80:83], v[198:201], v[230:233], v[80:83]
	v_mfma_f32_16x16x32_bf16 v[76:79], v[206:209], v[222:225], v[76:79]
	v_mfma_f32_16x16x32_bf16 v[72:75], v[206:209], v[230:233], v[72:75]
	v_mfma_f32_16x16x32_bf16 v[68:71], v[214:217], v[222:225], v[68:71]
	v_mfma_f32_16x16x32_bf16 v[64:67], v[214:217], v[230:233], v[64:67]
	v_mfma_f32_16x16x32_bf16 v[92:95], v[194:197], v[226:229], v[92:95]
	v_mfma_f32_16x16x32_bf16 v[88:91], v[194:197], v[234:237], v[88:91]
	v_mfma_f32_16x16x32_bf16 v[84:87], v[202:205], v[226:229], v[84:87]
	v_mfma_f32_16x16x32_bf16 v[80:83], v[202:205], v[234:237], v[80:83]
	v_mfma_f32_16x16x32_bf16 v[76:79], v[210:213], v[226:229], v[76:79]
	v_mfma_f32_16x16x32_bf16 v[72:75], v[210:213], v[234:237], v[72:75]
	v_mfma_f32_16x16x32_bf16 v[68:71], v[218:221], v[226:229], v[68:71]
	v_mfma_f32_16x16x32_bf16 v[64:67], v[218:221], v[234:237], v[64:67]
	s_barrier
	s_setprio 0
	v_readfirstlane_b32 s51, v158
	v_lshl_add_u64 v[246:247], v[238:239], 0, s[8:9]
	s_mov_b32 m0, s51
	v_readfirstlane_b32 s51, v159
	ds_read_b128 v[190:193], v153 offset:16384
	ds_read_b128 v[194:197], v153 offset:17408
	ds_read_b128 v[198:201], v152 offset:16384
	ds_read_b128 v[202:205], v152 offset:17408
	ds_read_b128 v[206:209], v151 offset:16384
	ds_read_b128 v[210:213], v151 offset:17408
	ds_read_b128 v[214:217], v150 offset:16384
	ds_read_b128 v[218:221], v150 offset:17408
	global_load_lds_dwordx4 v[246:247], off
	v_lshl_add_u64 v[246:247], v[240:241], 0, s[8:9]
	s_mov_b32 m0, s51
	s_nop 0
	global_load_lds_dwordx4 v[246:247], off
	s_setprio 1
	s_barrier
	s_waitcnt lgkmcnt(0)
	v_mfma_f32_16x16x32_bf16 v[60:63], v[190:193], v[174:177], v[60:63]
	v_mfma_f32_16x16x32_bf16 v[56:59], v[190:193], v[182:185], v[56:59]
	v_mfma_f32_16x16x32_bf16 v[52:55], v[198:201], v[174:177], v[52:55]
	v_mfma_f32_16x16x32_bf16 v[48:51], v[198:201], v[182:185], v[48:51]
	v_mfma_f32_16x16x32_bf16 v[44:47], v[206:209], v[174:177], v[44:47]
	v_mfma_f32_16x16x32_bf16 v[40:43], v[206:209], v[182:185], v[40:43]
	v_mfma_f32_16x16x32_bf16 v[36:39], v[214:217], v[174:177], v[36:39]
	v_mfma_f32_16x16x32_bf16 v[32:35], v[214:217], v[182:185], v[32:35]
	v_mfma_f32_16x16x32_bf16 v[60:63], v[194:197], v[178:181], v[60:63]
	v_mfma_f32_16x16x32_bf16 v[56:59], v[194:197], v[186:189], v[56:59]
	v_mfma_f32_16x16x32_bf16 v[52:55], v[202:205], v[178:181], v[52:55]
	v_mfma_f32_16x16x32_bf16 v[48:51], v[202:205], v[186:189], v[48:51]
	v_mfma_f32_16x16x32_bf16 v[44:47], v[210:213], v[178:181], v[44:47]
	v_mfma_f32_16x16x32_bf16 v[40:43], v[210:213], v[186:189], v[40:43]
	v_mfma_f32_16x16x32_bf16 v[36:39], v[218:221], v[178:181], v[36:39]
	v_mfma_f32_16x16x32_bf16 v[32:35], v[218:221], v[186:189], v[32:35]
	s_barrier
; #define STAGE(P, BASE, kt) do { const char* _g = (const char*)(BASE) + (size_t)((kt) * (BK * 2)); \
;     __builtin_amdgcn_global_load_lds((const unsigned*)(_g + (size_t)goff0), (unsigned*)((char*)(P) + tid_ * 16), 16, 0, 0); \
;     __builtin_amdgcn_global_load_lds((const unsigned*)(_g + (size_t)goff1), (unsigned*)((char*)(P) + tid_ * 16 + 8192), 16, 0, 0); } while (0)
; #define STAGEA(P, BASE, kt) do { const char* _g = (const char*)(BASE) + (size_t)((kt) * a_kbytes); \
;     __builtin_amdgcn_global_load_lds((const unsigned*)(_g + (size_t)goffA0), (unsigned*)((char*)(P) + tid_ * 16), 16, 0, 0); \
;     __builtin_amdgcn_global_load_lds((const unsigned*)(_g + (size_t)goffA1), (unsigned*)((char*)(P) + tid_ * 16 + 8192), 16, 0, 0); } while (0)
; #define LDA(dst, b, h) for (int m = 0; m < 4; ++m) for (int k = 0; k < 2; ++k) \
;     dst[m][k] = *reinterpret_cast<const bf16x8*>((char*)SA(b, h) + lds_byte(wr * 64 + m * 16 + fr, k * 32 + fq * 8))
; #define LDB(dst, b, h) for (int n = 0; n < 2; ++n) for (int k = 0; k < 2; ++k) \
;     dst[n][k] = *reinterpret_cast<const bf16x8*>((char*)SB(b, h) + lds_byte(wc * 32 + n * 16 + fr, k * 32 + fq * 8))
; #define MMA(ai, bj, At, Bt) do { __builtin_amdgcn_s_setprio(1); \
;     for (int m = 0; m < 4; ++m) for (int n = 0; n < 2; ++n) for (int k = 0; k < 2; ++k) \
;       acc[ai][bj][m][n] = __builtin_amdgcn_mfma_f32_16x16x32_bf16(At[m][k], Bt[n][k], acc[ai][bj][m][n], 0, 0, 0); \
;     __builtin_amdgcn_s_setprio(0); } while (0)
; #define WAIT_V(n) asm volatile("s_waitcnt vmcnt(" #n ")" ::: "memory")
; #define WAIT_L(n) asm volatile("s_waitcnt lgkmcnt(" #n ")" ::: "memory")
; #define BAR __builtin_amdgcn_s_barrier()
; #define SCHED __builtin_amdgcn_sched_barrier(0)
; template <int EPI> ...
;     ...
;     STAGE(SB(0, 1), B1p, t + 2);
;     WAIT_V(6); BAR; MMA(1, 1, At, B1); BAR;
;     LDB(B0, 1, 0); SCHED; LDA(At, 1, 0); STAGEA(SA(0, 1), A1, t + 2);
;     WAIT_L(8); BAR; WAIT_L(0); MMA(0, 0, At, B0); BAR; SCHED;
;     LDB(B1, 1, 1); STAGE(SB(1, 0), B0p, t + 3);
;     BAR; WAIT_L(0); MMA(0, 1, At, B1); BAR;
;     LDA(At, 1, 1); STAGEA(SA(1, 0), A0, t + 3);
;     BAR; WAIT_L(0); MMA(1, 0, At, B0); BAR; SCHED;
;     STAGE(SB(1, 1), B1p, t + 3);
;     WAIT_V(6); BAR; MMA(1, 1, At, B1); BAR;
	s_setprio 0
	v_readfirstlane_b32 s51, v160
	v_lshl_add_u64 v[174:175], v[242:243], 0, s[10:11]
	s_mov_b32 m0, s51
	v_readfirstlane_b32 s51, v161
	global_load_lds_dwordx4 v[174:175], off
	v_lshl_add_u64 v[174:175], v[244:245], 0, s[10:11]
	s_mov_b32 m0, s51
	s_nop 0
	global_load_lds_dwordx4 v[174:175], off
	s_waitcnt vmcnt(6)
	s_setprio 1
	s_barrier
	v_mfma_f32_16x16x32_bf16 v[28:31], v[190:193], v[222:225], v[28:31]
	v_mfma_f32_16x16x32_bf16 v[24:27], v[190:193], v[230:233], v[24:27]
	v_mfma_f32_16x16x32_bf16 v[20:23], v[198:201], v[222:225], v[20:23]
	v_mfma_f32_16x16x32_bf16 v[16:19], v[198:201], v[230:233], v[16:19]
	ds_read_b128 v[174:177], v156
	v_mfma_f32_16x16x32_bf16 v[12:15], v[206:209], v[222:225], v[12:15]
	v_mfma_f32_16x16x32_bf16 v[8:11], v[206:209], v[230:233], v[8:11]
	ds_read_b128 v[178:181], v156 offset:1024
	v_mfma_f32_16x16x32_bf16 v[4:7], v[214:217], v[222:225], v[4:7]
	v_mfma_f32_16x16x32_bf16 v[0:3], v[214:217], v[230:233], v[0:3]
	ds_read_b128 v[182:185], v156 offset:2048
	v_mfma_f32_16x16x32_bf16 v[28:31], v[194:197], v[226:229], v[28:31]
	v_mfma_f32_16x16x32_bf16 v[24:27], v[194:197], v[234:237], v[24:27]
	ds_read_b128 v[186:189], v156 offset:3072
	v_mfma_f32_16x16x32_bf16 v[20:23], v[202:205], v[226:229], v[20:23]
	v_mfma_f32_16x16x32_bf16 v[16:19], v[202:205], v[234:237], v[16:19]
	v_mfma_f32_16x16x32_bf16 v[12:15], v[210:213], v[226:229], v[12:15]
	v_mfma_f32_16x16x32_bf16 v[8:11], v[210:213], v[234:237], v[8:11]
	v_mfma_f32_16x16x32_bf16 v[4:7], v[218:221], v[226:229], v[4:7]
	v_mfma_f32_16x16x32_bf16 v[0:3], v[218:221], v[234:237], v[0:3]
	s_barrier
	s_setprio 0
	v_readfirstlane_b32 s51, v162
	v_lshl_add_u64 v[222:223], v[238:239], 0, s[12:13]
	s_mov_b32 m0, s51
	v_readfirstlane_b32 s51, v163
	ds_read_b128 v[190:193], v153 offset:32768
	ds_read_b128 v[194:197], v153 offset:33792
	ds_read_b128 v[198:201], v152 offset:32768
	ds_read_b128 v[202:205], v152 offset:33792
	ds_read_b128 v[206:209], v151 offset:32768
	ds_read_b128 v[210:213], v151 offset:33792
	ds_read_b128 v[214:217], v150 offset:32768
	ds_read_b128 v[218:221], v150 offset:33792
	global_load_lds_dwordx4 v[222:223], off
	v_lshl_add_u64 v[222:223], v[240:241], 0, s[12:13]
	s_mov_b32 m0, s51
	s_nop 0
	global_load_lds_dwordx4 v[222:223], off
	s_waitcnt lgkmcnt(8)
	s_setprio 1
	s_barrier
	s_waitcnt lgkmcnt(0)
	v_mfma_f32_16x16x32_bf16 v[124:127], v[190:193], v[174:177], v[124:127]
	v_mfma_f32_16x16x32_bf16 v[120:123], v[190:193], v[182:185], v[120:123]
	v_mfma_f32_16x16x32_bf16 v[116:119], v[198:201], v[174:177], v[116:119]
	v_mfma_f32_16x16x32_bf16 v[112:115], v[198:201], v[182:185], v[112:115]
	v_mfma_f32_16x16x32_bf16 v[108:111], v[206:209], v[174:177], v[108:111]
	v_mfma_f32_16x16x32_bf16 v[104:107], v[206:209], v[182:185], v[104:107]
	v_mfma_f32_16x16x32_bf16 v[100:103], v[214:217], v[174:177], v[100:103]
	v_mfma_f32_16x16x32_bf16 v[96:99], v[214:217], v[182:185], v[96:99]
	v_mfma_f32_16x16x32_bf16 v[124:127], v[194:197], v[178:181], v[124:127]
	v_mfma_f32_16x16x32_bf16 v[120:123], v[194:197], v[186:189], v[120:123]
	v_mfma_f32_16x16x32_bf16 v[116:119], v[202:205], v[178:181], v[116:119]
	v_mfma_f32_16x16x32_bf16 v[112:115], v[202:205], v[186:189], v[112:115]
	v_mfma_f32_16x16x32_bf16 v[108:111], v[210:213], v[178:181], v[108:111]
	v_mfma_f32_16x16x32_bf16 v[104:107], v[210:213], v[186:189], v[104:107]
	v_mfma_f32_16x16x32_bf16 v[100:103], v[218:221], v[178:181], v[100:103]
	v_mfma_f32_16x16x32_bf16 v[96:99], v[218:221], v[186:189], v[96:99]
	s_barrier
	s_setprio 0
	v_readfirstlane_b32 s51, v164
	v_lshl_add_u64 v[246:247], v[242:243], 0, s[14:15]
	s_mov_b32 m0, s51
	v_readfirstlane_b32 s51, v165
	ds_read_b128 v[222:225], v154
	ds_read_b128 v[226:229], v154 offset:1024
	ds_read_b128 v[230:233], v154 offset:2048
	ds_read_b128 v[234:237], v154 offset:3072
	global_load_lds_dwordx4 v[246:247], off
	v_lshl_add_u64 v[246:247], v[244:245], 0, s[14:15]
	s_mov_b32 m0, s51
	s_nop 0
	global_load_lds_dwordx4 v[246:247], off
	s_setprio 1
	s_barrier
	s_waitcnt lgkmcnt(0)
	v_mfma_f32_16x16x32_bf16 v[92:95], v[190:193], v[222:225], v[92:95]
	v_mfma_f32_16x16x32_bf16 v[88:91], v[190:193], v[230:233], v[88:91]
	v_mfma_f32_16x16x32_bf16 v[84:87], v[198:201], v[222:225], v[84:87]
	v_mfma_f32_16x16x32_bf16 v[80:83], v[198:201], v[230:233], v[80:83]
	v_mfma_f32_16x16x32_bf16 v[76:79], v[206:209], v[222:225], v[76:79]
	v_mfma_f32_16x16x32_bf16 v[72:75], v[206:209], v[230:233], v[72:75]
	v_mfma_f32_16x16x32_bf16 v[68:71], v[214:217], v[222:225], v[68:71]
	v_mfma_f32_16x16x32_bf16 v[64:67], v[214:217], v[230:233], v[64:67]
	v_mfma_f32_16x16x32_bf16 v[92:95], v[194:197], v[226:229], v[92:95]
	v_mfma_f32_16x16x32_bf16 v[88:91], v[194:197], v[234:237], v[88:91]
	v_mfma_f32_16x16x32_bf16 v[84:87], v[202:205], v[226:229], v[84:87]
	v_mfma_f32_16x16x32_bf16 v[80:83], v[202:205], v[234:237], v[80:83]
	v_mfma_f32_16x16x32_bf16 v[76:79], v[210:213], v[226:229], v[76:79]
	v_mfma_f32_16x16x32_bf16 v[72:75], v[210:213], v[234:237], v[72:75]
	v_mfma_f32_16x16x32_bf16 v[68:71], v[218:221], v[226:229], v[68:71]
	v_mfma_f32_16x16x32_bf16 v[64:67], v[218:221], v[234:237], v[64:67]
	s_barrier
	s_setprio 0
	v_readfirstlane_b32 s51, v166
	v_lshl_add_u64 v[238:239], v[238:239], 0, s[16:17]
	s_mov_b32 m0, s51
	v_readfirstlane_b32 s51, v168
	ds_read_b128 v[190:193], v153 offset:49152
	ds_read_b128 v[194:197], v153 offset:50176
	ds_read_b128 v[198:201], v152 offset:49152
	ds_read_b128 v[202:205], v152 offset:50176
	ds_read_b128 v[206:209], v151 offset:49152
	ds_read_b128 v[210:213], v151 offset:50176
	ds_read_b128 v[214:217], v150 offset:49152
	ds_read_b128 v[218:221], v150 offset:50176
	global_load_lds_dwordx4 v[238:239], off
	v_lshl_add_u64 v[238:239], v[240:241], 0, s[16:17]
	s_mov_b32 m0, s51
	s_nop 0
	global_load_lds_dwordx4 v[238:239], off
	s_setprio 1
	s_barrier
; #define STAGE(P, BASE, kt) do { const char* _g = (const char*)(BASE) + (size_t)((kt) * (BK * 2)); \
;     __builtin_amdgcn_global_load_lds((const unsigned*)(_g + (size_t)goff0), (unsigned*)((char*)(P) + tid_ * 16), 16, 0, 0); \
;     __builtin_amdgcn_global_load_lds((const unsigned*)(_g + (size_t)goff1), (unsigned*)((char*)(P) + tid_ * 16 + 8192), 16, 0, 0); } while (0)
; #define STAGEA(P, BASE, kt) do { const char* _g = (const char*)(BASE) + (size_t)((kt) * a_kbytes); \
;     __builtin_amdgcn_global_load_lds((const unsigned*)(_g + (size_t)goffA0), (unsigned*)((char*)(P) + tid_ * 16), 16, 0, 0); \
;     __builtin_amdgcn_global_load_lds((const unsigned*)(_g + (size_t)goffA1), (unsigned*)((char*)(P) + tid_ * 16 + 8192), 16, 0, 0); } while (0)
; #define LDA(dst, b, h) for (int m = 0; m < 4; ++m) for (int k = 0; k < 2; ++k) \
;     dst[m][k] = *reinterpret_cast<const bf16x8*>((char*)SA(b, h) + lds_byte(wr * 64 + m * 16 + fr, k * 32 + fq * 8))
; #define LDB(dst, b, h) for (int n = 0; n < 2; ++n) for (int k = 0; k < 2; ++k) \
;     dst[n][k] = *reinterpret_cast<const bf16x8*>((char*)SB(b, h) + lds_byte(wc * 32 + n * 16 + fr, k * 32 + fq * 8))
; #define MMA(ai, bj, At, Bt) do { __builtin_amdgcn_s_setprio(1); \
;     for (int m = 0; m < 4; ++m) for (int n = 0; n < 2; ++n) for (int k = 0; k < 2; ++k) \
;       acc[ai][bj][m][n] = __builtin_amdgcn_mfma_f32_16x16x32_bf16(At[m][k], Bt[n][k], acc[ai][bj][m][n], 0, 0, 0); \
;     __builtin_amdgcn_s_setprio(0); } while (0)
; #define WAIT_V(n) asm volatile("s_waitcnt vmcnt(" #n ")" ::: "memory")
; #define WAIT_L(n) asm volatile("s_waitcnt lgkmcnt(" #n ")" ::: "memory")
; #define BAR __builtin_amdgcn_s_barrier()
; template <int EPI> ...
;     ...
;     STAGE(SB(1, 1), B1p, t + 3);
;     WAIT_V(6); BAR; MMA(1, 1, At, B1); BAR;
;   }
;   { LDB(B0, 0, 0); LDA(At, 0, 0); STAGEA(SA(1, 1), A1, nt - 1);
;     BAR; WAIT_L(0); MMA(0, 0, At, B0); BAR;
;     LDB(B1, 0, 1); BAR; WAIT_L(0); MMA(0, 1, At, B1); BAR;
	s_waitcnt lgkmcnt(0)
	v_mfma_f32_16x16x32_bf16 v[60:63], v[190:193], v[174:177], v[60:63]
	v_mfma_f32_16x16x32_bf16 v[56:59], v[190:193], v[182:185], v[56:59]
	v_mfma_f32_16x16x32_bf16 v[52:55], v[198:201], v[174:177], v[52:55]
	v_mfma_f32_16x16x32_bf16 v[48:51], v[198:201], v[182:185], v[48:51]
	v_mfma_f32_16x16x32_bf16 v[44:47], v[206:209], v[174:177], v[44:47]
	v_mfma_f32_16x16x32_bf16 v[40:43], v[206:209], v[182:185], v[40:43]
	v_mfma_f32_16x16x32_bf16 v[36:39], v[214:217], v[174:177], v[36:39]
	v_mfma_f32_16x16x32_bf16 v[32:35], v[214:217], v[182:185], v[32:35]
	v_mfma_f32_16x16x32_bf16 v[60:63], v[194:197], v[178:181], v[60:63]
	v_mfma_f32_16x16x32_bf16 v[56:59], v[194:197], v[186:189], v[56:59]
	v_mfma_f32_16x16x32_bf16 v[52:55], v[202:205], v[178:181], v[52:55]
	v_mfma_f32_16x16x32_bf16 v[48:51], v[202:205], v[186:189], v[48:51]
	v_mfma_f32_16x16x32_bf16 v[44:47], v[210:213], v[178:181], v[44:47]
	v_mfma_f32_16x16x32_bf16 v[40:43], v[210:213], v[186:189], v[40:43]
	v_mfma_f32_16x16x32_bf16 v[36:39], v[218:221], v[178:181], v[36:39]
	v_mfma_f32_16x16x32_bf16 v[32:35], v[218:221], v[186:189], v[32:35]
	s_barrier
	s_setprio 0
	v_readfirstlane_b32 s51, v169
	v_lshl_add_u64 v[174:175], v[242:243], 0, s[18:19]
	s_mov_b32 m0, s51
	v_readfirstlane_b32 s51, v170
	global_load_lds_dwordx4 v[174:175], off
	v_lshl_add_u64 v[174:175], v[244:245], 0, s[18:19]
	s_mov_b32 m0, s51
	s_nop 0
	global_load_lds_dwordx4 v[174:175], off
	s_waitcnt vmcnt(6)
	s_setprio 1
	s_barrier
	v_mfma_f32_16x16x32_bf16 v[28:31], v[190:193], v[222:225], v[28:31]
	v_mfma_f32_16x16x32_bf16 v[24:27], v[190:193], v[230:233], v[24:27]
	v_mfma_f32_16x16x32_bf16 v[20:23], v[198:201], v[222:225], v[20:23]
	v_mfma_f32_16x16x32_bf16 v[16:19], v[198:201], v[230:233], v[16:19]
	ds_read_b128 v[174:177], v171
	v_mfma_f32_16x16x32_bf16 v[12:15], v[206:209], v[222:225], v[12:15]
	v_mfma_f32_16x16x32_bf16 v[8:11], v[206:209], v[230:233], v[8:11]
	ds_read_b128 v[178:181], v171 offset:1024
	v_mfma_f32_16x16x32_bf16 v[4:7], v[214:217], v[222:225], v[4:7]
	v_mfma_f32_16x16x32_bf16 v[0:3], v[214:217], v[230:233], v[0:3]
	ds_read_b128 v[182:185], v171 offset:2048
	v_mfma_f32_16x16x32_bf16 v[28:31], v[194:197], v[226:229], v[28:31]
	v_mfma_f32_16x16x32_bf16 v[24:27], v[194:197], v[234:237], v[24:27]
	ds_read_b128 v[186:189], v171 offset:3072
	v_mfma_f32_16x16x32_bf16 v[20:23], v[202:205], v[226:229], v[20:23]
	v_mfma_f32_16x16x32_bf16 v[16:19], v[202:205], v[234:237], v[16:19]
	v_mfma_f32_16x16x32_bf16 v[12:15], v[210:213], v[226:229], v[12:15]
	v_mfma_f32_16x16x32_bf16 v[8:11], v[210:213], v[234:237], v[8:11]
	v_mfma_f32_16x16x32_bf16 v[4:7], v[218:221], v[226:229], v[4:7]
	v_mfma_f32_16x16x32_bf16 v[0:3], v[218:221], v[234:237], v[0:3]
	s_barrier
	s_setprio 0
	s_add_i32 s50, s50, 2
	s_add_u32 s26, s26, 0x10000
	s_addc_u32 s27, s27, 0
	s_add_u32 s24, s24, 0x100
	s_addc_u32 s25, s25, 0
	s_cmpk_lt_u32 s50, 0x54
	s_cbranch_scc1 .LBB0_1738
	s_add_u32 s22, s22, 0x2bc000
	s_addc_u32 s23, s23, 0
	v_readfirstlane_b32 s24, v172
	v_lshl_add_u64 v[210:211], s[22:23], 0, v[130:131]
	s_mov_b32 m0, s24
	ds_read_b128 v[158:161], v171
	ds_read_b128 v[162:165], v171 offset:1024
	ds_read_b128 v[174:177], v171 offset:2048
	ds_read_b128 v[168:171], v171 offset:3072
	ds_read_b128 v[178:181], v153
	ds_read_b128 v[182:185], v153 offset:1024
	ds_read_b128 v[186:189], v152
	ds_read_b128 v[190:193], v152 offset:1024
	ds_read_b128 v[194:197], v151
	ds_read_b128 v[198:201], v151 offset:1024
	ds_read_b128 v[202:205], v150
	ds_read_b128 v[206:209], v150 offset:1024
	global_load_lds_dwordx4 v[210:211], off
	v_lshl_add_u64 v[210:211], s[22:23], 0, v[128:129]
	v_readfirstlane_b32 s22, v173
	s_mov_b32 m0, s22
	s_nop 0
	global_load_lds_dwordx4 v[210:211], off
	s_setprio 1
	s_barrier
	s_waitcnt lgkmcnt(0)
	v_mfma_f32_16x16x32_bf16 v[124:127], v[178:181], v[158:161], v[124:127]
	v_mfma_f32_16x16x32_bf16 v[120:123], v[178:181], v[174:177], v[120:123]
	v_mfma_f32_16x16x32_bf16 v[108:111], v[194:197], v[158:161], v[108:111]
	v_mfma_f32_16x16x32_bf16 v[104:107], v[194:197], v[174:177], v[104:107]
	v_mfma_f32_16x16x32_bf16 v[124:127], v[182:185], v[162:165], v[124:127]
	v_mfma_f32_16x16x32_bf16 v[120:123], v[182:185], v[168:171], v[120:123]
	v_mfma_f32_16x16x32_bf16 v[116:119], v[186:189], v[158:161], v[116:119]
	v_mfma_f32_16x16x32_bf16 v[112:115], v[186:189], v[174:177], v[112:115]
	v_mfma_f32_16x16x32_bf16 v[108:111], v[198:201], v[162:165], v[108:111]
	v_mfma_f32_16x16x32_bf16 v[104:107], v[198:201], v[168:171], v[104:107]
	v_mfma_f32_16x16x32_bf16 v[100:103], v[202:205], v[158:161], v[100:103]
	v_mfma_f32_16x16x32_bf16 v[96:99], v[202:205], v[174:177], v[96:99]
	v_mfma_f32_16x16x32_bf16 v[210:213], v[190:193], v[162:165], v[116:119]
	v_mfma_f32_16x16x32_bf16 v[214:217], v[190:193], v[168:171], v[112:115]
	v_mfma_f32_16x16x32_bf16 v[218:221], v[206:209], v[162:165], v[100:103]
	v_mfma_f32_16x16x32_bf16 v[222:225], v[206:209], v[168:171], v[96:99]
	s_barrier
	s_setprio 0
	s_nop 1
	ds_read_b128 v[96:99], v167
	ds_read_b128 v[100:103], v167 offset:1024
	ds_read_b128 v[112:115], v167 offset:2048
	ds_read_b128 v[116:119], v167 offset:3072
	s_setprio 1
	s_barrier
; #define LDA(dst, b, h) for (int m = 0; m < 4; ++m) for (int k = 0; k < 2; ++k) \
;     dst[m][k] = *reinterpret_cast<const bf16x8*>((char*)SA(b, h) + lds_byte(wr * 64 + m * 16 + fr, k * 32 + fq * 8))
; #define LDB(dst, b, h) for (int n = 0; n < 2; ++n) for (int k = 0; k < 2; ++k) \
;     dst[n][k] = *reinterpret_cast<const bf16x8*>((char*)SB(b, h) + lds_byte(wc * 32 + n * 16 + fr, k * 32 + fq * 8))
; #define MMA(ai, bj, At, Bt) do { __builtin_amdgcn_s_setprio(1); \
;     for (int m = 0; m < 4; ++m) for (int n = 0; n < 2; ++n) for (int k = 0; k < 2; ++k) \
;       acc[ai][bj][m][n] = __builtin_amdgcn_mfma_f32_16x16x32_bf16(At[m][k], Bt[n][k], acc[ai][bj][m][n], 0, 0, 0); \
;     __builtin_amdgcn_s_setprio(0); } while (0)
; #define WAIT_V(n) asm volatile("s_waitcnt vmcnt(" #n ")" ::: "memory")
; #define WAIT_L(n) asm volatile("s_waitcnt lgkmcnt(" #n ")" ::: "memory")
; #define BAR __builtin_amdgcn_s_barrier()
; template <int EPI> ...
;     ...
;     BAR; WAIT_L(0); MMA(0, 0, At, B0); BAR;
;     LDB(B1, 0, 1); BAR; WAIT_L(0); MMA(0, 1, At, B1); BAR;
;     LDA(At, 0, 1); WAIT_V(4); BAR; WAIT_L(0); MMA(1, 0, At, B0); MMA(1, 1, At, B1); BAR; }
;   { LDB(B0, 1, 0); LDA(At, 1, 0); WAIT_V(2); BAR; WAIT_L(0); MMA(0, 0, At, B0); BAR;
;     LDB(B1, 1, 1); WAIT_V(0); BAR; WAIT_L(0); MMA(0, 1, At, B1); BAR;
;     LDA(At, 1, 1); BAR; WAIT_L(0); MMA(1, 0, At, B0); MMA(1, 1, At, B1); BAR; }
	s_waitcnt lgkmcnt(0)
	v_mfma_f32_16x16x32_bf16 v[92:95], v[178:181], v[96:99], v[92:95]
	v_mfma_f32_16x16x32_bf16 v[88:91], v[178:181], v[112:115], v[88:91]
	v_mfma_f32_16x16x32_bf16 v[76:79], v[194:197], v[96:99], v[76:79]
	v_mfma_f32_16x16x32_bf16 v[72:75], v[194:197], v[112:115], v[72:75]
	v_mfma_f32_16x16x32_bf16 v[92:95], v[182:185], v[100:103], v[92:95]
	v_mfma_f32_16x16x32_bf16 v[88:91], v[182:185], v[116:119], v[88:91]
	v_mfma_f32_16x16x32_bf16 v[84:87], v[186:189], v[96:99], v[84:87]
	v_mfma_f32_16x16x32_bf16 v[80:83], v[186:189], v[112:115], v[80:83]
	v_mfma_f32_16x16x32_bf16 v[76:79], v[198:201], v[100:103], v[76:79]
	v_mfma_f32_16x16x32_bf16 v[72:75], v[198:201], v[116:119], v[72:75]
	v_mfma_f32_16x16x32_bf16 v[68:71], v[202:205], v[96:99], v[68:71]
	v_mfma_f32_16x16x32_bf16 v[64:67], v[202:205], v[112:115], v[64:67]
	v_mfma_f32_16x16x32_bf16 v[178:181], v[190:193], v[100:103], v[84:87]
	v_mfma_f32_16x16x32_bf16 v[182:185], v[190:193], v[116:119], v[80:83]
	v_mfma_f32_16x16x32_bf16 v[186:189], v[206:209], v[100:103], v[68:71]
	v_mfma_f32_16x16x32_bf16 v[190:193], v[206:209], v[116:119], v[64:67]
	s_barrier
	s_setprio 0
	s_nop 1
	ds_read_b128 v[64:67], v153 offset:16384
	ds_read_b128 v[68:71], v153 offset:17408
	ds_read_b128 v[80:83], v152 offset:16384
	ds_read_b128 v[84:87], v152 offset:17408
	ds_read_b128 v[194:197], v151 offset:16384
	ds_read_b128 v[198:201], v151 offset:17408
	ds_read_b128 v[202:205], v150 offset:16384
	ds_read_b128 v[206:209], v150 offset:17408
	s_waitcnt vmcnt(4)
	s_setprio 1
	s_barrier
	s_waitcnt lgkmcnt(0)
	v_mfma_f32_16x16x32_bf16 v[60:63], v[64:67], v[158:161], v[60:63]
	v_mfma_f32_16x16x32_bf16 v[56:59], v[64:67], v[174:177], v[56:59]
	v_mfma_f32_16x16x32_bf16 v[44:47], v[194:197], v[158:161], v[44:47]
	v_mfma_f32_16x16x32_bf16 v[40:43], v[194:197], v[174:177], v[40:43]
	v_mfma_f32_16x16x32_bf16 v[60:63], v[68:71], v[162:165], v[60:63]
	v_mfma_f32_16x16x32_bf16 v[56:59], v[68:71], v[168:171], v[56:59]
	v_mfma_f32_16x16x32_bf16 v[52:55], v[80:83], v[158:161], v[52:55]
	v_mfma_f32_16x16x32_bf16 v[48:51], v[80:83], v[174:177], v[48:51]
	v_mfma_f32_16x16x32_bf16 v[44:47], v[198:201], v[162:165], v[44:47]
	v_mfma_f32_16x16x32_bf16 v[40:43], v[198:201], v[168:171], v[40:43]
	v_mfma_f32_16x16x32_bf16 v[36:39], v[202:205], v[158:161], v[36:39]
	v_mfma_f32_16x16x32_bf16 v[32:35], v[202:205], v[174:177], v[32:35]
	v_mfma_f32_16x16x32_bf16 v[226:229], v[84:87], v[162:165], v[52:55]
	v_mfma_f32_16x16x32_bf16 v[230:233], v[84:87], v[168:171], v[48:51]
	v_mfma_f32_16x16x32_bf16 v[158:161], v[206:209], v[162:165], v[36:39]
	v_mfma_f32_16x16x32_bf16 v[162:165], v[206:209], v[168:171], v[32:35]
	s_setprio 0
	s_setprio 1
	v_mfma_f32_16x16x32_bf16 v[28:31], v[64:67], v[96:99], v[28:31]
	v_mfma_f32_16x16x32_bf16 v[24:27], v[64:67], v[112:115], v[24:27]
	v_mfma_f32_16x16x32_bf16 v[12:15], v[194:197], v[96:99], v[12:15]
	v_mfma_f32_16x16x32_bf16 v[8:11], v[194:197], v[112:115], v[8:11]
	v_mfma_f32_16x16x32_bf16 v[28:31], v[68:71], v[100:103], v[28:31]
	v_mfma_f32_16x16x32_bf16 v[24:27], v[68:71], v[116:119], v[24:27]
	v_mfma_f32_16x16x32_bf16 v[20:23], v[80:83], v[96:99], v[20:23]
	v_mfma_f32_16x16x32_bf16 v[16:19], v[80:83], v[112:115], v[16:19]
	v_mfma_f32_16x16x32_bf16 v[12:15], v[198:201], v[100:103], v[12:15]
	v_mfma_f32_16x16x32_bf16 v[8:11], v[198:201], v[116:119], v[8:11]
	v_mfma_f32_16x16x32_bf16 v[4:7], v[202:205], v[96:99], v[4:7]
	v_mfma_f32_16x16x32_bf16 v[0:3], v[202:205], v[112:115], v[0:3]
	v_mfma_f32_16x16x32_bf16 v[166:169], v[84:87], v[100:103], v[20:23]
	v_mfma_f32_16x16x32_bf16 v[170:173], v[84:87], v[116:119], v[16:19]
	v_mfma_f32_16x16x32_bf16 v[174:177], v[206:209], v[100:103], v[4:7]
	v_mfma_f32_16x16x32_bf16 v[194:197], v[206:209], v[116:119], v[0:3]
	s_barrier
	s_setprio 0
	s_nop 1
	ds_read_b128 v[0:3], v156
	ds_read_b128 v[4:7], v156 offset:1024
	ds_read_b128 v[198:201], v156 offset:2048
	ds_read_b128 v[202:205], v156 offset:3072
	ds_read_b128 v[16:19], v153 offset:32768
	ds_read_b128 v[20:23], v153 offset:33792
	ds_read_b128 v[32:35], v152 offset:32768
	ds_read_b128 v[36:39], v152 offset:33792
	ds_read_b128 v[48:51], v151 offset:32768
	ds_read_b128 v[52:55], v151 offset:33792
	ds_read_b128 v[206:209], v150 offset:32768
	ds_read_b128 v[234:237], v150 offset:33792
	s_waitcnt vmcnt(2)
	s_setprio 1
	s_barrier
	s_waitcnt lgkmcnt(0)
	v_mfma_f32_16x16x32_bf16 v[64:67], v[16:19], v[0:3], v[124:127]
	v_mfma_f32_16x16x32_bf16 v[116:119], v[20:23], v[4:7], v[64:67]
	v_mfma_f32_16x16x32_bf16 v[64:67], v[16:19], v[198:201], v[120:123]
	v_mfma_f32_16x16x32_bf16 v[112:115], v[20:23], v[202:205], v[64:67]
	v_mfma_f32_16x16x32_bf16 v[64:67], v[32:35], v[0:3], v[210:213]
	v_mfma_f32_16x16x32_bf16 v[100:103], v[36:39], v[4:7], v[64:67]
	v_mfma_f32_16x16x32_bf16 v[64:67], v[32:35], v[198:201], v[214:217]
	v_mfma_f32_16x16x32_bf16 v[96:99], v[36:39], v[202:205], v[64:67]
	v_mfma_f32_16x16x32_bf16 v[64:67], v[48:51], v[0:3], v[108:111]
	v_mfma_f32_16x16x32_bf16 v[84:87], v[52:55], v[4:7], v[64:67]
	v_mfma_f32_16x16x32_bf16 v[64:67], v[48:51], v[198:201], v[104:107]
	v_mfma_f32_16x16x32_bf16 v[80:83], v[52:55], v[202:205], v[64:67]
	v_mfma_f32_16x16x32_bf16 v[64:67], v[206:209], v[0:3], v[218:221]
	v_mfma_f32_16x16x32_bf16 v[68:71], v[234:237], v[4:7], v[64:67]
	v_mfma_f32_16x16x32_bf16 v[64:67], v[206:209], v[198:201], v[222:225]
	v_mfma_f32_16x16x32_bf16 v[64:67], v[234:237], v[202:205], v[64:67]
	s_barrier
	s_setprio 0
	ds_read_b128 v[210:213], v154
	ds_read_b128 v[214:217], v154 offset:1024
	ds_read_b128 v[218:221], v154 offset:2048
	ds_read_b128 v[154:157], v154 offset:3072
	s_waitcnt vmcnt(0)
	s_setprio 1
	s_barrier
; __device__ __forceinline__ u16 f2bf(float f) { unsigned u = __float_as_uint(f); u += 0x7fffu + ((u >> 16) & 1u); return (u16)(u >> 16); }
; __device__ __forceinline__ float frcp(float x) { return __builtin_amdgcn_rcpf(x); }
; #define LDA(dst, b, h) for (int m = 0; m < 4; ++m) for (int k = 0; k < 2; ++k) \
;     dst[m][k] = *reinterpret_cast<const bf16x8*>((char*)SA(b, h) + lds_byte(wr * 64 + m * 16 + fr, k * 32 + fq * 8))
; #define LDB(dst, b, h) for (int n = 0; n < 2; ++n) for (int k = 0; k < 2; ++k) \
;     dst[n][k] = *reinterpret_cast<const bf16x8*>((char*)SB(b, h) + lds_byte(wc * 32 + n * 16 + fr, k * 32 + fq * 8))
; #define WAIT_V(n) asm volatile("s_waitcnt vmcnt(" #n ")" ::: "memory")
; #define WAIT_L(n) asm volatile("s_waitcnt lgkmcnt(" #n ")" ::: "memory")
; #define BAR __builtin_amdgcn_s_barrier()
; template <int EPI> ...
;     ...
;     LDA(At, 0, 1); WAIT_V(4); BAR; WAIT_L(0); MMA(1, 0, At, B0); MMA(1, 1, At, B1); BAR; }
;   { LDB(B0, 1, 0); LDA(At, 1, 0); WAIT_V(2); BAR; WAIT_L(0); MMA(0, 0, At, B0); BAR;
;     LDB(B1, 1, 1); WAIT_V(0); BAR; WAIT_L(0); MMA(0, 1, At, B1); BAR;
;     LDA(At, 1, 1); BAR; WAIT_L(0); MMA(1, 0, At, B0); MMA(1, 1, At, B1); BAR; }
;   if (wr == 0) BAR;
;   {
;     constexpr int NC = (EPI == EPI_GU) ? 128 : 256;
;     constexpr int RB = NC * 2;
;     char* tb = (char*)shm;
; #pragma unroll
;     for (int ai = 0; ai < 2; ++ai)
; #pragma unroll
;       for (int m = 0; m < 4; ++m)
; #pragma unroll
;         for (int j = 0; j < 4; ++j) {
;           const int r = ai * 128 + wr * 64 + m * 16 + fq * 4 + j;
;           float rs = 1.0f;
;           if (EPI != EPI_RES) rs = e.rstd[brow + r];
;           char* rowp = tb + r * RB + fr * 2;
;           if (EPI == EPI_GU) {
; #pragma unroll
;             for (int n = 0; n < 2; ++n) {
;               float g = acc[ai][0][m][n][j] * rs, u = acc[ai][1][m][n][j] * rs;
;               float h = g * frcp(1.0f + __expf(-g)) * u;
;               const int seg = (wc * 2 + n) ^ fq;
;               *(u16*)(rowp + seg * 32) = f2bf(h);
;             }
;           } else {
; #pragma unroll
;             for (int bj = 0; bj < 2; ++bj)
; #pragma unroll
;               for (int n = 0; n < 2; ++n) {
;                 const int seg = (bj * 8 + wc * 2 + n) ^ fq;
;                 *(u16*)(rowp + seg * 32) = f2bf(acc[ai][bj][m][n][j] * rs);
;               }
	s_waitcnt lgkmcnt(0)
	v_mfma_f32_16x16x32_bf16 v[92:95], v[16:19], v[210:213], v[92:95]
	v_mfma_f32_16x16x32_bf16 v[16:19], v[16:19], v[218:221], v[88:91]
	v_mfma_f32_16x16x32_bf16 v[120:123], v[20:23], v[154:157], v[16:19]
	v_mfma_f32_16x16x32_bf16 v[16:19], v[32:35], v[210:213], v[178:181]
	v_mfma_f32_16x16x32_bf16 v[108:111], v[36:39], v[214:217], v[16:19]
	v_mfma_f32_16x16x32_bf16 v[16:19], v[32:35], v[218:221], v[182:185]
	v_mfma_f32_16x16x32_bf16 v[104:107], v[36:39], v[154:157], v[16:19]
	v_mfma_f32_16x16x32_bf16 v[16:19], v[48:51], v[210:213], v[76:79]
	v_mfma_f32_16x16x32_bf16 v[124:127], v[20:23], v[214:217], v[92:95]
	v_mfma_f32_16x16x32_bf16 v[92:95], v[52:55], v[214:217], v[16:19]
	v_mfma_f32_16x16x32_bf16 v[16:19], v[48:51], v[218:221], v[72:75]
	v_mfma_f32_16x16x32_bf16 v[88:91], v[52:55], v[154:157], v[16:19]
	v_mfma_f32_16x16x32_bf16 v[16:19], v[206:209], v[210:213], v[186:189]
	v_mfma_f32_16x16x32_bf16 v[76:79], v[234:237], v[214:217], v[16:19]
	v_mfma_f32_16x16x32_bf16 v[16:19], v[206:209], v[218:221], v[190:193]
	v_mfma_f32_16x16x32_bf16 v[72:75], v[234:237], v[154:157], v[16:19]
	s_barrier
	s_setprio 0
	ds_read_b128 v[178:181], v153 offset:49152
	ds_read_b128 v[182:185], v153 offset:50176
	ds_read_b128 v[186:189], v152 offset:49152
	ds_read_b128 v[190:193], v152 offset:50176
	ds_read_b128 v[206:209], v151 offset:49152
	ds_read_b128 v[222:225], v151 offset:50176
	ds_read_b128 v[234:237], v150 offset:49152
	ds_read_b128 v[150:153], v150 offset:50176
	s_setprio 1
	s_barrier
	s_waitcnt lgkmcnt(0)
	v_mfma_f32_16x16x32_bf16 v[16:19], v[178:181], v[0:3], v[60:63]
	v_mfma_f32_16x16x32_bf16 v[52:55], v[182:185], v[4:7], v[16:19]
	v_mfma_f32_16x16x32_bf16 v[16:19], v[178:181], v[198:201], v[56:59]
	v_mfma_f32_16x16x32_bf16 v[48:51], v[182:185], v[202:205], v[16:19]
	v_mfma_f32_16x16x32_bf16 v[16:19], v[186:189], v[0:3], v[226:229]
	v_mfma_f32_16x16x32_bf16 v[36:39], v[190:193], v[4:7], v[16:19]
	v_mfma_f32_16x16x32_bf16 v[16:19], v[186:189], v[198:201], v[230:233]
	v_mfma_f32_16x16x32_bf16 v[32:35], v[190:193], v[202:205], v[16:19]
	v_mfma_f32_16x16x32_bf16 v[16:19], v[206:209], v[0:3], v[44:47]
	v_mfma_f32_16x16x32_bf16 v[0:3], v[234:237], v[0:3], v[158:161]
	v_mfma_f32_16x16x32_bf16 v[20:23], v[222:225], v[4:7], v[16:19]
	v_mfma_f32_16x16x32_bf16 v[16:19], v[206:209], v[198:201], v[40:43]
	v_mfma_f32_16x16x32_bf16 v[4:7], v[150:153], v[4:7], v[0:3]
	v_mfma_f32_16x16x32_bf16 v[0:3], v[234:237], v[198:201], v[162:165]
	v_mfma_f32_16x16x32_bf16 v[16:19], v[222:225], v[202:205], v[16:19]
	v_mfma_f32_16x16x32_bf16 v[0:3], v[150:153], v[202:205], v[0:3]
	s_setprio 0
	s_setprio 1
	v_mfma_f32_16x16x32_bf16 v[24:27], v[178:181], v[218:221], v[24:27]
	v_mfma_f32_16x16x32_bf16 v[56:59], v[182:185], v[154:157], v[24:27]
	v_mfma_f32_16x16x32_bf16 v[24:27], v[186:189], v[210:213], v[166:169]
	v_mfma_f32_16x16x32_bf16 v[44:47], v[190:193], v[214:217], v[24:27]
	v_mfma_f32_16x16x32_bf16 v[24:27], v[186:189], v[218:221], v[170:173]
	v_mfma_f32_16x16x32_bf16 v[8:11], v[206:209], v[218:221], v[8:11]
	v_mfma_f32_16x16x32_bf16 v[28:31], v[178:181], v[210:213], v[28:31]
	v_mfma_f32_16x16x32_bf16 v[40:43], v[190:193], v[154:157], v[24:27]
	v_mfma_f32_16x16x32_bf16 v[12:15], v[206:209], v[210:213], v[12:15]
	v_mfma_f32_16x16x32_bf16 v[24:27], v[222:225], v[154:157], v[8:11]
	v_mfma_f32_16x16x32_bf16 v[8:11], v[234:237], v[210:213], v[174:177]
	v_mfma_f32_16x16x32_bf16 v[60:63], v[182:185], v[214:217], v[28:31]
	v_mfma_f32_16x16x32_bf16 v[28:31], v[222:225], v[214:217], v[12:15]
	v_mfma_f32_16x16x32_bf16 v[12:15], v[150:153], v[214:217], v[8:11]
	v_mfma_f32_16x16x32_bf16 v[8:11], v[234:237], v[218:221], v[194:197]
	v_mfma_f32_16x16x32_bf16 v[8:11], v[150:153], v[154:157], v[8:11]
	s_barrier
	s_setprio 0
	v_cmp_gt_u32_e32 vcc, s43, v144
	s_and_saveexec_b64 s[22:23], vcc
	s_cbranch_execz .LBB0_1741
	s_barrier
.LBB0_1741:
	s_or_b64 exec, exec, s[22:23]
	v_lshl_add_u32 v144, v149, 1, 0
	v_lshlrev_b32_e32 v148, 1, v148
	v_lshlrev_b32_e32 v150, 11, v145
	v_lshlrev_b32_e32 v147, 15, v147
	v_add3_u32 v144, v144, v150, v147
	v_xor_b32_e32 v147, v148, v145
	v_lshlrev_b32_e32 v147, 5, v147
	v_cvt_pk_bf16_f32 v116, v116, v116
	v_add_u32_e32 v150, v144, v147
	ds_write_b16_d16_hi v150, v116
	v_bitop3_b32 v116, v148, v145, 1 bitop3:0x36
	v_lshlrev_b32_e32 v116, 5, v116
	v_cvt_pk_bf16_f32 v112, v112, v112
	v_add_u32_e32 v151, v144, v116
	v_bitop3_b32 v149, v148, v145, 8 bitop3:0x36
	ds_write_b16_d16_hi v151, v112
	v_bfe_u32 v112, v124, 16, 1
	v_add3_u32 v112, v124, v112, s44
	v_lshlrev_b32_e32 v124, 5, v149
	v_add_u32_e32 v149, v144, v124
	ds_write_b16_d16_hi v149, v112
	v_bitop3_b32 v112, v148, v145, 9 bitop3:0x36
	v_lshlrev_b32_e32 v112, 5, v112
	v_cvt_pk_bf16_f32 v120, v120, v120
	v_add_u32_e32 v145, v144, v112
	ds_write_b16_d16_hi v145, v120
	v_cvt_pk_bf16_f32 v117, v117, v117
	ds_write_b16_d16_hi v150, v117 offset:512
	v_cvt_pk_bf16_f32 v113, v113, v113
	ds_write_b16_d16_hi v151, v113 offset:512
	v_bfe_u32 v113, v125, 16, 1
	v_add3_u32 v113, v125, v113, s44
	ds_write_b16_d16_hi v149, v113 offset:512
	v_bfe_u32 v113, v121, 16, 1
	v_add3_u32 v113, v121, v113, s44
	ds_write_b16_d16_hi v145, v113 offset:512
	v_bfe_u32 v113, v118, 16, 1
	v_add3_u32 v113, v118, v113, s44
	ds_write_b16_d16_hi v150, v113 offset:1024
	v_bfe_u32 v113, v114, 16, 1
	v_add3_u32 v113, v114, v113, s44
	ds_write_b16_d16_hi v151, v113 offset:1024
	v_bfe_u32 v113, v126, 16, 1
	v_add3_u32 v113, v126, v113, s44
	ds_write_b16_d16_hi v149, v113 offset:1024
	v_bfe_u32 v113, v122, 16, 1
	v_add3_u32 v113, v122, v113, s44
	ds_write_b16_d16_hi v145, v113 offset:1024
	v_bfe_u32 v113, v119, 16, 1
; __device__ __forceinline__ u16 f2bf(float f) { unsigned u = __float_as_uint(f); u += 0x7fffu + ((u >> 16) & 1u); return (u16)(u >> 16); }
; __device__ __forceinline__ float frcp(float x) { return __builtin_amdgcn_rcpf(x); }
; template <int EPI> ...
;     ...
;     for (int ai = 0; ai < 2; ++ai)
; #pragma unroll
;       for (int m = 0; m < 4; ++m)
; #pragma unroll
;         for (int j = 0; j < 4; ++j) {
;           const int r = ai * 128 + wr * 64 + m * 16 + fq * 4 + j;
;           float rs = 1.0f;
;           if (EPI != EPI_RES) rs = e.rstd[brow + r];
;           char* rowp = tb + r * RB + fr * 2;
;           if (EPI == EPI_GU) {
; #pragma unroll
;             for (int n = 0; n < 2; ++n) {
;               float g = acc[ai][0][m][n][j] * rs, u = acc[ai][1][m][n][j] * rs;
;               float h = g * frcp(1.0f + __expf(-g)) * u;
;               const int seg = (wc * 2 + n) ^ fq;
;               *(u16*)(rowp + seg * 32) = f2bf(h);
;             }
;           } else {
; #pragma unroll
;             for (int bj = 0; bj < 2; ++bj)
; #pragma unroll
;               for (int n = 0; n < 2; ++n) {
;                 const int seg = (bj * 8 + wc * 2 + n) ^ fq;
;                 *(u16*)(rowp + seg * 32) = f2bf(acc[ai][bj][m][n][j] * rs);
;               }
	v_add3_u32 v113, v119, v113, s44
	ds_write_b16_d16_hi v150, v113 offset:1536
	v_bfe_u32 v113, v115, 16, 1
	v_add3_u32 v113, v115, v113, s44
	ds_write_b16_d16_hi v151, v113 offset:1536
	v_bfe_u32 v113, v127, 16, 1
	v_add3_u32 v113, v127, v113, s44
	ds_write_b16_d16_hi v149, v113 offset:1536
	v_bfe_u32 v113, v123, 16, 1
	v_add3_u32 v113, v123, v113, s44
	ds_write_b16_d16_hi v145, v113 offset:1536
	v_cvt_pk_bf16_f32 v100, v100, v100
	ds_write_b16_d16_hi v150, v100 offset:8192
	v_cvt_pk_bf16_f32 v96, v96, v96
	ds_write_b16_d16_hi v151, v96 offset:8192
	v_bfe_u32 v96, v108, 16, 1
	v_add3_u32 v96, v108, v96, s44
	ds_write_b16_d16_hi v149, v96 offset:8192
	v_bfe_u32 v96, v104, 16, 1
	v_add3_u32 v96, v104, v96, s44
	ds_write_b16_d16_hi v145, v96 offset:8192
	v_bfe_u32 v96, v101, 16, 1
	v_add3_u32 v96, v101, v96, s44
	ds_write_b16_d16_hi v150, v96 offset:8704
	v_bfe_u32 v96, v97, 16, 1
	v_add3_u32 v96, v97, v96, s44
	ds_write_b16_d16_hi v151, v96 offset:8704
	v_bfe_u32 v96, v109, 16, 1
	v_add3_u32 v96, v109, v96, s44
	ds_write_b16_d16_hi v149, v96 offset:8704
	v_bfe_u32 v96, v105, 16, 1
	v_add3_u32 v96, v105, v96, s44
	ds_write_b16_d16_hi v145, v96 offset:8704
	v_bfe_u32 v96, v102, 16, 1
	v_add3_u32 v96, v102, v96, s44
	ds_write_b16_d16_hi v150, v96 offset:9216
	v_bfe_u32 v96, v98, 16, 1
	v_add3_u32 v96, v98, v96, s44
	ds_write_b16_d16_hi v151, v96 offset:9216
	v_bfe_u32 v96, v110, 16, 1
	v_add3_u32 v96, v110, v96, s44
	ds_write_b16_d16_hi v149, v96 offset:9216
	v_bfe_u32 v96, v106, 16, 1
	v_add3_u32 v96, v106, v96, s44
	ds_write_b16_d16_hi v145, v96 offset:9216
	v_bfe_u32 v96, v103, 16, 1
	v_add3_u32 v96, v103, v96, s44
	ds_write_b16_d16_hi v150, v96 offset:9728
	v_bfe_u32 v96, v99, 16, 1
	v_add3_u32 v96, v99, v96, s44
	ds_write_b16_d16_hi v151, v96 offset:9728
	v_bfe_u32 v96, v111, 16, 1
	v_add3_u32 v96, v111, v96, s44
	ds_write_b16_d16_hi v149, v96 offset:9728
	v_bfe_u32 v96, v107, 16, 1
	v_add3_u32 v96, v107, v96, s44
	ds_write_b16_d16_hi v145, v96 offset:9728
	v_bfe_u32 v96, v84, 16, 1
	v_add3_u32 v84, v84, v96, s44
	ds_write_b16_d16_hi v150, v84 offset:16384
	v_bfe_u32 v84, v80, 16, 1
	v_add3_u32 v80, v80, v84, s44
	ds_write_b16_d16_hi v151, v80 offset:16384
	v_bfe_u32 v80, v92, 16, 1
	v_add3_u32 v80, v92, v80, s44
	ds_write_b16_d16_hi v149, v80 offset:16384
	v_bfe_u32 v80, v88, 16, 1
	v_add3_u32 v80, v88, v80, s44
	ds_write_b16_d16_hi v145, v80 offset:16384
	v_bfe_u32 v80, v85, 16, 1
	v_add3_u32 v80, v85, v80, s44
	ds_write_b16_d16_hi v150, v80 offset:16896
	v_bfe_u32 v80, v81, 16, 1
	v_add3_u32 v80, v81, v80, s44
	ds_write_b16_d16_hi v151, v80 offset:16896
	v_bfe_u32 v80, v93, 16, 1
	v_add3_u32 v80, v93, v80, s44
	ds_write_b16_d16_hi v149, v80 offset:16896
	v_bfe_u32 v80, v89, 16, 1
	v_add3_u32 v80, v89, v80, s44
	ds_write_b16_d16_hi v145, v80 offset:16896
	v_bfe_u32 v80, v86, 16, 1
	v_add3_u32 v80, v86, v80, s44
	ds_write_b16_d16_hi v150, v80 offset:17408
	v_bfe_u32 v80, v82, 16, 1
	v_add3_u32 v80, v82, v80, s44
	ds_write_b16_d16_hi v151, v80 offset:17408
	v_bfe_u32 v80, v94, 16, 1
	v_add3_u32 v80, v94, v80, s44
	ds_write_b16_d16_hi v149, v80 offset:17408
	v_bfe_u32 v80, v90, 16, 1
	v_add3_u32 v80, v90, v80, s44
	ds_write_b16_d16_hi v145, v80 offset:17408
	v_bfe_u32 v80, v87, 16, 1
	v_add3_u32 v80, v87, v80, s44
	ds_write_b16_d16_hi v150, v80 offset:17920
	v_bfe_u32 v80, v83, 16, 1
	v_add3_u32 v80, v83, v80, s44
	ds_write_b16_d16_hi v151, v80 offset:17920
	v_bfe_u32 v80, v95, 16, 1
	v_add3_u32 v80, v95, v80, s44
	ds_write_b16_d16_hi v149, v80 offset:17920
	v_bfe_u32 v80, v91, 16, 1
	v_add3_u32 v80, v91, v80, s44
	ds_write_b16_d16_hi v145, v80 offset:17920
	v_bfe_u32 v80, v68, 16, 1
	v_add3_u32 v68, v68, v80, s44
	ds_write_b16_d16_hi v150, v68 offset:24576
	v_bfe_u32 v68, v64, 16, 1
	v_add3_u32 v64, v64, v68, s44
	ds_write_b16_d16_hi v151, v64 offset:24576
	v_bfe_u32 v64, v76, 16, 1
	v_add3_u32 v64, v76, v64, s44
	ds_write_b16_d16_hi v149, v64 offset:24576
	v_bfe_u32 v64, v72, 16, 1
	v_add3_u32 v64, v72, v64, s44
	ds_write_b16_d16_hi v145, v64 offset:24576
	v_bfe_u32 v64, v69, 16, 1
	v_add3_u32 v64, v69, v64, s44
	ds_write_b16_d16_hi v150, v64 offset:25088
	v_bfe_u32 v64, v65, 16, 1
	v_add3_u32 v64, v65, v64, s44
	ds_write_b16_d16_hi v151, v64 offset:25088
	v_bfe_u32 v64, v77, 16, 1
	v_add3_u32 v64, v77, v64, s44
	ds_write_b16_d16_hi v149, v64 offset:25088
	v_bfe_u32 v64, v73, 16, 1
	v_add3_u32 v64, v73, v64, s44
	ds_write_b16_d16_hi v145, v64 offset:25088
	v_bfe_u32 v64, v70, 16, 1
	v_add3_u32 v64, v70, v64, s44
	ds_write_b16_d16_hi v150, v64 offset:25600
	v_bfe_u32 v64, v66, 16, 1
	v_add3_u32 v64, v66, v64, s44
	ds_write_b16_d16_hi v151, v64 offset:25600
	v_bfe_u32 v64, v78, 16, 1
	v_add3_u32 v64, v78, v64, s44
	ds_write_b16_d16_hi v149, v64 offset:25600
	v_bfe_u32 v64, v74, 16, 1
	v_add3_u32 v64, v74, v64, s44
	ds_write_b16_d16_hi v145, v64 offset:25600
	v_bfe_u32 v64, v71, 16, 1
	v_add3_u32 v64, v71, v64, s44
	ds_write_b16_d16_hi v150, v64 offset:26112
	v_bfe_u32 v64, v67, 16, 1
	v_add3_u32 v64, v67, v64, s44
	ds_write_b16_d16_hi v151, v64 offset:26112
	v_bfe_u32 v64, v79, 16, 1
	v_add3_u32 v64, v79, v64, s44
	ds_write_b16_d16_hi v149, v64 offset:26112
	v_bfe_u32 v64, v75, 16, 1
	v_add3_u32 v64, v75, v64, s44
	ds_write_b16_d16_hi v145, v64 offset:26112
	v_add_u32_e32 v64, 0x10000, v144
	v_cvt_pk_bf16_f32 v52, v52, v52
	v_add_u32_e32 v65, v64, v147
	ds_write_b16_d16_hi v65, v52
	v_cvt_pk_bf16_f32 v48, v48, v48
	v_add_u32_e32 v52, v64, v116
	ds_write_b16_d16_hi v52, v48
	v_bfe_u32 v48, v60, 16, 1
	v_add3_u32 v48, v60, v48, s44
	v_add_u32_e32 v52, v64, v124
	ds_write_b16_d16_hi v52, v48
	v_bfe_u32 v48, v56, 16, 1
	v_add3_u32 v48, v56, v48, s44
; __device__ __forceinline__ u16 f2bf(float f) { unsigned u = __float_as_uint(f); u += 0x7fffu + ((u >> 16) & 1u); return (u16)(u >> 16); }
; __device__ __forceinline__ float frcp(float x) { return __builtin_amdgcn_rcpf(x); }
; template <int EPI> ...
;     ...
;     for (int ai = 0; ai < 2; ++ai)
; #pragma unroll
;       for (int m = 0; m < 4; ++m)
; #pragma unroll
;         for (int j = 0; j < 4; ++j) {
;           const int r = ai * 128 + wr * 64 + m * 16 + fq * 4 + j;
;           float rs = 1.0f;
;           if (EPI != EPI_RES) rs = e.rstd[brow + r];
;           char* rowp = tb + r * RB + fr * 2;
;           if (EPI == EPI_GU) {
; #pragma unroll
;             for (int n = 0; n < 2; ++n) {
;               float g = acc[ai][0][m][n][j] * rs, u = acc[ai][1][m][n][j] * rs;
;               float h = g * frcp(1.0f + __expf(-g)) * u;
;               const int seg = (wc * 2 + n) ^ fq;
;               *(u16*)(rowp + seg * 32) = f2bf(h);
;             }
;           } else {
; #pragma unroll
;             for (int bj = 0; bj < 2; ++bj)
; #pragma unroll
;               for (int n = 0; n < 2; ++n) {
;                 const int seg = (bj * 8 + wc * 2 + n) ^ fq;
;                 *(u16*)(rowp + seg * 32) = f2bf(acc[ai][bj][m][n][j] * rs);
;               }
	v_add_u32_e32 v52, v64, v112
	ds_write_b16_d16_hi v52, v48
	v_add_u32_e32 v48, 0x10200, v144
	v_bfe_u32 v52, v53, 16, 1
	v_add3_u32 v52, v53, v52, s44
	v_add_u32_e32 v53, v48, v147
	ds_write_b16_d16_hi v53, v52
	v_cvt_pk_bf16_f32 v49, v49, v49
	v_add_u32_e32 v52, v48, v116
	ds_write_b16_d16_hi v52, v49
	v_bfe_u32 v49, v61, 16, 1
	v_add3_u32 v49, v61, v49, s44
	v_add_u32_e32 v52, v48, v124
	ds_write_b16_d16_hi v52, v49
	v_bfe_u32 v49, v57, 16, 1
	v_add3_u32 v49, v57, v49, s44
	v_add_u32_e32 v48, v48, v112
	ds_write_b16_d16_hi v48, v49
	v_add_u32_e32 v48, 0x10400, v144
	v_bfe_u32 v49, v54, 16, 1
	v_add3_u32 v49, v54, v49, s44
	v_add_u32_e32 v52, v48, v147
	ds_write_b16_d16_hi v52, v49
	v_bfe_u32 v49, v50, 16, 1
	v_add3_u32 v49, v50, v49, s44
	v_add_u32_e32 v50, v48, v116
	ds_write_b16_d16_hi v50, v49
	v_bfe_u32 v49, v62, 16, 1
	v_add3_u32 v49, v62, v49, s44
	v_add_u32_e32 v50, v48, v124
	ds_write_b16_d16_hi v50, v49
	v_bfe_u32 v49, v58, 16, 1
	v_add3_u32 v49, v58, v49, s44
	v_add_u32_e32 v48, v48, v112
	ds_write_b16_d16_hi v48, v49
	v_add_u32_e32 v48, 0x10600, v144
	v_bfe_u32 v49, v55, 16, 1
	v_add3_u32 v49, v55, v49, s44
	v_add_u32_e32 v50, v48, v147
	ds_write_b16_d16_hi v50, v49
	v_bfe_u32 v49, v51, 16, 1
	v_add3_u32 v49, v51, v49, s44
	v_add_u32_e32 v50, v48, v116
	ds_write_b16_d16_hi v50, v49
	v_bfe_u32 v49, v63, 16, 1
	v_add3_u32 v49, v63, v49, s44
	v_add_u32_e32 v50, v48, v124
	ds_write_b16_d16_hi v50, v49
	v_bfe_u32 v49, v59, 16, 1
	v_add3_u32 v49, v59, v49, s44
	v_add_u32_e32 v48, v48, v112
	ds_write_b16_d16_hi v48, v49
	v_add_u32_e32 v48, 0x12000, v144
	v_cvt_pk_bf16_f32 v36, v36, v36
	v_add_u32_e32 v49, v48, v147
	ds_write_b16_d16_hi v49, v36
	v_cvt_pk_bf16_f32 v32, v32, v32
	v_add_u32_e32 v36, v48, v116
	ds_write_b16_d16_hi v36, v32
	v_bfe_u32 v32, v44, 16, 1
	v_add3_u32 v32, v44, v32, s44
	v_add_u32_e32 v36, v48, v124
	ds_write_b16_d16_hi v36, v32
	v_bfe_u32 v32, v40, 16, 1
	v_add3_u32 v32, v40, v32, s44
	v_add_u32_e32 v36, v48, v112
	ds_write_b16_d16_hi v36, v32
	v_add_u32_e32 v32, 0x12200, v144
	v_bfe_u32 v36, v37, 16, 1
	v_add3_u32 v36, v37, v36, s44
	v_add_u32_e32 v37, v32, v147
	ds_write_b16_d16_hi v37, v36
	v_cvt_pk_bf16_f32 v33, v33, v33
	v_add_u32_e32 v36, v32, v116
	ds_write_b16_d16_hi v36, v33
	v_bfe_u32 v33, v45, 16, 1
	v_add3_u32 v33, v45, v33, s44
	v_add_u32_e32 v36, v32, v124
	ds_write_b16_d16_hi v36, v33
	v_bfe_u32 v33, v41, 16, 1
	v_add3_u32 v33, v41, v33, s44
	v_add_u32_e32 v32, v32, v112
	ds_write_b16_d16_hi v32, v33
	v_add_u32_e32 v32, 0x12400, v144
	v_bfe_u32 v33, v38, 16, 1
	v_add3_u32 v33, v38, v33, s44
	v_add_u32_e32 v36, v32, v147
	ds_write_b16_d16_hi v36, v33
	v_bfe_u32 v33, v34, 16, 1
	v_add3_u32 v33, v34, v33, s44
	v_add_u32_e32 v34, v32, v116
	ds_write_b16_d16_hi v34, v33
	v_bfe_u32 v33, v46, 16, 1
	v_add3_u32 v33, v46, v33, s44
	v_add_u32_e32 v34, v32, v124
	ds_write_b16_d16_hi v34, v33
	v_bfe_u32 v33, v42, 16, 1
	v_add3_u32 v33, v42, v33, s44
	v_add_u32_e32 v32, v32, v112
	ds_write_b16_d16_hi v32, v33
	v_add_u32_e32 v32, 0x12600, v144
	v_bfe_u32 v33, v39, 16, 1
	v_add3_u32 v33, v39, v33, s44
	v_add_u32_e32 v34, v32, v147
	ds_write_b16_d16_hi v34, v33
	v_bfe_u32 v33, v35, 16, 1
	v_add3_u32 v33, v35, v33, s44
	v_add_u32_e32 v34, v32, v116
	ds_write_b16_d16_hi v34, v33
	v_bfe_u32 v33, v47, 16, 1
	v_add3_u32 v33, v47, v33, s44
	v_add_u32_e32 v34, v32, v124
	ds_write_b16_d16_hi v34, v33
	v_bfe_u32 v33, v43, 16, 1
	v_add3_u32 v33, v43, v33, s44
	v_add_u32_e32 v32, v32, v112
	ds_write_b16_d16_hi v32, v33
	v_add_u32_e32 v32, 0x14000, v144
	v_cvt_pk_bf16_f32 v20, v20, v20
	v_add_u32_e32 v33, v32, v147
	ds_write_b16_d16_hi v33, v20
	v_cvt_pk_bf16_f32 v16, v16, v16
	v_add_u32_e32 v20, v32, v116
	ds_write_b16_d16_hi v20, v16
	v_bfe_u32 v16, v28, 16, 1
	v_add3_u32 v16, v28, v16, s44
	v_add_u32_e32 v20, v32, v124
	ds_write_b16_d16_hi v20, v16
	v_bfe_u32 v16, v24, 16, 1
	v_add3_u32 v16, v24, v16, s44
	v_add_u32_e32 v20, v32, v112
	ds_write_b16_d16_hi v20, v16
	v_add_u32_e32 v16, 0x14200, v144
	v_bfe_u32 v20, v21, 16, 1
	v_add3_u32 v20, v21, v20, s44
; __device__ __forceinline__ u16 f2bf(float f) { unsigned u = __float_as_uint(f); u += 0x7fffu + ((u >> 16) & 1u); return (u16)(u >> 16); }
; __device__ __forceinline__ int opaque_tid() { int t; asm volatile("v_mov_b32 %0, %1" : "=v"(t) : "v"((int)threadIdx.x)); return t; }
; template <int EPI> ...
;     ...
;           } else {
; #pragma unroll
;             for (int bj = 0; bj < 2; ++bj)
; #pragma unroll
;               for (int n = 0; n < 2; ++n) {
;                 const int seg = (bj * 8 + wc * 2 + n) ^ fq;
;                 *(u16*)(rowp + seg * 32) = f2bf(acc[ai][bj][m][n][j] * rs);
;               }
;           }
;         }
;     __syncthreads();
;     constexpr int CPR = RB / 16;
;     constexpr int RPI = 512 / CPR;
;     const int tid2 = opaque_tid();
;     const int cc = tid2 % CPR, r0 = tid2 / CPR;
;     u16* gp = (EPI == EPI_GU) ? e.out + ((size_t)((e.bcol >> 6) + (cc >> 3)) * 256 + r0) * 64 + (cc & 7) * 8
;                               : e.out + (size_t)r0 * e.ld + e.bcol + cc * 8;
;     const size_t gstep = (EPI == EPI_GU) ? (size_t)RPI * 64 : (size_t)RPI * e.ld;
	v_add_u32_e32 v21, v16, v147
	ds_write_b16_d16_hi v21, v20
	v_cvt_pk_bf16_f32 v17, v17, v17
	v_add_u32_e32 v20, v16, v116
	ds_write_b16_d16_hi v20, v17
	v_bfe_u32 v17, v29, 16, 1
	v_add3_u32 v17, v29, v17, s44
	v_add_u32_e32 v20, v16, v124
	ds_write_b16_d16_hi v20, v17
	v_bfe_u32 v17, v25, 16, 1
	v_add3_u32 v17, v25, v17, s44
	v_add_u32_e32 v16, v16, v112
	ds_write_b16_d16_hi v16, v17
	v_add_u32_e32 v16, 0x14400, v144
	v_bfe_u32 v17, v22, 16, 1
	v_add3_u32 v17, v22, v17, s44
	v_add_u32_e32 v20, v16, v147
	ds_write_b16_d16_hi v20, v17
	v_bfe_u32 v17, v18, 16, 1
	v_add3_u32 v17, v18, v17, s44
	v_add_u32_e32 v18, v16, v116
	ds_write_b16_d16_hi v18, v17
	v_bfe_u32 v17, v30, 16, 1
	v_add3_u32 v17, v30, v17, s44
	v_add_u32_e32 v18, v16, v124
	ds_write_b16_d16_hi v18, v17
	v_bfe_u32 v17, v26, 16, 1
	v_add3_u32 v17, v26, v17, s44
	v_add_u32_e32 v16, v16, v112
	ds_write_b16_d16_hi v16, v17
	v_add_u32_e32 v16, 0x14600, v144
	v_bfe_u32 v17, v23, 16, 1
	v_add3_u32 v17, v23, v17, s44
	v_add_u32_e32 v18, v16, v147
	ds_write_b16_d16_hi v18, v17
	v_bfe_u32 v17, v19, 16, 1
	v_add3_u32 v17, v19, v17, s44
	v_add_u32_e32 v18, v16, v116
	ds_write_b16_d16_hi v18, v17
	v_bfe_u32 v17, v31, 16, 1
	v_add3_u32 v17, v31, v17, s44
	v_add_u32_e32 v18, v16, v124
	ds_write_b16_d16_hi v18, v17
	v_bfe_u32 v17, v27, 16, 1
	v_add3_u32 v17, v27, v17, s44
	v_add_u32_e32 v16, v16, v112
	ds_write_b16_d16_hi v16, v17
	v_add_u32_e32 v16, 0x16000, v144
	v_cvt_pk_bf16_f32 v4, v4, v4
	v_add_u32_e32 v17, v16, v147
	ds_write_b16_d16_hi v17, v4
	v_cvt_pk_bf16_f32 v0, v0, v0
	v_add_u32_e32 v4, v16, v116
	ds_write_b16_d16_hi v4, v0
	v_bfe_u32 v0, v12, 16, 1
	v_add3_u32 v0, v12, v0, s44
	v_add_u32_e32 v4, v16, v124
	ds_write_b16_d16_hi v4, v0
	v_bfe_u32 v0, v8, 16, 1
	v_add3_u32 v0, v8, v0, s44
	v_add_u32_e32 v4, v16, v112
	ds_write_b16_d16_hi v4, v0
	v_add_u32_e32 v0, 0x16200, v144
	v_bfe_u32 v4, v5, 16, 1
	v_add3_u32 v4, v5, v4, s44
	v_add_u32_e32 v5, v0, v147
	ds_write_b16_d16_hi v5, v4
	v_cvt_pk_bf16_f32 v1, v1, v1
	v_add_u32_e32 v4, v0, v116
	ds_write_b16_d16_hi v4, v1
	v_bfe_u32 v1, v13, 16, 1
	v_add3_u32 v1, v13, v1, s44
	v_add_u32_e32 v4, v0, v124
	ds_write_b16_d16_hi v4, v1
	v_bfe_u32 v1, v9, 16, 1
	v_add3_u32 v1, v9, v1, s44
	v_add_u32_e32 v0, v0, v112
	ds_write_b16_d16_hi v0, v1
	v_add_u32_e32 v0, 0x16400, v144
	v_bfe_u32 v1, v6, 16, 1
	v_add3_u32 v1, v6, v1, s44
	v_add_u32_e32 v4, v0, v147
	ds_write_b16_d16_hi v4, v1
	v_bfe_u32 v1, v2, 16, 1
	v_add3_u32 v1, v2, v1, s44
	v_add_u32_e32 v2, v0, v116
	ds_write_b16_d16_hi v2, v1
	v_bfe_u32 v1, v14, 16, 1
	v_add3_u32 v1, v14, v1, s44
	v_add_u32_e32 v2, v0, v124
	ds_write_b16_d16_hi v2, v1
	v_bfe_u32 v1, v10, 16, 1
	v_add3_u32 v1, v10, v1, s44
	v_add_u32_e32 v0, v0, v112
	ds_write_b16_d16_hi v0, v1
	v_add_u32_e32 v0, 0x16600, v144
	v_bfe_u32 v1, v7, 16, 1
	v_add3_u32 v1, v7, v1, s44
	v_add_u32_e32 v2, v0, v147
	ds_write_b16_d16_hi v2, v1
	v_bfe_u32 v1, v3, 16, 1
	v_add3_u32 v1, v3, v1, s44
	v_add_u32_e32 v2, v0, v116
	ds_write_b16_d16_hi v2, v1
	v_bfe_u32 v1, v15, 16, 1
	v_add3_u32 v1, v15, v1, s44
	v_add_u32_e32 v2, v0, v124
	ds_write_b16_d16_hi v2, v1
	v_bfe_u32 v1, v11, 16, 1
	v_add3_u32 v1, v11, v1, s44
	v_add_u32_e32 v0, v0, v112
	ds_write_b16_d16_hi v0, v1
	s_waitcnt vmcnt(0) lgkmcnt(0)
	s_barrier
	v_mov_b32 v0, v146
	s_lshl_b32 s22, s49, 8
	v_ashrrev_i32_e32 v1, 31, v0
	v_lshrrev_b32_e32 v1, 27, v1
	s_ashr_i32 s23, s22, 31
	v_add_u32_e32 v1, v0, v1
	s_lshl_b64 s[22:23], s[22:23], 12
	v_ashrrev_i32_e32 v2, 5, v1
	s_add_u32 s22, s74, s22
	v_and_b32_e32 v1, 0xffffffe0, v1
	v_ashrrev_i32_e32 v3, 31, v2
	s_addc_u32 s23, s75, s23
	s_lshl_b32 s24, s48, 8
	v_sub_u32_e32 v6, v0, v1
	v_lshlrev_b64 v[0:1], 12, v[2:3]
	v_lshrrev_b32_e32 v3, 1, v2
	v_lshl_add_u64 v[0:1], s[22:23], 0, v[0:1]
	s_ashr_i32 s25, s24, 31
	v_lshlrev_b32_e32 v4, 3, v6
	v_bitop3_b32 v3, v3, v6, 6 bitop3:0x6c
	v_lshl_add_u64 v[0:1], s[24:25], 1, v[0:1]
	v_ashrrev_i32_e32 v5, 31, v4
	v_lshlrev_b32_e32 v2, 9, v2
	v_lshlrev_b32_e32 v3, 4, v3
	v_lshl_add_u64 v[0:1], v[4:5], 1, v[0:1]
	v_add3_u32 v2, 0, v2, v3
	s_mov_b32 s22, 0
